# v6
# baseline (speedup 1.0000x reference)
; __device__ __forceinline__ float bf2f(unsigned h) { return __uint_as_float(h << 16); }
; __device__ __forceinline__ void b2_scan(const Ctx& C) {
;     const float* SDEC = (const float*)(C.ws + WS_SDEC); const float* GDEC = (const float*)(C.ws + WS_GDEC);
;     const int idx = C.bid * NTHR + C.tid;
;     if (idx >= 131072) return;
;     const bool gla = idx >= 65536; const int r = idx & 65535;
;     bf16* base; size_t cstride, vstride; const float* dec; int dstride;
;     if (!gla) { const int b = r >> 13, h = (r >> 9) & 15, e = r & 511;
;         base = (bf16*)(C.ws + WS_HS) + ((size_t)(b * NC) * 16 + h) * 8192 + (size_t)e * 8; vstride = 512 * 8; cstride = (size_t)16 * 8192; dec = SDEC + (b * NC) * 16 + h; dstride = 16; }
;     else { const int b = r >> 13, h = (r >> 11) & 3, q = r & 2047, doct = q & 15, vp = q >> 4;
;         base = (bf16*)(C.ws + WS_GS) + ((size_t)(b * NC) * 4 + h) * 32768 + (size_t)(2 * vp) * 128 + doct * 8; vstride = 128; cstride = (size_t)4 * 32768; dec = GDEC + ((b * NC) * 4 + h) * 128 + doct * 8; dstride = 512; }
;     float run[2][8];
; #pragma unroll
;     for (int j = 0; j < 2; ++j)
; #pragma unroll
;         for (int q = 0; q < 8; ++q) run[j][q] = 0.f;
;     v4u loc[2][4][2]; f32x4 d0[2][4], d1[2][4];
;     ...
;     B2_LOAD(0, 0);
; #pragma unroll
;     for (int g = 0; g < 8; ++g) {
;         const int cur = g & 1;
;         if (g + 1 < 8) B2_LOAD(g + 1, cur ^ 1);
; #pragma unroll
;         for (int k = 0; k < 4; ++k) {
;             const int c = 4 * g + k;
;             const float dd[8] = {d0[cur][k][0], d0[cur][k][1], d0[cur][k][2], d0[cur][k][3], d1[cur][k][0], d1[cur][k][1], d1[cur][k][2], d1[cur][k][3]};
; #pragma unroll
;             for (int j = 0; j < 2; ++j) {
;                 v4u o; o.x = pk2(run[j][0], run[j][1]); o.y = pk2(run[j][2], run[j][3]); o.z = pk2(run[j][4], run[j][5]); o.w = pk2(run[j][6], run[j][7]);
;                 __builtin_nontemporal_store(o, (v4u*)(base + (size_t)c * cstride + (size_t)j * vstride));
;                 const unsigned lw[4] = {loc[cur][k][j].x, loc[cur][k][j].y, loc[cur][k][j].z, loc[cur][k][j].w};
; #pragma unroll
;                 for (int q = 0; q < 4; ++q) {
;                     run[j][2 * q] = dd[2 * q] * run[j][2 * q] + bf2f(lw[q] & 0xffffu);
;                     run[j][2 * q + 1] = dd[2 * q + 1] * run[j][2 * q + 1] + __uint_as_float(lw[q] & 0xffff0000u);
;                 }
.LBB0_475:
	s_or_b64 exec, exec, s[6:7]
	v_mov_b32_e32 v8, v234
	s_mov_b32 s10, 0
	s_waitcnt lgkmcnt(0)
	s_barrier
	s_lshl_b32 s6, s2, 9
	v_writelane_b32 v254, s6, 3
	s_load_dwordx2 s[14:15], s[0:1], 0xc0
	s_mov_b64 s[8:9], exec
	s_cmp_ge_u32 s2, 256
	s_cbranch_scc1 .Lb2_end_l0
	v_mov_b32_e32 v16, 0
	v_mov_b32_e32 v17, 0
	v_mov_b32_e32 v18, 0
	v_mov_b32_e32 v19, 0
	v_mov_b32_e32 v20, 0
	v_mov_b32_e32 v21, 0
	v_mov_b32_e32 v22, 0
	v_mov_b32_e32 v23, 0
	v_mov_b32_e32 v24, 0
	v_mov_b32_e32 v25, 0
	v_mov_b32_e32 v26, 0
	v_mov_b32_e32 v27, 0
	v_mov_b32_e32 v28, 0
	v_mov_b32_e32 v29, 0
	v_mov_b32_e32 v30, 0
	v_mov_b32_e32 v31, 0
	v_mov_b32_e32 v4, 0
	s_cmp_ge_u32 s2, 128
	s_cbranch_scc1 .Lb2_gla_l0
	s_lshr_b32 s6, s2, 4
	s_lshl_b32 s6, s6, 9
	s_and_b32 s12, s2, 15
	s_add_u32 s6, s6, s12
	s_lshl_b32 s12, s6, 2
	s_lshl_b32 s6, s6, 14
	v_lshlrev_b32_e32 v2, 4, v234
	v_add_u32_e32 v3, 0x2000, v2
	s_waitcnt lgkmcnt(0)
	s_add_u32 s6, s6, s14
	s_addc_u32 s7, s15, 0
	s_add_u32 s6, s6, 0x1dc00000
	s_addc_u32 s7, s7, 0
	s_add_u32 s12, s12, s14
	s_addc_u32 s13, s15, 0
	s_add_u32 s12, s12, 0x25c00000
	s_addc_u32 s13, s13, 0
	s_mov_b32 s10, s6
	s_mov_b32 s11, s7
	global_load_dwordx4 v[64:67], v2, s[6:7] nt
	global_load_dwordx4 v[68:71], v3, s[6:7] nt
	global_load_dword v72, v4, s[12:13]
	s_add_u32 s6, s6, 0x40000
	s_addc_u32 s7, s7, 0
	s_add_u32 s12, s12, 64
	s_addc_u32 s13, s13, 0
	global_load_dwordx4 v[80:83], v2, s[6:7] nt
	global_load_dwordx4 v[84:87], v3, s[6:7] nt
	global_load_dword v88, v4, s[12:13]
	s_add_u32 s6, s6, 0x40000
	s_addc_u32 s7, s7, 0
	s_add_u32 s12, s12, 64
	s_addc_u32 s13, s13, 0
	global_load_dwordx4 v[96:99], v2, s[6:7] nt
	global_load_dwordx4 v[100:103], v3, s[6:7] nt
	global_load_dword v104, v4, s[12:13]
	s_add_u32 s6, s6, 0x40000
	s_addc_u32 s7, s7, 0
	s_add_u32 s12, s12, 64
	s_addc_u32 s13, s13, 0
	global_load_dwordx4 v[112:115], v2, s[6:7] nt
	global_load_dwordx4 v[116:119], v3, s[6:7] nt
	global_load_dword v120, v4, s[12:13]
	s_add_u32 s6, s6, 0x40000
	s_addc_u32 s7, s7, 0
	s_add_u32 s12, s12, 64
	s_addc_u32 s13, s13, 0
	global_load_dwordx4 v[128:131], v2, s[6:7] nt
	global_load_dwordx4 v[132:135], v3, s[6:7] nt
	global_load_dword v136, v4, s[12:13]
	s_add_u32 s6, s6, 0x40000
	s_addc_u32 s7, s7, 0
	s_add_u32 s12, s12, 64
	s_addc_u32 s13, s13, 0
	global_load_dwordx4 v[144:147], v2, s[6:7] nt
	global_load_dwordx4 v[148:151], v3, s[6:7] nt
	global_load_dword v152, v4, s[12:13]
	s_add_u32 s6, s6, 0x40000
	s_addc_u32 s7, s7, 0
	s_add_u32 s12, s12, 64
	s_addc_u32 s13, s13, 0
	global_load_dwordx4 v[160:163], v2, s[6:7] nt
	global_load_dwordx4 v[164:167], v3, s[6:7] nt
	global_load_dword v168, v4, s[12:13]
	s_add_u32 s6, s6, 0x40000
	s_addc_u32 s7, s7, 0
	s_add_u32 s12, s12, 64
	s_addc_u32 s13, s13, 0
	global_load_dwordx4 v[176:179], v2, s[6:7] nt
	global_load_dwordx4 v[180:183], v3, s[6:7] nt
	global_load_dword v184, v4, s[12:13]
	s_add_u32 s6, s6, 0x40000
	s_addc_u32 s7, s7, 0
	s_add_u32 s12, s12, 64
	s_addc_u32 s13, s13, 0
	s_waitcnt vmcnt(21)
	v_cvt_pk_bf16_f32 v32, v16, v17
	v_cvt_pk_bf16_f32 v33, v18, v19
	v_cvt_pk_bf16_f32 v34, v20, v21
	v_cvt_pk_bf16_f32 v35, v22, v23
	global_store_dwordx4 v2, v[32:35], s[10:11] nt
	v_cvt_pk_bf16_f32 v36, v24, v25
	v_cvt_pk_bf16_f32 v37, v26, v27
	v_cvt_pk_bf16_f32 v38, v28, v29
	v_cvt_pk_bf16_f32 v39, v30, v31
	global_store_dwordx4 v3, v[36:39], s[10:11] nt
	s_add_u32 s10, s10, 0x40000
	s_addc_u32 s11, s11, 0
	v_lshlrev_b32_e32 v48, 16, v64
	v_and_b32_e32 v49, 0xffff0000, v64
	v_fma_f32 v16, v72, v16, v48
	v_fma_f32 v17, v72, v17, v49
	v_lshlrev_b32_e32 v48, 16, v65
	v_and_b32_e32 v49, 0xffff0000, v65
	v_fma_f32 v18, v72, v18, v48
	v_fma_f32 v19, v72, v19, v49
	v_lshlrev_b32_e32 v48, 16, v66
	v_and_b32_e32 v49, 0xffff0000, v66
	v_fma_f32 v20, v72, v20, v48
	v_fma_f32 v21, v72, v21, v49
	v_lshlrev_b32_e32 v48, 16, v67
	v_and_b32_e32 v49, 0xffff0000, v67
	v_fma_f32 v22, v72, v22, v48
	v_fma_f32 v23, v72, v23, v49
	v_lshlrev_b32_e32 v48, 16, v68
	v_and_b32_e32 v49, 0xffff0000, v68
	v_fma_f32 v24, v72, v24, v48
	v_fma_f32 v25, v72, v25, v49
	v_lshlrev_b32_e32 v48, 16, v69
	v_and_b32_e32 v49, 0xffff0000, v69
	v_fma_f32 v26, v72, v26, v48
	v_fma_f32 v27, v72, v27, v49
	v_lshlrev_b32_e32 v48, 16, v70
	v_and_b32_e32 v49, 0xffff0000, v70
	v_fma_f32 v28, v72, v28, v48
	v_fma_f32 v29, v72, v29, v49
	v_lshlrev_b32_e32 v48, 16, v71
	v_and_b32_e32 v49, 0xffff0000, v71
	v_fma_f32 v30, v72, v30, v48
	v_fma_f32 v31, v72, v31, v49
	global_load_dwordx4 v[64:67], v2, s[6:7] nt
	global_load_dwordx4 v[68:71], v3, s[6:7] nt
	global_load_dword v72, v4, s[12:13]
	s_add_u32 s6, s6, 0x40000
	s_addc_u32 s7, s7, 0
	s_add_u32 s12, s12, 64
	s_addc_u32 s13, s13, 0
	s_waitcnt vmcnt(23)
	v_cvt_pk_bf16_f32 v40, v16, v17
	v_cvt_pk_bf16_f32 v41, v18, v19
	v_cvt_pk_bf16_f32 v42, v20, v21
	v_cvt_pk_bf16_f32 v43, v22, v23
	global_store_dwordx4 v2, v[40:43], s[10:11] nt
	v_cvt_pk_bf16_f32 v44, v24, v25
	v_cvt_pk_bf16_f32 v45, v26, v27
	v_cvt_pk_bf16_f32 v46, v28, v29
	v_cvt_pk_bf16_f32 v47, v30, v31
	global_store_dwordx4 v3, v[44:47], s[10:11] nt
	s_add_u32 s10, s10, 0x40000
	s_addc_u32 s11, s11, 0
	v_lshlrev_b32_e32 v48, 16, v80
	v_and_b32_e32 v49, 0xffff0000, v80
	v_fma_f32 v16, v88, v16, v48
	v_fma_f32 v17, v88, v17, v49
	v_lshlrev_b32_e32 v48, 16, v81
	v_and_b32_e32 v49, 0xffff0000, v81
	v_fma_f32 v18, v88, v18, v48
	v_fma_f32 v19, v88, v19, v49
	v_lshlrev_b32_e32 v48, 16, v82
	v_and_b32_e32 v49, 0xffff0000, v82
	v_fma_f32 v20, v88, v20, v48
	v_fma_f32 v21, v88, v21, v49
	v_lshlrev_b32_e32 v48, 16, v83
	v_and_b32_e32 v49, 0xffff0000, v83
	v_fma_f32 v22, v88, v22, v48
	v_fma_f32 v23, v88, v23, v49
	v_lshlrev_b32_e32 v48, 16, v84
	v_and_b32_e32 v49, 0xffff0000, v84
	v_fma_f32 v24, v88, v24, v48
	v_fma_f32 v25, v88, v25, v49
	v_lshlrev_b32_e32 v48, 16, v85
	v_and_b32_e32 v49, 0xffff0000, v85
	v_fma_f32 v26, v88, v26, v48
	v_fma_f32 v27, v88, v27, v49
	v_lshlrev_b32_e32 v48, 16, v86
	v_and_b32_e32 v49, 0xffff0000, v86
	v_fma_f32 v28, v88, v28, v48
	v_fma_f32 v29, v88, v29, v49
	v_lshlrev_b32_e32 v48, 16, v87
	v_and_b32_e32 v49, 0xffff0000, v87
	v_fma_f32 v30, v88, v30, v48
	v_fma_f32 v31, v88, v31, v49
	global_load_dwordx4 v[80:83], v2, s[6:7] nt
	global_load_dwordx4 v[84:87], v3, s[6:7] nt
	global_load_dword v88, v4, s[12:13]
	s_add_u32 s6, s6, 0x40000
	s_addc_u32 s7, s7, 0
	s_add_u32 s12, s12, 64
	s_addc_u32 s13, s13, 0
	s_waitcnt vmcnt(25)
; __device__ __forceinline__ float bf2f(unsigned h) { return __uint_as_float(h << 16); }
; __device__ __forceinline__ unsigned pk2(float lo, float hi) { return pg8::cvt_pk_bf16(lo, hi); }
; __device__ __forceinline__ void b2_scan(const Ctx& C) {
;     ...
;     B2_LOAD(0, 0);
; #pragma unroll
;     for (int g = 0; g < 8; ++g) {
;         const int cur = g & 1;
;         if (g + 1 < 8) B2_LOAD(g + 1, cur ^ 1);
; #pragma unroll
;         for (int k = 0; k < 4; ++k) {
;             const int c = 4 * g + k;
;             const float dd[8] = {d0[cur][k][0], d0[cur][k][1], d0[cur][k][2], d0[cur][k][3], d1[cur][k][0], d1[cur][k][1], d1[cur][k][2], d1[cur][k][3]};
; #pragma unroll
;             for (int j = 0; j < 2; ++j) {
;                 v4u o; o.x = pk2(run[j][0], run[j][1]); o.y = pk2(run[j][2], run[j][3]); o.z = pk2(run[j][4], run[j][5]); o.w = pk2(run[j][6], run[j][7]);
;                 __builtin_nontemporal_store(o, (v4u*)(base + (size_t)c * cstride + (size_t)j * vstride));
;                 const unsigned lw[4] = {loc[cur][k][j].x, loc[cur][k][j].y, loc[cur][k][j].z, loc[cur][k][j].w};
; #pragma unroll
;                 for (int q = 0; q < 4; ++q) {
;                     run[j][2 * q] = dd[2 * q] * run[j][2 * q] + bf2f(lw[q] & 0xffffu);
;                     run[j][2 * q + 1] = dd[2 * q + 1] * run[j][2 * q + 1] + __uint_as_float(lw[q] & 0xffff0000u);
;                 }
	v_cvt_pk_bf16_f32 v32, v16, v17
	v_cvt_pk_bf16_f32 v33, v18, v19
	v_cvt_pk_bf16_f32 v34, v20, v21
	v_cvt_pk_bf16_f32 v35, v22, v23
	global_store_dwordx4 v2, v[32:35], s[10:11] nt
	v_cvt_pk_bf16_f32 v36, v24, v25
	v_cvt_pk_bf16_f32 v37, v26, v27
	v_cvt_pk_bf16_f32 v38, v28, v29
	v_cvt_pk_bf16_f32 v39, v30, v31
	global_store_dwordx4 v3, v[36:39], s[10:11] nt
	s_add_u32 s10, s10, 0x40000
	s_addc_u32 s11, s11, 0
	v_lshlrev_b32_e32 v48, 16, v96
	v_and_b32_e32 v49, 0xffff0000, v96
	v_fma_f32 v16, v104, v16, v48
	v_fma_f32 v17, v104, v17, v49
	v_lshlrev_b32_e32 v48, 16, v97
	v_and_b32_e32 v49, 0xffff0000, v97
	v_fma_f32 v18, v104, v18, v48
	v_fma_f32 v19, v104, v19, v49
	v_lshlrev_b32_e32 v48, 16, v98
	v_and_b32_e32 v49, 0xffff0000, v98
	v_fma_f32 v20, v104, v20, v48
	v_fma_f32 v21, v104, v21, v49
	v_lshlrev_b32_e32 v48, 16, v99
	v_and_b32_e32 v49, 0xffff0000, v99
	v_fma_f32 v22, v104, v22, v48
	v_fma_f32 v23, v104, v23, v49
	v_lshlrev_b32_e32 v48, 16, v100
	v_and_b32_e32 v49, 0xffff0000, v100
	v_fma_f32 v24, v104, v24, v48
	v_fma_f32 v25, v104, v25, v49
	v_lshlrev_b32_e32 v48, 16, v101
	v_and_b32_e32 v49, 0xffff0000, v101
	v_fma_f32 v26, v104, v26, v48
	v_fma_f32 v27, v104, v27, v49
	v_lshlrev_b32_e32 v48, 16, v102
	v_and_b32_e32 v49, 0xffff0000, v102
	v_fma_f32 v28, v104, v28, v48
	v_fma_f32 v29, v104, v29, v49
	v_lshlrev_b32_e32 v48, 16, v103
	v_and_b32_e32 v49, 0xffff0000, v103
	v_fma_f32 v30, v104, v30, v48
	v_fma_f32 v31, v104, v31, v49
	global_load_dwordx4 v[96:99], v2, s[6:7] nt
	global_load_dwordx4 v[100:103], v3, s[6:7] nt
	global_load_dword v104, v4, s[12:13]
	s_add_u32 s6, s6, 0x40000
	s_addc_u32 s7, s7, 0
	s_add_u32 s12, s12, 64
	s_addc_u32 s13, s13, 0
	s_waitcnt vmcnt(27)
	v_cvt_pk_bf16_f32 v40, v16, v17
	v_cvt_pk_bf16_f32 v41, v18, v19
	v_cvt_pk_bf16_f32 v42, v20, v21
	v_cvt_pk_bf16_f32 v43, v22, v23
	global_store_dwordx4 v2, v[40:43], s[10:11] nt
	v_cvt_pk_bf16_f32 v44, v24, v25
	v_cvt_pk_bf16_f32 v45, v26, v27
	v_cvt_pk_bf16_f32 v46, v28, v29
	v_cvt_pk_bf16_f32 v47, v30, v31
	global_store_dwordx4 v3, v[44:47], s[10:11] nt
	s_add_u32 s10, s10, 0x40000
	s_addc_u32 s11, s11, 0
	v_lshlrev_b32_e32 v48, 16, v112
	v_and_b32_e32 v49, 0xffff0000, v112
	v_fma_f32 v16, v120, v16, v48
	v_fma_f32 v17, v120, v17, v49
	v_lshlrev_b32_e32 v48, 16, v113
	v_and_b32_e32 v49, 0xffff0000, v113
	v_fma_f32 v18, v120, v18, v48
	v_fma_f32 v19, v120, v19, v49
	v_lshlrev_b32_e32 v48, 16, v114
	v_and_b32_e32 v49, 0xffff0000, v114
	v_fma_f32 v20, v120, v20, v48
	v_fma_f32 v21, v120, v21, v49
	v_lshlrev_b32_e32 v48, 16, v115
	v_and_b32_e32 v49, 0xffff0000, v115
	v_fma_f32 v22, v120, v22, v48
	v_fma_f32 v23, v120, v23, v49
	v_lshlrev_b32_e32 v48, 16, v116
	v_and_b32_e32 v49, 0xffff0000, v116
	v_fma_f32 v24, v120, v24, v48
	v_fma_f32 v25, v120, v25, v49
	v_lshlrev_b32_e32 v48, 16, v117
	v_and_b32_e32 v49, 0xffff0000, v117
	v_fma_f32 v26, v120, v26, v48
	v_fma_f32 v27, v120, v27, v49
	v_lshlrev_b32_e32 v48, 16, v118
	v_and_b32_e32 v49, 0xffff0000, v118
	v_fma_f32 v28, v120, v28, v48
	v_fma_f32 v29, v120, v29, v49
	v_lshlrev_b32_e32 v48, 16, v119
	v_and_b32_e32 v49, 0xffff0000, v119
	v_fma_f32 v30, v120, v30, v48
	v_fma_f32 v31, v120, v31, v49
	global_load_dwordx4 v[112:115], v2, s[6:7] nt
	global_load_dwordx4 v[116:119], v3, s[6:7] nt
	global_load_dword v120, v4, s[12:13]
	s_add_u32 s6, s6, 0x40000
	s_addc_u32 s7, s7, 0
	s_add_u32 s12, s12, 64
	s_addc_u32 s13, s13, 0
	s_waitcnt vmcnt(29)
	v_cvt_pk_bf16_f32 v32, v16, v17
	v_cvt_pk_bf16_f32 v33, v18, v19
	v_cvt_pk_bf16_f32 v34, v20, v21
	v_cvt_pk_bf16_f32 v35, v22, v23
	global_store_dwordx4 v2, v[32:35], s[10:11] nt
	v_cvt_pk_bf16_f32 v36, v24, v25
	v_cvt_pk_bf16_f32 v37, v26, v27
	v_cvt_pk_bf16_f32 v38, v28, v29
	v_cvt_pk_bf16_f32 v39, v30, v31
	global_store_dwordx4 v3, v[36:39], s[10:11] nt
	s_add_u32 s10, s10, 0x40000
	s_addc_u32 s11, s11, 0
	v_lshlrev_b32_e32 v48, 16, v128
	v_and_b32_e32 v49, 0xffff0000, v128
	v_fma_f32 v16, v136, v16, v48
	v_fma_f32 v17, v136, v17, v49
	v_lshlrev_b32_e32 v48, 16, v129
	v_and_b32_e32 v49, 0xffff0000, v129
	v_fma_f32 v18, v136, v18, v48
	v_fma_f32 v19, v136, v19, v49
	v_lshlrev_b32_e32 v48, 16, v130
	v_and_b32_e32 v49, 0xffff0000, v130
	v_fma_f32 v20, v136, v20, v48
	v_fma_f32 v21, v136, v21, v49
	v_lshlrev_b32_e32 v48, 16, v131
	v_and_b32_e32 v49, 0xffff0000, v131
	v_fma_f32 v22, v136, v22, v48
	v_fma_f32 v23, v136, v23, v49
	v_lshlrev_b32_e32 v48, 16, v132
	v_and_b32_e32 v49, 0xffff0000, v132
	v_fma_f32 v24, v136, v24, v48
	v_fma_f32 v25, v136, v25, v49
	v_lshlrev_b32_e32 v48, 16, v133
	v_and_b32_e32 v49, 0xffff0000, v133
	v_fma_f32 v26, v136, v26, v48
	v_fma_f32 v27, v136, v27, v49
	v_lshlrev_b32_e32 v48, 16, v134
	v_and_b32_e32 v49, 0xffff0000, v134
	v_fma_f32 v28, v136, v28, v48
	v_fma_f32 v29, v136, v29, v49
	v_lshlrev_b32_e32 v48, 16, v135
	v_and_b32_e32 v49, 0xffff0000, v135
	v_fma_f32 v30, v136, v30, v48
	v_fma_f32 v31, v136, v31, v49
	global_load_dwordx4 v[128:131], v2, s[6:7] nt
	global_load_dwordx4 v[132:135], v3, s[6:7] nt
	global_load_dword v136, v4, s[12:13]
	s_add_u32 s6, s6, 0x40000
	s_addc_u32 s7, s7, 0
	s_add_u32 s12, s12, 64
	s_addc_u32 s13, s13, 0
	s_waitcnt vmcnt(31)
; __device__ __forceinline__ float bf2f(unsigned h) { return __uint_as_float(h << 16); }
; __device__ __forceinline__ unsigned pk2(float lo, float hi) { return pg8::cvt_pk_bf16(lo, hi); }
; __device__ __forceinline__ void b2_scan(const Ctx& C) {
;     ...
;     B2_LOAD(0, 0);
; #pragma unroll
;     for (int g = 0; g < 8; ++g) {
;         const int cur = g & 1;
;         if (g + 1 < 8) B2_LOAD(g + 1, cur ^ 1);
; #pragma unroll
;         for (int k = 0; k < 4; ++k) {
;             const int c = 4 * g + k;
;             const float dd[8] = {d0[cur][k][0], d0[cur][k][1], d0[cur][k][2], d0[cur][k][3], d1[cur][k][0], d1[cur][k][1], d1[cur][k][2], d1[cur][k][3]};
; #pragma unroll
;             for (int j = 0; j < 2; ++j) {
;                 v4u o; o.x = pk2(run[j][0], run[j][1]); o.y = pk2(run[j][2], run[j][3]); o.z = pk2(run[j][4], run[j][5]); o.w = pk2(run[j][6], run[j][7]);
;                 __builtin_nontemporal_store(o, (v4u*)(base + (size_t)c * cstride + (size_t)j * vstride));
;                 const unsigned lw[4] = {loc[cur][k][j].x, loc[cur][k][j].y, loc[cur][k][j].z, loc[cur][k][j].w};
; #pragma unroll
;                 for (int q = 0; q < 4; ++q) {
;                     run[j][2 * q] = dd[2 * q] * run[j][2 * q] + bf2f(lw[q] & 0xffffu);
;                     run[j][2 * q + 1] = dd[2 * q + 1] * run[j][2 * q + 1] + __uint_as_float(lw[q] & 0xffff0000u);
;                 }
	v_cvt_pk_bf16_f32 v40, v16, v17
	v_cvt_pk_bf16_f32 v41, v18, v19
	v_cvt_pk_bf16_f32 v42, v20, v21
	v_cvt_pk_bf16_f32 v43, v22, v23
	global_store_dwordx4 v2, v[40:43], s[10:11] nt
	v_cvt_pk_bf16_f32 v44, v24, v25
	v_cvt_pk_bf16_f32 v45, v26, v27
	v_cvt_pk_bf16_f32 v46, v28, v29
	v_cvt_pk_bf16_f32 v47, v30, v31
	global_store_dwordx4 v3, v[44:47], s[10:11] nt
	s_add_u32 s10, s10, 0x40000
	s_addc_u32 s11, s11, 0
	v_lshlrev_b32_e32 v48, 16, v144
	v_and_b32_e32 v49, 0xffff0000, v144
	v_fma_f32 v16, v152, v16, v48
	v_fma_f32 v17, v152, v17, v49
	v_lshlrev_b32_e32 v48, 16, v145
	v_and_b32_e32 v49, 0xffff0000, v145
	v_fma_f32 v18, v152, v18, v48
	v_fma_f32 v19, v152, v19, v49
	v_lshlrev_b32_e32 v48, 16, v146
	v_and_b32_e32 v49, 0xffff0000, v146
	v_fma_f32 v20, v152, v20, v48
	v_fma_f32 v21, v152, v21, v49
	v_lshlrev_b32_e32 v48, 16, v147
	v_and_b32_e32 v49, 0xffff0000, v147
	v_fma_f32 v22, v152, v22, v48
	v_fma_f32 v23, v152, v23, v49
	v_lshlrev_b32_e32 v48, 16, v148
	v_and_b32_e32 v49, 0xffff0000, v148
	v_fma_f32 v24, v152, v24, v48
	v_fma_f32 v25, v152, v25, v49
	v_lshlrev_b32_e32 v48, 16, v149
	v_and_b32_e32 v49, 0xffff0000, v149
	v_fma_f32 v26, v152, v26, v48
	v_fma_f32 v27, v152, v27, v49
	v_lshlrev_b32_e32 v48, 16, v150
	v_and_b32_e32 v49, 0xffff0000, v150
	v_fma_f32 v28, v152, v28, v48
	v_fma_f32 v29, v152, v29, v49
	v_lshlrev_b32_e32 v48, 16, v151
	v_and_b32_e32 v49, 0xffff0000, v151
	v_fma_f32 v30, v152, v30, v48
	v_fma_f32 v31, v152, v31, v49
	global_load_dwordx4 v[144:147], v2, s[6:7] nt
	global_load_dwordx4 v[148:151], v3, s[6:7] nt
	global_load_dword v152, v4, s[12:13]
	s_add_u32 s6, s6, 0x40000
	s_addc_u32 s7, s7, 0
	s_add_u32 s12, s12, 64
	s_addc_u32 s13, s13, 0
	s_waitcnt vmcnt(33)
	v_cvt_pk_bf16_f32 v32, v16, v17
	v_cvt_pk_bf16_f32 v33, v18, v19
	v_cvt_pk_bf16_f32 v34, v20, v21
	v_cvt_pk_bf16_f32 v35, v22, v23
	global_store_dwordx4 v2, v[32:35], s[10:11] nt
	v_cvt_pk_bf16_f32 v36, v24, v25
	v_cvt_pk_bf16_f32 v37, v26, v27
	v_cvt_pk_bf16_f32 v38, v28, v29
	v_cvt_pk_bf16_f32 v39, v30, v31
	global_store_dwordx4 v3, v[36:39], s[10:11] nt
	s_add_u32 s10, s10, 0x40000
	s_addc_u32 s11, s11, 0
	v_lshlrev_b32_e32 v48, 16, v160
	v_and_b32_e32 v49, 0xffff0000, v160
	v_fma_f32 v16, v168, v16, v48
	v_fma_f32 v17, v168, v17, v49
	v_lshlrev_b32_e32 v48, 16, v161
	v_and_b32_e32 v49, 0xffff0000, v161
	v_fma_f32 v18, v168, v18, v48
	v_fma_f32 v19, v168, v19, v49
	v_lshlrev_b32_e32 v48, 16, v162
	v_and_b32_e32 v49, 0xffff0000, v162
	v_fma_f32 v20, v168, v20, v48
	v_fma_f32 v21, v168, v21, v49
	v_lshlrev_b32_e32 v48, 16, v163
	v_and_b32_e32 v49, 0xffff0000, v163
	v_fma_f32 v22, v168, v22, v48
	v_fma_f32 v23, v168, v23, v49
	v_lshlrev_b32_e32 v48, 16, v164
	v_and_b32_e32 v49, 0xffff0000, v164
	v_fma_f32 v24, v168, v24, v48
	v_fma_f32 v25, v168, v25, v49
	v_lshlrev_b32_e32 v48, 16, v165
	v_and_b32_e32 v49, 0xffff0000, v165
	v_fma_f32 v26, v168, v26, v48
	v_fma_f32 v27, v168, v27, v49
	v_lshlrev_b32_e32 v48, 16, v166
	v_and_b32_e32 v49, 0xffff0000, v166
	v_fma_f32 v28, v168, v28, v48
	v_fma_f32 v29, v168, v29, v49
	v_lshlrev_b32_e32 v48, 16, v167
	v_and_b32_e32 v49, 0xffff0000, v167
	v_fma_f32 v30, v168, v30, v48
	v_fma_f32 v31, v168, v31, v49
	global_load_dwordx4 v[160:163], v2, s[6:7] nt
	global_load_dwordx4 v[164:167], v3, s[6:7] nt
	global_load_dword v168, v4, s[12:13]
	s_add_u32 s6, s6, 0x40000
	s_addc_u32 s7, s7, 0
	s_add_u32 s12, s12, 64
	s_addc_u32 s13, s13, 0
	s_waitcnt vmcnt(35)
	v_cvt_pk_bf16_f32 v40, v16, v17
	v_cvt_pk_bf16_f32 v41, v18, v19
	v_cvt_pk_bf16_f32 v42, v20, v21
	v_cvt_pk_bf16_f32 v43, v22, v23
	global_store_dwordx4 v2, v[40:43], s[10:11] nt
	v_cvt_pk_bf16_f32 v44, v24, v25
	v_cvt_pk_bf16_f32 v45, v26, v27
	v_cvt_pk_bf16_f32 v46, v28, v29
	v_cvt_pk_bf16_f32 v47, v30, v31
	global_store_dwordx4 v3, v[44:47], s[10:11] nt
	s_add_u32 s10, s10, 0x40000
	s_addc_u32 s11, s11, 0
	v_lshlrev_b32_e32 v48, 16, v176
	v_and_b32_e32 v49, 0xffff0000, v176
	v_fma_f32 v16, v184, v16, v48
	v_fma_f32 v17, v184, v17, v49
	v_lshlrev_b32_e32 v48, 16, v177
	v_and_b32_e32 v49, 0xffff0000, v177
	v_fma_f32 v18, v184, v18, v48
	v_fma_f32 v19, v184, v19, v49
	v_lshlrev_b32_e32 v48, 16, v178
	v_and_b32_e32 v49, 0xffff0000, v178
	v_fma_f32 v20, v184, v20, v48
	v_fma_f32 v21, v184, v21, v49
	v_lshlrev_b32_e32 v48, 16, v179
	v_and_b32_e32 v49, 0xffff0000, v179
	v_fma_f32 v22, v184, v22, v48
	v_fma_f32 v23, v184, v23, v49
	v_lshlrev_b32_e32 v48, 16, v180
	v_and_b32_e32 v49, 0xffff0000, v180
	v_fma_f32 v24, v184, v24, v48
	v_fma_f32 v25, v184, v25, v49
	v_lshlrev_b32_e32 v48, 16, v181
	v_and_b32_e32 v49, 0xffff0000, v181
	v_fma_f32 v26, v184, v26, v48
	v_fma_f32 v27, v184, v27, v49
	v_lshlrev_b32_e32 v48, 16, v182
	v_and_b32_e32 v49, 0xffff0000, v182
	v_fma_f32 v28, v184, v28, v48
	v_fma_f32 v29, v184, v29, v49
	v_lshlrev_b32_e32 v48, 16, v183
	v_and_b32_e32 v49, 0xffff0000, v183
	v_fma_f32 v30, v184, v30, v48
	v_fma_f32 v31, v184, v31, v49
	global_load_dwordx4 v[176:179], v2, s[6:7] nt
	global_load_dwordx4 v[180:183], v3, s[6:7] nt
	global_load_dword v184, v4, s[12:13]
	s_add_u32 s6, s6, 0x40000
	s_addc_u32 s7, s7, 0
	s_add_u32 s12, s12, 64
	s_addc_u32 s13, s13, 0
	s_waitcnt vmcnt(35)
; __device__ __forceinline__ float bf2f(unsigned h) { return __uint_as_float(h << 16); }
; __device__ __forceinline__ unsigned pk2(float lo, float hi) { return pg8::cvt_pk_bf16(lo, hi); }
; __device__ __forceinline__ void b2_scan(const Ctx& C) {
;     ...
;     B2_LOAD(0, 0);
; #pragma unroll
;     for (int g = 0; g < 8; ++g) {
;         const int cur = g & 1;
;         if (g + 1 < 8) B2_LOAD(g + 1, cur ^ 1);
; #pragma unroll
;         for (int k = 0; k < 4; ++k) {
;             const int c = 4 * g + k;
;             const float dd[8] = {d0[cur][k][0], d0[cur][k][1], d0[cur][k][2], d0[cur][k][3], d1[cur][k][0], d1[cur][k][1], d1[cur][k][2], d1[cur][k][3]};
; #pragma unroll
;             for (int j = 0; j < 2; ++j) {
;                 v4u o; o.x = pk2(run[j][0], run[j][1]); o.y = pk2(run[j][2], run[j][3]); o.z = pk2(run[j][4], run[j][5]); o.w = pk2(run[j][6], run[j][7]);
;                 __builtin_nontemporal_store(o, (v4u*)(base + (size_t)c * cstride + (size_t)j * vstride));
;                 const unsigned lw[4] = {loc[cur][k][j].x, loc[cur][k][j].y, loc[cur][k][j].z, loc[cur][k][j].w};
; #pragma unroll
;                 for (int q = 0; q < 4; ++q) {
;                     run[j][2 * q] = dd[2 * q] * run[j][2 * q] + bf2f(lw[q] & 0xffffu);
;                     run[j][2 * q + 1] = dd[2 * q + 1] * run[j][2 * q + 1] + __uint_as_float(lw[q] & 0xffff0000u);
;                 }
	v_cvt_pk_bf16_f32 v32, v16, v17
	v_cvt_pk_bf16_f32 v33, v18, v19
	v_cvt_pk_bf16_f32 v34, v20, v21
	v_cvt_pk_bf16_f32 v35, v22, v23
	global_store_dwordx4 v2, v[32:35], s[10:11] nt
	v_cvt_pk_bf16_f32 v36, v24, v25
	v_cvt_pk_bf16_f32 v37, v26, v27
	v_cvt_pk_bf16_f32 v38, v28, v29
	v_cvt_pk_bf16_f32 v39, v30, v31
	global_store_dwordx4 v3, v[36:39], s[10:11] nt
	s_add_u32 s10, s10, 0x40000
	s_addc_u32 s11, s11, 0
	v_lshlrev_b32_e32 v48, 16, v64
	v_and_b32_e32 v49, 0xffff0000, v64
	v_fma_f32 v16, v72, v16, v48
	v_fma_f32 v17, v72, v17, v49
	v_lshlrev_b32_e32 v48, 16, v65
	v_and_b32_e32 v49, 0xffff0000, v65
	v_fma_f32 v18, v72, v18, v48
	v_fma_f32 v19, v72, v19, v49
	v_lshlrev_b32_e32 v48, 16, v66
	v_and_b32_e32 v49, 0xffff0000, v66
	v_fma_f32 v20, v72, v20, v48
	v_fma_f32 v21, v72, v21, v49
	v_lshlrev_b32_e32 v48, 16, v67
	v_and_b32_e32 v49, 0xffff0000, v67
	v_fma_f32 v22, v72, v22, v48
	v_fma_f32 v23, v72, v23, v49
	v_lshlrev_b32_e32 v48, 16, v68
	v_and_b32_e32 v49, 0xffff0000, v68
	v_fma_f32 v24, v72, v24, v48
	v_fma_f32 v25, v72, v25, v49
	v_lshlrev_b32_e32 v48, 16, v69
	v_and_b32_e32 v49, 0xffff0000, v69
	v_fma_f32 v26, v72, v26, v48
	v_fma_f32 v27, v72, v27, v49
	v_lshlrev_b32_e32 v48, 16, v70
	v_and_b32_e32 v49, 0xffff0000, v70
	v_fma_f32 v28, v72, v28, v48
	v_fma_f32 v29, v72, v29, v49
	v_lshlrev_b32_e32 v48, 16, v71
	v_and_b32_e32 v49, 0xffff0000, v71
	v_fma_f32 v30, v72, v30, v48
	v_fma_f32 v31, v72, v31, v49
	global_load_dwordx4 v[64:67], v2, s[6:7] nt
	global_load_dwordx4 v[68:71], v3, s[6:7] nt
	global_load_dword v72, v4, s[12:13]
	s_add_u32 s6, s6, 0x40000
	s_addc_u32 s7, s7, 0
	s_add_u32 s12, s12, 64
	s_addc_u32 s13, s13, 0
	s_waitcnt vmcnt(35)
	v_cvt_pk_bf16_f32 v40, v16, v17
	v_cvt_pk_bf16_f32 v41, v18, v19
	v_cvt_pk_bf16_f32 v42, v20, v21
	v_cvt_pk_bf16_f32 v43, v22, v23
	global_store_dwordx4 v2, v[40:43], s[10:11] nt
	v_cvt_pk_bf16_f32 v44, v24, v25
	v_cvt_pk_bf16_f32 v45, v26, v27
	v_cvt_pk_bf16_f32 v46, v28, v29
	v_cvt_pk_bf16_f32 v47, v30, v31
	global_store_dwordx4 v3, v[44:47], s[10:11] nt
	s_add_u32 s10, s10, 0x40000
	s_addc_u32 s11, s11, 0
	v_lshlrev_b32_e32 v48, 16, v80
	v_and_b32_e32 v49, 0xffff0000, v80
	v_fma_f32 v16, v88, v16, v48
	v_fma_f32 v17, v88, v17, v49
	v_lshlrev_b32_e32 v48, 16, v81
	v_and_b32_e32 v49, 0xffff0000, v81
	v_fma_f32 v18, v88, v18, v48
	v_fma_f32 v19, v88, v19, v49
	v_lshlrev_b32_e32 v48, 16, v82
	v_and_b32_e32 v49, 0xffff0000, v82
	v_fma_f32 v20, v88, v20, v48
	v_fma_f32 v21, v88, v21, v49
	v_lshlrev_b32_e32 v48, 16, v83
	v_and_b32_e32 v49, 0xffff0000, v83
	v_fma_f32 v22, v88, v22, v48
	v_fma_f32 v23, v88, v23, v49
	v_lshlrev_b32_e32 v48, 16, v84
	v_and_b32_e32 v49, 0xffff0000, v84
	v_fma_f32 v24, v88, v24, v48
	v_fma_f32 v25, v88, v25, v49
	v_lshlrev_b32_e32 v48, 16, v85
	v_and_b32_e32 v49, 0xffff0000, v85
	v_fma_f32 v26, v88, v26, v48
	v_fma_f32 v27, v88, v27, v49
	v_lshlrev_b32_e32 v48, 16, v86
	v_and_b32_e32 v49, 0xffff0000, v86
	v_fma_f32 v28, v88, v28, v48
	v_fma_f32 v29, v88, v29, v49
	v_lshlrev_b32_e32 v48, 16, v87
	v_and_b32_e32 v49, 0xffff0000, v87
	v_fma_f32 v30, v88, v30, v48
	v_fma_f32 v31, v88, v31, v49
	global_load_dwordx4 v[80:83], v2, s[6:7] nt
	global_load_dwordx4 v[84:87], v3, s[6:7] nt
	global_load_dword v88, v4, s[12:13]
	s_add_u32 s6, s6, 0x40000
	s_addc_u32 s7, s7, 0
	s_add_u32 s12, s12, 64
	s_addc_u32 s13, s13, 0
	s_waitcnt vmcnt(35)
	v_cvt_pk_bf16_f32 v32, v16, v17
	v_cvt_pk_bf16_f32 v33, v18, v19
	v_cvt_pk_bf16_f32 v34, v20, v21
	v_cvt_pk_bf16_f32 v35, v22, v23
	global_store_dwordx4 v2, v[32:35], s[10:11] nt
	v_cvt_pk_bf16_f32 v36, v24, v25
	v_cvt_pk_bf16_f32 v37, v26, v27
	v_cvt_pk_bf16_f32 v38, v28, v29
	v_cvt_pk_bf16_f32 v39, v30, v31
	global_store_dwordx4 v3, v[36:39], s[10:11] nt
	s_add_u32 s10, s10, 0x40000
	s_addc_u32 s11, s11, 0
	v_lshlrev_b32_e32 v48, 16, v96
	v_and_b32_e32 v49, 0xffff0000, v96
	v_fma_f32 v16, v104, v16, v48
	v_fma_f32 v17, v104, v17, v49
	v_lshlrev_b32_e32 v48, 16, v97
	v_and_b32_e32 v49, 0xffff0000, v97
	v_fma_f32 v18, v104, v18, v48
	v_fma_f32 v19, v104, v19, v49
	v_lshlrev_b32_e32 v48, 16, v98
	v_and_b32_e32 v49, 0xffff0000, v98
	v_fma_f32 v20, v104, v20, v48
	v_fma_f32 v21, v104, v21, v49
	v_lshlrev_b32_e32 v48, 16, v99
	v_and_b32_e32 v49, 0xffff0000, v99
	v_fma_f32 v22, v104, v22, v48
	v_fma_f32 v23, v104, v23, v49
	v_lshlrev_b32_e32 v48, 16, v100
	v_and_b32_e32 v49, 0xffff0000, v100
	v_fma_f32 v24, v104, v24, v48
	v_fma_f32 v25, v104, v25, v49
	v_lshlrev_b32_e32 v48, 16, v101
	v_and_b32_e32 v49, 0xffff0000, v101
	v_fma_f32 v26, v104, v26, v48
	v_fma_f32 v27, v104, v27, v49
	v_lshlrev_b32_e32 v48, 16, v102
	v_and_b32_e32 v49, 0xffff0000, v102
	v_fma_f32 v28, v104, v28, v48
	v_fma_f32 v29, v104, v29, v49
	v_lshlrev_b32_e32 v48, 16, v103
	v_and_b32_e32 v49, 0xffff0000, v103
	v_fma_f32 v30, v104, v30, v48
	v_fma_f32 v31, v104, v31, v49
	global_load_dwordx4 v[96:99], v2, s[6:7] nt
	global_load_dwordx4 v[100:103], v3, s[6:7] nt
	global_load_dword v104, v4, s[12:13]
	s_add_u32 s6, s6, 0x40000
	s_addc_u32 s7, s7, 0
	s_add_u32 s12, s12, 64
	s_addc_u32 s13, s13, 0
	s_waitcnt vmcnt(35)
; __device__ __forceinline__ float bf2f(unsigned h) { return __uint_as_float(h << 16); }
; __device__ __forceinline__ unsigned pk2(float lo, float hi) { return pg8::cvt_pk_bf16(lo, hi); }
; __device__ __forceinline__ void b2_scan(const Ctx& C) {
;     ...
;     B2_LOAD(0, 0);
; #pragma unroll
;     for (int g = 0; g < 8; ++g) {
;         const int cur = g & 1;
;         if (g + 1 < 8) B2_LOAD(g + 1, cur ^ 1);
; #pragma unroll
;         for (int k = 0; k < 4; ++k) {
;             const int c = 4 * g + k;
;             const float dd[8] = {d0[cur][k][0], d0[cur][k][1], d0[cur][k][2], d0[cur][k][3], d1[cur][k][0], d1[cur][k][1], d1[cur][k][2], d1[cur][k][3]};
; #pragma unroll
;             for (int j = 0; j < 2; ++j) {
;                 v4u o; o.x = pk2(run[j][0], run[j][1]); o.y = pk2(run[j][2], run[j][3]); o.z = pk2(run[j][4], run[j][5]); o.w = pk2(run[j][6], run[j][7]);
;                 __builtin_nontemporal_store(o, (v4u*)(base + (size_t)c * cstride + (size_t)j * vstride));
;                 const unsigned lw[4] = {loc[cur][k][j].x, loc[cur][k][j].y, loc[cur][k][j].z, loc[cur][k][j].w};
; #pragma unroll
;                 for (int q = 0; q < 4; ++q) {
;                     run[j][2 * q] = dd[2 * q] * run[j][2 * q] + bf2f(lw[q] & 0xffffu);
;                     run[j][2 * q + 1] = dd[2 * q + 1] * run[j][2 * q + 1] + __uint_as_float(lw[q] & 0xffff0000u);
;                 }
	v_cvt_pk_bf16_f32 v40, v16, v17
	v_cvt_pk_bf16_f32 v41, v18, v19
	v_cvt_pk_bf16_f32 v42, v20, v21
	v_cvt_pk_bf16_f32 v43, v22, v23
	global_store_dwordx4 v2, v[40:43], s[10:11] nt
	v_cvt_pk_bf16_f32 v44, v24, v25
	v_cvt_pk_bf16_f32 v45, v26, v27
	v_cvt_pk_bf16_f32 v46, v28, v29
	v_cvt_pk_bf16_f32 v47, v30, v31
	global_store_dwordx4 v3, v[44:47], s[10:11] nt
	s_add_u32 s10, s10, 0x40000
	s_addc_u32 s11, s11, 0
	v_lshlrev_b32_e32 v48, 16, v112
	v_and_b32_e32 v49, 0xffff0000, v112
	v_fma_f32 v16, v120, v16, v48
	v_fma_f32 v17, v120, v17, v49
	v_lshlrev_b32_e32 v48, 16, v113
	v_and_b32_e32 v49, 0xffff0000, v113
	v_fma_f32 v18, v120, v18, v48
	v_fma_f32 v19, v120, v19, v49
	v_lshlrev_b32_e32 v48, 16, v114
	v_and_b32_e32 v49, 0xffff0000, v114
	v_fma_f32 v20, v120, v20, v48
	v_fma_f32 v21, v120, v21, v49
	v_lshlrev_b32_e32 v48, 16, v115
	v_and_b32_e32 v49, 0xffff0000, v115
	v_fma_f32 v22, v120, v22, v48
	v_fma_f32 v23, v120, v23, v49
	v_lshlrev_b32_e32 v48, 16, v116
	v_and_b32_e32 v49, 0xffff0000, v116
	v_fma_f32 v24, v120, v24, v48
	v_fma_f32 v25, v120, v25, v49
	v_lshlrev_b32_e32 v48, 16, v117
	v_and_b32_e32 v49, 0xffff0000, v117
	v_fma_f32 v26, v120, v26, v48
	v_fma_f32 v27, v120, v27, v49
	v_lshlrev_b32_e32 v48, 16, v118
	v_and_b32_e32 v49, 0xffff0000, v118
	v_fma_f32 v28, v120, v28, v48
	v_fma_f32 v29, v120, v29, v49
	v_lshlrev_b32_e32 v48, 16, v119
	v_and_b32_e32 v49, 0xffff0000, v119
	v_fma_f32 v30, v120, v30, v48
	v_fma_f32 v31, v120, v31, v49
	global_load_dwordx4 v[112:115], v2, s[6:7] nt
	global_load_dwordx4 v[116:119], v3, s[6:7] nt
	global_load_dword v120, v4, s[12:13]
	s_add_u32 s6, s6, 0x40000
	s_addc_u32 s7, s7, 0
	s_add_u32 s12, s12, 64
	s_addc_u32 s13, s13, 0
	s_waitcnt vmcnt(35)
	v_cvt_pk_bf16_f32 v32, v16, v17
	v_cvt_pk_bf16_f32 v33, v18, v19
	v_cvt_pk_bf16_f32 v34, v20, v21
	v_cvt_pk_bf16_f32 v35, v22, v23
	global_store_dwordx4 v2, v[32:35], s[10:11] nt
	v_cvt_pk_bf16_f32 v36, v24, v25
	v_cvt_pk_bf16_f32 v37, v26, v27
	v_cvt_pk_bf16_f32 v38, v28, v29
	v_cvt_pk_bf16_f32 v39, v30, v31
	global_store_dwordx4 v3, v[36:39], s[10:11] nt
	s_add_u32 s10, s10, 0x40000
	s_addc_u32 s11, s11, 0
	v_lshlrev_b32_e32 v48, 16, v128
	v_and_b32_e32 v49, 0xffff0000, v128
	v_fma_f32 v16, v136, v16, v48
	v_fma_f32 v17, v136, v17, v49
	v_lshlrev_b32_e32 v48, 16, v129
	v_and_b32_e32 v49, 0xffff0000, v129
	v_fma_f32 v18, v136, v18, v48
	v_fma_f32 v19, v136, v19, v49
	v_lshlrev_b32_e32 v48, 16, v130
	v_and_b32_e32 v49, 0xffff0000, v130
	v_fma_f32 v20, v136, v20, v48
	v_fma_f32 v21, v136, v21, v49
	v_lshlrev_b32_e32 v48, 16, v131
	v_and_b32_e32 v49, 0xffff0000, v131
	v_fma_f32 v22, v136, v22, v48
	v_fma_f32 v23, v136, v23, v49
	v_lshlrev_b32_e32 v48, 16, v132
	v_and_b32_e32 v49, 0xffff0000, v132
	v_fma_f32 v24, v136, v24, v48
	v_fma_f32 v25, v136, v25, v49
	v_lshlrev_b32_e32 v48, 16, v133
	v_and_b32_e32 v49, 0xffff0000, v133
	v_fma_f32 v26, v136, v26, v48
	v_fma_f32 v27, v136, v27, v49
	v_lshlrev_b32_e32 v48, 16, v134
	v_and_b32_e32 v49, 0xffff0000, v134
	v_fma_f32 v28, v136, v28, v48
	v_fma_f32 v29, v136, v29, v49
	v_lshlrev_b32_e32 v48, 16, v135
	v_and_b32_e32 v49, 0xffff0000, v135
	v_fma_f32 v30, v136, v30, v48
	v_fma_f32 v31, v136, v31, v49
	global_load_dwordx4 v[128:131], v2, s[6:7] nt
	global_load_dwordx4 v[132:135], v3, s[6:7] nt
	global_load_dword v136, v4, s[12:13]
	s_add_u32 s6, s6, 0x40000
	s_addc_u32 s7, s7, 0
	s_add_u32 s12, s12, 64
	s_addc_u32 s13, s13, 0
	s_waitcnt vmcnt(35)
	v_cvt_pk_bf16_f32 v40, v16, v17
	v_cvt_pk_bf16_f32 v41, v18, v19
	v_cvt_pk_bf16_f32 v42, v20, v21
	v_cvt_pk_bf16_f32 v43, v22, v23
	global_store_dwordx4 v2, v[40:43], s[10:11] nt
	v_cvt_pk_bf16_f32 v44, v24, v25
	v_cvt_pk_bf16_f32 v45, v26, v27
	v_cvt_pk_bf16_f32 v46, v28, v29
	v_cvt_pk_bf16_f32 v47, v30, v31
	global_store_dwordx4 v3, v[44:47], s[10:11] nt
	s_add_u32 s10, s10, 0x40000
	s_addc_u32 s11, s11, 0
	v_lshlrev_b32_e32 v48, 16, v144
	v_and_b32_e32 v49, 0xffff0000, v144
	v_fma_f32 v16, v152, v16, v48
	v_fma_f32 v17, v152, v17, v49
	v_lshlrev_b32_e32 v48, 16, v145
	v_and_b32_e32 v49, 0xffff0000, v145
	v_fma_f32 v18, v152, v18, v48
	v_fma_f32 v19, v152, v19, v49
	v_lshlrev_b32_e32 v48, 16, v146
	v_and_b32_e32 v49, 0xffff0000, v146
	v_fma_f32 v20, v152, v20, v48
	v_fma_f32 v21, v152, v21, v49
	v_lshlrev_b32_e32 v48, 16, v147
	v_and_b32_e32 v49, 0xffff0000, v147
	v_fma_f32 v22, v152, v22, v48
	v_fma_f32 v23, v152, v23, v49
	v_lshlrev_b32_e32 v48, 16, v148
	v_and_b32_e32 v49, 0xffff0000, v148
	v_fma_f32 v24, v152, v24, v48
	v_fma_f32 v25, v152, v25, v49
	v_lshlrev_b32_e32 v48, 16, v149
	v_and_b32_e32 v49, 0xffff0000, v149
	v_fma_f32 v26, v152, v26, v48
	v_fma_f32 v27, v152, v27, v49
	v_lshlrev_b32_e32 v48, 16, v150
	v_and_b32_e32 v49, 0xffff0000, v150
	v_fma_f32 v28, v152, v28, v48
	v_fma_f32 v29, v152, v29, v49
	v_lshlrev_b32_e32 v48, 16, v151
	v_and_b32_e32 v49, 0xffff0000, v151
	v_fma_f32 v30, v152, v30, v48
	v_fma_f32 v31, v152, v31, v49
	global_load_dwordx4 v[144:147], v2, s[6:7] nt
	global_load_dwordx4 v[148:151], v3, s[6:7] nt
	global_load_dword v152, v4, s[12:13]
	s_add_u32 s6, s6, 0x40000
	s_addc_u32 s7, s7, 0
	s_add_u32 s12, s12, 64
	s_addc_u32 s13, s13, 0
	s_waitcnt vmcnt(35)
; __device__ __forceinline__ float bf2f(unsigned h) { return __uint_as_float(h << 16); }
; __device__ __forceinline__ unsigned pk2(float lo, float hi) { return pg8::cvt_pk_bf16(lo, hi); }
; __device__ __forceinline__ void b2_scan(const Ctx& C) {
;     ...
;     B2_LOAD(0, 0);
; #pragma unroll
;     for (int g = 0; g < 8; ++g) {
;         const int cur = g & 1;
;         if (g + 1 < 8) B2_LOAD(g + 1, cur ^ 1);
; #pragma unroll
;         for (int k = 0; k < 4; ++k) {
;             const int c = 4 * g + k;
;             const float dd[8] = {d0[cur][k][0], d0[cur][k][1], d0[cur][k][2], d0[cur][k][3], d1[cur][k][0], d1[cur][k][1], d1[cur][k][2], d1[cur][k][3]};
; #pragma unroll
;             for (int j = 0; j < 2; ++j) {
;                 v4u o; o.x = pk2(run[j][0], run[j][1]); o.y = pk2(run[j][2], run[j][3]); o.z = pk2(run[j][4], run[j][5]); o.w = pk2(run[j][6], run[j][7]);
;                 __builtin_nontemporal_store(o, (v4u*)(base + (size_t)c * cstride + (size_t)j * vstride));
;                 const unsigned lw[4] = {loc[cur][k][j].x, loc[cur][k][j].y, loc[cur][k][j].z, loc[cur][k][j].w};
; #pragma unroll
;                 for (int q = 0; q < 4; ++q) {
;                     run[j][2 * q] = dd[2 * q] * run[j][2 * q] + bf2f(lw[q] & 0xffffu);
;                     run[j][2 * q + 1] = dd[2 * q + 1] * run[j][2 * q + 1] + __uint_as_float(lw[q] & 0xffff0000u);
;                 }
	v_cvt_pk_bf16_f32 v32, v16, v17
	v_cvt_pk_bf16_f32 v33, v18, v19
	v_cvt_pk_bf16_f32 v34, v20, v21
	v_cvt_pk_bf16_f32 v35, v22, v23
	global_store_dwordx4 v2, v[32:35], s[10:11] nt
	v_cvt_pk_bf16_f32 v36, v24, v25
	v_cvt_pk_bf16_f32 v37, v26, v27
	v_cvt_pk_bf16_f32 v38, v28, v29
	v_cvt_pk_bf16_f32 v39, v30, v31
	global_store_dwordx4 v3, v[36:39], s[10:11] nt
	s_add_u32 s10, s10, 0x40000
	s_addc_u32 s11, s11, 0
	v_lshlrev_b32_e32 v48, 16, v160
	v_and_b32_e32 v49, 0xffff0000, v160
	v_fma_f32 v16, v168, v16, v48
	v_fma_f32 v17, v168, v17, v49
	v_lshlrev_b32_e32 v48, 16, v161
	v_and_b32_e32 v49, 0xffff0000, v161
	v_fma_f32 v18, v168, v18, v48
	v_fma_f32 v19, v168, v19, v49
	v_lshlrev_b32_e32 v48, 16, v162
	v_and_b32_e32 v49, 0xffff0000, v162
	v_fma_f32 v20, v168, v20, v48
	v_fma_f32 v21, v168, v21, v49
	v_lshlrev_b32_e32 v48, 16, v163
	v_and_b32_e32 v49, 0xffff0000, v163
	v_fma_f32 v22, v168, v22, v48
	v_fma_f32 v23, v168, v23, v49
	v_lshlrev_b32_e32 v48, 16, v164
	v_and_b32_e32 v49, 0xffff0000, v164
	v_fma_f32 v24, v168, v24, v48
	v_fma_f32 v25, v168, v25, v49
	v_lshlrev_b32_e32 v48, 16, v165
	v_and_b32_e32 v49, 0xffff0000, v165
	v_fma_f32 v26, v168, v26, v48
	v_fma_f32 v27, v168, v27, v49
	v_lshlrev_b32_e32 v48, 16, v166
	v_and_b32_e32 v49, 0xffff0000, v166
	v_fma_f32 v28, v168, v28, v48
	v_fma_f32 v29, v168, v29, v49
	v_lshlrev_b32_e32 v48, 16, v167
	v_and_b32_e32 v49, 0xffff0000, v167
	v_fma_f32 v30, v168, v30, v48
	v_fma_f32 v31, v168, v31, v49
	global_load_dwordx4 v[160:163], v2, s[6:7] nt
	global_load_dwordx4 v[164:167], v3, s[6:7] nt
	global_load_dword v168, v4, s[12:13]
	s_add_u32 s6, s6, 0x40000
	s_addc_u32 s7, s7, 0
	s_add_u32 s12, s12, 64
	s_addc_u32 s13, s13, 0
	s_waitcnt vmcnt(35)
	v_cvt_pk_bf16_f32 v40, v16, v17
	v_cvt_pk_bf16_f32 v41, v18, v19
	v_cvt_pk_bf16_f32 v42, v20, v21
	v_cvt_pk_bf16_f32 v43, v22, v23
	global_store_dwordx4 v2, v[40:43], s[10:11] nt
	v_cvt_pk_bf16_f32 v44, v24, v25
	v_cvt_pk_bf16_f32 v45, v26, v27
	v_cvt_pk_bf16_f32 v46, v28, v29
	v_cvt_pk_bf16_f32 v47, v30, v31
	global_store_dwordx4 v3, v[44:47], s[10:11] nt
	s_add_u32 s10, s10, 0x40000
	s_addc_u32 s11, s11, 0
	v_lshlrev_b32_e32 v48, 16, v176
	v_and_b32_e32 v49, 0xffff0000, v176
	v_fma_f32 v16, v184, v16, v48
	v_fma_f32 v17, v184, v17, v49
	v_lshlrev_b32_e32 v48, 16, v177
	v_and_b32_e32 v49, 0xffff0000, v177
	v_fma_f32 v18, v184, v18, v48
	v_fma_f32 v19, v184, v19, v49
	v_lshlrev_b32_e32 v48, 16, v178
	v_and_b32_e32 v49, 0xffff0000, v178
	v_fma_f32 v20, v184, v20, v48
	v_fma_f32 v21, v184, v21, v49
	v_lshlrev_b32_e32 v48, 16, v179
	v_and_b32_e32 v49, 0xffff0000, v179
	v_fma_f32 v22, v184, v22, v48
	v_fma_f32 v23, v184, v23, v49
	v_lshlrev_b32_e32 v48, 16, v180
	v_and_b32_e32 v49, 0xffff0000, v180
	v_fma_f32 v24, v184, v24, v48
	v_fma_f32 v25, v184, v25, v49
	v_lshlrev_b32_e32 v48, 16, v181
	v_and_b32_e32 v49, 0xffff0000, v181
	v_fma_f32 v26, v184, v26, v48
	v_fma_f32 v27, v184, v27, v49
	v_lshlrev_b32_e32 v48, 16, v182
	v_and_b32_e32 v49, 0xffff0000, v182
	v_fma_f32 v28, v184, v28, v48
	v_fma_f32 v29, v184, v29, v49
	v_lshlrev_b32_e32 v48, 16, v183
	v_and_b32_e32 v49, 0xffff0000, v183
	v_fma_f32 v30, v184, v30, v48
	v_fma_f32 v31, v184, v31, v49
	global_load_dwordx4 v[176:179], v2, s[6:7] nt
	global_load_dwordx4 v[180:183], v3, s[6:7] nt
	global_load_dword v184, v4, s[12:13]
	s_add_u32 s6, s6, 0x40000
	s_addc_u32 s7, s7, 0
	s_add_u32 s12, s12, 64
	s_addc_u32 s13, s13, 0
	s_waitcnt vmcnt(35)
	v_cvt_pk_bf16_f32 v32, v16, v17
	v_cvt_pk_bf16_f32 v33, v18, v19
	v_cvt_pk_bf16_f32 v34, v20, v21
	v_cvt_pk_bf16_f32 v35, v22, v23
	global_store_dwordx4 v2, v[32:35], s[10:11] nt
	v_cvt_pk_bf16_f32 v36, v24, v25
	v_cvt_pk_bf16_f32 v37, v26, v27
	v_cvt_pk_bf16_f32 v38, v28, v29
	v_cvt_pk_bf16_f32 v39, v30, v31
	global_store_dwordx4 v3, v[36:39], s[10:11] nt
	s_add_u32 s10, s10, 0x40000
	s_addc_u32 s11, s11, 0
	v_lshlrev_b32_e32 v48, 16, v64
	v_and_b32_e32 v49, 0xffff0000, v64
	v_fma_f32 v16, v72, v16, v48
	v_fma_f32 v17, v72, v17, v49
	v_lshlrev_b32_e32 v48, 16, v65
	v_and_b32_e32 v49, 0xffff0000, v65
	v_fma_f32 v18, v72, v18, v48
	v_fma_f32 v19, v72, v19, v49
	v_lshlrev_b32_e32 v48, 16, v66
	v_and_b32_e32 v49, 0xffff0000, v66
	v_fma_f32 v20, v72, v20, v48
	v_fma_f32 v21, v72, v21, v49
	v_lshlrev_b32_e32 v48, 16, v67
	v_and_b32_e32 v49, 0xffff0000, v67
	v_fma_f32 v22, v72, v22, v48
	v_fma_f32 v23, v72, v23, v49
	v_lshlrev_b32_e32 v48, 16, v68
	v_and_b32_e32 v49, 0xffff0000, v68
	v_fma_f32 v24, v72, v24, v48
	v_fma_f32 v25, v72, v25, v49
	v_lshlrev_b32_e32 v48, 16, v69
	v_and_b32_e32 v49, 0xffff0000, v69
	v_fma_f32 v26, v72, v26, v48
	v_fma_f32 v27, v72, v27, v49
	v_lshlrev_b32_e32 v48, 16, v70
	v_and_b32_e32 v49, 0xffff0000, v70
	v_fma_f32 v28, v72, v28, v48
	v_fma_f32 v29, v72, v29, v49
	v_lshlrev_b32_e32 v48, 16, v71
	v_and_b32_e32 v49, 0xffff0000, v71
	v_fma_f32 v30, v72, v30, v48
	v_fma_f32 v31, v72, v31, v49
	global_load_dwordx4 v[64:67], v2, s[6:7] nt
	global_load_dwordx4 v[68:71], v3, s[6:7] nt
	global_load_dword v72, v4, s[12:13]
	s_add_u32 s6, s6, 0x40000
	s_addc_u32 s7, s7, 0
	s_add_u32 s12, s12, 64
	s_addc_u32 s13, s13, 0
	s_waitcnt vmcnt(35)
; __device__ __forceinline__ float bf2f(unsigned h) { return __uint_as_float(h << 16); }
; __device__ __forceinline__ unsigned pk2(float lo, float hi) { return pg8::cvt_pk_bf16(lo, hi); }
; __device__ __forceinline__ void b2_scan(const Ctx& C) {
;     ...
;     B2_LOAD(0, 0);
; #pragma unroll
;     for (int g = 0; g < 8; ++g) {
;         const int cur = g & 1;
;         if (g + 1 < 8) B2_LOAD(g + 1, cur ^ 1);
; #pragma unroll
;         for (int k = 0; k < 4; ++k) {
;             const int c = 4 * g + k;
;             const float dd[8] = {d0[cur][k][0], d0[cur][k][1], d0[cur][k][2], d0[cur][k][3], d1[cur][k][0], d1[cur][k][1], d1[cur][k][2], d1[cur][k][3]};
; #pragma unroll
;             for (int j = 0; j < 2; ++j) {
;                 v4u o; o.x = pk2(run[j][0], run[j][1]); o.y = pk2(run[j][2], run[j][3]); o.z = pk2(run[j][4], run[j][5]); o.w = pk2(run[j][6], run[j][7]);
;                 __builtin_nontemporal_store(o, (v4u*)(base + (size_t)c * cstride + (size_t)j * vstride));
;                 const unsigned lw[4] = {loc[cur][k][j].x, loc[cur][k][j].y, loc[cur][k][j].z, loc[cur][k][j].w};
; #pragma unroll
;                 for (int q = 0; q < 4; ++q) {
;                     run[j][2 * q] = dd[2 * q] * run[j][2 * q] + bf2f(lw[q] & 0xffffu);
;                     run[j][2 * q + 1] = dd[2 * q + 1] * run[j][2 * q + 1] + __uint_as_float(lw[q] & 0xffff0000u);
;                 }
	v_cvt_pk_bf16_f32 v40, v16, v17
	v_cvt_pk_bf16_f32 v41, v18, v19
	v_cvt_pk_bf16_f32 v42, v20, v21
	v_cvt_pk_bf16_f32 v43, v22, v23
	global_store_dwordx4 v2, v[40:43], s[10:11] nt
	v_cvt_pk_bf16_f32 v44, v24, v25
	v_cvt_pk_bf16_f32 v45, v26, v27
	v_cvt_pk_bf16_f32 v46, v28, v29
	v_cvt_pk_bf16_f32 v47, v30, v31
	global_store_dwordx4 v3, v[44:47], s[10:11] nt
	s_add_u32 s10, s10, 0x40000
	s_addc_u32 s11, s11, 0
	v_lshlrev_b32_e32 v48, 16, v80
	v_and_b32_e32 v49, 0xffff0000, v80
	v_fma_f32 v16, v88, v16, v48
	v_fma_f32 v17, v88, v17, v49
	v_lshlrev_b32_e32 v48, 16, v81
	v_and_b32_e32 v49, 0xffff0000, v81
	v_fma_f32 v18, v88, v18, v48
	v_fma_f32 v19, v88, v19, v49
	v_lshlrev_b32_e32 v48, 16, v82
	v_and_b32_e32 v49, 0xffff0000, v82
	v_fma_f32 v20, v88, v20, v48
	v_fma_f32 v21, v88, v21, v49
	v_lshlrev_b32_e32 v48, 16, v83
	v_and_b32_e32 v49, 0xffff0000, v83
	v_fma_f32 v22, v88, v22, v48
	v_fma_f32 v23, v88, v23, v49
	v_lshlrev_b32_e32 v48, 16, v84
	v_and_b32_e32 v49, 0xffff0000, v84
	v_fma_f32 v24, v88, v24, v48
	v_fma_f32 v25, v88, v25, v49
	v_lshlrev_b32_e32 v48, 16, v85
	v_and_b32_e32 v49, 0xffff0000, v85
	v_fma_f32 v26, v88, v26, v48
	v_fma_f32 v27, v88, v27, v49
	v_lshlrev_b32_e32 v48, 16, v86
	v_and_b32_e32 v49, 0xffff0000, v86
	v_fma_f32 v28, v88, v28, v48
	v_fma_f32 v29, v88, v29, v49
	v_lshlrev_b32_e32 v48, 16, v87
	v_and_b32_e32 v49, 0xffff0000, v87
	v_fma_f32 v30, v88, v30, v48
	v_fma_f32 v31, v88, v31, v49
	global_load_dwordx4 v[80:83], v2, s[6:7] nt
	global_load_dwordx4 v[84:87], v3, s[6:7] nt
	global_load_dword v88, v4, s[12:13]
	s_add_u32 s6, s6, 0x40000
	s_addc_u32 s7, s7, 0
	s_add_u32 s12, s12, 64
	s_addc_u32 s13, s13, 0
	s_waitcnt vmcnt(35)
	v_cvt_pk_bf16_f32 v32, v16, v17
	v_cvt_pk_bf16_f32 v33, v18, v19
	v_cvt_pk_bf16_f32 v34, v20, v21
	v_cvt_pk_bf16_f32 v35, v22, v23
	global_store_dwordx4 v2, v[32:35], s[10:11] nt
	v_cvt_pk_bf16_f32 v36, v24, v25
	v_cvt_pk_bf16_f32 v37, v26, v27
	v_cvt_pk_bf16_f32 v38, v28, v29
	v_cvt_pk_bf16_f32 v39, v30, v31
	global_store_dwordx4 v3, v[36:39], s[10:11] nt
	s_add_u32 s10, s10, 0x40000
	s_addc_u32 s11, s11, 0
	v_lshlrev_b32_e32 v48, 16, v96
	v_and_b32_e32 v49, 0xffff0000, v96
	v_fma_f32 v16, v104, v16, v48
	v_fma_f32 v17, v104, v17, v49
	v_lshlrev_b32_e32 v48, 16, v97
	v_and_b32_e32 v49, 0xffff0000, v97
	v_fma_f32 v18, v104, v18, v48
	v_fma_f32 v19, v104, v19, v49
	v_lshlrev_b32_e32 v48, 16, v98
	v_and_b32_e32 v49, 0xffff0000, v98
	v_fma_f32 v20, v104, v20, v48
	v_fma_f32 v21, v104, v21, v49
	v_lshlrev_b32_e32 v48, 16, v99
	v_and_b32_e32 v49, 0xffff0000, v99
	v_fma_f32 v22, v104, v22, v48
	v_fma_f32 v23, v104, v23, v49
	v_lshlrev_b32_e32 v48, 16, v100
	v_and_b32_e32 v49, 0xffff0000, v100
	v_fma_f32 v24, v104, v24, v48
	v_fma_f32 v25, v104, v25, v49
	v_lshlrev_b32_e32 v48, 16, v101
	v_and_b32_e32 v49, 0xffff0000, v101
	v_fma_f32 v26, v104, v26, v48
	v_fma_f32 v27, v104, v27, v49
	v_lshlrev_b32_e32 v48, 16, v102
	v_and_b32_e32 v49, 0xffff0000, v102
	v_fma_f32 v28, v104, v28, v48
	v_fma_f32 v29, v104, v29, v49
	v_lshlrev_b32_e32 v48, 16, v103
	v_and_b32_e32 v49, 0xffff0000, v103
	v_fma_f32 v30, v104, v30, v48
	v_fma_f32 v31, v104, v31, v49
	global_load_dwordx4 v[96:99], v2, s[6:7] nt
	global_load_dwordx4 v[100:103], v3, s[6:7] nt
	global_load_dword v104, v4, s[12:13]
	s_add_u32 s6, s6, 0x40000
	s_addc_u32 s7, s7, 0
	s_add_u32 s12, s12, 64
	s_addc_u32 s13, s13, 0
	s_waitcnt vmcnt(35)
	v_cvt_pk_bf16_f32 v40, v16, v17
	v_cvt_pk_bf16_f32 v41, v18, v19
	v_cvt_pk_bf16_f32 v42, v20, v21
	v_cvt_pk_bf16_f32 v43, v22, v23
	global_store_dwordx4 v2, v[40:43], s[10:11] nt
	v_cvt_pk_bf16_f32 v44, v24, v25
	v_cvt_pk_bf16_f32 v45, v26, v27
	v_cvt_pk_bf16_f32 v46, v28, v29
	v_cvt_pk_bf16_f32 v47, v30, v31
	global_store_dwordx4 v3, v[44:47], s[10:11] nt
	s_add_u32 s10, s10, 0x40000
	s_addc_u32 s11, s11, 0
	v_lshlrev_b32_e32 v48, 16, v112
	v_and_b32_e32 v49, 0xffff0000, v112
	v_fma_f32 v16, v120, v16, v48
	v_fma_f32 v17, v120, v17, v49
	v_lshlrev_b32_e32 v48, 16, v113
	v_and_b32_e32 v49, 0xffff0000, v113
	v_fma_f32 v18, v120, v18, v48
	v_fma_f32 v19, v120, v19, v49
	v_lshlrev_b32_e32 v48, 16, v114
	v_and_b32_e32 v49, 0xffff0000, v114
	v_fma_f32 v20, v120, v20, v48
	v_fma_f32 v21, v120, v21, v49
	v_lshlrev_b32_e32 v48, 16, v115
	v_and_b32_e32 v49, 0xffff0000, v115
	v_fma_f32 v22, v120, v22, v48
	v_fma_f32 v23, v120, v23, v49
	v_lshlrev_b32_e32 v48, 16, v116
	v_and_b32_e32 v49, 0xffff0000, v116
	v_fma_f32 v24, v120, v24, v48
	v_fma_f32 v25, v120, v25, v49
	v_lshlrev_b32_e32 v48, 16, v117
	v_and_b32_e32 v49, 0xffff0000, v117
	v_fma_f32 v26, v120, v26, v48
	v_fma_f32 v27, v120, v27, v49
	v_lshlrev_b32_e32 v48, 16, v118
	v_and_b32_e32 v49, 0xffff0000, v118
	v_fma_f32 v28, v120, v28, v48
	v_fma_f32 v29, v120, v29, v49
	v_lshlrev_b32_e32 v48, 16, v119
	v_and_b32_e32 v49, 0xffff0000, v119
	v_fma_f32 v30, v120, v30, v48
	v_fma_f32 v31, v120, v31, v49
	global_load_dwordx4 v[112:115], v2, s[6:7] nt
	global_load_dwordx4 v[116:119], v3, s[6:7] nt
	global_load_dword v120, v4, s[12:13]
	s_add_u32 s6, s6, 0x40000
	s_addc_u32 s7, s7, 0
	s_add_u32 s12, s12, 64
	s_addc_u32 s13, s13, 0
	s_waitcnt vmcnt(35)
; __device__ __forceinline__ float bf2f(unsigned h) { return __uint_as_float(h << 16); }
; __device__ __forceinline__ unsigned pk2(float lo, float hi) { return pg8::cvt_pk_bf16(lo, hi); }
; __device__ __forceinline__ void b2_scan(const Ctx& C) {
;     ...
;     B2_LOAD(0, 0);
; #pragma unroll
;     for (int g = 0; g < 8; ++g) {
;         const int cur = g & 1;
;         if (g + 1 < 8) B2_LOAD(g + 1, cur ^ 1);
; #pragma unroll
;         for (int k = 0; k < 4; ++k) {
;             const int c = 4 * g + k;
;             const float dd[8] = {d0[cur][k][0], d0[cur][k][1], d0[cur][k][2], d0[cur][k][3], d1[cur][k][0], d1[cur][k][1], d1[cur][k][2], d1[cur][k][3]};
; #pragma unroll
;             for (int j = 0; j < 2; ++j) {
;                 v4u o; o.x = pk2(run[j][0], run[j][1]); o.y = pk2(run[j][2], run[j][3]); o.z = pk2(run[j][4], run[j][5]); o.w = pk2(run[j][6], run[j][7]);
;                 __builtin_nontemporal_store(o, (v4u*)(base + (size_t)c * cstride + (size_t)j * vstride));
;                 const unsigned lw[4] = {loc[cur][k][j].x, loc[cur][k][j].y, loc[cur][k][j].z, loc[cur][k][j].w};
; #pragma unroll
;                 for (int q = 0; q < 4; ++q) {
;                     run[j][2 * q] = dd[2 * q] * run[j][2 * q] + bf2f(lw[q] & 0xffffu);
;                     run[j][2 * q + 1] = dd[2 * q + 1] * run[j][2 * q + 1] + __uint_as_float(lw[q] & 0xffff0000u);
;                 }
	v_cvt_pk_bf16_f32 v32, v16, v17
	v_cvt_pk_bf16_f32 v33, v18, v19
	v_cvt_pk_bf16_f32 v34, v20, v21
	v_cvt_pk_bf16_f32 v35, v22, v23
	global_store_dwordx4 v2, v[32:35], s[10:11] nt
	v_cvt_pk_bf16_f32 v36, v24, v25
	v_cvt_pk_bf16_f32 v37, v26, v27
	v_cvt_pk_bf16_f32 v38, v28, v29
	v_cvt_pk_bf16_f32 v39, v30, v31
	global_store_dwordx4 v3, v[36:39], s[10:11] nt
	s_add_u32 s10, s10, 0x40000
	s_addc_u32 s11, s11, 0
	v_lshlrev_b32_e32 v48, 16, v128
	v_and_b32_e32 v49, 0xffff0000, v128
	v_fma_f32 v16, v136, v16, v48
	v_fma_f32 v17, v136, v17, v49
	v_lshlrev_b32_e32 v48, 16, v129
	v_and_b32_e32 v49, 0xffff0000, v129
	v_fma_f32 v18, v136, v18, v48
	v_fma_f32 v19, v136, v19, v49
	v_lshlrev_b32_e32 v48, 16, v130
	v_and_b32_e32 v49, 0xffff0000, v130
	v_fma_f32 v20, v136, v20, v48
	v_fma_f32 v21, v136, v21, v49
	v_lshlrev_b32_e32 v48, 16, v131
	v_and_b32_e32 v49, 0xffff0000, v131
	v_fma_f32 v22, v136, v22, v48
	v_fma_f32 v23, v136, v23, v49
	v_lshlrev_b32_e32 v48, 16, v132
	v_and_b32_e32 v49, 0xffff0000, v132
	v_fma_f32 v24, v136, v24, v48
	v_fma_f32 v25, v136, v25, v49
	v_lshlrev_b32_e32 v48, 16, v133
	v_and_b32_e32 v49, 0xffff0000, v133
	v_fma_f32 v26, v136, v26, v48
	v_fma_f32 v27, v136, v27, v49
	v_lshlrev_b32_e32 v48, 16, v134
	v_and_b32_e32 v49, 0xffff0000, v134
	v_fma_f32 v28, v136, v28, v48
	v_fma_f32 v29, v136, v29, v49
	v_lshlrev_b32_e32 v48, 16, v135
	v_and_b32_e32 v49, 0xffff0000, v135
	v_fma_f32 v30, v136, v30, v48
	v_fma_f32 v31, v136, v31, v49
	global_load_dwordx4 v[128:131], v2, s[6:7] nt
	global_load_dwordx4 v[132:135], v3, s[6:7] nt
	global_load_dword v136, v4, s[12:13]
	s_add_u32 s6, s6, 0x40000
	s_addc_u32 s7, s7, 0
	s_add_u32 s12, s12, 64
	s_addc_u32 s13, s13, 0
	s_waitcnt vmcnt(35)
	v_cvt_pk_bf16_f32 v40, v16, v17
	v_cvt_pk_bf16_f32 v41, v18, v19
	v_cvt_pk_bf16_f32 v42, v20, v21
	v_cvt_pk_bf16_f32 v43, v22, v23
	global_store_dwordx4 v2, v[40:43], s[10:11] nt
	v_cvt_pk_bf16_f32 v44, v24, v25
	v_cvt_pk_bf16_f32 v45, v26, v27
	v_cvt_pk_bf16_f32 v46, v28, v29
	v_cvt_pk_bf16_f32 v47, v30, v31
	global_store_dwordx4 v3, v[44:47], s[10:11] nt
	s_add_u32 s10, s10, 0x40000
	s_addc_u32 s11, s11, 0
	v_lshlrev_b32_e32 v48, 16, v144
	v_and_b32_e32 v49, 0xffff0000, v144
	v_fma_f32 v16, v152, v16, v48
	v_fma_f32 v17, v152, v17, v49
	v_lshlrev_b32_e32 v48, 16, v145
	v_and_b32_e32 v49, 0xffff0000, v145
	v_fma_f32 v18, v152, v18, v48
	v_fma_f32 v19, v152, v19, v49
	v_lshlrev_b32_e32 v48, 16, v146
	v_and_b32_e32 v49, 0xffff0000, v146
	v_fma_f32 v20, v152, v20, v48
	v_fma_f32 v21, v152, v21, v49
	v_lshlrev_b32_e32 v48, 16, v147
	v_and_b32_e32 v49, 0xffff0000, v147
	v_fma_f32 v22, v152, v22, v48
	v_fma_f32 v23, v152, v23, v49
	v_lshlrev_b32_e32 v48, 16, v148
	v_and_b32_e32 v49, 0xffff0000, v148
	v_fma_f32 v24, v152, v24, v48
	v_fma_f32 v25, v152, v25, v49
	v_lshlrev_b32_e32 v48, 16, v149
	v_and_b32_e32 v49, 0xffff0000, v149
	v_fma_f32 v26, v152, v26, v48
	v_fma_f32 v27, v152, v27, v49
	v_lshlrev_b32_e32 v48, 16, v150
	v_and_b32_e32 v49, 0xffff0000, v150
	v_fma_f32 v28, v152, v28, v48
	v_fma_f32 v29, v152, v29, v49
	v_lshlrev_b32_e32 v48, 16, v151
	v_and_b32_e32 v49, 0xffff0000, v151
	v_fma_f32 v30, v152, v30, v48
	v_fma_f32 v31, v152, v31, v49
	global_load_dwordx4 v[144:147], v2, s[6:7] nt
	global_load_dwordx4 v[148:151], v3, s[6:7] nt
	global_load_dword v152, v4, s[12:13]
	s_add_u32 s6, s6, 0x40000
	s_addc_u32 s7, s7, 0
	s_add_u32 s12, s12, 64
	s_addc_u32 s13, s13, 0
	s_waitcnt vmcnt(35)
	v_cvt_pk_bf16_f32 v32, v16, v17
	v_cvt_pk_bf16_f32 v33, v18, v19
	v_cvt_pk_bf16_f32 v34, v20, v21
	v_cvt_pk_bf16_f32 v35, v22, v23
	global_store_dwordx4 v2, v[32:35], s[10:11] nt
	v_cvt_pk_bf16_f32 v36, v24, v25
	v_cvt_pk_bf16_f32 v37, v26, v27
	v_cvt_pk_bf16_f32 v38, v28, v29
	v_cvt_pk_bf16_f32 v39, v30, v31
	global_store_dwordx4 v3, v[36:39], s[10:11] nt
	s_add_u32 s10, s10, 0x40000
	s_addc_u32 s11, s11, 0
	v_lshlrev_b32_e32 v48, 16, v160
	v_and_b32_e32 v49, 0xffff0000, v160
	v_fma_f32 v16, v168, v16, v48
	v_fma_f32 v17, v168, v17, v49
	v_lshlrev_b32_e32 v48, 16, v161
	v_and_b32_e32 v49, 0xffff0000, v161
	v_fma_f32 v18, v168, v18, v48
	v_fma_f32 v19, v168, v19, v49
	v_lshlrev_b32_e32 v48, 16, v162
	v_and_b32_e32 v49, 0xffff0000, v162
	v_fma_f32 v20, v168, v20, v48
	v_fma_f32 v21, v168, v21, v49
	v_lshlrev_b32_e32 v48, 16, v163
	v_and_b32_e32 v49, 0xffff0000, v163
	v_fma_f32 v22, v168, v22, v48
	v_fma_f32 v23, v168, v23, v49
	v_lshlrev_b32_e32 v48, 16, v164
	v_and_b32_e32 v49, 0xffff0000, v164
	v_fma_f32 v24, v168, v24, v48
	v_fma_f32 v25, v168, v25, v49
	v_lshlrev_b32_e32 v48, 16, v165
	v_and_b32_e32 v49, 0xffff0000, v165
	v_fma_f32 v26, v168, v26, v48
	v_fma_f32 v27, v168, v27, v49
	v_lshlrev_b32_e32 v48, 16, v166
	v_and_b32_e32 v49, 0xffff0000, v166
	v_fma_f32 v28, v168, v28, v48
	v_fma_f32 v29, v168, v29, v49
	v_lshlrev_b32_e32 v48, 16, v167
	v_and_b32_e32 v49, 0xffff0000, v167
	v_fma_f32 v30, v168, v30, v48
	v_fma_f32 v31, v168, v31, v49
	global_load_dwordx4 v[160:163], v2, s[6:7] nt
	global_load_dwordx4 v[164:167], v3, s[6:7] nt
	global_load_dword v168, v4, s[12:13]
	s_add_u32 s6, s6, 0x40000
	s_addc_u32 s7, s7, 0
	s_add_u32 s12, s12, 64
	s_addc_u32 s13, s13, 0
	s_waitcnt vmcnt(35)
; __device__ __forceinline__ float bf2f(unsigned h) { return __uint_as_float(h << 16); }
; __device__ __forceinline__ unsigned pk2(float lo, float hi) { return pg8::cvt_pk_bf16(lo, hi); }
; __device__ __forceinline__ void b2_scan(const Ctx& C) {
;     ...
;     B2_LOAD(0, 0);
; #pragma unroll
;     for (int g = 0; g < 8; ++g) {
;         const int cur = g & 1;
;         if (g + 1 < 8) B2_LOAD(g + 1, cur ^ 1);
; #pragma unroll
;         for (int k = 0; k < 4; ++k) {
;             const int c = 4 * g + k;
;             const float dd[8] = {d0[cur][k][0], d0[cur][k][1], d0[cur][k][2], d0[cur][k][3], d1[cur][k][0], d1[cur][k][1], d1[cur][k][2], d1[cur][k][3]};
; #pragma unroll
;             for (int j = 0; j < 2; ++j) {
;                 v4u o; o.x = pk2(run[j][0], run[j][1]); o.y = pk2(run[j][2], run[j][3]); o.z = pk2(run[j][4], run[j][5]); o.w = pk2(run[j][6], run[j][7]);
;                 __builtin_nontemporal_store(o, (v4u*)(base + (size_t)c * cstride + (size_t)j * vstride));
;                 const unsigned lw[4] = {loc[cur][k][j].x, loc[cur][k][j].y, loc[cur][k][j].z, loc[cur][k][j].w};
; #pragma unroll
;                 for (int q = 0; q < 4; ++q) {
;                     run[j][2 * q] = dd[2 * q] * run[j][2 * q] + bf2f(lw[q] & 0xffffu);
;                     run[j][2 * q + 1] = dd[2 * q + 1] * run[j][2 * q + 1] + __uint_as_float(lw[q] & 0xffff0000u);
;                 }
	v_cvt_pk_bf16_f32 v40, v16, v17
	v_cvt_pk_bf16_f32 v41, v18, v19
	v_cvt_pk_bf16_f32 v42, v20, v21
	v_cvt_pk_bf16_f32 v43, v22, v23
	global_store_dwordx4 v2, v[40:43], s[10:11] nt
	v_cvt_pk_bf16_f32 v44, v24, v25
	v_cvt_pk_bf16_f32 v45, v26, v27
	v_cvt_pk_bf16_f32 v46, v28, v29
	v_cvt_pk_bf16_f32 v47, v30, v31
	global_store_dwordx4 v3, v[44:47], s[10:11] nt
	s_add_u32 s10, s10, 0x40000
	s_addc_u32 s11, s11, 0
	v_lshlrev_b32_e32 v48, 16, v176
	v_and_b32_e32 v49, 0xffff0000, v176
	v_fma_f32 v16, v184, v16, v48
	v_fma_f32 v17, v184, v17, v49
	v_lshlrev_b32_e32 v48, 16, v177
	v_and_b32_e32 v49, 0xffff0000, v177
	v_fma_f32 v18, v184, v18, v48
	v_fma_f32 v19, v184, v19, v49
	v_lshlrev_b32_e32 v48, 16, v178
	v_and_b32_e32 v49, 0xffff0000, v178
	v_fma_f32 v20, v184, v20, v48
	v_fma_f32 v21, v184, v21, v49
	v_lshlrev_b32_e32 v48, 16, v179
	v_and_b32_e32 v49, 0xffff0000, v179
	v_fma_f32 v22, v184, v22, v48
	v_fma_f32 v23, v184, v23, v49
	v_lshlrev_b32_e32 v48, 16, v180
	v_and_b32_e32 v49, 0xffff0000, v180
	v_fma_f32 v24, v184, v24, v48
	v_fma_f32 v25, v184, v25, v49
	v_lshlrev_b32_e32 v48, 16, v181
	v_and_b32_e32 v49, 0xffff0000, v181
	v_fma_f32 v26, v184, v26, v48
	v_fma_f32 v27, v184, v27, v49
	v_lshlrev_b32_e32 v48, 16, v182
	v_and_b32_e32 v49, 0xffff0000, v182
	v_fma_f32 v28, v184, v28, v48
	v_fma_f32 v29, v184, v29, v49
	v_lshlrev_b32_e32 v48, 16, v183
	v_and_b32_e32 v49, 0xffff0000, v183
	v_fma_f32 v30, v184, v30, v48
	v_fma_f32 v31, v184, v31, v49
	global_load_dwordx4 v[176:179], v2, s[6:7] nt
	global_load_dwordx4 v[180:183], v3, s[6:7] nt
	global_load_dword v184, v4, s[12:13]
	s_add_u32 s6, s6, 0x40000
	s_addc_u32 s7, s7, 0
	s_add_u32 s12, s12, 64
	s_addc_u32 s13, s13, 0
	s_waitcnt vmcnt(35)
	v_cvt_pk_bf16_f32 v32, v16, v17
	v_cvt_pk_bf16_f32 v33, v18, v19
	v_cvt_pk_bf16_f32 v34, v20, v21
	v_cvt_pk_bf16_f32 v35, v22, v23
	global_store_dwordx4 v2, v[32:35], s[10:11] nt
	v_cvt_pk_bf16_f32 v36, v24, v25
	v_cvt_pk_bf16_f32 v37, v26, v27
	v_cvt_pk_bf16_f32 v38, v28, v29
	v_cvt_pk_bf16_f32 v39, v30, v31
	global_store_dwordx4 v3, v[36:39], s[10:11] nt
	s_add_u32 s10, s10, 0x40000
	s_addc_u32 s11, s11, 0
	v_lshlrev_b32_e32 v48, 16, v64
	v_and_b32_e32 v49, 0xffff0000, v64
	v_fma_f32 v16, v72, v16, v48
	v_fma_f32 v17, v72, v17, v49
	v_lshlrev_b32_e32 v48, 16, v65
	v_and_b32_e32 v49, 0xffff0000, v65
	v_fma_f32 v18, v72, v18, v48
	v_fma_f32 v19, v72, v19, v49
	v_lshlrev_b32_e32 v48, 16, v66
	v_and_b32_e32 v49, 0xffff0000, v66
	v_fma_f32 v20, v72, v20, v48
	v_fma_f32 v21, v72, v21, v49
	v_lshlrev_b32_e32 v48, 16, v67
	v_and_b32_e32 v49, 0xffff0000, v67
	v_fma_f32 v22, v72, v22, v48
	v_fma_f32 v23, v72, v23, v49
	v_lshlrev_b32_e32 v48, 16, v68
	v_and_b32_e32 v49, 0xffff0000, v68
	v_fma_f32 v24, v72, v24, v48
	v_fma_f32 v25, v72, v25, v49
	v_lshlrev_b32_e32 v48, 16, v69
	v_and_b32_e32 v49, 0xffff0000, v69
	v_fma_f32 v26, v72, v26, v48
	v_fma_f32 v27, v72, v27, v49
	v_lshlrev_b32_e32 v48, 16, v70
	v_and_b32_e32 v49, 0xffff0000, v70
	v_fma_f32 v28, v72, v28, v48
	v_fma_f32 v29, v72, v29, v49
	v_lshlrev_b32_e32 v48, 16, v71
	v_and_b32_e32 v49, 0xffff0000, v71
	v_fma_f32 v30, v72, v30, v48
	v_fma_f32 v31, v72, v31, v49
	s_waitcnt vmcnt(32)
	v_cvt_pk_bf16_f32 v40, v16, v17
	v_cvt_pk_bf16_f32 v41, v18, v19
	v_cvt_pk_bf16_f32 v42, v20, v21
	v_cvt_pk_bf16_f32 v43, v22, v23
	global_store_dwordx4 v2, v[40:43], s[10:11] nt
	v_cvt_pk_bf16_f32 v44, v24, v25
	v_cvt_pk_bf16_f32 v45, v26, v27
	v_cvt_pk_bf16_f32 v46, v28, v29
	v_cvt_pk_bf16_f32 v47, v30, v31
	global_store_dwordx4 v3, v[44:47], s[10:11] nt
	s_add_u32 s10, s10, 0x40000
	s_addc_u32 s11, s11, 0
	v_lshlrev_b32_e32 v48, 16, v80
	v_and_b32_e32 v49, 0xffff0000, v80
	v_fma_f32 v16, v88, v16, v48
	v_fma_f32 v17, v88, v17, v49
	v_lshlrev_b32_e32 v48, 16, v81
	v_and_b32_e32 v49, 0xffff0000, v81
	v_fma_f32 v18, v88, v18, v48
	v_fma_f32 v19, v88, v19, v49
	v_lshlrev_b32_e32 v48, 16, v82
	v_and_b32_e32 v49, 0xffff0000, v82
	v_fma_f32 v20, v88, v20, v48
	v_fma_f32 v21, v88, v21, v49
	v_lshlrev_b32_e32 v48, 16, v83
	v_and_b32_e32 v49, 0xffff0000, v83
	v_fma_f32 v22, v88, v22, v48
	v_fma_f32 v23, v88, v23, v49
	v_lshlrev_b32_e32 v48, 16, v84
	v_and_b32_e32 v49, 0xffff0000, v84
	v_fma_f32 v24, v88, v24, v48
	v_fma_f32 v25, v88, v25, v49
	v_lshlrev_b32_e32 v48, 16, v85
	v_and_b32_e32 v49, 0xffff0000, v85
	v_fma_f32 v26, v88, v26, v48
	v_fma_f32 v27, v88, v27, v49
	v_lshlrev_b32_e32 v48, 16, v86
	v_and_b32_e32 v49, 0xffff0000, v86
	v_fma_f32 v28, v88, v28, v48
	v_fma_f32 v29, v88, v29, v49
	v_lshlrev_b32_e32 v48, 16, v87
	v_and_b32_e32 v49, 0xffff0000, v87
	v_fma_f32 v30, v88, v30, v48
	v_fma_f32 v31, v88, v31, v49
	s_waitcnt vmcnt(29)
	v_cvt_pk_bf16_f32 v32, v16, v17
	v_cvt_pk_bf16_f32 v33, v18, v19
	v_cvt_pk_bf16_f32 v34, v20, v21
	v_cvt_pk_bf16_f32 v35, v22, v23
	global_store_dwordx4 v2, v[32:35], s[10:11] nt
	v_cvt_pk_bf16_f32 v36, v24, v25
	v_cvt_pk_bf16_f32 v37, v26, v27
	v_cvt_pk_bf16_f32 v38, v28, v29
	v_cvt_pk_bf16_f32 v39, v30, v31
	global_store_dwordx4 v3, v[36:39], s[10:11] nt
	s_add_u32 s10, s10, 0x40000
	s_addc_u32 s11, s11, 0
	v_lshlrev_b32_e32 v48, 16, v96
	v_and_b32_e32 v49, 0xffff0000, v96
	v_fma_f32 v16, v104, v16, v48
	v_fma_f32 v17, v104, v17, v49
	v_lshlrev_b32_e32 v48, 16, v97
	v_and_b32_e32 v49, 0xffff0000, v97
	v_fma_f32 v18, v104, v18, v48
	v_fma_f32 v19, v104, v19, v49
	v_lshlrev_b32_e32 v48, 16, v98
	v_and_b32_e32 v49, 0xffff0000, v98
	v_fma_f32 v20, v104, v20, v48
	v_fma_f32 v21, v104, v21, v49
	v_lshlrev_b32_e32 v48, 16, v99
	v_and_b32_e32 v49, 0xffff0000, v99
	v_fma_f32 v22, v104, v22, v48
	v_fma_f32 v23, v104, v23, v49
	v_lshlrev_b32_e32 v48, 16, v100
	v_and_b32_e32 v49, 0xffff0000, v100
	v_fma_f32 v24, v104, v24, v48
	v_fma_f32 v25, v104, v25, v49
	v_lshlrev_b32_e32 v48, 16, v101
	v_and_b32_e32 v49, 0xffff0000, v101
	v_fma_f32 v26, v104, v26, v48
	v_fma_f32 v27, v104, v27, v49
	v_lshlrev_b32_e32 v48, 16, v102
	v_and_b32_e32 v49, 0xffff0000, v102
	v_fma_f32 v28, v104, v28, v48
	v_fma_f32 v29, v104, v29, v49
	v_lshlrev_b32_e32 v48, 16, v103
	v_and_b32_e32 v49, 0xffff0000, v103
	v_fma_f32 v30, v104, v30, v48
	v_fma_f32 v31, v104, v31, v49
	s_waitcnt vmcnt(26)
; __device__ __forceinline__ float bf2f(unsigned h) { return __uint_as_float(h << 16); }
; __device__ __forceinline__ unsigned pk2(float lo, float hi) { return pg8::cvt_pk_bf16(lo, hi); }
; __device__ __forceinline__ void b2_scan(const Ctx& C) {
;     ...
;     B2_LOAD(0, 0);
; #pragma unroll
;     for (int g = 0; g < 8; ++g) {
;         const int cur = g & 1;
;         if (g + 1 < 8) B2_LOAD(g + 1, cur ^ 1);
; #pragma unroll
;         for (int k = 0; k < 4; ++k) {
;             const int c = 4 * g + k;
;             const float dd[8] = {d0[cur][k][0], d0[cur][k][1], d0[cur][k][2], d0[cur][k][3], d1[cur][k][0], d1[cur][k][1], d1[cur][k][2], d1[cur][k][3]};
; #pragma unroll
;             for (int j = 0; j < 2; ++j) {
;                 v4u o; o.x = pk2(run[j][0], run[j][1]); o.y = pk2(run[j][2], run[j][3]); o.z = pk2(run[j][4], run[j][5]); o.w = pk2(run[j][6], run[j][7]);
;                 __builtin_nontemporal_store(o, (v4u*)(base + (size_t)c * cstride + (size_t)j * vstride));
;                 const unsigned lw[4] = {loc[cur][k][j].x, loc[cur][k][j].y, loc[cur][k][j].z, loc[cur][k][j].w};
; #pragma unroll
;                 for (int q = 0; q < 4; ++q) {
;                     run[j][2 * q] = dd[2 * q] * run[j][2 * q] + bf2f(lw[q] & 0xffffu);
;                     run[j][2 * q + 1] = dd[2 * q + 1] * run[j][2 * q + 1] + __uint_as_float(lw[q] & 0xffff0000u);
;                 }
	v_cvt_pk_bf16_f32 v40, v16, v17
	v_cvt_pk_bf16_f32 v41, v18, v19
	v_cvt_pk_bf16_f32 v42, v20, v21
	v_cvt_pk_bf16_f32 v43, v22, v23
	global_store_dwordx4 v2, v[40:43], s[10:11] nt
	v_cvt_pk_bf16_f32 v44, v24, v25
	v_cvt_pk_bf16_f32 v45, v26, v27
	v_cvt_pk_bf16_f32 v46, v28, v29
	v_cvt_pk_bf16_f32 v47, v30, v31
	global_store_dwordx4 v3, v[44:47], s[10:11] nt
	s_add_u32 s10, s10, 0x40000
	s_addc_u32 s11, s11, 0
	v_lshlrev_b32_e32 v48, 16, v112
	v_and_b32_e32 v49, 0xffff0000, v112
	v_fma_f32 v16, v120, v16, v48
	v_fma_f32 v17, v120, v17, v49
	v_lshlrev_b32_e32 v48, 16, v113
	v_and_b32_e32 v49, 0xffff0000, v113
	v_fma_f32 v18, v120, v18, v48
	v_fma_f32 v19, v120, v19, v49
	v_lshlrev_b32_e32 v48, 16, v114
	v_and_b32_e32 v49, 0xffff0000, v114
	v_fma_f32 v20, v120, v20, v48
	v_fma_f32 v21, v120, v21, v49
	v_lshlrev_b32_e32 v48, 16, v115
	v_and_b32_e32 v49, 0xffff0000, v115
	v_fma_f32 v22, v120, v22, v48
	v_fma_f32 v23, v120, v23, v49
	v_lshlrev_b32_e32 v48, 16, v116
	v_and_b32_e32 v49, 0xffff0000, v116
	v_fma_f32 v24, v120, v24, v48
	v_fma_f32 v25, v120, v25, v49
	v_lshlrev_b32_e32 v48, 16, v117
	v_and_b32_e32 v49, 0xffff0000, v117
	v_fma_f32 v26, v120, v26, v48
	v_fma_f32 v27, v120, v27, v49
	v_lshlrev_b32_e32 v48, 16, v118
	v_and_b32_e32 v49, 0xffff0000, v118
	v_fma_f32 v28, v120, v28, v48
	v_fma_f32 v29, v120, v29, v49
	v_lshlrev_b32_e32 v48, 16, v119
	v_and_b32_e32 v49, 0xffff0000, v119
	v_fma_f32 v30, v120, v30, v48
	v_fma_f32 v31, v120, v31, v49
	s_waitcnt vmcnt(23)
	v_cvt_pk_bf16_f32 v32, v16, v17
	v_cvt_pk_bf16_f32 v33, v18, v19
	v_cvt_pk_bf16_f32 v34, v20, v21
	v_cvt_pk_bf16_f32 v35, v22, v23
	global_store_dwordx4 v2, v[32:35], s[10:11] nt
	v_cvt_pk_bf16_f32 v36, v24, v25
	v_cvt_pk_bf16_f32 v37, v26, v27
	v_cvt_pk_bf16_f32 v38, v28, v29
	v_cvt_pk_bf16_f32 v39, v30, v31
	global_store_dwordx4 v3, v[36:39], s[10:11] nt
	s_add_u32 s10, s10, 0x40000
	s_addc_u32 s11, s11, 0
	v_lshlrev_b32_e32 v48, 16, v128
	v_and_b32_e32 v49, 0xffff0000, v128
	v_fma_f32 v16, v136, v16, v48
	v_fma_f32 v17, v136, v17, v49
	v_lshlrev_b32_e32 v48, 16, v129
	v_and_b32_e32 v49, 0xffff0000, v129
	v_fma_f32 v18, v136, v18, v48
	v_fma_f32 v19, v136, v19, v49
	v_lshlrev_b32_e32 v48, 16, v130
	v_and_b32_e32 v49, 0xffff0000, v130
	v_fma_f32 v20, v136, v20, v48
	v_fma_f32 v21, v136, v21, v49
	v_lshlrev_b32_e32 v48, 16, v131
	v_and_b32_e32 v49, 0xffff0000, v131
	v_fma_f32 v22, v136, v22, v48
	v_fma_f32 v23, v136, v23, v49
	v_lshlrev_b32_e32 v48, 16, v132
	v_and_b32_e32 v49, 0xffff0000, v132
	v_fma_f32 v24, v136, v24, v48
	v_fma_f32 v25, v136, v25, v49
	v_lshlrev_b32_e32 v48, 16, v133
	v_and_b32_e32 v49, 0xffff0000, v133
	v_fma_f32 v26, v136, v26, v48
	v_fma_f32 v27, v136, v27, v49
	v_lshlrev_b32_e32 v48, 16, v134
	v_and_b32_e32 v49, 0xffff0000, v134
	v_fma_f32 v28, v136, v28, v48
	v_fma_f32 v29, v136, v29, v49
	v_lshlrev_b32_e32 v48, 16, v135
	v_and_b32_e32 v49, 0xffff0000, v135
	v_fma_f32 v30, v136, v30, v48
	v_fma_f32 v31, v136, v31, v49
	s_waitcnt vmcnt(20)
	v_cvt_pk_bf16_f32 v40, v16, v17
	v_cvt_pk_bf16_f32 v41, v18, v19
	v_cvt_pk_bf16_f32 v42, v20, v21
	v_cvt_pk_bf16_f32 v43, v22, v23
	global_store_dwordx4 v2, v[40:43], s[10:11] nt
	v_cvt_pk_bf16_f32 v44, v24, v25
	v_cvt_pk_bf16_f32 v45, v26, v27
	v_cvt_pk_bf16_f32 v46, v28, v29
	v_cvt_pk_bf16_f32 v47, v30, v31
	global_store_dwordx4 v3, v[44:47], s[10:11] nt
	s_add_u32 s10, s10, 0x40000
	s_addc_u32 s11, s11, 0
	v_lshlrev_b32_e32 v48, 16, v144
	v_and_b32_e32 v49, 0xffff0000, v144
	v_fma_f32 v16, v152, v16, v48
	v_fma_f32 v17, v152, v17, v49
	v_lshlrev_b32_e32 v48, 16, v145
	v_and_b32_e32 v49, 0xffff0000, v145
	v_fma_f32 v18, v152, v18, v48
	v_fma_f32 v19, v152, v19, v49
	v_lshlrev_b32_e32 v48, 16, v146
	v_and_b32_e32 v49, 0xffff0000, v146
	v_fma_f32 v20, v152, v20, v48
	v_fma_f32 v21, v152, v21, v49
	v_lshlrev_b32_e32 v48, 16, v147
	v_and_b32_e32 v49, 0xffff0000, v147
	v_fma_f32 v22, v152, v22, v48
	v_fma_f32 v23, v152, v23, v49
	v_lshlrev_b32_e32 v48, 16, v148
	v_and_b32_e32 v49, 0xffff0000, v148
	v_fma_f32 v24, v152, v24, v48
	v_fma_f32 v25, v152, v25, v49
	v_lshlrev_b32_e32 v48, 16, v149
	v_and_b32_e32 v49, 0xffff0000, v149
	v_fma_f32 v26, v152, v26, v48
	v_fma_f32 v27, v152, v27, v49
	v_lshlrev_b32_e32 v48, 16, v150
	v_and_b32_e32 v49, 0xffff0000, v150
	v_fma_f32 v28, v152, v28, v48
	v_fma_f32 v29, v152, v29, v49
	v_lshlrev_b32_e32 v48, 16, v151
	v_and_b32_e32 v49, 0xffff0000, v151
	v_fma_f32 v30, v152, v30, v48
	v_fma_f32 v31, v152, v31, v49
	s_waitcnt vmcnt(17)
	v_cvt_pk_bf16_f32 v32, v16, v17
	v_cvt_pk_bf16_f32 v33, v18, v19
	v_cvt_pk_bf16_f32 v34, v20, v21
	v_cvt_pk_bf16_f32 v35, v22, v23
	global_store_dwordx4 v2, v[32:35], s[10:11] nt
	v_cvt_pk_bf16_f32 v36, v24, v25
	v_cvt_pk_bf16_f32 v37, v26, v27
	v_cvt_pk_bf16_f32 v38, v28, v29
	v_cvt_pk_bf16_f32 v39, v30, v31
	global_store_dwordx4 v3, v[36:39], s[10:11] nt
	s_add_u32 s10, s10, 0x40000
	s_addc_u32 s11, s11, 0
	v_lshlrev_b32_e32 v48, 16, v160
	v_and_b32_e32 v49, 0xffff0000, v160
	v_fma_f32 v16, v168, v16, v48
	v_fma_f32 v17, v168, v17, v49
	v_lshlrev_b32_e32 v48, 16, v161
	v_and_b32_e32 v49, 0xffff0000, v161
	v_fma_f32 v18, v168, v18, v48
	v_fma_f32 v19, v168, v19, v49
	v_lshlrev_b32_e32 v48, 16, v162
	v_and_b32_e32 v49, 0xffff0000, v162
	v_fma_f32 v20, v168, v20, v48
	v_fma_f32 v21, v168, v21, v49
	v_lshlrev_b32_e32 v48, 16, v163
	v_and_b32_e32 v49, 0xffff0000, v163
	v_fma_f32 v22, v168, v22, v48
	v_fma_f32 v23, v168, v23, v49
	v_lshlrev_b32_e32 v48, 16, v164
	v_and_b32_e32 v49, 0xffff0000, v164
	v_fma_f32 v24, v168, v24, v48
	v_fma_f32 v25, v168, v25, v49
	v_lshlrev_b32_e32 v48, 16, v165
	v_and_b32_e32 v49, 0xffff0000, v165
	v_fma_f32 v26, v168, v26, v48
	v_fma_f32 v27, v168, v27, v49
	v_lshlrev_b32_e32 v48, 16, v166
	v_and_b32_e32 v49, 0xffff0000, v166
	v_fma_f32 v28, v168, v28, v48
	v_fma_f32 v29, v168, v29, v49
	v_lshlrev_b32_e32 v48, 16, v167
	v_and_b32_e32 v49, 0xffff0000, v167
	v_fma_f32 v30, v168, v30, v48
	v_fma_f32 v31, v168, v31, v49
	s_waitcnt vmcnt(14)
; __device__ __forceinline__ float bf2f(unsigned h) { return __uint_as_float(h << 16); }
; __device__ __forceinline__ unsigned pk2(float lo, float hi) { return pg8::cvt_pk_bf16(lo, hi); }
; __device__ __forceinline__ void b2_scan(const Ctx& C) {
;     ...
;     const bool gla = idx >= 65536; const int r = idx & 65535;
;     bf16* base; size_t cstride, vstride; const float* dec; int dstride;
;     if (!gla) { const int b = r >> 13, h = (r >> 9) & 15, e = r & 511;
;         base = (bf16*)(C.ws + WS_HS) + ((size_t)(b * NC) * 16 + h) * 8192 + (size_t)e * 8; vstride = 512 * 8; cstride = (size_t)16 * 8192; dec = SDEC + (b * NC) * 16 + h; dstride = 16; }
;     else { const int b = r >> 13, h = (r >> 11) & 3, q = r & 2047, doct = q & 15, vp = q >> 4;
;         base = (bf16*)(C.ws + WS_GS) + ((size_t)(b * NC) * 4 + h) * 32768 + (size_t)(2 * vp) * 128 + doct * 8; vstride = 128; cstride = (size_t)4 * 32768; dec = GDEC + ((b * NC) * 4 + h) * 128 + doct * 8; dstride = 512; }
;     float run[2][8];
; #pragma unroll
;     for (int j = 0; j < 2; ++j)
; #pragma unroll
;         for (int q = 0; q < 8; ++q) run[j][q] = 0.f;
;     v4u loc[2][4][2]; f32x4 d0[2][4], d1[2][4];
;     ...
;     B2_LOAD(0, 0);
; #pragma unroll
;     for (int g = 0; g < 8; ++g) {
;         const int cur = g & 1;
;         if (g + 1 < 8) B2_LOAD(g + 1, cur ^ 1);
; #pragma unroll
;         for (int k = 0; k < 4; ++k) {
;             const int c = 4 * g + k;
;             const float dd[8] = {d0[cur][k][0], d0[cur][k][1], d0[cur][k][2], d0[cur][k][3], d1[cur][k][0], d1[cur][k][1], d1[cur][k][2], d1[cur][k][3]};
; #pragma unroll
;             for (int j = 0; j < 2; ++j) {
;                 v4u o; o.x = pk2(run[j][0], run[j][1]); o.y = pk2(run[j][2], run[j][3]); o.z = pk2(run[j][4], run[j][5]); o.w = pk2(run[j][6], run[j][7]);
;                 __builtin_nontemporal_store(o, (v4u*)(base + (size_t)c * cstride + (size_t)j * vstride));
;                 const unsigned lw[4] = {loc[cur][k][j].x, loc[cur][k][j].y, loc[cur][k][j].z, loc[cur][k][j].w};
; #pragma unroll
;                 for (int q = 0; q < 4; ++q) {
;                     run[j][2 * q] = dd[2 * q] * run[j][2 * q] + bf2f(lw[q] & 0xffffu);
;                     run[j][2 * q + 1] = dd[2 * q + 1] * run[j][2 * q + 1] + __uint_as_float(lw[q] & 0xffff0000u);
;                 }
	v_cvt_pk_bf16_f32 v40, v16, v17
	v_cvt_pk_bf16_f32 v41, v18, v19
	v_cvt_pk_bf16_f32 v42, v20, v21
	v_cvt_pk_bf16_f32 v43, v22, v23
	global_store_dwordx4 v2, v[40:43], s[10:11] nt
	v_cvt_pk_bf16_f32 v44, v24, v25
	v_cvt_pk_bf16_f32 v45, v26, v27
	v_cvt_pk_bf16_f32 v46, v28, v29
	v_cvt_pk_bf16_f32 v47, v30, v31
	global_store_dwordx4 v3, v[44:47], s[10:11] nt
	s_add_u32 s10, s10, 0x40000
	s_addc_u32 s11, s11, 0
	v_lshlrev_b32_e32 v48, 16, v176
	v_and_b32_e32 v49, 0xffff0000, v176
	v_fma_f32 v16, v184, v16, v48
	v_fma_f32 v17, v184, v17, v49
	v_lshlrev_b32_e32 v48, 16, v177
	v_and_b32_e32 v49, 0xffff0000, v177
	v_fma_f32 v18, v184, v18, v48
	v_fma_f32 v19, v184, v19, v49
	v_lshlrev_b32_e32 v48, 16, v178
	v_and_b32_e32 v49, 0xffff0000, v178
	v_fma_f32 v20, v184, v20, v48
	v_fma_f32 v21, v184, v21, v49
	v_lshlrev_b32_e32 v48, 16, v179
	v_and_b32_e32 v49, 0xffff0000, v179
	v_fma_f32 v22, v184, v22, v48
	v_fma_f32 v23, v184, v23, v49
	v_lshlrev_b32_e32 v48, 16, v180
	v_and_b32_e32 v49, 0xffff0000, v180
	v_fma_f32 v24, v184, v24, v48
	v_fma_f32 v25, v184, v25, v49
	v_lshlrev_b32_e32 v48, 16, v181
	v_and_b32_e32 v49, 0xffff0000, v181
	v_fma_f32 v26, v184, v26, v48
	v_fma_f32 v27, v184, v27, v49
	v_lshlrev_b32_e32 v48, 16, v182
	v_and_b32_e32 v49, 0xffff0000, v182
	v_fma_f32 v28, v184, v28, v48
	v_fma_f32 v29, v184, v29, v49
	v_lshlrev_b32_e32 v48, 16, v183
	v_and_b32_e32 v49, 0xffff0000, v183
	v_fma_f32 v30, v184, v30, v48
	v_fma_f32 v31, v184, v31, v49
	s_branch .Lb2_end_l0
.Lb2_gla_l0:
	s_sub_u32 s6, s2, 128
	s_lshr_b32 s12, s6, 4
	s_lshl_b32 s12, s12, 7
	s_lshr_b32 s10, s6, 2
	s_and_b32 s10, s10, 3
	s_add_u32 s12, s12, s10
	s_and_b32 s10, s6, 3
	s_lshl_b32 s10, s10, 14
	s_lshl_b32 s6, s12, 16
	s_add_u32 s6, s6, s10
	s_lshl_b32 s12, s12, 9
	v_lshrrev_b32_e32 v2, 4, v234
	v_lshlrev_b32_e32 v2, 9, v2
	v_and_b32_e32 v5, 15, v234
	v_lshl_add_u32 v2, v5, 4, v2
	v_add_u32_e32 v3, 0x100, v2
	v_lshlrev_b32_e32 v5, 5, v5
	s_waitcnt lgkmcnt(0)
	s_add_u32 s6, s6, s14
	s_addc_u32 s7, s15, 0
	s_add_u32 s6, s6, 0x21c00000
	s_addc_u32 s7, s7, 0
	s_add_u32 s12, s12, s14
	s_addc_u32 s13, s15, 0
	s_add_u32 s12, s12, 0x25c10000
	s_addc_u32 s13, s13, 0
	s_mov_b32 s10, s6
	s_mov_b32 s11, s7
	global_load_dwordx4 v[64:67], v2, s[6:7] nt
	global_load_dwordx4 v[68:71], v3, s[6:7] nt
	global_load_dwordx4 v[72:75], v5, s[12:13]
	global_load_dwordx4 v[76:79], v5, s[12:13] offset:16
	s_add_u32 s6, s6, 0x40000
	s_addc_u32 s7, s7, 0
	s_add_u32 s12, s12, 2048
	s_addc_u32 s13, s13, 0
	global_load_dwordx4 v[80:83], v2, s[6:7] nt
	global_load_dwordx4 v[84:87], v3, s[6:7] nt
	global_load_dwordx4 v[88:91], v5, s[12:13]
	global_load_dwordx4 v[92:95], v5, s[12:13] offset:16
	s_add_u32 s6, s6, 0x40000
	s_addc_u32 s7, s7, 0
	s_add_u32 s12, s12, 2048
	s_addc_u32 s13, s13, 0
	global_load_dwordx4 v[96:99], v2, s[6:7] nt
	global_load_dwordx4 v[100:103], v3, s[6:7] nt
	global_load_dwordx4 v[104:107], v5, s[12:13]
	global_load_dwordx4 v[108:111], v5, s[12:13] offset:16
	s_add_u32 s6, s6, 0x40000
	s_addc_u32 s7, s7, 0
	s_add_u32 s12, s12, 2048
	s_addc_u32 s13, s13, 0
	global_load_dwordx4 v[112:115], v2, s[6:7] nt
	global_load_dwordx4 v[116:119], v3, s[6:7] nt
	global_load_dwordx4 v[120:123], v5, s[12:13]
	global_load_dwordx4 v[124:127], v5, s[12:13] offset:16
	s_add_u32 s6, s6, 0x40000
	s_addc_u32 s7, s7, 0
	s_add_u32 s12, s12, 2048
	s_addc_u32 s13, s13, 0
	global_load_dwordx4 v[128:131], v2, s[6:7] nt
	global_load_dwordx4 v[132:135], v3, s[6:7] nt
	global_load_dwordx4 v[136:139], v5, s[12:13]
	global_load_dwordx4 v[140:143], v5, s[12:13] offset:16
	s_add_u32 s6, s6, 0x40000
	s_addc_u32 s7, s7, 0
	s_add_u32 s12, s12, 2048
	s_addc_u32 s13, s13, 0
	global_load_dwordx4 v[144:147], v2, s[6:7] nt
	global_load_dwordx4 v[148:151], v3, s[6:7] nt
	global_load_dwordx4 v[152:155], v5, s[12:13]
	global_load_dwordx4 v[156:159], v5, s[12:13] offset:16
	s_add_u32 s6, s6, 0x40000
	s_addc_u32 s7, s7, 0
	s_add_u32 s12, s12, 2048
	s_addc_u32 s13, s13, 0
	global_load_dwordx4 v[160:163], v2, s[6:7] nt
	global_load_dwordx4 v[164:167], v3, s[6:7] nt
	global_load_dwordx4 v[168:171], v5, s[12:13]
	global_load_dwordx4 v[172:175], v5, s[12:13] offset:16
	s_add_u32 s6, s6, 0x40000
	s_addc_u32 s7, s7, 0
	s_add_u32 s12, s12, 2048
	s_addc_u32 s13, s13, 0
	global_load_dwordx4 v[176:179], v2, s[6:7] nt
	global_load_dwordx4 v[180:183], v3, s[6:7] nt
	global_load_dwordx4 v[184:187], v5, s[12:13]
	global_load_dwordx4 v[188:191], v5, s[12:13] offset:16
	s_add_u32 s6, s6, 0x40000
	s_addc_u32 s7, s7, 0
	s_add_u32 s12, s12, 2048
	s_addc_u32 s13, s13, 0
	s_waitcnt vmcnt(28)
	v_cvt_pk_bf16_f32 v32, v16, v17
	v_cvt_pk_bf16_f32 v33, v18, v19
	v_cvt_pk_bf16_f32 v34, v20, v21
	v_cvt_pk_bf16_f32 v35, v22, v23
	global_store_dwordx4 v2, v[32:35], s[10:11] nt
	v_cvt_pk_bf16_f32 v36, v24, v25
	v_cvt_pk_bf16_f32 v37, v26, v27
	v_cvt_pk_bf16_f32 v38, v28, v29
	v_cvt_pk_bf16_f32 v39, v30, v31
	global_store_dwordx4 v3, v[36:39], s[10:11] nt
	s_add_u32 s10, s10, 0x40000
	s_addc_u32 s11, s11, 0
	v_lshlrev_b32_e32 v48, 16, v64
	v_and_b32_e32 v49, 0xffff0000, v64
	v_fma_f32 v16, v72, v16, v48
	v_fma_f32 v17, v73, v17, v49
	v_lshlrev_b32_e32 v48, 16, v65
	v_and_b32_e32 v49, 0xffff0000, v65
	v_fma_f32 v18, v74, v18, v48
	v_fma_f32 v19, v75, v19, v49
	v_lshlrev_b32_e32 v48, 16, v66
	v_and_b32_e32 v49, 0xffff0000, v66
	v_fma_f32 v20, v76, v20, v48
	v_fma_f32 v21, v77, v21, v49
	v_lshlrev_b32_e32 v48, 16, v67
	v_and_b32_e32 v49, 0xffff0000, v67
	v_fma_f32 v22, v78, v22, v48
	v_fma_f32 v23, v79, v23, v49
	v_lshlrev_b32_e32 v48, 16, v68
	v_and_b32_e32 v49, 0xffff0000, v68
	v_fma_f32 v24, v72, v24, v48
	v_fma_f32 v25, v73, v25, v49
	v_lshlrev_b32_e32 v48, 16, v69
	v_and_b32_e32 v49, 0xffff0000, v69
	v_fma_f32 v26, v74, v26, v48
	v_fma_f32 v27, v75, v27, v49
	v_lshlrev_b32_e32 v48, 16, v70
	v_and_b32_e32 v49, 0xffff0000, v70
	v_fma_f32 v28, v76, v28, v48
	v_fma_f32 v29, v77, v29, v49
	v_lshlrev_b32_e32 v48, 16, v71
	v_and_b32_e32 v49, 0xffff0000, v71
	v_fma_f32 v30, v78, v30, v48
	v_fma_f32 v31, v79, v31, v49
	global_load_dwordx4 v[64:67], v2, s[6:7] nt
	global_load_dwordx4 v[68:71], v3, s[6:7] nt
	global_load_dwordx4 v[72:75], v5, s[12:13]
	global_load_dwordx4 v[76:79], v5, s[12:13] offset:16
	s_add_u32 s6, s6, 0x40000
	s_addc_u32 s7, s7, 0
	s_add_u32 s12, s12, 2048
	s_addc_u32 s13, s13, 0
	s_waitcnt vmcnt(30)
; __device__ __forceinline__ float bf2f(unsigned h) { return __uint_as_float(h << 16); }
; __device__ __forceinline__ unsigned pk2(float lo, float hi) { return pg8::cvt_pk_bf16(lo, hi); }
; __device__ __forceinline__ void b2_scan(const Ctx& C) {
;     ...
;     B2_LOAD(0, 0);
; #pragma unroll
;     for (int g = 0; g < 8; ++g) {
;         const int cur = g & 1;
;         if (g + 1 < 8) B2_LOAD(g + 1, cur ^ 1);
; #pragma unroll
;         for (int k = 0; k < 4; ++k) {
;             const int c = 4 * g + k;
;             const float dd[8] = {d0[cur][k][0], d0[cur][k][1], d0[cur][k][2], d0[cur][k][3], d1[cur][k][0], d1[cur][k][1], d1[cur][k][2], d1[cur][k][3]};
; #pragma unroll
;             for (int j = 0; j < 2; ++j) {
;                 v4u o; o.x = pk2(run[j][0], run[j][1]); o.y = pk2(run[j][2], run[j][3]); o.z = pk2(run[j][4], run[j][5]); o.w = pk2(run[j][6], run[j][7]);
;                 __builtin_nontemporal_store(o, (v4u*)(base + (size_t)c * cstride + (size_t)j * vstride));
;                 const unsigned lw[4] = {loc[cur][k][j].x, loc[cur][k][j].y, loc[cur][k][j].z, loc[cur][k][j].w};
; #pragma unroll
;                 for (int q = 0; q < 4; ++q) {
;                     run[j][2 * q] = dd[2 * q] * run[j][2 * q] + bf2f(lw[q] & 0xffffu);
;                     run[j][2 * q + 1] = dd[2 * q + 1] * run[j][2 * q + 1] + __uint_as_float(lw[q] & 0xffff0000u);
;                 }
	v_cvt_pk_bf16_f32 v40, v16, v17
	v_cvt_pk_bf16_f32 v41, v18, v19
	v_cvt_pk_bf16_f32 v42, v20, v21
	v_cvt_pk_bf16_f32 v43, v22, v23
	global_store_dwordx4 v2, v[40:43], s[10:11] nt
	v_cvt_pk_bf16_f32 v44, v24, v25
	v_cvt_pk_bf16_f32 v45, v26, v27
	v_cvt_pk_bf16_f32 v46, v28, v29
	v_cvt_pk_bf16_f32 v47, v30, v31
	global_store_dwordx4 v3, v[44:47], s[10:11] nt
	s_add_u32 s10, s10, 0x40000
	s_addc_u32 s11, s11, 0
	v_lshlrev_b32_e32 v48, 16, v80
	v_and_b32_e32 v49, 0xffff0000, v80
	v_fma_f32 v16, v88, v16, v48
	v_fma_f32 v17, v89, v17, v49
	v_lshlrev_b32_e32 v48, 16, v81
	v_and_b32_e32 v49, 0xffff0000, v81
	v_fma_f32 v18, v90, v18, v48
	v_fma_f32 v19, v91, v19, v49
	v_lshlrev_b32_e32 v48, 16, v82
	v_and_b32_e32 v49, 0xffff0000, v82
	v_fma_f32 v20, v92, v20, v48
	v_fma_f32 v21, v93, v21, v49
	v_lshlrev_b32_e32 v48, 16, v83
	v_and_b32_e32 v49, 0xffff0000, v83
	v_fma_f32 v22, v94, v22, v48
	v_fma_f32 v23, v95, v23, v49
	v_lshlrev_b32_e32 v48, 16, v84
	v_and_b32_e32 v49, 0xffff0000, v84
	v_fma_f32 v24, v88, v24, v48
	v_fma_f32 v25, v89, v25, v49
	v_lshlrev_b32_e32 v48, 16, v85
	v_and_b32_e32 v49, 0xffff0000, v85
	v_fma_f32 v26, v90, v26, v48
	v_fma_f32 v27, v91, v27, v49
	v_lshlrev_b32_e32 v48, 16, v86
	v_and_b32_e32 v49, 0xffff0000, v86
	v_fma_f32 v28, v92, v28, v48
	v_fma_f32 v29, v93, v29, v49
	v_lshlrev_b32_e32 v48, 16, v87
	v_and_b32_e32 v49, 0xffff0000, v87
	v_fma_f32 v30, v94, v30, v48
	v_fma_f32 v31, v95, v31, v49
	global_load_dwordx4 v[80:83], v2, s[6:7] nt
	global_load_dwordx4 v[84:87], v3, s[6:7] nt
	global_load_dwordx4 v[88:91], v5, s[12:13]
	global_load_dwordx4 v[92:95], v5, s[12:13] offset:16
	s_add_u32 s6, s6, 0x40000
	s_addc_u32 s7, s7, 0
	s_add_u32 s12, s12, 2048
	s_addc_u32 s13, s13, 0
	s_waitcnt vmcnt(32)
	v_cvt_pk_bf16_f32 v32, v16, v17
	v_cvt_pk_bf16_f32 v33, v18, v19
	v_cvt_pk_bf16_f32 v34, v20, v21
	v_cvt_pk_bf16_f32 v35, v22, v23
	global_store_dwordx4 v2, v[32:35], s[10:11] nt
	v_cvt_pk_bf16_f32 v36, v24, v25
	v_cvt_pk_bf16_f32 v37, v26, v27
	v_cvt_pk_bf16_f32 v38, v28, v29
	v_cvt_pk_bf16_f32 v39, v30, v31
	global_store_dwordx4 v3, v[36:39], s[10:11] nt
	s_add_u32 s10, s10, 0x40000
	s_addc_u32 s11, s11, 0
	v_lshlrev_b32_e32 v48, 16, v96
	v_and_b32_e32 v49, 0xffff0000, v96
	v_fma_f32 v16, v104, v16, v48
	v_fma_f32 v17, v105, v17, v49
	v_lshlrev_b32_e32 v48, 16, v97
	v_and_b32_e32 v49, 0xffff0000, v97
	v_fma_f32 v18, v106, v18, v48
	v_fma_f32 v19, v107, v19, v49
	v_lshlrev_b32_e32 v48, 16, v98
	v_and_b32_e32 v49, 0xffff0000, v98
	v_fma_f32 v20, v108, v20, v48
	v_fma_f32 v21, v109, v21, v49
	v_lshlrev_b32_e32 v48, 16, v99
	v_and_b32_e32 v49, 0xffff0000, v99
	v_fma_f32 v22, v110, v22, v48
	v_fma_f32 v23, v111, v23, v49
	v_lshlrev_b32_e32 v48, 16, v100
	v_and_b32_e32 v49, 0xffff0000, v100
	v_fma_f32 v24, v104, v24, v48
	v_fma_f32 v25, v105, v25, v49
	v_lshlrev_b32_e32 v48, 16, v101
	v_and_b32_e32 v49, 0xffff0000, v101
	v_fma_f32 v26, v106, v26, v48
	v_fma_f32 v27, v107, v27, v49
	v_lshlrev_b32_e32 v48, 16, v102
	v_and_b32_e32 v49, 0xffff0000, v102
	v_fma_f32 v28, v108, v28, v48
	v_fma_f32 v29, v109, v29, v49
	v_lshlrev_b32_e32 v48, 16, v103
	v_and_b32_e32 v49, 0xffff0000, v103
	v_fma_f32 v30, v110, v30, v48
	v_fma_f32 v31, v111, v31, v49
	global_load_dwordx4 v[96:99], v2, s[6:7] nt
	global_load_dwordx4 v[100:103], v3, s[6:7] nt
	global_load_dwordx4 v[104:107], v5, s[12:13]
	global_load_dwordx4 v[108:111], v5, s[12:13] offset:16
	s_add_u32 s6, s6, 0x40000
	s_addc_u32 s7, s7, 0
	s_add_u32 s12, s12, 2048
	s_addc_u32 s13, s13, 0
	s_waitcnt vmcnt(34)
	v_cvt_pk_bf16_f32 v40, v16, v17
	v_cvt_pk_bf16_f32 v41, v18, v19
	v_cvt_pk_bf16_f32 v42, v20, v21
	v_cvt_pk_bf16_f32 v43, v22, v23
	global_store_dwordx4 v2, v[40:43], s[10:11] nt
	v_cvt_pk_bf16_f32 v44, v24, v25
	v_cvt_pk_bf16_f32 v45, v26, v27
	v_cvt_pk_bf16_f32 v46, v28, v29
	v_cvt_pk_bf16_f32 v47, v30, v31
	global_store_dwordx4 v3, v[44:47], s[10:11] nt
	s_add_u32 s10, s10, 0x40000
	s_addc_u32 s11, s11, 0
	v_lshlrev_b32_e32 v48, 16, v112
	v_and_b32_e32 v49, 0xffff0000, v112
	v_fma_f32 v16, v120, v16, v48
	v_fma_f32 v17, v121, v17, v49
	v_lshlrev_b32_e32 v48, 16, v113
	v_and_b32_e32 v49, 0xffff0000, v113
	v_fma_f32 v18, v122, v18, v48
	v_fma_f32 v19, v123, v19, v49
	v_lshlrev_b32_e32 v48, 16, v114
	v_and_b32_e32 v49, 0xffff0000, v114
	v_fma_f32 v20, v124, v20, v48
	v_fma_f32 v21, v125, v21, v49
	v_lshlrev_b32_e32 v48, 16, v115
	v_and_b32_e32 v49, 0xffff0000, v115
	v_fma_f32 v22, v126, v22, v48
	v_fma_f32 v23, v127, v23, v49
	v_lshlrev_b32_e32 v48, 16, v116
	v_and_b32_e32 v49, 0xffff0000, v116
	v_fma_f32 v24, v120, v24, v48
	v_fma_f32 v25, v121, v25, v49
	v_lshlrev_b32_e32 v48, 16, v117
	v_and_b32_e32 v49, 0xffff0000, v117
	v_fma_f32 v26, v122, v26, v48
	v_fma_f32 v27, v123, v27, v49
	v_lshlrev_b32_e32 v48, 16, v118
	v_and_b32_e32 v49, 0xffff0000, v118
	v_fma_f32 v28, v124, v28, v48
	v_fma_f32 v29, v125, v29, v49
	v_lshlrev_b32_e32 v48, 16, v119
	v_and_b32_e32 v49, 0xffff0000, v119
	v_fma_f32 v30, v126, v30, v48
	v_fma_f32 v31, v127, v31, v49
	global_load_dwordx4 v[112:115], v2, s[6:7] nt
	global_load_dwordx4 v[116:119], v3, s[6:7] nt
	global_load_dwordx4 v[120:123], v5, s[12:13]
	global_load_dwordx4 v[124:127], v5, s[12:13] offset:16
	s_add_u32 s6, s6, 0x40000
	s_addc_u32 s7, s7, 0
	s_add_u32 s12, s12, 2048
	s_addc_u32 s13, s13, 0
	s_waitcnt vmcnt(36)
; __device__ __forceinline__ float bf2f(unsigned h) { return __uint_as_float(h << 16); }
; __device__ __forceinline__ unsigned pk2(float lo, float hi) { return pg8::cvt_pk_bf16(lo, hi); }
; __device__ __forceinline__ void b2_scan(const Ctx& C) {
;     ...
;     B2_LOAD(0, 0);
; #pragma unroll
;     for (int g = 0; g < 8; ++g) {
;         const int cur = g & 1;
;         if (g + 1 < 8) B2_LOAD(g + 1, cur ^ 1);
; #pragma unroll
;         for (int k = 0; k < 4; ++k) {
;             const int c = 4 * g + k;
;             const float dd[8] = {d0[cur][k][0], d0[cur][k][1], d0[cur][k][2], d0[cur][k][3], d1[cur][k][0], d1[cur][k][1], d1[cur][k][2], d1[cur][k][3]};
; #pragma unroll
;             for (int j = 0; j < 2; ++j) {
;                 v4u o; o.x = pk2(run[j][0], run[j][1]); o.y = pk2(run[j][2], run[j][3]); o.z = pk2(run[j][4], run[j][5]); o.w = pk2(run[j][6], run[j][7]);
;                 __builtin_nontemporal_store(o, (v4u*)(base + (size_t)c * cstride + (size_t)j * vstride));
;                 const unsigned lw[4] = {loc[cur][k][j].x, loc[cur][k][j].y, loc[cur][k][j].z, loc[cur][k][j].w};
; #pragma unroll
;                 for (int q = 0; q < 4; ++q) {
;                     run[j][2 * q] = dd[2 * q] * run[j][2 * q] + bf2f(lw[q] & 0xffffu);
;                     run[j][2 * q + 1] = dd[2 * q + 1] * run[j][2 * q + 1] + __uint_as_float(lw[q] & 0xffff0000u);
;                 }
	v_cvt_pk_bf16_f32 v32, v16, v17
	v_cvt_pk_bf16_f32 v33, v18, v19
	v_cvt_pk_bf16_f32 v34, v20, v21
	v_cvt_pk_bf16_f32 v35, v22, v23
	global_store_dwordx4 v2, v[32:35], s[10:11] nt
	v_cvt_pk_bf16_f32 v36, v24, v25
	v_cvt_pk_bf16_f32 v37, v26, v27
	v_cvt_pk_bf16_f32 v38, v28, v29
	v_cvt_pk_bf16_f32 v39, v30, v31
	global_store_dwordx4 v3, v[36:39], s[10:11] nt
	s_add_u32 s10, s10, 0x40000
	s_addc_u32 s11, s11, 0
	v_lshlrev_b32_e32 v48, 16, v128
	v_and_b32_e32 v49, 0xffff0000, v128
	v_fma_f32 v16, v136, v16, v48
	v_fma_f32 v17, v137, v17, v49
	v_lshlrev_b32_e32 v48, 16, v129
	v_and_b32_e32 v49, 0xffff0000, v129
	v_fma_f32 v18, v138, v18, v48
	v_fma_f32 v19, v139, v19, v49
	v_lshlrev_b32_e32 v48, 16, v130
	v_and_b32_e32 v49, 0xffff0000, v130
	v_fma_f32 v20, v140, v20, v48
	v_fma_f32 v21, v141, v21, v49
	v_lshlrev_b32_e32 v48, 16, v131
	v_and_b32_e32 v49, 0xffff0000, v131
	v_fma_f32 v22, v142, v22, v48
	v_fma_f32 v23, v143, v23, v49
	v_lshlrev_b32_e32 v48, 16, v132
	v_and_b32_e32 v49, 0xffff0000, v132
	v_fma_f32 v24, v136, v24, v48
	v_fma_f32 v25, v137, v25, v49
	v_lshlrev_b32_e32 v48, 16, v133
	v_and_b32_e32 v49, 0xffff0000, v133
	v_fma_f32 v26, v138, v26, v48
	v_fma_f32 v27, v139, v27, v49
	v_lshlrev_b32_e32 v48, 16, v134
	v_and_b32_e32 v49, 0xffff0000, v134
	v_fma_f32 v28, v140, v28, v48
	v_fma_f32 v29, v141, v29, v49
	v_lshlrev_b32_e32 v48, 16, v135
	v_and_b32_e32 v49, 0xffff0000, v135
	v_fma_f32 v30, v142, v30, v48
	v_fma_f32 v31, v143, v31, v49
	global_load_dwordx4 v[128:131], v2, s[6:7] nt
	global_load_dwordx4 v[132:135], v3, s[6:7] nt
	global_load_dwordx4 v[136:139], v5, s[12:13]
	global_load_dwordx4 v[140:143], v5, s[12:13] offset:16
	s_add_u32 s6, s6, 0x40000
	s_addc_u32 s7, s7, 0
	s_add_u32 s12, s12, 2048
	s_addc_u32 s13, s13, 0
	s_waitcnt vmcnt(38)
	v_cvt_pk_bf16_f32 v40, v16, v17
	v_cvt_pk_bf16_f32 v41, v18, v19
	v_cvt_pk_bf16_f32 v42, v20, v21
	v_cvt_pk_bf16_f32 v43, v22, v23
	global_store_dwordx4 v2, v[40:43], s[10:11] nt
	v_cvt_pk_bf16_f32 v44, v24, v25
	v_cvt_pk_bf16_f32 v45, v26, v27
	v_cvt_pk_bf16_f32 v46, v28, v29
	v_cvt_pk_bf16_f32 v47, v30, v31
	global_store_dwordx4 v3, v[44:47], s[10:11] nt
	s_add_u32 s10, s10, 0x40000
	s_addc_u32 s11, s11, 0
	v_lshlrev_b32_e32 v48, 16, v144
	v_and_b32_e32 v49, 0xffff0000, v144
	v_fma_f32 v16, v152, v16, v48
	v_fma_f32 v17, v153, v17, v49
	v_lshlrev_b32_e32 v48, 16, v145
	v_and_b32_e32 v49, 0xffff0000, v145
	v_fma_f32 v18, v154, v18, v48
	v_fma_f32 v19, v155, v19, v49
	v_lshlrev_b32_e32 v48, 16, v146
	v_and_b32_e32 v49, 0xffff0000, v146
	v_fma_f32 v20, v156, v20, v48
	v_fma_f32 v21, v157, v21, v49
	v_lshlrev_b32_e32 v48, 16, v147
	v_and_b32_e32 v49, 0xffff0000, v147
	v_fma_f32 v22, v158, v22, v48
	v_fma_f32 v23, v159, v23, v49
	v_lshlrev_b32_e32 v48, 16, v148
	v_and_b32_e32 v49, 0xffff0000, v148
	v_fma_f32 v24, v152, v24, v48
	v_fma_f32 v25, v153, v25, v49
	v_lshlrev_b32_e32 v48, 16, v149
	v_and_b32_e32 v49, 0xffff0000, v149
	v_fma_f32 v26, v154, v26, v48
	v_fma_f32 v27, v155, v27, v49
	v_lshlrev_b32_e32 v48, 16, v150
	v_and_b32_e32 v49, 0xffff0000, v150
	v_fma_f32 v28, v156, v28, v48
	v_fma_f32 v29, v157, v29, v49
	v_lshlrev_b32_e32 v48, 16, v151
	v_and_b32_e32 v49, 0xffff0000, v151
	v_fma_f32 v30, v158, v30, v48
	v_fma_f32 v31, v159, v31, v49
	global_load_dwordx4 v[144:147], v2, s[6:7] nt
	global_load_dwordx4 v[148:151], v3, s[6:7] nt
	global_load_dwordx4 v[152:155], v5, s[12:13]
	global_load_dwordx4 v[156:159], v5, s[12:13] offset:16
	s_add_u32 s6, s6, 0x40000
	s_addc_u32 s7, s7, 0
	s_add_u32 s12, s12, 2048
	s_addc_u32 s13, s13, 0
	s_waitcnt vmcnt(40)
	v_cvt_pk_bf16_f32 v32, v16, v17
	v_cvt_pk_bf16_f32 v33, v18, v19
	v_cvt_pk_bf16_f32 v34, v20, v21
	v_cvt_pk_bf16_f32 v35, v22, v23
	global_store_dwordx4 v2, v[32:35], s[10:11] nt
	v_cvt_pk_bf16_f32 v36, v24, v25
	v_cvt_pk_bf16_f32 v37, v26, v27
	v_cvt_pk_bf16_f32 v38, v28, v29
	v_cvt_pk_bf16_f32 v39, v30, v31
	global_store_dwordx4 v3, v[36:39], s[10:11] nt
	s_add_u32 s10, s10, 0x40000
	s_addc_u32 s11, s11, 0
	v_lshlrev_b32_e32 v48, 16, v160
	v_and_b32_e32 v49, 0xffff0000, v160
	v_fma_f32 v16, v168, v16, v48
	v_fma_f32 v17, v169, v17, v49
	v_lshlrev_b32_e32 v48, 16, v161
	v_and_b32_e32 v49, 0xffff0000, v161
	v_fma_f32 v18, v170, v18, v48
	v_fma_f32 v19, v171, v19, v49
	v_lshlrev_b32_e32 v48, 16, v162
	v_and_b32_e32 v49, 0xffff0000, v162
	v_fma_f32 v20, v172, v20, v48
	v_fma_f32 v21, v173, v21, v49
	v_lshlrev_b32_e32 v48, 16, v163
	v_and_b32_e32 v49, 0xffff0000, v163
	v_fma_f32 v22, v174, v22, v48
	v_fma_f32 v23, v175, v23, v49
	v_lshlrev_b32_e32 v48, 16, v164
	v_and_b32_e32 v49, 0xffff0000, v164
	v_fma_f32 v24, v168, v24, v48
	v_fma_f32 v25, v169, v25, v49
	v_lshlrev_b32_e32 v48, 16, v165
	v_and_b32_e32 v49, 0xffff0000, v165
	v_fma_f32 v26, v170, v26, v48
	v_fma_f32 v27, v171, v27, v49
	v_lshlrev_b32_e32 v48, 16, v166
	v_and_b32_e32 v49, 0xffff0000, v166
	v_fma_f32 v28, v172, v28, v48
	v_fma_f32 v29, v173, v29, v49
	v_lshlrev_b32_e32 v48, 16, v167
	v_and_b32_e32 v49, 0xffff0000, v167
	v_fma_f32 v30, v174, v30, v48
	v_fma_f32 v31, v175, v31, v49
	global_load_dwordx4 v[160:163], v2, s[6:7] nt
	global_load_dwordx4 v[164:167], v3, s[6:7] nt
	global_load_dwordx4 v[168:171], v5, s[12:13]
	global_load_dwordx4 v[172:175], v5, s[12:13] offset:16
	s_add_u32 s6, s6, 0x40000
	s_addc_u32 s7, s7, 0
	s_add_u32 s12, s12, 2048
	s_addc_u32 s13, s13, 0
	s_waitcnt vmcnt(42)
; __device__ __forceinline__ float bf2f(unsigned h) { return __uint_as_float(h << 16); }
; __device__ __forceinline__ unsigned pk2(float lo, float hi) { return pg8::cvt_pk_bf16(lo, hi); }
; __device__ __forceinline__ void b2_scan(const Ctx& C) {
;     ...
;     B2_LOAD(0, 0);
; #pragma unroll
;     for (int g = 0; g < 8; ++g) {
;         const int cur = g & 1;
;         if (g + 1 < 8) B2_LOAD(g + 1, cur ^ 1);
; #pragma unroll
;         for (int k = 0; k < 4; ++k) {
;             const int c = 4 * g + k;
;             const float dd[8] = {d0[cur][k][0], d0[cur][k][1], d0[cur][k][2], d0[cur][k][3], d1[cur][k][0], d1[cur][k][1], d1[cur][k][2], d1[cur][k][3]};
; #pragma unroll
;             for (int j = 0; j < 2; ++j) {
;                 v4u o; o.x = pk2(run[j][0], run[j][1]); o.y = pk2(run[j][2], run[j][3]); o.z = pk2(run[j][4], run[j][5]); o.w = pk2(run[j][6], run[j][7]);
;                 __builtin_nontemporal_store(o, (v4u*)(base + (size_t)c * cstride + (size_t)j * vstride));
;                 const unsigned lw[4] = {loc[cur][k][j].x, loc[cur][k][j].y, loc[cur][k][j].z, loc[cur][k][j].w};
; #pragma unroll
;                 for (int q = 0; q < 4; ++q) {
;                     run[j][2 * q] = dd[2 * q] * run[j][2 * q] + bf2f(lw[q] & 0xffffu);
;                     run[j][2 * q + 1] = dd[2 * q + 1] * run[j][2 * q + 1] + __uint_as_float(lw[q] & 0xffff0000u);
;                 }
	v_cvt_pk_bf16_f32 v40, v16, v17
	v_cvt_pk_bf16_f32 v41, v18, v19
	v_cvt_pk_bf16_f32 v42, v20, v21
	v_cvt_pk_bf16_f32 v43, v22, v23
	global_store_dwordx4 v2, v[40:43], s[10:11] nt
	v_cvt_pk_bf16_f32 v44, v24, v25
	v_cvt_pk_bf16_f32 v45, v26, v27
	v_cvt_pk_bf16_f32 v46, v28, v29
	v_cvt_pk_bf16_f32 v47, v30, v31
	global_store_dwordx4 v3, v[44:47], s[10:11] nt
	s_add_u32 s10, s10, 0x40000
	s_addc_u32 s11, s11, 0
	v_lshlrev_b32_e32 v48, 16, v176
	v_and_b32_e32 v49, 0xffff0000, v176
	v_fma_f32 v16, v184, v16, v48
	v_fma_f32 v17, v185, v17, v49
	v_lshlrev_b32_e32 v48, 16, v177
	v_and_b32_e32 v49, 0xffff0000, v177
	v_fma_f32 v18, v186, v18, v48
	v_fma_f32 v19, v187, v19, v49
	v_lshlrev_b32_e32 v48, 16, v178
	v_and_b32_e32 v49, 0xffff0000, v178
	v_fma_f32 v20, v188, v20, v48
	v_fma_f32 v21, v189, v21, v49
	v_lshlrev_b32_e32 v48, 16, v179
	v_and_b32_e32 v49, 0xffff0000, v179
	v_fma_f32 v22, v190, v22, v48
	v_fma_f32 v23, v191, v23, v49
	v_lshlrev_b32_e32 v48, 16, v180
	v_and_b32_e32 v49, 0xffff0000, v180
	v_fma_f32 v24, v184, v24, v48
	v_fma_f32 v25, v185, v25, v49
	v_lshlrev_b32_e32 v48, 16, v181
	v_and_b32_e32 v49, 0xffff0000, v181
	v_fma_f32 v26, v186, v26, v48
	v_fma_f32 v27, v187, v27, v49
	v_lshlrev_b32_e32 v48, 16, v182
	v_and_b32_e32 v49, 0xffff0000, v182
	v_fma_f32 v28, v188, v28, v48
	v_fma_f32 v29, v189, v29, v49
	v_lshlrev_b32_e32 v48, 16, v183
	v_and_b32_e32 v49, 0xffff0000, v183
	v_fma_f32 v30, v190, v30, v48
	v_fma_f32 v31, v191, v31, v49
	global_load_dwordx4 v[176:179], v2, s[6:7] nt
	global_load_dwordx4 v[180:183], v3, s[6:7] nt
	global_load_dwordx4 v[184:187], v5, s[12:13]
	global_load_dwordx4 v[188:191], v5, s[12:13] offset:16
	s_add_u32 s6, s6, 0x40000
	s_addc_u32 s7, s7, 0
	s_add_u32 s12, s12, 2048
	s_addc_u32 s13, s13, 0
	s_waitcnt vmcnt(42)
	v_cvt_pk_bf16_f32 v32, v16, v17
	v_cvt_pk_bf16_f32 v33, v18, v19
	v_cvt_pk_bf16_f32 v34, v20, v21
	v_cvt_pk_bf16_f32 v35, v22, v23
	global_store_dwordx4 v2, v[32:35], s[10:11] nt
	v_cvt_pk_bf16_f32 v36, v24, v25
	v_cvt_pk_bf16_f32 v37, v26, v27
	v_cvt_pk_bf16_f32 v38, v28, v29
	v_cvt_pk_bf16_f32 v39, v30, v31
	global_store_dwordx4 v3, v[36:39], s[10:11] nt
	s_add_u32 s10, s10, 0x40000
	s_addc_u32 s11, s11, 0
	v_lshlrev_b32_e32 v48, 16, v64
	v_and_b32_e32 v49, 0xffff0000, v64
	v_fma_f32 v16, v72, v16, v48
	v_fma_f32 v17, v73, v17, v49
	v_lshlrev_b32_e32 v48, 16, v65
	v_and_b32_e32 v49, 0xffff0000, v65
	v_fma_f32 v18, v74, v18, v48
	v_fma_f32 v19, v75, v19, v49
	v_lshlrev_b32_e32 v48, 16, v66
	v_and_b32_e32 v49, 0xffff0000, v66
	v_fma_f32 v20, v76, v20, v48
	v_fma_f32 v21, v77, v21, v49
	v_lshlrev_b32_e32 v48, 16, v67
	v_and_b32_e32 v49, 0xffff0000, v67
	v_fma_f32 v22, v78, v22, v48
	v_fma_f32 v23, v79, v23, v49
	v_lshlrev_b32_e32 v48, 16, v68
	v_and_b32_e32 v49, 0xffff0000, v68
	v_fma_f32 v24, v72, v24, v48
	v_fma_f32 v25, v73, v25, v49
	v_lshlrev_b32_e32 v48, 16, v69
	v_and_b32_e32 v49, 0xffff0000, v69
	v_fma_f32 v26, v74, v26, v48
	v_fma_f32 v27, v75, v27, v49
	v_lshlrev_b32_e32 v48, 16, v70
	v_and_b32_e32 v49, 0xffff0000, v70
	v_fma_f32 v28, v76, v28, v48
	v_fma_f32 v29, v77, v29, v49
	v_lshlrev_b32_e32 v48, 16, v71
	v_and_b32_e32 v49, 0xffff0000, v71
	v_fma_f32 v30, v78, v30, v48
	v_fma_f32 v31, v79, v31, v49
	global_load_dwordx4 v[64:67], v2, s[6:7] nt
	global_load_dwordx4 v[68:71], v3, s[6:7] nt
	global_load_dwordx4 v[72:75], v5, s[12:13]
	global_load_dwordx4 v[76:79], v5, s[12:13] offset:16
	s_add_u32 s6, s6, 0x40000
	s_addc_u32 s7, s7, 0
	s_add_u32 s12, s12, 2048
	s_addc_u32 s13, s13, 0
	s_waitcnt vmcnt(42)
	v_cvt_pk_bf16_f32 v40, v16, v17
	v_cvt_pk_bf16_f32 v41, v18, v19
	v_cvt_pk_bf16_f32 v42, v20, v21
	v_cvt_pk_bf16_f32 v43, v22, v23
	global_store_dwordx4 v2, v[40:43], s[10:11] nt
	v_cvt_pk_bf16_f32 v44, v24, v25
	v_cvt_pk_bf16_f32 v45, v26, v27
	v_cvt_pk_bf16_f32 v46, v28, v29
	v_cvt_pk_bf16_f32 v47, v30, v31
	global_store_dwordx4 v3, v[44:47], s[10:11] nt
	s_add_u32 s10, s10, 0x40000
	s_addc_u32 s11, s11, 0
	v_lshlrev_b32_e32 v48, 16, v80
	v_and_b32_e32 v49, 0xffff0000, v80
	v_fma_f32 v16, v88, v16, v48
	v_fma_f32 v17, v89, v17, v49
	v_lshlrev_b32_e32 v48, 16, v81
	v_and_b32_e32 v49, 0xffff0000, v81
	v_fma_f32 v18, v90, v18, v48
	v_fma_f32 v19, v91, v19, v49
	v_lshlrev_b32_e32 v48, 16, v82
	v_and_b32_e32 v49, 0xffff0000, v82
	v_fma_f32 v20, v92, v20, v48
	v_fma_f32 v21, v93, v21, v49
	v_lshlrev_b32_e32 v48, 16, v83
	v_and_b32_e32 v49, 0xffff0000, v83
	v_fma_f32 v22, v94, v22, v48
	v_fma_f32 v23, v95, v23, v49
	v_lshlrev_b32_e32 v48, 16, v84
	v_and_b32_e32 v49, 0xffff0000, v84
	v_fma_f32 v24, v88, v24, v48
	v_fma_f32 v25, v89, v25, v49
	v_lshlrev_b32_e32 v48, 16, v85
	v_and_b32_e32 v49, 0xffff0000, v85
	v_fma_f32 v26, v90, v26, v48
	v_fma_f32 v27, v91, v27, v49
	v_lshlrev_b32_e32 v48, 16, v86
	v_and_b32_e32 v49, 0xffff0000, v86
	v_fma_f32 v28, v92, v28, v48
	v_fma_f32 v29, v93, v29, v49
	v_lshlrev_b32_e32 v48, 16, v87
	v_and_b32_e32 v49, 0xffff0000, v87
	v_fma_f32 v30, v94, v30, v48
	v_fma_f32 v31, v95, v31, v49
	global_load_dwordx4 v[80:83], v2, s[6:7] nt
	global_load_dwordx4 v[84:87], v3, s[6:7] nt
	global_load_dwordx4 v[88:91], v5, s[12:13]
	global_load_dwordx4 v[92:95], v5, s[12:13] offset:16
	s_add_u32 s6, s6, 0x40000
	s_addc_u32 s7, s7, 0
	s_add_u32 s12, s12, 2048
	s_addc_u32 s13, s13, 0
	s_waitcnt vmcnt(42)
; __device__ __forceinline__ float bf2f(unsigned h) { return __uint_as_float(h << 16); }
; __device__ __forceinline__ unsigned pk2(float lo, float hi) { return pg8::cvt_pk_bf16(lo, hi); }
; __device__ __forceinline__ void b2_scan(const Ctx& C) {
;     ...
;     B2_LOAD(0, 0);
; #pragma unroll
;     for (int g = 0; g < 8; ++g) {
;         const int cur = g & 1;
;         if (g + 1 < 8) B2_LOAD(g + 1, cur ^ 1);
; #pragma unroll
;         for (int k = 0; k < 4; ++k) {
;             const int c = 4 * g + k;
;             const float dd[8] = {d0[cur][k][0], d0[cur][k][1], d0[cur][k][2], d0[cur][k][3], d1[cur][k][0], d1[cur][k][1], d1[cur][k][2], d1[cur][k][3]};
; #pragma unroll
;             for (int j = 0; j < 2; ++j) {
;                 v4u o; o.x = pk2(run[j][0], run[j][1]); o.y = pk2(run[j][2], run[j][3]); o.z = pk2(run[j][4], run[j][5]); o.w = pk2(run[j][6], run[j][7]);
;                 __builtin_nontemporal_store(o, (v4u*)(base + (size_t)c * cstride + (size_t)j * vstride));
;                 const unsigned lw[4] = {loc[cur][k][j].x, loc[cur][k][j].y, loc[cur][k][j].z, loc[cur][k][j].w};
; #pragma unroll
;                 for (int q = 0; q < 4; ++q) {
;                     run[j][2 * q] = dd[2 * q] * run[j][2 * q] + bf2f(lw[q] & 0xffffu);
;                     run[j][2 * q + 1] = dd[2 * q + 1] * run[j][2 * q + 1] + __uint_as_float(lw[q] & 0xffff0000u);
;                 }
	v_cvt_pk_bf16_f32 v32, v16, v17
	v_cvt_pk_bf16_f32 v33, v18, v19
	v_cvt_pk_bf16_f32 v34, v20, v21
	v_cvt_pk_bf16_f32 v35, v22, v23
	global_store_dwordx4 v2, v[32:35], s[10:11] nt
	v_cvt_pk_bf16_f32 v36, v24, v25
	v_cvt_pk_bf16_f32 v37, v26, v27
	v_cvt_pk_bf16_f32 v38, v28, v29
	v_cvt_pk_bf16_f32 v39, v30, v31
	global_store_dwordx4 v3, v[36:39], s[10:11] nt
	s_add_u32 s10, s10, 0x40000
	s_addc_u32 s11, s11, 0
	v_lshlrev_b32_e32 v48, 16, v96
	v_and_b32_e32 v49, 0xffff0000, v96
	v_fma_f32 v16, v104, v16, v48
	v_fma_f32 v17, v105, v17, v49
	v_lshlrev_b32_e32 v48, 16, v97
	v_and_b32_e32 v49, 0xffff0000, v97
	v_fma_f32 v18, v106, v18, v48
	v_fma_f32 v19, v107, v19, v49
	v_lshlrev_b32_e32 v48, 16, v98
	v_and_b32_e32 v49, 0xffff0000, v98
	v_fma_f32 v20, v108, v20, v48
	v_fma_f32 v21, v109, v21, v49
	v_lshlrev_b32_e32 v48, 16, v99
	v_and_b32_e32 v49, 0xffff0000, v99
	v_fma_f32 v22, v110, v22, v48
	v_fma_f32 v23, v111, v23, v49
	v_lshlrev_b32_e32 v48, 16, v100
	v_and_b32_e32 v49, 0xffff0000, v100
	v_fma_f32 v24, v104, v24, v48
	v_fma_f32 v25, v105, v25, v49
	v_lshlrev_b32_e32 v48, 16, v101
	v_and_b32_e32 v49, 0xffff0000, v101
	v_fma_f32 v26, v106, v26, v48
	v_fma_f32 v27, v107, v27, v49
	v_lshlrev_b32_e32 v48, 16, v102
	v_and_b32_e32 v49, 0xffff0000, v102
	v_fma_f32 v28, v108, v28, v48
	v_fma_f32 v29, v109, v29, v49
	v_lshlrev_b32_e32 v48, 16, v103
	v_and_b32_e32 v49, 0xffff0000, v103
	v_fma_f32 v30, v110, v30, v48
	v_fma_f32 v31, v111, v31, v49
	global_load_dwordx4 v[96:99], v2, s[6:7] nt
	global_load_dwordx4 v[100:103], v3, s[6:7] nt
	global_load_dwordx4 v[104:107], v5, s[12:13]
	global_load_dwordx4 v[108:111], v5, s[12:13] offset:16
	s_add_u32 s6, s6, 0x40000
	s_addc_u32 s7, s7, 0
	s_add_u32 s12, s12, 2048
	s_addc_u32 s13, s13, 0
	s_waitcnt vmcnt(42)
	v_cvt_pk_bf16_f32 v40, v16, v17
	v_cvt_pk_bf16_f32 v41, v18, v19
	v_cvt_pk_bf16_f32 v42, v20, v21
	v_cvt_pk_bf16_f32 v43, v22, v23
	global_store_dwordx4 v2, v[40:43], s[10:11] nt
	v_cvt_pk_bf16_f32 v44, v24, v25
	v_cvt_pk_bf16_f32 v45, v26, v27
	v_cvt_pk_bf16_f32 v46, v28, v29
	v_cvt_pk_bf16_f32 v47, v30, v31
	global_store_dwordx4 v3, v[44:47], s[10:11] nt
	s_add_u32 s10, s10, 0x40000
	s_addc_u32 s11, s11, 0
	v_lshlrev_b32_e32 v48, 16, v112
	v_and_b32_e32 v49, 0xffff0000, v112
	v_fma_f32 v16, v120, v16, v48
	v_fma_f32 v17, v121, v17, v49
	v_lshlrev_b32_e32 v48, 16, v113
	v_and_b32_e32 v49, 0xffff0000, v113
	v_fma_f32 v18, v122, v18, v48
	v_fma_f32 v19, v123, v19, v49
	v_lshlrev_b32_e32 v48, 16, v114
	v_and_b32_e32 v49, 0xffff0000, v114
	v_fma_f32 v20, v124, v20, v48
	v_fma_f32 v21, v125, v21, v49
	v_lshlrev_b32_e32 v48, 16, v115
	v_and_b32_e32 v49, 0xffff0000, v115
	v_fma_f32 v22, v126, v22, v48
	v_fma_f32 v23, v127, v23, v49
	v_lshlrev_b32_e32 v48, 16, v116
	v_and_b32_e32 v49, 0xffff0000, v116
	v_fma_f32 v24, v120, v24, v48
	v_fma_f32 v25, v121, v25, v49
	v_lshlrev_b32_e32 v48, 16, v117
	v_and_b32_e32 v49, 0xffff0000, v117
	v_fma_f32 v26, v122, v26, v48
	v_fma_f32 v27, v123, v27, v49
	v_lshlrev_b32_e32 v48, 16, v118
	v_and_b32_e32 v49, 0xffff0000, v118
	v_fma_f32 v28, v124, v28, v48
	v_fma_f32 v29, v125, v29, v49
	v_lshlrev_b32_e32 v48, 16, v119
	v_and_b32_e32 v49, 0xffff0000, v119
	v_fma_f32 v30, v126, v30, v48
	v_fma_f32 v31, v127, v31, v49
	global_load_dwordx4 v[112:115], v2, s[6:7] nt
	global_load_dwordx4 v[116:119], v3, s[6:7] nt
	global_load_dwordx4 v[120:123], v5, s[12:13]
	global_load_dwordx4 v[124:127], v5, s[12:13] offset:16
	s_add_u32 s6, s6, 0x40000
	s_addc_u32 s7, s7, 0
	s_add_u32 s12, s12, 2048
	s_addc_u32 s13, s13, 0
	s_waitcnt vmcnt(42)
	v_cvt_pk_bf16_f32 v32, v16, v17
	v_cvt_pk_bf16_f32 v33, v18, v19
	v_cvt_pk_bf16_f32 v34, v20, v21
	v_cvt_pk_bf16_f32 v35, v22, v23
	global_store_dwordx4 v2, v[32:35], s[10:11] nt
	v_cvt_pk_bf16_f32 v36, v24, v25
	v_cvt_pk_bf16_f32 v37, v26, v27
	v_cvt_pk_bf16_f32 v38, v28, v29
	v_cvt_pk_bf16_f32 v39, v30, v31
	global_store_dwordx4 v3, v[36:39], s[10:11] nt
	s_add_u32 s10, s10, 0x40000
	s_addc_u32 s11, s11, 0
	v_lshlrev_b32_e32 v48, 16, v128
	v_and_b32_e32 v49, 0xffff0000, v128
	v_fma_f32 v16, v136, v16, v48
	v_fma_f32 v17, v137, v17, v49
	v_lshlrev_b32_e32 v48, 16, v129
	v_and_b32_e32 v49, 0xffff0000, v129
	v_fma_f32 v18, v138, v18, v48
	v_fma_f32 v19, v139, v19, v49
	v_lshlrev_b32_e32 v48, 16, v130
	v_and_b32_e32 v49, 0xffff0000, v130
	v_fma_f32 v20, v140, v20, v48
	v_fma_f32 v21, v141, v21, v49
	v_lshlrev_b32_e32 v48, 16, v131
	v_and_b32_e32 v49, 0xffff0000, v131
	v_fma_f32 v22, v142, v22, v48
	v_fma_f32 v23, v143, v23, v49
	v_lshlrev_b32_e32 v48, 16, v132
	v_and_b32_e32 v49, 0xffff0000, v132
	v_fma_f32 v24, v136, v24, v48
	v_fma_f32 v25, v137, v25, v49
	v_lshlrev_b32_e32 v48, 16, v133
	v_and_b32_e32 v49, 0xffff0000, v133
	v_fma_f32 v26, v138, v26, v48
	v_fma_f32 v27, v139, v27, v49
	v_lshlrev_b32_e32 v48, 16, v134
	v_and_b32_e32 v49, 0xffff0000, v134
	v_fma_f32 v28, v140, v28, v48
	v_fma_f32 v29, v141, v29, v49
	v_lshlrev_b32_e32 v48, 16, v135
	v_and_b32_e32 v49, 0xffff0000, v135
	v_fma_f32 v30, v142, v30, v48
	v_fma_f32 v31, v143, v31, v49
	global_load_dwordx4 v[128:131], v2, s[6:7] nt
	global_load_dwordx4 v[132:135], v3, s[6:7] nt
	global_load_dwordx4 v[136:139], v5, s[12:13]
	global_load_dwordx4 v[140:143], v5, s[12:13] offset:16
	s_add_u32 s6, s6, 0x40000
	s_addc_u32 s7, s7, 0
	s_add_u32 s12, s12, 2048
	s_addc_u32 s13, s13, 0
	s_waitcnt vmcnt(42)
; __device__ __forceinline__ float bf2f(unsigned h) { return __uint_as_float(h << 16); }
; __device__ __forceinline__ unsigned pk2(float lo, float hi) { return pg8::cvt_pk_bf16(lo, hi); }
; __device__ __forceinline__ void b2_scan(const Ctx& C) {
;     ...
;     B2_LOAD(0, 0);
; #pragma unroll
;     for (int g = 0; g < 8; ++g) {
;         const int cur = g & 1;
;         if (g + 1 < 8) B2_LOAD(g + 1, cur ^ 1);
; #pragma unroll
;         for (int k = 0; k < 4; ++k) {
;             const int c = 4 * g + k;
;             const float dd[8] = {d0[cur][k][0], d0[cur][k][1], d0[cur][k][2], d0[cur][k][3], d1[cur][k][0], d1[cur][k][1], d1[cur][k][2], d1[cur][k][3]};
; #pragma unroll
;             for (int j = 0; j < 2; ++j) {
;                 v4u o; o.x = pk2(run[j][0], run[j][1]); o.y = pk2(run[j][2], run[j][3]); o.z = pk2(run[j][4], run[j][5]); o.w = pk2(run[j][6], run[j][7]);
;                 __builtin_nontemporal_store(o, (v4u*)(base + (size_t)c * cstride + (size_t)j * vstride));
;                 const unsigned lw[4] = {loc[cur][k][j].x, loc[cur][k][j].y, loc[cur][k][j].z, loc[cur][k][j].w};
; #pragma unroll
;                 for (int q = 0; q < 4; ++q) {
;                     run[j][2 * q] = dd[2 * q] * run[j][2 * q] + bf2f(lw[q] & 0xffffu);
;                     run[j][2 * q + 1] = dd[2 * q + 1] * run[j][2 * q + 1] + __uint_as_float(lw[q] & 0xffff0000u);
;                 }
	v_cvt_pk_bf16_f32 v40, v16, v17
	v_cvt_pk_bf16_f32 v41, v18, v19
	v_cvt_pk_bf16_f32 v42, v20, v21
	v_cvt_pk_bf16_f32 v43, v22, v23
	global_store_dwordx4 v2, v[40:43], s[10:11] nt
	v_cvt_pk_bf16_f32 v44, v24, v25
	v_cvt_pk_bf16_f32 v45, v26, v27
	v_cvt_pk_bf16_f32 v46, v28, v29
	v_cvt_pk_bf16_f32 v47, v30, v31
	global_store_dwordx4 v3, v[44:47], s[10:11] nt
	s_add_u32 s10, s10, 0x40000
	s_addc_u32 s11, s11, 0
	v_lshlrev_b32_e32 v48, 16, v144
	v_and_b32_e32 v49, 0xffff0000, v144
	v_fma_f32 v16, v152, v16, v48
	v_fma_f32 v17, v153, v17, v49
	v_lshlrev_b32_e32 v48, 16, v145
	v_and_b32_e32 v49, 0xffff0000, v145
	v_fma_f32 v18, v154, v18, v48
	v_fma_f32 v19, v155, v19, v49
	v_lshlrev_b32_e32 v48, 16, v146
	v_and_b32_e32 v49, 0xffff0000, v146
	v_fma_f32 v20, v156, v20, v48
	v_fma_f32 v21, v157, v21, v49
	v_lshlrev_b32_e32 v48, 16, v147
	v_and_b32_e32 v49, 0xffff0000, v147
	v_fma_f32 v22, v158, v22, v48
	v_fma_f32 v23, v159, v23, v49
	v_lshlrev_b32_e32 v48, 16, v148
	v_and_b32_e32 v49, 0xffff0000, v148
	v_fma_f32 v24, v152, v24, v48
	v_fma_f32 v25, v153, v25, v49
	v_lshlrev_b32_e32 v48, 16, v149
	v_and_b32_e32 v49, 0xffff0000, v149
	v_fma_f32 v26, v154, v26, v48
	v_fma_f32 v27, v155, v27, v49
	v_lshlrev_b32_e32 v48, 16, v150
	v_and_b32_e32 v49, 0xffff0000, v150
	v_fma_f32 v28, v156, v28, v48
	v_fma_f32 v29, v157, v29, v49
	v_lshlrev_b32_e32 v48, 16, v151
	v_and_b32_e32 v49, 0xffff0000, v151
	v_fma_f32 v30, v158, v30, v48
	v_fma_f32 v31, v159, v31, v49
	global_load_dwordx4 v[144:147], v2, s[6:7] nt
	global_load_dwordx4 v[148:151], v3, s[6:7] nt
	global_load_dwordx4 v[152:155], v5, s[12:13]
	global_load_dwordx4 v[156:159], v5, s[12:13] offset:16
	s_add_u32 s6, s6, 0x40000
	s_addc_u32 s7, s7, 0
	s_add_u32 s12, s12, 2048
	s_addc_u32 s13, s13, 0
	s_waitcnt vmcnt(42)
	v_cvt_pk_bf16_f32 v32, v16, v17
	v_cvt_pk_bf16_f32 v33, v18, v19
	v_cvt_pk_bf16_f32 v34, v20, v21
	v_cvt_pk_bf16_f32 v35, v22, v23
	global_store_dwordx4 v2, v[32:35], s[10:11] nt
	v_cvt_pk_bf16_f32 v36, v24, v25
	v_cvt_pk_bf16_f32 v37, v26, v27
	v_cvt_pk_bf16_f32 v38, v28, v29
	v_cvt_pk_bf16_f32 v39, v30, v31
	global_store_dwordx4 v3, v[36:39], s[10:11] nt
	s_add_u32 s10, s10, 0x40000
	s_addc_u32 s11, s11, 0
	v_lshlrev_b32_e32 v48, 16, v160
	v_and_b32_e32 v49, 0xffff0000, v160
	v_fma_f32 v16, v168, v16, v48
	v_fma_f32 v17, v169, v17, v49
	v_lshlrev_b32_e32 v48, 16, v161
	v_and_b32_e32 v49, 0xffff0000, v161
	v_fma_f32 v18, v170, v18, v48
	v_fma_f32 v19, v171, v19, v49
	v_lshlrev_b32_e32 v48, 16, v162
	v_and_b32_e32 v49, 0xffff0000, v162
	v_fma_f32 v20, v172, v20, v48
	v_fma_f32 v21, v173, v21, v49
	v_lshlrev_b32_e32 v48, 16, v163
	v_and_b32_e32 v49, 0xffff0000, v163
	v_fma_f32 v22, v174, v22, v48
	v_fma_f32 v23, v175, v23, v49
	v_lshlrev_b32_e32 v48, 16, v164
	v_and_b32_e32 v49, 0xffff0000, v164
	v_fma_f32 v24, v168, v24, v48
	v_fma_f32 v25, v169, v25, v49
	v_lshlrev_b32_e32 v48, 16, v165
	v_and_b32_e32 v49, 0xffff0000, v165
	v_fma_f32 v26, v170, v26, v48
	v_fma_f32 v27, v171, v27, v49
	v_lshlrev_b32_e32 v48, 16, v166
	v_and_b32_e32 v49, 0xffff0000, v166
	v_fma_f32 v28, v172, v28, v48
	v_fma_f32 v29, v173, v29, v49
	v_lshlrev_b32_e32 v48, 16, v167
	v_and_b32_e32 v49, 0xffff0000, v167
	v_fma_f32 v30, v174, v30, v48
	v_fma_f32 v31, v175, v31, v49
	global_load_dwordx4 v[160:163], v2, s[6:7] nt
	global_load_dwordx4 v[164:167], v3, s[6:7] nt
	global_load_dwordx4 v[168:171], v5, s[12:13]
	global_load_dwordx4 v[172:175], v5, s[12:13] offset:16
	s_add_u32 s6, s6, 0x40000
	s_addc_u32 s7, s7, 0
	s_add_u32 s12, s12, 2048
	s_addc_u32 s13, s13, 0
	s_waitcnt vmcnt(42)
	v_cvt_pk_bf16_f32 v40, v16, v17
	v_cvt_pk_bf16_f32 v41, v18, v19
	v_cvt_pk_bf16_f32 v42, v20, v21
	v_cvt_pk_bf16_f32 v43, v22, v23
	global_store_dwordx4 v2, v[40:43], s[10:11] nt
	v_cvt_pk_bf16_f32 v44, v24, v25
	v_cvt_pk_bf16_f32 v45, v26, v27
	v_cvt_pk_bf16_f32 v46, v28, v29
	v_cvt_pk_bf16_f32 v47, v30, v31
	global_store_dwordx4 v3, v[44:47], s[10:11] nt
	s_add_u32 s10, s10, 0x40000
	s_addc_u32 s11, s11, 0
	v_lshlrev_b32_e32 v48, 16, v176
	v_and_b32_e32 v49, 0xffff0000, v176
	v_fma_f32 v16, v184, v16, v48
	v_fma_f32 v17, v185, v17, v49
	v_lshlrev_b32_e32 v48, 16, v177
	v_and_b32_e32 v49, 0xffff0000, v177
	v_fma_f32 v18, v186, v18, v48
	v_fma_f32 v19, v187, v19, v49
	v_lshlrev_b32_e32 v48, 16, v178
	v_and_b32_e32 v49, 0xffff0000, v178
	v_fma_f32 v20, v188, v20, v48
	v_fma_f32 v21, v189, v21, v49
	v_lshlrev_b32_e32 v48, 16, v179
	v_and_b32_e32 v49, 0xffff0000, v179
	v_fma_f32 v22, v190, v22, v48
	v_fma_f32 v23, v191, v23, v49
	v_lshlrev_b32_e32 v48, 16, v180
	v_and_b32_e32 v49, 0xffff0000, v180
	v_fma_f32 v24, v184, v24, v48
	v_fma_f32 v25, v185, v25, v49
	v_lshlrev_b32_e32 v48, 16, v181
	v_and_b32_e32 v49, 0xffff0000, v181
	v_fma_f32 v26, v186, v26, v48
	v_fma_f32 v27, v187, v27, v49
	v_lshlrev_b32_e32 v48, 16, v182
	v_and_b32_e32 v49, 0xffff0000, v182
	v_fma_f32 v28, v188, v28, v48
	v_fma_f32 v29, v189, v29, v49
	v_lshlrev_b32_e32 v48, 16, v183
	v_and_b32_e32 v49, 0xffff0000, v183
	v_fma_f32 v30, v190, v30, v48
	v_fma_f32 v31, v191, v31, v49
	global_load_dwordx4 v[176:179], v2, s[6:7] nt
	global_load_dwordx4 v[180:183], v3, s[6:7] nt
	global_load_dwordx4 v[184:187], v5, s[12:13]
	global_load_dwordx4 v[188:191], v5, s[12:13] offset:16
	s_add_u32 s6, s6, 0x40000
	s_addc_u32 s7, s7, 0
	s_add_u32 s12, s12, 2048
	s_addc_u32 s13, s13, 0
	s_waitcnt vmcnt(42)
; __device__ __forceinline__ float bf2f(unsigned h) { return __uint_as_float(h << 16); }
; __device__ __forceinline__ unsigned pk2(float lo, float hi) { return pg8::cvt_pk_bf16(lo, hi); }
; __device__ __forceinline__ void b2_scan(const Ctx& C) {
;     ...
;     B2_LOAD(0, 0);
; #pragma unroll
;     for (int g = 0; g < 8; ++g) {
;         const int cur = g & 1;
;         if (g + 1 < 8) B2_LOAD(g + 1, cur ^ 1);
; #pragma unroll
;         for (int k = 0; k < 4; ++k) {
;             const int c = 4 * g + k;
;             const float dd[8] = {d0[cur][k][0], d0[cur][k][1], d0[cur][k][2], d0[cur][k][3], d1[cur][k][0], d1[cur][k][1], d1[cur][k][2], d1[cur][k][3]};
; #pragma unroll
;             for (int j = 0; j < 2; ++j) {
;                 v4u o; o.x = pk2(run[j][0], run[j][1]); o.y = pk2(run[j][2], run[j][3]); o.z = pk2(run[j][4], run[j][5]); o.w = pk2(run[j][6], run[j][7]);
;                 __builtin_nontemporal_store(o, (v4u*)(base + (size_t)c * cstride + (size_t)j * vstride));
;                 const unsigned lw[4] = {loc[cur][k][j].x, loc[cur][k][j].y, loc[cur][k][j].z, loc[cur][k][j].w};
; #pragma unroll
;                 for (int q = 0; q < 4; ++q) {
;                     run[j][2 * q] = dd[2 * q] * run[j][2 * q] + bf2f(lw[q] & 0xffffu);
;                     run[j][2 * q + 1] = dd[2 * q + 1] * run[j][2 * q + 1] + __uint_as_float(lw[q] & 0xffff0000u);
;                 }
	v_cvt_pk_bf16_f32 v32, v16, v17
	v_cvt_pk_bf16_f32 v33, v18, v19
	v_cvt_pk_bf16_f32 v34, v20, v21
	v_cvt_pk_bf16_f32 v35, v22, v23
	global_store_dwordx4 v2, v[32:35], s[10:11] nt
	v_cvt_pk_bf16_f32 v36, v24, v25
	v_cvt_pk_bf16_f32 v37, v26, v27
	v_cvt_pk_bf16_f32 v38, v28, v29
	v_cvt_pk_bf16_f32 v39, v30, v31
	global_store_dwordx4 v3, v[36:39], s[10:11] nt
	s_add_u32 s10, s10, 0x40000
	s_addc_u32 s11, s11, 0
	v_lshlrev_b32_e32 v48, 16, v64
	v_and_b32_e32 v49, 0xffff0000, v64
	v_fma_f32 v16, v72, v16, v48
	v_fma_f32 v17, v73, v17, v49
	v_lshlrev_b32_e32 v48, 16, v65
	v_and_b32_e32 v49, 0xffff0000, v65
	v_fma_f32 v18, v74, v18, v48
	v_fma_f32 v19, v75, v19, v49
	v_lshlrev_b32_e32 v48, 16, v66
	v_and_b32_e32 v49, 0xffff0000, v66
	v_fma_f32 v20, v76, v20, v48
	v_fma_f32 v21, v77, v21, v49
	v_lshlrev_b32_e32 v48, 16, v67
	v_and_b32_e32 v49, 0xffff0000, v67
	v_fma_f32 v22, v78, v22, v48
	v_fma_f32 v23, v79, v23, v49
	v_lshlrev_b32_e32 v48, 16, v68
	v_and_b32_e32 v49, 0xffff0000, v68
	v_fma_f32 v24, v72, v24, v48
	v_fma_f32 v25, v73, v25, v49
	v_lshlrev_b32_e32 v48, 16, v69
	v_and_b32_e32 v49, 0xffff0000, v69
	v_fma_f32 v26, v74, v26, v48
	v_fma_f32 v27, v75, v27, v49
	v_lshlrev_b32_e32 v48, 16, v70
	v_and_b32_e32 v49, 0xffff0000, v70
	v_fma_f32 v28, v76, v28, v48
	v_fma_f32 v29, v77, v29, v49
	v_lshlrev_b32_e32 v48, 16, v71
	v_and_b32_e32 v49, 0xffff0000, v71
	v_fma_f32 v30, v78, v30, v48
	v_fma_f32 v31, v79, v31, v49
	global_load_dwordx4 v[64:67], v2, s[6:7] nt
	global_load_dwordx4 v[68:71], v3, s[6:7] nt
	global_load_dwordx4 v[72:75], v5, s[12:13]
	global_load_dwordx4 v[76:79], v5, s[12:13] offset:16
	s_add_u32 s6, s6, 0x40000
	s_addc_u32 s7, s7, 0
	s_add_u32 s12, s12, 2048
	s_addc_u32 s13, s13, 0
	s_waitcnt vmcnt(42)
	v_cvt_pk_bf16_f32 v40, v16, v17
	v_cvt_pk_bf16_f32 v41, v18, v19
	v_cvt_pk_bf16_f32 v42, v20, v21
	v_cvt_pk_bf16_f32 v43, v22, v23
	global_store_dwordx4 v2, v[40:43], s[10:11] nt
	v_cvt_pk_bf16_f32 v44, v24, v25
	v_cvt_pk_bf16_f32 v45, v26, v27
	v_cvt_pk_bf16_f32 v46, v28, v29
	v_cvt_pk_bf16_f32 v47, v30, v31
	global_store_dwordx4 v3, v[44:47], s[10:11] nt
	s_add_u32 s10, s10, 0x40000
	s_addc_u32 s11, s11, 0
	v_lshlrev_b32_e32 v48, 16, v80
	v_and_b32_e32 v49, 0xffff0000, v80
	v_fma_f32 v16, v88, v16, v48
	v_fma_f32 v17, v89, v17, v49
	v_lshlrev_b32_e32 v48, 16, v81
	v_and_b32_e32 v49, 0xffff0000, v81
	v_fma_f32 v18, v90, v18, v48
	v_fma_f32 v19, v91, v19, v49
	v_lshlrev_b32_e32 v48, 16, v82
	v_and_b32_e32 v49, 0xffff0000, v82
	v_fma_f32 v20, v92, v20, v48
	v_fma_f32 v21, v93, v21, v49
	v_lshlrev_b32_e32 v48, 16, v83
	v_and_b32_e32 v49, 0xffff0000, v83
	v_fma_f32 v22, v94, v22, v48
	v_fma_f32 v23, v95, v23, v49
	v_lshlrev_b32_e32 v48, 16, v84
	v_and_b32_e32 v49, 0xffff0000, v84
	v_fma_f32 v24, v88, v24, v48
	v_fma_f32 v25, v89, v25, v49
	v_lshlrev_b32_e32 v48, 16, v85
	v_and_b32_e32 v49, 0xffff0000, v85
	v_fma_f32 v26, v90, v26, v48
	v_fma_f32 v27, v91, v27, v49
	v_lshlrev_b32_e32 v48, 16, v86
	v_and_b32_e32 v49, 0xffff0000, v86
	v_fma_f32 v28, v92, v28, v48
	v_fma_f32 v29, v93, v29, v49
	v_lshlrev_b32_e32 v48, 16, v87
	v_and_b32_e32 v49, 0xffff0000, v87
	v_fma_f32 v30, v94, v30, v48
	v_fma_f32 v31, v95, v31, v49
	global_load_dwordx4 v[80:83], v2, s[6:7] nt
	global_load_dwordx4 v[84:87], v3, s[6:7] nt
	global_load_dwordx4 v[88:91], v5, s[12:13]
	global_load_dwordx4 v[92:95], v5, s[12:13] offset:16
	s_add_u32 s6, s6, 0x40000
	s_addc_u32 s7, s7, 0
	s_add_u32 s12, s12, 2048
	s_addc_u32 s13, s13, 0
	s_waitcnt vmcnt(42)
	v_cvt_pk_bf16_f32 v32, v16, v17
	v_cvt_pk_bf16_f32 v33, v18, v19
	v_cvt_pk_bf16_f32 v34, v20, v21
	v_cvt_pk_bf16_f32 v35, v22, v23
	global_store_dwordx4 v2, v[32:35], s[10:11] nt
	v_cvt_pk_bf16_f32 v36, v24, v25
	v_cvt_pk_bf16_f32 v37, v26, v27
	v_cvt_pk_bf16_f32 v38, v28, v29
	v_cvt_pk_bf16_f32 v39, v30, v31
	global_store_dwordx4 v3, v[36:39], s[10:11] nt
	s_add_u32 s10, s10, 0x40000
	s_addc_u32 s11, s11, 0
	v_lshlrev_b32_e32 v48, 16, v96
	v_and_b32_e32 v49, 0xffff0000, v96
	v_fma_f32 v16, v104, v16, v48
	v_fma_f32 v17, v105, v17, v49
	v_lshlrev_b32_e32 v48, 16, v97
	v_and_b32_e32 v49, 0xffff0000, v97
	v_fma_f32 v18, v106, v18, v48
	v_fma_f32 v19, v107, v19, v49
	v_lshlrev_b32_e32 v48, 16, v98
	v_and_b32_e32 v49, 0xffff0000, v98
	v_fma_f32 v20, v108, v20, v48
	v_fma_f32 v21, v109, v21, v49
	v_lshlrev_b32_e32 v48, 16, v99
	v_and_b32_e32 v49, 0xffff0000, v99
	v_fma_f32 v22, v110, v22, v48
	v_fma_f32 v23, v111, v23, v49
	v_lshlrev_b32_e32 v48, 16, v100
	v_and_b32_e32 v49, 0xffff0000, v100
	v_fma_f32 v24, v104, v24, v48
	v_fma_f32 v25, v105, v25, v49
	v_lshlrev_b32_e32 v48, 16, v101
	v_and_b32_e32 v49, 0xffff0000, v101
	v_fma_f32 v26, v106, v26, v48
	v_fma_f32 v27, v107, v27, v49
	v_lshlrev_b32_e32 v48, 16, v102
	v_and_b32_e32 v49, 0xffff0000, v102
	v_fma_f32 v28, v108, v28, v48
	v_fma_f32 v29, v109, v29, v49
	v_lshlrev_b32_e32 v48, 16, v103
	v_and_b32_e32 v49, 0xffff0000, v103
	v_fma_f32 v30, v110, v30, v48
	v_fma_f32 v31, v111, v31, v49
	global_load_dwordx4 v[96:99], v2, s[6:7] nt
	global_load_dwordx4 v[100:103], v3, s[6:7] nt
	global_load_dwordx4 v[104:107], v5, s[12:13]
	global_load_dwordx4 v[108:111], v5, s[12:13] offset:16
	s_add_u32 s6, s6, 0x40000
	s_addc_u32 s7, s7, 0
	s_add_u32 s12, s12, 2048
	s_addc_u32 s13, s13, 0
	s_waitcnt vmcnt(42)
; __device__ __forceinline__ float bf2f(unsigned h) { return __uint_as_float(h << 16); }
; __device__ __forceinline__ unsigned pk2(float lo, float hi) { return pg8::cvt_pk_bf16(lo, hi); }
; __device__ __forceinline__ void b2_scan(const Ctx& C) {
;     ...
;     B2_LOAD(0, 0);
; #pragma unroll
;     for (int g = 0; g < 8; ++g) {
;         const int cur = g & 1;
;         if (g + 1 < 8) B2_LOAD(g + 1, cur ^ 1);
; #pragma unroll
;         for (int k = 0; k < 4; ++k) {
;             const int c = 4 * g + k;
;             const float dd[8] = {d0[cur][k][0], d0[cur][k][1], d0[cur][k][2], d0[cur][k][3], d1[cur][k][0], d1[cur][k][1], d1[cur][k][2], d1[cur][k][3]};
; #pragma unroll
;             for (int j = 0; j < 2; ++j) {
;                 v4u o; o.x = pk2(run[j][0], run[j][1]); o.y = pk2(run[j][2], run[j][3]); o.z = pk2(run[j][4], run[j][5]); o.w = pk2(run[j][6], run[j][7]);
;                 __builtin_nontemporal_store(o, (v4u*)(base + (size_t)c * cstride + (size_t)j * vstride));
;                 const unsigned lw[4] = {loc[cur][k][j].x, loc[cur][k][j].y, loc[cur][k][j].z, loc[cur][k][j].w};
; #pragma unroll
;                 for (int q = 0; q < 4; ++q) {
;                     run[j][2 * q] = dd[2 * q] * run[j][2 * q] + bf2f(lw[q] & 0xffffu);
;                     run[j][2 * q + 1] = dd[2 * q + 1] * run[j][2 * q + 1] + __uint_as_float(lw[q] & 0xffff0000u);
;                 }
	v_cvt_pk_bf16_f32 v40, v16, v17
	v_cvt_pk_bf16_f32 v41, v18, v19
	v_cvt_pk_bf16_f32 v42, v20, v21
	v_cvt_pk_bf16_f32 v43, v22, v23
	global_store_dwordx4 v2, v[40:43], s[10:11] nt
	v_cvt_pk_bf16_f32 v44, v24, v25
	v_cvt_pk_bf16_f32 v45, v26, v27
	v_cvt_pk_bf16_f32 v46, v28, v29
	v_cvt_pk_bf16_f32 v47, v30, v31
	global_store_dwordx4 v3, v[44:47], s[10:11] nt
	s_add_u32 s10, s10, 0x40000
	s_addc_u32 s11, s11, 0
	v_lshlrev_b32_e32 v48, 16, v112
	v_and_b32_e32 v49, 0xffff0000, v112
	v_fma_f32 v16, v120, v16, v48
	v_fma_f32 v17, v121, v17, v49
	v_lshlrev_b32_e32 v48, 16, v113
	v_and_b32_e32 v49, 0xffff0000, v113
	v_fma_f32 v18, v122, v18, v48
	v_fma_f32 v19, v123, v19, v49
	v_lshlrev_b32_e32 v48, 16, v114
	v_and_b32_e32 v49, 0xffff0000, v114
	v_fma_f32 v20, v124, v20, v48
	v_fma_f32 v21, v125, v21, v49
	v_lshlrev_b32_e32 v48, 16, v115
	v_and_b32_e32 v49, 0xffff0000, v115
	v_fma_f32 v22, v126, v22, v48
	v_fma_f32 v23, v127, v23, v49
	v_lshlrev_b32_e32 v48, 16, v116
	v_and_b32_e32 v49, 0xffff0000, v116
	v_fma_f32 v24, v120, v24, v48
	v_fma_f32 v25, v121, v25, v49
	v_lshlrev_b32_e32 v48, 16, v117
	v_and_b32_e32 v49, 0xffff0000, v117
	v_fma_f32 v26, v122, v26, v48
	v_fma_f32 v27, v123, v27, v49
	v_lshlrev_b32_e32 v48, 16, v118
	v_and_b32_e32 v49, 0xffff0000, v118
	v_fma_f32 v28, v124, v28, v48
	v_fma_f32 v29, v125, v29, v49
	v_lshlrev_b32_e32 v48, 16, v119
	v_and_b32_e32 v49, 0xffff0000, v119
	v_fma_f32 v30, v126, v30, v48
	v_fma_f32 v31, v127, v31, v49
	global_load_dwordx4 v[112:115], v2, s[6:7] nt
	global_load_dwordx4 v[116:119], v3, s[6:7] nt
	global_load_dwordx4 v[120:123], v5, s[12:13]
	global_load_dwordx4 v[124:127], v5, s[12:13] offset:16
	s_add_u32 s6, s6, 0x40000
	s_addc_u32 s7, s7, 0
	s_add_u32 s12, s12, 2048
	s_addc_u32 s13, s13, 0
	s_waitcnt vmcnt(42)
	v_cvt_pk_bf16_f32 v32, v16, v17
	v_cvt_pk_bf16_f32 v33, v18, v19
	v_cvt_pk_bf16_f32 v34, v20, v21
	v_cvt_pk_bf16_f32 v35, v22, v23
	global_store_dwordx4 v2, v[32:35], s[10:11] nt
	v_cvt_pk_bf16_f32 v36, v24, v25
	v_cvt_pk_bf16_f32 v37, v26, v27
	v_cvt_pk_bf16_f32 v38, v28, v29
	v_cvt_pk_bf16_f32 v39, v30, v31
	global_store_dwordx4 v3, v[36:39], s[10:11] nt
	s_add_u32 s10, s10, 0x40000
	s_addc_u32 s11, s11, 0
	v_lshlrev_b32_e32 v48, 16, v128
	v_and_b32_e32 v49, 0xffff0000, v128
	v_fma_f32 v16, v136, v16, v48
	v_fma_f32 v17, v137, v17, v49
	v_lshlrev_b32_e32 v48, 16, v129
	v_and_b32_e32 v49, 0xffff0000, v129
	v_fma_f32 v18, v138, v18, v48
	v_fma_f32 v19, v139, v19, v49
	v_lshlrev_b32_e32 v48, 16, v130
	v_and_b32_e32 v49, 0xffff0000, v130
	v_fma_f32 v20, v140, v20, v48
	v_fma_f32 v21, v141, v21, v49
	v_lshlrev_b32_e32 v48, 16, v131
	v_and_b32_e32 v49, 0xffff0000, v131
	v_fma_f32 v22, v142, v22, v48
	v_fma_f32 v23, v143, v23, v49
	v_lshlrev_b32_e32 v48, 16, v132
	v_and_b32_e32 v49, 0xffff0000, v132
	v_fma_f32 v24, v136, v24, v48
	v_fma_f32 v25, v137, v25, v49
	v_lshlrev_b32_e32 v48, 16, v133
	v_and_b32_e32 v49, 0xffff0000, v133
	v_fma_f32 v26, v138, v26, v48
	v_fma_f32 v27, v139, v27, v49
	v_lshlrev_b32_e32 v48, 16, v134
	v_and_b32_e32 v49, 0xffff0000, v134
	v_fma_f32 v28, v140, v28, v48
	v_fma_f32 v29, v141, v29, v49
	v_lshlrev_b32_e32 v48, 16, v135
	v_and_b32_e32 v49, 0xffff0000, v135
	v_fma_f32 v30, v142, v30, v48
	v_fma_f32 v31, v143, v31, v49
	global_load_dwordx4 v[128:131], v2, s[6:7] nt
	global_load_dwordx4 v[132:135], v3, s[6:7] nt
	global_load_dwordx4 v[136:139], v5, s[12:13]
	global_load_dwordx4 v[140:143], v5, s[12:13] offset:16
	s_add_u32 s6, s6, 0x40000
	s_addc_u32 s7, s7, 0
	s_add_u32 s12, s12, 2048
	s_addc_u32 s13, s13, 0
	s_waitcnt vmcnt(42)
	v_cvt_pk_bf16_f32 v40, v16, v17
	v_cvt_pk_bf16_f32 v41, v18, v19
	v_cvt_pk_bf16_f32 v42, v20, v21
	v_cvt_pk_bf16_f32 v43, v22, v23
	global_store_dwordx4 v2, v[40:43], s[10:11] nt
	v_cvt_pk_bf16_f32 v44, v24, v25
	v_cvt_pk_bf16_f32 v45, v26, v27
	v_cvt_pk_bf16_f32 v46, v28, v29
	v_cvt_pk_bf16_f32 v47, v30, v31
	global_store_dwordx4 v3, v[44:47], s[10:11] nt
	s_add_u32 s10, s10, 0x40000
	s_addc_u32 s11, s11, 0
	v_lshlrev_b32_e32 v48, 16, v144
	v_and_b32_e32 v49, 0xffff0000, v144
	v_fma_f32 v16, v152, v16, v48
	v_fma_f32 v17, v153, v17, v49
	v_lshlrev_b32_e32 v48, 16, v145
	v_and_b32_e32 v49, 0xffff0000, v145
	v_fma_f32 v18, v154, v18, v48
	v_fma_f32 v19, v155, v19, v49
	v_lshlrev_b32_e32 v48, 16, v146
	v_and_b32_e32 v49, 0xffff0000, v146
	v_fma_f32 v20, v156, v20, v48
	v_fma_f32 v21, v157, v21, v49
	v_lshlrev_b32_e32 v48, 16, v147
	v_and_b32_e32 v49, 0xffff0000, v147
	v_fma_f32 v22, v158, v22, v48
	v_fma_f32 v23, v159, v23, v49
	v_lshlrev_b32_e32 v48, 16, v148
	v_and_b32_e32 v49, 0xffff0000, v148
	v_fma_f32 v24, v152, v24, v48
	v_fma_f32 v25, v153, v25, v49
	v_lshlrev_b32_e32 v48, 16, v149
	v_and_b32_e32 v49, 0xffff0000, v149
	v_fma_f32 v26, v154, v26, v48
	v_fma_f32 v27, v155, v27, v49
	v_lshlrev_b32_e32 v48, 16, v150
	v_and_b32_e32 v49, 0xffff0000, v150
	v_fma_f32 v28, v156, v28, v48
	v_fma_f32 v29, v157, v29, v49
	v_lshlrev_b32_e32 v48, 16, v151
	v_and_b32_e32 v49, 0xffff0000, v151
	v_fma_f32 v30, v158, v30, v48
	v_fma_f32 v31, v159, v31, v49
	global_load_dwordx4 v[144:147], v2, s[6:7] nt
	global_load_dwordx4 v[148:151], v3, s[6:7] nt
	global_load_dwordx4 v[152:155], v5, s[12:13]
	global_load_dwordx4 v[156:159], v5, s[12:13] offset:16
	s_add_u32 s6, s6, 0x40000
	s_addc_u32 s7, s7, 0
	s_add_u32 s12, s12, 2048
	s_addc_u32 s13, s13, 0
	s_waitcnt vmcnt(42)
; __device__ __forceinline__ float bf2f(unsigned h) { return __uint_as_float(h << 16); }
; __device__ __forceinline__ unsigned pk2(float lo, float hi) { return pg8::cvt_pk_bf16(lo, hi); }
; __device__ __forceinline__ void b2_scan(const Ctx& C) {
;     ...
;     B2_LOAD(0, 0);
; #pragma unroll
;     for (int g = 0; g < 8; ++g) {
;         const int cur = g & 1;
;         if (g + 1 < 8) B2_LOAD(g + 1, cur ^ 1);
; #pragma unroll
;         for (int k = 0; k < 4; ++k) {
;             const int c = 4 * g + k;
;             const float dd[8] = {d0[cur][k][0], d0[cur][k][1], d0[cur][k][2], d0[cur][k][3], d1[cur][k][0], d1[cur][k][1], d1[cur][k][2], d1[cur][k][3]};
; #pragma unroll
;             for (int j = 0; j < 2; ++j) {
;                 v4u o; o.x = pk2(run[j][0], run[j][1]); o.y = pk2(run[j][2], run[j][3]); o.z = pk2(run[j][4], run[j][5]); o.w = pk2(run[j][6], run[j][7]);
;                 __builtin_nontemporal_store(o, (v4u*)(base + (size_t)c * cstride + (size_t)j * vstride));
;                 const unsigned lw[4] = {loc[cur][k][j].x, loc[cur][k][j].y, loc[cur][k][j].z, loc[cur][k][j].w};
; #pragma unroll
;                 for (int q = 0; q < 4; ++q) {
;                     run[j][2 * q] = dd[2 * q] * run[j][2 * q] + bf2f(lw[q] & 0xffffu);
;                     run[j][2 * q + 1] = dd[2 * q + 1] * run[j][2 * q + 1] + __uint_as_float(lw[q] & 0xffff0000u);
;                 }
	v_cvt_pk_bf16_f32 v32, v16, v17
	v_cvt_pk_bf16_f32 v33, v18, v19
	v_cvt_pk_bf16_f32 v34, v20, v21
	v_cvt_pk_bf16_f32 v35, v22, v23
	global_store_dwordx4 v2, v[32:35], s[10:11] nt
	v_cvt_pk_bf16_f32 v36, v24, v25
	v_cvt_pk_bf16_f32 v37, v26, v27
	v_cvt_pk_bf16_f32 v38, v28, v29
	v_cvt_pk_bf16_f32 v39, v30, v31
	global_store_dwordx4 v3, v[36:39], s[10:11] nt
	s_add_u32 s10, s10, 0x40000
	s_addc_u32 s11, s11, 0
	v_lshlrev_b32_e32 v48, 16, v160
	v_and_b32_e32 v49, 0xffff0000, v160
	v_fma_f32 v16, v168, v16, v48
	v_fma_f32 v17, v169, v17, v49
	v_lshlrev_b32_e32 v48, 16, v161
	v_and_b32_e32 v49, 0xffff0000, v161
	v_fma_f32 v18, v170, v18, v48
	v_fma_f32 v19, v171, v19, v49
	v_lshlrev_b32_e32 v48, 16, v162
	v_and_b32_e32 v49, 0xffff0000, v162
	v_fma_f32 v20, v172, v20, v48
	v_fma_f32 v21, v173, v21, v49
	v_lshlrev_b32_e32 v48, 16, v163
	v_and_b32_e32 v49, 0xffff0000, v163
	v_fma_f32 v22, v174, v22, v48
	v_fma_f32 v23, v175, v23, v49
	v_lshlrev_b32_e32 v48, 16, v164
	v_and_b32_e32 v49, 0xffff0000, v164
	v_fma_f32 v24, v168, v24, v48
	v_fma_f32 v25, v169, v25, v49
	v_lshlrev_b32_e32 v48, 16, v165
	v_and_b32_e32 v49, 0xffff0000, v165
	v_fma_f32 v26, v170, v26, v48
	v_fma_f32 v27, v171, v27, v49
	v_lshlrev_b32_e32 v48, 16, v166
	v_and_b32_e32 v49, 0xffff0000, v166
	v_fma_f32 v28, v172, v28, v48
	v_fma_f32 v29, v173, v29, v49
	v_lshlrev_b32_e32 v48, 16, v167
	v_and_b32_e32 v49, 0xffff0000, v167
	v_fma_f32 v30, v174, v30, v48
	v_fma_f32 v31, v175, v31, v49
	global_load_dwordx4 v[160:163], v2, s[6:7] nt
	global_load_dwordx4 v[164:167], v3, s[6:7] nt
	global_load_dwordx4 v[168:171], v5, s[12:13]
	global_load_dwordx4 v[172:175], v5, s[12:13] offset:16
	s_add_u32 s6, s6, 0x40000
	s_addc_u32 s7, s7, 0
	s_add_u32 s12, s12, 2048
	s_addc_u32 s13, s13, 0
	s_waitcnt vmcnt(42)
	v_cvt_pk_bf16_f32 v40, v16, v17
	v_cvt_pk_bf16_f32 v41, v18, v19
	v_cvt_pk_bf16_f32 v42, v20, v21
	v_cvt_pk_bf16_f32 v43, v22, v23
	global_store_dwordx4 v2, v[40:43], s[10:11] nt
	v_cvt_pk_bf16_f32 v44, v24, v25
	v_cvt_pk_bf16_f32 v45, v26, v27
	v_cvt_pk_bf16_f32 v46, v28, v29
	v_cvt_pk_bf16_f32 v47, v30, v31
	global_store_dwordx4 v3, v[44:47], s[10:11] nt
	s_add_u32 s10, s10, 0x40000
	s_addc_u32 s11, s11, 0
	v_lshlrev_b32_e32 v48, 16, v176
	v_and_b32_e32 v49, 0xffff0000, v176
	v_fma_f32 v16, v184, v16, v48
	v_fma_f32 v17, v185, v17, v49
	v_lshlrev_b32_e32 v48, 16, v177
	v_and_b32_e32 v49, 0xffff0000, v177
	v_fma_f32 v18, v186, v18, v48
	v_fma_f32 v19, v187, v19, v49
	v_lshlrev_b32_e32 v48, 16, v178
	v_and_b32_e32 v49, 0xffff0000, v178
	v_fma_f32 v20, v188, v20, v48
	v_fma_f32 v21, v189, v21, v49
	v_lshlrev_b32_e32 v48, 16, v179
	v_and_b32_e32 v49, 0xffff0000, v179
	v_fma_f32 v22, v190, v22, v48
	v_fma_f32 v23, v191, v23, v49
	v_lshlrev_b32_e32 v48, 16, v180
	v_and_b32_e32 v49, 0xffff0000, v180
	v_fma_f32 v24, v184, v24, v48
	v_fma_f32 v25, v185, v25, v49
	v_lshlrev_b32_e32 v48, 16, v181
	v_and_b32_e32 v49, 0xffff0000, v181
	v_fma_f32 v26, v186, v26, v48
	v_fma_f32 v27, v187, v27, v49
	v_lshlrev_b32_e32 v48, 16, v182
	v_and_b32_e32 v49, 0xffff0000, v182
	v_fma_f32 v28, v188, v28, v48
	v_fma_f32 v29, v189, v29, v49
	v_lshlrev_b32_e32 v48, 16, v183
	v_and_b32_e32 v49, 0xffff0000, v183
	v_fma_f32 v30, v190, v30, v48
	v_fma_f32 v31, v191, v31, v49
	global_load_dwordx4 v[176:179], v2, s[6:7] nt
	global_load_dwordx4 v[180:183], v3, s[6:7] nt
	global_load_dwordx4 v[184:187], v5, s[12:13]
	global_load_dwordx4 v[188:191], v5, s[12:13] offset:16
	s_add_u32 s6, s6, 0x40000
	s_addc_u32 s7, s7, 0
	s_add_u32 s12, s12, 2048
	s_addc_u32 s13, s13, 0
	s_waitcnt vmcnt(42)
	v_cvt_pk_bf16_f32 v32, v16, v17
	v_cvt_pk_bf16_f32 v33, v18, v19
	v_cvt_pk_bf16_f32 v34, v20, v21
	v_cvt_pk_bf16_f32 v35, v22, v23
	global_store_dwordx4 v2, v[32:35], s[10:11] nt
	v_cvt_pk_bf16_f32 v36, v24, v25
	v_cvt_pk_bf16_f32 v37, v26, v27
	v_cvt_pk_bf16_f32 v38, v28, v29
	v_cvt_pk_bf16_f32 v39, v30, v31
	global_store_dwordx4 v3, v[36:39], s[10:11] nt
	s_add_u32 s10, s10, 0x40000
	s_addc_u32 s11, s11, 0
	v_lshlrev_b32_e32 v48, 16, v64
	v_and_b32_e32 v49, 0xffff0000, v64
	v_fma_f32 v16, v72, v16, v48
	v_fma_f32 v17, v73, v17, v49
	v_lshlrev_b32_e32 v48, 16, v65
	v_and_b32_e32 v49, 0xffff0000, v65
	v_fma_f32 v18, v74, v18, v48
	v_fma_f32 v19, v75, v19, v49
	v_lshlrev_b32_e32 v48, 16, v66
	v_and_b32_e32 v49, 0xffff0000, v66
	v_fma_f32 v20, v76, v20, v48
	v_fma_f32 v21, v77, v21, v49
	v_lshlrev_b32_e32 v48, 16, v67
	v_and_b32_e32 v49, 0xffff0000, v67
	v_fma_f32 v22, v78, v22, v48
	v_fma_f32 v23, v79, v23, v49
	v_lshlrev_b32_e32 v48, 16, v68
	v_and_b32_e32 v49, 0xffff0000, v68
	v_fma_f32 v24, v72, v24, v48
	v_fma_f32 v25, v73, v25, v49
	v_lshlrev_b32_e32 v48, 16, v69
	v_and_b32_e32 v49, 0xffff0000, v69
	v_fma_f32 v26, v74, v26, v48
	v_fma_f32 v27, v75, v27, v49
	v_lshlrev_b32_e32 v48, 16, v70
	v_and_b32_e32 v49, 0xffff0000, v70
	v_fma_f32 v28, v76, v28, v48
	v_fma_f32 v29, v77, v29, v49
	v_lshlrev_b32_e32 v48, 16, v71
	v_and_b32_e32 v49, 0xffff0000, v71
	v_fma_f32 v30, v78, v30, v48
	v_fma_f32 v31, v79, v31, v49
	s_waitcnt vmcnt(38)
; __device__ __forceinline__ float bf2f(unsigned h) { return __uint_as_float(h << 16); }
; __device__ __forceinline__ unsigned pk2(float lo, float hi) { return pg8::cvt_pk_bf16(lo, hi); }
; __device__ __forceinline__ void b2_scan(const Ctx& C) {
;     ...
;     B2_LOAD(0, 0);
; #pragma unroll
;     for (int g = 0; g < 8; ++g) {
;         const int cur = g & 1;
;         if (g + 1 < 8) B2_LOAD(g + 1, cur ^ 1);
; #pragma unroll
;         for (int k = 0; k < 4; ++k) {
;             const int c = 4 * g + k;
;             const float dd[8] = {d0[cur][k][0], d0[cur][k][1], d0[cur][k][2], d0[cur][k][3], d1[cur][k][0], d1[cur][k][1], d1[cur][k][2], d1[cur][k][3]};
; #pragma unroll
;             for (int j = 0; j < 2; ++j) {
;                 v4u o; o.x = pk2(run[j][0], run[j][1]); o.y = pk2(run[j][2], run[j][3]); o.z = pk2(run[j][4], run[j][5]); o.w = pk2(run[j][6], run[j][7]);
;                 __builtin_nontemporal_store(o, (v4u*)(base + (size_t)c * cstride + (size_t)j * vstride));
;                 const unsigned lw[4] = {loc[cur][k][j].x, loc[cur][k][j].y, loc[cur][k][j].z, loc[cur][k][j].w};
; #pragma unroll
;                 for (int q = 0; q < 4; ++q) {
;                     run[j][2 * q] = dd[2 * q] * run[j][2 * q] + bf2f(lw[q] & 0xffffu);
;                     run[j][2 * q + 1] = dd[2 * q + 1] * run[j][2 * q + 1] + __uint_as_float(lw[q] & 0xffff0000u);
;                 }
	v_cvt_pk_bf16_f32 v40, v16, v17
	v_cvt_pk_bf16_f32 v41, v18, v19
	v_cvt_pk_bf16_f32 v42, v20, v21
	v_cvt_pk_bf16_f32 v43, v22, v23
	global_store_dwordx4 v2, v[40:43], s[10:11] nt
	v_cvt_pk_bf16_f32 v44, v24, v25
	v_cvt_pk_bf16_f32 v45, v26, v27
	v_cvt_pk_bf16_f32 v46, v28, v29
	v_cvt_pk_bf16_f32 v47, v30, v31
	global_store_dwordx4 v3, v[44:47], s[10:11] nt
	s_add_u32 s10, s10, 0x40000
	s_addc_u32 s11, s11, 0
	v_lshlrev_b32_e32 v48, 16, v80
	v_and_b32_e32 v49, 0xffff0000, v80
	v_fma_f32 v16, v88, v16, v48
	v_fma_f32 v17, v89, v17, v49
	v_lshlrev_b32_e32 v48, 16, v81
	v_and_b32_e32 v49, 0xffff0000, v81
	v_fma_f32 v18, v90, v18, v48
	v_fma_f32 v19, v91, v19, v49
	v_lshlrev_b32_e32 v48, 16, v82
	v_and_b32_e32 v49, 0xffff0000, v82
	v_fma_f32 v20, v92, v20, v48
	v_fma_f32 v21, v93, v21, v49
	v_lshlrev_b32_e32 v48, 16, v83
	v_and_b32_e32 v49, 0xffff0000, v83
	v_fma_f32 v22, v94, v22, v48
	v_fma_f32 v23, v95, v23, v49
	v_lshlrev_b32_e32 v48, 16, v84
	v_and_b32_e32 v49, 0xffff0000, v84
	v_fma_f32 v24, v88, v24, v48
	v_fma_f32 v25, v89, v25, v49
	v_lshlrev_b32_e32 v48, 16, v85
	v_and_b32_e32 v49, 0xffff0000, v85
	v_fma_f32 v26, v90, v26, v48
	v_fma_f32 v27, v91, v27, v49
	v_lshlrev_b32_e32 v48, 16, v86
	v_and_b32_e32 v49, 0xffff0000, v86
	v_fma_f32 v28, v92, v28, v48
	v_fma_f32 v29, v93, v29, v49
	v_lshlrev_b32_e32 v48, 16, v87
	v_and_b32_e32 v49, 0xffff0000, v87
	v_fma_f32 v30, v94, v30, v48
	v_fma_f32 v31, v95, v31, v49
	s_waitcnt vmcnt(34)
	v_cvt_pk_bf16_f32 v32, v16, v17
	v_cvt_pk_bf16_f32 v33, v18, v19
	v_cvt_pk_bf16_f32 v34, v20, v21
	v_cvt_pk_bf16_f32 v35, v22, v23
	global_store_dwordx4 v2, v[32:35], s[10:11] nt
	v_cvt_pk_bf16_f32 v36, v24, v25
	v_cvt_pk_bf16_f32 v37, v26, v27
	v_cvt_pk_bf16_f32 v38, v28, v29
	v_cvt_pk_bf16_f32 v39, v30, v31
	global_store_dwordx4 v3, v[36:39], s[10:11] nt
	s_add_u32 s10, s10, 0x40000
	s_addc_u32 s11, s11, 0
	v_lshlrev_b32_e32 v48, 16, v96
	v_and_b32_e32 v49, 0xffff0000, v96
	v_fma_f32 v16, v104, v16, v48
	v_fma_f32 v17, v105, v17, v49
	v_lshlrev_b32_e32 v48, 16, v97
	v_and_b32_e32 v49, 0xffff0000, v97
	v_fma_f32 v18, v106, v18, v48
	v_fma_f32 v19, v107, v19, v49
	v_lshlrev_b32_e32 v48, 16, v98
	v_and_b32_e32 v49, 0xffff0000, v98
	v_fma_f32 v20, v108, v20, v48
	v_fma_f32 v21, v109, v21, v49
	v_lshlrev_b32_e32 v48, 16, v99
	v_and_b32_e32 v49, 0xffff0000, v99
	v_fma_f32 v22, v110, v22, v48
	v_fma_f32 v23, v111, v23, v49
	v_lshlrev_b32_e32 v48, 16, v100
	v_and_b32_e32 v49, 0xffff0000, v100
	v_fma_f32 v24, v104, v24, v48
	v_fma_f32 v25, v105, v25, v49
	v_lshlrev_b32_e32 v48, 16, v101
	v_and_b32_e32 v49, 0xffff0000, v101
	v_fma_f32 v26, v106, v26, v48
	v_fma_f32 v27, v107, v27, v49
	v_lshlrev_b32_e32 v48, 16, v102
	v_and_b32_e32 v49, 0xffff0000, v102
	v_fma_f32 v28, v108, v28, v48
	v_fma_f32 v29, v109, v29, v49
	v_lshlrev_b32_e32 v48, 16, v103
	v_and_b32_e32 v49, 0xffff0000, v103
	v_fma_f32 v30, v110, v30, v48
	v_fma_f32 v31, v111, v31, v49
	s_waitcnt vmcnt(30)
	v_cvt_pk_bf16_f32 v40, v16, v17
	v_cvt_pk_bf16_f32 v41, v18, v19
	v_cvt_pk_bf16_f32 v42, v20, v21
	v_cvt_pk_bf16_f32 v43, v22, v23
	global_store_dwordx4 v2, v[40:43], s[10:11] nt
	v_cvt_pk_bf16_f32 v44, v24, v25
	v_cvt_pk_bf16_f32 v45, v26, v27
	v_cvt_pk_bf16_f32 v46, v28, v29
	v_cvt_pk_bf16_f32 v47, v30, v31
	global_store_dwordx4 v3, v[44:47], s[10:11] nt
	s_add_u32 s10, s10, 0x40000
	s_addc_u32 s11, s11, 0
	v_lshlrev_b32_e32 v48, 16, v112
	v_and_b32_e32 v49, 0xffff0000, v112
	v_fma_f32 v16, v120, v16, v48
	v_fma_f32 v17, v121, v17, v49
	v_lshlrev_b32_e32 v48, 16, v113
	v_and_b32_e32 v49, 0xffff0000, v113
	v_fma_f32 v18, v122, v18, v48
	v_fma_f32 v19, v123, v19, v49
	v_lshlrev_b32_e32 v48, 16, v114
	v_and_b32_e32 v49, 0xffff0000, v114
	v_fma_f32 v20, v124, v20, v48
	v_fma_f32 v21, v125, v21, v49
	v_lshlrev_b32_e32 v48, 16, v115
	v_and_b32_e32 v49, 0xffff0000, v115
	v_fma_f32 v22, v126, v22, v48
	v_fma_f32 v23, v127, v23, v49
	v_lshlrev_b32_e32 v48, 16, v116
	v_and_b32_e32 v49, 0xffff0000, v116
	v_fma_f32 v24, v120, v24, v48
	v_fma_f32 v25, v121, v25, v49
	v_lshlrev_b32_e32 v48, 16, v117
	v_and_b32_e32 v49, 0xffff0000, v117
	v_fma_f32 v26, v122, v26, v48
	v_fma_f32 v27, v123, v27, v49
	v_lshlrev_b32_e32 v48, 16, v118
	v_and_b32_e32 v49, 0xffff0000, v118
	v_fma_f32 v28, v124, v28, v48
	v_fma_f32 v29, v125, v29, v49
	v_lshlrev_b32_e32 v48, 16, v119
	v_and_b32_e32 v49, 0xffff0000, v119
	v_fma_f32 v30, v126, v30, v48
	v_fma_f32 v31, v127, v31, v49
	s_waitcnt vmcnt(26)
	v_cvt_pk_bf16_f32 v32, v16, v17
	v_cvt_pk_bf16_f32 v33, v18, v19
	v_cvt_pk_bf16_f32 v34, v20, v21
	v_cvt_pk_bf16_f32 v35, v22, v23
	global_store_dwordx4 v2, v[32:35], s[10:11] nt
	v_cvt_pk_bf16_f32 v36, v24, v25
	v_cvt_pk_bf16_f32 v37, v26, v27
	v_cvt_pk_bf16_f32 v38, v28, v29
	v_cvt_pk_bf16_f32 v39, v30, v31
	global_store_dwordx4 v3, v[36:39], s[10:11] nt
	s_add_u32 s10, s10, 0x40000
	s_addc_u32 s11, s11, 0
	v_lshlrev_b32_e32 v48, 16, v128
	v_and_b32_e32 v49, 0xffff0000, v128
	v_fma_f32 v16, v136, v16, v48
	v_fma_f32 v17, v137, v17, v49
	v_lshlrev_b32_e32 v48, 16, v129
	v_and_b32_e32 v49, 0xffff0000, v129
	v_fma_f32 v18, v138, v18, v48
	v_fma_f32 v19, v139, v19, v49
	v_lshlrev_b32_e32 v48, 16, v130
	v_and_b32_e32 v49, 0xffff0000, v130
	v_fma_f32 v20, v140, v20, v48
	v_fma_f32 v21, v141, v21, v49
	v_lshlrev_b32_e32 v48, 16, v131
	v_and_b32_e32 v49, 0xffff0000, v131
	v_fma_f32 v22, v142, v22, v48
	v_fma_f32 v23, v143, v23, v49
	v_lshlrev_b32_e32 v48, 16, v132
	v_and_b32_e32 v49, 0xffff0000, v132
	v_fma_f32 v24, v136, v24, v48
	v_fma_f32 v25, v137, v25, v49
	v_lshlrev_b32_e32 v48, 16, v133
	v_and_b32_e32 v49, 0xffff0000, v133
	v_fma_f32 v26, v138, v26, v48
	v_fma_f32 v27, v139, v27, v49
	v_lshlrev_b32_e32 v48, 16, v134
	v_and_b32_e32 v49, 0xffff0000, v134
	v_fma_f32 v28, v140, v28, v48
	v_fma_f32 v29, v141, v29, v49
	v_lshlrev_b32_e32 v48, 16, v135
	v_and_b32_e32 v49, 0xffff0000, v135
	v_fma_f32 v30, v142, v30, v48
	v_fma_f32 v31, v143, v31, v49
	s_waitcnt vmcnt(22)
; __device__ __forceinline__ float bf2f(unsigned h) { return __uint_as_float(h << 16); }
; __device__ __forceinline__ unsigned pk2(float lo, float hi) { return pg8::cvt_pk_bf16(lo, hi); }
; __device__ __forceinline__ void b2_scan(const Ctx& C) {
;     ...
;         for (int k = 0; k < 4; ++k) {
;             const int c = 4 * g + k;
;             const float dd[8] = {d0[cur][k][0], d0[cur][k][1], d0[cur][k][2], d0[cur][k][3], d1[cur][k][0], d1[cur][k][1], d1[cur][k][2], d1[cur][k][3]};
; #pragma unroll
;             for (int j = 0; j < 2; ++j) {
;                 v4u o; o.x = pk2(run[j][0], run[j][1]); o.y = pk2(run[j][2], run[j][3]); o.z = pk2(run[j][4], run[j][5]); o.w = pk2(run[j][6], run[j][7]);
;                 __builtin_nontemporal_store(o, (v4u*)(base + (size_t)c * cstride + (size_t)j * vstride));
;                 const unsigned lw[4] = {loc[cur][k][j].x, loc[cur][k][j].y, loc[cur][k][j].z, loc[cur][k][j].w};
; #pragma unroll
;                 for (int q = 0; q < 4; ++q) {
;                     run[j][2 * q] = dd[2 * q] * run[j][2 * q] + bf2f(lw[q] & 0xffffu);
;                     run[j][2 * q + 1] = dd[2 * q + 1] * run[j][2 * q + 1] + __uint_as_float(lw[q] & 0xffff0000u);
;                 }
	v_cvt_pk_bf16_f32 v40, v16, v17
	v_cvt_pk_bf16_f32 v41, v18, v19
	v_cvt_pk_bf16_f32 v42, v20, v21
	v_cvt_pk_bf16_f32 v43, v22, v23
	global_store_dwordx4 v2, v[40:43], s[10:11] nt
	v_cvt_pk_bf16_f32 v44, v24, v25
	v_cvt_pk_bf16_f32 v45, v26, v27
	v_cvt_pk_bf16_f32 v46, v28, v29
	v_cvt_pk_bf16_f32 v47, v30, v31
	global_store_dwordx4 v3, v[44:47], s[10:11] nt
	s_add_u32 s10, s10, 0x40000
	s_addc_u32 s11, s11, 0
	v_lshlrev_b32_e32 v48, 16, v144
	v_and_b32_e32 v49, 0xffff0000, v144
	v_fma_f32 v16, v152, v16, v48
	v_fma_f32 v17, v153, v17, v49
	v_lshlrev_b32_e32 v48, 16, v145
	v_and_b32_e32 v49, 0xffff0000, v145
	v_fma_f32 v18, v154, v18, v48
	v_fma_f32 v19, v155, v19, v49
	v_lshlrev_b32_e32 v48, 16, v146
	v_and_b32_e32 v49, 0xffff0000, v146
	v_fma_f32 v20, v156, v20, v48
	v_fma_f32 v21, v157, v21, v49
	v_lshlrev_b32_e32 v48, 16, v147
	v_and_b32_e32 v49, 0xffff0000, v147
	v_fma_f32 v22, v158, v22, v48
	v_fma_f32 v23, v159, v23, v49
	v_lshlrev_b32_e32 v48, 16, v148
	v_and_b32_e32 v49, 0xffff0000, v148
	v_fma_f32 v24, v152, v24, v48
	v_fma_f32 v25, v153, v25, v49
	v_lshlrev_b32_e32 v48, 16, v149
	v_and_b32_e32 v49, 0xffff0000, v149
	v_fma_f32 v26, v154, v26, v48
	v_fma_f32 v27, v155, v27, v49
	v_lshlrev_b32_e32 v48, 16, v150
	v_and_b32_e32 v49, 0xffff0000, v150
	v_fma_f32 v28, v156, v28, v48
	v_fma_f32 v29, v157, v29, v49
	v_lshlrev_b32_e32 v48, 16, v151
	v_and_b32_e32 v49, 0xffff0000, v151
	v_fma_f32 v30, v158, v30, v48
	v_fma_f32 v31, v159, v31, v49
	s_waitcnt vmcnt(18)
	v_cvt_pk_bf16_f32 v32, v16, v17
	v_cvt_pk_bf16_f32 v33, v18, v19
	v_cvt_pk_bf16_f32 v34, v20, v21
	v_cvt_pk_bf16_f32 v35, v22, v23
	global_store_dwordx4 v2, v[32:35], s[10:11] nt
	v_cvt_pk_bf16_f32 v36, v24, v25
	v_cvt_pk_bf16_f32 v37, v26, v27
	v_cvt_pk_bf16_f32 v38, v28, v29
	v_cvt_pk_bf16_f32 v39, v30, v31
	global_store_dwordx4 v3, v[36:39], s[10:11] nt
	s_add_u32 s10, s10, 0x40000
	s_addc_u32 s11, s11, 0
	v_lshlrev_b32_e32 v48, 16, v160
	v_and_b32_e32 v49, 0xffff0000, v160
	v_fma_f32 v16, v168, v16, v48
	v_fma_f32 v17, v169, v17, v49
	v_lshlrev_b32_e32 v48, 16, v161
	v_and_b32_e32 v49, 0xffff0000, v161
	v_fma_f32 v18, v170, v18, v48
	v_fma_f32 v19, v171, v19, v49
	v_lshlrev_b32_e32 v48, 16, v162
	v_and_b32_e32 v49, 0xffff0000, v162
	v_fma_f32 v20, v172, v20, v48
	v_fma_f32 v21, v173, v21, v49
	v_lshlrev_b32_e32 v48, 16, v163
	v_and_b32_e32 v49, 0xffff0000, v163
	v_fma_f32 v22, v174, v22, v48
	v_fma_f32 v23, v175, v23, v49
	v_lshlrev_b32_e32 v48, 16, v164
	v_and_b32_e32 v49, 0xffff0000, v164
	v_fma_f32 v24, v168, v24, v48
	v_fma_f32 v25, v169, v25, v49
	v_lshlrev_b32_e32 v48, 16, v165
	v_and_b32_e32 v49, 0xffff0000, v165
	v_fma_f32 v26, v170, v26, v48
	v_fma_f32 v27, v171, v27, v49
	v_lshlrev_b32_e32 v48, 16, v166
	v_and_b32_e32 v49, 0xffff0000, v166
	v_fma_f32 v28, v172, v28, v48
	v_fma_f32 v29, v173, v29, v49
	v_lshlrev_b32_e32 v48, 16, v167
	v_and_b32_e32 v49, 0xffff0000, v167
	v_fma_f32 v30, v174, v30, v48
	v_fma_f32 v31, v175, v31, v49
	s_waitcnt vmcnt(14)
	v_cvt_pk_bf16_f32 v40, v16, v17
	v_cvt_pk_bf16_f32 v41, v18, v19
	v_cvt_pk_bf16_f32 v42, v20, v21
	v_cvt_pk_bf16_f32 v43, v22, v23
	global_store_dwordx4 v2, v[40:43], s[10:11] nt
	v_cvt_pk_bf16_f32 v44, v24, v25
	v_cvt_pk_bf16_f32 v45, v26, v27
	v_cvt_pk_bf16_f32 v46, v28, v29
	v_cvt_pk_bf16_f32 v47, v30, v31
	global_store_dwordx4 v3, v[44:47], s[10:11] nt
	s_add_u32 s10, s10, 0x40000
	s_addc_u32 s11, s11, 0
	v_lshlrev_b32_e32 v48, 16, v176
	v_and_b32_e32 v49, 0xffff0000, v176
	v_fma_f32 v16, v184, v16, v48
	v_fma_f32 v17, v185, v17, v49
	v_lshlrev_b32_e32 v48, 16, v177
	v_and_b32_e32 v49, 0xffff0000, v177
	v_fma_f32 v18, v186, v18, v48
	v_fma_f32 v19, v187, v19, v49
	v_lshlrev_b32_e32 v48, 16, v178
	v_and_b32_e32 v49, 0xffff0000, v178
	v_fma_f32 v20, v188, v20, v48
	v_fma_f32 v21, v189, v21, v49
	v_lshlrev_b32_e32 v48, 16, v179
	v_and_b32_e32 v49, 0xffff0000, v179
	v_fma_f32 v22, v190, v22, v48
	v_fma_f32 v23, v191, v23, v49
	v_lshlrev_b32_e32 v48, 16, v180
	v_and_b32_e32 v49, 0xffff0000, v180
	v_fma_f32 v24, v184, v24, v48
	v_fma_f32 v25, v185, v25, v49
	v_lshlrev_b32_e32 v48, 16, v181
	v_and_b32_e32 v49, 0xffff0000, v181
	v_fma_f32 v26, v186, v26, v48
	v_fma_f32 v27, v187, v27, v49
	v_lshlrev_b32_e32 v48, 16, v182
	v_and_b32_e32 v49, 0xffff0000, v182
	v_fma_f32 v28, v188, v28, v48
	v_fma_f32 v29, v189, v29, v49
	v_lshlrev_b32_e32 v48, 16, v183
	v_and_b32_e32 v49, 0xffff0000, v183
	v_fma_f32 v30, v190, v30, v48
	v_fma_f32 v31, v191, v31, v49
.Lb2_end_l0:
	s_waitcnt lgkmcnt(0)
	v_mov_b64_e32 v[0:1], s[14:15]

;     __device__ __forceinline__ void operator()(const f32x4 (&acc)[2][2][4][2], const Unit& u, int wr, int wc, int fr, int fq) const {
;     ...
;                     for (int m = 3; m >= 0; --m) {
;                         const f32x4 cur = acc[ai][bj][m][n] * rs[m];
;                         f32x4 prev = zero4;
;                         if (m > 0) prev = acc[ai][bj][m - 1][n] * rs[m - 1];
;                         f32x4 r1, r2;
; #pragma unroll
;                         for (int i = 0; i < 4; ++i) {
;                             r1[i] = dpp_mov<0x111>(dpp_mov<0x121>(0.f, prev[i]), cur[i]);
;                             r2[i] = dpp_mov<0x112>(dpp_mov<0x122>(0.f, prev[i]), cur[i]); }
;                         const f32x4 cvv = wb + w2 * cur + w1 * r1 + w0 * r2;
.LBB0_996:
	s_or_b64 exec, exec, s[58:59]
	v_pk_mul_f32 v[200:201], v[122:123], v[184:185] op_sel_hi:[1,0]
	v_pk_mul_f32 v[202:203], v[120:121], v[184:185] op_sel_hi:[1,0]
	s_nop 1
	v_mov_b32_dpp v226, v202 row_ror:1 row_mask:0xf bank_mask:0xf
	v_mov_b32_dpp v224, v202 row_ror:2 row_mask:0xf bank_mask:0xf
	v_mov_b32_dpp v227, v203 row_ror:1 row_mask:0xf bank_mask:0xf
	v_mov_b32_dpp v225, v203 row_ror:2 row_mask:0xf bank_mask:0xf
	v_mov_b32_dpp v232, v200 row_ror:1 row_mask:0xf bank_mask:0xf
	v_mov_b32_dpp v228, v200 row_ror:2 row_mask:0xf bank_mask:0xf
	v_mov_b32_dpp v233, v201 row_ror:1 row_mask:0xf bank_mask:0xf
	v_mov_b32_dpp v229, v201 row_ror:2 row_mask:0xf bank_mask:0xf
	v_mov_b32_dpp v226, v150 row_shr:1 row_mask:0xf bank_mask:0xf
	v_mov_b32_dpp v224, v150 row_shr:2 row_mask:0xf bank_mask:0xf
	v_mov_b32_dpp v227, v151 row_shr:1 row_mask:0xf bank_mask:0xf
	v_mov_b32_dpp v225, v151 row_shr:2 row_mask:0xf bank_mask:0xf
	v_mov_b32_dpp v232, v152 row_shr:1 row_mask:0xf bank_mask:0xf
	v_mov_b32_dpp v228, v152 row_shr:2 row_mask:0xf bank_mask:0xf
	v_mov_b32_dpp v233, v153 row_shr:1 row_mask:0xf bank_mask:0xf
	v_mov_b32_dpp v229, v153 row_shr:2 row_mask:0xf bank_mask:0xf
	v_pk_mul_f32 v[194:195], v[118:119], v[182:183] op_sel_hi:[1,0]
	v_pk_mul_f32 v[196:197], v[116:117], v[182:183] op_sel_hi:[1,0]
	s_nop 1
	v_mov_b32_dpp v218, v196 row_ror:1 row_mask:0xf bank_mask:0xf
	v_mov_b32_dpp v216, v196 row_ror:2 row_mask:0xf bank_mask:0xf
	v_mov_b32_dpp v219, v197 row_ror:1 row_mask:0xf bank_mask:0xf
	v_mov_b32_dpp v217, v197 row_ror:2 row_mask:0xf bank_mask:0xf
	v_mov_b32_dpp v230, v194 row_ror:1 row_mask:0xf bank_mask:0xf
	v_mov_b32_dpp v220, v194 row_ror:2 row_mask:0xf bank_mask:0xf
	v_mov_b32_dpp v231, v195 row_ror:1 row_mask:0xf bank_mask:0xf
	v_mov_b32_dpp v221, v195 row_ror:2 row_mask:0xf bank_mask:0xf
	v_mov_b32_dpp v218, v202 row_shr:1 row_mask:0xf bank_mask:0xf
	v_mov_b32_dpp v216, v202 row_shr:2 row_mask:0xf bank_mask:0xf
	v_mov_b32_dpp v219, v203 row_shr:1 row_mask:0xf bank_mask:0xf
	v_mov_b32_dpp v217, v203 row_shr:2 row_mask:0xf bank_mask:0xf
	v_mov_b32_dpp v230, v200 row_shr:1 row_mask:0xf bank_mask:0xf
	v_mov_b32_dpp v220, v200 row_shr:2 row_mask:0xf bank_mask:0xf
	v_mov_b32_dpp v231, v201 row_shr:1 row_mask:0xf bank_mask:0xf
	v_mov_b32_dpp v221, v201 row_shr:2 row_mask:0xf bank_mask:0xf
	v_mov_b32_e32 v130, v180
	v_mov_b32_e32 v131, v180
	v_pk_mul_f32 v[192:193], v[114:115], v[130:131]
	v_mov_b32_dpp v212, v148 row_ror:1 row_mask:0xf bank_mask:0xf
	v_mov_b32_dpp v210, v148 row_ror:2 row_mask:0xf bank_mask:0xf
	v_mov_b32_dpp v213, v149 row_ror:1 row_mask:0xf bank_mask:0xf
	v_mov_b32_dpp v211, v149 row_ror:2 row_mask:0xf bank_mask:0xf
	v_mov_b32_dpp v222, v192 row_ror:1 row_mask:0xf bank_mask:0xf
	v_mov_b32_dpp v214, v192 row_ror:2 row_mask:0xf bank_mask:0xf
	v_mov_b32_dpp v223, v193 row_ror:1 row_mask:0xf bank_mask:0xf
	v_mov_b32_dpp v215, v193 row_ror:2 row_mask:0xf bank_mask:0xf
	v_mov_b32_dpp v212, v196 row_shr:1 row_mask:0xf bank_mask:0xf
	v_mov_b32_dpp v210, v196 row_shr:2 row_mask:0xf bank_mask:0xf
	v_mov_b32_dpp v213, v197 row_shr:1 row_mask:0xf bank_mask:0xf
	v_mov_b32_dpp v211, v197 row_shr:2 row_mask:0xf bank_mask:0xf
	v_mov_b32_dpp v222, v194 row_shr:1 row_mask:0xf bank_mask:0xf
	v_mov_b32_dpp v214, v194 row_shr:2 row_mask:0xf bank_mask:0xf
	v_mov_b32_dpp v223, v195 row_shr:1 row_mask:0xf bank_mask:0xf
	v_mov_b32_dpp v215, v195 row_shr:2 row_mask:0xf bank_mask:0xf
	v_mov_b32_e32 v209, 0
	v_mov_b32_e32 v199, 0
	s_nop 0
	v_mov_b32_dpp v209, v209 row_ror:1 row_mask:0xf bank_mask:0xf
	v_mov_b32_dpp v199, v199 row_ror:2 row_mask:0xf bank_mask:0xf
	v_mov_b32_e32 v206, v209
	v_mov_b32_e32 v204, v199
	v_mov_b32_e32 v207, v209
	v_mov_b32_e32 v205, v199
	v_mov_b32_e32 v208, v209
	v_mov_b32_e32 v198, v199
	v_mov_b32_dpp v206, v148 row_shr:1 row_mask:0xf bank_mask:0xf
	v_mov_b32_dpp v204, v148 row_shr:2 row_mask:0xf bank_mask:0xf
	v_mov_b32_dpp v207, v149 row_shr:1 row_mask:0xf bank_mask:0xf
	v_mov_b32_dpp v205, v149 row_shr:2 row_mask:0xf bank_mask:0xf
	v_mov_b32_dpp v208, v192 row_shr:1 row_mask:0xf bank_mask:0xf
	v_mov_b32_dpp v198, v192 row_shr:2 row_mask:0xf bank_mask:0xf
	v_mov_b32_dpp v209, v193 row_shr:1 row_mask:0xf bank_mask:0xf
	v_mov_b32_dpp v199, v193 row_shr:2 row_mask:0xf bank_mask:0xf
	v_add_co_u32_e32 v188, vcc, s88, v172
	v_pk_mul_f32 v[128:129], v[96:97], v[180:181]
	s_nop 0
	v_addc_co_u32_e32 v189, vcc, 0, v173, vcc
	v_add_co_u32_e32 v190, vcc, s88, v174
	s_nop 1
	v_addc_co_u32_e32 v191, vcc, 0, v175, vcc
	v_add_co_u32_e32 v120, vcc, 0x5000, v176
	global_load_dwordx4 v[112:115], v[188:189], off offset:2048
	global_load_dwordx4 v[116:119], v[190:191], off offset:2048
	v_addc_co_u32_e32 v121, vcc, 0, v177, vcc
	v_add_co_u32_e32 v124, vcc, 0x5000, v178
	global_load_dwordx4 v[120:123], v[120:121], off offset:2048
	s_nop 0
	v_addc_co_u32_e32 v125, vcc, 0, v179, vcc
	global_load_dwordx4 v[124:127], v[124:125], off offset:2048
	s_and_saveexec_b64 s[58:59], s[12:13]
	s_cbranch_execz .LBB0_998
	v_mov_b64_e32 v[96:97], s[26:27]
	v_mad_i64_i32 v[96:97], s[50:51], v246, s87, v[96:97]
	v_lshl_add_u64 v[96:97], v[170:171], 2, v[96:97]
	v_add_co_u32_e32 v96, vcc, 0x5000, v96
	v_pk_mul_f32 v[130:131], v[98:99], v[130:131]
	s_nop 0
	v_addc_co_u32_e32 v97, vcc, 0, v97, vcc
	global_store_dwordx4 v[96:97], v[128:131], off offset:2048

; __device__ __forceinline__ unsigned cvt_pk_bf16(float lo, float hi) { f32x2_cv v = {lo, hi}; bf16x2_cv b = __builtin_convertvector(v, bf16x2_cv); return __builtin_bit_cast(unsigned, b); }
;     __device__ __forceinline__ void operator()(const f32x4 (&acc)[2][2][4][2], const Unit& u, int wr, int wc, int fr, int fq) const {
;     ...
;                 for (int bj = 0; bj < 2; ++bj) {
;                     const int col = bj * dff + cg;
;                     const f32x4 w0 = *(const f32x4*)(cw + col), w1 = *(const f32x4*)(cw + 2 * dff + col), w2 = *(const f32x4*)(cw + 4 * dff + col), wb = *(const f32x4*)(cb + col);
;                     if (fr < 2) *(f32x4*)(RB + ((size_t)(blk * 4 + fr) * 2 + bj) * dff + cg) = acc[ai][bj][0][n] * rs[0];
;                     if (fr >= 14) *(f32x4*)(RB + ((size_t)(blk * 4 + fr - 12) * 2 + bj) * dff + cg) = acc[ai][bj][3][n] * rs[3];
; #pragma unroll
;                     for (int m = 3; m >= 0; --m) {
;                         const f32x4 cur = acc[ai][bj][m][n] * rs[m];
;                         f32x4 prev = zero4;
;                         if (m > 0) prev = acc[ai][bj][m - 1][n] * rs[m - 1];
;                         f32x4 r1, r2;
; #pragma unroll
;                         for (int i = 0; i < 4; ++i) {
;                             r1[i] = dpp_mov<0x111>(dpp_mov<0x121>(0.f, prev[i]), cur[i]);
;                             r2[i] = dpp_mov<0x112>(dpp_mov<0x122>(0.f, prev[i]), cur[i]); }
;                         const f32x4 cvv = wb + w2 * cur + w1 * r1 + w0 * r2;
;                         if (bj == 0) {
;                             sg[m].x = cvt_pk_bf16(siluf_(cvv[0]), siluf_(cvv[1])); sg[m].y = cvt_pk_bf16(siluf_(cvv[2]), siluf_(cvv[3]));
;                         } else {
;                             f32x4 h;
;                             h[0] = __uint_as_float(sg[m].x << 16) * cvv[0]; h[1] = __uint_as_float(sg[m].x & 0xffff0000u) * cvv[1];
;                             h[2] = __uint_as_float(sg[m].y << 16) * cvv[2]; h[3] = __uint_as_float(sg[m].y & 0xffff0000u) * cvv[3];
;                             u32x2v w; w.x = cvt_pk_bf16(h[0], h[1]); w.y = cvt_pk_bf16(h[2], h[3]);
;                             *(u32x2v*)(H + (size_t)(rowb + m * 16 + fr) * dff + cg) = w;
;                         }
;                         __builtin_amdgcn_sched_barrier(0);
;                     }
.LBB0_1000:
	s_or_b64 exec, exec, s[58:59]
	s_waitcnt vmcnt(0)
	v_pk_fma_f32 v[130:131], v[140:141], v[150:151], v[144:145]
	v_pk_fma_f32 v[96:97], v[142:143], v[152:153], v[146:147]
	v_pk_fma_f32 v[130:131], v[136:137], v[226:227], v[130:131]
	v_pk_fma_f32 v[96:97], v[138:139], v[232:233], v[96:97]
	v_pk_fma_f32 v[130:131], v[132:133], v[224:225], v[130:131]
	v_pk_fma_f32 v[96:97], v[134:135], v[228:229], v[96:97]
	v_mul_f32_e32 v150, 0xbfb8aa3b, v130
	v_mul_f32_e32 v151, 0xbfb8aa3b, v131
	v_exp_f32_e32 v150, v150
	v_exp_f32_e32 v151, v151
	v_mul_f32_e32 v152, 0xbfb8aa3b, v96
	v_mul_f32_e32 v153, 0xbfb8aa3b, v97
	v_exp_f32_e32 v152, v152
	v_exp_f32_e32 v153, v153
	v_add_f32_e32 v150, 1.0, v150
	v_add_f32_e32 v151, 1.0, v151
	v_rcp_f32_e32 v150, v150
	v_rcp_f32_e32 v151, v151
	v_add_f32_e32 v152, 1.0, v152
	v_add_f32_e32 v153, 1.0, v153
	v_rcp_f32_e32 v152, v152
	v_rcp_f32_e32 v153, v153
	v_pk_mul_f32 v[130:131], v[130:131], v[150:151]
	v_pk_fma_f32 v[150:151], v[202:203], v[140:141], v[144:145]
	v_cvt_pk_bf16_f32 v224, v130, v131
	v_pk_fma_f32 v[130:131], v[200:201], v[142:143], v[146:147]
	v_pk_fma_f32 v[150:151], v[136:137], v[218:219], v[150:151]
	v_pk_fma_f32 v[130:131], v[138:139], v[230:231], v[130:131]
	v_pk_fma_f32 v[150:151], v[132:133], v[216:217], v[150:151]
	v_pk_mul_f32 v[96:97], v[96:97], v[152:153]
	v_mul_f32_e32 v152, 0xbfb8aa3b, v150
	v_mul_f32_e32 v153, 0xbfb8aa3b, v151
	v_pk_fma_f32 v[130:131], v[134:135], v[220:221], v[130:131]
	v_exp_f32_e32 v152, v152
	v_exp_f32_e32 v153, v153
	v_mul_f32_e32 v200, 0xbfb8aa3b, v130
	v_mul_f32_e32 v201, 0xbfb8aa3b, v131
	v_exp_f32_e32 v200, v200
	v_exp_f32_e32 v201, v201
	v_add_f32_e32 v152, 1.0, v152
	v_add_f32_e32 v153, 1.0, v153
	v_rcp_f32_e32 v152, v152
	v_rcp_f32_e32 v153, v153
	v_add_f32_e32 v200, 1.0, v200
	v_add_f32_e32 v201, 1.0, v201
	v_rcp_f32_e32 v200, v200
	v_rcp_f32_e32 v201, v201
	v_cvt_pk_bf16_f32 v202, v96, v97
	v_pk_mul_f32 v[96:97], v[150:151], v[152:153]
	v_pk_fma_f32 v[150:151], v[196:197], v[140:141], v[144:145]
	v_cvt_pk_bf16_f32 v203, v96, v97
	v_pk_mul_f32 v[96:97], v[130:131], v[200:201]
	v_pk_fma_f32 v[130:131], v[194:195], v[142:143], v[146:147]
	v_pk_fma_f32 v[150:151], v[136:137], v[212:213], v[150:151]
	v_pk_fma_f32 v[130:131], v[138:139], v[222:223], v[130:131]
	v_pk_fma_f32 v[150:151], v[132:133], v[210:211], v[150:151]
	v_pk_fma_f32 v[130:131], v[134:135], v[214:215], v[130:131]
	v_mul_f32_e32 v152, 0xbfb8aa3b, v150
	v_mul_f32_e32 v153, 0xbfb8aa3b, v151
	v_exp_f32_e32 v152, v152
	v_exp_f32_e32 v153, v153
	v_mul_f32_e32 v194, 0xbfb8aa3b, v130
	v_mul_f32_e32 v195, 0xbfb8aa3b, v131
	v_exp_f32_e32 v194, v194
	v_exp_f32_e32 v195, v195
	v_add_f32_e32 v152, 1.0, v152
	v_add_f32_e32 v153, 1.0, v153
	v_rcp_f32_e32 v152, v152
	v_rcp_f32_e32 v153, v153
	v_add_f32_e32 v194, 1.0, v194
	v_add_f32_e32 v195, 1.0, v195
	v_pk_fma_f32 v[140:141], v[148:149], v[140:141], v[144:145]
	v_rcp_f32_e32 v194, v194
	v_rcp_f32_e32 v195, v195
	v_pk_fma_f32 v[136:137], v[136:137], v[206:207], v[140:141]
	v_cvt_pk_bf16_f32 v196, v96, v97
	v_pk_fma_f32 v[132:133], v[132:133], v[204:205], v[136:137]
	v_pk_mul_f32 v[96:97], v[150:151], v[152:153]
	v_mul_f32_e32 v136, 0xbfb8aa3b, v132
	v_mul_f32_e32 v137, 0xbfb8aa3b, v133
	v_exp_f32_e32 v136, v136
	v_exp_f32_e32 v137, v137
	v_cvt_pk_bf16_f32 v150, v96, v97
	v_pk_mul_f32 v[96:97], v[130:131], v[194:195]
	v_pk_fma_f32 v[130:131], v[192:193], v[142:143], v[146:147]
	v_mov_b32_e32 v185, v184
	v_pk_fma_f32 v[130:131], v[138:139], v[208:209], v[130:131]
	v_cvt_pk_bf16_f32 v138, v96, v97
	v_pk_fma_f32 v[130:131], v[134:135], v[198:199], v[130:131]
	v_add_f32_e32 v134, 1.0, v136
	v_add_f32_e32 v135, 1.0, v137
	v_mul_f32_e32 v136, 0xbfb8aa3b, v130
	v_mul_f32_e32 v137, 0xbfb8aa3b, v131
	v_exp_f32_e32 v136, v136
	v_exp_f32_e32 v137, v137
	v_rcp_f32_e32 v134, v134
	v_rcp_f32_e32 v135, v135
	v_add_f32_e32 v136, 1.0, v136
	v_add_f32_e32 v137, 1.0, v137
	v_rcp_f32_e32 v136, v136
	v_rcp_f32_e32 v137, v137
	v_pk_mul_f32 v[96:97], v[132:133], v[134:135]
	v_pk_mul_f32 v[104:105], v[104:105], v[184:185]
	v_cvt_pk_bf16_f32 v139, v96, v97
	v_pk_mul_f32 v[96:97], v[130:131], v[136:137]
	v_cvt_pk_bf16_f32 v140, v96, v97
	v_mov_b32_e32 v96, v184
	v_mov_b32_e32 v97, v184
	v_pk_mul_f32 v[96:97], v[106:107], v[96:97]
	v_mov_b32_dpp v106, v104 row_ror:1 row_mask:0xf bank_mask:0xf
	v_mov_b32_dpp v130, v104 row_ror:2 row_mask:0xf bank_mask:0xf
	v_mov_b32_dpp v107, v105 row_ror:1 row_mask:0xf bank_mask:0xf
	v_mov_b32_dpp v131, v105 row_ror:2 row_mask:0xf bank_mask:0xf
	v_mov_b32_dpp v132, v96 row_ror:1 row_mask:0xf bank_mask:0xf
	v_mov_b32_dpp v134, v96 row_ror:2 row_mask:0xf bank_mask:0xf
	v_mov_b32_dpp v133, v97 row_ror:1 row_mask:0xf bank_mask:0xf
	v_mov_b32_dpp v135, v97 row_ror:2 row_mask:0xf bank_mask:0xf
	v_mov_b32_dpp v106, v108 row_shr:1 row_mask:0xf bank_mask:0xf
	v_mov_b32_dpp v130, v108 row_shr:2 row_mask:0xf bank_mask:0xf
	v_mov_b32_dpp v107, v109 row_shr:1 row_mask:0xf bank_mask:0xf
	v_mov_b32_dpp v131, v109 row_shr:2 row_mask:0xf bank_mask:0xf
	v_mov_b32_dpp v132, v110 row_shr:1 row_mask:0xf bank_mask:0xf
	v_mov_b32_dpp v134, v110 row_shr:2 row_mask:0xf bank_mask:0xf
	v_mov_b32_dpp v133, v111 row_shr:1 row_mask:0xf bank_mask:0xf
	v_mov_b32_dpp v135, v111 row_shr:2 row_mask:0xf bank_mask:0xf
	v_pk_fma_f32 v[110:111], v[110:111], v[122:123], v[126:127]
	v_pk_fma_f32 v[108:109], v[108:109], v[120:121], v[124:125]
	v_pk_fma_f32 v[110:111], v[118:119], v[132:133], v[110:111]
	v_pk_fma_f32 v[106:107], v[116:117], v[106:107], v[108:109]
	v_pk_fma_f32 v[108:109], v[114:115], v[134:135], v[110:111]
	v_pk_fma_f32 v[106:107], v[112:113], v[130:131], v[106:107]
; __device__ __forceinline__ unsigned cvt_pk_bf16(float lo, float hi) { f32x2_cv v = {lo, hi}; bf16x2_cv b = __builtin_convertvector(v, bf16x2_cv); return __builtin_bit_cast(unsigned, b); }
; __device__ __forceinline__ float siluf_(float x) { return x * __builtin_amdgcn_rcpf(1.0f + __expf(-x)); }
;     __device__ __forceinline__ void operator()(const f32x4 (&acc)[2][2][4][2], const Unit& u, int wr, int wc, int fr, int fq) const {
;     ...
;                     for (int m = 3; m >= 0; --m) {
;                         const f32x4 cur = acc[ai][bj][m][n] * rs[m];
;                         f32x4 prev = zero4;
;                         if (m > 0) prev = acc[ai][bj][m - 1][n] * rs[m - 1];
;                         f32x4 r1, r2;
; #pragma unroll
;                         for (int i = 0; i < 4; ++i) {
;                             r1[i] = dpp_mov<0x111>(dpp_mov<0x121>(0.f, prev[i]), cur[i]);
;                             r2[i] = dpp_mov<0x112>(dpp_mov<0x122>(0.f, prev[i]), cur[i]); }
;                         const f32x4 cvv = wb + w2 * cur + w1 * r1 + w0 * r2;
;                         if (bj == 0) {
;                             sg[m].x = cvt_pk_bf16(siluf_(cvv[0]), siluf_(cvv[1])); sg[m].y = cvt_pk_bf16(siluf_(cvv[2]), siluf_(cvv[3]));
;                         } else {
;                             f32x4 h;
;                             h[0] = __uint_as_float(sg[m].x << 16) * cvv[0]; h[1] = __uint_as_float(sg[m].x & 0xffff0000u) * cvv[1];
;                             h[2] = __uint_as_float(sg[m].y << 16) * cvv[2]; h[3] = __uint_as_float(sg[m].y & 0xffff0000u) * cvv[3];
;                             u32x2v w; w.x = cvt_pk_bf16(h[0], h[1]); w.y = cvt_pk_bf16(h[2], h[3]);
;                             *(u32x2v*)(H + (size_t)(rowb + m * 16 + fr) * dff + cg) = w;
	v_lshlrev_b32_e32 v110, 16, v224
	v_and_b32_e32 v111, 0xffff0000, v224
	v_pk_mul_f32 v[106:107], v[106:107], v[110:111]
	v_lshlrev_b32_e32 v110, 16, v202
	v_and_b32_e32 v111, 0xffff0000, v202
	v_or_b32_e32 v141, s43, v236
	v_pk_mul_f32 v[108:109], v[108:109], v[110:111]
	v_cvt_pk_bf16_f32 v106, v106, v107
	v_cvt_pk_bf16_f32 v107, v108, v109
	v_or_b32_e32 v110, 48, v141
	v_mov_b64_e32 v[108:109], s[24:25]
	v_mad_i64_i32 v[110:111], s[50:51], v110, s89, v[108:109]
	v_lshlrev_b64 v[130:131], 1, v[170:171]
	v_mov_b32_e32 v183, v182
	v_lshl_add_u64 v[132:133], v[110:111], 0, v[130:131]
	global_store_dwordx2 v[132:133], v[106:107], off
	v_mov_b32_e32 v106, v182
	v_mov_b32_e32 v107, v182
	v_pk_mul_f32 v[102:103], v[102:103], v[106:107]
	v_pk_mul_f32 v[100:101], v[100:101], v[182:183]
	s_nop 1
	v_mov_b32_dpp v106, v100 row_ror:1 row_mask:0xf bank_mask:0xf
	v_mov_b32_dpp v110, v100 row_ror:2 row_mask:0xf bank_mask:0xf
	v_mov_b32_dpp v107, v101 row_ror:1 row_mask:0xf bank_mask:0xf
	v_mov_b32_dpp v111, v101 row_ror:2 row_mask:0xf bank_mask:0xf
	v_mov_b32_dpp v106, v104 row_shr:1 row_mask:0xf bank_mask:0xf
	v_mov_b32_dpp v110, v104 row_shr:2 row_mask:0xf bank_mask:0xf
	v_mov_b32_dpp v107, v105 row_shr:1 row_mask:0xf bank_mask:0xf
	v_mov_b32_dpp v111, v105 row_shr:2 row_mask:0xf bank_mask:0xf
	v_mov_b32_dpp v134, v102 row_ror:1 row_mask:0xf bank_mask:0xf
	v_mov_b32_dpp v136, v102 row_ror:2 row_mask:0xf bank_mask:0xf
	v_mov_b32_dpp v135, v103 row_ror:1 row_mask:0xf bank_mask:0xf
	v_mov_b32_dpp v137, v103 row_ror:2 row_mask:0xf bank_mask:0xf
	v_pk_fma_f32 v[104:105], v[104:105], v[120:121], v[124:125]
	v_mov_b32_dpp v134, v96 row_shr:1 row_mask:0xf bank_mask:0xf
	v_mov_b32_dpp v136, v96 row_shr:2 row_mask:0xf bank_mask:0xf
	v_mov_b32_dpp v135, v97 row_shr:1 row_mask:0xf bank_mask:0xf
	v_mov_b32_dpp v137, v97 row_shr:2 row_mask:0xf bank_mask:0xf
	v_pk_fma_f32 v[96:97], v[96:97], v[122:123], v[126:127]
	v_pk_fma_f32 v[104:105], v[116:117], v[106:107], v[104:105]
	v_pk_fma_f32 v[96:97], v[118:119], v[134:135], v[96:97]
	v_pk_fma_f32 v[104:105], v[112:113], v[110:111], v[104:105]
	v_lshlrev_b32_e32 v106, 16, v203
	v_and_b32_e32 v107, 0xffff0000, v203
	v_pk_fma_f32 v[96:97], v[114:115], v[136:137], v[96:97]
	v_pk_mul_f32 v[104:105], v[104:105], v[106:107]
	v_lshlrev_b32_e32 v106, 16, v196
	v_and_b32_e32 v107, 0xffff0000, v196
	v_pk_mul_f32 v[96:97], v[96:97], v[106:107]
	v_cvt_pk_bf16_f32 v104, v104, v105
	v_cvt_pk_bf16_f32 v105, v96, v97
	v_or_b32_e32 v96, 32, v141
	v_mad_i64_i32 v[96:97], s[50:51], v96, s89, v[108:109]
	v_lshl_add_u64 v[134:135], v[96:97], 0, v[130:131]
	global_store_dwordx2 v[134:135], v[104:105], off
	v_mov_b32_e32 v96, v180
	v_mov_b32_e32 v97, v180
	v_pk_mul_f32 v[98:99], v[98:99], v[96:97]
	v_mov_b32_dpp v104, v128 row_ror:1 row_mask:0xf bank_mask:0xf
	v_mov_b32_dpp v106, v128 row_ror:2 row_mask:0xf bank_mask:0xf
	v_mov_b32_dpp v105, v129 row_ror:1 row_mask:0xf bank_mask:0xf
	v_mov_b32_dpp v107, v129 row_ror:2 row_mask:0xf bank_mask:0xf
	v_mov_b32_dpp v104, v100 row_shr:1 row_mask:0xf bank_mask:0xf
	v_mov_b32_dpp v106, v100 row_shr:2 row_mask:0xf bank_mask:0xf
	v_mov_b32_dpp v105, v101 row_shr:1 row_mask:0xf bank_mask:0xf
	v_mov_b32_dpp v107, v101 row_shr:2 row_mask:0xf bank_mask:0xf
	v_mov_b32_dpp v110, v98 row_ror:1 row_mask:0xf bank_mask:0xf
	v_mov_b32_dpp v136, v98 row_ror:2 row_mask:0xf bank_mask:0xf
	v_mov_b32_dpp v111, v99 row_ror:1 row_mask:0xf bank_mask:0xf
	v_mov_b32_dpp v137, v99 row_ror:2 row_mask:0xf bank_mask:0xf
	v_pk_fma_f32 v[100:101], v[100:101], v[120:121], v[124:125]
	v_mov_b32_dpp v110, v102 row_shr:1 row_mask:0xf bank_mask:0xf
	v_mov_b32_dpp v136, v102 row_shr:2 row_mask:0xf bank_mask:0xf
	v_mov_b32_dpp v111, v103 row_shr:1 row_mask:0xf bank_mask:0xf
	v_mov_b32_dpp v137, v103 row_shr:2 row_mask:0xf bank_mask:0xf
	v_pk_fma_f32 v[102:103], v[102:103], v[122:123], v[126:127]
	v_pk_fma_f32 v[100:101], v[116:117], v[104:105], v[100:101]
	v_pk_fma_f32 v[102:103], v[118:119], v[110:111], v[102:103]
	v_pk_fma_f32 v[100:101], v[112:113], v[106:107], v[100:101]
	v_lshlrev_b32_e32 v104, 16, v150
	v_and_b32_e32 v105, 0xffff0000, v150
	v_pk_fma_f32 v[102:103], v[114:115], v[136:137], v[102:103]
	v_pk_mul_f32 v[100:101], v[100:101], v[104:105]
	v_lshlrev_b32_e32 v104, 16, v138
	v_and_b32_e32 v105, 0xffff0000, v138
	v_pk_mul_f32 v[102:103], v[102:103], v[104:105]
	v_cvt_pk_bf16_f32 v100, v100, v101
	v_cvt_pk_bf16_f32 v101, v102, v103
	v_or_b32_e32 v102, 16, v141
	v_mad_i64_i32 v[102:103], s[50:51], v102, s89, v[108:109]
	v_lshl_add_u64 v[136:137], v[102:103], 0, v[130:131]
	global_store_dwordx2 v[136:137], v[100:101], off
	v_mov_b32_e32 v101, 0
	v_mov_b32_e32 v105, 0
	v_pk_fma_f32 v[110:111], v[128:129], v[120:121], v[124:125]
	v_mov_b32_dpp v101, v101 row_ror:1 row_mask:0xf bank_mask:0xf
	v_mov_b32_dpp v105, v105 row_ror:2 row_mask:0xf bank_mask:0xf
	v_mov_b32_e32 v102, v101
	v_mov_b32_e32 v103, v101
	v_mov_b32_e32 v100, v101
	v_mov_b32_e32 v104, v105
	v_mov_b32_dpp v102, v128 row_shr:1 row_mask:0xf bank_mask:0xf
	v_mov_b32_e32 v106, v105
	v_mov_b32_dpp v103, v129 row_shr:1 row_mask:0xf bank_mask:0xf
	v_mov_b32_e32 v107, v105
	v_mov_b32_dpp v100, v98 row_shr:1 row_mask:0xf bank_mask:0xf
	v_mov_b32_dpp v104, v98 row_shr:2 row_mask:0xf bank_mask:0xf
	v_mov_b32_dpp v101, v99 row_shr:1 row_mask:0xf bank_mask:0xf
	v_mov_b32_dpp v105, v99 row_shr:2 row_mask:0xf bank_mask:0xf
	v_pk_fma_f32 v[98:99], v[98:99], v[122:123], v[126:127]
	v_mov_b32_dpp v106, v128 row_shr:2 row_mask:0xf bank_mask:0xf
	v_mov_b32_dpp v107, v129 row_shr:2 row_mask:0xf bank_mask:0xf
	v_pk_fma_f32 v[98:99], v[118:119], v[100:101], v[98:99]
	v_pk_fma_f32 v[100:101], v[116:117], v[102:103], v[110:111]
	v_lshlrev_b32_e32 v102, 16, v139
	v_pk_fma_f32 v[100:101], v[112:113], v[106:107], v[100:101]
	v_and_b32_e32 v103, 0xffff0000, v139
	v_pk_fma_f32 v[98:99], v[114:115], v[104:105], v[98:99]
	v_pk_mul_f32 v[100:101], v[100:101], v[102:103]
	v_lshlrev_b32_e32 v102, 16, v140
	v_and_b32_e32 v103, 0xffff0000, v140
	v_pk_mul_f32 v[98:99], v[98:99], v[102:103]
	v_cvt_pk_bf16_f32 v100, v100, v101
	v_cvt_pk_bf16_f32 v101, v98, v99
	v_mad_i64_i32 v[98:99], s[50:51], v141, s89, v[108:109]
	v_lshl_add_u64 v[128:129], v[98:99], 0, v[130:131]
	global_store_dwordx2 v[128:129], v[100:101], off
	v_or_b32_e32 v122, 4, v170
	v_ashrrev_i32_e32 v123, 31, v122
	v_lshlrev_b64 v[98:99], 2, v[122:123]
	v_lshl_add_u64 v[124:125], s[34:35], 0, v[98:99]
	global_load_dwordx4 v[100:103], v[172:173], off offset:16
	v_lshl_add_u64 v[126:127], s[36:37], 0, v[98:99]
	global_load_dwordx4 v[104:107], v[124:125], off
	global_load_dwordx4 v[108:111], v[126:127], off
	global_load_dwordx4 v[112:115], v[178:179], off offset:16
	v_pk_mul_f32 v[116:117], v[80:81], v[180:181]
	s_and_saveexec_b64 s[58:59], s[12:13]
	s_cbranch_execz .LBB0_1002
	v_mov_b64_e32 v[80:81], s[26:27]
	v_mad_i64_i32 v[80:81], s[50:51], v246, s87, v[80:81]
	v_pk_mul_f32 v[118:119], v[82:83], v[96:97]
	v_lshl_add_u64 v[80:81], v[170:171], 2, v[80:81]
	global_store_dwordx4 v[80:81], v[116:119], off offset:16

;     __device__ __forceinline__ void operator()(const f32x4 (&acc)[2][2][4][2], const Unit& u, int wr, int wc, int fr, int fq) const {
;     ...
;                 for (int bj = 0; bj < 2; ++bj) {
;                     const int col = bj * dff + cg;
;                     const f32x4 w0 = *(const f32x4*)(cw + col), w1 = *(const f32x4*)(cw + 2 * dff + col), w2 = *(const f32x4*)(cw + 4 * dff + col), wb = *(const f32x4*)(cb + col);
;                     if (fr < 2) *(f32x4*)(RB + ((size_t)(blk * 4 + fr) * 2 + bj) * dff + cg) = acc[ai][bj][0][n] * rs[0];
;                     if (fr >= 14) *(f32x4*)(RB + ((size_t)(blk * 4 + fr - 12) * 2 + bj) * dff + cg) = acc[ai][bj][3][n] * rs[3];
; #pragma unroll
;                     for (int m = 3; m >= 0; --m) {
;                         const f32x4 cur = acc[ai][bj][m][n] * rs[m];
;                         f32x4 prev = zero4;
;                         if (m > 0) prev = acc[ai][bj][m - 1][n] * rs[m - 1];
;                         f32x4 r1, r2;
; #pragma unroll
;                         for (int i = 0; i < 4; ++i) {
;                             r1[i] = dpp_mov<0x111>(dpp_mov<0x121>(0.f, prev[i]), cur[i]);
;                             r2[i] = dpp_mov<0x112>(dpp_mov<0x122>(0.f, prev[i]), cur[i]); }
.LBB0_1004:
	s_or_b64 exec, exec, s[58:59]
	v_mov_b32_e32 v80, v184
	v_mov_b32_e32 v81, v184
	v_pk_mul_f32 v[146:147], v[90:91], v[80:81]
	v_pk_mul_f32 v[148:149], v[88:89], v[184:185]
	s_nop 1
	v_mov_b32_dpp v210, v148 row_ror:1 row_mask:0xf bank_mask:0xf
	v_mov_b32_dpp v206, v148 row_ror:2 row_mask:0xf bank_mask:0xf
	v_mov_b32_dpp v211, v149 row_ror:1 row_mask:0xf bank_mask:0xf
	v_mov_b32_dpp v207, v149 row_ror:2 row_mask:0xf bank_mask:0xf
	v_mov_b32_dpp v216, v146 row_ror:1 row_mask:0xf bank_mask:0xf
	v_mov_b32_dpp v212, v146 row_ror:2 row_mask:0xf bank_mask:0xf
	v_mov_b32_dpp v217, v147 row_ror:1 row_mask:0xf bank_mask:0xf
	v_mov_b32_dpp v213, v147 row_ror:2 row_mask:0xf bank_mask:0xf
	v_mov_b32_dpp v210, v118 row_shr:1 row_mask:0xf bank_mask:0xf
	v_mov_b32_dpp v206, v118 row_shr:2 row_mask:0xf bank_mask:0xf
	v_mov_b32_dpp v211, v119 row_shr:1 row_mask:0xf bank_mask:0xf
	v_mov_b32_dpp v207, v119 row_shr:2 row_mask:0xf bank_mask:0xf
	v_mov_b32_dpp v216, v120 row_shr:1 row_mask:0xf bank_mask:0xf
	v_mov_b32_dpp v212, v120 row_shr:2 row_mask:0xf bank_mask:0xf
	v_mov_b32_dpp v217, v121 row_shr:1 row_mask:0xf bank_mask:0xf
	v_mov_b32_dpp v213, v121 row_shr:2 row_mask:0xf bank_mask:0xf
	v_mov_b32_e32 v80, v182
	v_mov_b32_e32 v81, v182
	v_pk_mul_f32 v[140:141], v[86:87], v[80:81]
	v_pk_mul_f32 v[142:143], v[84:85], v[182:183]
	s_nop 1
	v_mov_b32_dpp v202, v142 row_ror:1 row_mask:0xf bank_mask:0xf
	v_mov_b32_dpp v200, v142 row_ror:2 row_mask:0xf bank_mask:0xf
	v_mov_b32_dpp v203, v143 row_ror:1 row_mask:0xf bank_mask:0xf
	v_mov_b32_dpp v201, v143 row_ror:2 row_mask:0xf bank_mask:0xf
	v_mov_b32_dpp v214, v140 row_ror:1 row_mask:0xf bank_mask:0xf
	v_mov_b32_dpp v204, v140 row_ror:2 row_mask:0xf bank_mask:0xf
	v_mov_b32_dpp v215, v141 row_ror:1 row_mask:0xf bank_mask:0xf
	v_mov_b32_dpp v205, v141 row_ror:2 row_mask:0xf bank_mask:0xf
	v_mov_b32_dpp v202, v148 row_shr:1 row_mask:0xf bank_mask:0xf
	v_mov_b32_dpp v200, v148 row_shr:2 row_mask:0xf bank_mask:0xf
	v_mov_b32_dpp v203, v149 row_shr:1 row_mask:0xf bank_mask:0xf
	v_mov_b32_dpp v201, v149 row_shr:2 row_mask:0xf bank_mask:0xf
	v_mov_b32_dpp v214, v146 row_shr:1 row_mask:0xf bank_mask:0xf
	v_mov_b32_dpp v204, v146 row_shr:2 row_mask:0xf bank_mask:0xf
	v_mov_b32_dpp v215, v147 row_shr:1 row_mask:0xf bank_mask:0xf
	v_mov_b32_dpp v205, v147 row_shr:2 row_mask:0xf bank_mask:0xf
	v_mov_b32_e32 v98, v180
	v_mov_b32_e32 v99, v180
	v_pk_mul_f32 v[138:139], v[82:83], v[98:99]
	v_mov_b32_dpp v196, v116 row_ror:1 row_mask:0xf bank_mask:0xf
	v_mov_b32_dpp v194, v116 row_ror:2 row_mask:0xf bank_mask:0xf
	v_mov_b32_dpp v197, v117 row_ror:1 row_mask:0xf bank_mask:0xf
	v_mov_b32_dpp v195, v117 row_ror:2 row_mask:0xf bank_mask:0xf
	v_mov_b32_dpp v208, v138 row_ror:1 row_mask:0xf bank_mask:0xf
	v_mov_b32_dpp v198, v138 row_ror:2 row_mask:0xf bank_mask:0xf
	v_mov_b32_dpp v209, v139 row_ror:1 row_mask:0xf bank_mask:0xf
	v_mov_b32_dpp v199, v139 row_ror:2 row_mask:0xf bank_mask:0xf
	v_mov_b32_dpp v196, v142 row_shr:1 row_mask:0xf bank_mask:0xf
	v_mov_b32_dpp v194, v142 row_shr:2 row_mask:0xf bank_mask:0xf
	v_mov_b32_dpp v197, v143 row_shr:1 row_mask:0xf bank_mask:0xf
	v_mov_b32_dpp v195, v143 row_shr:2 row_mask:0xf bank_mask:0xf
	v_mov_b32_dpp v208, v140 row_shr:1 row_mask:0xf bank_mask:0xf
	v_mov_b32_dpp v198, v140 row_shr:2 row_mask:0xf bank_mask:0xf
	v_mov_b32_dpp v209, v141 row_shr:1 row_mask:0xf bank_mask:0xf
	v_mov_b32_dpp v199, v141 row_shr:2 row_mask:0xf bank_mask:0xf
	v_mov_b32_e32 v193, 0
	v_mov_b32_e32 v145, 0
	s_nop 0
	v_mov_b32_dpp v193, v193 row_ror:1 row_mask:0xf bank_mask:0xf
	v_mov_b32_dpp v145, v145 row_ror:2 row_mask:0xf bank_mask:0xf
	v_mov_b32_e32 v152, v193
	v_mov_b32_e32 v150, v145
	v_mov_b32_e32 v153, v193
	v_mov_b32_e32 v151, v145
	v_mov_b32_e32 v192, v193
	v_mov_b32_e32 v144, v145
	v_mov_b32_dpp v152, v116 row_shr:1 row_mask:0xf bank_mask:0xf
	v_mov_b32_dpp v150, v116 row_shr:2 row_mask:0xf bank_mask:0xf
	v_mov_b32_dpp v153, v117 row_shr:1 row_mask:0xf bank_mask:0xf
	v_mov_b32_dpp v151, v117 row_shr:2 row_mask:0xf bank_mask:0xf
	v_mov_b32_dpp v192, v138 row_shr:1 row_mask:0xf bank_mask:0xf
	v_mov_b32_dpp v144, v138 row_shr:2 row_mask:0xf bank_mask:0xf
	v_mov_b32_dpp v193, v139 row_shr:1 row_mask:0xf bank_mask:0xf
	v_mov_b32_dpp v145, v139 row_shr:2 row_mask:0xf bank_mask:0xf
	v_add_co_u32_e32 v88, vcc, 0x5000, v176
	global_load_dwordx4 v[80:83], v[188:189], off offset:2064
	global_load_dwordx4 v[84:87], v[190:191], off offset:2064
	v_addc_co_u32_e32 v89, vcc, 0, v177, vcc
	v_add_co_u32_e32 v92, vcc, 0x5000, v178
	global_load_dwordx4 v[88:91], v[88:89], off offset:2064
	s_nop 0
	v_addc_co_u32_e32 v93, vcc, 0, v179, vcc
	global_load_dwordx4 v[92:95], v[92:93], off offset:2064
	v_pk_mul_f32 v[96:97], v[64:65], v[180:181]
	s_and_saveexec_b64 s[58:59], s[12:13]
	s_cbranch_execz .LBB0_1006
	v_mov_b64_e32 v[64:65], s[26:27]
	v_mad_i64_i32 v[64:65], s[50:51], v246, s87, v[64:65]
	v_lshl_add_u64 v[64:65], v[122:123], 2, v[64:65]
	v_add_co_u32_e32 v64, vcc, 0x5000, v64
	v_pk_mul_f32 v[98:99], v[66:67], v[98:99]
	s_nop 0
	v_addc_co_u32_e32 v65, vcc, 0, v65, vcc
	global_store_dwordx4 v[64:65], v[96:99], off offset:2048

; __device__ __forceinline__ unsigned cvt_pk_bf16(float lo, float hi) { f32x2_cv v = {lo, hi}; bf16x2_cv b = __builtin_convertvector(v, bf16x2_cv); return __builtin_bit_cast(unsigned, b); }
; __device__ __forceinline__ float siluf_(float x) { return x * __builtin_amdgcn_rcpf(1.0f + __expf(-x)); }
;     __device__ __forceinline__ void operator()(const f32x4 (&acc)[2][2][4][2], const Unit& u, int wr, int wc, int fr, int fq) const {
;     ...
;                     for (int m = 3; m >= 0; --m) {
;                         const f32x4 cur = acc[ai][bj][m][n] * rs[m];
;                         f32x4 prev = zero4;
;                         if (m > 0) prev = acc[ai][bj][m - 1][n] * rs[m - 1];
;                         f32x4 r1, r2;
; #pragma unroll
;                         for (int i = 0; i < 4; ++i) {
;                             r1[i] = dpp_mov<0x111>(dpp_mov<0x121>(0.f, prev[i]), cur[i]);
;                             r2[i] = dpp_mov<0x112>(dpp_mov<0x122>(0.f, prev[i]), cur[i]); }
;                         const f32x4 cvv = wb + w2 * cur + w1 * r1 + w0 * r2;
;                         if (bj == 0) {
;                             sg[m].x = cvt_pk_bf16(siluf_(cvv[0]), siluf_(cvv[1])); sg[m].y = cvt_pk_bf16(siluf_(cvv[2]), siluf_(cvv[3]));
.LBB0_1008:
	s_or_b64 exec, exec, s[58:59]
	s_waitcnt vmcnt(4)
	v_pk_fma_f32 v[98:99], v[118:119], v[108:109], v[112:113]
	v_pk_fma_f32 v[64:65], v[120:121], v[110:111], v[114:115]
	v_pk_fma_f32 v[98:99], v[104:105], v[210:211], v[98:99]
	v_pk_fma_f32 v[64:65], v[106:107], v[216:217], v[64:65]
	v_pk_fma_f32 v[98:99], v[100:101], v[206:207], v[98:99]
	v_pk_fma_f32 v[64:65], v[102:103], v[212:213], v[64:65]
	v_mul_f32_e32 v118, 0xbfb8aa3b, v98
	v_mul_f32_e32 v119, 0xbfb8aa3b, v99
	v_exp_f32_e32 v118, v118
	v_exp_f32_e32 v119, v119
	v_mul_f32_e32 v120, 0xbfb8aa3b, v64
	v_mul_f32_e32 v121, 0xbfb8aa3b, v65
	v_exp_f32_e32 v120, v120
	v_exp_f32_e32 v121, v121
	v_add_f32_e32 v118, 1.0, v118
	v_add_f32_e32 v119, 1.0, v119
	v_rcp_f32_e32 v118, v118
	v_rcp_f32_e32 v119, v119
	v_add_f32_e32 v120, 1.0, v120
	v_add_f32_e32 v121, 1.0, v121
	v_rcp_f32_e32 v120, v120
	v_rcp_f32_e32 v121, v121
	v_pk_mul_f32 v[98:99], v[98:99], v[118:119]
	v_pk_fma_f32 v[118:119], v[148:149], v[108:109], v[112:113]
	v_cvt_pk_bf16_f32 v181, v98, v99
	v_pk_fma_f32 v[98:99], v[146:147], v[110:111], v[114:115]
	v_pk_fma_f32 v[118:119], v[104:105], v[202:203], v[118:119]
	v_pk_fma_f32 v[98:99], v[106:107], v[214:215], v[98:99]
	v_pk_fma_f32 v[118:119], v[100:101], v[200:201], v[118:119]
	v_pk_mul_f32 v[64:65], v[64:65], v[120:121]
	v_mul_f32_e32 v120, 0xbfb8aa3b, v118
	v_mul_f32_e32 v121, 0xbfb8aa3b, v119
	v_pk_fma_f32 v[98:99], v[102:103], v[204:205], v[98:99]
	v_exp_f32_e32 v120, v120
	v_exp_f32_e32 v121, v121
	v_mul_f32_e32 v146, 0xbfb8aa3b, v98
	v_mul_f32_e32 v147, 0xbfb8aa3b, v99
	v_exp_f32_e32 v146, v146
	v_exp_f32_e32 v147, v147
	v_add_f32_e32 v120, 1.0, v120
	v_add_f32_e32 v121, 1.0, v121
	v_rcp_f32_e32 v120, v120
	v_rcp_f32_e32 v121, v121
	v_add_f32_e32 v146, 1.0, v146
	v_add_f32_e32 v147, 1.0, v147
	v_rcp_f32_e32 v146, v146
	v_rcp_f32_e32 v147, v147
	v_cvt_pk_bf16_f32 v148, v64, v65
	v_pk_mul_f32 v[64:65], v[118:119], v[120:121]
	v_pk_fma_f32 v[118:119], v[142:143], v[108:109], v[112:113]
	v_cvt_pk_bf16_f32 v149, v64, v65
	v_pk_mul_f32 v[64:65], v[98:99], v[146:147]
	v_pk_fma_f32 v[98:99], v[140:141], v[110:111], v[114:115]
	v_pk_fma_f32 v[118:119], v[104:105], v[196:197], v[118:119]
	v_pk_fma_f32 v[98:99], v[106:107], v[208:209], v[98:99]
	v_pk_fma_f32 v[118:119], v[100:101], v[194:195], v[118:119]
	v_pk_fma_f32 v[98:99], v[102:103], v[198:199], v[98:99]
	v_mul_f32_e32 v120, 0xbfb8aa3b, v118
	v_mul_f32_e32 v121, 0xbfb8aa3b, v119
	v_exp_f32_e32 v120, v120
	v_exp_f32_e32 v121, v121
	v_mul_f32_e32 v140, 0xbfb8aa3b, v98
	v_mul_f32_e32 v141, 0xbfb8aa3b, v99
	v_exp_f32_e32 v140, v140
	v_exp_f32_e32 v141, v141
	v_add_f32_e32 v120, 1.0, v120
	v_add_f32_e32 v121, 1.0, v121
	v_rcp_f32_e32 v120, v120
	v_rcp_f32_e32 v121, v121
	v_add_f32_e32 v140, 1.0, v140
	v_add_f32_e32 v141, 1.0, v141
	v_pk_fma_f32 v[108:109], v[116:117], v[108:109], v[112:113]
	v_rcp_f32_e32 v140, v140
	v_rcp_f32_e32 v141, v141
	v_pk_fma_f32 v[104:105], v[104:105], v[152:153], v[108:109]
	v_cvt_pk_bf16_f32 v142, v64, v65
	v_pk_fma_f32 v[100:101], v[100:101], v[150:151], v[104:105]
	v_pk_mul_f32 v[64:65], v[118:119], v[120:121]
	v_mul_f32_e32 v104, 0xbfb8aa3b, v100
	v_mul_f32_e32 v105, 0xbfb8aa3b, v101
	v_exp_f32_e32 v104, v104
	v_exp_f32_e32 v105, v105
	v_cvt_pk_bf16_f32 v118, v64, v65
	v_pk_mul_f32 v[64:65], v[98:99], v[140:141]
	v_pk_fma_f32 v[98:99], v[138:139], v[110:111], v[114:115]
	v_pk_mul_f32 v[72:73], v[72:73], v[184:185]
	v_pk_fma_f32 v[98:99], v[106:107], v[192:193], v[98:99]
	v_cvt_pk_bf16_f32 v106, v64, v65
	v_pk_fma_f32 v[98:99], v[102:103], v[144:145], v[98:99]
	v_add_f32_e32 v102, 1.0, v104
	v_add_f32_e32 v103, 1.0, v105
	v_mul_f32_e32 v104, 0xbfb8aa3b, v98
	v_mul_f32_e32 v105, 0xbfb8aa3b, v99
	v_exp_f32_e32 v104, v104
	v_exp_f32_e32 v105, v105
	v_rcp_f32_e32 v102, v102
	v_rcp_f32_e32 v103, v103
	v_add_f32_e32 v104, 1.0, v104
	v_add_f32_e32 v105, 1.0, v105
	v_rcp_f32_e32 v104, v104
	v_rcp_f32_e32 v105, v105
	v_pk_mul_f32 v[64:65], v[100:101], v[102:103]
	v_cvt_pk_bf16_f32 v107, v64, v65
	v_pk_mul_f32 v[64:65], v[98:99], v[104:105]
	v_cvt_pk_bf16_f32 v104, v64, v65
	v_mov_b32_e32 v64, v184
	v_mov_b32_e32 v65, v184
	v_pk_mul_f32 v[64:65], v[74:75], v[64:65]
	v_mov_b32_dpp v74, v72 row_ror:1 row_mask:0xf bank_mask:0xf
	v_mov_b32_dpp v98, v72 row_ror:2 row_mask:0xf bank_mask:0xf
	v_mov_b32_dpp v75, v73 row_ror:1 row_mask:0xf bank_mask:0xf
	v_mov_b32_dpp v99, v73 row_ror:2 row_mask:0xf bank_mask:0xf
	v_mov_b32_dpp v100, v64 row_ror:1 row_mask:0xf bank_mask:0xf
	v_mov_b32_dpp v102, v64 row_ror:2 row_mask:0xf bank_mask:0xf
	v_mov_b32_dpp v101, v65 row_ror:1 row_mask:0xf bank_mask:0xf
	v_mov_b32_dpp v103, v65 row_ror:2 row_mask:0xf bank_mask:0xf
	v_mov_b32_dpp v74, v76 row_shr:1 row_mask:0xf bank_mask:0xf
	v_mov_b32_dpp v98, v76 row_shr:2 row_mask:0xf bank_mask:0xf
	v_mov_b32_dpp v75, v77 row_shr:1 row_mask:0xf bank_mask:0xf
	v_mov_b32_dpp v99, v77 row_shr:2 row_mask:0xf bank_mask:0xf
	v_mov_b32_dpp v100, v78 row_shr:1 row_mask:0xf bank_mask:0xf
	v_mov_b32_dpp v102, v78 row_shr:2 row_mask:0xf bank_mask:0xf
	v_mov_b32_dpp v101, v79 row_shr:1 row_mask:0xf bank_mask:0xf
	v_mov_b32_dpp v103, v79 row_shr:2 row_mask:0xf bank_mask:0xf
	s_waitcnt vmcnt(0)
; __device__ __forceinline__ unsigned cvt_pk_bf16(float lo, float hi) { f32x2_cv v = {lo, hi}; bf16x2_cv b = __builtin_convertvector(v, bf16x2_cv); return __builtin_bit_cast(unsigned, b); }
; __device__ __forceinline__ float siluf_(float x) { return x * __builtin_amdgcn_rcpf(1.0f + __expf(-x)); }
;     __device__ __forceinline__ void operator()(const f32x4 (&acc)[2][2][4][2], const Unit& u, int wr, int wc, int fr, int fq) const {
;     ...
;                     for (int m = 3; m >= 0; --m) {
;                         const f32x4 cur = acc[ai][bj][m][n] * rs[m];
;                         f32x4 prev = zero4;
;                         if (m > 0) prev = acc[ai][bj][m - 1][n] * rs[m - 1];
;                         f32x4 r1, r2;
; #pragma unroll
;                         for (int i = 0; i < 4; ++i) {
;                             r1[i] = dpp_mov<0x111>(dpp_mov<0x121>(0.f, prev[i]), cur[i]);
;                             r2[i] = dpp_mov<0x112>(dpp_mov<0x122>(0.f, prev[i]), cur[i]); }
;                         const f32x4 cvv = wb + w2 * cur + w1 * r1 + w0 * r2;
;                         if (bj == 0) {
;                             sg[m].x = cvt_pk_bf16(siluf_(cvv[0]), siluf_(cvv[1])); sg[m].y = cvt_pk_bf16(siluf_(cvv[2]), siluf_(cvv[3]));
;                         } else {
;                             f32x4 h;
;                             h[0] = __uint_as_float(sg[m].x << 16) * cvv[0]; h[1] = __uint_as_float(sg[m].x & 0xffff0000u) * cvv[1];
;                             h[2] = __uint_as_float(sg[m].y << 16) * cvv[2]; h[3] = __uint_as_float(sg[m].y & 0xffff0000u) * cvv[3];
;                             u32x2v w; w.x = cvt_pk_bf16(h[0], h[1]); w.y = cvt_pk_bf16(h[2], h[3]);
;                             *(u32x2v*)(H + (size_t)(rowb + m * 16 + fr) * dff + cg) = w;
;                         }
	v_pk_fma_f32 v[78:79], v[78:79], v[90:91], v[94:95]
	v_pk_fma_f32 v[76:77], v[76:77], v[88:89], v[92:93]
	v_pk_fma_f32 v[78:79], v[86:87], v[100:101], v[78:79]
	v_pk_fma_f32 v[74:75], v[84:85], v[74:75], v[76:77]
	v_pk_fma_f32 v[76:77], v[82:83], v[102:103], v[78:79]
	v_pk_fma_f32 v[74:75], v[80:81], v[98:99], v[74:75]
	v_lshlrev_b32_e32 v78, 16, v181
	v_and_b32_e32 v79, 0xffff0000, v181
	v_pk_mul_f32 v[74:75], v[74:75], v[78:79]
	v_lshlrev_b32_e32 v78, 16, v148
	v_and_b32_e32 v79, 0xffff0000, v148
	v_pk_mul_f32 v[76:77], v[76:77], v[78:79]
	v_cvt_pk_bf16_f32 v74, v74, v75
	v_cvt_pk_bf16_f32 v75, v76, v77
	global_store_dwordx2 v[132:133], v[74:75], off offset:8
	v_mov_b32_e32 v74, v182
	v_mov_b32_e32 v75, v182
	v_pk_mul_f32 v[70:71], v[70:71], v[74:75]
	v_pk_mul_f32 v[68:69], v[68:69], v[182:183]
	s_nop 1
	v_mov_b32_dpp v74, v68 row_ror:1 row_mask:0xf bank_mask:0xf
	v_mov_b32_dpp v76, v68 row_ror:2 row_mask:0xf bank_mask:0xf
	v_mov_b32_dpp v75, v69 row_ror:1 row_mask:0xf bank_mask:0xf
	v_mov_b32_dpp v77, v69 row_ror:2 row_mask:0xf bank_mask:0xf
	v_mov_b32_dpp v74, v72 row_shr:1 row_mask:0xf bank_mask:0xf
	v_mov_b32_dpp v76, v72 row_shr:2 row_mask:0xf bank_mask:0xf
	v_mov_b32_dpp v75, v73 row_shr:1 row_mask:0xf bank_mask:0xf
	v_mov_b32_dpp v77, v73 row_shr:2 row_mask:0xf bank_mask:0xf
	v_mov_b32_dpp v78, v70 row_ror:1 row_mask:0xf bank_mask:0xf
	v_mov_b32_dpp v98, v70 row_ror:2 row_mask:0xf bank_mask:0xf
	v_mov_b32_dpp v79, v71 row_ror:1 row_mask:0xf bank_mask:0xf
	v_mov_b32_dpp v99, v71 row_ror:2 row_mask:0xf bank_mask:0xf
	v_pk_fma_f32 v[72:73], v[72:73], v[88:89], v[92:93]
	v_mov_b32_dpp v78, v64 row_shr:1 row_mask:0xf bank_mask:0xf
	v_mov_b32_dpp v98, v64 row_shr:2 row_mask:0xf bank_mask:0xf
	v_mov_b32_dpp v79, v65 row_shr:1 row_mask:0xf bank_mask:0xf
	v_mov_b32_dpp v99, v65 row_shr:2 row_mask:0xf bank_mask:0xf
	v_pk_fma_f32 v[64:65], v[64:65], v[90:91], v[94:95]
	v_pk_fma_f32 v[72:73], v[84:85], v[74:75], v[72:73]
	v_pk_fma_f32 v[64:65], v[86:87], v[78:79], v[64:65]
	v_pk_fma_f32 v[72:73], v[80:81], v[76:77], v[72:73]
	v_lshlrev_b32_e32 v74, 16, v149
	v_and_b32_e32 v75, 0xffff0000, v149
	v_pk_fma_f32 v[64:65], v[82:83], v[98:99], v[64:65]
	v_pk_mul_f32 v[72:73], v[72:73], v[74:75]
	v_lshlrev_b32_e32 v74, 16, v142
	v_and_b32_e32 v75, 0xffff0000, v142
	v_pk_mul_f32 v[64:65], v[64:65], v[74:75]
	v_cvt_pk_bf16_f32 v72, v72, v73
	v_cvt_pk_bf16_f32 v73, v64, v65
	global_store_dwordx2 v[134:135], v[72:73], off offset:8
	v_mov_b32_e32 v181, v180
	v_pk_mul_f32 v[64:65], v[66:67], v[180:181]
	v_mov_b32_dpp v66, v96 row_ror:1 row_mask:0xf bank_mask:0xf
	v_mov_b32_dpp v72, v96 row_ror:2 row_mask:0xf bank_mask:0xf
	v_mov_b32_dpp v67, v97 row_ror:1 row_mask:0xf bank_mask:0xf
	v_mov_b32_dpp v73, v97 row_ror:2 row_mask:0xf bank_mask:0xf
	v_mov_b32_dpp v74, v64 row_ror:1 row_mask:0xf bank_mask:0xf
	v_mov_b32_dpp v76, v64 row_ror:2 row_mask:0xf bank_mask:0xf
	v_mov_b32_dpp v75, v65 row_ror:1 row_mask:0xf bank_mask:0xf
	v_mov_b32_dpp v77, v65 row_ror:2 row_mask:0xf bank_mask:0xf
	v_mov_b32_dpp v66, v68 row_shr:1 row_mask:0xf bank_mask:0xf
	v_mov_b32_dpp v72, v68 row_shr:2 row_mask:0xf bank_mask:0xf
	v_mov_b32_dpp v67, v69 row_shr:1 row_mask:0xf bank_mask:0xf
	v_mov_b32_dpp v73, v69 row_shr:2 row_mask:0xf bank_mask:0xf
	v_mov_b32_dpp v74, v70 row_shr:1 row_mask:0xf bank_mask:0xf
	v_mov_b32_dpp v76, v70 row_shr:2 row_mask:0xf bank_mask:0xf
	v_mov_b32_dpp v75, v71 row_shr:1 row_mask:0xf bank_mask:0xf
	v_mov_b32_dpp v77, v71 row_shr:2 row_mask:0xf bank_mask:0xf
	v_pk_fma_f32 v[70:71], v[70:71], v[90:91], v[94:95]
	v_pk_fma_f32 v[68:69], v[68:69], v[88:89], v[92:93]
	v_pk_fma_f32 v[70:71], v[86:87], v[74:75], v[70:71]
	v_pk_fma_f32 v[66:67], v[84:85], v[66:67], v[68:69]
	v_pk_fma_f32 v[68:69], v[82:83], v[76:77], v[70:71]
	v_pk_fma_f32 v[66:67], v[80:81], v[72:73], v[66:67]
	v_lshlrev_b32_e32 v70, 16, v118
	v_and_b32_e32 v71, 0xffff0000, v118
	v_pk_mul_f32 v[66:67], v[66:67], v[70:71]
	v_lshlrev_b32_e32 v70, 16, v106
	v_and_b32_e32 v71, 0xffff0000, v106
	v_pk_mul_f32 v[68:69], v[68:69], v[70:71]
	v_cvt_pk_bf16_f32 v66, v66, v67
	v_cvt_pk_bf16_f32 v67, v68, v69
	global_store_dwordx2 v[136:137], v[66:67], off offset:8
	v_mov_b32_e32 v67, 0
	v_mov_b32_e32 v71, 0
	v_pk_fma_f32 v[74:75], v[96:97], v[88:89], v[92:93]
	v_mov_b32_dpp v67, v67 row_ror:1 row_mask:0xf bank_mask:0xf
	v_mov_b32_dpp v71, v71 row_ror:2 row_mask:0xf bank_mask:0xf
	v_mov_b32_e32 v68, v67
	v_mov_b32_e32 v69, v67
	v_mov_b32_e32 v66, v67
	v_mov_b32_e32 v70, v71
	v_mov_b32_dpp v68, v96 row_shr:1 row_mask:0xf bank_mask:0xf
	v_mov_b32_e32 v72, v71
	v_mov_b32_dpp v69, v97 row_shr:1 row_mask:0xf bank_mask:0xf
	v_mov_b32_e32 v73, v71
	v_mov_b32_dpp v66, v64 row_shr:1 row_mask:0xf bank_mask:0xf
	v_mov_b32_dpp v70, v64 row_shr:2 row_mask:0xf bank_mask:0xf
	v_mov_b32_dpp v67, v65 row_shr:1 row_mask:0xf bank_mask:0xf
	v_mov_b32_dpp v71, v65 row_shr:2 row_mask:0xf bank_mask:0xf
	v_pk_fma_f32 v[64:65], v[64:65], v[90:91], v[94:95]
	v_mov_b32_dpp v72, v96 row_shr:2 row_mask:0xf bank_mask:0xf
	v_mov_b32_dpp v73, v97 row_shr:2 row_mask:0xf bank_mask:0xf
	v_pk_fma_f32 v[64:65], v[86:87], v[66:67], v[64:65]
	v_pk_fma_f32 v[66:67], v[84:85], v[68:69], v[74:75]
	v_lshlrev_b32_e32 v68, 16, v107
	v_pk_fma_f32 v[66:67], v[80:81], v[72:73], v[66:67]
	v_and_b32_e32 v69, 0xffff0000, v107
	v_pk_fma_f32 v[64:65], v[82:83], v[70:71], v[64:65]
	v_pk_mul_f32 v[66:67], v[66:67], v[68:69]
	v_lshlrev_b32_e32 v68, 16, v104
	v_and_b32_e32 v69, 0xffff0000, v104
	v_pk_mul_f32 v[64:65], v[64:65], v[68:69]
	v_cvt_pk_bf16_f32 v66, v66, v67
	v_cvt_pk_bf16_f32 v67, v64, v65
	global_store_dwordx2 v[128:129], v[66:67], off offset:8
	global_load_dwordx4 v[68:71], v[172:173], off
	global_load_dwordx4 v[72:75], v[174:175], off
	global_load_dwordx4 v[76:79], v[176:177], off
	global_load_dwordx4 v[80:83], v[178:179], off
	ds_read2_b32 v[90:91], v244 offset0:128 offset1:144
	ds_read2_b32 v[94:95], v244 offset0:160 offset1:176
	s_addk_i32 s43, 0x80
	s_ashr_i32 s50, s43, 4
	v_or_b32_e32 v149, s50, v236
	s_waitcnt lgkmcnt(1)
	v_mov_b32_e32 v92, v91
	v_mov_b32_e32 v91, v90
	s_waitcnt lgkmcnt(0)
	v_mov_b32_e32 v96, v95
	v_pk_mul_f32 v[84:85], v[48:49], v[90:91]
	s_and_saveexec_b64 s[58:59], s[12:13]
	s_cbranch_execz .LBB0_1010
	v_mov_b32_e32 v48, v90
	v_mov_b32_e32 v49, v90
	v_pk_mul_f32 v[86:87], v[50:51], v[48:49]
	v_mov_b64_e32 v[48:49], s[26:27]
	v_mad_i64_i32 v[48:49], s[62:63], v149, s87, v[48:49]
	v_lshl_add_u64 v[48:49], v[170:171], 2, v[48:49]
	global_store_dwordx4 v[48:49], v[84:87], off

;     __device__ __forceinline__ void operator()(const f32x4 (&acc)[2][2][4][2], const Unit& u, int wr, int wc, int fr, int fq) const {
;     ...
;                 for (int bj = 0; bj < 2; ++bj) {
;                     const int col = bj * dff + cg;
;                     const f32x4 w0 = *(const f32x4*)(cw + col), w1 = *(const f32x4*)(cw + 2 * dff + col), w2 = *(const f32x4*)(cw + 4 * dff + col), wb = *(const f32x4*)(cb + col);
;                     if (fr < 2) *(f32x4*)(RB + ((size_t)(blk * 4 + fr) * 2 + bj) * dff + cg) = acc[ai][bj][0][n] * rs[0];
;                     if (fr >= 14) *(f32x4*)(RB + ((size_t)(blk * 4 + fr - 12) * 2 + bj) * dff + cg) = acc[ai][bj][3][n] * rs[3];
; #pragma unroll
;                     for (int m = 3; m >= 0; --m) {
;                         const f32x4 cur = acc[ai][bj][m][n] * rs[m];
;                         f32x4 prev = zero4;
;                         if (m > 0) prev = acc[ai][bj][m - 1][n] * rs[m - 1];
;                         f32x4 r1, r2;
; #pragma unroll
;                         for (int i = 0; i < 4; ++i) {
;                             r1[i] = dpp_mov<0x111>(dpp_mov<0x121>(0.f, prev[i]), cur[i]);
;                             r2[i] = dpp_mov<0x112>(dpp_mov<0x122>(0.f, prev[i]), cur[i]); }
.LBB0_1012:
	s_or_b64 exec, exec, s[58:59]
	v_pk_mul_f32 v[106:107], v[58:59], v[94:95] op_sel_hi:[1,0]
	v_pk_mul_f32 v[108:109], v[56:57], v[94:95] op_sel_hi:[1,0]
	s_nop 1
	v_mov_b32_dpp v140, v108 row_ror:1 row_mask:0xf bank_mask:0xf
	v_mov_b32_dpp v138, v108 row_ror:2 row_mask:0xf bank_mask:0xf
	v_mov_b32_dpp v141, v109 row_ror:1 row_mask:0xf bank_mask:0xf
	v_mov_b32_dpp v139, v109 row_ror:2 row_mask:0xf bank_mask:0xf
	v_mov_b32_dpp v146, v106 row_ror:1 row_mask:0xf bank_mask:0xf
	v_mov_b32_dpp v142, v106 row_ror:2 row_mask:0xf bank_mask:0xf
	v_mov_b32_dpp v147, v107 row_ror:1 row_mask:0xf bank_mask:0xf
	v_mov_b32_dpp v143, v107 row_ror:2 row_mask:0xf bank_mask:0xf
	v_lshl_add_u64 v[48:49], v[172:173], 0, s[38:39]
	v_lshl_add_u64 v[60:61], v[174:175], 0, s[38:39]
	v_lshl_add_u64 v[62:63], v[176:177], 0, s[38:39]
	v_lshl_add_u64 v[64:65], v[178:179], 0, s[38:39]
	v_mov_b32_dpp v140, v86 row_shr:1 row_mask:0xf bank_mask:0xf
	v_mov_b32_dpp v138, v86 row_shr:2 row_mask:0xf bank_mask:0xf
	v_mov_b32_dpp v141, v87 row_shr:1 row_mask:0xf bank_mask:0xf
	v_mov_b32_dpp v139, v87 row_shr:2 row_mask:0xf bank_mask:0xf
	v_mov_b32_dpp v146, v88 row_shr:1 row_mask:0xf bank_mask:0xf
	v_mov_b32_dpp v142, v88 row_shr:2 row_mask:0xf bank_mask:0xf
	v_mov_b32_dpp v147, v89 row_shr:1 row_mask:0xf bank_mask:0xf
	v_mov_b32_dpp v143, v89 row_shr:2 row_mask:0xf bank_mask:0xf
	v_pk_mul_f32 v[100:101], v[54:55], v[92:93] op_sel_hi:[1,0]
	v_pk_mul_f32 v[102:103], v[52:53], v[92:93] op_sel_hi:[1,0]
	s_nop 1
	v_mov_b32_dpp v132, v102 row_ror:1 row_mask:0xf bank_mask:0xf
	v_mov_b32_dpp v128, v102 row_ror:2 row_mask:0xf bank_mask:0xf
	v_mov_b32_dpp v133, v103 row_ror:1 row_mask:0xf bank_mask:0xf
	v_mov_b32_dpp v129, v103 row_ror:2 row_mask:0xf bank_mask:0xf
	v_mov_b32_dpp v144, v100 row_ror:1 row_mask:0xf bank_mask:0xf
	v_mov_b32_dpp v134, v100 row_ror:2 row_mask:0xf bank_mask:0xf
	v_mov_b32_dpp v145, v101 row_ror:1 row_mask:0xf bank_mask:0xf
	v_mov_b32_dpp v135, v101 row_ror:2 row_mask:0xf bank_mask:0xf
	v_mov_b32_dpp v132, v108 row_shr:1 row_mask:0xf bank_mask:0xf
	v_mov_b32_dpp v128, v108 row_shr:2 row_mask:0xf bank_mask:0xf
	v_mov_b32_dpp v133, v109 row_shr:1 row_mask:0xf bank_mask:0xf
	v_mov_b32_dpp v129, v109 row_shr:2 row_mask:0xf bank_mask:0xf
	v_mov_b32_dpp v144, v106 row_shr:1 row_mask:0xf bank_mask:0xf
	v_mov_b32_dpp v134, v106 row_shr:2 row_mask:0xf bank_mask:0xf
	v_mov_b32_dpp v145, v107 row_shr:1 row_mask:0xf bank_mask:0xf
	v_mov_b32_dpp v135, v107 row_shr:2 row_mask:0xf bank_mask:0xf
	v_mov_b32_e32 v66, v90
	v_mov_b32_e32 v67, v90
	v_pk_mul_f32 v[98:99], v[50:51], v[66:67]
	v_mov_b32_dpp v118, v84 row_ror:1 row_mask:0xf bank_mask:0xf
	v_mov_b32_dpp v116, v84 row_ror:2 row_mask:0xf bank_mask:0xf
	v_mov_b32_dpp v119, v85 row_ror:1 row_mask:0xf bank_mask:0xf
	v_mov_b32_dpp v117, v85 row_ror:2 row_mask:0xf bank_mask:0xf
	v_mov_b32_dpp v136, v98 row_ror:1 row_mask:0xf bank_mask:0xf
	v_mov_b32_dpp v120, v98 row_ror:2 row_mask:0xf bank_mask:0xf
	v_mov_b32_dpp v137, v99 row_ror:1 row_mask:0xf bank_mask:0xf
	v_mov_b32_dpp v121, v99 row_ror:2 row_mask:0xf bank_mask:0xf
	v_mov_b32_dpp v118, v102 row_shr:1 row_mask:0xf bank_mask:0xf
	v_mov_b32_dpp v116, v102 row_shr:2 row_mask:0xf bank_mask:0xf
	v_mov_b32_dpp v119, v103 row_shr:1 row_mask:0xf bank_mask:0xf
	v_mov_b32_dpp v117, v103 row_shr:2 row_mask:0xf bank_mask:0xf
	v_mov_b32_dpp v136, v100 row_shr:1 row_mask:0xf bank_mask:0xf
	v_mov_b32_dpp v120, v100 row_shr:2 row_mask:0xf bank_mask:0xf
	v_mov_b32_dpp v137, v101 row_shr:1 row_mask:0xf bank_mask:0xf
	v_mov_b32_dpp v121, v101 row_shr:2 row_mask:0xf bank_mask:0xf
	v_mov_b32_e32 v115, 0
	v_mov_b32_e32 v105, 0
	s_nop 0
	v_mov_b32_dpp v115, v115 row_ror:1 row_mask:0xf bank_mask:0xf
	v_mov_b32_dpp v105, v105 row_ror:2 row_mask:0xf bank_mask:0xf
	v_mov_b32_e32 v112, v115
	v_mov_b32_e32 v110, v105
	v_mov_b32_e32 v113, v115
	v_mov_b32_e32 v111, v105
	v_mov_b32_e32 v114, v115
	v_mov_b32_e32 v104, v105
	v_mov_b32_dpp v112, v84 row_shr:1 row_mask:0xf bank_mask:0xf
	v_mov_b32_dpp v110, v84 row_shr:2 row_mask:0xf bank_mask:0xf
	v_mov_b32_dpp v113, v85 row_shr:1 row_mask:0xf bank_mask:0xf
	v_mov_b32_dpp v111, v85 row_shr:2 row_mask:0xf bank_mask:0xf
	v_mov_b32_dpp v114, v98 row_shr:1 row_mask:0xf bank_mask:0xf
	v_mov_b32_dpp v104, v98 row_shr:2 row_mask:0xf bank_mask:0xf
	v_mov_b32_dpp v115, v99 row_shr:1 row_mask:0xf bank_mask:0xf
	v_mov_b32_dpp v105, v99 row_shr:2 row_mask:0xf bank_mask:0xf
	global_load_dwordx4 v[48:51], v[48:49], off
	s_nop 0
	global_load_dwordx4 v[52:55], v[60:61], off
	global_load_dwordx4 v[56:59], v[62:63], off
	s_nop 0
	global_load_dwordx4 v[60:63], v[64:65], off
	v_pk_mul_f32 v[64:65], v[32:33], v[90:91]
	s_and_saveexec_b64 s[58:59], s[12:13]
	s_cbranch_execz .LBB0_1014
	v_mov_b64_e32 v[32:33], s[26:27]
	v_mad_i64_i32 v[32:33], s[50:51], v149, s87, v[32:33]
	v_lshl_add_u64 v[32:33], v[170:171], 2, v[32:33]
	v_add_co_u32_e32 v32, vcc, 0x5000, v32
	v_pk_mul_f32 v[66:67], v[34:35], v[66:67]
	s_nop 0
	v_addc_co_u32_e32 v33, vcc, 0, v33, vcc
	global_store_dwordx4 v[32:33], v[64:67], off offset:2048

; __device__ __forceinline__ unsigned cvt_pk_bf16(float lo, float hi) { f32x2_cv v = {lo, hi}; bf16x2_cv b = __builtin_convertvector(v, bf16x2_cv); return __builtin_bit_cast(unsigned, b); }
; __device__ __forceinline__ float siluf_(float x) { return x * __builtin_amdgcn_rcpf(1.0f + __expf(-x)); }
;     __device__ __forceinline__ void operator()(const f32x4 (&acc)[2][2][4][2], const Unit& u, int wr, int wc, int fr, int fq) const {
;     ...
;                     for (int m = 3; m >= 0; --m) {
;                         const f32x4 cur = acc[ai][bj][m][n] * rs[m];
;                         f32x4 prev = zero4;
;                         if (m > 0) prev = acc[ai][bj][m - 1][n] * rs[m - 1];
;                         f32x4 r1, r2;
; #pragma unroll
;                         for (int i = 0; i < 4; ++i) {
;                             r1[i] = dpp_mov<0x111>(dpp_mov<0x121>(0.f, prev[i]), cur[i]);
;                             r2[i] = dpp_mov<0x112>(dpp_mov<0x122>(0.f, prev[i]), cur[i]); }
;                         const f32x4 cvv = wb + w2 * cur + w1 * r1 + w0 * r2;
;                         if (bj == 0) {
;                             sg[m].x = cvt_pk_bf16(siluf_(cvv[0]), siluf_(cvv[1])); sg[m].y = cvt_pk_bf16(siluf_(cvv[2]), siluf_(cvv[3]));
.LBB0_1016:
	s_or_b64 exec, exec, s[58:59]
	s_waitcnt vmcnt(4)
	v_pk_fma_f32 v[66:67], v[76:77], v[86:87], v[80:81]
	v_pk_fma_f32 v[32:33], v[78:79], v[88:89], v[82:83]
	v_pk_fma_f32 v[66:67], v[72:73], v[140:141], v[66:67]
	v_pk_fma_f32 v[32:33], v[74:75], v[146:147], v[32:33]
	v_pk_fma_f32 v[66:67], v[68:69], v[138:139], v[66:67]
	v_pk_fma_f32 v[32:33], v[70:71], v[142:143], v[32:33]
	v_mul_f32_e32 v86, 0xbfb8aa3b, v66
	v_mul_f32_e32 v87, 0xbfb8aa3b, v67
	v_exp_f32_e32 v86, v86
	v_exp_f32_e32 v87, v87
	v_mul_f32_e32 v88, 0xbfb8aa3b, v32
	v_mul_f32_e32 v89, 0xbfb8aa3b, v33
	v_exp_f32_e32 v88, v88
	v_exp_f32_e32 v89, v89
	v_add_f32_e32 v86, 1.0, v86
	v_add_f32_e32 v87, 1.0, v87
	v_rcp_f32_e32 v86, v86
	v_rcp_f32_e32 v87, v87
	v_add_f32_e32 v88, 1.0, v88
	v_add_f32_e32 v89, 1.0, v89
	v_rcp_f32_e32 v88, v88
	v_rcp_f32_e32 v89, v89
	v_pk_mul_f32 v[66:67], v[66:67], v[86:87]
	v_pk_fma_f32 v[86:87], v[108:109], v[76:77], v[80:81]
	v_cvt_pk_bf16_f32 v138, v66, v67
	v_pk_fma_f32 v[66:67], v[106:107], v[78:79], v[82:83]
	v_pk_fma_f32 v[86:87], v[72:73], v[132:133], v[86:87]
	v_pk_fma_f32 v[66:67], v[74:75], v[144:145], v[66:67]
	v_pk_fma_f32 v[86:87], v[68:69], v[128:129], v[86:87]
	v_pk_mul_f32 v[32:33], v[32:33], v[88:89]
	v_mul_f32_e32 v88, 0xbfb8aa3b, v86
	v_mul_f32_e32 v89, 0xbfb8aa3b, v87
	v_pk_fma_f32 v[66:67], v[70:71], v[134:135], v[66:67]
	v_exp_f32_e32 v88, v88
	v_exp_f32_e32 v89, v89
	v_mul_f32_e32 v106, 0xbfb8aa3b, v66
	v_mul_f32_e32 v107, 0xbfb8aa3b, v67
	v_exp_f32_e32 v106, v106
	v_exp_f32_e32 v107, v107
	v_add_f32_e32 v88, 1.0, v88
	v_add_f32_e32 v89, 1.0, v89
	v_rcp_f32_e32 v88, v88
	v_rcp_f32_e32 v89, v89
	v_add_f32_e32 v106, 1.0, v106
	v_add_f32_e32 v107, 1.0, v107
	v_rcp_f32_e32 v106, v106
	v_rcp_f32_e32 v107, v107
	v_cvt_pk_bf16_f32 v108, v32, v33
	v_pk_mul_f32 v[32:33], v[86:87], v[88:89]
	v_pk_fma_f32 v[86:87], v[102:103], v[76:77], v[80:81]
	v_cvt_pk_bf16_f32 v109, v32, v33
	v_pk_mul_f32 v[32:33], v[66:67], v[106:107]
	v_pk_fma_f32 v[66:67], v[100:101], v[78:79], v[82:83]
	v_pk_fma_f32 v[86:87], v[72:73], v[118:119], v[86:87]
	v_pk_fma_f32 v[66:67], v[74:75], v[136:137], v[66:67]
	v_pk_fma_f32 v[86:87], v[68:69], v[116:117], v[86:87]
	v_pk_fma_f32 v[66:67], v[70:71], v[120:121], v[66:67]
	v_mul_f32_e32 v88, 0xbfb8aa3b, v86
	v_mul_f32_e32 v89, 0xbfb8aa3b, v87
	v_exp_f32_e32 v88, v88
	v_exp_f32_e32 v89, v89
	v_mul_f32_e32 v100, 0xbfb8aa3b, v66
	v_mul_f32_e32 v101, 0xbfb8aa3b, v67
	v_exp_f32_e32 v100, v100
	v_exp_f32_e32 v101, v101
	v_add_f32_e32 v88, 1.0, v88
	v_add_f32_e32 v89, 1.0, v89
	v_rcp_f32_e32 v88, v88
	v_rcp_f32_e32 v89, v89
	v_add_f32_e32 v100, 1.0, v100
	v_add_f32_e32 v101, 1.0, v101
	v_pk_fma_f32 v[76:77], v[84:85], v[76:77], v[80:81]
	v_rcp_f32_e32 v100, v100
	v_rcp_f32_e32 v101, v101
	v_pk_fma_f32 v[72:73], v[72:73], v[112:113], v[76:77]
	v_cvt_pk_bf16_f32 v102, v32, v33
	v_pk_fma_f32 v[68:69], v[68:69], v[110:111], v[72:73]
	v_pk_mul_f32 v[32:33], v[86:87], v[88:89]
	v_mul_f32_e32 v72, 0xbfb8aa3b, v68
	v_mul_f32_e32 v73, 0xbfb8aa3b, v69
	v_exp_f32_e32 v72, v72
	v_exp_f32_e32 v73, v73
	v_cvt_pk_bf16_f32 v86, v32, v33
	v_pk_mul_f32 v[32:33], v[66:67], v[100:101]
	v_pk_fma_f32 v[66:67], v[98:99], v[78:79], v[82:83]
	v_mov_b32_e32 v95, v94
	v_pk_fma_f32 v[66:67], v[74:75], v[114:115], v[66:67]
	v_cvt_pk_bf16_f32 v74, v32, v33
	v_pk_fma_f32 v[66:67], v[70:71], v[104:105], v[66:67]
	v_add_f32_e32 v70, 1.0, v72
	v_add_f32_e32 v71, 1.0, v73
	v_mul_f32_e32 v72, 0xbfb8aa3b, v66
	v_mul_f32_e32 v73, 0xbfb8aa3b, v67
	v_exp_f32_e32 v72, v72
	v_exp_f32_e32 v73, v73
	v_rcp_f32_e32 v70, v70
	v_rcp_f32_e32 v71, v71
	v_add_f32_e32 v72, 1.0, v72
	v_add_f32_e32 v73, 1.0, v73
	v_rcp_f32_e32 v72, v72
	v_rcp_f32_e32 v73, v73
	v_pk_mul_f32 v[32:33], v[68:69], v[70:71]
	v_pk_mul_f32 v[40:41], v[40:41], v[94:95]
	v_cvt_pk_bf16_f32 v75, v32, v33
	v_pk_mul_f32 v[32:33], v[66:67], v[72:73]
	v_cvt_pk_bf16_f32 v72, v32, v33
	v_mov_b32_e32 v32, v94
	v_mov_b32_e32 v33, v94
	v_pk_mul_f32 v[32:33], v[42:43], v[32:33]
	v_mov_b32_dpp v42, v40 row_ror:1 row_mask:0xf bank_mask:0xf
	v_mov_b32_dpp v66, v40 row_ror:2 row_mask:0xf bank_mask:0xf
	v_mov_b32_dpp v43, v41 row_ror:1 row_mask:0xf bank_mask:0xf
	v_mov_b32_dpp v67, v41 row_ror:2 row_mask:0xf bank_mask:0xf
	v_mov_b32_dpp v68, v32 row_ror:1 row_mask:0xf bank_mask:0xf
	v_mov_b32_dpp v70, v32 row_ror:2 row_mask:0xf bank_mask:0xf
	v_mov_b32_dpp v69, v33 row_ror:1 row_mask:0xf bank_mask:0xf
	v_mov_b32_dpp v71, v33 row_ror:2 row_mask:0xf bank_mask:0xf
	v_mov_b32_dpp v42, v44 row_shr:1 row_mask:0xf bank_mask:0xf
	v_mov_b32_dpp v66, v44 row_shr:2 row_mask:0xf bank_mask:0xf
	v_mov_b32_dpp v43, v45 row_shr:1 row_mask:0xf bank_mask:0xf
	v_mov_b32_dpp v67, v45 row_shr:2 row_mask:0xf bank_mask:0xf
	v_mov_b32_dpp v68, v46 row_shr:1 row_mask:0xf bank_mask:0xf
	v_mov_b32_dpp v70, v46 row_shr:2 row_mask:0xf bank_mask:0xf
	v_mov_b32_dpp v69, v47 row_shr:1 row_mask:0xf bank_mask:0xf
	v_mov_b32_dpp v71, v47 row_shr:2 row_mask:0xf bank_mask:0xf
	s_waitcnt vmcnt(0)
; __device__ __forceinline__ unsigned cvt_pk_bf16(float lo, float hi) { f32x2_cv v = {lo, hi}; bf16x2_cv b = __builtin_convertvector(v, bf16x2_cv); return __builtin_bit_cast(unsigned, b); }
; __device__ __forceinline__ float siluf_(float x) { return x * __builtin_amdgcn_rcpf(1.0f + __expf(-x)); }
;     __device__ __forceinline__ void operator()(const f32x4 (&acc)[2][2][4][2], const Unit& u, int wr, int wc, int fr, int fq) const {
;     ...
;                     for (int m = 3; m >= 0; --m) {
;                         const f32x4 cur = acc[ai][bj][m][n] * rs[m];
;                         f32x4 prev = zero4;
;                         if (m > 0) prev = acc[ai][bj][m - 1][n] * rs[m - 1];
;                         f32x4 r1, r2;
; #pragma unroll
;                         for (int i = 0; i < 4; ++i) {
;                             r1[i] = dpp_mov<0x111>(dpp_mov<0x121>(0.f, prev[i]), cur[i]);
;                             r2[i] = dpp_mov<0x112>(dpp_mov<0x122>(0.f, prev[i]), cur[i]); }
;                         const f32x4 cvv = wb + w2 * cur + w1 * r1 + w0 * r2;
;                         if (bj == 0) {
;                             sg[m].x = cvt_pk_bf16(siluf_(cvv[0]), siluf_(cvv[1])); sg[m].y = cvt_pk_bf16(siluf_(cvv[2]), siluf_(cvv[3]));
;                         } else {
;                             f32x4 h;
;                             h[0] = __uint_as_float(sg[m].x << 16) * cvv[0]; h[1] = __uint_as_float(sg[m].x & 0xffff0000u) * cvv[1];
;                             h[2] = __uint_as_float(sg[m].y << 16) * cvv[2]; h[3] = __uint_as_float(sg[m].y & 0xffff0000u) * cvv[3];
;                             u32x2v w; w.x = cvt_pk_bf16(h[0], h[1]); w.y = cvt_pk_bf16(h[2], h[3]);
;                             *(u32x2v*)(H + (size_t)(rowb + m * 16 + fr) * dff + cg) = w;
;                         }
	v_pk_fma_f32 v[46:47], v[46:47], v[58:59], v[62:63]
	v_pk_fma_f32 v[44:45], v[44:45], v[56:57], v[60:61]
	v_pk_fma_f32 v[46:47], v[54:55], v[68:69], v[46:47]
	v_pk_fma_f32 v[42:43], v[52:53], v[42:43], v[44:45]
	v_pk_fma_f32 v[44:45], v[50:51], v[70:71], v[46:47]
	v_pk_fma_f32 v[42:43], v[48:49], v[66:67], v[42:43]
	v_lshlrev_b32_e32 v46, 16, v138
	v_and_b32_e32 v47, 0xffff0000, v138
	v_pk_mul_f32 v[42:43], v[42:43], v[46:47]
	v_lshlrev_b32_e32 v46, 16, v108
	v_and_b32_e32 v47, 0xffff0000, v108
	v_or_b32_e32 v73, s43, v236
	v_pk_mul_f32 v[44:45], v[44:45], v[46:47]
	v_cvt_pk_bf16_f32 v42, v42, v43
	v_cvt_pk_bf16_f32 v43, v44, v45
	v_or_b32_e32 v46, 48, v73
	v_mov_b64_e32 v[44:45], s[24:25]
	v_mad_i64_i32 v[46:47], s[50:51], v46, s89, v[44:45]
	v_mov_b32_e32 v93, v92
	v_lshl_add_u64 v[66:67], v[46:47], 0, v[130:131]
	global_store_dwordx2 v[66:67], v[42:43], off
	v_mov_b32_e32 v42, v92
	v_mov_b32_e32 v43, v92
	v_pk_mul_f32 v[38:39], v[38:39], v[42:43]
	v_pk_mul_f32 v[36:37], v[36:37], v[92:93]
	s_nop 1
	v_mov_b32_dpp v42, v36 row_ror:1 row_mask:0xf bank_mask:0xf
	v_mov_b32_dpp v46, v36 row_ror:2 row_mask:0xf bank_mask:0xf
	v_mov_b32_dpp v43, v37 row_ror:1 row_mask:0xf bank_mask:0xf
	v_mov_b32_dpp v47, v37 row_ror:2 row_mask:0xf bank_mask:0xf
	v_mov_b32_dpp v42, v40 row_shr:1 row_mask:0xf bank_mask:0xf
	v_mov_b32_dpp v46, v40 row_shr:2 row_mask:0xf bank_mask:0xf
	v_mov_b32_dpp v43, v41 row_shr:1 row_mask:0xf bank_mask:0xf
	v_mov_b32_dpp v47, v41 row_shr:2 row_mask:0xf bank_mask:0xf
	v_mov_b32_dpp v68, v38 row_ror:1 row_mask:0xf bank_mask:0xf
	v_mov_b32_dpp v70, v38 row_ror:2 row_mask:0xf bank_mask:0xf
	v_mov_b32_dpp v69, v39 row_ror:1 row_mask:0xf bank_mask:0xf
	v_mov_b32_dpp v71, v39 row_ror:2 row_mask:0xf bank_mask:0xf
	v_pk_fma_f32 v[40:41], v[40:41], v[56:57], v[60:61]
	v_mov_b32_dpp v68, v32 row_shr:1 row_mask:0xf bank_mask:0xf
	v_mov_b32_dpp v70, v32 row_shr:2 row_mask:0xf bank_mask:0xf
	v_mov_b32_dpp v69, v33 row_shr:1 row_mask:0xf bank_mask:0xf
	v_mov_b32_dpp v71, v33 row_shr:2 row_mask:0xf bank_mask:0xf
	v_pk_fma_f32 v[32:33], v[32:33], v[58:59], v[62:63]
	v_pk_fma_f32 v[40:41], v[52:53], v[42:43], v[40:41]
	v_pk_fma_f32 v[32:33], v[54:55], v[68:69], v[32:33]
	v_pk_fma_f32 v[40:41], v[48:49], v[46:47], v[40:41]
	v_lshlrev_b32_e32 v42, 16, v109
	v_and_b32_e32 v43, 0xffff0000, v109
	v_pk_fma_f32 v[32:33], v[50:51], v[70:71], v[32:33]
	v_pk_mul_f32 v[40:41], v[40:41], v[42:43]
	v_lshlrev_b32_e32 v42, 16, v102
	v_and_b32_e32 v43, 0xffff0000, v102
	v_pk_mul_f32 v[32:33], v[32:33], v[42:43]
	v_cvt_pk_bf16_f32 v40, v40, v41
	v_cvt_pk_bf16_f32 v41, v32, v33
	v_or_b32_e32 v32, 32, v73
	v_mad_i64_i32 v[32:33], s[50:51], v32, s89, v[44:45]
	v_lshl_add_u64 v[68:69], v[32:33], 0, v[130:131]
	global_store_dwordx2 v[68:69], v[40:41], off
	v_mov_b32_e32 v32, v90
	v_mov_b32_e32 v33, v90
	v_pk_mul_f32 v[34:35], v[34:35], v[32:33]
	v_mov_b32_dpp v40, v64 row_ror:1 row_mask:0xf bank_mask:0xf
	v_mov_b32_dpp v42, v64 row_ror:2 row_mask:0xf bank_mask:0xf
	v_mov_b32_dpp v41, v65 row_ror:1 row_mask:0xf bank_mask:0xf
	v_mov_b32_dpp v43, v65 row_ror:2 row_mask:0xf bank_mask:0xf
	v_mov_b32_dpp v40, v36 row_shr:1 row_mask:0xf bank_mask:0xf
	v_mov_b32_dpp v42, v36 row_shr:2 row_mask:0xf bank_mask:0xf
	v_mov_b32_dpp v41, v37 row_shr:1 row_mask:0xf bank_mask:0xf
	v_mov_b32_dpp v43, v37 row_shr:2 row_mask:0xf bank_mask:0xf
	v_mov_b32_dpp v46, v34 row_ror:1 row_mask:0xf bank_mask:0xf
	v_mov_b32_dpp v70, v34 row_ror:2 row_mask:0xf bank_mask:0xf
	v_mov_b32_dpp v47, v35 row_ror:1 row_mask:0xf bank_mask:0xf
	v_mov_b32_dpp v71, v35 row_ror:2 row_mask:0xf bank_mask:0xf
	v_pk_fma_f32 v[36:37], v[36:37], v[56:57], v[60:61]
	v_mov_b32_dpp v46, v38 row_shr:1 row_mask:0xf bank_mask:0xf
	v_mov_b32_dpp v70, v38 row_shr:2 row_mask:0xf bank_mask:0xf
	v_mov_b32_dpp v47, v39 row_shr:1 row_mask:0xf bank_mask:0xf
	v_mov_b32_dpp v71, v39 row_shr:2 row_mask:0xf bank_mask:0xf
	v_pk_fma_f32 v[38:39], v[38:39], v[58:59], v[62:63]
	v_pk_fma_f32 v[36:37], v[52:53], v[40:41], v[36:37]
	v_pk_fma_f32 v[38:39], v[54:55], v[46:47], v[38:39]
	v_pk_fma_f32 v[36:37], v[48:49], v[42:43], v[36:37]
	v_lshlrev_b32_e32 v40, 16, v86
	v_and_b32_e32 v41, 0xffff0000, v86
	v_pk_fma_f32 v[38:39], v[50:51], v[70:71], v[38:39]
	v_pk_mul_f32 v[36:37], v[36:37], v[40:41]
	v_lshlrev_b32_e32 v40, 16, v74
	v_and_b32_e32 v41, 0xffff0000, v74
	v_pk_mul_f32 v[38:39], v[38:39], v[40:41]
	v_cvt_pk_bf16_f32 v36, v36, v37
	v_cvt_pk_bf16_f32 v37, v38, v39
	v_or_b32_e32 v38, 16, v73
	v_mad_i64_i32 v[38:39], s[50:51], v38, s89, v[44:45]
	v_lshl_add_u64 v[70:71], v[38:39], 0, v[130:131]
	global_store_dwordx2 v[70:71], v[36:37], off
	v_mov_b32_e32 v37, 0
	v_mov_b32_e32 v41, 0
	v_pk_fma_f32 v[46:47], v[64:65], v[56:57], v[60:61]
	v_mov_b32_dpp v37, v37 row_ror:1 row_mask:0xf bank_mask:0xf
	v_mov_b32_dpp v41, v41 row_ror:2 row_mask:0xf bank_mask:0xf
	v_mov_b32_e32 v38, v37
	v_mov_b32_e32 v39, v37
	v_mov_b32_e32 v36, v37
	v_mov_b32_e32 v40, v41
	v_mov_b32_dpp v38, v64 row_shr:1 row_mask:0xf bank_mask:0xf
	v_mov_b32_e32 v42, v41
	v_mov_b32_dpp v39, v65 row_shr:1 row_mask:0xf bank_mask:0xf
	v_mov_b32_e32 v43, v41
	v_mov_b32_dpp v36, v34 row_shr:1 row_mask:0xf bank_mask:0xf
	v_mov_b32_dpp v40, v34 row_shr:2 row_mask:0xf bank_mask:0xf
	v_mov_b32_dpp v37, v35 row_shr:1 row_mask:0xf bank_mask:0xf
	v_mov_b32_dpp v41, v35 row_shr:2 row_mask:0xf bank_mask:0xf
	v_pk_fma_f32 v[34:35], v[34:35], v[58:59], v[62:63]
	v_mov_b32_dpp v42, v64 row_shr:2 row_mask:0xf bank_mask:0xf
	v_mov_b32_dpp v43, v65 row_shr:2 row_mask:0xf bank_mask:0xf
	v_pk_fma_f32 v[34:35], v[54:55], v[36:37], v[34:35]
	v_pk_fma_f32 v[36:37], v[52:53], v[38:39], v[46:47]
	v_lshlrev_b32_e32 v38, 16, v75
	v_pk_fma_f32 v[36:37], v[48:49], v[42:43], v[36:37]
	v_and_b32_e32 v39, 0xffff0000, v75
	v_pk_fma_f32 v[34:35], v[50:51], v[40:41], v[34:35]
	v_pk_mul_f32 v[36:37], v[36:37], v[38:39]
	v_lshlrev_b32_e32 v38, 16, v72
	v_and_b32_e32 v39, 0xffff0000, v72
	v_pk_mul_f32 v[34:35], v[34:35], v[38:39]
	v_cvt_pk_bf16_f32 v36, v36, v37
	v_cvt_pk_bf16_f32 v37, v34, v35
	v_mad_i64_i32 v[34:35], s[50:51], v73, s89, v[44:45]
	v_lshl_add_u64 v[60:61], v[34:35], 0, v[130:131]
	global_store_dwordx2 v[60:61], v[36:37], off
	global_load_dwordx4 v[36:39], v[172:173], off offset:16
	global_load_dwordx4 v[40:43], v[124:125], off
	global_load_dwordx4 v[44:47], v[126:127], off
	global_load_dwordx4 v[48:51], v[178:179], off offset:16
	v_pk_mul_f32 v[56:57], v[16:17], v[90:91]
	s_and_saveexec_b64 s[58:59], s[12:13]
	s_cbranch_execz .LBB0_1018
	v_mov_b64_e32 v[16:17], s[26:27]
	v_mad_i64_i32 v[16:17], s[50:51], v149, s87, v[16:17]
	v_pk_mul_f32 v[58:59], v[18:19], v[32:33]
	v_lshl_add_u64 v[16:17], v[170:171], 2, v[16:17]
	global_store_dwordx4 v[16:17], v[56:59], off offset:16

;     __device__ __forceinline__ void operator()(const f32x4 (&acc)[2][2][4][2], const Unit& u, int wr, int wc, int fr, int fq) const {
;     ...
;                 for (int bj = 0; bj < 2; ++bj) {
;                     const int col = bj * dff + cg;
;                     const f32x4 w0 = *(const f32x4*)(cw + col), w1 = *(const f32x4*)(cw + 2 * dff + col), w2 = *(const f32x4*)(cw + 4 * dff + col), wb = *(const f32x4*)(cb + col);
;                     if (fr < 2) *(f32x4*)(RB + ((size_t)(blk * 4 + fr) * 2 + bj) * dff + cg) = acc[ai][bj][0][n] * rs[0];
;                     if (fr >= 14) *(f32x4*)(RB + ((size_t)(blk * 4 + fr - 12) * 2 + bj) * dff + cg) = acc[ai][bj][3][n] * rs[3];
; #pragma unroll
;                     for (int m = 3; m >= 0; --m) {
;                         const f32x4 cur = acc[ai][bj][m][n] * rs[m];
;                         f32x4 prev = zero4;
;                         if (m > 0) prev = acc[ai][bj][m - 1][n] * rs[m - 1];
;                         f32x4 r1, r2;
; #pragma unroll
;                         for (int i = 0; i < 4; ++i) {
;                             r1[i] = dpp_mov<0x111>(dpp_mov<0x121>(0.f, prev[i]), cur[i]);
;                             r2[i] = dpp_mov<0x112>(dpp_mov<0x122>(0.f, prev[i]), cur[i]); }
.LBB0_1020:
	s_or_b64 exec, exec, s[58:59]
	v_mov_b32_e32 v34, v94
	v_mov_b32_e32 v35, v94
	v_pk_mul_f32 v[74:75], v[26:27], v[34:35]
	v_pk_mul_f32 v[76:77], v[24:25], v[94:95]
	s_nop 1
	v_mov_b32_dpp v62, v76 row_ror:1 row_mask:0xf bank_mask:0xf
	v_mov_b32_dpp v58, v76 row_ror:2 row_mask:0xf bank_mask:0xf
	v_mov_b32_dpp v63, v77 row_ror:1 row_mask:0xf bank_mask:0xf
	v_mov_b32_dpp v59, v77 row_ror:2 row_mask:0xf bank_mask:0xf
	v_mov_b32_dpp v72, v74 row_ror:1 row_mask:0xf bank_mask:0xf
	v_mov_b32_dpp v64, v74 row_ror:2 row_mask:0xf bank_mask:0xf
	v_mov_b32_dpp v73, v75 row_ror:1 row_mask:0xf bank_mask:0xf
	v_mov_b32_dpp v65, v75 row_ror:2 row_mask:0xf bank_mask:0xf
	v_lshl_add_u64 v[16:17], v[172:173], 0, s[40:41]
	v_lshl_add_u64 v[28:29], v[174:175], 0, s[40:41]
	v_lshl_add_u64 v[30:31], v[176:177], 0, s[40:41]
	v_lshl_add_u64 v[32:33], v[178:179], 0, s[40:41]
	v_mov_b32_dpp v62, v52 row_shr:1 row_mask:0xf bank_mask:0xf
	v_mov_b32_dpp v58, v52 row_shr:2 row_mask:0xf bank_mask:0xf
	v_mov_b32_dpp v63, v53 row_shr:1 row_mask:0xf bank_mask:0xf
	v_mov_b32_dpp v59, v53 row_shr:2 row_mask:0xf bank_mask:0xf
	v_mov_b32_dpp v72, v54 row_shr:1 row_mask:0xf bank_mask:0xf
	v_mov_b32_dpp v64, v54 row_shr:2 row_mask:0xf bank_mask:0xf
	v_mov_b32_dpp v73, v55 row_shr:1 row_mask:0xf bank_mask:0xf
	v_mov_b32_dpp v65, v55 row_shr:2 row_mask:0xf bank_mask:0xf
	v_mov_b32_e32 v24, v92
	v_mov_b32_e32 v25, v92
	v_pk_mul_f32 v[86:87], v[22:23], v[24:25]
	v_pk_mul_f32 v[88:89], v[20:21], v[92:93]
	s_nop 1
	v_mov_b32_dpp v80, v88 row_ror:1 row_mask:0xf bank_mask:0xf
	v_mov_b32_dpp v78, v88 row_ror:2 row_mask:0xf bank_mask:0xf
	v_mov_b32_dpp v81, v89 row_ror:1 row_mask:0xf bank_mask:0xf
	v_mov_b32_dpp v79, v89 row_ror:2 row_mask:0xf bank_mask:0xf
	v_mov_b32_dpp v84, v86 row_ror:1 row_mask:0xf bank_mask:0xf
	v_mov_b32_dpp v82, v86 row_ror:2 row_mask:0xf bank_mask:0xf
	v_mov_b32_dpp v85, v87 row_ror:1 row_mask:0xf bank_mask:0xf
	v_mov_b32_dpp v83, v87 row_ror:2 row_mask:0xf bank_mask:0xf
	v_mov_b32_dpp v80, v76 row_shr:1 row_mask:0xf bank_mask:0xf
	v_mov_b32_dpp v78, v76 row_shr:2 row_mask:0xf bank_mask:0xf
	v_mov_b32_dpp v81, v77 row_shr:1 row_mask:0xf bank_mask:0xf
	v_mov_b32_dpp v79, v77 row_shr:2 row_mask:0xf bank_mask:0xf
	v_mov_b32_dpp v84, v74 row_shr:1 row_mask:0xf bank_mask:0xf
	v_mov_b32_dpp v82, v74 row_shr:2 row_mask:0xf bank_mask:0xf
	v_mov_b32_dpp v85, v75 row_shr:1 row_mask:0xf bank_mask:0xf
	v_mov_b32_dpp v83, v75 row_shr:2 row_mask:0xf bank_mask:0xf
	v_mov_b32_e32 v34, v90
	v_mov_b32_e32 v35, v90
	v_pk_mul_f32 v[106:107], v[18:19], v[34:35]
	v_mov_b32_dpp v100, v56 row_ror:1 row_mask:0xf bank_mask:0xf
	v_mov_b32_dpp v98, v56 row_ror:2 row_mask:0xf bank_mask:0xf
	v_mov_b32_dpp v101, v57 row_ror:1 row_mask:0xf bank_mask:0xf
	v_mov_b32_dpp v99, v57 row_ror:2 row_mask:0xf bank_mask:0xf
	v_mov_b32_dpp v104, v106 row_ror:1 row_mask:0xf bank_mask:0xf
	v_mov_b32_dpp v102, v106 row_ror:2 row_mask:0xf bank_mask:0xf
	v_mov_b32_dpp v105, v107 row_ror:1 row_mask:0xf bank_mask:0xf
	v_mov_b32_dpp v103, v107 row_ror:2 row_mask:0xf bank_mask:0xf
	v_mov_b32_dpp v100, v88 row_shr:1 row_mask:0xf bank_mask:0xf
	v_mov_b32_dpp v98, v88 row_shr:2 row_mask:0xf bank_mask:0xf
	v_mov_b32_dpp v101, v89 row_shr:1 row_mask:0xf bank_mask:0xf
	v_mov_b32_dpp v99, v89 row_shr:2 row_mask:0xf bank_mask:0xf
	v_mov_b32_dpp v104, v86 row_shr:1 row_mask:0xf bank_mask:0xf
	v_mov_b32_dpp v102, v86 row_shr:2 row_mask:0xf bank_mask:0xf
	v_mov_b32_dpp v105, v87 row_shr:1 row_mask:0xf bank_mask:0xf
	v_mov_b32_dpp v103, v87 row_shr:2 row_mask:0xf bank_mask:0xf
	v_mov_b32_e32 v115, 0
	v_mov_b32_e32 v111, 0
	s_nop 0
	v_mov_b32_dpp v115, v115 row_ror:1 row_mask:0xf bank_mask:0xf
	v_mov_b32_dpp v111, v111 row_ror:2 row_mask:0xf bank_mask:0xf
	v_mov_b32_e32 v112, v115
	v_mov_b32_e32 v108, v111
	v_mov_b32_e32 v113, v115
	v_mov_b32_e32 v109, v111
	v_mov_b32_e32 v114, v115
	v_mov_b32_e32 v110, v111
	v_mov_b32_dpp v112, v56 row_shr:1 row_mask:0xf bank_mask:0xf
	v_mov_b32_dpp v108, v56 row_shr:2 row_mask:0xf bank_mask:0xf
	v_mov_b32_dpp v113, v57 row_shr:1 row_mask:0xf bank_mask:0xf
	v_mov_b32_dpp v109, v57 row_shr:2 row_mask:0xf bank_mask:0xf
	v_mov_b32_dpp v114, v106 row_shr:1 row_mask:0xf bank_mask:0xf
	v_mov_b32_dpp v110, v106 row_shr:2 row_mask:0xf bank_mask:0xf
	v_mov_b32_dpp v115, v107 row_shr:1 row_mask:0xf bank_mask:0xf
	v_mov_b32_dpp v111, v107 row_shr:2 row_mask:0xf bank_mask:0xf
	global_load_dwordx4 v[16:19], v[16:17], off
	s_nop 0
	global_load_dwordx4 v[20:23], v[28:29], off
	global_load_dwordx4 v[24:27], v[30:31], off
	s_nop 0
	global_load_dwordx4 v[28:31], v[32:33], off
	v_pk_mul_f32 v[32:33], v[0:1], v[90:91]
	s_and_saveexec_b64 s[58:59], s[12:13]
	s_cbranch_execz .LBB0_1022
	v_mov_b64_e32 v[0:1], s[26:27]
	v_mad_i64_i32 v[0:1], s[50:51], v149, s87, v[0:1]
	v_lshl_add_u64 v[0:1], v[122:123], 2, v[0:1]
	v_add_co_u32_e32 v0, vcc, 0x5000, v0
	v_pk_mul_f32 v[34:35], v[2:3], v[34:35]
	s_nop 0
	v_addc_co_u32_e32 v1, vcc, 0, v1, vcc
	global_store_dwordx4 v[0:1], v[32:35], off offset:2048

; __device__ __forceinline__ unsigned cvt_pk_bf16(float lo, float hi) { f32x2_cv v = {lo, hi}; bf16x2_cv b = __builtin_convertvector(v, bf16x2_cv); return __builtin_bit_cast(unsigned, b); }
; __device__ __forceinline__ float siluf_(float x) { return x * __builtin_amdgcn_rcpf(1.0f + __expf(-x)); }
;     __device__ __forceinline__ void operator()(const f32x4 (&acc)[2][2][4][2], const Unit& u, int wr, int wc, int fr, int fq) const {
;     ...
;                     for (int m = 3; m >= 0; --m) {
;                         const f32x4 cur = acc[ai][bj][m][n] * rs[m];
;                         f32x4 prev = zero4;
;                         if (m > 0) prev = acc[ai][bj][m - 1][n] * rs[m - 1];
;                         f32x4 r1, r2;
; #pragma unroll
;                         for (int i = 0; i < 4; ++i) {
;                             r1[i] = dpp_mov<0x111>(dpp_mov<0x121>(0.f, prev[i]), cur[i]);
;                             r2[i] = dpp_mov<0x112>(dpp_mov<0x122>(0.f, prev[i]), cur[i]); }
;                         const f32x4 cvv = wb + w2 * cur + w1 * r1 + w0 * r2;
;                         if (bj == 0) {
;                             sg[m].x = cvt_pk_bf16(siluf_(cvv[0]), siluf_(cvv[1])); sg[m].y = cvt_pk_bf16(siluf_(cvv[2]), siluf_(cvv[3]));
.LBB0_1024:
	s_or_b64 exec, exec, s[58:59]
	s_waitcnt vmcnt(4)
	v_pk_fma_f32 v[0:1], v[106:107], v[46:47], v[50:51]
	v_pk_fma_f32 v[34:35], v[56:57], v[44:45], v[48:49]
	v_pk_fma_f32 v[0:1], v[42:43], v[114:115], v[0:1]
	v_pk_fma_f32 v[34:35], v[40:41], v[112:113], v[34:35]
	v_pk_fma_f32 v[0:1], v[38:39], v[110:111], v[0:1]
	v_pk_fma_f32 v[34:35], v[36:37], v[108:109], v[34:35]
	v_mul_f32_e32 v56, 0xbfb8aa3b, v0
	v_mul_f32_e32 v57, 0xbfb8aa3b, v1
	v_mul_f32_e32 v91, 0xbfb8aa3b, v34
	v_exp_f32_e32 v56, v56
	v_exp_f32_e32 v57, v57
	v_exp_f32_e32 v91, v91
	v_mul_f32_e32 v96, 0xbfb8aa3b, v35
	v_exp_f32_e32 v97, v96
	v_add_f32_e32 v56, 1.0, v56
	v_add_f32_e32 v57, 1.0, v57
	v_add_f32_e32 v91, 1.0, v91
	v_rcp_f32_e32 v56, v56
	v_rcp_f32_e32 v57, v57
	v_rcp_f32_e32 v96, v91
	v_add_f32_e32 v91, 1.0, v97
	v_rcp_f32_e32 v97, v91
	v_pk_mul_f32 v[0:1], v[0:1], v[56:57]
	v_pk_fma_f32 v[56:57], v[88:89], v[44:45], v[48:49]
	v_cvt_pk_bf16_f32 v106, v0, v1
	v_pk_mul_f32 v[0:1], v[34:35], v[96:97]
	v_pk_fma_f32 v[34:35], v[86:87], v[46:47], v[50:51]
	v_pk_fma_f32 v[56:57], v[40:41], v[100:101], v[56:57]
	v_pk_fma_f32 v[34:35], v[42:43], v[104:105], v[34:35]
	v_pk_fma_f32 v[56:57], v[36:37], v[98:99], v[56:57]
	v_pk_fma_f32 v[34:35], v[38:39], v[102:103], v[34:35]
	v_cvt_pk_bf16_f32 v96, v0, v1
	v_mul_f32_e32 v86, 0xbfb8aa3b, v34
	v_mul_f32_e32 v87, 0xbfb8aa3b, v35
	v_exp_f32_e32 v86, v86
	v_exp_f32_e32 v87, v87
	v_mul_f32_e32 v88, 0xbfb8aa3b, v56
	v_mul_f32_e32 v89, 0xbfb8aa3b, v57
	v_add_f32_e32 v86, 1.0, v86
	v_add_f32_e32 v87, 1.0, v87
	v_rcp_f32_e32 v86, v86
	v_rcp_f32_e32 v87, v87
	v_exp_f32_e32 v88, v88
	v_exp_f32_e32 v89, v89
	v_pk_mul_f32 v[8:9], v[8:9], v[94:95]
	v_pk_mul_f32 v[0:1], v[34:35], v[86:87]
	v_pk_fma_f32 v[34:35], v[74:75], v[46:47], v[50:51]
	v_add_f32_e32 v88, 1.0, v88
	v_pk_fma_f32 v[34:35], v[42:43], v[84:85], v[34:35]
	v_add_f32_e32 v89, 1.0, v89
	v_pk_fma_f32 v[34:35], v[38:39], v[82:83], v[34:35]
	v_rcp_f32_e32 v88, v88
	v_mul_f32_e32 v74, 0xbfb8aa3b, v34
	v_mul_f32_e32 v75, 0xbfb8aa3b, v35
	v_exp_f32_e32 v74, v74
	v_exp_f32_e32 v75, v75
	v_rcp_f32_e32 v89, v89
	v_cvt_pk_bf16_f32 v86, v0, v1
	v_add_f32_e32 v74, 1.0, v74
	v_add_f32_e32 v75, 1.0, v75
	v_rcp_f32_e32 v74, v74
	v_rcp_f32_e32 v75, v75
	v_pk_mul_f32 v[0:1], v[56:57], v[88:89]
	v_pk_fma_f32 v[56:57], v[76:77], v[44:45], v[48:49]
	v_pk_fma_f32 v[44:45], v[52:53], v[44:45], v[48:49]
	v_pk_fma_f32 v[56:57], v[40:41], v[80:81], v[56:57]
	v_pk_fma_f32 v[40:41], v[40:41], v[62:63], v[44:45]
	v_pk_fma_f32 v[56:57], v[36:37], v[78:79], v[56:57]
	v_cvt_pk_bf16_f32 v78, v0, v1
	v_pk_mul_f32 v[0:1], v[34:35], v[74:75]
	v_pk_fma_f32 v[34:35], v[54:55], v[46:47], v[50:51]
	v_mul_f32_e32 v76, 0xbfb8aa3b, v56
	v_pk_fma_f32 v[34:35], v[42:43], v[72:73], v[34:35]
	v_mul_f32_e32 v77, 0xbfb8aa3b, v57
	v_pk_fma_f32 v[34:35], v[38:39], v[64:65], v[34:35]
	v_exp_f32_e32 v76, v76
	v_exp_f32_e32 v77, v77
	v_mul_f32_e32 v38, 0xbfb8aa3b, v34
	v_mul_f32_e32 v39, 0xbfb8aa3b, v35
	v_pk_fma_f32 v[36:37], v[36:37], v[58:59], v[40:41]
	v_exp_f32_e32 v38, v38
	v_exp_f32_e32 v39, v39
	v_mul_f32_e32 v40, 0xbfb8aa3b, v36
	v_mul_f32_e32 v41, 0xbfb8aa3b, v37
	v_exp_f32_e32 v40, v40
	v_exp_f32_e32 v41, v41
	v_add_f32_e32 v76, 1.0, v76
	v_add_f32_e32 v77, 1.0, v77
	v_rcp_f32_e32 v76, v76
	v_rcp_f32_e32 v77, v77
	v_add_f32_e32 v38, 1.0, v38
	v_add_f32_e32 v39, 1.0, v39
	v_rcp_f32_e32 v38, v38
	v_rcp_f32_e32 v39, v39
	v_add_f32_e32 v40, 1.0, v40
	v_add_f32_e32 v41, 1.0, v41
	v_rcp_f32_e32 v40, v40
	v_rcp_f32_e32 v41, v41
	v_cvt_pk_bf16_f32 v74, v0, v1
	v_pk_mul_f32 v[0:1], v[56:57], v[76:77]
	s_nop 0
	v_cvt_pk_bf16_f32 v42, v0, v1
	v_pk_mul_f32 v[0:1], v[34:35], v[38:39]
	v_cvt_pk_bf16_f32 v43, v0, v1
	v_pk_mul_f32 v[0:1], v[36:37], v[40:41]
	v_cvt_pk_bf16_f32 v40, v0, v1
	v_mov_b32_e32 v0, v94
	v_mov_b32_e32 v1, v94
	v_pk_mul_f32 v[0:1], v[10:11], v[0:1]
	v_mov_b32_dpp v10, v8 row_ror:1 row_mask:0xf bank_mask:0xf
	v_mov_b32_dpp v34, v8 row_ror:2 row_mask:0xf bank_mask:0xf
	v_mov_b32_dpp v11, v9 row_ror:1 row_mask:0xf bank_mask:0xf
	v_mov_b32_dpp v35, v9 row_ror:2 row_mask:0xf bank_mask:0xf
	v_mov_b32_dpp v36, v0 row_ror:1 row_mask:0xf bank_mask:0xf
	v_mov_b32_dpp v38, v0 row_ror:2 row_mask:0xf bank_mask:0xf
	v_mov_b32_dpp v37, v1 row_ror:1 row_mask:0xf bank_mask:0xf
	v_mov_b32_dpp v39, v1 row_ror:2 row_mask:0xf bank_mask:0xf
	v_mov_b32_dpp v10, v12 row_shr:1 row_mask:0xf bank_mask:0xf
	v_mov_b32_dpp v34, v12 row_shr:2 row_mask:0xf bank_mask:0xf
	v_mov_b32_dpp v11, v13 row_shr:1 row_mask:0xf bank_mask:0xf
	v_mov_b32_dpp v35, v13 row_shr:2 row_mask:0xf bank_mask:0xf
	v_mov_b32_dpp v36, v14 row_shr:1 row_mask:0xf bank_mask:0xf
	v_mov_b32_dpp v38, v14 row_shr:2 row_mask:0xf bank_mask:0xf
	v_mov_b32_dpp v37, v15 row_shr:1 row_mask:0xf bank_mask:0xf
	v_mov_b32_dpp v39, v15 row_shr:2 row_mask:0xf bank_mask:0xf
	s_waitcnt vmcnt(0)
; __device__ __forceinline__ unsigned cvt_pk_bf16(float lo, float hi) { f32x2_cv v = {lo, hi}; bf16x2_cv b = __builtin_convertvector(v, bf16x2_cv); return __builtin_bit_cast(unsigned, b); }
; __device__ __forceinline__ float siluf_(float x) { return x * __builtin_amdgcn_rcpf(1.0f + __expf(-x)); }
;     __device__ __forceinline__ void operator()(const f32x4 (&acc)[2][2][4][2], const Unit& u, int wr, int wc, int fr, int fq) const {
;     ...
;                     for (int m = 3; m >= 0; --m) {
;                         const f32x4 cur = acc[ai][bj][m][n] * rs[m];
;                         f32x4 prev = zero4;
;                         if (m > 0) prev = acc[ai][bj][m - 1][n] * rs[m - 1];
;                         f32x4 r1, r2;
; #pragma unroll
;                         for (int i = 0; i < 4; ++i) {
;                             r1[i] = dpp_mov<0x111>(dpp_mov<0x121>(0.f, prev[i]), cur[i]);
;                             r2[i] = dpp_mov<0x112>(dpp_mov<0x122>(0.f, prev[i]), cur[i]); }
;                         const f32x4 cvv = wb + w2 * cur + w1 * r1 + w0 * r2;
;                         if (bj == 0) {
;                             sg[m].x = cvt_pk_bf16(siluf_(cvv[0]), siluf_(cvv[1])); sg[m].y = cvt_pk_bf16(siluf_(cvv[2]), siluf_(cvv[3]));
;                         } else {
;                             f32x4 h;
;                             h[0] = __uint_as_float(sg[m].x << 16) * cvv[0]; h[1] = __uint_as_float(sg[m].x & 0xffff0000u) * cvv[1];
;                             h[2] = __uint_as_float(sg[m].y << 16) * cvv[2]; h[3] = __uint_as_float(sg[m].y & 0xffff0000u) * cvv[3];
;                             u32x2v w; w.x = cvt_pk_bf16(h[0], h[1]); w.y = cvt_pk_bf16(h[2], h[3]);
;                             *(u32x2v*)(H + (size_t)(rowb + m * 16 + fr) * dff + cg) = w;
;                         }
	v_pk_fma_f32 v[14:15], v[14:15], v[26:27], v[30:31]
	v_pk_fma_f32 v[12:13], v[12:13], v[24:25], v[28:29]
	v_pk_fma_f32 v[14:15], v[22:23], v[36:37], v[14:15]
	v_pk_fma_f32 v[10:11], v[20:21], v[10:11], v[12:13]
	v_pk_fma_f32 v[12:13], v[18:19], v[38:39], v[14:15]
	v_pk_fma_f32 v[10:11], v[16:17], v[34:35], v[10:11]
	v_lshlrev_b32_e32 v14, 16, v40
	v_and_b32_e32 v15, 0xffff0000, v40
	v_pk_mul_f32 v[10:11], v[10:11], v[14:15]
	v_lshlrev_b32_e32 v14, 16, v43
	v_and_b32_e32 v15, 0xffff0000, v43
	v_pk_mul_f32 v[12:13], v[12:13], v[14:15]
	v_cvt_pk_bf16_f32 v10, v10, v11
	v_cvt_pk_bf16_f32 v11, v12, v13
	global_store_dwordx2 v[66:67], v[10:11], off offset:8
	v_mov_b32_e32 v10, v92
	v_mov_b32_e32 v11, v92
	v_pk_mul_f32 v[6:7], v[6:7], v[10:11]
	v_pk_mul_f32 v[4:5], v[4:5], v[92:93]
	s_nop 1
	v_mov_b32_dpp v10, v4 row_ror:1 row_mask:0xf bank_mask:0xf
	v_mov_b32_dpp v12, v4 row_ror:2 row_mask:0xf bank_mask:0xf
	v_mov_b32_dpp v11, v5 row_ror:1 row_mask:0xf bank_mask:0xf
	v_mov_b32_dpp v13, v5 row_ror:2 row_mask:0xf bank_mask:0xf
	v_mov_b32_dpp v10, v8 row_shr:1 row_mask:0xf bank_mask:0xf
	v_mov_b32_dpp v12, v8 row_shr:2 row_mask:0xf bank_mask:0xf
	v_mov_b32_dpp v11, v9 row_shr:1 row_mask:0xf bank_mask:0xf
	v_mov_b32_dpp v13, v9 row_shr:2 row_mask:0xf bank_mask:0xf
	v_mov_b32_dpp v14, v6 row_ror:1 row_mask:0xf bank_mask:0xf
	v_mov_b32_dpp v34, v6 row_ror:2 row_mask:0xf bank_mask:0xf
	v_mov_b32_dpp v15, v7 row_ror:1 row_mask:0xf bank_mask:0xf
	v_mov_b32_dpp v35, v7 row_ror:2 row_mask:0xf bank_mask:0xf
	v_pk_fma_f32 v[8:9], v[8:9], v[24:25], v[28:29]
	v_mov_b32_dpp v14, v0 row_shr:1 row_mask:0xf bank_mask:0xf
	v_mov_b32_dpp v34, v0 row_shr:2 row_mask:0xf bank_mask:0xf
	v_mov_b32_dpp v15, v1 row_shr:1 row_mask:0xf bank_mask:0xf
	v_mov_b32_dpp v35, v1 row_shr:2 row_mask:0xf bank_mask:0xf
	v_pk_fma_f32 v[0:1], v[0:1], v[26:27], v[30:31]
	v_pk_fma_f32 v[8:9], v[20:21], v[10:11], v[8:9]
	v_pk_fma_f32 v[0:1], v[22:23], v[14:15], v[0:1]
	v_pk_fma_f32 v[8:9], v[16:17], v[12:13], v[8:9]
	v_lshlrev_b32_e32 v10, 16, v42
	v_and_b32_e32 v11, 0xffff0000, v42
	v_pk_fma_f32 v[0:1], v[18:19], v[34:35], v[0:1]
	v_pk_mul_f32 v[8:9], v[8:9], v[10:11]
	v_lshlrev_b32_e32 v10, 16, v74
	v_and_b32_e32 v11, 0xffff0000, v74
	v_pk_mul_f32 v[0:1], v[0:1], v[10:11]
	v_cvt_pk_bf16_f32 v8, v8, v9
	v_cvt_pk_bf16_f32 v9, v0, v1
	global_store_dwordx2 v[68:69], v[8:9], off offset:8
	v_mov_b32_e32 v91, v90
	v_pk_mul_f32 v[0:1], v[2:3], v[90:91]
	v_mov_b32_dpp v2, v32 row_ror:1 row_mask:0xf bank_mask:0xf
	v_mov_b32_dpp v8, v32 row_ror:2 row_mask:0xf bank_mask:0xf
	v_mov_b32_dpp v3, v33 row_ror:1 row_mask:0xf bank_mask:0xf
	v_mov_b32_dpp v9, v33 row_ror:2 row_mask:0xf bank_mask:0xf
	v_mov_b32_dpp v10, v0 row_ror:1 row_mask:0xf bank_mask:0xf
	v_mov_b32_dpp v12, v0 row_ror:2 row_mask:0xf bank_mask:0xf
	v_mov_b32_dpp v11, v1 row_ror:1 row_mask:0xf bank_mask:0xf
	v_mov_b32_dpp v13, v1 row_ror:2 row_mask:0xf bank_mask:0xf
	v_mov_b32_dpp v2, v4 row_shr:1 row_mask:0xf bank_mask:0xf
	v_mov_b32_dpp v8, v4 row_shr:2 row_mask:0xf bank_mask:0xf
	v_mov_b32_dpp v3, v5 row_shr:1 row_mask:0xf bank_mask:0xf
	v_mov_b32_dpp v9, v5 row_shr:2 row_mask:0xf bank_mask:0xf
	v_mov_b32_dpp v10, v6 row_shr:1 row_mask:0xf bank_mask:0xf
	v_mov_b32_dpp v12, v6 row_shr:2 row_mask:0xf bank_mask:0xf
	v_mov_b32_dpp v11, v7 row_shr:1 row_mask:0xf bank_mask:0xf
	v_mov_b32_dpp v13, v7 row_shr:2 row_mask:0xf bank_mask:0xf
	v_pk_fma_f32 v[6:7], v[6:7], v[26:27], v[30:31]
	v_pk_fma_f32 v[4:5], v[4:5], v[24:25], v[28:29]
	v_pk_fma_f32 v[6:7], v[22:23], v[10:11], v[6:7]
	v_pk_fma_f32 v[2:3], v[20:21], v[2:3], v[4:5]
	v_pk_fma_f32 v[4:5], v[18:19], v[12:13], v[6:7]
	v_pk_fma_f32 v[2:3], v[16:17], v[8:9], v[2:3]
	v_lshlrev_b32_e32 v6, 16, v78
	v_and_b32_e32 v7, 0xffff0000, v78
	v_pk_mul_f32 v[2:3], v[2:3], v[6:7]
	v_lshlrev_b32_e32 v6, 16, v86
	v_and_b32_e32 v7, 0xffff0000, v86
	v_pk_mul_f32 v[4:5], v[4:5], v[6:7]
	v_cvt_pk_bf16_f32 v2, v2, v3
	v_cvt_pk_bf16_f32 v3, v4, v5
	global_store_dwordx2 v[70:71], v[2:3], off offset:8
	v_mov_b32_e32 v3, 0
	v_mov_b32_e32 v7, 0
	v_pk_fma_f32 v[10:11], v[32:33], v[24:25], v[28:29]
	v_mov_b32_dpp v3, v3 row_ror:1 row_mask:0xf bank_mask:0xf
	v_mov_b32_dpp v7, v7 row_ror:2 row_mask:0xf bank_mask:0xf
	v_mov_b32_e32 v4, v3
	v_mov_b32_e32 v5, v3
	v_mov_b32_e32 v2, v3
	v_mov_b32_e32 v6, v7
	v_mov_b32_dpp v4, v32 row_shr:1 row_mask:0xf bank_mask:0xf
	v_mov_b32_e32 v8, v7
	v_mov_b32_dpp v5, v33 row_shr:1 row_mask:0xf bank_mask:0xf
	v_mov_b32_e32 v9, v7
	v_mov_b32_dpp v2, v0 row_shr:1 row_mask:0xf bank_mask:0xf
	v_mov_b32_dpp v6, v0 row_shr:2 row_mask:0xf bank_mask:0xf
	v_mov_b32_dpp v3, v1 row_shr:1 row_mask:0xf bank_mask:0xf
	v_mov_b32_dpp v7, v1 row_shr:2 row_mask:0xf bank_mask:0xf
	v_pk_fma_f32 v[0:1], v[0:1], v[26:27], v[30:31]
	v_mov_b32_dpp v8, v32 row_shr:2 row_mask:0xf bank_mask:0xf
	v_mov_b32_dpp v9, v33 row_shr:2 row_mask:0xf bank_mask:0xf
	v_pk_fma_f32 v[0:1], v[22:23], v[2:3], v[0:1]
	v_pk_fma_f32 v[2:3], v[20:21], v[4:5], v[10:11]
	v_lshlrev_b32_e32 v4, 16, v96
	v_pk_fma_f32 v[2:3], v[16:17], v[8:9], v[2:3]
	v_and_b32_e32 v5, 0xffff0000, v96
	v_pk_fma_f32 v[0:1], v[18:19], v[6:7], v[0:1]
	v_pk_mul_f32 v[2:3], v[2:3], v[4:5]
	v_lshlrev_b32_e32 v4, 16, v106
	v_and_b32_e32 v5, 0xffff0000, v106
	v_pk_mul_f32 v[0:1], v[0:1], v[4:5]
	v_cvt_pk_bf16_f32 v2, v2, v3
	v_cvt_pk_bf16_f32 v3, v0, v1
	global_store_dwordx2 v[60:61], v[2:3], off offset:8
	s_andn2_b64 vcc, exec, s[16:17]
	s_mov_b64 s[16:17], -1
	s_cbranch_vccnz .LBB0_985
	s_andn2_b64 vcc, exec, s[18:19]
	s_cbranch_vccnz .LBB0_984
	s_barrier
	s_branch .LBB0_984

; __device__ __forceinline__ float bf2f(unsigned h) { return __uint_as_float(h << 16); }
; __device__ __forceinline__ unsigned pk2(float lo, float hi) { return pg8::cvt_pk_bf16(lo, hi); }
; __device__ __forceinline__ void b2_scan(const Ctx& C) {
;     ...
;     const int idx = C.bid * NTHR + C.tid;
;     if (idx >= 131072) return;
;     const bool gla = idx >= 65536; const int r = idx & 65535;
;     bf16* base; size_t cstride, vstride; const float* dec; int dstride;
;     if (!gla) { const int b = r >> 13, h = (r >> 9) & 15, e = r & 511;
;         base = (bf16*)(C.ws + WS_HS) + ((size_t)(b * NC) * 16 + h) * 8192 + (size_t)e * 8; vstride = 512 * 8; cstride = (size_t)16 * 8192; dec = SDEC + (b * NC) * 16 + h; dstride = 16; }
;     else { const int b = r >> 13, h = (r >> 11) & 3, q = r & 2047, doct = q & 15, vp = q >> 4;
;         base = (bf16*)(C.ws + WS_GS) + ((size_t)(b * NC) * 4 + h) * 32768 + (size_t)(2 * vp) * 128 + doct * 8; vstride = 128; cstride = (size_t)4 * 32768; dec = GDEC + ((b * NC) * 4 + h) * 128 + doct * 8; dstride = 512; }
;     float run[2][8];
; #pragma unroll
;     for (int j = 0; j < 2; ++j)
; #pragma unroll
;         for (int q = 0; q < 8; ++q) run[j][q] = 0.f;
;     v4u loc[2][4][2]; f32x4 d0[2][4], d1[2][4];
;     ...
;     B2_LOAD(0, 0);
; #pragma unroll
;     for (int g = 0; g < 8; ++g) {
;         const int cur = g & 1;
;         if (g + 1 < 8) B2_LOAD(g + 1, cur ^ 1);
; #pragma unroll
;         for (int k = 0; k < 4; ++k) {
;             const int c = 4 * g + k;
;             const float dd[8] = {d0[cur][k][0], d0[cur][k][1], d0[cur][k][2], d0[cur][k][3], d1[cur][k][0], d1[cur][k][1], d1[cur][k][2], d1[cur][k][3]};
; #pragma unroll
;             for (int j = 0; j < 2; ++j) {
;                 v4u o; o.x = pk2(run[j][0], run[j][1]); o.y = pk2(run[j][2], run[j][3]); o.z = pk2(run[j][4], run[j][5]); o.w = pk2(run[j][6], run[j][7]);
;                 __builtin_nontemporal_store(o, (v4u*)(base + (size_t)c * cstride + (size_t)j * vstride));
;                 const unsigned lw[4] = {loc[cur][k][j].x, loc[cur][k][j].y, loc[cur][k][j].z, loc[cur][k][j].w};
; #pragma unroll
;                 for (int q = 0; q < 4; ++q) {
;                     run[j][2 * q] = dd[2 * q] * run[j][2 * q] + bf2f(lw[q] & 0xffffu);
;                     run[j][2 * q + 1] = dd[2 * q + 1] * run[j][2 * q + 1] + __uint_as_float(lw[q] & 0xffff0000u);
;                 }
.LBB0_1563:
	s_or_b64 exec, exec, s[12:13]
	v_mov_b32_e32 v8, v234
	s_mov_b32 s10, 0
	s_waitcnt lgkmcnt(0)
	s_barrier
	s_load_dwordx2 s[18:19], s[0:1], 0xc0
	s_mov_b64 s[14:15], exec
	s_cmp_ge_u32 s2, 256
	s_cbranch_scc1 .Lb2_end_l1
	v_mov_b32_e32 v16, 0
	v_mov_b32_e32 v17, 0
	v_mov_b32_e32 v18, 0
	v_mov_b32_e32 v19, 0
	v_mov_b32_e32 v20, 0
	v_mov_b32_e32 v21, 0
	v_mov_b32_e32 v22, 0
	v_mov_b32_e32 v23, 0
	v_mov_b32_e32 v24, 0
	v_mov_b32_e32 v25, 0
	v_mov_b32_e32 v26, 0
	v_mov_b32_e32 v27, 0
	v_mov_b32_e32 v28, 0
	v_mov_b32_e32 v29, 0
	v_mov_b32_e32 v30, 0
	v_mov_b32_e32 v31, 0
	v_mov_b32_e32 v4, 0
	s_cmp_ge_u32 s2, 128
	s_cbranch_scc1 .Lb2_gla_l1
	s_lshr_b32 s10, s2, 4
	s_lshl_b32 s10, s10, 9
	s_and_b32 s16, s2, 15
	s_add_u32 s10, s10, s16
	s_lshl_b32 s16, s10, 2
	s_lshl_b32 s10, s10, 14
	v_lshlrev_b32_e32 v2, 4, v234
	v_add_u32_e32 v3, 0x2000, v2
	s_waitcnt lgkmcnt(0)
	s_add_u32 s10, s10, s18
	s_addc_u32 s11, s19, 0
	s_add_u32 s10, s10, 0x1dc00000
	s_addc_u32 s11, s11, 0
	s_add_u32 s16, s16, s18
	s_addc_u32 s17, s19, 0
	s_add_u32 s16, s16, 0x25c00000
	s_addc_u32 s17, s17, 0
	s_mov_b32 s12, s10
	s_mov_b32 s13, s11
	global_load_dwordx4 v[64:67], v2, s[10:11] nt
	global_load_dwordx4 v[68:71], v3, s[10:11] nt
	global_load_dword v72, v4, s[16:17]
	s_add_u32 s10, s10, 0x40000
	s_addc_u32 s11, s11, 0
	s_add_u32 s16, s16, 64
	s_addc_u32 s17, s17, 0
	global_load_dwordx4 v[80:83], v2, s[10:11] nt
	global_load_dwordx4 v[84:87], v3, s[10:11] nt
	global_load_dword v88, v4, s[16:17]
	s_add_u32 s10, s10, 0x40000
	s_addc_u32 s11, s11, 0
	s_add_u32 s16, s16, 64
	s_addc_u32 s17, s17, 0
	global_load_dwordx4 v[96:99], v2, s[10:11] nt
	global_load_dwordx4 v[100:103], v3, s[10:11] nt
	global_load_dword v104, v4, s[16:17]
	s_add_u32 s10, s10, 0x40000
	s_addc_u32 s11, s11, 0
	s_add_u32 s16, s16, 64
	s_addc_u32 s17, s17, 0
	global_load_dwordx4 v[112:115], v2, s[10:11] nt
	global_load_dwordx4 v[116:119], v3, s[10:11] nt
	global_load_dword v120, v4, s[16:17]
	s_add_u32 s10, s10, 0x40000
	s_addc_u32 s11, s11, 0
	s_add_u32 s16, s16, 64
	s_addc_u32 s17, s17, 0
	global_load_dwordx4 v[128:131], v2, s[10:11] nt
	global_load_dwordx4 v[132:135], v3, s[10:11] nt
	global_load_dword v136, v4, s[16:17]
	s_add_u32 s10, s10, 0x40000
	s_addc_u32 s11, s11, 0
	s_add_u32 s16, s16, 64
	s_addc_u32 s17, s17, 0
	global_load_dwordx4 v[144:147], v2, s[10:11] nt
	global_load_dwordx4 v[148:151], v3, s[10:11] nt
	global_load_dword v152, v4, s[16:17]
	s_add_u32 s10, s10, 0x40000
	s_addc_u32 s11, s11, 0
	s_add_u32 s16, s16, 64
	s_addc_u32 s17, s17, 0
	global_load_dwordx4 v[160:163], v2, s[10:11] nt
	global_load_dwordx4 v[164:167], v3, s[10:11] nt
	global_load_dword v168, v4, s[16:17]
	s_add_u32 s10, s10, 0x40000
	s_addc_u32 s11, s11, 0
	s_add_u32 s16, s16, 64
	s_addc_u32 s17, s17, 0
	global_load_dwordx4 v[176:179], v2, s[10:11] nt
	global_load_dwordx4 v[180:183], v3, s[10:11] nt
	global_load_dword v184, v4, s[16:17]
	s_add_u32 s10, s10, 0x40000
	s_addc_u32 s11, s11, 0
	s_add_u32 s16, s16, 64
	s_addc_u32 s17, s17, 0
	s_waitcnt vmcnt(21)
	v_cvt_pk_bf16_f32 v32, v16, v17
	v_cvt_pk_bf16_f32 v33, v18, v19
	v_cvt_pk_bf16_f32 v34, v20, v21
	v_cvt_pk_bf16_f32 v35, v22, v23
	global_store_dwordx4 v2, v[32:35], s[12:13] nt
	v_cvt_pk_bf16_f32 v36, v24, v25
	v_cvt_pk_bf16_f32 v37, v26, v27
	v_cvt_pk_bf16_f32 v38, v28, v29
	v_cvt_pk_bf16_f32 v39, v30, v31
	global_store_dwordx4 v3, v[36:39], s[12:13] nt
	s_add_u32 s12, s12, 0x40000
	s_addc_u32 s13, s13, 0
	v_lshlrev_b32_e32 v48, 16, v64
	v_and_b32_e32 v49, 0xffff0000, v64
	v_fma_f32 v16, v72, v16, v48
	v_fma_f32 v17, v72, v17, v49
	v_lshlrev_b32_e32 v48, 16, v65
	v_and_b32_e32 v49, 0xffff0000, v65
	v_fma_f32 v18, v72, v18, v48
	v_fma_f32 v19, v72, v19, v49
	v_lshlrev_b32_e32 v48, 16, v66
	v_and_b32_e32 v49, 0xffff0000, v66
	v_fma_f32 v20, v72, v20, v48
	v_fma_f32 v21, v72, v21, v49
	v_lshlrev_b32_e32 v48, 16, v67
	v_and_b32_e32 v49, 0xffff0000, v67
	v_fma_f32 v22, v72, v22, v48
	v_fma_f32 v23, v72, v23, v49
	v_lshlrev_b32_e32 v48, 16, v68
	v_and_b32_e32 v49, 0xffff0000, v68
	v_fma_f32 v24, v72, v24, v48
	v_fma_f32 v25, v72, v25, v49
	v_lshlrev_b32_e32 v48, 16, v69
	v_and_b32_e32 v49, 0xffff0000, v69
	v_fma_f32 v26, v72, v26, v48
	v_fma_f32 v27, v72, v27, v49
	v_lshlrev_b32_e32 v48, 16, v70
	v_and_b32_e32 v49, 0xffff0000, v70
	v_fma_f32 v28, v72, v28, v48
	v_fma_f32 v29, v72, v29, v49
	v_lshlrev_b32_e32 v48, 16, v71
	v_and_b32_e32 v49, 0xffff0000, v71
	v_fma_f32 v30, v72, v30, v48
	v_fma_f32 v31, v72, v31, v49
	global_load_dwordx4 v[64:67], v2, s[10:11] nt
	global_load_dwordx4 v[68:71], v3, s[10:11] nt
	global_load_dword v72, v4, s[16:17]
	s_add_u32 s10, s10, 0x40000
	s_addc_u32 s11, s11, 0
	s_add_u32 s16, s16, 64
	s_addc_u32 s17, s17, 0
	s_waitcnt vmcnt(23)
	v_cvt_pk_bf16_f32 v40, v16, v17
	v_cvt_pk_bf16_f32 v41, v18, v19
	v_cvt_pk_bf16_f32 v42, v20, v21
	v_cvt_pk_bf16_f32 v43, v22, v23
	global_store_dwordx4 v2, v[40:43], s[12:13] nt
	v_cvt_pk_bf16_f32 v44, v24, v25
	v_cvt_pk_bf16_f32 v45, v26, v27
	v_cvt_pk_bf16_f32 v46, v28, v29
	v_cvt_pk_bf16_f32 v47, v30, v31
	global_store_dwordx4 v3, v[44:47], s[12:13] nt
	s_add_u32 s12, s12, 0x40000
	s_addc_u32 s13, s13, 0
	v_lshlrev_b32_e32 v48, 16, v80
	v_and_b32_e32 v49, 0xffff0000, v80
	v_fma_f32 v16, v88, v16, v48
	v_fma_f32 v17, v88, v17, v49
	v_lshlrev_b32_e32 v48, 16, v81
	v_and_b32_e32 v49, 0xffff0000, v81
	v_fma_f32 v18, v88, v18, v48
	v_fma_f32 v19, v88, v19, v49
	v_lshlrev_b32_e32 v48, 16, v82
	v_and_b32_e32 v49, 0xffff0000, v82
	v_fma_f32 v20, v88, v20, v48
	v_fma_f32 v21, v88, v21, v49
	v_lshlrev_b32_e32 v48, 16, v83
	v_and_b32_e32 v49, 0xffff0000, v83
	v_fma_f32 v22, v88, v22, v48
	v_fma_f32 v23, v88, v23, v49
	v_lshlrev_b32_e32 v48, 16, v84
	v_and_b32_e32 v49, 0xffff0000, v84
	v_fma_f32 v24, v88, v24, v48
	v_fma_f32 v25, v88, v25, v49
	v_lshlrev_b32_e32 v48, 16, v85
	v_and_b32_e32 v49, 0xffff0000, v85
	v_fma_f32 v26, v88, v26, v48
	v_fma_f32 v27, v88, v27, v49
	v_lshlrev_b32_e32 v48, 16, v86
	v_and_b32_e32 v49, 0xffff0000, v86
	v_fma_f32 v28, v88, v28, v48
	v_fma_f32 v29, v88, v29, v49
	v_lshlrev_b32_e32 v48, 16, v87
	v_and_b32_e32 v49, 0xffff0000, v87
	v_fma_f32 v30, v88, v30, v48
	v_fma_f32 v31, v88, v31, v49
	global_load_dwordx4 v[80:83], v2, s[10:11] nt
	global_load_dwordx4 v[84:87], v3, s[10:11] nt
	global_load_dword v88, v4, s[16:17]
	s_add_u32 s10, s10, 0x40000
	s_addc_u32 s11, s11, 0
	s_add_u32 s16, s16, 64
	s_addc_u32 s17, s17, 0
	s_waitcnt vmcnt(25)
; __device__ __forceinline__ float bf2f(unsigned h) { return __uint_as_float(h << 16); }
; __device__ __forceinline__ unsigned pk2(float lo, float hi) { return pg8::cvt_pk_bf16(lo, hi); }
; __device__ __forceinline__ void b2_scan(const Ctx& C) {
;     ...
;         for (int k = 0; k < 4; ++k) {
;             const int c = 4 * g + k;
;             const float dd[8] = {d0[cur][k][0], d0[cur][k][1], d0[cur][k][2], d0[cur][k][3], d1[cur][k][0], d1[cur][k][1], d1[cur][k][2], d1[cur][k][3]};
; #pragma unroll
;             for (int j = 0; j < 2; ++j) {
;                 v4u o; o.x = pk2(run[j][0], run[j][1]); o.y = pk2(run[j][2], run[j][3]); o.z = pk2(run[j][4], run[j][5]); o.w = pk2(run[j][6], run[j][7]);
;                 __builtin_nontemporal_store(o, (v4u*)(base + (size_t)c * cstride + (size_t)j * vstride));
;                 const unsigned lw[4] = {loc[cur][k][j].x, loc[cur][k][j].y, loc[cur][k][j].z, loc[cur][k][j].w};
; #pragma unroll
;                 for (int q = 0; q < 4; ++q) {
;                     run[j][2 * q] = dd[2 * q] * run[j][2 * q] + bf2f(lw[q] & 0xffffu);
;                     run[j][2 * q + 1] = dd[2 * q + 1] * run[j][2 * q + 1] + __uint_as_float(lw[q] & 0xffff0000u);
;                 }
	v_cvt_pk_bf16_f32 v32, v16, v17
	v_cvt_pk_bf16_f32 v33, v18, v19
	v_cvt_pk_bf16_f32 v34, v20, v21
	v_cvt_pk_bf16_f32 v35, v22, v23
	global_store_dwordx4 v2, v[32:35], s[12:13] nt
	v_cvt_pk_bf16_f32 v36, v24, v25
	v_cvt_pk_bf16_f32 v37, v26, v27
	v_cvt_pk_bf16_f32 v38, v28, v29
	v_cvt_pk_bf16_f32 v39, v30, v31
	global_store_dwordx4 v3, v[36:39], s[12:13] nt
	s_add_u32 s12, s12, 0x40000
	s_addc_u32 s13, s13, 0
	v_lshlrev_b32_e32 v48, 16, v96
	v_and_b32_e32 v49, 0xffff0000, v96
	v_fma_f32 v16, v104, v16, v48
	v_fma_f32 v17, v104, v17, v49
	v_lshlrev_b32_e32 v48, 16, v97
	v_and_b32_e32 v49, 0xffff0000, v97
	v_fma_f32 v18, v104, v18, v48
	v_fma_f32 v19, v104, v19, v49
	v_lshlrev_b32_e32 v48, 16, v98
	v_and_b32_e32 v49, 0xffff0000, v98
	v_fma_f32 v20, v104, v20, v48
	v_fma_f32 v21, v104, v21, v49
	v_lshlrev_b32_e32 v48, 16, v99
	v_and_b32_e32 v49, 0xffff0000, v99
	v_fma_f32 v22, v104, v22, v48
	v_fma_f32 v23, v104, v23, v49
	v_lshlrev_b32_e32 v48, 16, v100
	v_and_b32_e32 v49, 0xffff0000, v100
	v_fma_f32 v24, v104, v24, v48
	v_fma_f32 v25, v104, v25, v49
	v_lshlrev_b32_e32 v48, 16, v101
	v_and_b32_e32 v49, 0xffff0000, v101
	v_fma_f32 v26, v104, v26, v48
	v_fma_f32 v27, v104, v27, v49
	v_lshlrev_b32_e32 v48, 16, v102
	v_and_b32_e32 v49, 0xffff0000, v102
	v_fma_f32 v28, v104, v28, v48
	v_fma_f32 v29, v104, v29, v49
	v_lshlrev_b32_e32 v48, 16, v103
	v_and_b32_e32 v49, 0xffff0000, v103
	v_fma_f32 v30, v104, v30, v48
	v_fma_f32 v31, v104, v31, v49
	global_load_dwordx4 v[96:99], v2, s[10:11] nt
	global_load_dwordx4 v[100:103], v3, s[10:11] nt
	global_load_dword v104, v4, s[16:17]
	s_add_u32 s10, s10, 0x40000
	s_addc_u32 s11, s11, 0
	s_add_u32 s16, s16, 64
	s_addc_u32 s17, s17, 0
	s_waitcnt vmcnt(27)
	v_cvt_pk_bf16_f32 v40, v16, v17
	v_cvt_pk_bf16_f32 v41, v18, v19
	v_cvt_pk_bf16_f32 v42, v20, v21
	v_cvt_pk_bf16_f32 v43, v22, v23
	global_store_dwordx4 v2, v[40:43], s[12:13] nt
	v_cvt_pk_bf16_f32 v44, v24, v25
	v_cvt_pk_bf16_f32 v45, v26, v27
	v_cvt_pk_bf16_f32 v46, v28, v29
	v_cvt_pk_bf16_f32 v47, v30, v31
	global_store_dwordx4 v3, v[44:47], s[12:13] nt
	s_add_u32 s12, s12, 0x40000
	s_addc_u32 s13, s13, 0
	v_lshlrev_b32_e32 v48, 16, v112
	v_and_b32_e32 v49, 0xffff0000, v112
	v_fma_f32 v16, v120, v16, v48
	v_fma_f32 v17, v120, v17, v49
	v_lshlrev_b32_e32 v48, 16, v113
	v_and_b32_e32 v49, 0xffff0000, v113
	v_fma_f32 v18, v120, v18, v48
	v_fma_f32 v19, v120, v19, v49
	v_lshlrev_b32_e32 v48, 16, v114
	v_and_b32_e32 v49, 0xffff0000, v114
	v_fma_f32 v20, v120, v20, v48
	v_fma_f32 v21, v120, v21, v49
	v_lshlrev_b32_e32 v48, 16, v115
	v_and_b32_e32 v49, 0xffff0000, v115
	v_fma_f32 v22, v120, v22, v48
	v_fma_f32 v23, v120, v23, v49
	v_lshlrev_b32_e32 v48, 16, v116
	v_and_b32_e32 v49, 0xffff0000, v116
	v_fma_f32 v24, v120, v24, v48
	v_fma_f32 v25, v120, v25, v49
	v_lshlrev_b32_e32 v48, 16, v117
	v_and_b32_e32 v49, 0xffff0000, v117
	v_fma_f32 v26, v120, v26, v48
	v_fma_f32 v27, v120, v27, v49
	v_lshlrev_b32_e32 v48, 16, v118
	v_and_b32_e32 v49, 0xffff0000, v118
	v_fma_f32 v28, v120, v28, v48
	v_fma_f32 v29, v120, v29, v49
	v_lshlrev_b32_e32 v48, 16, v119
	v_and_b32_e32 v49, 0xffff0000, v119
	v_fma_f32 v30, v120, v30, v48
	v_fma_f32 v31, v120, v31, v49
	global_load_dwordx4 v[112:115], v2, s[10:11] nt
	global_load_dwordx4 v[116:119], v3, s[10:11] nt
	global_load_dword v120, v4, s[16:17]
	s_add_u32 s10, s10, 0x40000
	s_addc_u32 s11, s11, 0
	s_add_u32 s16, s16, 64
	s_addc_u32 s17, s17, 0
	s_waitcnt vmcnt(29)
	v_cvt_pk_bf16_f32 v32, v16, v17
	v_cvt_pk_bf16_f32 v33, v18, v19
	v_cvt_pk_bf16_f32 v34, v20, v21
	v_cvt_pk_bf16_f32 v35, v22, v23
	global_store_dwordx4 v2, v[32:35], s[12:13] nt
	v_cvt_pk_bf16_f32 v36, v24, v25
	v_cvt_pk_bf16_f32 v37, v26, v27
	v_cvt_pk_bf16_f32 v38, v28, v29
	v_cvt_pk_bf16_f32 v39, v30, v31
	global_store_dwordx4 v3, v[36:39], s[12:13] nt
	s_add_u32 s12, s12, 0x40000
	s_addc_u32 s13, s13, 0
	v_lshlrev_b32_e32 v48, 16, v128
	v_and_b32_e32 v49, 0xffff0000, v128
	v_fma_f32 v16, v136, v16, v48
	v_fma_f32 v17, v136, v17, v49
	v_lshlrev_b32_e32 v48, 16, v129
	v_and_b32_e32 v49, 0xffff0000, v129
	v_fma_f32 v18, v136, v18, v48
	v_fma_f32 v19, v136, v19, v49
	v_lshlrev_b32_e32 v48, 16, v130
	v_and_b32_e32 v49, 0xffff0000, v130
	v_fma_f32 v20, v136, v20, v48
	v_fma_f32 v21, v136, v21, v49
	v_lshlrev_b32_e32 v48, 16, v131
	v_and_b32_e32 v49, 0xffff0000, v131
	v_fma_f32 v22, v136, v22, v48
	v_fma_f32 v23, v136, v23, v49
	v_lshlrev_b32_e32 v48, 16, v132
	v_and_b32_e32 v49, 0xffff0000, v132
	v_fma_f32 v24, v136, v24, v48
	v_fma_f32 v25, v136, v25, v49
	v_lshlrev_b32_e32 v48, 16, v133
	v_and_b32_e32 v49, 0xffff0000, v133
	v_fma_f32 v26, v136, v26, v48
	v_fma_f32 v27, v136, v27, v49
	v_lshlrev_b32_e32 v48, 16, v134
	v_and_b32_e32 v49, 0xffff0000, v134
	v_fma_f32 v28, v136, v28, v48
	v_fma_f32 v29, v136, v29, v49
	v_lshlrev_b32_e32 v48, 16, v135
	v_and_b32_e32 v49, 0xffff0000, v135
	v_fma_f32 v30, v136, v30, v48
	v_fma_f32 v31, v136, v31, v49
	global_load_dwordx4 v[128:131], v2, s[10:11] nt
	global_load_dwordx4 v[132:135], v3, s[10:11] nt
	global_load_dword v136, v4, s[16:17]
	s_add_u32 s10, s10, 0x40000
	s_addc_u32 s11, s11, 0
	s_add_u32 s16, s16, 64
	s_addc_u32 s17, s17, 0
	s_waitcnt vmcnt(31)
; __device__ __forceinline__ float bf2f(unsigned h) { return __uint_as_float(h << 16); }
; __device__ __forceinline__ unsigned pk2(float lo, float hi) { return pg8::cvt_pk_bf16(lo, hi); }
; __device__ __forceinline__ void b2_scan(const Ctx& C) {
;     ...
;         for (int k = 0; k < 4; ++k) {
;             const int c = 4 * g + k;
;             const float dd[8] = {d0[cur][k][0], d0[cur][k][1], d0[cur][k][2], d0[cur][k][3], d1[cur][k][0], d1[cur][k][1], d1[cur][k][2], d1[cur][k][3]};
; #pragma unroll
;             for (int j = 0; j < 2; ++j) {
;                 v4u o; o.x = pk2(run[j][0], run[j][1]); o.y = pk2(run[j][2], run[j][3]); o.z = pk2(run[j][4], run[j][5]); o.w = pk2(run[j][6], run[j][7]);
;                 __builtin_nontemporal_store(o, (v4u*)(base + (size_t)c * cstride + (size_t)j * vstride));
;                 const unsigned lw[4] = {loc[cur][k][j].x, loc[cur][k][j].y, loc[cur][k][j].z, loc[cur][k][j].w};
; #pragma unroll
;                 for (int q = 0; q < 4; ++q) {
;                     run[j][2 * q] = dd[2 * q] * run[j][2 * q] + bf2f(lw[q] & 0xffffu);
;                     run[j][2 * q + 1] = dd[2 * q + 1] * run[j][2 * q + 1] + __uint_as_float(lw[q] & 0xffff0000u);
;                 }
	v_cvt_pk_bf16_f32 v40, v16, v17
	v_cvt_pk_bf16_f32 v41, v18, v19
	v_cvt_pk_bf16_f32 v42, v20, v21
	v_cvt_pk_bf16_f32 v43, v22, v23
	global_store_dwordx4 v2, v[40:43], s[12:13] nt
	v_cvt_pk_bf16_f32 v44, v24, v25
	v_cvt_pk_bf16_f32 v45, v26, v27
	v_cvt_pk_bf16_f32 v46, v28, v29
	v_cvt_pk_bf16_f32 v47, v30, v31
	global_store_dwordx4 v3, v[44:47], s[12:13] nt
	s_add_u32 s12, s12, 0x40000
	s_addc_u32 s13, s13, 0
	v_lshlrev_b32_e32 v48, 16, v144
	v_and_b32_e32 v49, 0xffff0000, v144
	v_fma_f32 v16, v152, v16, v48
	v_fma_f32 v17, v152, v17, v49
	v_lshlrev_b32_e32 v48, 16, v145
	v_and_b32_e32 v49, 0xffff0000, v145
	v_fma_f32 v18, v152, v18, v48
	v_fma_f32 v19, v152, v19, v49
	v_lshlrev_b32_e32 v48, 16, v146
	v_and_b32_e32 v49, 0xffff0000, v146
	v_fma_f32 v20, v152, v20, v48
	v_fma_f32 v21, v152, v21, v49
	v_lshlrev_b32_e32 v48, 16, v147
	v_and_b32_e32 v49, 0xffff0000, v147
	v_fma_f32 v22, v152, v22, v48
	v_fma_f32 v23, v152, v23, v49
	v_lshlrev_b32_e32 v48, 16, v148
	v_and_b32_e32 v49, 0xffff0000, v148
	v_fma_f32 v24, v152, v24, v48
	v_fma_f32 v25, v152, v25, v49
	v_lshlrev_b32_e32 v48, 16, v149
	v_and_b32_e32 v49, 0xffff0000, v149
	v_fma_f32 v26, v152, v26, v48
	v_fma_f32 v27, v152, v27, v49
	v_lshlrev_b32_e32 v48, 16, v150
	v_and_b32_e32 v49, 0xffff0000, v150
	v_fma_f32 v28, v152, v28, v48
	v_fma_f32 v29, v152, v29, v49
	v_lshlrev_b32_e32 v48, 16, v151
	v_and_b32_e32 v49, 0xffff0000, v151
	v_fma_f32 v30, v152, v30, v48
	v_fma_f32 v31, v152, v31, v49
	global_load_dwordx4 v[144:147], v2, s[10:11] nt
	global_load_dwordx4 v[148:151], v3, s[10:11] nt
	global_load_dword v152, v4, s[16:17]
	s_add_u32 s10, s10, 0x40000
	s_addc_u32 s11, s11, 0
	s_add_u32 s16, s16, 64
	s_addc_u32 s17, s17, 0
	s_waitcnt vmcnt(33)
	v_cvt_pk_bf16_f32 v32, v16, v17
	v_cvt_pk_bf16_f32 v33, v18, v19
	v_cvt_pk_bf16_f32 v34, v20, v21
	v_cvt_pk_bf16_f32 v35, v22, v23
	global_store_dwordx4 v2, v[32:35], s[12:13] nt
	v_cvt_pk_bf16_f32 v36, v24, v25
	v_cvt_pk_bf16_f32 v37, v26, v27
	v_cvt_pk_bf16_f32 v38, v28, v29
	v_cvt_pk_bf16_f32 v39, v30, v31
	global_store_dwordx4 v3, v[36:39], s[12:13] nt
	s_add_u32 s12, s12, 0x40000
	s_addc_u32 s13, s13, 0
	v_lshlrev_b32_e32 v48, 16, v160
	v_and_b32_e32 v49, 0xffff0000, v160
	v_fma_f32 v16, v168, v16, v48
	v_fma_f32 v17, v168, v17, v49
	v_lshlrev_b32_e32 v48, 16, v161
	v_and_b32_e32 v49, 0xffff0000, v161
	v_fma_f32 v18, v168, v18, v48
	v_fma_f32 v19, v168, v19, v49
	v_lshlrev_b32_e32 v48, 16, v162
	v_and_b32_e32 v49, 0xffff0000, v162
	v_fma_f32 v20, v168, v20, v48
	v_fma_f32 v21, v168, v21, v49
	v_lshlrev_b32_e32 v48, 16, v163
	v_and_b32_e32 v49, 0xffff0000, v163
	v_fma_f32 v22, v168, v22, v48
	v_fma_f32 v23, v168, v23, v49
	v_lshlrev_b32_e32 v48, 16, v164
	v_and_b32_e32 v49, 0xffff0000, v164
	v_fma_f32 v24, v168, v24, v48
	v_fma_f32 v25, v168, v25, v49
	v_lshlrev_b32_e32 v48, 16, v165
	v_and_b32_e32 v49, 0xffff0000, v165
	v_fma_f32 v26, v168, v26, v48
	v_fma_f32 v27, v168, v27, v49
	v_lshlrev_b32_e32 v48, 16, v166
	v_and_b32_e32 v49, 0xffff0000, v166
	v_fma_f32 v28, v168, v28, v48
	v_fma_f32 v29, v168, v29, v49
	v_lshlrev_b32_e32 v48, 16, v167
	v_and_b32_e32 v49, 0xffff0000, v167
	v_fma_f32 v30, v168, v30, v48
	v_fma_f32 v31, v168, v31, v49
	global_load_dwordx4 v[160:163], v2, s[10:11] nt
	global_load_dwordx4 v[164:167], v3, s[10:11] nt
	global_load_dword v168, v4, s[16:17]
	s_add_u32 s10, s10, 0x40000
	s_addc_u32 s11, s11, 0
	s_add_u32 s16, s16, 64
	s_addc_u32 s17, s17, 0
	s_waitcnt vmcnt(35)
	v_cvt_pk_bf16_f32 v40, v16, v17
	v_cvt_pk_bf16_f32 v41, v18, v19
	v_cvt_pk_bf16_f32 v42, v20, v21
	v_cvt_pk_bf16_f32 v43, v22, v23
	global_store_dwordx4 v2, v[40:43], s[12:13] nt
	v_cvt_pk_bf16_f32 v44, v24, v25
	v_cvt_pk_bf16_f32 v45, v26, v27
	v_cvt_pk_bf16_f32 v46, v28, v29
	v_cvt_pk_bf16_f32 v47, v30, v31
	global_store_dwordx4 v3, v[44:47], s[12:13] nt
	s_add_u32 s12, s12, 0x40000
	s_addc_u32 s13, s13, 0
	v_lshlrev_b32_e32 v48, 16, v176
	v_and_b32_e32 v49, 0xffff0000, v176
	v_fma_f32 v16, v184, v16, v48
	v_fma_f32 v17, v184, v17, v49
	v_lshlrev_b32_e32 v48, 16, v177
	v_and_b32_e32 v49, 0xffff0000, v177
	v_fma_f32 v18, v184, v18, v48
	v_fma_f32 v19, v184, v19, v49
	v_lshlrev_b32_e32 v48, 16, v178
	v_and_b32_e32 v49, 0xffff0000, v178
	v_fma_f32 v20, v184, v20, v48
	v_fma_f32 v21, v184, v21, v49
	v_lshlrev_b32_e32 v48, 16, v179
	v_and_b32_e32 v49, 0xffff0000, v179
	v_fma_f32 v22, v184, v22, v48
	v_fma_f32 v23, v184, v23, v49
	v_lshlrev_b32_e32 v48, 16, v180
	v_and_b32_e32 v49, 0xffff0000, v180
	v_fma_f32 v24, v184, v24, v48
	v_fma_f32 v25, v184, v25, v49
	v_lshlrev_b32_e32 v48, 16, v181
	v_and_b32_e32 v49, 0xffff0000, v181
	v_fma_f32 v26, v184, v26, v48
	v_fma_f32 v27, v184, v27, v49
	v_lshlrev_b32_e32 v48, 16, v182
	v_and_b32_e32 v49, 0xffff0000, v182
	v_fma_f32 v28, v184, v28, v48
	v_fma_f32 v29, v184, v29, v49
	v_lshlrev_b32_e32 v48, 16, v183
	v_and_b32_e32 v49, 0xffff0000, v183
	v_fma_f32 v30, v184, v30, v48
	v_fma_f32 v31, v184, v31, v49
	global_load_dwordx4 v[176:179], v2, s[10:11] nt
	global_load_dwordx4 v[180:183], v3, s[10:11] nt
	global_load_dword v184, v4, s[16:17]
	s_add_u32 s10, s10, 0x40000
	s_addc_u32 s11, s11, 0
	s_add_u32 s16, s16, 64
	s_addc_u32 s17, s17, 0
	s_waitcnt vmcnt(35)
; __device__ __forceinline__ float bf2f(unsigned h) { return __uint_as_float(h << 16); }
; __device__ __forceinline__ unsigned pk2(float lo, float hi) { return pg8::cvt_pk_bf16(lo, hi); }
; __device__ __forceinline__ void b2_scan(const Ctx& C) {
;     ...
;         for (int k = 0; k < 4; ++k) {
;             const int c = 4 * g + k;
;             const float dd[8] = {d0[cur][k][0], d0[cur][k][1], d0[cur][k][2], d0[cur][k][3], d1[cur][k][0], d1[cur][k][1], d1[cur][k][2], d1[cur][k][3]};
; #pragma unroll
;             for (int j = 0; j < 2; ++j) {
;                 v4u o; o.x = pk2(run[j][0], run[j][1]); o.y = pk2(run[j][2], run[j][3]); o.z = pk2(run[j][4], run[j][5]); o.w = pk2(run[j][6], run[j][7]);
;                 __builtin_nontemporal_store(o, (v4u*)(base + (size_t)c * cstride + (size_t)j * vstride));
;                 const unsigned lw[4] = {loc[cur][k][j].x, loc[cur][k][j].y, loc[cur][k][j].z, loc[cur][k][j].w};
; #pragma unroll
;                 for (int q = 0; q < 4; ++q) {
;                     run[j][2 * q] = dd[2 * q] * run[j][2 * q] + bf2f(lw[q] & 0xffffu);
;                     run[j][2 * q + 1] = dd[2 * q + 1] * run[j][2 * q + 1] + __uint_as_float(lw[q] & 0xffff0000u);
;                 }
	v_cvt_pk_bf16_f32 v32, v16, v17
	v_cvt_pk_bf16_f32 v33, v18, v19
	v_cvt_pk_bf16_f32 v34, v20, v21
	v_cvt_pk_bf16_f32 v35, v22, v23
	global_store_dwordx4 v2, v[32:35], s[12:13] nt
	v_cvt_pk_bf16_f32 v36, v24, v25
	v_cvt_pk_bf16_f32 v37, v26, v27
	v_cvt_pk_bf16_f32 v38, v28, v29
	v_cvt_pk_bf16_f32 v39, v30, v31
	global_store_dwordx4 v3, v[36:39], s[12:13] nt
	s_add_u32 s12, s12, 0x40000
	s_addc_u32 s13, s13, 0
	v_lshlrev_b32_e32 v48, 16, v64
	v_and_b32_e32 v49, 0xffff0000, v64
	v_fma_f32 v16, v72, v16, v48
	v_fma_f32 v17, v72, v17, v49
	v_lshlrev_b32_e32 v48, 16, v65
	v_and_b32_e32 v49, 0xffff0000, v65
	v_fma_f32 v18, v72, v18, v48
	v_fma_f32 v19, v72, v19, v49
	v_lshlrev_b32_e32 v48, 16, v66
	v_and_b32_e32 v49, 0xffff0000, v66
	v_fma_f32 v20, v72, v20, v48
	v_fma_f32 v21, v72, v21, v49
	v_lshlrev_b32_e32 v48, 16, v67
	v_and_b32_e32 v49, 0xffff0000, v67
	v_fma_f32 v22, v72, v22, v48
	v_fma_f32 v23, v72, v23, v49
	v_lshlrev_b32_e32 v48, 16, v68
	v_and_b32_e32 v49, 0xffff0000, v68
	v_fma_f32 v24, v72, v24, v48
	v_fma_f32 v25, v72, v25, v49
	v_lshlrev_b32_e32 v48, 16, v69
	v_and_b32_e32 v49, 0xffff0000, v69
	v_fma_f32 v26, v72, v26, v48
	v_fma_f32 v27, v72, v27, v49
	v_lshlrev_b32_e32 v48, 16, v70
	v_and_b32_e32 v49, 0xffff0000, v70
	v_fma_f32 v28, v72, v28, v48
	v_fma_f32 v29, v72, v29, v49
	v_lshlrev_b32_e32 v48, 16, v71
	v_and_b32_e32 v49, 0xffff0000, v71
	v_fma_f32 v30, v72, v30, v48
	v_fma_f32 v31, v72, v31, v49
	global_load_dwordx4 v[64:67], v2, s[10:11] nt
	global_load_dwordx4 v[68:71], v3, s[10:11] nt
	global_load_dword v72, v4, s[16:17]
	s_add_u32 s10, s10, 0x40000
	s_addc_u32 s11, s11, 0
	s_add_u32 s16, s16, 64
	s_addc_u32 s17, s17, 0
	s_waitcnt vmcnt(35)
	v_cvt_pk_bf16_f32 v40, v16, v17
	v_cvt_pk_bf16_f32 v41, v18, v19
	v_cvt_pk_bf16_f32 v42, v20, v21
	v_cvt_pk_bf16_f32 v43, v22, v23
	global_store_dwordx4 v2, v[40:43], s[12:13] nt
	v_cvt_pk_bf16_f32 v44, v24, v25
	v_cvt_pk_bf16_f32 v45, v26, v27
	v_cvt_pk_bf16_f32 v46, v28, v29
	v_cvt_pk_bf16_f32 v47, v30, v31
	global_store_dwordx4 v3, v[44:47], s[12:13] nt
	s_add_u32 s12, s12, 0x40000
	s_addc_u32 s13, s13, 0
	v_lshlrev_b32_e32 v48, 16, v80
	v_and_b32_e32 v49, 0xffff0000, v80
	v_fma_f32 v16, v88, v16, v48
	v_fma_f32 v17, v88, v17, v49
	v_lshlrev_b32_e32 v48, 16, v81
	v_and_b32_e32 v49, 0xffff0000, v81
	v_fma_f32 v18, v88, v18, v48
	v_fma_f32 v19, v88, v19, v49
	v_lshlrev_b32_e32 v48, 16, v82
	v_and_b32_e32 v49, 0xffff0000, v82
	v_fma_f32 v20, v88, v20, v48
	v_fma_f32 v21, v88, v21, v49
	v_lshlrev_b32_e32 v48, 16, v83
	v_and_b32_e32 v49, 0xffff0000, v83
	v_fma_f32 v22, v88, v22, v48
	v_fma_f32 v23, v88, v23, v49
	v_lshlrev_b32_e32 v48, 16, v84
	v_and_b32_e32 v49, 0xffff0000, v84
	v_fma_f32 v24, v88, v24, v48
	v_fma_f32 v25, v88, v25, v49
	v_lshlrev_b32_e32 v48, 16, v85
	v_and_b32_e32 v49, 0xffff0000, v85
	v_fma_f32 v26, v88, v26, v48
	v_fma_f32 v27, v88, v27, v49
	v_lshlrev_b32_e32 v48, 16, v86
	v_and_b32_e32 v49, 0xffff0000, v86
	v_fma_f32 v28, v88, v28, v48
	v_fma_f32 v29, v88, v29, v49
	v_lshlrev_b32_e32 v48, 16, v87
	v_and_b32_e32 v49, 0xffff0000, v87
	v_fma_f32 v30, v88, v30, v48
	v_fma_f32 v31, v88, v31, v49
	global_load_dwordx4 v[80:83], v2, s[10:11] nt
	global_load_dwordx4 v[84:87], v3, s[10:11] nt
	global_load_dword v88, v4, s[16:17]
	s_add_u32 s10, s10, 0x40000
	s_addc_u32 s11, s11, 0
	s_add_u32 s16, s16, 64
	s_addc_u32 s17, s17, 0
	s_waitcnt vmcnt(35)
	v_cvt_pk_bf16_f32 v32, v16, v17
	v_cvt_pk_bf16_f32 v33, v18, v19
	v_cvt_pk_bf16_f32 v34, v20, v21
	v_cvt_pk_bf16_f32 v35, v22, v23
	global_store_dwordx4 v2, v[32:35], s[12:13] nt
	v_cvt_pk_bf16_f32 v36, v24, v25
	v_cvt_pk_bf16_f32 v37, v26, v27
	v_cvt_pk_bf16_f32 v38, v28, v29
	v_cvt_pk_bf16_f32 v39, v30, v31
	global_store_dwordx4 v3, v[36:39], s[12:13] nt
	s_add_u32 s12, s12, 0x40000
	s_addc_u32 s13, s13, 0
	v_lshlrev_b32_e32 v48, 16, v96
	v_and_b32_e32 v49, 0xffff0000, v96
	v_fma_f32 v16, v104, v16, v48
	v_fma_f32 v17, v104, v17, v49
	v_lshlrev_b32_e32 v48, 16, v97
	v_and_b32_e32 v49, 0xffff0000, v97
	v_fma_f32 v18, v104, v18, v48
	v_fma_f32 v19, v104, v19, v49
	v_lshlrev_b32_e32 v48, 16, v98
	v_and_b32_e32 v49, 0xffff0000, v98
	v_fma_f32 v20, v104, v20, v48
	v_fma_f32 v21, v104, v21, v49
	v_lshlrev_b32_e32 v48, 16, v99
	v_and_b32_e32 v49, 0xffff0000, v99
	v_fma_f32 v22, v104, v22, v48
	v_fma_f32 v23, v104, v23, v49
	v_lshlrev_b32_e32 v48, 16, v100
	v_and_b32_e32 v49, 0xffff0000, v100
	v_fma_f32 v24, v104, v24, v48
	v_fma_f32 v25, v104, v25, v49
	v_lshlrev_b32_e32 v48, 16, v101
	v_and_b32_e32 v49, 0xffff0000, v101
	v_fma_f32 v26, v104, v26, v48
	v_fma_f32 v27, v104, v27, v49
	v_lshlrev_b32_e32 v48, 16, v102
	v_and_b32_e32 v49, 0xffff0000, v102
	v_fma_f32 v28, v104, v28, v48
	v_fma_f32 v29, v104, v29, v49
	v_lshlrev_b32_e32 v48, 16, v103
	v_and_b32_e32 v49, 0xffff0000, v103
	v_fma_f32 v30, v104, v30, v48
	v_fma_f32 v31, v104, v31, v49
	global_load_dwordx4 v[96:99], v2, s[10:11] nt
	global_load_dwordx4 v[100:103], v3, s[10:11] nt
	global_load_dword v104, v4, s[16:17]
	s_add_u32 s10, s10, 0x40000
	s_addc_u32 s11, s11, 0
	s_add_u32 s16, s16, 64
	s_addc_u32 s17, s17, 0
	s_waitcnt vmcnt(35)
; __device__ __forceinline__ float bf2f(unsigned h) { return __uint_as_float(h << 16); }
; __device__ __forceinline__ unsigned pk2(float lo, float hi) { return pg8::cvt_pk_bf16(lo, hi); }
; __device__ __forceinline__ void b2_scan(const Ctx& C) {
;     ...
;         for (int k = 0; k < 4; ++k) {
;             const int c = 4 * g + k;
;             const float dd[8] = {d0[cur][k][0], d0[cur][k][1], d0[cur][k][2], d0[cur][k][3], d1[cur][k][0], d1[cur][k][1], d1[cur][k][2], d1[cur][k][3]};
; #pragma unroll
;             for (int j = 0; j < 2; ++j) {
;                 v4u o; o.x = pk2(run[j][0], run[j][1]); o.y = pk2(run[j][2], run[j][3]); o.z = pk2(run[j][4], run[j][5]); o.w = pk2(run[j][6], run[j][7]);
;                 __builtin_nontemporal_store(o, (v4u*)(base + (size_t)c * cstride + (size_t)j * vstride));
;                 const unsigned lw[4] = {loc[cur][k][j].x, loc[cur][k][j].y, loc[cur][k][j].z, loc[cur][k][j].w};
; #pragma unroll
;                 for (int q = 0; q < 4; ++q) {
;                     run[j][2 * q] = dd[2 * q] * run[j][2 * q] + bf2f(lw[q] & 0xffffu);
;                     run[j][2 * q + 1] = dd[2 * q + 1] * run[j][2 * q + 1] + __uint_as_float(lw[q] & 0xffff0000u);
;                 }
	v_cvt_pk_bf16_f32 v40, v16, v17
	v_cvt_pk_bf16_f32 v41, v18, v19
	v_cvt_pk_bf16_f32 v42, v20, v21
	v_cvt_pk_bf16_f32 v43, v22, v23
	global_store_dwordx4 v2, v[40:43], s[12:13] nt
	v_cvt_pk_bf16_f32 v44, v24, v25
	v_cvt_pk_bf16_f32 v45, v26, v27
	v_cvt_pk_bf16_f32 v46, v28, v29
	v_cvt_pk_bf16_f32 v47, v30, v31
	global_store_dwordx4 v3, v[44:47], s[12:13] nt
	s_add_u32 s12, s12, 0x40000
	s_addc_u32 s13, s13, 0
	v_lshlrev_b32_e32 v48, 16, v112
	v_and_b32_e32 v49, 0xffff0000, v112
	v_fma_f32 v16, v120, v16, v48
	v_fma_f32 v17, v120, v17, v49
	v_lshlrev_b32_e32 v48, 16, v113
	v_and_b32_e32 v49, 0xffff0000, v113
	v_fma_f32 v18, v120, v18, v48
	v_fma_f32 v19, v120, v19, v49
	v_lshlrev_b32_e32 v48, 16, v114
	v_and_b32_e32 v49, 0xffff0000, v114
	v_fma_f32 v20, v120, v20, v48
	v_fma_f32 v21, v120, v21, v49
	v_lshlrev_b32_e32 v48, 16, v115
	v_and_b32_e32 v49, 0xffff0000, v115
	v_fma_f32 v22, v120, v22, v48
	v_fma_f32 v23, v120, v23, v49
	v_lshlrev_b32_e32 v48, 16, v116
	v_and_b32_e32 v49, 0xffff0000, v116
	v_fma_f32 v24, v120, v24, v48
	v_fma_f32 v25, v120, v25, v49
	v_lshlrev_b32_e32 v48, 16, v117
	v_and_b32_e32 v49, 0xffff0000, v117
	v_fma_f32 v26, v120, v26, v48
	v_fma_f32 v27, v120, v27, v49
	v_lshlrev_b32_e32 v48, 16, v118
	v_and_b32_e32 v49, 0xffff0000, v118
	v_fma_f32 v28, v120, v28, v48
	v_fma_f32 v29, v120, v29, v49
	v_lshlrev_b32_e32 v48, 16, v119
	v_and_b32_e32 v49, 0xffff0000, v119
	v_fma_f32 v30, v120, v30, v48
	v_fma_f32 v31, v120, v31, v49
	global_load_dwordx4 v[112:115], v2, s[10:11] nt
	global_load_dwordx4 v[116:119], v3, s[10:11] nt
	global_load_dword v120, v4, s[16:17]
	s_add_u32 s10, s10, 0x40000
	s_addc_u32 s11, s11, 0
	s_add_u32 s16, s16, 64
	s_addc_u32 s17, s17, 0
	s_waitcnt vmcnt(35)
	v_cvt_pk_bf16_f32 v32, v16, v17
	v_cvt_pk_bf16_f32 v33, v18, v19
	v_cvt_pk_bf16_f32 v34, v20, v21
	v_cvt_pk_bf16_f32 v35, v22, v23
	global_store_dwordx4 v2, v[32:35], s[12:13] nt
	v_cvt_pk_bf16_f32 v36, v24, v25
	v_cvt_pk_bf16_f32 v37, v26, v27
	v_cvt_pk_bf16_f32 v38, v28, v29
	v_cvt_pk_bf16_f32 v39, v30, v31
	global_store_dwordx4 v3, v[36:39], s[12:13] nt
	s_add_u32 s12, s12, 0x40000
	s_addc_u32 s13, s13, 0
	v_lshlrev_b32_e32 v48, 16, v128
	v_and_b32_e32 v49, 0xffff0000, v128
	v_fma_f32 v16, v136, v16, v48
	v_fma_f32 v17, v136, v17, v49
	v_lshlrev_b32_e32 v48, 16, v129
	v_and_b32_e32 v49, 0xffff0000, v129
	v_fma_f32 v18, v136, v18, v48
	v_fma_f32 v19, v136, v19, v49
	v_lshlrev_b32_e32 v48, 16, v130
	v_and_b32_e32 v49, 0xffff0000, v130
	v_fma_f32 v20, v136, v20, v48
	v_fma_f32 v21, v136, v21, v49
	v_lshlrev_b32_e32 v48, 16, v131
	v_and_b32_e32 v49, 0xffff0000, v131
	v_fma_f32 v22, v136, v22, v48
	v_fma_f32 v23, v136, v23, v49
	v_lshlrev_b32_e32 v48, 16, v132
	v_and_b32_e32 v49, 0xffff0000, v132
	v_fma_f32 v24, v136, v24, v48
	v_fma_f32 v25, v136, v25, v49
	v_lshlrev_b32_e32 v48, 16, v133
	v_and_b32_e32 v49, 0xffff0000, v133
	v_fma_f32 v26, v136, v26, v48
	v_fma_f32 v27, v136, v27, v49
	v_lshlrev_b32_e32 v48, 16, v134
	v_and_b32_e32 v49, 0xffff0000, v134
	v_fma_f32 v28, v136, v28, v48
	v_fma_f32 v29, v136, v29, v49
	v_lshlrev_b32_e32 v48, 16, v135
	v_and_b32_e32 v49, 0xffff0000, v135
	v_fma_f32 v30, v136, v30, v48
	v_fma_f32 v31, v136, v31, v49
	global_load_dwordx4 v[128:131], v2, s[10:11] nt
	global_load_dwordx4 v[132:135], v3, s[10:11] nt
	global_load_dword v136, v4, s[16:17]
	s_add_u32 s10, s10, 0x40000
	s_addc_u32 s11, s11, 0
	s_add_u32 s16, s16, 64
	s_addc_u32 s17, s17, 0
	s_waitcnt vmcnt(35)
	v_cvt_pk_bf16_f32 v40, v16, v17
	v_cvt_pk_bf16_f32 v41, v18, v19
	v_cvt_pk_bf16_f32 v42, v20, v21
	v_cvt_pk_bf16_f32 v43, v22, v23
	global_store_dwordx4 v2, v[40:43], s[12:13] nt
	v_cvt_pk_bf16_f32 v44, v24, v25
	v_cvt_pk_bf16_f32 v45, v26, v27
	v_cvt_pk_bf16_f32 v46, v28, v29
	v_cvt_pk_bf16_f32 v47, v30, v31
	global_store_dwordx4 v3, v[44:47], s[12:13] nt
	s_add_u32 s12, s12, 0x40000
	s_addc_u32 s13, s13, 0
	v_lshlrev_b32_e32 v48, 16, v144
	v_and_b32_e32 v49, 0xffff0000, v144
	v_fma_f32 v16, v152, v16, v48
	v_fma_f32 v17, v152, v17, v49
	v_lshlrev_b32_e32 v48, 16, v145
	v_and_b32_e32 v49, 0xffff0000, v145
	v_fma_f32 v18, v152, v18, v48
	v_fma_f32 v19, v152, v19, v49
	v_lshlrev_b32_e32 v48, 16, v146
	v_and_b32_e32 v49, 0xffff0000, v146
	v_fma_f32 v20, v152, v20, v48
	v_fma_f32 v21, v152, v21, v49
	v_lshlrev_b32_e32 v48, 16, v147
	v_and_b32_e32 v49, 0xffff0000, v147
	v_fma_f32 v22, v152, v22, v48
	v_fma_f32 v23, v152, v23, v49
	v_lshlrev_b32_e32 v48, 16, v148
	v_and_b32_e32 v49, 0xffff0000, v148
	v_fma_f32 v24, v152, v24, v48
	v_fma_f32 v25, v152, v25, v49
	v_lshlrev_b32_e32 v48, 16, v149
	v_and_b32_e32 v49, 0xffff0000, v149
	v_fma_f32 v26, v152, v26, v48
	v_fma_f32 v27, v152, v27, v49
	v_lshlrev_b32_e32 v48, 16, v150
	v_and_b32_e32 v49, 0xffff0000, v150
	v_fma_f32 v28, v152, v28, v48
	v_fma_f32 v29, v152, v29, v49
	v_lshlrev_b32_e32 v48, 16, v151
	v_and_b32_e32 v49, 0xffff0000, v151
	v_fma_f32 v30, v152, v30, v48
	v_fma_f32 v31, v152, v31, v49
	global_load_dwordx4 v[144:147], v2, s[10:11] nt
	global_load_dwordx4 v[148:151], v3, s[10:11] nt
	global_load_dword v152, v4, s[16:17]
	s_add_u32 s10, s10, 0x40000
	s_addc_u32 s11, s11, 0
	s_add_u32 s16, s16, 64
	s_addc_u32 s17, s17, 0
	s_waitcnt vmcnt(35)
; __device__ __forceinline__ float bf2f(unsigned h) { return __uint_as_float(h << 16); }
; __device__ __forceinline__ unsigned pk2(float lo, float hi) { return pg8::cvt_pk_bf16(lo, hi); }
; __device__ __forceinline__ void b2_scan(const Ctx& C) {
;     ...
;         for (int k = 0; k < 4; ++k) {
;             const int c = 4 * g + k;
;             const float dd[8] = {d0[cur][k][0], d0[cur][k][1], d0[cur][k][2], d0[cur][k][3], d1[cur][k][0], d1[cur][k][1], d1[cur][k][2], d1[cur][k][3]};
; #pragma unroll
;             for (int j = 0; j < 2; ++j) {
;                 v4u o; o.x = pk2(run[j][0], run[j][1]); o.y = pk2(run[j][2], run[j][3]); o.z = pk2(run[j][4], run[j][5]); o.w = pk2(run[j][6], run[j][7]);
;                 __builtin_nontemporal_store(o, (v4u*)(base + (size_t)c * cstride + (size_t)j * vstride));
;                 const unsigned lw[4] = {loc[cur][k][j].x, loc[cur][k][j].y, loc[cur][k][j].z, loc[cur][k][j].w};
; #pragma unroll
;                 for (int q = 0; q < 4; ++q) {
;                     run[j][2 * q] = dd[2 * q] * run[j][2 * q] + bf2f(lw[q] & 0xffffu);
;                     run[j][2 * q + 1] = dd[2 * q + 1] * run[j][2 * q + 1] + __uint_as_float(lw[q] & 0xffff0000u);
;                 }
	v_cvt_pk_bf16_f32 v32, v16, v17
	v_cvt_pk_bf16_f32 v33, v18, v19
	v_cvt_pk_bf16_f32 v34, v20, v21
	v_cvt_pk_bf16_f32 v35, v22, v23
	global_store_dwordx4 v2, v[32:35], s[12:13] nt
	v_cvt_pk_bf16_f32 v36, v24, v25
	v_cvt_pk_bf16_f32 v37, v26, v27
	v_cvt_pk_bf16_f32 v38, v28, v29
	v_cvt_pk_bf16_f32 v39, v30, v31
	global_store_dwordx4 v3, v[36:39], s[12:13] nt
	s_add_u32 s12, s12, 0x40000
	s_addc_u32 s13, s13, 0
	v_lshlrev_b32_e32 v48, 16, v160
	v_and_b32_e32 v49, 0xffff0000, v160
	v_fma_f32 v16, v168, v16, v48
	v_fma_f32 v17, v168, v17, v49
	v_lshlrev_b32_e32 v48, 16, v161
	v_and_b32_e32 v49, 0xffff0000, v161
	v_fma_f32 v18, v168, v18, v48
	v_fma_f32 v19, v168, v19, v49
	v_lshlrev_b32_e32 v48, 16, v162
	v_and_b32_e32 v49, 0xffff0000, v162
	v_fma_f32 v20, v168, v20, v48
	v_fma_f32 v21, v168, v21, v49
	v_lshlrev_b32_e32 v48, 16, v163
	v_and_b32_e32 v49, 0xffff0000, v163
	v_fma_f32 v22, v168, v22, v48
	v_fma_f32 v23, v168, v23, v49
	v_lshlrev_b32_e32 v48, 16, v164
	v_and_b32_e32 v49, 0xffff0000, v164
	v_fma_f32 v24, v168, v24, v48
	v_fma_f32 v25, v168, v25, v49
	v_lshlrev_b32_e32 v48, 16, v165
	v_and_b32_e32 v49, 0xffff0000, v165
	v_fma_f32 v26, v168, v26, v48
	v_fma_f32 v27, v168, v27, v49
	v_lshlrev_b32_e32 v48, 16, v166
	v_and_b32_e32 v49, 0xffff0000, v166
	v_fma_f32 v28, v168, v28, v48
	v_fma_f32 v29, v168, v29, v49
	v_lshlrev_b32_e32 v48, 16, v167
	v_and_b32_e32 v49, 0xffff0000, v167
	v_fma_f32 v30, v168, v30, v48
	v_fma_f32 v31, v168, v31, v49
	global_load_dwordx4 v[160:163], v2, s[10:11] nt
	global_load_dwordx4 v[164:167], v3, s[10:11] nt
	global_load_dword v168, v4, s[16:17]
	s_add_u32 s10, s10, 0x40000
	s_addc_u32 s11, s11, 0
	s_add_u32 s16, s16, 64
	s_addc_u32 s17, s17, 0
	s_waitcnt vmcnt(35)
	v_cvt_pk_bf16_f32 v40, v16, v17
	v_cvt_pk_bf16_f32 v41, v18, v19
	v_cvt_pk_bf16_f32 v42, v20, v21
	v_cvt_pk_bf16_f32 v43, v22, v23
	global_store_dwordx4 v2, v[40:43], s[12:13] nt
	v_cvt_pk_bf16_f32 v44, v24, v25
	v_cvt_pk_bf16_f32 v45, v26, v27
	v_cvt_pk_bf16_f32 v46, v28, v29
	v_cvt_pk_bf16_f32 v47, v30, v31
	global_store_dwordx4 v3, v[44:47], s[12:13] nt
	s_add_u32 s12, s12, 0x40000
	s_addc_u32 s13, s13, 0
	v_lshlrev_b32_e32 v48, 16, v176
	v_and_b32_e32 v49, 0xffff0000, v176
	v_fma_f32 v16, v184, v16, v48
	v_fma_f32 v17, v184, v17, v49
	v_lshlrev_b32_e32 v48, 16, v177
	v_and_b32_e32 v49, 0xffff0000, v177
	v_fma_f32 v18, v184, v18, v48
	v_fma_f32 v19, v184, v19, v49
	v_lshlrev_b32_e32 v48, 16, v178
	v_and_b32_e32 v49, 0xffff0000, v178
	v_fma_f32 v20, v184, v20, v48
	v_fma_f32 v21, v184, v21, v49
	v_lshlrev_b32_e32 v48, 16, v179
	v_and_b32_e32 v49, 0xffff0000, v179
	v_fma_f32 v22, v184, v22, v48
	v_fma_f32 v23, v184, v23, v49
	v_lshlrev_b32_e32 v48, 16, v180
	v_and_b32_e32 v49, 0xffff0000, v180
	v_fma_f32 v24, v184, v24, v48
	v_fma_f32 v25, v184, v25, v49
	v_lshlrev_b32_e32 v48, 16, v181
	v_and_b32_e32 v49, 0xffff0000, v181
	v_fma_f32 v26, v184, v26, v48
	v_fma_f32 v27, v184, v27, v49
	v_lshlrev_b32_e32 v48, 16, v182
	v_and_b32_e32 v49, 0xffff0000, v182
	v_fma_f32 v28, v184, v28, v48
	v_fma_f32 v29, v184, v29, v49
	v_lshlrev_b32_e32 v48, 16, v183
	v_and_b32_e32 v49, 0xffff0000, v183
	v_fma_f32 v30, v184, v30, v48
	v_fma_f32 v31, v184, v31, v49
	global_load_dwordx4 v[176:179], v2, s[10:11] nt
	global_load_dwordx4 v[180:183], v3, s[10:11] nt
	global_load_dword v184, v4, s[16:17]
	s_add_u32 s10, s10, 0x40000
	s_addc_u32 s11, s11, 0
	s_add_u32 s16, s16, 64
	s_addc_u32 s17, s17, 0
	s_waitcnt vmcnt(35)
	v_cvt_pk_bf16_f32 v32, v16, v17
	v_cvt_pk_bf16_f32 v33, v18, v19
	v_cvt_pk_bf16_f32 v34, v20, v21
	v_cvt_pk_bf16_f32 v35, v22, v23
	global_store_dwordx4 v2, v[32:35], s[12:13] nt
	v_cvt_pk_bf16_f32 v36, v24, v25
	v_cvt_pk_bf16_f32 v37, v26, v27
	v_cvt_pk_bf16_f32 v38, v28, v29
	v_cvt_pk_bf16_f32 v39, v30, v31
	global_store_dwordx4 v3, v[36:39], s[12:13] nt
	s_add_u32 s12, s12, 0x40000
	s_addc_u32 s13, s13, 0
	v_lshlrev_b32_e32 v48, 16, v64
	v_and_b32_e32 v49, 0xffff0000, v64
	v_fma_f32 v16, v72, v16, v48
	v_fma_f32 v17, v72, v17, v49
	v_lshlrev_b32_e32 v48, 16, v65
	v_and_b32_e32 v49, 0xffff0000, v65
	v_fma_f32 v18, v72, v18, v48
	v_fma_f32 v19, v72, v19, v49
	v_lshlrev_b32_e32 v48, 16, v66
	v_and_b32_e32 v49, 0xffff0000, v66
	v_fma_f32 v20, v72, v20, v48
	v_fma_f32 v21, v72, v21, v49
	v_lshlrev_b32_e32 v48, 16, v67
	v_and_b32_e32 v49, 0xffff0000, v67
	v_fma_f32 v22, v72, v22, v48
	v_fma_f32 v23, v72, v23, v49
	v_lshlrev_b32_e32 v48, 16, v68
	v_and_b32_e32 v49, 0xffff0000, v68
	v_fma_f32 v24, v72, v24, v48
	v_fma_f32 v25, v72, v25, v49
	v_lshlrev_b32_e32 v48, 16, v69
	v_and_b32_e32 v49, 0xffff0000, v69
	v_fma_f32 v26, v72, v26, v48
	v_fma_f32 v27, v72, v27, v49
	v_lshlrev_b32_e32 v48, 16, v70
	v_and_b32_e32 v49, 0xffff0000, v70
	v_fma_f32 v28, v72, v28, v48
	v_fma_f32 v29, v72, v29, v49
	v_lshlrev_b32_e32 v48, 16, v71
	v_and_b32_e32 v49, 0xffff0000, v71
	v_fma_f32 v30, v72, v30, v48
	v_fma_f32 v31, v72, v31, v49
	global_load_dwordx4 v[64:67], v2, s[10:11] nt
	global_load_dwordx4 v[68:71], v3, s[10:11] nt
	global_load_dword v72, v4, s[16:17]
	s_add_u32 s10, s10, 0x40000
	s_addc_u32 s11, s11, 0
	s_add_u32 s16, s16, 64
	s_addc_u32 s17, s17, 0
	s_waitcnt vmcnt(35)
; __device__ __forceinline__ float bf2f(unsigned h) { return __uint_as_float(h << 16); }
; __device__ __forceinline__ unsigned pk2(float lo, float hi) { return pg8::cvt_pk_bf16(lo, hi); }
; __device__ __forceinline__ void b2_scan(const Ctx& C) {
;     ...
;         for (int k = 0; k < 4; ++k) {
;             const int c = 4 * g + k;
;             const float dd[8] = {d0[cur][k][0], d0[cur][k][1], d0[cur][k][2], d0[cur][k][3], d1[cur][k][0], d1[cur][k][1], d1[cur][k][2], d1[cur][k][3]};
; #pragma unroll
;             for (int j = 0; j < 2; ++j) {
;                 v4u o; o.x = pk2(run[j][0], run[j][1]); o.y = pk2(run[j][2], run[j][3]); o.z = pk2(run[j][4], run[j][5]); o.w = pk2(run[j][6], run[j][7]);
;                 __builtin_nontemporal_store(o, (v4u*)(base + (size_t)c * cstride + (size_t)j * vstride));
;                 const unsigned lw[4] = {loc[cur][k][j].x, loc[cur][k][j].y, loc[cur][k][j].z, loc[cur][k][j].w};
; #pragma unroll
;                 for (int q = 0; q < 4; ++q) {
;                     run[j][2 * q] = dd[2 * q] * run[j][2 * q] + bf2f(lw[q] & 0xffffu);
;                     run[j][2 * q + 1] = dd[2 * q + 1] * run[j][2 * q + 1] + __uint_as_float(lw[q] & 0xffff0000u);
;                 }
	v_cvt_pk_bf16_f32 v40, v16, v17
	v_cvt_pk_bf16_f32 v41, v18, v19
	v_cvt_pk_bf16_f32 v42, v20, v21
	v_cvt_pk_bf16_f32 v43, v22, v23
	global_store_dwordx4 v2, v[40:43], s[12:13] nt
	v_cvt_pk_bf16_f32 v44, v24, v25
	v_cvt_pk_bf16_f32 v45, v26, v27
	v_cvt_pk_bf16_f32 v46, v28, v29
	v_cvt_pk_bf16_f32 v47, v30, v31
	global_store_dwordx4 v3, v[44:47], s[12:13] nt
	s_add_u32 s12, s12, 0x40000
	s_addc_u32 s13, s13, 0
	v_lshlrev_b32_e32 v48, 16, v80
	v_and_b32_e32 v49, 0xffff0000, v80
	v_fma_f32 v16, v88, v16, v48
	v_fma_f32 v17, v88, v17, v49
	v_lshlrev_b32_e32 v48, 16, v81
	v_and_b32_e32 v49, 0xffff0000, v81
	v_fma_f32 v18, v88, v18, v48
	v_fma_f32 v19, v88, v19, v49
	v_lshlrev_b32_e32 v48, 16, v82
	v_and_b32_e32 v49, 0xffff0000, v82
	v_fma_f32 v20, v88, v20, v48
	v_fma_f32 v21, v88, v21, v49
	v_lshlrev_b32_e32 v48, 16, v83
	v_and_b32_e32 v49, 0xffff0000, v83
	v_fma_f32 v22, v88, v22, v48
	v_fma_f32 v23, v88, v23, v49
	v_lshlrev_b32_e32 v48, 16, v84
	v_and_b32_e32 v49, 0xffff0000, v84
	v_fma_f32 v24, v88, v24, v48
	v_fma_f32 v25, v88, v25, v49
	v_lshlrev_b32_e32 v48, 16, v85
	v_and_b32_e32 v49, 0xffff0000, v85
	v_fma_f32 v26, v88, v26, v48
	v_fma_f32 v27, v88, v27, v49
	v_lshlrev_b32_e32 v48, 16, v86
	v_and_b32_e32 v49, 0xffff0000, v86
	v_fma_f32 v28, v88, v28, v48
	v_fma_f32 v29, v88, v29, v49
	v_lshlrev_b32_e32 v48, 16, v87
	v_and_b32_e32 v49, 0xffff0000, v87
	v_fma_f32 v30, v88, v30, v48
	v_fma_f32 v31, v88, v31, v49
	global_load_dwordx4 v[80:83], v2, s[10:11] nt
	global_load_dwordx4 v[84:87], v3, s[10:11] nt
	global_load_dword v88, v4, s[16:17]
	s_add_u32 s10, s10, 0x40000
	s_addc_u32 s11, s11, 0
	s_add_u32 s16, s16, 64
	s_addc_u32 s17, s17, 0
	s_waitcnt vmcnt(35)
	v_cvt_pk_bf16_f32 v32, v16, v17
	v_cvt_pk_bf16_f32 v33, v18, v19
	v_cvt_pk_bf16_f32 v34, v20, v21
	v_cvt_pk_bf16_f32 v35, v22, v23
	global_store_dwordx4 v2, v[32:35], s[12:13] nt
	v_cvt_pk_bf16_f32 v36, v24, v25
	v_cvt_pk_bf16_f32 v37, v26, v27
	v_cvt_pk_bf16_f32 v38, v28, v29
	v_cvt_pk_bf16_f32 v39, v30, v31
	global_store_dwordx4 v3, v[36:39], s[12:13] nt
	s_add_u32 s12, s12, 0x40000
	s_addc_u32 s13, s13, 0
	v_lshlrev_b32_e32 v48, 16, v96
	v_and_b32_e32 v49, 0xffff0000, v96
	v_fma_f32 v16, v104, v16, v48
	v_fma_f32 v17, v104, v17, v49
	v_lshlrev_b32_e32 v48, 16, v97
	v_and_b32_e32 v49, 0xffff0000, v97
	v_fma_f32 v18, v104, v18, v48
	v_fma_f32 v19, v104, v19, v49
	v_lshlrev_b32_e32 v48, 16, v98
	v_and_b32_e32 v49, 0xffff0000, v98
	v_fma_f32 v20, v104, v20, v48
	v_fma_f32 v21, v104, v21, v49
	v_lshlrev_b32_e32 v48, 16, v99
	v_and_b32_e32 v49, 0xffff0000, v99
	v_fma_f32 v22, v104, v22, v48
	v_fma_f32 v23, v104, v23, v49
	v_lshlrev_b32_e32 v48, 16, v100
	v_and_b32_e32 v49, 0xffff0000, v100
	v_fma_f32 v24, v104, v24, v48
	v_fma_f32 v25, v104, v25, v49
	v_lshlrev_b32_e32 v48, 16, v101
	v_and_b32_e32 v49, 0xffff0000, v101
	v_fma_f32 v26, v104, v26, v48
	v_fma_f32 v27, v104, v27, v49
	v_lshlrev_b32_e32 v48, 16, v102
	v_and_b32_e32 v49, 0xffff0000, v102
	v_fma_f32 v28, v104, v28, v48
	v_fma_f32 v29, v104, v29, v49
	v_lshlrev_b32_e32 v48, 16, v103
	v_and_b32_e32 v49, 0xffff0000, v103
	v_fma_f32 v30, v104, v30, v48
	v_fma_f32 v31, v104, v31, v49
	global_load_dwordx4 v[96:99], v2, s[10:11] nt
	global_load_dwordx4 v[100:103], v3, s[10:11] nt
	global_load_dword v104, v4, s[16:17]
	s_add_u32 s10, s10, 0x40000
	s_addc_u32 s11, s11, 0
	s_add_u32 s16, s16, 64
	s_addc_u32 s17, s17, 0
	s_waitcnt vmcnt(35)
	v_cvt_pk_bf16_f32 v40, v16, v17
	v_cvt_pk_bf16_f32 v41, v18, v19
	v_cvt_pk_bf16_f32 v42, v20, v21
	v_cvt_pk_bf16_f32 v43, v22, v23
	global_store_dwordx4 v2, v[40:43], s[12:13] nt
	v_cvt_pk_bf16_f32 v44, v24, v25
	v_cvt_pk_bf16_f32 v45, v26, v27
	v_cvt_pk_bf16_f32 v46, v28, v29
	v_cvt_pk_bf16_f32 v47, v30, v31
	global_store_dwordx4 v3, v[44:47], s[12:13] nt
	s_add_u32 s12, s12, 0x40000
	s_addc_u32 s13, s13, 0
	v_lshlrev_b32_e32 v48, 16, v112
	v_and_b32_e32 v49, 0xffff0000, v112
	v_fma_f32 v16, v120, v16, v48
	v_fma_f32 v17, v120, v17, v49
	v_lshlrev_b32_e32 v48, 16, v113
	v_and_b32_e32 v49, 0xffff0000, v113
	v_fma_f32 v18, v120, v18, v48
	v_fma_f32 v19, v120, v19, v49
	v_lshlrev_b32_e32 v48, 16, v114
	v_and_b32_e32 v49, 0xffff0000, v114
	v_fma_f32 v20, v120, v20, v48
	v_fma_f32 v21, v120, v21, v49
	v_lshlrev_b32_e32 v48, 16, v115
	v_and_b32_e32 v49, 0xffff0000, v115
	v_fma_f32 v22, v120, v22, v48
	v_fma_f32 v23, v120, v23, v49
	v_lshlrev_b32_e32 v48, 16, v116
	v_and_b32_e32 v49, 0xffff0000, v116
	v_fma_f32 v24, v120, v24, v48
	v_fma_f32 v25, v120, v25, v49
	v_lshlrev_b32_e32 v48, 16, v117
	v_and_b32_e32 v49, 0xffff0000, v117
	v_fma_f32 v26, v120, v26, v48
	v_fma_f32 v27, v120, v27, v49
	v_lshlrev_b32_e32 v48, 16, v118
	v_and_b32_e32 v49, 0xffff0000, v118
	v_fma_f32 v28, v120, v28, v48
	v_fma_f32 v29, v120, v29, v49
	v_lshlrev_b32_e32 v48, 16, v119
	v_and_b32_e32 v49, 0xffff0000, v119
	v_fma_f32 v30, v120, v30, v48
	v_fma_f32 v31, v120, v31, v49
	global_load_dwordx4 v[112:115], v2, s[10:11] nt
	global_load_dwordx4 v[116:119], v3, s[10:11] nt
	global_load_dword v120, v4, s[16:17]
	s_add_u32 s10, s10, 0x40000
	s_addc_u32 s11, s11, 0
	s_add_u32 s16, s16, 64
	s_addc_u32 s17, s17, 0
	s_waitcnt vmcnt(35)
; __device__ __forceinline__ float bf2f(unsigned h) { return __uint_as_float(h << 16); }
; __device__ __forceinline__ unsigned pk2(float lo, float hi) { return pg8::cvt_pk_bf16(lo, hi); }
; __device__ __forceinline__ void b2_scan(const Ctx& C) {
;     ...
;         for (int k = 0; k < 4; ++k) {
;             const int c = 4 * g + k;
;             const float dd[8] = {d0[cur][k][0], d0[cur][k][1], d0[cur][k][2], d0[cur][k][3], d1[cur][k][0], d1[cur][k][1], d1[cur][k][2], d1[cur][k][3]};
; #pragma unroll
;             for (int j = 0; j < 2; ++j) {
;                 v4u o; o.x = pk2(run[j][0], run[j][1]); o.y = pk2(run[j][2], run[j][3]); o.z = pk2(run[j][4], run[j][5]); o.w = pk2(run[j][6], run[j][7]);
;                 __builtin_nontemporal_store(o, (v4u*)(base + (size_t)c * cstride + (size_t)j * vstride));
;                 const unsigned lw[4] = {loc[cur][k][j].x, loc[cur][k][j].y, loc[cur][k][j].z, loc[cur][k][j].w};
; #pragma unroll
;                 for (int q = 0; q < 4; ++q) {
;                     run[j][2 * q] = dd[2 * q] * run[j][2 * q] + bf2f(lw[q] & 0xffffu);
;                     run[j][2 * q + 1] = dd[2 * q + 1] * run[j][2 * q + 1] + __uint_as_float(lw[q] & 0xffff0000u);
;                 }
	v_cvt_pk_bf16_f32 v32, v16, v17
	v_cvt_pk_bf16_f32 v33, v18, v19
	v_cvt_pk_bf16_f32 v34, v20, v21
	v_cvt_pk_bf16_f32 v35, v22, v23
	global_store_dwordx4 v2, v[32:35], s[12:13] nt
	v_cvt_pk_bf16_f32 v36, v24, v25
	v_cvt_pk_bf16_f32 v37, v26, v27
	v_cvt_pk_bf16_f32 v38, v28, v29
	v_cvt_pk_bf16_f32 v39, v30, v31
	global_store_dwordx4 v3, v[36:39], s[12:13] nt
	s_add_u32 s12, s12, 0x40000
	s_addc_u32 s13, s13, 0
	v_lshlrev_b32_e32 v48, 16, v128
	v_and_b32_e32 v49, 0xffff0000, v128
	v_fma_f32 v16, v136, v16, v48
	v_fma_f32 v17, v136, v17, v49
	v_lshlrev_b32_e32 v48, 16, v129
	v_and_b32_e32 v49, 0xffff0000, v129
	v_fma_f32 v18, v136, v18, v48
	v_fma_f32 v19, v136, v19, v49
	v_lshlrev_b32_e32 v48, 16, v130
	v_and_b32_e32 v49, 0xffff0000, v130
	v_fma_f32 v20, v136, v20, v48
	v_fma_f32 v21, v136, v21, v49
	v_lshlrev_b32_e32 v48, 16, v131
	v_and_b32_e32 v49, 0xffff0000, v131
	v_fma_f32 v22, v136, v22, v48
	v_fma_f32 v23, v136, v23, v49
	v_lshlrev_b32_e32 v48, 16, v132
	v_and_b32_e32 v49, 0xffff0000, v132
	v_fma_f32 v24, v136, v24, v48
	v_fma_f32 v25, v136, v25, v49
	v_lshlrev_b32_e32 v48, 16, v133
	v_and_b32_e32 v49, 0xffff0000, v133
	v_fma_f32 v26, v136, v26, v48
	v_fma_f32 v27, v136, v27, v49
	v_lshlrev_b32_e32 v48, 16, v134
	v_and_b32_e32 v49, 0xffff0000, v134
	v_fma_f32 v28, v136, v28, v48
	v_fma_f32 v29, v136, v29, v49
	v_lshlrev_b32_e32 v48, 16, v135
	v_and_b32_e32 v49, 0xffff0000, v135
	v_fma_f32 v30, v136, v30, v48
	v_fma_f32 v31, v136, v31, v49
	global_load_dwordx4 v[128:131], v2, s[10:11] nt
	global_load_dwordx4 v[132:135], v3, s[10:11] nt
	global_load_dword v136, v4, s[16:17]
	s_add_u32 s10, s10, 0x40000
	s_addc_u32 s11, s11, 0
	s_add_u32 s16, s16, 64
	s_addc_u32 s17, s17, 0
	s_waitcnt vmcnt(35)
	v_cvt_pk_bf16_f32 v40, v16, v17
	v_cvt_pk_bf16_f32 v41, v18, v19
	v_cvt_pk_bf16_f32 v42, v20, v21
	v_cvt_pk_bf16_f32 v43, v22, v23
	global_store_dwordx4 v2, v[40:43], s[12:13] nt
	v_cvt_pk_bf16_f32 v44, v24, v25
	v_cvt_pk_bf16_f32 v45, v26, v27
	v_cvt_pk_bf16_f32 v46, v28, v29
	v_cvt_pk_bf16_f32 v47, v30, v31
	global_store_dwordx4 v3, v[44:47], s[12:13] nt
	s_add_u32 s12, s12, 0x40000
	s_addc_u32 s13, s13, 0
	v_lshlrev_b32_e32 v48, 16, v144
	v_and_b32_e32 v49, 0xffff0000, v144
	v_fma_f32 v16, v152, v16, v48
	v_fma_f32 v17, v152, v17, v49
	v_lshlrev_b32_e32 v48, 16, v145
	v_and_b32_e32 v49, 0xffff0000, v145
	v_fma_f32 v18, v152, v18, v48
	v_fma_f32 v19, v152, v19, v49
	v_lshlrev_b32_e32 v48, 16, v146
	v_and_b32_e32 v49, 0xffff0000, v146
	v_fma_f32 v20, v152, v20, v48
	v_fma_f32 v21, v152, v21, v49
	v_lshlrev_b32_e32 v48, 16, v147
	v_and_b32_e32 v49, 0xffff0000, v147
	v_fma_f32 v22, v152, v22, v48
	v_fma_f32 v23, v152, v23, v49
	v_lshlrev_b32_e32 v48, 16, v148
	v_and_b32_e32 v49, 0xffff0000, v148
	v_fma_f32 v24, v152, v24, v48
	v_fma_f32 v25, v152, v25, v49
	v_lshlrev_b32_e32 v48, 16, v149
	v_and_b32_e32 v49, 0xffff0000, v149
	v_fma_f32 v26, v152, v26, v48
	v_fma_f32 v27, v152, v27, v49
	v_lshlrev_b32_e32 v48, 16, v150
	v_and_b32_e32 v49, 0xffff0000, v150
	v_fma_f32 v28, v152, v28, v48
	v_fma_f32 v29, v152, v29, v49
	v_lshlrev_b32_e32 v48, 16, v151
	v_and_b32_e32 v49, 0xffff0000, v151
	v_fma_f32 v30, v152, v30, v48
	v_fma_f32 v31, v152, v31, v49
	global_load_dwordx4 v[144:147], v2, s[10:11] nt
	global_load_dwordx4 v[148:151], v3, s[10:11] nt
	global_load_dword v152, v4, s[16:17]
	s_add_u32 s10, s10, 0x40000
	s_addc_u32 s11, s11, 0
	s_add_u32 s16, s16, 64
	s_addc_u32 s17, s17, 0
	s_waitcnt vmcnt(35)
	v_cvt_pk_bf16_f32 v32, v16, v17
	v_cvt_pk_bf16_f32 v33, v18, v19
	v_cvt_pk_bf16_f32 v34, v20, v21
	v_cvt_pk_bf16_f32 v35, v22, v23
	global_store_dwordx4 v2, v[32:35], s[12:13] nt
	v_cvt_pk_bf16_f32 v36, v24, v25
	v_cvt_pk_bf16_f32 v37, v26, v27
	v_cvt_pk_bf16_f32 v38, v28, v29
	v_cvt_pk_bf16_f32 v39, v30, v31
	global_store_dwordx4 v3, v[36:39], s[12:13] nt
	s_add_u32 s12, s12, 0x40000
	s_addc_u32 s13, s13, 0
	v_lshlrev_b32_e32 v48, 16, v160
	v_and_b32_e32 v49, 0xffff0000, v160
	v_fma_f32 v16, v168, v16, v48
	v_fma_f32 v17, v168, v17, v49
	v_lshlrev_b32_e32 v48, 16, v161
	v_and_b32_e32 v49, 0xffff0000, v161
	v_fma_f32 v18, v168, v18, v48
	v_fma_f32 v19, v168, v19, v49
	v_lshlrev_b32_e32 v48, 16, v162
	v_and_b32_e32 v49, 0xffff0000, v162
	v_fma_f32 v20, v168, v20, v48
	v_fma_f32 v21, v168, v21, v49
	v_lshlrev_b32_e32 v48, 16, v163
	v_and_b32_e32 v49, 0xffff0000, v163
	v_fma_f32 v22, v168, v22, v48
	v_fma_f32 v23, v168, v23, v49
	v_lshlrev_b32_e32 v48, 16, v164
	v_and_b32_e32 v49, 0xffff0000, v164
	v_fma_f32 v24, v168, v24, v48
	v_fma_f32 v25, v168, v25, v49
	v_lshlrev_b32_e32 v48, 16, v165
	v_and_b32_e32 v49, 0xffff0000, v165
	v_fma_f32 v26, v168, v26, v48
	v_fma_f32 v27, v168, v27, v49
	v_lshlrev_b32_e32 v48, 16, v166
	v_and_b32_e32 v49, 0xffff0000, v166
	v_fma_f32 v28, v168, v28, v48
	v_fma_f32 v29, v168, v29, v49
	v_lshlrev_b32_e32 v48, 16, v167
	v_and_b32_e32 v49, 0xffff0000, v167
	v_fma_f32 v30, v168, v30, v48
	v_fma_f32 v31, v168, v31, v49
	global_load_dwordx4 v[160:163], v2, s[10:11] nt
	global_load_dwordx4 v[164:167], v3, s[10:11] nt
	global_load_dword v168, v4, s[16:17]
	s_add_u32 s10, s10, 0x40000
	s_addc_u32 s11, s11, 0
	s_add_u32 s16, s16, 64
	s_addc_u32 s17, s17, 0
	s_waitcnt vmcnt(35)
; __device__ __forceinline__ float bf2f(unsigned h) { return __uint_as_float(h << 16); }
; __device__ __forceinline__ unsigned pk2(float lo, float hi) { return pg8::cvt_pk_bf16(lo, hi); }
; __device__ __forceinline__ void b2_scan(const Ctx& C) {
;     ...
;         for (int k = 0; k < 4; ++k) {
;             const int c = 4 * g + k;
;             const float dd[8] = {d0[cur][k][0], d0[cur][k][1], d0[cur][k][2], d0[cur][k][3], d1[cur][k][0], d1[cur][k][1], d1[cur][k][2], d1[cur][k][3]};
; #pragma unroll
;             for (int j = 0; j < 2; ++j) {
;                 v4u o; o.x = pk2(run[j][0], run[j][1]); o.y = pk2(run[j][2], run[j][3]); o.z = pk2(run[j][4], run[j][5]); o.w = pk2(run[j][6], run[j][7]);
;                 __builtin_nontemporal_store(o, (v4u*)(base + (size_t)c * cstride + (size_t)j * vstride));
;                 const unsigned lw[4] = {loc[cur][k][j].x, loc[cur][k][j].y, loc[cur][k][j].z, loc[cur][k][j].w};
; #pragma unroll
;                 for (int q = 0; q < 4; ++q) {
;                     run[j][2 * q] = dd[2 * q] * run[j][2 * q] + bf2f(lw[q] & 0xffffu);
;                     run[j][2 * q + 1] = dd[2 * q + 1] * run[j][2 * q + 1] + __uint_as_float(lw[q] & 0xffff0000u);
;                 }
	v_cvt_pk_bf16_f32 v40, v16, v17
	v_cvt_pk_bf16_f32 v41, v18, v19
	v_cvt_pk_bf16_f32 v42, v20, v21
	v_cvt_pk_bf16_f32 v43, v22, v23
	global_store_dwordx4 v2, v[40:43], s[12:13] nt
	v_cvt_pk_bf16_f32 v44, v24, v25
	v_cvt_pk_bf16_f32 v45, v26, v27
	v_cvt_pk_bf16_f32 v46, v28, v29
	v_cvt_pk_bf16_f32 v47, v30, v31
	global_store_dwordx4 v3, v[44:47], s[12:13] nt
	s_add_u32 s12, s12, 0x40000
	s_addc_u32 s13, s13, 0
	v_lshlrev_b32_e32 v48, 16, v176
	v_and_b32_e32 v49, 0xffff0000, v176
	v_fma_f32 v16, v184, v16, v48
	v_fma_f32 v17, v184, v17, v49
	v_lshlrev_b32_e32 v48, 16, v177
	v_and_b32_e32 v49, 0xffff0000, v177
	v_fma_f32 v18, v184, v18, v48
	v_fma_f32 v19, v184, v19, v49
	v_lshlrev_b32_e32 v48, 16, v178
	v_and_b32_e32 v49, 0xffff0000, v178
	v_fma_f32 v20, v184, v20, v48
	v_fma_f32 v21, v184, v21, v49
	v_lshlrev_b32_e32 v48, 16, v179
	v_and_b32_e32 v49, 0xffff0000, v179
	v_fma_f32 v22, v184, v22, v48
	v_fma_f32 v23, v184, v23, v49
	v_lshlrev_b32_e32 v48, 16, v180
	v_and_b32_e32 v49, 0xffff0000, v180
	v_fma_f32 v24, v184, v24, v48
	v_fma_f32 v25, v184, v25, v49
	v_lshlrev_b32_e32 v48, 16, v181
	v_and_b32_e32 v49, 0xffff0000, v181
	v_fma_f32 v26, v184, v26, v48
	v_fma_f32 v27, v184, v27, v49
	v_lshlrev_b32_e32 v48, 16, v182
	v_and_b32_e32 v49, 0xffff0000, v182
	v_fma_f32 v28, v184, v28, v48
	v_fma_f32 v29, v184, v29, v49
	v_lshlrev_b32_e32 v48, 16, v183
	v_and_b32_e32 v49, 0xffff0000, v183
	v_fma_f32 v30, v184, v30, v48
	v_fma_f32 v31, v184, v31, v49
	global_load_dwordx4 v[176:179], v2, s[10:11] nt
	global_load_dwordx4 v[180:183], v3, s[10:11] nt
	global_load_dword v184, v4, s[16:17]
	s_add_u32 s10, s10, 0x40000
	s_addc_u32 s11, s11, 0
	s_add_u32 s16, s16, 64
	s_addc_u32 s17, s17, 0
	s_waitcnt vmcnt(35)
	v_cvt_pk_bf16_f32 v32, v16, v17
	v_cvt_pk_bf16_f32 v33, v18, v19
	v_cvt_pk_bf16_f32 v34, v20, v21
	v_cvt_pk_bf16_f32 v35, v22, v23
	global_store_dwordx4 v2, v[32:35], s[12:13] nt
	v_cvt_pk_bf16_f32 v36, v24, v25
	v_cvt_pk_bf16_f32 v37, v26, v27
	v_cvt_pk_bf16_f32 v38, v28, v29
	v_cvt_pk_bf16_f32 v39, v30, v31
	global_store_dwordx4 v3, v[36:39], s[12:13] nt
	s_add_u32 s12, s12, 0x40000
	s_addc_u32 s13, s13, 0
	v_lshlrev_b32_e32 v48, 16, v64
	v_and_b32_e32 v49, 0xffff0000, v64
	v_fma_f32 v16, v72, v16, v48
	v_fma_f32 v17, v72, v17, v49
	v_lshlrev_b32_e32 v48, 16, v65
	v_and_b32_e32 v49, 0xffff0000, v65
	v_fma_f32 v18, v72, v18, v48
	v_fma_f32 v19, v72, v19, v49
	v_lshlrev_b32_e32 v48, 16, v66
	v_and_b32_e32 v49, 0xffff0000, v66
	v_fma_f32 v20, v72, v20, v48
	v_fma_f32 v21, v72, v21, v49
	v_lshlrev_b32_e32 v48, 16, v67
	v_and_b32_e32 v49, 0xffff0000, v67
	v_fma_f32 v22, v72, v22, v48
	v_fma_f32 v23, v72, v23, v49
	v_lshlrev_b32_e32 v48, 16, v68
	v_and_b32_e32 v49, 0xffff0000, v68
	v_fma_f32 v24, v72, v24, v48
	v_fma_f32 v25, v72, v25, v49
	v_lshlrev_b32_e32 v48, 16, v69
	v_and_b32_e32 v49, 0xffff0000, v69
	v_fma_f32 v26, v72, v26, v48
	v_fma_f32 v27, v72, v27, v49
	v_lshlrev_b32_e32 v48, 16, v70
	v_and_b32_e32 v49, 0xffff0000, v70
	v_fma_f32 v28, v72, v28, v48
	v_fma_f32 v29, v72, v29, v49
	v_lshlrev_b32_e32 v48, 16, v71
	v_and_b32_e32 v49, 0xffff0000, v71
	v_fma_f32 v30, v72, v30, v48
	v_fma_f32 v31, v72, v31, v49
	s_waitcnt vmcnt(32)
	v_cvt_pk_bf16_f32 v40, v16, v17
	v_cvt_pk_bf16_f32 v41, v18, v19
	v_cvt_pk_bf16_f32 v42, v20, v21
	v_cvt_pk_bf16_f32 v43, v22, v23
	global_store_dwordx4 v2, v[40:43], s[12:13] nt
	v_cvt_pk_bf16_f32 v44, v24, v25
	v_cvt_pk_bf16_f32 v45, v26, v27
	v_cvt_pk_bf16_f32 v46, v28, v29
	v_cvt_pk_bf16_f32 v47, v30, v31
	global_store_dwordx4 v3, v[44:47], s[12:13] nt
	s_add_u32 s12, s12, 0x40000
	s_addc_u32 s13, s13, 0
	v_lshlrev_b32_e32 v48, 16, v80
	v_and_b32_e32 v49, 0xffff0000, v80
	v_fma_f32 v16, v88, v16, v48
	v_fma_f32 v17, v88, v17, v49
	v_lshlrev_b32_e32 v48, 16, v81
	v_and_b32_e32 v49, 0xffff0000, v81
	v_fma_f32 v18, v88, v18, v48
	v_fma_f32 v19, v88, v19, v49
	v_lshlrev_b32_e32 v48, 16, v82
	v_and_b32_e32 v49, 0xffff0000, v82
	v_fma_f32 v20, v88, v20, v48
	v_fma_f32 v21, v88, v21, v49
	v_lshlrev_b32_e32 v48, 16, v83
	v_and_b32_e32 v49, 0xffff0000, v83
	v_fma_f32 v22, v88, v22, v48
	v_fma_f32 v23, v88, v23, v49
	v_lshlrev_b32_e32 v48, 16, v84
	v_and_b32_e32 v49, 0xffff0000, v84
	v_fma_f32 v24, v88, v24, v48
	v_fma_f32 v25, v88, v25, v49
	v_lshlrev_b32_e32 v48, 16, v85
	v_and_b32_e32 v49, 0xffff0000, v85
	v_fma_f32 v26, v88, v26, v48
	v_fma_f32 v27, v88, v27, v49
	v_lshlrev_b32_e32 v48, 16, v86
	v_and_b32_e32 v49, 0xffff0000, v86
	v_fma_f32 v28, v88, v28, v48
	v_fma_f32 v29, v88, v29, v49
	v_lshlrev_b32_e32 v48, 16, v87
	v_and_b32_e32 v49, 0xffff0000, v87
	v_fma_f32 v30, v88, v30, v48
	v_fma_f32 v31, v88, v31, v49
	s_waitcnt vmcnt(29)
	v_cvt_pk_bf16_f32 v32, v16, v17
	v_cvt_pk_bf16_f32 v33, v18, v19
	v_cvt_pk_bf16_f32 v34, v20, v21
	v_cvt_pk_bf16_f32 v35, v22, v23
	global_store_dwordx4 v2, v[32:35], s[12:13] nt
	v_cvt_pk_bf16_f32 v36, v24, v25
	v_cvt_pk_bf16_f32 v37, v26, v27
	v_cvt_pk_bf16_f32 v38, v28, v29
	v_cvt_pk_bf16_f32 v39, v30, v31
	global_store_dwordx4 v3, v[36:39], s[12:13] nt
	s_add_u32 s12, s12, 0x40000
	s_addc_u32 s13, s13, 0
	v_lshlrev_b32_e32 v48, 16, v96
	v_and_b32_e32 v49, 0xffff0000, v96
	v_fma_f32 v16, v104, v16, v48
	v_fma_f32 v17, v104, v17, v49
	v_lshlrev_b32_e32 v48, 16, v97
	v_and_b32_e32 v49, 0xffff0000, v97
	v_fma_f32 v18, v104, v18, v48
	v_fma_f32 v19, v104, v19, v49
	v_lshlrev_b32_e32 v48, 16, v98
	v_and_b32_e32 v49, 0xffff0000, v98
	v_fma_f32 v20, v104, v20, v48
	v_fma_f32 v21, v104, v21, v49
	v_lshlrev_b32_e32 v48, 16, v99
	v_and_b32_e32 v49, 0xffff0000, v99
	v_fma_f32 v22, v104, v22, v48
	v_fma_f32 v23, v104, v23, v49
	v_lshlrev_b32_e32 v48, 16, v100
	v_and_b32_e32 v49, 0xffff0000, v100
	v_fma_f32 v24, v104, v24, v48
	v_fma_f32 v25, v104, v25, v49
	v_lshlrev_b32_e32 v48, 16, v101
	v_and_b32_e32 v49, 0xffff0000, v101
	v_fma_f32 v26, v104, v26, v48
	v_fma_f32 v27, v104, v27, v49
	v_lshlrev_b32_e32 v48, 16, v102
	v_and_b32_e32 v49, 0xffff0000, v102
	v_fma_f32 v28, v104, v28, v48
	v_fma_f32 v29, v104, v29, v49
	v_lshlrev_b32_e32 v48, 16, v103
	v_and_b32_e32 v49, 0xffff0000, v103
	v_fma_f32 v30, v104, v30, v48
	v_fma_f32 v31, v104, v31, v49
	s_waitcnt vmcnt(26)
; __device__ __forceinline__ float bf2f(unsigned h) { return __uint_as_float(h << 16); }
; __device__ __forceinline__ unsigned pk2(float lo, float hi) { return pg8::cvt_pk_bf16(lo, hi); }
; __device__ __forceinline__ void b2_scan(const Ctx& C) {
;     ...
;         for (int k = 0; k < 4; ++k) {
;             const int c = 4 * g + k;
;             const float dd[8] = {d0[cur][k][0], d0[cur][k][1], d0[cur][k][2], d0[cur][k][3], d1[cur][k][0], d1[cur][k][1], d1[cur][k][2], d1[cur][k][3]};
; #pragma unroll
;             for (int j = 0; j < 2; ++j) {
;                 v4u o; o.x = pk2(run[j][0], run[j][1]); o.y = pk2(run[j][2], run[j][3]); o.z = pk2(run[j][4], run[j][5]); o.w = pk2(run[j][6], run[j][7]);
;                 __builtin_nontemporal_store(o, (v4u*)(base + (size_t)c * cstride + (size_t)j * vstride));
;                 const unsigned lw[4] = {loc[cur][k][j].x, loc[cur][k][j].y, loc[cur][k][j].z, loc[cur][k][j].w};
; #pragma unroll
;                 for (int q = 0; q < 4; ++q) {
;                     run[j][2 * q] = dd[2 * q] * run[j][2 * q] + bf2f(lw[q] & 0xffffu);
;                     run[j][2 * q + 1] = dd[2 * q + 1] * run[j][2 * q + 1] + __uint_as_float(lw[q] & 0xffff0000u);
;                 }
	v_cvt_pk_bf16_f32 v40, v16, v17
	v_cvt_pk_bf16_f32 v41, v18, v19
	v_cvt_pk_bf16_f32 v42, v20, v21
	v_cvt_pk_bf16_f32 v43, v22, v23
	global_store_dwordx4 v2, v[40:43], s[12:13] nt
	v_cvt_pk_bf16_f32 v44, v24, v25
	v_cvt_pk_bf16_f32 v45, v26, v27
	v_cvt_pk_bf16_f32 v46, v28, v29
	v_cvt_pk_bf16_f32 v47, v30, v31
	global_store_dwordx4 v3, v[44:47], s[12:13] nt
	s_add_u32 s12, s12, 0x40000
	s_addc_u32 s13, s13, 0
	v_lshlrev_b32_e32 v48, 16, v112
	v_and_b32_e32 v49, 0xffff0000, v112
	v_fma_f32 v16, v120, v16, v48
	v_fma_f32 v17, v120, v17, v49
	v_lshlrev_b32_e32 v48, 16, v113
	v_and_b32_e32 v49, 0xffff0000, v113
	v_fma_f32 v18, v120, v18, v48
	v_fma_f32 v19, v120, v19, v49
	v_lshlrev_b32_e32 v48, 16, v114
	v_and_b32_e32 v49, 0xffff0000, v114
	v_fma_f32 v20, v120, v20, v48
	v_fma_f32 v21, v120, v21, v49
	v_lshlrev_b32_e32 v48, 16, v115
	v_and_b32_e32 v49, 0xffff0000, v115
	v_fma_f32 v22, v120, v22, v48
	v_fma_f32 v23, v120, v23, v49
	v_lshlrev_b32_e32 v48, 16, v116
	v_and_b32_e32 v49, 0xffff0000, v116
	v_fma_f32 v24, v120, v24, v48
	v_fma_f32 v25, v120, v25, v49
	v_lshlrev_b32_e32 v48, 16, v117
	v_and_b32_e32 v49, 0xffff0000, v117
	v_fma_f32 v26, v120, v26, v48
	v_fma_f32 v27, v120, v27, v49
	v_lshlrev_b32_e32 v48, 16, v118
	v_and_b32_e32 v49, 0xffff0000, v118
	v_fma_f32 v28, v120, v28, v48
	v_fma_f32 v29, v120, v29, v49
	v_lshlrev_b32_e32 v48, 16, v119
	v_and_b32_e32 v49, 0xffff0000, v119
	v_fma_f32 v30, v120, v30, v48
	v_fma_f32 v31, v120, v31, v49
	s_waitcnt vmcnt(23)
	v_cvt_pk_bf16_f32 v32, v16, v17
	v_cvt_pk_bf16_f32 v33, v18, v19
	v_cvt_pk_bf16_f32 v34, v20, v21
	v_cvt_pk_bf16_f32 v35, v22, v23
	global_store_dwordx4 v2, v[32:35], s[12:13] nt
	v_cvt_pk_bf16_f32 v36, v24, v25
	v_cvt_pk_bf16_f32 v37, v26, v27
	v_cvt_pk_bf16_f32 v38, v28, v29
	v_cvt_pk_bf16_f32 v39, v30, v31
	global_store_dwordx4 v3, v[36:39], s[12:13] nt
	s_add_u32 s12, s12, 0x40000
	s_addc_u32 s13, s13, 0
	v_lshlrev_b32_e32 v48, 16, v128
	v_and_b32_e32 v49, 0xffff0000, v128
	v_fma_f32 v16, v136, v16, v48
	v_fma_f32 v17, v136, v17, v49
	v_lshlrev_b32_e32 v48, 16, v129
	v_and_b32_e32 v49, 0xffff0000, v129
	v_fma_f32 v18, v136, v18, v48
	v_fma_f32 v19, v136, v19, v49
	v_lshlrev_b32_e32 v48, 16, v130
	v_and_b32_e32 v49, 0xffff0000, v130
	v_fma_f32 v20, v136, v20, v48
	v_fma_f32 v21, v136, v21, v49
	v_lshlrev_b32_e32 v48, 16, v131
	v_and_b32_e32 v49, 0xffff0000, v131
	v_fma_f32 v22, v136, v22, v48
	v_fma_f32 v23, v136, v23, v49
	v_lshlrev_b32_e32 v48, 16, v132
	v_and_b32_e32 v49, 0xffff0000, v132
	v_fma_f32 v24, v136, v24, v48
	v_fma_f32 v25, v136, v25, v49
	v_lshlrev_b32_e32 v48, 16, v133
	v_and_b32_e32 v49, 0xffff0000, v133
	v_fma_f32 v26, v136, v26, v48
	v_fma_f32 v27, v136, v27, v49
	v_lshlrev_b32_e32 v48, 16, v134
	v_and_b32_e32 v49, 0xffff0000, v134
	v_fma_f32 v28, v136, v28, v48
	v_fma_f32 v29, v136, v29, v49
	v_lshlrev_b32_e32 v48, 16, v135
	v_and_b32_e32 v49, 0xffff0000, v135
	v_fma_f32 v30, v136, v30, v48
	v_fma_f32 v31, v136, v31, v49
	s_waitcnt vmcnt(20)
	v_cvt_pk_bf16_f32 v40, v16, v17
	v_cvt_pk_bf16_f32 v41, v18, v19
	v_cvt_pk_bf16_f32 v42, v20, v21
	v_cvt_pk_bf16_f32 v43, v22, v23
	global_store_dwordx4 v2, v[40:43], s[12:13] nt
	v_cvt_pk_bf16_f32 v44, v24, v25
	v_cvt_pk_bf16_f32 v45, v26, v27
	v_cvt_pk_bf16_f32 v46, v28, v29
	v_cvt_pk_bf16_f32 v47, v30, v31
	global_store_dwordx4 v3, v[44:47], s[12:13] nt
	s_add_u32 s12, s12, 0x40000
	s_addc_u32 s13, s13, 0
	v_lshlrev_b32_e32 v48, 16, v144
	v_and_b32_e32 v49, 0xffff0000, v144
	v_fma_f32 v16, v152, v16, v48
	v_fma_f32 v17, v152, v17, v49
	v_lshlrev_b32_e32 v48, 16, v145
	v_and_b32_e32 v49, 0xffff0000, v145
	v_fma_f32 v18, v152, v18, v48
	v_fma_f32 v19, v152, v19, v49
	v_lshlrev_b32_e32 v48, 16, v146
	v_and_b32_e32 v49, 0xffff0000, v146
	v_fma_f32 v20, v152, v20, v48
	v_fma_f32 v21, v152, v21, v49
	v_lshlrev_b32_e32 v48, 16, v147
	v_and_b32_e32 v49, 0xffff0000, v147
	v_fma_f32 v22, v152, v22, v48
	v_fma_f32 v23, v152, v23, v49
	v_lshlrev_b32_e32 v48, 16, v148
	v_and_b32_e32 v49, 0xffff0000, v148
	v_fma_f32 v24, v152, v24, v48
	v_fma_f32 v25, v152, v25, v49
	v_lshlrev_b32_e32 v48, 16, v149
	v_and_b32_e32 v49, 0xffff0000, v149
	v_fma_f32 v26, v152, v26, v48
	v_fma_f32 v27, v152, v27, v49
	v_lshlrev_b32_e32 v48, 16, v150
	v_and_b32_e32 v49, 0xffff0000, v150
	v_fma_f32 v28, v152, v28, v48
	v_fma_f32 v29, v152, v29, v49
	v_lshlrev_b32_e32 v48, 16, v151
	v_and_b32_e32 v49, 0xffff0000, v151
	v_fma_f32 v30, v152, v30, v48
	v_fma_f32 v31, v152, v31, v49
	s_waitcnt vmcnt(17)
	v_cvt_pk_bf16_f32 v32, v16, v17
	v_cvt_pk_bf16_f32 v33, v18, v19
	v_cvt_pk_bf16_f32 v34, v20, v21
	v_cvt_pk_bf16_f32 v35, v22, v23
	global_store_dwordx4 v2, v[32:35], s[12:13] nt
	v_cvt_pk_bf16_f32 v36, v24, v25
	v_cvt_pk_bf16_f32 v37, v26, v27
	v_cvt_pk_bf16_f32 v38, v28, v29
	v_cvt_pk_bf16_f32 v39, v30, v31
	global_store_dwordx4 v3, v[36:39], s[12:13] nt
	s_add_u32 s12, s12, 0x40000
	s_addc_u32 s13, s13, 0
	v_lshlrev_b32_e32 v48, 16, v160
	v_and_b32_e32 v49, 0xffff0000, v160
	v_fma_f32 v16, v168, v16, v48
	v_fma_f32 v17, v168, v17, v49
	v_lshlrev_b32_e32 v48, 16, v161
	v_and_b32_e32 v49, 0xffff0000, v161
	v_fma_f32 v18, v168, v18, v48
	v_fma_f32 v19, v168, v19, v49
	v_lshlrev_b32_e32 v48, 16, v162
	v_and_b32_e32 v49, 0xffff0000, v162
	v_fma_f32 v20, v168, v20, v48
	v_fma_f32 v21, v168, v21, v49
	v_lshlrev_b32_e32 v48, 16, v163
	v_and_b32_e32 v49, 0xffff0000, v163
	v_fma_f32 v22, v168, v22, v48
	v_fma_f32 v23, v168, v23, v49
	v_lshlrev_b32_e32 v48, 16, v164
	v_and_b32_e32 v49, 0xffff0000, v164
	v_fma_f32 v24, v168, v24, v48
	v_fma_f32 v25, v168, v25, v49
	v_lshlrev_b32_e32 v48, 16, v165
	v_and_b32_e32 v49, 0xffff0000, v165
	v_fma_f32 v26, v168, v26, v48
	v_fma_f32 v27, v168, v27, v49
	v_lshlrev_b32_e32 v48, 16, v166
	v_and_b32_e32 v49, 0xffff0000, v166
	v_fma_f32 v28, v168, v28, v48
	v_fma_f32 v29, v168, v29, v49
	v_lshlrev_b32_e32 v48, 16, v167
	v_and_b32_e32 v49, 0xffff0000, v167
	v_fma_f32 v30, v168, v30, v48
	v_fma_f32 v31, v168, v31, v49
	s_waitcnt vmcnt(14)
; __device__ __forceinline__ float bf2f(unsigned h) { return __uint_as_float(h << 16); }
; __device__ __forceinline__ unsigned pk2(float lo, float hi) { return pg8::cvt_pk_bf16(lo, hi); }
; __device__ __forceinline__ void b2_scan(const Ctx& C) {
;     ...
;     if (!gla) { const int b = r >> 13, h = (r >> 9) & 15, e = r & 511;
;         base = (bf16*)(C.ws + WS_HS) + ((size_t)(b * NC) * 16 + h) * 8192 + (size_t)e * 8; vstride = 512 * 8; cstride = (size_t)16 * 8192; dec = SDEC + (b * NC) * 16 + h; dstride = 16; }
;     else { const int b = r >> 13, h = (r >> 11) & 3, q = r & 2047, doct = q & 15, vp = q >> 4;
;         base = (bf16*)(C.ws + WS_GS) + ((size_t)(b * NC) * 4 + h) * 32768 + (size_t)(2 * vp) * 128 + doct * 8; vstride = 128; cstride = (size_t)4 * 32768; dec = GDEC + ((b * NC) * 4 + h) * 128 + doct * 8; dstride = 512; }
;     float run[2][8];
; #pragma unroll
;     for (int j = 0; j < 2; ++j)
; #pragma unroll
;         for (int q = 0; q < 8; ++q) run[j][q] = 0.f;
;     v4u loc[2][4][2]; f32x4 d0[2][4], d1[2][4];
;     ...
;     B2_LOAD(0, 0);
; #pragma unroll
;     for (int g = 0; g < 8; ++g) {
;         const int cur = g & 1;
;         if (g + 1 < 8) B2_LOAD(g + 1, cur ^ 1);
; #pragma unroll
;         for (int k = 0; k < 4; ++k) {
;             const int c = 4 * g + k;
;             const float dd[8] = {d0[cur][k][0], d0[cur][k][1], d0[cur][k][2], d0[cur][k][3], d1[cur][k][0], d1[cur][k][1], d1[cur][k][2], d1[cur][k][3]};
; #pragma unroll
;             for (int j = 0; j < 2; ++j) {
;                 v4u o; o.x = pk2(run[j][0], run[j][1]); o.y = pk2(run[j][2], run[j][3]); o.z = pk2(run[j][4], run[j][5]); o.w = pk2(run[j][6], run[j][7]);
;                 __builtin_nontemporal_store(o, (v4u*)(base + (size_t)c * cstride + (size_t)j * vstride));
;                 const unsigned lw[4] = {loc[cur][k][j].x, loc[cur][k][j].y, loc[cur][k][j].z, loc[cur][k][j].w};
; #pragma unroll
;                 for (int q = 0; q < 4; ++q) {
;                     run[j][2 * q] = dd[2 * q] * run[j][2 * q] + bf2f(lw[q] & 0xffffu);
;                     run[j][2 * q + 1] = dd[2 * q + 1] * run[j][2 * q + 1] + __uint_as_float(lw[q] & 0xffff0000u);
;                 }
;             }
	v_cvt_pk_bf16_f32 v40, v16, v17
	v_cvt_pk_bf16_f32 v41, v18, v19
	v_cvt_pk_bf16_f32 v42, v20, v21
	v_cvt_pk_bf16_f32 v43, v22, v23
	global_store_dwordx4 v2, v[40:43], s[12:13] nt
	v_cvt_pk_bf16_f32 v44, v24, v25
	v_cvt_pk_bf16_f32 v45, v26, v27
	v_cvt_pk_bf16_f32 v46, v28, v29
	v_cvt_pk_bf16_f32 v47, v30, v31
	global_store_dwordx4 v3, v[44:47], s[12:13] nt
	s_add_u32 s12, s12, 0x40000
	s_addc_u32 s13, s13, 0
	v_lshlrev_b32_e32 v48, 16, v176
	v_and_b32_e32 v49, 0xffff0000, v176
	v_fma_f32 v16, v184, v16, v48
	v_fma_f32 v17, v184, v17, v49
	v_lshlrev_b32_e32 v48, 16, v177
	v_and_b32_e32 v49, 0xffff0000, v177
	v_fma_f32 v18, v184, v18, v48
	v_fma_f32 v19, v184, v19, v49
	v_lshlrev_b32_e32 v48, 16, v178
	v_and_b32_e32 v49, 0xffff0000, v178
	v_fma_f32 v20, v184, v20, v48
	v_fma_f32 v21, v184, v21, v49
	v_lshlrev_b32_e32 v48, 16, v179
	v_and_b32_e32 v49, 0xffff0000, v179
	v_fma_f32 v22, v184, v22, v48
	v_fma_f32 v23, v184, v23, v49
	v_lshlrev_b32_e32 v48, 16, v180
	v_and_b32_e32 v49, 0xffff0000, v180
	v_fma_f32 v24, v184, v24, v48
	v_fma_f32 v25, v184, v25, v49
	v_lshlrev_b32_e32 v48, 16, v181
	v_and_b32_e32 v49, 0xffff0000, v181
	v_fma_f32 v26, v184, v26, v48
	v_fma_f32 v27, v184, v27, v49
	v_lshlrev_b32_e32 v48, 16, v182
	v_and_b32_e32 v49, 0xffff0000, v182
	v_fma_f32 v28, v184, v28, v48
	v_fma_f32 v29, v184, v29, v49
	v_lshlrev_b32_e32 v48, 16, v183
	v_and_b32_e32 v49, 0xffff0000, v183
	v_fma_f32 v30, v184, v30, v48
	v_fma_f32 v31, v184, v31, v49
	s_branch .Lb2_end_l1
.Lb2_gla_l1:
	s_sub_u32 s10, s2, 128
	s_lshr_b32 s16, s10, 4
	s_lshl_b32 s16, s16, 7
	s_lshr_b32 s12, s10, 2
	s_and_b32 s12, s12, 3
	s_add_u32 s16, s16, s12
	s_and_b32 s12, s10, 3
	s_lshl_b32 s12, s12, 14
	s_lshl_b32 s10, s16, 16
	s_add_u32 s10, s10, s12
	s_lshl_b32 s16, s16, 9
	v_lshrrev_b32_e32 v2, 4, v234
	v_lshlrev_b32_e32 v2, 9, v2
	v_and_b32_e32 v5, 15, v234
	v_lshl_add_u32 v2, v5, 4, v2
	v_add_u32_e32 v3, 0x100, v2
	v_lshlrev_b32_e32 v5, 5, v5
	s_waitcnt lgkmcnt(0)
	s_add_u32 s10, s10, s18
	s_addc_u32 s11, s19, 0
	s_add_u32 s10, s10, 0x21c00000
	s_addc_u32 s11, s11, 0
	s_add_u32 s16, s16, s18
	s_addc_u32 s17, s19, 0
	s_add_u32 s16, s16, 0x25c10000
	s_addc_u32 s17, s17, 0
	s_mov_b32 s12, s10
	s_mov_b32 s13, s11
	global_load_dwordx4 v[64:67], v2, s[10:11] nt
	global_load_dwordx4 v[68:71], v3, s[10:11] nt
	global_load_dwordx4 v[72:75], v5, s[16:17]
	global_load_dwordx4 v[76:79], v5, s[16:17] offset:16
	s_add_u32 s10, s10, 0x40000
	s_addc_u32 s11, s11, 0
	s_add_u32 s16, s16, 2048
	s_addc_u32 s17, s17, 0
	global_load_dwordx4 v[80:83], v2, s[10:11] nt
	global_load_dwordx4 v[84:87], v3, s[10:11] nt
	global_load_dwordx4 v[88:91], v5, s[16:17]
	global_load_dwordx4 v[92:95], v5, s[16:17] offset:16
	s_add_u32 s10, s10, 0x40000
	s_addc_u32 s11, s11, 0
	s_add_u32 s16, s16, 2048
	s_addc_u32 s17, s17, 0
	global_load_dwordx4 v[96:99], v2, s[10:11] nt
	global_load_dwordx4 v[100:103], v3, s[10:11] nt
	global_load_dwordx4 v[104:107], v5, s[16:17]
	global_load_dwordx4 v[108:111], v5, s[16:17] offset:16
	s_add_u32 s10, s10, 0x40000
	s_addc_u32 s11, s11, 0
	s_add_u32 s16, s16, 2048
	s_addc_u32 s17, s17, 0
	global_load_dwordx4 v[112:115], v2, s[10:11] nt
	global_load_dwordx4 v[116:119], v3, s[10:11] nt
	global_load_dwordx4 v[120:123], v5, s[16:17]
	global_load_dwordx4 v[124:127], v5, s[16:17] offset:16
	s_add_u32 s10, s10, 0x40000
	s_addc_u32 s11, s11, 0
	s_add_u32 s16, s16, 2048
	s_addc_u32 s17, s17, 0
	global_load_dwordx4 v[128:131], v2, s[10:11] nt
	global_load_dwordx4 v[132:135], v3, s[10:11] nt
	global_load_dwordx4 v[136:139], v5, s[16:17]
	global_load_dwordx4 v[140:143], v5, s[16:17] offset:16
	s_add_u32 s10, s10, 0x40000
	s_addc_u32 s11, s11, 0
	s_add_u32 s16, s16, 2048
	s_addc_u32 s17, s17, 0
	global_load_dwordx4 v[144:147], v2, s[10:11] nt
	global_load_dwordx4 v[148:151], v3, s[10:11] nt
	global_load_dwordx4 v[152:155], v5, s[16:17]
	global_load_dwordx4 v[156:159], v5, s[16:17] offset:16
	s_add_u32 s10, s10, 0x40000
	s_addc_u32 s11, s11, 0
	s_add_u32 s16, s16, 2048
	s_addc_u32 s17, s17, 0
	global_load_dwordx4 v[160:163], v2, s[10:11] nt
	global_load_dwordx4 v[164:167], v3, s[10:11] nt
	global_load_dwordx4 v[168:171], v5, s[16:17]
	global_load_dwordx4 v[172:175], v5, s[16:17] offset:16
	s_add_u32 s10, s10, 0x40000
	s_addc_u32 s11, s11, 0
	s_add_u32 s16, s16, 2048
	s_addc_u32 s17, s17, 0
	global_load_dwordx4 v[176:179], v2, s[10:11] nt
	global_load_dwordx4 v[180:183], v3, s[10:11] nt
	global_load_dwordx4 v[184:187], v5, s[16:17]
	global_load_dwordx4 v[188:191], v5, s[16:17] offset:16
	s_add_u32 s10, s10, 0x40000
	s_addc_u32 s11, s11, 0
	s_add_u32 s16, s16, 2048
	s_addc_u32 s17, s17, 0
	s_waitcnt vmcnt(28)
	v_cvt_pk_bf16_f32 v32, v16, v17
	v_cvt_pk_bf16_f32 v33, v18, v19
	v_cvt_pk_bf16_f32 v34, v20, v21
	v_cvt_pk_bf16_f32 v35, v22, v23
	global_store_dwordx4 v2, v[32:35], s[12:13] nt
	v_cvt_pk_bf16_f32 v36, v24, v25
	v_cvt_pk_bf16_f32 v37, v26, v27
	v_cvt_pk_bf16_f32 v38, v28, v29
	v_cvt_pk_bf16_f32 v39, v30, v31
	global_store_dwordx4 v3, v[36:39], s[12:13] nt
	s_add_u32 s12, s12, 0x40000
	s_addc_u32 s13, s13, 0
	v_lshlrev_b32_e32 v48, 16, v64
	v_and_b32_e32 v49, 0xffff0000, v64
	v_fma_f32 v16, v72, v16, v48
	v_fma_f32 v17, v73, v17, v49
	v_lshlrev_b32_e32 v48, 16, v65
	v_and_b32_e32 v49, 0xffff0000, v65
	v_fma_f32 v18, v74, v18, v48
	v_fma_f32 v19, v75, v19, v49
	v_lshlrev_b32_e32 v48, 16, v66
	v_and_b32_e32 v49, 0xffff0000, v66
	v_fma_f32 v20, v76, v20, v48
	v_fma_f32 v21, v77, v21, v49
	v_lshlrev_b32_e32 v48, 16, v67
	v_and_b32_e32 v49, 0xffff0000, v67
	v_fma_f32 v22, v78, v22, v48
	v_fma_f32 v23, v79, v23, v49
	v_lshlrev_b32_e32 v48, 16, v68
	v_and_b32_e32 v49, 0xffff0000, v68
	v_fma_f32 v24, v72, v24, v48
	v_fma_f32 v25, v73, v25, v49
	v_lshlrev_b32_e32 v48, 16, v69
	v_and_b32_e32 v49, 0xffff0000, v69
	v_fma_f32 v26, v74, v26, v48
	v_fma_f32 v27, v75, v27, v49
	v_lshlrev_b32_e32 v48, 16, v70
	v_and_b32_e32 v49, 0xffff0000, v70
	v_fma_f32 v28, v76, v28, v48
	v_fma_f32 v29, v77, v29, v49
	v_lshlrev_b32_e32 v48, 16, v71
	v_and_b32_e32 v49, 0xffff0000, v71
	v_fma_f32 v30, v78, v30, v48
	v_fma_f32 v31, v79, v31, v49
	global_load_dwordx4 v[64:67], v2, s[10:11] nt
	global_load_dwordx4 v[68:71], v3, s[10:11] nt
	global_load_dwordx4 v[72:75], v5, s[16:17]
	global_load_dwordx4 v[76:79], v5, s[16:17] offset:16
	s_add_u32 s10, s10, 0x40000
	s_addc_u32 s11, s11, 0
	s_add_u32 s16, s16, 2048
	s_addc_u32 s17, s17, 0
	s_waitcnt vmcnt(30)
; __device__ __forceinline__ float bf2f(unsigned h) { return __uint_as_float(h << 16); }
; __device__ __forceinline__ unsigned pk2(float lo, float hi) { return pg8::cvt_pk_bf16(lo, hi); }
; __device__ __forceinline__ void b2_scan(const Ctx& C) {
;     ...
;     B2_LOAD(0, 0);
; #pragma unroll
;     for (int g = 0; g < 8; ++g) {
;         const int cur = g & 1;
;         if (g + 1 < 8) B2_LOAD(g + 1, cur ^ 1);
; #pragma unroll
;         for (int k = 0; k < 4; ++k) {
;             const int c = 4 * g + k;
;             const float dd[8] = {d0[cur][k][0], d0[cur][k][1], d0[cur][k][2], d0[cur][k][3], d1[cur][k][0], d1[cur][k][1], d1[cur][k][2], d1[cur][k][3]};
; #pragma unroll
;             for (int j = 0; j < 2; ++j) {
;                 v4u o; o.x = pk2(run[j][0], run[j][1]); o.y = pk2(run[j][2], run[j][3]); o.z = pk2(run[j][4], run[j][5]); o.w = pk2(run[j][6], run[j][7]);
;                 __builtin_nontemporal_store(o, (v4u*)(base + (size_t)c * cstride + (size_t)j * vstride));
;                 const unsigned lw[4] = {loc[cur][k][j].x, loc[cur][k][j].y, loc[cur][k][j].z, loc[cur][k][j].w};
; #pragma unroll
;                 for (int q = 0; q < 4; ++q) {
;                     run[j][2 * q] = dd[2 * q] * run[j][2 * q] + bf2f(lw[q] & 0xffffu);
;                     run[j][2 * q + 1] = dd[2 * q + 1] * run[j][2 * q + 1] + __uint_as_float(lw[q] & 0xffff0000u);
;                 }
;             }
	v_cvt_pk_bf16_f32 v40, v16, v17
	v_cvt_pk_bf16_f32 v41, v18, v19
	v_cvt_pk_bf16_f32 v42, v20, v21
	v_cvt_pk_bf16_f32 v43, v22, v23
	global_store_dwordx4 v2, v[40:43], s[12:13] nt
	v_cvt_pk_bf16_f32 v44, v24, v25
	v_cvt_pk_bf16_f32 v45, v26, v27
	v_cvt_pk_bf16_f32 v46, v28, v29
	v_cvt_pk_bf16_f32 v47, v30, v31
	global_store_dwordx4 v3, v[44:47], s[12:13] nt
	s_add_u32 s12, s12, 0x40000
	s_addc_u32 s13, s13, 0
	v_lshlrev_b32_e32 v48, 16, v80
	v_and_b32_e32 v49, 0xffff0000, v80
	v_fma_f32 v16, v88, v16, v48
	v_fma_f32 v17, v89, v17, v49
	v_lshlrev_b32_e32 v48, 16, v81
	v_and_b32_e32 v49, 0xffff0000, v81
	v_fma_f32 v18, v90, v18, v48
	v_fma_f32 v19, v91, v19, v49
	v_lshlrev_b32_e32 v48, 16, v82
	v_and_b32_e32 v49, 0xffff0000, v82
	v_fma_f32 v20, v92, v20, v48
	v_fma_f32 v21, v93, v21, v49
	v_lshlrev_b32_e32 v48, 16, v83
	v_and_b32_e32 v49, 0xffff0000, v83
	v_fma_f32 v22, v94, v22, v48
	v_fma_f32 v23, v95, v23, v49
	v_lshlrev_b32_e32 v48, 16, v84
	v_and_b32_e32 v49, 0xffff0000, v84
	v_fma_f32 v24, v88, v24, v48
	v_fma_f32 v25, v89, v25, v49
	v_lshlrev_b32_e32 v48, 16, v85
	v_and_b32_e32 v49, 0xffff0000, v85
	v_fma_f32 v26, v90, v26, v48
	v_fma_f32 v27, v91, v27, v49
	v_lshlrev_b32_e32 v48, 16, v86
	v_and_b32_e32 v49, 0xffff0000, v86
	v_fma_f32 v28, v92, v28, v48
	v_fma_f32 v29, v93, v29, v49
	v_lshlrev_b32_e32 v48, 16, v87
	v_and_b32_e32 v49, 0xffff0000, v87
	v_fma_f32 v30, v94, v30, v48
	v_fma_f32 v31, v95, v31, v49
	global_load_dwordx4 v[80:83], v2, s[10:11] nt
	global_load_dwordx4 v[84:87], v3, s[10:11] nt
	global_load_dwordx4 v[88:91], v5, s[16:17]
	global_load_dwordx4 v[92:95], v5, s[16:17] offset:16
	s_add_u32 s10, s10, 0x40000
	s_addc_u32 s11, s11, 0
	s_add_u32 s16, s16, 2048
	s_addc_u32 s17, s17, 0
	s_waitcnt vmcnt(32)
	v_cvt_pk_bf16_f32 v32, v16, v17
	v_cvt_pk_bf16_f32 v33, v18, v19
	v_cvt_pk_bf16_f32 v34, v20, v21
	v_cvt_pk_bf16_f32 v35, v22, v23
	global_store_dwordx4 v2, v[32:35], s[12:13] nt
	v_cvt_pk_bf16_f32 v36, v24, v25
	v_cvt_pk_bf16_f32 v37, v26, v27
	v_cvt_pk_bf16_f32 v38, v28, v29
	v_cvt_pk_bf16_f32 v39, v30, v31
	global_store_dwordx4 v3, v[36:39], s[12:13] nt
	s_add_u32 s12, s12, 0x40000
	s_addc_u32 s13, s13, 0
	v_lshlrev_b32_e32 v48, 16, v96
	v_and_b32_e32 v49, 0xffff0000, v96
	v_fma_f32 v16, v104, v16, v48
	v_fma_f32 v17, v105, v17, v49
	v_lshlrev_b32_e32 v48, 16, v97
	v_and_b32_e32 v49, 0xffff0000, v97
	v_fma_f32 v18, v106, v18, v48
	v_fma_f32 v19, v107, v19, v49
	v_lshlrev_b32_e32 v48, 16, v98
	v_and_b32_e32 v49, 0xffff0000, v98
	v_fma_f32 v20, v108, v20, v48
	v_fma_f32 v21, v109, v21, v49
	v_lshlrev_b32_e32 v48, 16, v99
	v_and_b32_e32 v49, 0xffff0000, v99
	v_fma_f32 v22, v110, v22, v48
	v_fma_f32 v23, v111, v23, v49
	v_lshlrev_b32_e32 v48, 16, v100
	v_and_b32_e32 v49, 0xffff0000, v100
	v_fma_f32 v24, v104, v24, v48
	v_fma_f32 v25, v105, v25, v49
	v_lshlrev_b32_e32 v48, 16, v101
	v_and_b32_e32 v49, 0xffff0000, v101
	v_fma_f32 v26, v106, v26, v48
	v_fma_f32 v27, v107, v27, v49
	v_lshlrev_b32_e32 v48, 16, v102
	v_and_b32_e32 v49, 0xffff0000, v102
	v_fma_f32 v28, v108, v28, v48
	v_fma_f32 v29, v109, v29, v49
	v_lshlrev_b32_e32 v48, 16, v103
	v_and_b32_e32 v49, 0xffff0000, v103
	v_fma_f32 v30, v110, v30, v48
	v_fma_f32 v31, v111, v31, v49
	global_load_dwordx4 v[96:99], v2, s[10:11] nt
	global_load_dwordx4 v[100:103], v3, s[10:11] nt
	global_load_dwordx4 v[104:107], v5, s[16:17]
	global_load_dwordx4 v[108:111], v5, s[16:17] offset:16
	s_add_u32 s10, s10, 0x40000
	s_addc_u32 s11, s11, 0
	s_add_u32 s16, s16, 2048
	s_addc_u32 s17, s17, 0
	s_waitcnt vmcnt(34)
	v_cvt_pk_bf16_f32 v40, v16, v17
	v_cvt_pk_bf16_f32 v41, v18, v19
	v_cvt_pk_bf16_f32 v42, v20, v21
	v_cvt_pk_bf16_f32 v43, v22, v23
	global_store_dwordx4 v2, v[40:43], s[12:13] nt
	v_cvt_pk_bf16_f32 v44, v24, v25
	v_cvt_pk_bf16_f32 v45, v26, v27
	v_cvt_pk_bf16_f32 v46, v28, v29
	v_cvt_pk_bf16_f32 v47, v30, v31
	global_store_dwordx4 v3, v[44:47], s[12:13] nt
	s_add_u32 s12, s12, 0x40000
	s_addc_u32 s13, s13, 0
	v_lshlrev_b32_e32 v48, 16, v112
	v_and_b32_e32 v49, 0xffff0000, v112
	v_fma_f32 v16, v120, v16, v48
	v_fma_f32 v17, v121, v17, v49
	v_lshlrev_b32_e32 v48, 16, v113
	v_and_b32_e32 v49, 0xffff0000, v113
	v_fma_f32 v18, v122, v18, v48
	v_fma_f32 v19, v123, v19, v49
	v_lshlrev_b32_e32 v48, 16, v114
	v_and_b32_e32 v49, 0xffff0000, v114
	v_fma_f32 v20, v124, v20, v48
	v_fma_f32 v21, v125, v21, v49
	v_lshlrev_b32_e32 v48, 16, v115
	v_and_b32_e32 v49, 0xffff0000, v115
	v_fma_f32 v22, v126, v22, v48
	v_fma_f32 v23, v127, v23, v49
	v_lshlrev_b32_e32 v48, 16, v116
	v_and_b32_e32 v49, 0xffff0000, v116
	v_fma_f32 v24, v120, v24, v48
	v_fma_f32 v25, v121, v25, v49
	v_lshlrev_b32_e32 v48, 16, v117
	v_and_b32_e32 v49, 0xffff0000, v117
	v_fma_f32 v26, v122, v26, v48
	v_fma_f32 v27, v123, v27, v49
	v_lshlrev_b32_e32 v48, 16, v118
	v_and_b32_e32 v49, 0xffff0000, v118
	v_fma_f32 v28, v124, v28, v48
	v_fma_f32 v29, v125, v29, v49
	v_lshlrev_b32_e32 v48, 16, v119
	v_and_b32_e32 v49, 0xffff0000, v119
	v_fma_f32 v30, v126, v30, v48
	v_fma_f32 v31, v127, v31, v49
	global_load_dwordx4 v[112:115], v2, s[10:11] nt
	global_load_dwordx4 v[116:119], v3, s[10:11] nt
	global_load_dwordx4 v[120:123], v5, s[16:17]
	global_load_dwordx4 v[124:127], v5, s[16:17] offset:16
	s_add_u32 s10, s10, 0x40000
	s_addc_u32 s11, s11, 0
	s_add_u32 s16, s16, 2048
	s_addc_u32 s17, s17, 0
	s_waitcnt vmcnt(36)
; __device__ __forceinline__ float bf2f(unsigned h) { return __uint_as_float(h << 16); }
; __device__ __forceinline__ unsigned pk2(float lo, float hi) { return pg8::cvt_pk_bf16(lo, hi); }
; __device__ __forceinline__ void b2_scan(const Ctx& C) {
;     ...
;     B2_LOAD(0, 0);
; #pragma unroll
;     for (int g = 0; g < 8; ++g) {
;         const int cur = g & 1;
;         if (g + 1 < 8) B2_LOAD(g + 1, cur ^ 1);
; #pragma unroll
;         for (int k = 0; k < 4; ++k) {
;             const int c = 4 * g + k;
;             const float dd[8] = {d0[cur][k][0], d0[cur][k][1], d0[cur][k][2], d0[cur][k][3], d1[cur][k][0], d1[cur][k][1], d1[cur][k][2], d1[cur][k][3]};
; #pragma unroll
;             for (int j = 0; j < 2; ++j) {
;                 v4u o; o.x = pk2(run[j][0], run[j][1]); o.y = pk2(run[j][2], run[j][3]); o.z = pk2(run[j][4], run[j][5]); o.w = pk2(run[j][6], run[j][7]);
;                 __builtin_nontemporal_store(o, (v4u*)(base + (size_t)c * cstride + (size_t)j * vstride));
;                 const unsigned lw[4] = {loc[cur][k][j].x, loc[cur][k][j].y, loc[cur][k][j].z, loc[cur][k][j].w};
; #pragma unroll
;                 for (int q = 0; q < 4; ++q) {
;                     run[j][2 * q] = dd[2 * q] * run[j][2 * q] + bf2f(lw[q] & 0xffffu);
;                     run[j][2 * q + 1] = dd[2 * q + 1] * run[j][2 * q + 1] + __uint_as_float(lw[q] & 0xffff0000u);
;                 }
;             }
	v_cvt_pk_bf16_f32 v32, v16, v17
	v_cvt_pk_bf16_f32 v33, v18, v19
	v_cvt_pk_bf16_f32 v34, v20, v21
	v_cvt_pk_bf16_f32 v35, v22, v23
	global_store_dwordx4 v2, v[32:35], s[12:13] nt
	v_cvt_pk_bf16_f32 v36, v24, v25
	v_cvt_pk_bf16_f32 v37, v26, v27
	v_cvt_pk_bf16_f32 v38, v28, v29
	v_cvt_pk_bf16_f32 v39, v30, v31
	global_store_dwordx4 v3, v[36:39], s[12:13] nt
	s_add_u32 s12, s12, 0x40000
	s_addc_u32 s13, s13, 0
	v_lshlrev_b32_e32 v48, 16, v128
	v_and_b32_e32 v49, 0xffff0000, v128
	v_fma_f32 v16, v136, v16, v48
	v_fma_f32 v17, v137, v17, v49
	v_lshlrev_b32_e32 v48, 16, v129
	v_and_b32_e32 v49, 0xffff0000, v129
	v_fma_f32 v18, v138, v18, v48
	v_fma_f32 v19, v139, v19, v49
	v_lshlrev_b32_e32 v48, 16, v130
	v_and_b32_e32 v49, 0xffff0000, v130
	v_fma_f32 v20, v140, v20, v48
	v_fma_f32 v21, v141, v21, v49
	v_lshlrev_b32_e32 v48, 16, v131
	v_and_b32_e32 v49, 0xffff0000, v131
	v_fma_f32 v22, v142, v22, v48
	v_fma_f32 v23, v143, v23, v49
	v_lshlrev_b32_e32 v48, 16, v132
	v_and_b32_e32 v49, 0xffff0000, v132
	v_fma_f32 v24, v136, v24, v48
	v_fma_f32 v25, v137, v25, v49
	v_lshlrev_b32_e32 v48, 16, v133
	v_and_b32_e32 v49, 0xffff0000, v133
	v_fma_f32 v26, v138, v26, v48
	v_fma_f32 v27, v139, v27, v49
	v_lshlrev_b32_e32 v48, 16, v134
	v_and_b32_e32 v49, 0xffff0000, v134
	v_fma_f32 v28, v140, v28, v48
	v_fma_f32 v29, v141, v29, v49
	v_lshlrev_b32_e32 v48, 16, v135
	v_and_b32_e32 v49, 0xffff0000, v135
	v_fma_f32 v30, v142, v30, v48
	v_fma_f32 v31, v143, v31, v49
	global_load_dwordx4 v[128:131], v2, s[10:11] nt
	global_load_dwordx4 v[132:135], v3, s[10:11] nt
	global_load_dwordx4 v[136:139], v5, s[16:17]
	global_load_dwordx4 v[140:143], v5, s[16:17] offset:16
	s_add_u32 s10, s10, 0x40000
	s_addc_u32 s11, s11, 0
	s_add_u32 s16, s16, 2048
	s_addc_u32 s17, s17, 0
	s_waitcnt vmcnt(38)
	v_cvt_pk_bf16_f32 v40, v16, v17
	v_cvt_pk_bf16_f32 v41, v18, v19
	v_cvt_pk_bf16_f32 v42, v20, v21
	v_cvt_pk_bf16_f32 v43, v22, v23
	global_store_dwordx4 v2, v[40:43], s[12:13] nt
	v_cvt_pk_bf16_f32 v44, v24, v25
	v_cvt_pk_bf16_f32 v45, v26, v27
	v_cvt_pk_bf16_f32 v46, v28, v29
	v_cvt_pk_bf16_f32 v47, v30, v31
	global_store_dwordx4 v3, v[44:47], s[12:13] nt
	s_add_u32 s12, s12, 0x40000
	s_addc_u32 s13, s13, 0
	v_lshlrev_b32_e32 v48, 16, v144
	v_and_b32_e32 v49, 0xffff0000, v144
	v_fma_f32 v16, v152, v16, v48
	v_fma_f32 v17, v153, v17, v49
	v_lshlrev_b32_e32 v48, 16, v145
	v_and_b32_e32 v49, 0xffff0000, v145
	v_fma_f32 v18, v154, v18, v48
	v_fma_f32 v19, v155, v19, v49
	v_lshlrev_b32_e32 v48, 16, v146
	v_and_b32_e32 v49, 0xffff0000, v146
	v_fma_f32 v20, v156, v20, v48
	v_fma_f32 v21, v157, v21, v49
	v_lshlrev_b32_e32 v48, 16, v147
	v_and_b32_e32 v49, 0xffff0000, v147
	v_fma_f32 v22, v158, v22, v48
	v_fma_f32 v23, v159, v23, v49
	v_lshlrev_b32_e32 v48, 16, v148
	v_and_b32_e32 v49, 0xffff0000, v148
	v_fma_f32 v24, v152, v24, v48
	v_fma_f32 v25, v153, v25, v49
	v_lshlrev_b32_e32 v48, 16, v149
	v_and_b32_e32 v49, 0xffff0000, v149
	v_fma_f32 v26, v154, v26, v48
	v_fma_f32 v27, v155, v27, v49
	v_lshlrev_b32_e32 v48, 16, v150
	v_and_b32_e32 v49, 0xffff0000, v150
	v_fma_f32 v28, v156, v28, v48
	v_fma_f32 v29, v157, v29, v49
	v_lshlrev_b32_e32 v48, 16, v151
	v_and_b32_e32 v49, 0xffff0000, v151
	v_fma_f32 v30, v158, v30, v48
	v_fma_f32 v31, v159, v31, v49
	global_load_dwordx4 v[144:147], v2, s[10:11] nt
	global_load_dwordx4 v[148:151], v3, s[10:11] nt
	global_load_dwordx4 v[152:155], v5, s[16:17]
	global_load_dwordx4 v[156:159], v5, s[16:17] offset:16
	s_add_u32 s10, s10, 0x40000
	s_addc_u32 s11, s11, 0
	s_add_u32 s16, s16, 2048
	s_addc_u32 s17, s17, 0
	s_waitcnt vmcnt(40)
	v_cvt_pk_bf16_f32 v32, v16, v17
	v_cvt_pk_bf16_f32 v33, v18, v19
	v_cvt_pk_bf16_f32 v34, v20, v21
	v_cvt_pk_bf16_f32 v35, v22, v23
	global_store_dwordx4 v2, v[32:35], s[12:13] nt
	v_cvt_pk_bf16_f32 v36, v24, v25
	v_cvt_pk_bf16_f32 v37, v26, v27
	v_cvt_pk_bf16_f32 v38, v28, v29
	v_cvt_pk_bf16_f32 v39, v30, v31
	global_store_dwordx4 v3, v[36:39], s[12:13] nt
	s_add_u32 s12, s12, 0x40000
	s_addc_u32 s13, s13, 0
	v_lshlrev_b32_e32 v48, 16, v160
	v_and_b32_e32 v49, 0xffff0000, v160
	v_fma_f32 v16, v168, v16, v48
	v_fma_f32 v17, v169, v17, v49
	v_lshlrev_b32_e32 v48, 16, v161
	v_and_b32_e32 v49, 0xffff0000, v161
	v_fma_f32 v18, v170, v18, v48
	v_fma_f32 v19, v171, v19, v49
	v_lshlrev_b32_e32 v48, 16, v162
	v_and_b32_e32 v49, 0xffff0000, v162
	v_fma_f32 v20, v172, v20, v48
	v_fma_f32 v21, v173, v21, v49
	v_lshlrev_b32_e32 v48, 16, v163
	v_and_b32_e32 v49, 0xffff0000, v163
	v_fma_f32 v22, v174, v22, v48
	v_fma_f32 v23, v175, v23, v49
	v_lshlrev_b32_e32 v48, 16, v164
	v_and_b32_e32 v49, 0xffff0000, v164
	v_fma_f32 v24, v168, v24, v48
	v_fma_f32 v25, v169, v25, v49
	v_lshlrev_b32_e32 v48, 16, v165
	v_and_b32_e32 v49, 0xffff0000, v165
	v_fma_f32 v26, v170, v26, v48
	v_fma_f32 v27, v171, v27, v49
	v_lshlrev_b32_e32 v48, 16, v166
	v_and_b32_e32 v49, 0xffff0000, v166
	v_fma_f32 v28, v172, v28, v48
	v_fma_f32 v29, v173, v29, v49
	v_lshlrev_b32_e32 v48, 16, v167
	v_and_b32_e32 v49, 0xffff0000, v167
	v_fma_f32 v30, v174, v30, v48
	v_fma_f32 v31, v175, v31, v49
	global_load_dwordx4 v[160:163], v2, s[10:11] nt
	global_load_dwordx4 v[164:167], v3, s[10:11] nt
	global_load_dwordx4 v[168:171], v5, s[16:17]
	global_load_dwordx4 v[172:175], v5, s[16:17] offset:16
	s_add_u32 s10, s10, 0x40000
	s_addc_u32 s11, s11, 0
	s_add_u32 s16, s16, 2048
	s_addc_u32 s17, s17, 0
	s_waitcnt vmcnt(42)
; __device__ __forceinline__ float bf2f(unsigned h) { return __uint_as_float(h << 16); }
; __device__ __forceinline__ unsigned pk2(float lo, float hi) { return pg8::cvt_pk_bf16(lo, hi); }
; __device__ __forceinline__ void b2_scan(const Ctx& C) {
;     ...
;     B2_LOAD(0, 0);
; #pragma unroll
;     for (int g = 0; g < 8; ++g) {
;         const int cur = g & 1;
;         if (g + 1 < 8) B2_LOAD(g + 1, cur ^ 1);
; #pragma unroll
;         for (int k = 0; k < 4; ++k) {
;             const int c = 4 * g + k;
;             const float dd[8] = {d0[cur][k][0], d0[cur][k][1], d0[cur][k][2], d0[cur][k][3], d1[cur][k][0], d1[cur][k][1], d1[cur][k][2], d1[cur][k][3]};
; #pragma unroll
;             for (int j = 0; j < 2; ++j) {
;                 v4u o; o.x = pk2(run[j][0], run[j][1]); o.y = pk2(run[j][2], run[j][3]); o.z = pk2(run[j][4], run[j][5]); o.w = pk2(run[j][6], run[j][7]);
;                 __builtin_nontemporal_store(o, (v4u*)(base + (size_t)c * cstride + (size_t)j * vstride));
;                 const unsigned lw[4] = {loc[cur][k][j].x, loc[cur][k][j].y, loc[cur][k][j].z, loc[cur][k][j].w};
; #pragma unroll
;                 for (int q = 0; q < 4; ++q) {
;                     run[j][2 * q] = dd[2 * q] * run[j][2 * q] + bf2f(lw[q] & 0xffffu);
;                     run[j][2 * q + 1] = dd[2 * q + 1] * run[j][2 * q + 1] + __uint_as_float(lw[q] & 0xffff0000u);
;                 }
;             }
	v_cvt_pk_bf16_f32 v40, v16, v17
	v_cvt_pk_bf16_f32 v41, v18, v19
	v_cvt_pk_bf16_f32 v42, v20, v21
	v_cvt_pk_bf16_f32 v43, v22, v23
	global_store_dwordx4 v2, v[40:43], s[12:13] nt
	v_cvt_pk_bf16_f32 v44, v24, v25
	v_cvt_pk_bf16_f32 v45, v26, v27
	v_cvt_pk_bf16_f32 v46, v28, v29
	v_cvt_pk_bf16_f32 v47, v30, v31
	global_store_dwordx4 v3, v[44:47], s[12:13] nt
	s_add_u32 s12, s12, 0x40000
	s_addc_u32 s13, s13, 0
	v_lshlrev_b32_e32 v48, 16, v176
	v_and_b32_e32 v49, 0xffff0000, v176
	v_fma_f32 v16, v184, v16, v48
	v_fma_f32 v17, v185, v17, v49
	v_lshlrev_b32_e32 v48, 16, v177
	v_and_b32_e32 v49, 0xffff0000, v177
	v_fma_f32 v18, v186, v18, v48
	v_fma_f32 v19, v187, v19, v49
	v_lshlrev_b32_e32 v48, 16, v178
	v_and_b32_e32 v49, 0xffff0000, v178
	v_fma_f32 v20, v188, v20, v48
	v_fma_f32 v21, v189, v21, v49
	v_lshlrev_b32_e32 v48, 16, v179
	v_and_b32_e32 v49, 0xffff0000, v179
	v_fma_f32 v22, v190, v22, v48
	v_fma_f32 v23, v191, v23, v49
	v_lshlrev_b32_e32 v48, 16, v180
	v_and_b32_e32 v49, 0xffff0000, v180
	v_fma_f32 v24, v184, v24, v48
	v_fma_f32 v25, v185, v25, v49
	v_lshlrev_b32_e32 v48, 16, v181
	v_and_b32_e32 v49, 0xffff0000, v181
	v_fma_f32 v26, v186, v26, v48
	v_fma_f32 v27, v187, v27, v49
	v_lshlrev_b32_e32 v48, 16, v182
	v_and_b32_e32 v49, 0xffff0000, v182
	v_fma_f32 v28, v188, v28, v48
	v_fma_f32 v29, v189, v29, v49
	v_lshlrev_b32_e32 v48, 16, v183
	v_and_b32_e32 v49, 0xffff0000, v183
	v_fma_f32 v30, v190, v30, v48
	v_fma_f32 v31, v191, v31, v49
	global_load_dwordx4 v[176:179], v2, s[10:11] nt
	global_load_dwordx4 v[180:183], v3, s[10:11] nt
	global_load_dwordx4 v[184:187], v5, s[16:17]
	global_load_dwordx4 v[188:191], v5, s[16:17] offset:16
	s_add_u32 s10, s10, 0x40000
	s_addc_u32 s11, s11, 0
	s_add_u32 s16, s16, 2048
	s_addc_u32 s17, s17, 0
	s_waitcnt vmcnt(42)
	v_cvt_pk_bf16_f32 v32, v16, v17
	v_cvt_pk_bf16_f32 v33, v18, v19
	v_cvt_pk_bf16_f32 v34, v20, v21
	v_cvt_pk_bf16_f32 v35, v22, v23
	global_store_dwordx4 v2, v[32:35], s[12:13] nt
	v_cvt_pk_bf16_f32 v36, v24, v25
	v_cvt_pk_bf16_f32 v37, v26, v27
	v_cvt_pk_bf16_f32 v38, v28, v29
	v_cvt_pk_bf16_f32 v39, v30, v31
	global_store_dwordx4 v3, v[36:39], s[12:13] nt
	s_add_u32 s12, s12, 0x40000
	s_addc_u32 s13, s13, 0
	v_lshlrev_b32_e32 v48, 16, v64
	v_and_b32_e32 v49, 0xffff0000, v64
	v_fma_f32 v16, v72, v16, v48
	v_fma_f32 v17, v73, v17, v49
	v_lshlrev_b32_e32 v48, 16, v65
	v_and_b32_e32 v49, 0xffff0000, v65
	v_fma_f32 v18, v74, v18, v48
	v_fma_f32 v19, v75, v19, v49
	v_lshlrev_b32_e32 v48, 16, v66
	v_and_b32_e32 v49, 0xffff0000, v66
	v_fma_f32 v20, v76, v20, v48
	v_fma_f32 v21, v77, v21, v49
	v_lshlrev_b32_e32 v48, 16, v67
	v_and_b32_e32 v49, 0xffff0000, v67
	v_fma_f32 v22, v78, v22, v48
	v_fma_f32 v23, v79, v23, v49
	v_lshlrev_b32_e32 v48, 16, v68
	v_and_b32_e32 v49, 0xffff0000, v68
	v_fma_f32 v24, v72, v24, v48
	v_fma_f32 v25, v73, v25, v49
	v_lshlrev_b32_e32 v48, 16, v69
	v_and_b32_e32 v49, 0xffff0000, v69
	v_fma_f32 v26, v74, v26, v48
	v_fma_f32 v27, v75, v27, v49
	v_lshlrev_b32_e32 v48, 16, v70
	v_and_b32_e32 v49, 0xffff0000, v70
	v_fma_f32 v28, v76, v28, v48
	v_fma_f32 v29, v77, v29, v49
	v_lshlrev_b32_e32 v48, 16, v71
	v_and_b32_e32 v49, 0xffff0000, v71
	v_fma_f32 v30, v78, v30, v48
	v_fma_f32 v31, v79, v31, v49
	global_load_dwordx4 v[64:67], v2, s[10:11] nt
	global_load_dwordx4 v[68:71], v3, s[10:11] nt
	global_load_dwordx4 v[72:75], v5, s[16:17]
	global_load_dwordx4 v[76:79], v5, s[16:17] offset:16
	s_add_u32 s10, s10, 0x40000
	s_addc_u32 s11, s11, 0
	s_add_u32 s16, s16, 2048
	s_addc_u32 s17, s17, 0
	s_waitcnt vmcnt(42)
	v_cvt_pk_bf16_f32 v40, v16, v17
	v_cvt_pk_bf16_f32 v41, v18, v19
	v_cvt_pk_bf16_f32 v42, v20, v21
	v_cvt_pk_bf16_f32 v43, v22, v23
	global_store_dwordx4 v2, v[40:43], s[12:13] nt
	v_cvt_pk_bf16_f32 v44, v24, v25
	v_cvt_pk_bf16_f32 v45, v26, v27
	v_cvt_pk_bf16_f32 v46, v28, v29
	v_cvt_pk_bf16_f32 v47, v30, v31
	global_store_dwordx4 v3, v[44:47], s[12:13] nt
	s_add_u32 s12, s12, 0x40000
	s_addc_u32 s13, s13, 0
	v_lshlrev_b32_e32 v48, 16, v80
	v_and_b32_e32 v49, 0xffff0000, v80
	v_fma_f32 v16, v88, v16, v48
	v_fma_f32 v17, v89, v17, v49
	v_lshlrev_b32_e32 v48, 16, v81
	v_and_b32_e32 v49, 0xffff0000, v81
	v_fma_f32 v18, v90, v18, v48
	v_fma_f32 v19, v91, v19, v49
	v_lshlrev_b32_e32 v48, 16, v82
	v_and_b32_e32 v49, 0xffff0000, v82
	v_fma_f32 v20, v92, v20, v48
	v_fma_f32 v21, v93, v21, v49
	v_lshlrev_b32_e32 v48, 16, v83
	v_and_b32_e32 v49, 0xffff0000, v83
	v_fma_f32 v22, v94, v22, v48
	v_fma_f32 v23, v95, v23, v49
	v_lshlrev_b32_e32 v48, 16, v84
	v_and_b32_e32 v49, 0xffff0000, v84
	v_fma_f32 v24, v88, v24, v48
	v_fma_f32 v25, v89, v25, v49
	v_lshlrev_b32_e32 v48, 16, v85
	v_and_b32_e32 v49, 0xffff0000, v85
	v_fma_f32 v26, v90, v26, v48
	v_fma_f32 v27, v91, v27, v49
	v_lshlrev_b32_e32 v48, 16, v86
	v_and_b32_e32 v49, 0xffff0000, v86
	v_fma_f32 v28, v92, v28, v48
	v_fma_f32 v29, v93, v29, v49
	v_lshlrev_b32_e32 v48, 16, v87
	v_and_b32_e32 v49, 0xffff0000, v87
	v_fma_f32 v30, v94, v30, v48
	v_fma_f32 v31, v95, v31, v49
	global_load_dwordx4 v[80:83], v2, s[10:11] nt
	global_load_dwordx4 v[84:87], v3, s[10:11] nt
	global_load_dwordx4 v[88:91], v5, s[16:17]
	global_load_dwordx4 v[92:95], v5, s[16:17] offset:16
	s_add_u32 s10, s10, 0x40000
	s_addc_u32 s11, s11, 0
	s_add_u32 s16, s16, 2048
	s_addc_u32 s17, s17, 0
	s_waitcnt vmcnt(42)
; __device__ __forceinline__ float bf2f(unsigned h) { return __uint_as_float(h << 16); }
; __device__ __forceinline__ unsigned pk2(float lo, float hi) { return pg8::cvt_pk_bf16(lo, hi); }
; __device__ __forceinline__ void b2_scan(const Ctx& C) {
;     ...
;     B2_LOAD(0, 0);
; #pragma unroll
;     for (int g = 0; g < 8; ++g) {
;         const int cur = g & 1;
;         if (g + 1 < 8) B2_LOAD(g + 1, cur ^ 1);
; #pragma unroll
;         for (int k = 0; k < 4; ++k) {
;             const int c = 4 * g + k;
;             const float dd[8] = {d0[cur][k][0], d0[cur][k][1], d0[cur][k][2], d0[cur][k][3], d1[cur][k][0], d1[cur][k][1], d1[cur][k][2], d1[cur][k][3]};
; #pragma unroll
;             for (int j = 0; j < 2; ++j) {
;                 v4u o; o.x = pk2(run[j][0], run[j][1]); o.y = pk2(run[j][2], run[j][3]); o.z = pk2(run[j][4], run[j][5]); o.w = pk2(run[j][6], run[j][7]);
;                 __builtin_nontemporal_store(o, (v4u*)(base + (size_t)c * cstride + (size_t)j * vstride));
;                 const unsigned lw[4] = {loc[cur][k][j].x, loc[cur][k][j].y, loc[cur][k][j].z, loc[cur][k][j].w};
; #pragma unroll
;                 for (int q = 0; q < 4; ++q) {
;                     run[j][2 * q] = dd[2 * q] * run[j][2 * q] + bf2f(lw[q] & 0xffffu);
;                     run[j][2 * q + 1] = dd[2 * q + 1] * run[j][2 * q + 1] + __uint_as_float(lw[q] & 0xffff0000u);
;                 }
;             }
	v_cvt_pk_bf16_f32 v32, v16, v17
	v_cvt_pk_bf16_f32 v33, v18, v19
	v_cvt_pk_bf16_f32 v34, v20, v21
	v_cvt_pk_bf16_f32 v35, v22, v23
	global_store_dwordx4 v2, v[32:35], s[12:13] nt
	v_cvt_pk_bf16_f32 v36, v24, v25
	v_cvt_pk_bf16_f32 v37, v26, v27
	v_cvt_pk_bf16_f32 v38, v28, v29
	v_cvt_pk_bf16_f32 v39, v30, v31
	global_store_dwordx4 v3, v[36:39], s[12:13] nt
	s_add_u32 s12, s12, 0x40000
	s_addc_u32 s13, s13, 0
	v_lshlrev_b32_e32 v48, 16, v96
	v_and_b32_e32 v49, 0xffff0000, v96
	v_fma_f32 v16, v104, v16, v48
	v_fma_f32 v17, v105, v17, v49
	v_lshlrev_b32_e32 v48, 16, v97
	v_and_b32_e32 v49, 0xffff0000, v97
	v_fma_f32 v18, v106, v18, v48
	v_fma_f32 v19, v107, v19, v49
	v_lshlrev_b32_e32 v48, 16, v98
	v_and_b32_e32 v49, 0xffff0000, v98
	v_fma_f32 v20, v108, v20, v48
	v_fma_f32 v21, v109, v21, v49
	v_lshlrev_b32_e32 v48, 16, v99
	v_and_b32_e32 v49, 0xffff0000, v99
	v_fma_f32 v22, v110, v22, v48
	v_fma_f32 v23, v111, v23, v49
	v_lshlrev_b32_e32 v48, 16, v100
	v_and_b32_e32 v49, 0xffff0000, v100
	v_fma_f32 v24, v104, v24, v48
	v_fma_f32 v25, v105, v25, v49
	v_lshlrev_b32_e32 v48, 16, v101
	v_and_b32_e32 v49, 0xffff0000, v101
	v_fma_f32 v26, v106, v26, v48
	v_fma_f32 v27, v107, v27, v49
	v_lshlrev_b32_e32 v48, 16, v102
	v_and_b32_e32 v49, 0xffff0000, v102
	v_fma_f32 v28, v108, v28, v48
	v_fma_f32 v29, v109, v29, v49
	v_lshlrev_b32_e32 v48, 16, v103
	v_and_b32_e32 v49, 0xffff0000, v103
	v_fma_f32 v30, v110, v30, v48
	v_fma_f32 v31, v111, v31, v49
	global_load_dwordx4 v[96:99], v2, s[10:11] nt
	global_load_dwordx4 v[100:103], v3, s[10:11] nt
	global_load_dwordx4 v[104:107], v5, s[16:17]
	global_load_dwordx4 v[108:111], v5, s[16:17] offset:16
	s_add_u32 s10, s10, 0x40000
	s_addc_u32 s11, s11, 0
	s_add_u32 s16, s16, 2048
	s_addc_u32 s17, s17, 0
	s_waitcnt vmcnt(42)
	v_cvt_pk_bf16_f32 v40, v16, v17
	v_cvt_pk_bf16_f32 v41, v18, v19
	v_cvt_pk_bf16_f32 v42, v20, v21
	v_cvt_pk_bf16_f32 v43, v22, v23
	global_store_dwordx4 v2, v[40:43], s[12:13] nt
	v_cvt_pk_bf16_f32 v44, v24, v25
	v_cvt_pk_bf16_f32 v45, v26, v27
	v_cvt_pk_bf16_f32 v46, v28, v29
	v_cvt_pk_bf16_f32 v47, v30, v31
	global_store_dwordx4 v3, v[44:47], s[12:13] nt
	s_add_u32 s12, s12, 0x40000
	s_addc_u32 s13, s13, 0
	v_lshlrev_b32_e32 v48, 16, v112
	v_and_b32_e32 v49, 0xffff0000, v112
	v_fma_f32 v16, v120, v16, v48
	v_fma_f32 v17, v121, v17, v49
	v_lshlrev_b32_e32 v48, 16, v113
	v_and_b32_e32 v49, 0xffff0000, v113
	v_fma_f32 v18, v122, v18, v48
	v_fma_f32 v19, v123, v19, v49
	v_lshlrev_b32_e32 v48, 16, v114
	v_and_b32_e32 v49, 0xffff0000, v114
	v_fma_f32 v20, v124, v20, v48
	v_fma_f32 v21, v125, v21, v49
	v_lshlrev_b32_e32 v48, 16, v115
	v_and_b32_e32 v49, 0xffff0000, v115
	v_fma_f32 v22, v126, v22, v48
	v_fma_f32 v23, v127, v23, v49
	v_lshlrev_b32_e32 v48, 16, v116
	v_and_b32_e32 v49, 0xffff0000, v116
	v_fma_f32 v24, v120, v24, v48
	v_fma_f32 v25, v121, v25, v49
	v_lshlrev_b32_e32 v48, 16, v117
	v_and_b32_e32 v49, 0xffff0000, v117
	v_fma_f32 v26, v122, v26, v48
	v_fma_f32 v27, v123, v27, v49
	v_lshlrev_b32_e32 v48, 16, v118
	v_and_b32_e32 v49, 0xffff0000, v118
	v_fma_f32 v28, v124, v28, v48
	v_fma_f32 v29, v125, v29, v49
	v_lshlrev_b32_e32 v48, 16, v119
	v_and_b32_e32 v49, 0xffff0000, v119
	v_fma_f32 v30, v126, v30, v48
	v_fma_f32 v31, v127, v31, v49
	global_load_dwordx4 v[112:115], v2, s[10:11] nt
	global_load_dwordx4 v[116:119], v3, s[10:11] nt
	global_load_dwordx4 v[120:123], v5, s[16:17]
	global_load_dwordx4 v[124:127], v5, s[16:17] offset:16
	s_add_u32 s10, s10, 0x40000
	s_addc_u32 s11, s11, 0
	s_add_u32 s16, s16, 2048
	s_addc_u32 s17, s17, 0
	s_waitcnt vmcnt(42)
	v_cvt_pk_bf16_f32 v32, v16, v17
	v_cvt_pk_bf16_f32 v33, v18, v19
	v_cvt_pk_bf16_f32 v34, v20, v21
	v_cvt_pk_bf16_f32 v35, v22, v23
	global_store_dwordx4 v2, v[32:35], s[12:13] nt
	v_cvt_pk_bf16_f32 v36, v24, v25
	v_cvt_pk_bf16_f32 v37, v26, v27
	v_cvt_pk_bf16_f32 v38, v28, v29
	v_cvt_pk_bf16_f32 v39, v30, v31
	global_store_dwordx4 v3, v[36:39], s[12:13] nt
	s_add_u32 s12, s12, 0x40000
	s_addc_u32 s13, s13, 0
	v_lshlrev_b32_e32 v48, 16, v128
	v_and_b32_e32 v49, 0xffff0000, v128
	v_fma_f32 v16, v136, v16, v48
	v_fma_f32 v17, v137, v17, v49
	v_lshlrev_b32_e32 v48, 16, v129
	v_and_b32_e32 v49, 0xffff0000, v129
	v_fma_f32 v18, v138, v18, v48
	v_fma_f32 v19, v139, v19, v49
	v_lshlrev_b32_e32 v48, 16, v130
	v_and_b32_e32 v49, 0xffff0000, v130
	v_fma_f32 v20, v140, v20, v48
	v_fma_f32 v21, v141, v21, v49
	v_lshlrev_b32_e32 v48, 16, v131
	v_and_b32_e32 v49, 0xffff0000, v131
	v_fma_f32 v22, v142, v22, v48
	v_fma_f32 v23, v143, v23, v49
	v_lshlrev_b32_e32 v48, 16, v132
	v_and_b32_e32 v49, 0xffff0000, v132
	v_fma_f32 v24, v136, v24, v48
	v_fma_f32 v25, v137, v25, v49
	v_lshlrev_b32_e32 v48, 16, v133
	v_and_b32_e32 v49, 0xffff0000, v133
	v_fma_f32 v26, v138, v26, v48
	v_fma_f32 v27, v139, v27, v49
	v_lshlrev_b32_e32 v48, 16, v134
	v_and_b32_e32 v49, 0xffff0000, v134
	v_fma_f32 v28, v140, v28, v48
	v_fma_f32 v29, v141, v29, v49
	v_lshlrev_b32_e32 v48, 16, v135
	v_and_b32_e32 v49, 0xffff0000, v135
	v_fma_f32 v30, v142, v30, v48
	v_fma_f32 v31, v143, v31, v49
	global_load_dwordx4 v[128:131], v2, s[10:11] nt
	global_load_dwordx4 v[132:135], v3, s[10:11] nt
	global_load_dwordx4 v[136:139], v5, s[16:17]
	global_load_dwordx4 v[140:143], v5, s[16:17] offset:16
	s_add_u32 s10, s10, 0x40000
	s_addc_u32 s11, s11, 0
	s_add_u32 s16, s16, 2048
	s_addc_u32 s17, s17, 0
	s_waitcnt vmcnt(42)
; __device__ __forceinline__ float bf2f(unsigned h) { return __uint_as_float(h << 16); }
; __device__ __forceinline__ unsigned pk2(float lo, float hi) { return pg8::cvt_pk_bf16(lo, hi); }
; __device__ __forceinline__ void b2_scan(const Ctx& C) {
;     ...
;     B2_LOAD(0, 0);
; #pragma unroll
;     for (int g = 0; g < 8; ++g) {
;         const int cur = g & 1;
;         if (g + 1 < 8) B2_LOAD(g + 1, cur ^ 1);
; #pragma unroll
;         for (int k = 0; k < 4; ++k) {
;             const int c = 4 * g + k;
;             const float dd[8] = {d0[cur][k][0], d0[cur][k][1], d0[cur][k][2], d0[cur][k][3], d1[cur][k][0], d1[cur][k][1], d1[cur][k][2], d1[cur][k][3]};
; #pragma unroll
;             for (int j = 0; j < 2; ++j) {
;                 v4u o; o.x = pk2(run[j][0], run[j][1]); o.y = pk2(run[j][2], run[j][3]); o.z = pk2(run[j][4], run[j][5]); o.w = pk2(run[j][6], run[j][7]);
;                 __builtin_nontemporal_store(o, (v4u*)(base + (size_t)c * cstride + (size_t)j * vstride));
;                 const unsigned lw[4] = {loc[cur][k][j].x, loc[cur][k][j].y, loc[cur][k][j].z, loc[cur][k][j].w};
; #pragma unroll
;                 for (int q = 0; q < 4; ++q) {
;                     run[j][2 * q] = dd[2 * q] * run[j][2 * q] + bf2f(lw[q] & 0xffffu);
;                     run[j][2 * q + 1] = dd[2 * q + 1] * run[j][2 * q + 1] + __uint_as_float(lw[q] & 0xffff0000u);
;                 }
;             }
	v_cvt_pk_bf16_f32 v40, v16, v17
	v_cvt_pk_bf16_f32 v41, v18, v19
	v_cvt_pk_bf16_f32 v42, v20, v21
	v_cvt_pk_bf16_f32 v43, v22, v23
	global_store_dwordx4 v2, v[40:43], s[12:13] nt
	v_cvt_pk_bf16_f32 v44, v24, v25
	v_cvt_pk_bf16_f32 v45, v26, v27
	v_cvt_pk_bf16_f32 v46, v28, v29
	v_cvt_pk_bf16_f32 v47, v30, v31
	global_store_dwordx4 v3, v[44:47], s[12:13] nt
	s_add_u32 s12, s12, 0x40000
	s_addc_u32 s13, s13, 0
	v_lshlrev_b32_e32 v48, 16, v144
	v_and_b32_e32 v49, 0xffff0000, v144
	v_fma_f32 v16, v152, v16, v48
	v_fma_f32 v17, v153, v17, v49
	v_lshlrev_b32_e32 v48, 16, v145
	v_and_b32_e32 v49, 0xffff0000, v145
	v_fma_f32 v18, v154, v18, v48
	v_fma_f32 v19, v155, v19, v49
	v_lshlrev_b32_e32 v48, 16, v146
	v_and_b32_e32 v49, 0xffff0000, v146
	v_fma_f32 v20, v156, v20, v48
	v_fma_f32 v21, v157, v21, v49
	v_lshlrev_b32_e32 v48, 16, v147
	v_and_b32_e32 v49, 0xffff0000, v147
	v_fma_f32 v22, v158, v22, v48
	v_fma_f32 v23, v159, v23, v49
	v_lshlrev_b32_e32 v48, 16, v148
	v_and_b32_e32 v49, 0xffff0000, v148
	v_fma_f32 v24, v152, v24, v48
	v_fma_f32 v25, v153, v25, v49
	v_lshlrev_b32_e32 v48, 16, v149
	v_and_b32_e32 v49, 0xffff0000, v149
	v_fma_f32 v26, v154, v26, v48
	v_fma_f32 v27, v155, v27, v49
	v_lshlrev_b32_e32 v48, 16, v150
	v_and_b32_e32 v49, 0xffff0000, v150
	v_fma_f32 v28, v156, v28, v48
	v_fma_f32 v29, v157, v29, v49
	v_lshlrev_b32_e32 v48, 16, v151
	v_and_b32_e32 v49, 0xffff0000, v151
	v_fma_f32 v30, v158, v30, v48
	v_fma_f32 v31, v159, v31, v49
	global_load_dwordx4 v[144:147], v2, s[10:11] nt
	global_load_dwordx4 v[148:151], v3, s[10:11] nt
	global_load_dwordx4 v[152:155], v5, s[16:17]
	global_load_dwordx4 v[156:159], v5, s[16:17] offset:16
	s_add_u32 s10, s10, 0x40000
	s_addc_u32 s11, s11, 0
	s_add_u32 s16, s16, 2048
	s_addc_u32 s17, s17, 0
	s_waitcnt vmcnt(42)
	v_cvt_pk_bf16_f32 v32, v16, v17
	v_cvt_pk_bf16_f32 v33, v18, v19
	v_cvt_pk_bf16_f32 v34, v20, v21
	v_cvt_pk_bf16_f32 v35, v22, v23
	global_store_dwordx4 v2, v[32:35], s[12:13] nt
	v_cvt_pk_bf16_f32 v36, v24, v25
	v_cvt_pk_bf16_f32 v37, v26, v27
	v_cvt_pk_bf16_f32 v38, v28, v29
	v_cvt_pk_bf16_f32 v39, v30, v31
	global_store_dwordx4 v3, v[36:39], s[12:13] nt
	s_add_u32 s12, s12, 0x40000
	s_addc_u32 s13, s13, 0
	v_lshlrev_b32_e32 v48, 16, v160
	v_and_b32_e32 v49, 0xffff0000, v160
	v_fma_f32 v16, v168, v16, v48
	v_fma_f32 v17, v169, v17, v49
	v_lshlrev_b32_e32 v48, 16, v161
	v_and_b32_e32 v49, 0xffff0000, v161
	v_fma_f32 v18, v170, v18, v48
	v_fma_f32 v19, v171, v19, v49
	v_lshlrev_b32_e32 v48, 16, v162
	v_and_b32_e32 v49, 0xffff0000, v162
	v_fma_f32 v20, v172, v20, v48
	v_fma_f32 v21, v173, v21, v49
	v_lshlrev_b32_e32 v48, 16, v163
	v_and_b32_e32 v49, 0xffff0000, v163
	v_fma_f32 v22, v174, v22, v48
	v_fma_f32 v23, v175, v23, v49
	v_lshlrev_b32_e32 v48, 16, v164
	v_and_b32_e32 v49, 0xffff0000, v164
	v_fma_f32 v24, v168, v24, v48
	v_fma_f32 v25, v169, v25, v49
	v_lshlrev_b32_e32 v48, 16, v165
	v_and_b32_e32 v49, 0xffff0000, v165
	v_fma_f32 v26, v170, v26, v48
	v_fma_f32 v27, v171, v27, v49
	v_lshlrev_b32_e32 v48, 16, v166
	v_and_b32_e32 v49, 0xffff0000, v166
	v_fma_f32 v28, v172, v28, v48
	v_fma_f32 v29, v173, v29, v49
	v_lshlrev_b32_e32 v48, 16, v167
	v_and_b32_e32 v49, 0xffff0000, v167
	v_fma_f32 v30, v174, v30, v48
	v_fma_f32 v31, v175, v31, v49
	global_load_dwordx4 v[160:163], v2, s[10:11] nt
	global_load_dwordx4 v[164:167], v3, s[10:11] nt
	global_load_dwordx4 v[168:171], v5, s[16:17]
	global_load_dwordx4 v[172:175], v5, s[16:17] offset:16
	s_add_u32 s10, s10, 0x40000
	s_addc_u32 s11, s11, 0
	s_add_u32 s16, s16, 2048
	s_addc_u32 s17, s17, 0
	s_waitcnt vmcnt(42)
	v_cvt_pk_bf16_f32 v40, v16, v17
	v_cvt_pk_bf16_f32 v41, v18, v19
	v_cvt_pk_bf16_f32 v42, v20, v21
	v_cvt_pk_bf16_f32 v43, v22, v23
	global_store_dwordx4 v2, v[40:43], s[12:13] nt
	v_cvt_pk_bf16_f32 v44, v24, v25
	v_cvt_pk_bf16_f32 v45, v26, v27
	v_cvt_pk_bf16_f32 v46, v28, v29
	v_cvt_pk_bf16_f32 v47, v30, v31
	global_store_dwordx4 v3, v[44:47], s[12:13] nt
	s_add_u32 s12, s12, 0x40000
	s_addc_u32 s13, s13, 0
	v_lshlrev_b32_e32 v48, 16, v176
	v_and_b32_e32 v49, 0xffff0000, v176
	v_fma_f32 v16, v184, v16, v48
	v_fma_f32 v17, v185, v17, v49
	v_lshlrev_b32_e32 v48, 16, v177
	v_and_b32_e32 v49, 0xffff0000, v177
	v_fma_f32 v18, v186, v18, v48
	v_fma_f32 v19, v187, v19, v49
	v_lshlrev_b32_e32 v48, 16, v178
	v_and_b32_e32 v49, 0xffff0000, v178
	v_fma_f32 v20, v188, v20, v48
	v_fma_f32 v21, v189, v21, v49
	v_lshlrev_b32_e32 v48, 16, v179
	v_and_b32_e32 v49, 0xffff0000, v179
	v_fma_f32 v22, v190, v22, v48
	v_fma_f32 v23, v191, v23, v49
	v_lshlrev_b32_e32 v48, 16, v180
	v_and_b32_e32 v49, 0xffff0000, v180
	v_fma_f32 v24, v184, v24, v48
	v_fma_f32 v25, v185, v25, v49
	v_lshlrev_b32_e32 v48, 16, v181
	v_and_b32_e32 v49, 0xffff0000, v181
	v_fma_f32 v26, v186, v26, v48
	v_fma_f32 v27, v187, v27, v49
	v_lshlrev_b32_e32 v48, 16, v182
	v_and_b32_e32 v49, 0xffff0000, v182
	v_fma_f32 v28, v188, v28, v48
	v_fma_f32 v29, v189, v29, v49
	v_lshlrev_b32_e32 v48, 16, v183
	v_and_b32_e32 v49, 0xffff0000, v183
	v_fma_f32 v30, v190, v30, v48
	v_fma_f32 v31, v191, v31, v49
	global_load_dwordx4 v[176:179], v2, s[10:11] nt
	global_load_dwordx4 v[180:183], v3, s[10:11] nt
	global_load_dwordx4 v[184:187], v5, s[16:17]
	global_load_dwordx4 v[188:191], v5, s[16:17] offset:16
	s_add_u32 s10, s10, 0x40000
	s_addc_u32 s11, s11, 0
	s_add_u32 s16, s16, 2048
	s_addc_u32 s17, s17, 0
	s_waitcnt vmcnt(42)
; __device__ __forceinline__ float bf2f(unsigned h) { return __uint_as_float(h << 16); }
; __device__ __forceinline__ unsigned pk2(float lo, float hi) { return pg8::cvt_pk_bf16(lo, hi); }
; __device__ __forceinline__ void b2_scan(const Ctx& C) {
;     ...
;     B2_LOAD(0, 0);
; #pragma unroll
;     for (int g = 0; g < 8; ++g) {
;         const int cur = g & 1;
;         if (g + 1 < 8) B2_LOAD(g + 1, cur ^ 1);
; #pragma unroll
;         for (int k = 0; k < 4; ++k) {
;             const int c = 4 * g + k;
;             const float dd[8] = {d0[cur][k][0], d0[cur][k][1], d0[cur][k][2], d0[cur][k][3], d1[cur][k][0], d1[cur][k][1], d1[cur][k][2], d1[cur][k][3]};
; #pragma unroll
;             for (int j = 0; j < 2; ++j) {
;                 v4u o; o.x = pk2(run[j][0], run[j][1]); o.y = pk2(run[j][2], run[j][3]); o.z = pk2(run[j][4], run[j][5]); o.w = pk2(run[j][6], run[j][7]);
;                 __builtin_nontemporal_store(o, (v4u*)(base + (size_t)c * cstride + (size_t)j * vstride));
;                 const unsigned lw[4] = {loc[cur][k][j].x, loc[cur][k][j].y, loc[cur][k][j].z, loc[cur][k][j].w};
; #pragma unroll
;                 for (int q = 0; q < 4; ++q) {
;                     run[j][2 * q] = dd[2 * q] * run[j][2 * q] + bf2f(lw[q] & 0xffffu);
;                     run[j][2 * q + 1] = dd[2 * q + 1] * run[j][2 * q + 1] + __uint_as_float(lw[q] & 0xffff0000u);
;                 }
;             }
	v_cvt_pk_bf16_f32 v32, v16, v17
	v_cvt_pk_bf16_f32 v33, v18, v19
	v_cvt_pk_bf16_f32 v34, v20, v21
	v_cvt_pk_bf16_f32 v35, v22, v23
	global_store_dwordx4 v2, v[32:35], s[12:13] nt
	v_cvt_pk_bf16_f32 v36, v24, v25
	v_cvt_pk_bf16_f32 v37, v26, v27
	v_cvt_pk_bf16_f32 v38, v28, v29
	v_cvt_pk_bf16_f32 v39, v30, v31
	global_store_dwordx4 v3, v[36:39], s[12:13] nt
	s_add_u32 s12, s12, 0x40000
	s_addc_u32 s13, s13, 0
	v_lshlrev_b32_e32 v48, 16, v64
	v_and_b32_e32 v49, 0xffff0000, v64
	v_fma_f32 v16, v72, v16, v48
	v_fma_f32 v17, v73, v17, v49
	v_lshlrev_b32_e32 v48, 16, v65
	v_and_b32_e32 v49, 0xffff0000, v65
	v_fma_f32 v18, v74, v18, v48
	v_fma_f32 v19, v75, v19, v49
	v_lshlrev_b32_e32 v48, 16, v66
	v_and_b32_e32 v49, 0xffff0000, v66
	v_fma_f32 v20, v76, v20, v48
	v_fma_f32 v21, v77, v21, v49
	v_lshlrev_b32_e32 v48, 16, v67
	v_and_b32_e32 v49, 0xffff0000, v67
	v_fma_f32 v22, v78, v22, v48
	v_fma_f32 v23, v79, v23, v49
	v_lshlrev_b32_e32 v48, 16, v68
	v_and_b32_e32 v49, 0xffff0000, v68
	v_fma_f32 v24, v72, v24, v48
	v_fma_f32 v25, v73, v25, v49
	v_lshlrev_b32_e32 v48, 16, v69
	v_and_b32_e32 v49, 0xffff0000, v69
	v_fma_f32 v26, v74, v26, v48
	v_fma_f32 v27, v75, v27, v49
	v_lshlrev_b32_e32 v48, 16, v70
	v_and_b32_e32 v49, 0xffff0000, v70
	v_fma_f32 v28, v76, v28, v48
	v_fma_f32 v29, v77, v29, v49
	v_lshlrev_b32_e32 v48, 16, v71
	v_and_b32_e32 v49, 0xffff0000, v71
	v_fma_f32 v30, v78, v30, v48
	v_fma_f32 v31, v79, v31, v49
	global_load_dwordx4 v[64:67], v2, s[10:11] nt
	global_load_dwordx4 v[68:71], v3, s[10:11] nt
	global_load_dwordx4 v[72:75], v5, s[16:17]
	global_load_dwordx4 v[76:79], v5, s[16:17] offset:16
	s_add_u32 s10, s10, 0x40000
	s_addc_u32 s11, s11, 0
	s_add_u32 s16, s16, 2048
	s_addc_u32 s17, s17, 0
	s_waitcnt vmcnt(42)
	v_cvt_pk_bf16_f32 v40, v16, v17
	v_cvt_pk_bf16_f32 v41, v18, v19
	v_cvt_pk_bf16_f32 v42, v20, v21
	v_cvt_pk_bf16_f32 v43, v22, v23
	global_store_dwordx4 v2, v[40:43], s[12:13] nt
	v_cvt_pk_bf16_f32 v44, v24, v25
	v_cvt_pk_bf16_f32 v45, v26, v27
	v_cvt_pk_bf16_f32 v46, v28, v29
	v_cvt_pk_bf16_f32 v47, v30, v31
	global_store_dwordx4 v3, v[44:47], s[12:13] nt
	s_add_u32 s12, s12, 0x40000
	s_addc_u32 s13, s13, 0
	v_lshlrev_b32_e32 v48, 16, v80
	v_and_b32_e32 v49, 0xffff0000, v80
	v_fma_f32 v16, v88, v16, v48
	v_fma_f32 v17, v89, v17, v49
	v_lshlrev_b32_e32 v48, 16, v81
	v_and_b32_e32 v49, 0xffff0000, v81
	v_fma_f32 v18, v90, v18, v48
	v_fma_f32 v19, v91, v19, v49
	v_lshlrev_b32_e32 v48, 16, v82
	v_and_b32_e32 v49, 0xffff0000, v82
	v_fma_f32 v20, v92, v20, v48
	v_fma_f32 v21, v93, v21, v49
	v_lshlrev_b32_e32 v48, 16, v83
	v_and_b32_e32 v49, 0xffff0000, v83
	v_fma_f32 v22, v94, v22, v48
	v_fma_f32 v23, v95, v23, v49
	v_lshlrev_b32_e32 v48, 16, v84
	v_and_b32_e32 v49, 0xffff0000, v84
	v_fma_f32 v24, v88, v24, v48
	v_fma_f32 v25, v89, v25, v49
	v_lshlrev_b32_e32 v48, 16, v85
	v_and_b32_e32 v49, 0xffff0000, v85
	v_fma_f32 v26, v90, v26, v48
	v_fma_f32 v27, v91, v27, v49
	v_lshlrev_b32_e32 v48, 16, v86
	v_and_b32_e32 v49, 0xffff0000, v86
	v_fma_f32 v28, v92, v28, v48
	v_fma_f32 v29, v93, v29, v49
	v_lshlrev_b32_e32 v48, 16, v87
	v_and_b32_e32 v49, 0xffff0000, v87
	v_fma_f32 v30, v94, v30, v48
	v_fma_f32 v31, v95, v31, v49
	global_load_dwordx4 v[80:83], v2, s[10:11] nt
	global_load_dwordx4 v[84:87], v3, s[10:11] nt
	global_load_dwordx4 v[88:91], v5, s[16:17]
	global_load_dwordx4 v[92:95], v5, s[16:17] offset:16
	s_add_u32 s10, s10, 0x40000
	s_addc_u32 s11, s11, 0
	s_add_u32 s16, s16, 2048
	s_addc_u32 s17, s17, 0
	s_waitcnt vmcnt(42)
	v_cvt_pk_bf16_f32 v32, v16, v17
	v_cvt_pk_bf16_f32 v33, v18, v19
	v_cvt_pk_bf16_f32 v34, v20, v21
	v_cvt_pk_bf16_f32 v35, v22, v23
	global_store_dwordx4 v2, v[32:35], s[12:13] nt
	v_cvt_pk_bf16_f32 v36, v24, v25
	v_cvt_pk_bf16_f32 v37, v26, v27
	v_cvt_pk_bf16_f32 v38, v28, v29
	v_cvt_pk_bf16_f32 v39, v30, v31
	global_store_dwordx4 v3, v[36:39], s[12:13] nt
	s_add_u32 s12, s12, 0x40000
	s_addc_u32 s13, s13, 0
	v_lshlrev_b32_e32 v48, 16, v96
	v_and_b32_e32 v49, 0xffff0000, v96
	v_fma_f32 v16, v104, v16, v48
	v_fma_f32 v17, v105, v17, v49
	v_lshlrev_b32_e32 v48, 16, v97
	v_and_b32_e32 v49, 0xffff0000, v97
	v_fma_f32 v18, v106, v18, v48
	v_fma_f32 v19, v107, v19, v49
	v_lshlrev_b32_e32 v48, 16, v98
	v_and_b32_e32 v49, 0xffff0000, v98
	v_fma_f32 v20, v108, v20, v48
	v_fma_f32 v21, v109, v21, v49
	v_lshlrev_b32_e32 v48, 16, v99
	v_and_b32_e32 v49, 0xffff0000, v99
	v_fma_f32 v22, v110, v22, v48
	v_fma_f32 v23, v111, v23, v49
	v_lshlrev_b32_e32 v48, 16, v100
	v_and_b32_e32 v49, 0xffff0000, v100
	v_fma_f32 v24, v104, v24, v48
	v_fma_f32 v25, v105, v25, v49
	v_lshlrev_b32_e32 v48, 16, v101
	v_and_b32_e32 v49, 0xffff0000, v101
	v_fma_f32 v26, v106, v26, v48
	v_fma_f32 v27, v107, v27, v49
	v_lshlrev_b32_e32 v48, 16, v102
	v_and_b32_e32 v49, 0xffff0000, v102
	v_fma_f32 v28, v108, v28, v48
	v_fma_f32 v29, v109, v29, v49
	v_lshlrev_b32_e32 v48, 16, v103
	v_and_b32_e32 v49, 0xffff0000, v103
	v_fma_f32 v30, v110, v30, v48
	v_fma_f32 v31, v111, v31, v49
	global_load_dwordx4 v[96:99], v2, s[10:11] nt
	global_load_dwordx4 v[100:103], v3, s[10:11] nt
	global_load_dwordx4 v[104:107], v5, s[16:17]
	global_load_dwordx4 v[108:111], v5, s[16:17] offset:16
	s_add_u32 s10, s10, 0x40000
	s_addc_u32 s11, s11, 0
	s_add_u32 s16, s16, 2048
	s_addc_u32 s17, s17, 0
	s_waitcnt vmcnt(42)
; __device__ __forceinline__ float bf2f(unsigned h) { return __uint_as_float(h << 16); }
; __device__ __forceinline__ unsigned pk2(float lo, float hi) { return pg8::cvt_pk_bf16(lo, hi); }
; __device__ __forceinline__ void b2_scan(const Ctx& C) {
;     ...
;     B2_LOAD(0, 0);
; #pragma unroll
;     for (int g = 0; g < 8; ++g) {
;         const int cur = g & 1;
;         if (g + 1 < 8) B2_LOAD(g + 1, cur ^ 1);
; #pragma unroll
;         for (int k = 0; k < 4; ++k) {
;             const int c = 4 * g + k;
;             const float dd[8] = {d0[cur][k][0], d0[cur][k][1], d0[cur][k][2], d0[cur][k][3], d1[cur][k][0], d1[cur][k][1], d1[cur][k][2], d1[cur][k][3]};
; #pragma unroll
;             for (int j = 0; j < 2; ++j) {
;                 v4u o; o.x = pk2(run[j][0], run[j][1]); o.y = pk2(run[j][2], run[j][3]); o.z = pk2(run[j][4], run[j][5]); o.w = pk2(run[j][6], run[j][7]);
;                 __builtin_nontemporal_store(o, (v4u*)(base + (size_t)c * cstride + (size_t)j * vstride));
;                 const unsigned lw[4] = {loc[cur][k][j].x, loc[cur][k][j].y, loc[cur][k][j].z, loc[cur][k][j].w};
; #pragma unroll
;                 for (int q = 0; q < 4; ++q) {
;                     run[j][2 * q] = dd[2 * q] * run[j][2 * q] + bf2f(lw[q] & 0xffffu);
;                     run[j][2 * q + 1] = dd[2 * q + 1] * run[j][2 * q + 1] + __uint_as_float(lw[q] & 0xffff0000u);
;                 }
;             }
	v_cvt_pk_bf16_f32 v40, v16, v17
	v_cvt_pk_bf16_f32 v41, v18, v19
	v_cvt_pk_bf16_f32 v42, v20, v21
	v_cvt_pk_bf16_f32 v43, v22, v23
	global_store_dwordx4 v2, v[40:43], s[12:13] nt
	v_cvt_pk_bf16_f32 v44, v24, v25
	v_cvt_pk_bf16_f32 v45, v26, v27
	v_cvt_pk_bf16_f32 v46, v28, v29
	v_cvt_pk_bf16_f32 v47, v30, v31
	global_store_dwordx4 v3, v[44:47], s[12:13] nt
	s_add_u32 s12, s12, 0x40000
	s_addc_u32 s13, s13, 0
	v_lshlrev_b32_e32 v48, 16, v112
	v_and_b32_e32 v49, 0xffff0000, v112
	v_fma_f32 v16, v120, v16, v48
	v_fma_f32 v17, v121, v17, v49
	v_lshlrev_b32_e32 v48, 16, v113
	v_and_b32_e32 v49, 0xffff0000, v113
	v_fma_f32 v18, v122, v18, v48
	v_fma_f32 v19, v123, v19, v49
	v_lshlrev_b32_e32 v48, 16, v114
	v_and_b32_e32 v49, 0xffff0000, v114
	v_fma_f32 v20, v124, v20, v48
	v_fma_f32 v21, v125, v21, v49
	v_lshlrev_b32_e32 v48, 16, v115
	v_and_b32_e32 v49, 0xffff0000, v115
	v_fma_f32 v22, v126, v22, v48
	v_fma_f32 v23, v127, v23, v49
	v_lshlrev_b32_e32 v48, 16, v116
	v_and_b32_e32 v49, 0xffff0000, v116
	v_fma_f32 v24, v120, v24, v48
	v_fma_f32 v25, v121, v25, v49
	v_lshlrev_b32_e32 v48, 16, v117
	v_and_b32_e32 v49, 0xffff0000, v117
	v_fma_f32 v26, v122, v26, v48
	v_fma_f32 v27, v123, v27, v49
	v_lshlrev_b32_e32 v48, 16, v118
	v_and_b32_e32 v49, 0xffff0000, v118
	v_fma_f32 v28, v124, v28, v48
	v_fma_f32 v29, v125, v29, v49
	v_lshlrev_b32_e32 v48, 16, v119
	v_and_b32_e32 v49, 0xffff0000, v119
	v_fma_f32 v30, v126, v30, v48
	v_fma_f32 v31, v127, v31, v49
	global_load_dwordx4 v[112:115], v2, s[10:11] nt
	global_load_dwordx4 v[116:119], v3, s[10:11] nt
	global_load_dwordx4 v[120:123], v5, s[16:17]
	global_load_dwordx4 v[124:127], v5, s[16:17] offset:16
	s_add_u32 s10, s10, 0x40000
	s_addc_u32 s11, s11, 0
	s_add_u32 s16, s16, 2048
	s_addc_u32 s17, s17, 0
	s_waitcnt vmcnt(42)
	v_cvt_pk_bf16_f32 v32, v16, v17
	v_cvt_pk_bf16_f32 v33, v18, v19
	v_cvt_pk_bf16_f32 v34, v20, v21
	v_cvt_pk_bf16_f32 v35, v22, v23
	global_store_dwordx4 v2, v[32:35], s[12:13] nt
	v_cvt_pk_bf16_f32 v36, v24, v25
	v_cvt_pk_bf16_f32 v37, v26, v27
	v_cvt_pk_bf16_f32 v38, v28, v29
	v_cvt_pk_bf16_f32 v39, v30, v31
	global_store_dwordx4 v3, v[36:39], s[12:13] nt
	s_add_u32 s12, s12, 0x40000
	s_addc_u32 s13, s13, 0
	v_lshlrev_b32_e32 v48, 16, v128
	v_and_b32_e32 v49, 0xffff0000, v128
	v_fma_f32 v16, v136, v16, v48
	v_fma_f32 v17, v137, v17, v49
	v_lshlrev_b32_e32 v48, 16, v129
	v_and_b32_e32 v49, 0xffff0000, v129
	v_fma_f32 v18, v138, v18, v48
	v_fma_f32 v19, v139, v19, v49
	v_lshlrev_b32_e32 v48, 16, v130
	v_and_b32_e32 v49, 0xffff0000, v130
	v_fma_f32 v20, v140, v20, v48
	v_fma_f32 v21, v141, v21, v49
	v_lshlrev_b32_e32 v48, 16, v131
	v_and_b32_e32 v49, 0xffff0000, v131
	v_fma_f32 v22, v142, v22, v48
	v_fma_f32 v23, v143, v23, v49
	v_lshlrev_b32_e32 v48, 16, v132
	v_and_b32_e32 v49, 0xffff0000, v132
	v_fma_f32 v24, v136, v24, v48
	v_fma_f32 v25, v137, v25, v49
	v_lshlrev_b32_e32 v48, 16, v133
	v_and_b32_e32 v49, 0xffff0000, v133
	v_fma_f32 v26, v138, v26, v48
	v_fma_f32 v27, v139, v27, v49
	v_lshlrev_b32_e32 v48, 16, v134
	v_and_b32_e32 v49, 0xffff0000, v134
	v_fma_f32 v28, v140, v28, v48
	v_fma_f32 v29, v141, v29, v49
	v_lshlrev_b32_e32 v48, 16, v135
	v_and_b32_e32 v49, 0xffff0000, v135
	v_fma_f32 v30, v142, v30, v48
	v_fma_f32 v31, v143, v31, v49
	global_load_dwordx4 v[128:131], v2, s[10:11] nt
	global_load_dwordx4 v[132:135], v3, s[10:11] nt
	global_load_dwordx4 v[136:139], v5, s[16:17]
	global_load_dwordx4 v[140:143], v5, s[16:17] offset:16
	s_add_u32 s10, s10, 0x40000
	s_addc_u32 s11, s11, 0
	s_add_u32 s16, s16, 2048
	s_addc_u32 s17, s17, 0
	s_waitcnt vmcnt(42)
	v_cvt_pk_bf16_f32 v40, v16, v17
	v_cvt_pk_bf16_f32 v41, v18, v19
	v_cvt_pk_bf16_f32 v42, v20, v21
	v_cvt_pk_bf16_f32 v43, v22, v23
	global_store_dwordx4 v2, v[40:43], s[12:13] nt
	v_cvt_pk_bf16_f32 v44, v24, v25
	v_cvt_pk_bf16_f32 v45, v26, v27
	v_cvt_pk_bf16_f32 v46, v28, v29
	v_cvt_pk_bf16_f32 v47, v30, v31
	global_store_dwordx4 v3, v[44:47], s[12:13] nt
	s_add_u32 s12, s12, 0x40000
	s_addc_u32 s13, s13, 0
	v_lshlrev_b32_e32 v48, 16, v144
	v_and_b32_e32 v49, 0xffff0000, v144
	v_fma_f32 v16, v152, v16, v48
	v_fma_f32 v17, v153, v17, v49
	v_lshlrev_b32_e32 v48, 16, v145
	v_and_b32_e32 v49, 0xffff0000, v145
	v_fma_f32 v18, v154, v18, v48
	v_fma_f32 v19, v155, v19, v49
	v_lshlrev_b32_e32 v48, 16, v146
	v_and_b32_e32 v49, 0xffff0000, v146
	v_fma_f32 v20, v156, v20, v48
	v_fma_f32 v21, v157, v21, v49
	v_lshlrev_b32_e32 v48, 16, v147
	v_and_b32_e32 v49, 0xffff0000, v147
	v_fma_f32 v22, v158, v22, v48
	v_fma_f32 v23, v159, v23, v49
	v_lshlrev_b32_e32 v48, 16, v148
	v_and_b32_e32 v49, 0xffff0000, v148
	v_fma_f32 v24, v152, v24, v48
	v_fma_f32 v25, v153, v25, v49
	v_lshlrev_b32_e32 v48, 16, v149
	v_and_b32_e32 v49, 0xffff0000, v149
	v_fma_f32 v26, v154, v26, v48
	v_fma_f32 v27, v155, v27, v49
	v_lshlrev_b32_e32 v48, 16, v150
	v_and_b32_e32 v49, 0xffff0000, v150
	v_fma_f32 v28, v156, v28, v48
	v_fma_f32 v29, v157, v29, v49
	v_lshlrev_b32_e32 v48, 16, v151
	v_and_b32_e32 v49, 0xffff0000, v151
	v_fma_f32 v30, v158, v30, v48
	v_fma_f32 v31, v159, v31, v49
	global_load_dwordx4 v[144:147], v2, s[10:11] nt
	global_load_dwordx4 v[148:151], v3, s[10:11] nt
	global_load_dwordx4 v[152:155], v5, s[16:17]
	global_load_dwordx4 v[156:159], v5, s[16:17] offset:16
	s_add_u32 s10, s10, 0x40000
	s_addc_u32 s11, s11, 0
	s_add_u32 s16, s16, 2048
	s_addc_u32 s17, s17, 0
	s_waitcnt vmcnt(42)
; __device__ __forceinline__ float bf2f(unsigned h) { return __uint_as_float(h << 16); }
; __device__ __forceinline__ unsigned pk2(float lo, float hi) { return pg8::cvt_pk_bf16(lo, hi); }
; __device__ __forceinline__ void b2_scan(const Ctx& C) {
;     ...
;     B2_LOAD(0, 0);
; #pragma unroll
;     for (int g = 0; g < 8; ++g) {
;         const int cur = g & 1;
;         if (g + 1 < 8) B2_LOAD(g + 1, cur ^ 1);
; #pragma unroll
;         for (int k = 0; k < 4; ++k) {
;             const int c = 4 * g + k;
;             const float dd[8] = {d0[cur][k][0], d0[cur][k][1], d0[cur][k][2], d0[cur][k][3], d1[cur][k][0], d1[cur][k][1], d1[cur][k][2], d1[cur][k][3]};
; #pragma unroll
;             for (int j = 0; j < 2; ++j) {
;                 v4u o; o.x = pk2(run[j][0], run[j][1]); o.y = pk2(run[j][2], run[j][3]); o.z = pk2(run[j][4], run[j][5]); o.w = pk2(run[j][6], run[j][7]);
;                 __builtin_nontemporal_store(o, (v4u*)(base + (size_t)c * cstride + (size_t)j * vstride));
;                 const unsigned lw[4] = {loc[cur][k][j].x, loc[cur][k][j].y, loc[cur][k][j].z, loc[cur][k][j].w};
; #pragma unroll
;                 for (int q = 0; q < 4; ++q) {
;                     run[j][2 * q] = dd[2 * q] * run[j][2 * q] + bf2f(lw[q] & 0xffffu);
;                     run[j][2 * q + 1] = dd[2 * q + 1] * run[j][2 * q + 1] + __uint_as_float(lw[q] & 0xffff0000u);
;                 }
;             }
	v_cvt_pk_bf16_f32 v32, v16, v17
	v_cvt_pk_bf16_f32 v33, v18, v19
	v_cvt_pk_bf16_f32 v34, v20, v21
	v_cvt_pk_bf16_f32 v35, v22, v23
	global_store_dwordx4 v2, v[32:35], s[12:13] nt
	v_cvt_pk_bf16_f32 v36, v24, v25
	v_cvt_pk_bf16_f32 v37, v26, v27
	v_cvt_pk_bf16_f32 v38, v28, v29
	v_cvt_pk_bf16_f32 v39, v30, v31
	global_store_dwordx4 v3, v[36:39], s[12:13] nt
	s_add_u32 s12, s12, 0x40000
	s_addc_u32 s13, s13, 0
	v_lshlrev_b32_e32 v48, 16, v160
	v_and_b32_e32 v49, 0xffff0000, v160
	v_fma_f32 v16, v168, v16, v48
	v_fma_f32 v17, v169, v17, v49
	v_lshlrev_b32_e32 v48, 16, v161
	v_and_b32_e32 v49, 0xffff0000, v161
	v_fma_f32 v18, v170, v18, v48
	v_fma_f32 v19, v171, v19, v49
	v_lshlrev_b32_e32 v48, 16, v162
	v_and_b32_e32 v49, 0xffff0000, v162
	v_fma_f32 v20, v172, v20, v48
	v_fma_f32 v21, v173, v21, v49
	v_lshlrev_b32_e32 v48, 16, v163
	v_and_b32_e32 v49, 0xffff0000, v163
	v_fma_f32 v22, v174, v22, v48
	v_fma_f32 v23, v175, v23, v49
	v_lshlrev_b32_e32 v48, 16, v164
	v_and_b32_e32 v49, 0xffff0000, v164
	v_fma_f32 v24, v168, v24, v48
	v_fma_f32 v25, v169, v25, v49
	v_lshlrev_b32_e32 v48, 16, v165
	v_and_b32_e32 v49, 0xffff0000, v165
	v_fma_f32 v26, v170, v26, v48
	v_fma_f32 v27, v171, v27, v49
	v_lshlrev_b32_e32 v48, 16, v166
	v_and_b32_e32 v49, 0xffff0000, v166
	v_fma_f32 v28, v172, v28, v48
	v_fma_f32 v29, v173, v29, v49
	v_lshlrev_b32_e32 v48, 16, v167
	v_and_b32_e32 v49, 0xffff0000, v167
	v_fma_f32 v30, v174, v30, v48
	v_fma_f32 v31, v175, v31, v49
	global_load_dwordx4 v[160:163], v2, s[10:11] nt
	global_load_dwordx4 v[164:167], v3, s[10:11] nt
	global_load_dwordx4 v[168:171], v5, s[16:17]
	global_load_dwordx4 v[172:175], v5, s[16:17] offset:16
	s_add_u32 s10, s10, 0x40000
	s_addc_u32 s11, s11, 0
	s_add_u32 s16, s16, 2048
	s_addc_u32 s17, s17, 0
	s_waitcnt vmcnt(42)
	v_cvt_pk_bf16_f32 v40, v16, v17
	v_cvt_pk_bf16_f32 v41, v18, v19
	v_cvt_pk_bf16_f32 v42, v20, v21
	v_cvt_pk_bf16_f32 v43, v22, v23
	global_store_dwordx4 v2, v[40:43], s[12:13] nt
	v_cvt_pk_bf16_f32 v44, v24, v25
	v_cvt_pk_bf16_f32 v45, v26, v27
	v_cvt_pk_bf16_f32 v46, v28, v29
	v_cvt_pk_bf16_f32 v47, v30, v31
	global_store_dwordx4 v3, v[44:47], s[12:13] nt
	s_add_u32 s12, s12, 0x40000
	s_addc_u32 s13, s13, 0
	v_lshlrev_b32_e32 v48, 16, v176
	v_and_b32_e32 v49, 0xffff0000, v176
	v_fma_f32 v16, v184, v16, v48
	v_fma_f32 v17, v185, v17, v49
	v_lshlrev_b32_e32 v48, 16, v177
	v_and_b32_e32 v49, 0xffff0000, v177
	v_fma_f32 v18, v186, v18, v48
	v_fma_f32 v19, v187, v19, v49
	v_lshlrev_b32_e32 v48, 16, v178
	v_and_b32_e32 v49, 0xffff0000, v178
	v_fma_f32 v20, v188, v20, v48
	v_fma_f32 v21, v189, v21, v49
	v_lshlrev_b32_e32 v48, 16, v179
	v_and_b32_e32 v49, 0xffff0000, v179
	v_fma_f32 v22, v190, v22, v48
	v_fma_f32 v23, v191, v23, v49
	v_lshlrev_b32_e32 v48, 16, v180
	v_and_b32_e32 v49, 0xffff0000, v180
	v_fma_f32 v24, v184, v24, v48
	v_fma_f32 v25, v185, v25, v49
	v_lshlrev_b32_e32 v48, 16, v181
	v_and_b32_e32 v49, 0xffff0000, v181
	v_fma_f32 v26, v186, v26, v48
	v_fma_f32 v27, v187, v27, v49
	v_lshlrev_b32_e32 v48, 16, v182
	v_and_b32_e32 v49, 0xffff0000, v182
	v_fma_f32 v28, v188, v28, v48
	v_fma_f32 v29, v189, v29, v49
	v_lshlrev_b32_e32 v48, 16, v183
	v_and_b32_e32 v49, 0xffff0000, v183
	v_fma_f32 v30, v190, v30, v48
	v_fma_f32 v31, v191, v31, v49
	global_load_dwordx4 v[176:179], v2, s[10:11] nt
	global_load_dwordx4 v[180:183], v3, s[10:11] nt
	global_load_dwordx4 v[184:187], v5, s[16:17]
	global_load_dwordx4 v[188:191], v5, s[16:17] offset:16
	s_add_u32 s10, s10, 0x40000
	s_addc_u32 s11, s11, 0
	s_add_u32 s16, s16, 2048
	s_addc_u32 s17, s17, 0
	s_waitcnt vmcnt(42)
	v_cvt_pk_bf16_f32 v32, v16, v17
	v_cvt_pk_bf16_f32 v33, v18, v19
	v_cvt_pk_bf16_f32 v34, v20, v21
	v_cvt_pk_bf16_f32 v35, v22, v23
	global_store_dwordx4 v2, v[32:35], s[12:13] nt
	v_cvt_pk_bf16_f32 v36, v24, v25
	v_cvt_pk_bf16_f32 v37, v26, v27
	v_cvt_pk_bf16_f32 v38, v28, v29
	v_cvt_pk_bf16_f32 v39, v30, v31
	global_store_dwordx4 v3, v[36:39], s[12:13] nt
	s_add_u32 s12, s12, 0x40000
	s_addc_u32 s13, s13, 0
	v_lshlrev_b32_e32 v48, 16, v64
	v_and_b32_e32 v49, 0xffff0000, v64
	v_fma_f32 v16, v72, v16, v48
	v_fma_f32 v17, v73, v17, v49
	v_lshlrev_b32_e32 v48, 16, v65
	v_and_b32_e32 v49, 0xffff0000, v65
	v_fma_f32 v18, v74, v18, v48
	v_fma_f32 v19, v75, v19, v49
	v_lshlrev_b32_e32 v48, 16, v66
	v_and_b32_e32 v49, 0xffff0000, v66
	v_fma_f32 v20, v76, v20, v48
	v_fma_f32 v21, v77, v21, v49
	v_lshlrev_b32_e32 v48, 16, v67
	v_and_b32_e32 v49, 0xffff0000, v67
	v_fma_f32 v22, v78, v22, v48
	v_fma_f32 v23, v79, v23, v49
	v_lshlrev_b32_e32 v48, 16, v68
	v_and_b32_e32 v49, 0xffff0000, v68
	v_fma_f32 v24, v72, v24, v48
	v_fma_f32 v25, v73, v25, v49
	v_lshlrev_b32_e32 v48, 16, v69
	v_and_b32_e32 v49, 0xffff0000, v69
	v_fma_f32 v26, v74, v26, v48
	v_fma_f32 v27, v75, v27, v49
	v_lshlrev_b32_e32 v48, 16, v70
	v_and_b32_e32 v49, 0xffff0000, v70
	v_fma_f32 v28, v76, v28, v48
	v_fma_f32 v29, v77, v29, v49
	v_lshlrev_b32_e32 v48, 16, v71
	v_and_b32_e32 v49, 0xffff0000, v71
	v_fma_f32 v30, v78, v30, v48
	v_fma_f32 v31, v79, v31, v49
	s_waitcnt vmcnt(38)
; __device__ __forceinline__ float bf2f(unsigned h) { return __uint_as_float(h << 16); }
; __device__ __forceinline__ unsigned pk2(float lo, float hi) { return pg8::cvt_pk_bf16(lo, hi); }
; __device__ __forceinline__ void b2_scan(const Ctx& C) {
;     ...
;     B2_LOAD(0, 0);
; #pragma unroll
;     for (int g = 0; g < 8; ++g) {
;         const int cur = g & 1;
;         if (g + 1 < 8) B2_LOAD(g + 1, cur ^ 1);
; #pragma unroll
;         for (int k = 0; k < 4; ++k) {
;             const int c = 4 * g + k;
;             const float dd[8] = {d0[cur][k][0], d0[cur][k][1], d0[cur][k][2], d0[cur][k][3], d1[cur][k][0], d1[cur][k][1], d1[cur][k][2], d1[cur][k][3]};
; #pragma unroll
;             for (int j = 0; j < 2; ++j) {
;                 v4u o; o.x = pk2(run[j][0], run[j][1]); o.y = pk2(run[j][2], run[j][3]); o.z = pk2(run[j][4], run[j][5]); o.w = pk2(run[j][6], run[j][7]);
;                 __builtin_nontemporal_store(o, (v4u*)(base + (size_t)c * cstride + (size_t)j * vstride));
;                 const unsigned lw[4] = {loc[cur][k][j].x, loc[cur][k][j].y, loc[cur][k][j].z, loc[cur][k][j].w};
; #pragma unroll
;                 for (int q = 0; q < 4; ++q) {
;                     run[j][2 * q] = dd[2 * q] * run[j][2 * q] + bf2f(lw[q] & 0xffffu);
;                     run[j][2 * q + 1] = dd[2 * q + 1] * run[j][2 * q + 1] + __uint_as_float(lw[q] & 0xffff0000u);
;                 }
;             }
	v_cvt_pk_bf16_f32 v40, v16, v17
	v_cvt_pk_bf16_f32 v41, v18, v19
	v_cvt_pk_bf16_f32 v42, v20, v21
	v_cvt_pk_bf16_f32 v43, v22, v23
	global_store_dwordx4 v2, v[40:43], s[12:13] nt
	v_cvt_pk_bf16_f32 v44, v24, v25
	v_cvt_pk_bf16_f32 v45, v26, v27
	v_cvt_pk_bf16_f32 v46, v28, v29
	v_cvt_pk_bf16_f32 v47, v30, v31
	global_store_dwordx4 v3, v[44:47], s[12:13] nt
	s_add_u32 s12, s12, 0x40000
	s_addc_u32 s13, s13, 0
	v_lshlrev_b32_e32 v48, 16, v80
	v_and_b32_e32 v49, 0xffff0000, v80
	v_fma_f32 v16, v88, v16, v48
	v_fma_f32 v17, v89, v17, v49
	v_lshlrev_b32_e32 v48, 16, v81
	v_and_b32_e32 v49, 0xffff0000, v81
	v_fma_f32 v18, v90, v18, v48
	v_fma_f32 v19, v91, v19, v49
	v_lshlrev_b32_e32 v48, 16, v82
	v_and_b32_e32 v49, 0xffff0000, v82
	v_fma_f32 v20, v92, v20, v48
	v_fma_f32 v21, v93, v21, v49
	v_lshlrev_b32_e32 v48, 16, v83
	v_and_b32_e32 v49, 0xffff0000, v83
	v_fma_f32 v22, v94, v22, v48
	v_fma_f32 v23, v95, v23, v49
	v_lshlrev_b32_e32 v48, 16, v84
	v_and_b32_e32 v49, 0xffff0000, v84
	v_fma_f32 v24, v88, v24, v48
	v_fma_f32 v25, v89, v25, v49
	v_lshlrev_b32_e32 v48, 16, v85
	v_and_b32_e32 v49, 0xffff0000, v85
	v_fma_f32 v26, v90, v26, v48
	v_fma_f32 v27, v91, v27, v49
	v_lshlrev_b32_e32 v48, 16, v86
	v_and_b32_e32 v49, 0xffff0000, v86
	v_fma_f32 v28, v92, v28, v48
	v_fma_f32 v29, v93, v29, v49
	v_lshlrev_b32_e32 v48, 16, v87
	v_and_b32_e32 v49, 0xffff0000, v87
	v_fma_f32 v30, v94, v30, v48
	v_fma_f32 v31, v95, v31, v49
	s_waitcnt vmcnt(34)
	v_cvt_pk_bf16_f32 v32, v16, v17
	v_cvt_pk_bf16_f32 v33, v18, v19
	v_cvt_pk_bf16_f32 v34, v20, v21
	v_cvt_pk_bf16_f32 v35, v22, v23
	global_store_dwordx4 v2, v[32:35], s[12:13] nt
	v_cvt_pk_bf16_f32 v36, v24, v25
	v_cvt_pk_bf16_f32 v37, v26, v27
	v_cvt_pk_bf16_f32 v38, v28, v29
	v_cvt_pk_bf16_f32 v39, v30, v31
	global_store_dwordx4 v3, v[36:39], s[12:13] nt
	s_add_u32 s12, s12, 0x40000
	s_addc_u32 s13, s13, 0
	v_lshlrev_b32_e32 v48, 16, v96
	v_and_b32_e32 v49, 0xffff0000, v96
	v_fma_f32 v16, v104, v16, v48
	v_fma_f32 v17, v105, v17, v49
	v_lshlrev_b32_e32 v48, 16, v97
	v_and_b32_e32 v49, 0xffff0000, v97
	v_fma_f32 v18, v106, v18, v48
	v_fma_f32 v19, v107, v19, v49
	v_lshlrev_b32_e32 v48, 16, v98
	v_and_b32_e32 v49, 0xffff0000, v98
	v_fma_f32 v20, v108, v20, v48
	v_fma_f32 v21, v109, v21, v49
	v_lshlrev_b32_e32 v48, 16, v99
	v_and_b32_e32 v49, 0xffff0000, v99
	v_fma_f32 v22, v110, v22, v48
	v_fma_f32 v23, v111, v23, v49
	v_lshlrev_b32_e32 v48, 16, v100
	v_and_b32_e32 v49, 0xffff0000, v100
	v_fma_f32 v24, v104, v24, v48
	v_fma_f32 v25, v105, v25, v49
	v_lshlrev_b32_e32 v48, 16, v101
	v_and_b32_e32 v49, 0xffff0000, v101
	v_fma_f32 v26, v106, v26, v48
	v_fma_f32 v27, v107, v27, v49
	v_lshlrev_b32_e32 v48, 16, v102
	v_and_b32_e32 v49, 0xffff0000, v102
	v_fma_f32 v28, v108, v28, v48
	v_fma_f32 v29, v109, v29, v49
	v_lshlrev_b32_e32 v48, 16, v103
	v_and_b32_e32 v49, 0xffff0000, v103
	v_fma_f32 v30, v110, v30, v48
	v_fma_f32 v31, v111, v31, v49
	s_waitcnt vmcnt(30)
	v_cvt_pk_bf16_f32 v40, v16, v17
	v_cvt_pk_bf16_f32 v41, v18, v19
	v_cvt_pk_bf16_f32 v42, v20, v21
	v_cvt_pk_bf16_f32 v43, v22, v23
	global_store_dwordx4 v2, v[40:43], s[12:13] nt
	v_cvt_pk_bf16_f32 v44, v24, v25
	v_cvt_pk_bf16_f32 v45, v26, v27
	v_cvt_pk_bf16_f32 v46, v28, v29
	v_cvt_pk_bf16_f32 v47, v30, v31
	global_store_dwordx4 v3, v[44:47], s[12:13] nt
	s_add_u32 s12, s12, 0x40000
	s_addc_u32 s13, s13, 0
	v_lshlrev_b32_e32 v48, 16, v112
	v_and_b32_e32 v49, 0xffff0000, v112
	v_fma_f32 v16, v120, v16, v48
	v_fma_f32 v17, v121, v17, v49
	v_lshlrev_b32_e32 v48, 16, v113
	v_and_b32_e32 v49, 0xffff0000, v113
	v_fma_f32 v18, v122, v18, v48
	v_fma_f32 v19, v123, v19, v49
	v_lshlrev_b32_e32 v48, 16, v114
	v_and_b32_e32 v49, 0xffff0000, v114
	v_fma_f32 v20, v124, v20, v48
	v_fma_f32 v21, v125, v21, v49
	v_lshlrev_b32_e32 v48, 16, v115
	v_and_b32_e32 v49, 0xffff0000, v115
	v_fma_f32 v22, v126, v22, v48
	v_fma_f32 v23, v127, v23, v49
	v_lshlrev_b32_e32 v48, 16, v116
	v_and_b32_e32 v49, 0xffff0000, v116
	v_fma_f32 v24, v120, v24, v48
	v_fma_f32 v25, v121, v25, v49
	v_lshlrev_b32_e32 v48, 16, v117
	v_and_b32_e32 v49, 0xffff0000, v117
	v_fma_f32 v26, v122, v26, v48
	v_fma_f32 v27, v123, v27, v49
	v_lshlrev_b32_e32 v48, 16, v118
	v_and_b32_e32 v49, 0xffff0000, v118
	v_fma_f32 v28, v124, v28, v48
	v_fma_f32 v29, v125, v29, v49
	v_lshlrev_b32_e32 v48, 16, v119
	v_and_b32_e32 v49, 0xffff0000, v119
	v_fma_f32 v30, v126, v30, v48
	v_fma_f32 v31, v127, v31, v49
	s_waitcnt vmcnt(26)
	v_cvt_pk_bf16_f32 v32, v16, v17
	v_cvt_pk_bf16_f32 v33, v18, v19
	v_cvt_pk_bf16_f32 v34, v20, v21
	v_cvt_pk_bf16_f32 v35, v22, v23
	global_store_dwordx4 v2, v[32:35], s[12:13] nt
	v_cvt_pk_bf16_f32 v36, v24, v25
	v_cvt_pk_bf16_f32 v37, v26, v27
	v_cvt_pk_bf16_f32 v38, v28, v29
	v_cvt_pk_bf16_f32 v39, v30, v31
	global_store_dwordx4 v3, v[36:39], s[12:13] nt
	s_add_u32 s12, s12, 0x40000
	s_addc_u32 s13, s13, 0
	v_lshlrev_b32_e32 v48, 16, v128
	v_and_b32_e32 v49, 0xffff0000, v128
	v_fma_f32 v16, v136, v16, v48
	v_fma_f32 v17, v137, v17, v49
	v_lshlrev_b32_e32 v48, 16, v129
	v_and_b32_e32 v49, 0xffff0000, v129
	v_fma_f32 v18, v138, v18, v48
	v_fma_f32 v19, v139, v19, v49
	v_lshlrev_b32_e32 v48, 16, v130
	v_and_b32_e32 v49, 0xffff0000, v130
	v_fma_f32 v20, v140, v20, v48
	v_fma_f32 v21, v141, v21, v49
	v_lshlrev_b32_e32 v48, 16, v131
	v_and_b32_e32 v49, 0xffff0000, v131
	v_fma_f32 v22, v142, v22, v48
	v_fma_f32 v23, v143, v23, v49
	v_lshlrev_b32_e32 v48, 16, v132
	v_and_b32_e32 v49, 0xffff0000, v132
	v_fma_f32 v24, v136, v24, v48
	v_fma_f32 v25, v137, v25, v49
	v_lshlrev_b32_e32 v48, 16, v133
	v_and_b32_e32 v49, 0xffff0000, v133
	v_fma_f32 v26, v138, v26, v48
	v_fma_f32 v27, v139, v27, v49
	v_lshlrev_b32_e32 v48, 16, v134
	v_and_b32_e32 v49, 0xffff0000, v134
	v_fma_f32 v28, v140, v28, v48
	v_fma_f32 v29, v141, v29, v49
	v_lshlrev_b32_e32 v48, 16, v135
	v_and_b32_e32 v49, 0xffff0000, v135
	v_fma_f32 v30, v142, v30, v48
	v_fma_f32 v31, v143, v31, v49
	s_waitcnt vmcnt(22)
; __device__ __forceinline__ float bf2f(unsigned h) { return __uint_as_float(h << 16); }
; __device__ __forceinline__ unsigned pk2(float lo, float hi) { return pg8::cvt_pk_bf16(lo, hi); }
; __device__ __forceinline__ void b2_scan(const Ctx& C) {
;     ...
;         for (int k = 0; k < 4; ++k) {
;             const int c = 4 * g + k;
;             const float dd[8] = {d0[cur][k][0], d0[cur][k][1], d0[cur][k][2], d0[cur][k][3], d1[cur][k][0], d1[cur][k][1], d1[cur][k][2], d1[cur][k][3]};
; #pragma unroll
;             for (int j = 0; j < 2; ++j) {
;                 v4u o; o.x = pk2(run[j][0], run[j][1]); o.y = pk2(run[j][2], run[j][3]); o.z = pk2(run[j][4], run[j][5]); o.w = pk2(run[j][6], run[j][7]);
;                 __builtin_nontemporal_store(o, (v4u*)(base + (size_t)c * cstride + (size_t)j * vstride));
;                 const unsigned lw[4] = {loc[cur][k][j].x, loc[cur][k][j].y, loc[cur][k][j].z, loc[cur][k][j].w};
; #pragma unroll
;                 for (int q = 0; q < 4; ++q) {
;                     run[j][2 * q] = dd[2 * q] * run[j][2 * q] + bf2f(lw[q] & 0xffffu);
;                     run[j][2 * q + 1] = dd[2 * q + 1] * run[j][2 * q + 1] + __uint_as_float(lw[q] & 0xffff0000u);
;                 }
;             }
	v_cvt_pk_bf16_f32 v40, v16, v17
	v_cvt_pk_bf16_f32 v41, v18, v19
	v_cvt_pk_bf16_f32 v42, v20, v21
	v_cvt_pk_bf16_f32 v43, v22, v23
	global_store_dwordx4 v2, v[40:43], s[12:13] nt
	v_cvt_pk_bf16_f32 v44, v24, v25
	v_cvt_pk_bf16_f32 v45, v26, v27
	v_cvt_pk_bf16_f32 v46, v28, v29
	v_cvt_pk_bf16_f32 v47, v30, v31
	global_store_dwordx4 v3, v[44:47], s[12:13] nt
	s_add_u32 s12, s12, 0x40000
	s_addc_u32 s13, s13, 0
	v_lshlrev_b32_e32 v48, 16, v144
	v_and_b32_e32 v49, 0xffff0000, v144
	v_fma_f32 v16, v152, v16, v48
	v_fma_f32 v17, v153, v17, v49
	v_lshlrev_b32_e32 v48, 16, v145
	v_and_b32_e32 v49, 0xffff0000, v145
	v_fma_f32 v18, v154, v18, v48
	v_fma_f32 v19, v155, v19, v49
	v_lshlrev_b32_e32 v48, 16, v146
	v_and_b32_e32 v49, 0xffff0000, v146
	v_fma_f32 v20, v156, v20, v48
	v_fma_f32 v21, v157, v21, v49
	v_lshlrev_b32_e32 v48, 16, v147
	v_and_b32_e32 v49, 0xffff0000, v147
	v_fma_f32 v22, v158, v22, v48
	v_fma_f32 v23, v159, v23, v49
	v_lshlrev_b32_e32 v48, 16, v148
	v_and_b32_e32 v49, 0xffff0000, v148
	v_fma_f32 v24, v152, v24, v48
	v_fma_f32 v25, v153, v25, v49
	v_lshlrev_b32_e32 v48, 16, v149
	v_and_b32_e32 v49, 0xffff0000, v149
	v_fma_f32 v26, v154, v26, v48
	v_fma_f32 v27, v155, v27, v49
	v_lshlrev_b32_e32 v48, 16, v150
	v_and_b32_e32 v49, 0xffff0000, v150
	v_fma_f32 v28, v156, v28, v48
	v_fma_f32 v29, v157, v29, v49
	v_lshlrev_b32_e32 v48, 16, v151
	v_and_b32_e32 v49, 0xffff0000, v151
	v_fma_f32 v30, v158, v30, v48
	v_fma_f32 v31, v159, v31, v49
	s_waitcnt vmcnt(18)
	v_cvt_pk_bf16_f32 v32, v16, v17
	v_cvt_pk_bf16_f32 v33, v18, v19
	v_cvt_pk_bf16_f32 v34, v20, v21
	v_cvt_pk_bf16_f32 v35, v22, v23
	global_store_dwordx4 v2, v[32:35], s[12:13] nt
	v_cvt_pk_bf16_f32 v36, v24, v25
	v_cvt_pk_bf16_f32 v37, v26, v27
	v_cvt_pk_bf16_f32 v38, v28, v29
	v_cvt_pk_bf16_f32 v39, v30, v31
	global_store_dwordx4 v3, v[36:39], s[12:13] nt
	s_add_u32 s12, s12, 0x40000
	s_addc_u32 s13, s13, 0
	v_lshlrev_b32_e32 v48, 16, v160
	v_and_b32_e32 v49, 0xffff0000, v160
	v_fma_f32 v16, v168, v16, v48
	v_fma_f32 v17, v169, v17, v49
	v_lshlrev_b32_e32 v48, 16, v161
	v_and_b32_e32 v49, 0xffff0000, v161
	v_fma_f32 v18, v170, v18, v48
	v_fma_f32 v19, v171, v19, v49
	v_lshlrev_b32_e32 v48, 16, v162
	v_and_b32_e32 v49, 0xffff0000, v162
	v_fma_f32 v20, v172, v20, v48
	v_fma_f32 v21, v173, v21, v49
	v_lshlrev_b32_e32 v48, 16, v163
	v_and_b32_e32 v49, 0xffff0000, v163
	v_fma_f32 v22, v174, v22, v48
	v_fma_f32 v23, v175, v23, v49
	v_lshlrev_b32_e32 v48, 16, v164
	v_and_b32_e32 v49, 0xffff0000, v164
	v_fma_f32 v24, v168, v24, v48
	v_fma_f32 v25, v169, v25, v49
	v_lshlrev_b32_e32 v48, 16, v165
	v_and_b32_e32 v49, 0xffff0000, v165
	v_fma_f32 v26, v170, v26, v48
	v_fma_f32 v27, v171, v27, v49
	v_lshlrev_b32_e32 v48, 16, v166
	v_and_b32_e32 v49, 0xffff0000, v166
	v_fma_f32 v28, v172, v28, v48
	v_fma_f32 v29, v173, v29, v49
	v_lshlrev_b32_e32 v48, 16, v167
	v_and_b32_e32 v49, 0xffff0000, v167
	v_fma_f32 v30, v174, v30, v48
	v_fma_f32 v31, v175, v31, v49
	s_waitcnt vmcnt(14)
	v_cvt_pk_bf16_f32 v40, v16, v17
	v_cvt_pk_bf16_f32 v41, v18, v19
	v_cvt_pk_bf16_f32 v42, v20, v21
	v_cvt_pk_bf16_f32 v43, v22, v23
	global_store_dwordx4 v2, v[40:43], s[12:13] nt
	v_cvt_pk_bf16_f32 v44, v24, v25
	v_cvt_pk_bf16_f32 v45, v26, v27
	v_cvt_pk_bf16_f32 v46, v28, v29
	v_cvt_pk_bf16_f32 v47, v30, v31
	global_store_dwordx4 v3, v[44:47], s[12:13] nt
	s_add_u32 s12, s12, 0x40000
	s_addc_u32 s13, s13, 0
	v_lshlrev_b32_e32 v48, 16, v176
	v_and_b32_e32 v49, 0xffff0000, v176
	v_fma_f32 v16, v184, v16, v48
	v_fma_f32 v17, v185, v17, v49
	v_lshlrev_b32_e32 v48, 16, v177
	v_and_b32_e32 v49, 0xffff0000, v177
	v_fma_f32 v18, v186, v18, v48
	v_fma_f32 v19, v187, v19, v49
	v_lshlrev_b32_e32 v48, 16, v178
	v_and_b32_e32 v49, 0xffff0000, v178
	v_fma_f32 v20, v188, v20, v48
	v_fma_f32 v21, v189, v21, v49
	v_lshlrev_b32_e32 v48, 16, v179
	v_and_b32_e32 v49, 0xffff0000, v179
	v_fma_f32 v22, v190, v22, v48
	v_fma_f32 v23, v191, v23, v49
	v_lshlrev_b32_e32 v48, 16, v180
	v_and_b32_e32 v49, 0xffff0000, v180
	v_fma_f32 v24, v184, v24, v48
	v_fma_f32 v25, v185, v25, v49
	v_lshlrev_b32_e32 v48, 16, v181
	v_and_b32_e32 v49, 0xffff0000, v181
	v_fma_f32 v26, v186, v26, v48
	v_fma_f32 v27, v187, v27, v49
	v_lshlrev_b32_e32 v48, 16, v182
	v_and_b32_e32 v49, 0xffff0000, v182
	v_fma_f32 v28, v188, v28, v48
	v_fma_f32 v29, v189, v29, v49
	v_lshlrev_b32_e32 v48, 16, v183
	v_and_b32_e32 v49, 0xffff0000, v183
	v_fma_f32 v30, v190, v30, v48
	v_fma_f32 v31, v191, v31, v49
.Lb2_end_l1:
	s_waitcnt lgkmcnt(0)
	v_mov_b64_e32 v[0:1], s[18:19]

;     __device__ __forceinline__ void operator()(const f32x4 (&acc)[2][2][4][2], const Unit& u, int wr, int wc, int fr, int fq) const {
;     ...
;                     const f32x4 w0 = *(const f32x4*)(cw + col), w1 = *(const f32x4*)(cw + 2 * dff + col), w2 = *(const f32x4*)(cw + 4 * dff + col), wb = *(const f32x4*)(cb + col);
;                     if (fr < 2) *(f32x4*)(RB + ((size_t)(blk * 4 + fr) * 2 + bj) * dff + cg) = acc[ai][bj][0][n] * rs[0];
;                     if (fr >= 14) *(f32x4*)(RB + ((size_t)(blk * 4 + fr - 12) * 2 + bj) * dff + cg) = acc[ai][bj][3][n] * rs[3];
; #pragma unroll
;                     for (int m = 3; m >= 0; --m) {
;                         const f32x4 cur = acc[ai][bj][m][n] * rs[m];
;                         f32x4 prev = zero4;
;                         if (m > 0) prev = acc[ai][bj][m - 1][n] * rs[m - 1];
;                         f32x4 r1, r2;
; #pragma unroll
;                         for (int i = 0; i < 4; ++i) {
;                             r1[i] = dpp_mov<0x111>(dpp_mov<0x121>(0.f, prev[i]), cur[i]);
;                             r2[i] = dpp_mov<0x112>(dpp_mov<0x122>(0.f, prev[i]), cur[i]); }
;                         const f32x4 cvv = wb + w2 * cur + w1 * r1 + w0 * r2;
.LBB0_2084:
	s_or_b64 exec, exec, s[50:51]
	v_pk_mul_f32 v[200:201], v[122:123], v[184:185] op_sel_hi:[1,0]
	v_pk_mul_f32 v[202:203], v[120:121], v[184:185] op_sel_hi:[1,0]
	s_nop 1
	v_mov_b32_dpp v226, v202 row_ror:1 row_mask:0xf bank_mask:0xf
	v_mov_b32_dpp v224, v202 row_ror:2 row_mask:0xf bank_mask:0xf
	v_mov_b32_dpp v227, v203 row_ror:1 row_mask:0xf bank_mask:0xf
	v_mov_b32_dpp v225, v203 row_ror:2 row_mask:0xf bank_mask:0xf
	v_mov_b32_dpp v232, v200 row_ror:1 row_mask:0xf bank_mask:0xf
	v_mov_b32_dpp v228, v200 row_ror:2 row_mask:0xf bank_mask:0xf
	v_mov_b32_dpp v233, v201 row_ror:1 row_mask:0xf bank_mask:0xf
	v_mov_b32_dpp v229, v201 row_ror:2 row_mask:0xf bank_mask:0xf
	v_mov_b32_dpp v226, v150 row_shr:1 row_mask:0xf bank_mask:0xf
	v_mov_b32_dpp v224, v150 row_shr:2 row_mask:0xf bank_mask:0xf
	v_mov_b32_dpp v227, v151 row_shr:1 row_mask:0xf bank_mask:0xf
	v_mov_b32_dpp v225, v151 row_shr:2 row_mask:0xf bank_mask:0xf
	v_mov_b32_dpp v232, v152 row_shr:1 row_mask:0xf bank_mask:0xf
	v_mov_b32_dpp v228, v152 row_shr:2 row_mask:0xf bank_mask:0xf
	v_mov_b32_dpp v233, v153 row_shr:1 row_mask:0xf bank_mask:0xf
	v_mov_b32_dpp v229, v153 row_shr:2 row_mask:0xf bank_mask:0xf
	v_pk_mul_f32 v[194:195], v[118:119], v[182:183] op_sel_hi:[1,0]
	v_pk_mul_f32 v[196:197], v[116:117], v[182:183] op_sel_hi:[1,0]
	s_nop 1
	v_mov_b32_dpp v218, v196 row_ror:1 row_mask:0xf bank_mask:0xf
	v_mov_b32_dpp v216, v196 row_ror:2 row_mask:0xf bank_mask:0xf
	v_mov_b32_dpp v219, v197 row_ror:1 row_mask:0xf bank_mask:0xf
	v_mov_b32_dpp v217, v197 row_ror:2 row_mask:0xf bank_mask:0xf
	v_mov_b32_dpp v230, v194 row_ror:1 row_mask:0xf bank_mask:0xf
	v_mov_b32_dpp v220, v194 row_ror:2 row_mask:0xf bank_mask:0xf
	v_mov_b32_dpp v231, v195 row_ror:1 row_mask:0xf bank_mask:0xf
	v_mov_b32_dpp v221, v195 row_ror:2 row_mask:0xf bank_mask:0xf
	v_mov_b32_dpp v218, v202 row_shr:1 row_mask:0xf bank_mask:0xf
	v_mov_b32_dpp v216, v202 row_shr:2 row_mask:0xf bank_mask:0xf
	v_mov_b32_dpp v219, v203 row_shr:1 row_mask:0xf bank_mask:0xf
	v_mov_b32_dpp v217, v203 row_shr:2 row_mask:0xf bank_mask:0xf
	v_mov_b32_dpp v230, v200 row_shr:1 row_mask:0xf bank_mask:0xf
	v_mov_b32_dpp v220, v200 row_shr:2 row_mask:0xf bank_mask:0xf
	v_mov_b32_dpp v231, v201 row_shr:1 row_mask:0xf bank_mask:0xf
	v_mov_b32_dpp v221, v201 row_shr:2 row_mask:0xf bank_mask:0xf
	v_mov_b32_e32 v130, v180
	v_mov_b32_e32 v131, v180
	v_pk_mul_f32 v[192:193], v[114:115], v[130:131]
	v_mov_b32_dpp v212, v148 row_ror:1 row_mask:0xf bank_mask:0xf
	v_mov_b32_dpp v210, v148 row_ror:2 row_mask:0xf bank_mask:0xf
	v_mov_b32_dpp v213, v149 row_ror:1 row_mask:0xf bank_mask:0xf
	v_mov_b32_dpp v211, v149 row_ror:2 row_mask:0xf bank_mask:0xf
	v_mov_b32_dpp v222, v192 row_ror:1 row_mask:0xf bank_mask:0xf
	v_mov_b32_dpp v214, v192 row_ror:2 row_mask:0xf bank_mask:0xf
	v_mov_b32_dpp v223, v193 row_ror:1 row_mask:0xf bank_mask:0xf
	v_mov_b32_dpp v215, v193 row_ror:2 row_mask:0xf bank_mask:0xf
	v_mov_b32_dpp v212, v196 row_shr:1 row_mask:0xf bank_mask:0xf
	v_mov_b32_dpp v210, v196 row_shr:2 row_mask:0xf bank_mask:0xf
	v_mov_b32_dpp v213, v197 row_shr:1 row_mask:0xf bank_mask:0xf
	v_mov_b32_dpp v211, v197 row_shr:2 row_mask:0xf bank_mask:0xf
	v_mov_b32_dpp v222, v194 row_shr:1 row_mask:0xf bank_mask:0xf
	v_mov_b32_dpp v214, v194 row_shr:2 row_mask:0xf bank_mask:0xf
	v_mov_b32_dpp v223, v195 row_shr:1 row_mask:0xf bank_mask:0xf
	v_mov_b32_dpp v215, v195 row_shr:2 row_mask:0xf bank_mask:0xf
	v_mov_b32_e32 v209, 0
	v_mov_b32_e32 v199, 0
	s_nop 0
	v_mov_b32_dpp v209, v209 row_ror:1 row_mask:0xf bank_mask:0xf
	v_mov_b32_dpp v199, v199 row_ror:2 row_mask:0xf bank_mask:0xf
	v_mov_b32_e32 v206, v209
	v_mov_b32_e32 v204, v199
	v_mov_b32_e32 v207, v209
	v_mov_b32_e32 v205, v199
	v_mov_b32_e32 v208, v209
	v_mov_b32_e32 v198, v199
	v_mov_b32_dpp v206, v148 row_shr:1 row_mask:0xf bank_mask:0xf
	v_mov_b32_dpp v204, v148 row_shr:2 row_mask:0xf bank_mask:0xf
	v_mov_b32_dpp v207, v149 row_shr:1 row_mask:0xf bank_mask:0xf
	v_mov_b32_dpp v205, v149 row_shr:2 row_mask:0xf bank_mask:0xf
	v_mov_b32_dpp v208, v192 row_shr:1 row_mask:0xf bank_mask:0xf
	v_mov_b32_dpp v198, v192 row_shr:2 row_mask:0xf bank_mask:0xf
	v_mov_b32_dpp v209, v193 row_shr:1 row_mask:0xf bank_mask:0xf
	v_mov_b32_dpp v199, v193 row_shr:2 row_mask:0xf bank_mask:0xf
	v_add_co_u32_e32 v188, vcc, s82, v172
	v_pk_mul_f32 v[128:129], v[96:97], v[180:181]
	s_nop 0
	v_addc_co_u32_e32 v189, vcc, 0, v173, vcc
	v_add_co_u32_e32 v190, vcc, s82, v174
	s_nop 1
	v_addc_co_u32_e32 v191, vcc, 0, v175, vcc
	v_add_co_u32_e32 v120, vcc, 0x5000, v176
	global_load_dwordx4 v[112:115], v[188:189], off offset:2048
	global_load_dwordx4 v[116:119], v[190:191], off offset:2048
	v_addc_co_u32_e32 v121, vcc, 0, v177, vcc
	v_add_co_u32_e32 v124, vcc, 0x5000, v178
	global_load_dwordx4 v[120:123], v[120:121], off offset:2048
	s_nop 0
	v_addc_co_u32_e32 v125, vcc, 0, v179, vcc
	global_load_dwordx4 v[124:127], v[124:125], off offset:2048
	s_and_saveexec_b64 s[50:51], s[8:9]
	s_cbranch_execz .LBB0_2086
	v_mov_b64_e32 v[96:97], s[20:21]
	v_mad_i64_i32 v[96:97], s[54:55], v246, s81, v[96:97]
	v_lshl_add_u64 v[96:97], v[170:171], 2, v[96:97]
	v_add_co_u32_e32 v96, vcc, 0x5000, v96
	v_pk_mul_f32 v[130:131], v[98:99], v[130:131]
	s_nop 0
	v_addc_co_u32_e32 v97, vcc, 0, v97, vcc
	global_store_dwordx4 v[96:97], v[128:131], off offset:2048

; __device__ __forceinline__ unsigned cvt_pk_bf16(float lo, float hi) { f32x2_cv v = {lo, hi}; bf16x2_cv b = __builtin_convertvector(v, bf16x2_cv); return __builtin_bit_cast(unsigned, b); }
; __device__ __forceinline__ float siluf_(float x) { return x * __builtin_amdgcn_rcpf(1.0f + __expf(-x)); }
;     __device__ __forceinline__ void operator()(const f32x4 (&acc)[2][2][4][2], const Unit& u, int wr, int wc, int fr, int fq) const {
;     ...
;                     for (int m = 3; m >= 0; --m) {
;                         const f32x4 cur = acc[ai][bj][m][n] * rs[m];
;                         f32x4 prev = zero4;
;                         if (m > 0) prev = acc[ai][bj][m - 1][n] * rs[m - 1];
;                         f32x4 r1, r2;
; #pragma unroll
;                         for (int i = 0; i < 4; ++i) {
;                             r1[i] = dpp_mov<0x111>(dpp_mov<0x121>(0.f, prev[i]), cur[i]);
;                             r2[i] = dpp_mov<0x112>(dpp_mov<0x122>(0.f, prev[i]), cur[i]); }
;                         const f32x4 cvv = wb + w2 * cur + w1 * r1 + w0 * r2;
;                         if (bj == 0) {
;                             sg[m].x = cvt_pk_bf16(siluf_(cvv[0]), siluf_(cvv[1])); sg[m].y = cvt_pk_bf16(siluf_(cvv[2]), siluf_(cvv[3]));
;                         } else {
;                             f32x4 h;
;                             h[0] = __uint_as_float(sg[m].x << 16) * cvv[0]; h[1] = __uint_as_float(sg[m].x & 0xffff0000u) * cvv[1];
;                             h[2] = __uint_as_float(sg[m].y << 16) * cvv[2]; h[3] = __uint_as_float(sg[m].y & 0xffff0000u) * cvv[3];
;                             u32x2v w; w.x = cvt_pk_bf16(h[0], h[1]); w.y = cvt_pk_bf16(h[2], h[3]);
.LBB0_2088:
	s_or_b64 exec, exec, s[50:51]
	s_waitcnt vmcnt(0)
	v_pk_fma_f32 v[130:131], v[140:141], v[150:151], v[144:145]
	v_pk_fma_f32 v[96:97], v[142:143], v[152:153], v[146:147]
	v_pk_fma_f32 v[130:131], v[136:137], v[226:227], v[130:131]
	v_pk_fma_f32 v[96:97], v[138:139], v[232:233], v[96:97]
	v_pk_fma_f32 v[130:131], v[132:133], v[224:225], v[130:131]
	v_pk_fma_f32 v[96:97], v[134:135], v[228:229], v[96:97]
	v_mul_f32_e32 v150, 0xbfb8aa3b, v130
	v_mul_f32_e32 v151, 0xbfb8aa3b, v131
	v_exp_f32_e32 v150, v150
	v_exp_f32_e32 v151, v151
	v_mul_f32_e32 v152, 0xbfb8aa3b, v96
	v_mul_f32_e32 v153, 0xbfb8aa3b, v97
	v_exp_f32_e32 v152, v152
	v_exp_f32_e32 v153, v153
	v_add_f32_e32 v150, 1.0, v150
	v_add_f32_e32 v151, 1.0, v151
	v_rcp_f32_e32 v150, v150
	v_rcp_f32_e32 v151, v151
	v_add_f32_e32 v152, 1.0, v152
	v_add_f32_e32 v153, 1.0, v153
	v_rcp_f32_e32 v152, v152
	v_rcp_f32_e32 v153, v153
	v_pk_mul_f32 v[130:131], v[130:131], v[150:151]
	v_pk_fma_f32 v[150:151], v[202:203], v[140:141], v[144:145]
	v_cvt_pk_bf16_f32 v224, v130, v131
	v_pk_fma_f32 v[130:131], v[200:201], v[142:143], v[146:147]
	v_pk_fma_f32 v[150:151], v[136:137], v[218:219], v[150:151]
	v_pk_fma_f32 v[130:131], v[138:139], v[230:231], v[130:131]
	v_pk_fma_f32 v[150:151], v[132:133], v[216:217], v[150:151]
	v_pk_mul_f32 v[96:97], v[96:97], v[152:153]
	v_mul_f32_e32 v152, 0xbfb8aa3b, v150
	v_mul_f32_e32 v153, 0xbfb8aa3b, v151
	v_pk_fma_f32 v[130:131], v[134:135], v[220:221], v[130:131]
	v_exp_f32_e32 v152, v152
	v_exp_f32_e32 v153, v153
	v_mul_f32_e32 v200, 0xbfb8aa3b, v130
	v_mul_f32_e32 v201, 0xbfb8aa3b, v131
	v_exp_f32_e32 v200, v200
	v_exp_f32_e32 v201, v201
	v_add_f32_e32 v152, 1.0, v152
	v_add_f32_e32 v153, 1.0, v153
	v_rcp_f32_e32 v152, v152
	v_rcp_f32_e32 v153, v153
	v_add_f32_e32 v200, 1.0, v200
	v_add_f32_e32 v201, 1.0, v201
	v_rcp_f32_e32 v200, v200
	v_rcp_f32_e32 v201, v201
	v_cvt_pk_bf16_f32 v202, v96, v97
	v_pk_mul_f32 v[96:97], v[150:151], v[152:153]
	v_pk_fma_f32 v[150:151], v[196:197], v[140:141], v[144:145]
	v_cvt_pk_bf16_f32 v203, v96, v97
	v_pk_mul_f32 v[96:97], v[130:131], v[200:201]
	v_pk_fma_f32 v[130:131], v[194:195], v[142:143], v[146:147]
	v_pk_fma_f32 v[150:151], v[136:137], v[212:213], v[150:151]
	v_pk_fma_f32 v[130:131], v[138:139], v[222:223], v[130:131]
	v_pk_fma_f32 v[150:151], v[132:133], v[210:211], v[150:151]
	v_pk_fma_f32 v[130:131], v[134:135], v[214:215], v[130:131]
	v_mul_f32_e32 v152, 0xbfb8aa3b, v150
	v_mul_f32_e32 v153, 0xbfb8aa3b, v151
	v_exp_f32_e32 v152, v152
	v_exp_f32_e32 v153, v153
	v_mul_f32_e32 v194, 0xbfb8aa3b, v130
	v_mul_f32_e32 v195, 0xbfb8aa3b, v131
	v_exp_f32_e32 v194, v194
	v_exp_f32_e32 v195, v195
	v_add_f32_e32 v152, 1.0, v152
	v_add_f32_e32 v153, 1.0, v153
	v_rcp_f32_e32 v152, v152
	v_rcp_f32_e32 v153, v153
	v_add_f32_e32 v194, 1.0, v194
	v_add_f32_e32 v195, 1.0, v195
	v_pk_fma_f32 v[140:141], v[148:149], v[140:141], v[144:145]
	v_rcp_f32_e32 v194, v194
	v_rcp_f32_e32 v195, v195
	v_pk_fma_f32 v[136:137], v[136:137], v[206:207], v[140:141]
	v_cvt_pk_bf16_f32 v196, v96, v97
	v_pk_fma_f32 v[132:133], v[132:133], v[204:205], v[136:137]
	v_pk_mul_f32 v[96:97], v[150:151], v[152:153]
	v_mul_f32_e32 v136, 0xbfb8aa3b, v132
	v_mul_f32_e32 v137, 0xbfb8aa3b, v133
	v_exp_f32_e32 v136, v136
	v_exp_f32_e32 v137, v137
	v_cvt_pk_bf16_f32 v150, v96, v97
	v_pk_mul_f32 v[96:97], v[130:131], v[194:195]
	v_pk_fma_f32 v[130:131], v[192:193], v[142:143], v[146:147]
	v_mov_b32_e32 v185, v184
	v_pk_fma_f32 v[130:131], v[138:139], v[208:209], v[130:131]
	v_cvt_pk_bf16_f32 v138, v96, v97
	v_pk_fma_f32 v[130:131], v[134:135], v[198:199], v[130:131]
	v_add_f32_e32 v134, 1.0, v136
	v_add_f32_e32 v135, 1.0, v137
	v_mul_f32_e32 v136, 0xbfb8aa3b, v130
	v_mul_f32_e32 v137, 0xbfb8aa3b, v131
	v_exp_f32_e32 v136, v136
	v_exp_f32_e32 v137, v137
	v_rcp_f32_e32 v134, v134
	v_rcp_f32_e32 v135, v135
	v_add_f32_e32 v136, 1.0, v136
	v_add_f32_e32 v137, 1.0, v137
	v_rcp_f32_e32 v136, v136
	v_rcp_f32_e32 v137, v137
	v_pk_mul_f32 v[96:97], v[132:133], v[134:135]
	v_pk_mul_f32 v[104:105], v[104:105], v[184:185]
	v_cvt_pk_bf16_f32 v140, v96, v97
	v_pk_mul_f32 v[96:97], v[130:131], v[136:137]
	v_cvt_pk_bf16_f32 v141, v96, v97
	v_mov_b32_e32 v96, v184
	v_mov_b32_e32 v97, v184
	v_pk_mul_f32 v[96:97], v[106:107], v[96:97]
	v_mov_b32_dpp v106, v104 row_ror:1 row_mask:0xf bank_mask:0xf
	v_mov_b32_dpp v130, v104 row_ror:2 row_mask:0xf bank_mask:0xf
	v_mov_b32_dpp v107, v105 row_ror:1 row_mask:0xf bank_mask:0xf
	v_mov_b32_dpp v131, v105 row_ror:2 row_mask:0xf bank_mask:0xf
	v_mov_b32_dpp v132, v96 row_ror:1 row_mask:0xf bank_mask:0xf
	v_mov_b32_dpp v134, v96 row_ror:2 row_mask:0xf bank_mask:0xf
	v_mov_b32_dpp v133, v97 row_ror:1 row_mask:0xf bank_mask:0xf
	v_mov_b32_dpp v135, v97 row_ror:2 row_mask:0xf bank_mask:0xf
	v_mov_b32_dpp v106, v108 row_shr:1 row_mask:0xf bank_mask:0xf
	v_mov_b32_dpp v130, v108 row_shr:2 row_mask:0xf bank_mask:0xf
	v_mov_b32_dpp v107, v109 row_shr:1 row_mask:0xf bank_mask:0xf
	v_mov_b32_dpp v131, v109 row_shr:2 row_mask:0xf bank_mask:0xf
	v_mov_b32_dpp v132, v110 row_shr:1 row_mask:0xf bank_mask:0xf
	v_mov_b32_dpp v134, v110 row_shr:2 row_mask:0xf bank_mask:0xf
	v_mov_b32_dpp v133, v111 row_shr:1 row_mask:0xf bank_mask:0xf
	v_mov_b32_dpp v135, v111 row_shr:2 row_mask:0xf bank_mask:0xf
	v_pk_fma_f32 v[110:111], v[110:111], v[122:123], v[126:127]
	v_pk_fma_f32 v[108:109], v[108:109], v[120:121], v[124:125]
	v_pk_fma_f32 v[110:111], v[118:119], v[132:133], v[110:111]
	v_pk_fma_f32 v[106:107], v[116:117], v[106:107], v[108:109]
	v_pk_fma_f32 v[108:109], v[114:115], v[134:135], v[110:111]
	v_pk_fma_f32 v[106:107], v[112:113], v[130:131], v[106:107]
; __device__ __forceinline__ unsigned cvt_pk_bf16(float lo, float hi) { f32x2_cv v = {lo, hi}; bf16x2_cv b = __builtin_convertvector(v, bf16x2_cv); return __builtin_bit_cast(unsigned, b); }
; __device__ __forceinline__ float siluf_(float x) { return x * __builtin_amdgcn_rcpf(1.0f + __expf(-x)); }
;     __device__ __forceinline__ void operator()(const f32x4 (&acc)[2][2][4][2], const Unit& u, int wr, int wc, int fr, int fq) const {
;     ...
;                         const f32x4 cvv = wb + w2 * cur + w1 * r1 + w0 * r2;
;                         if (bj == 0) {
;                             sg[m].x = cvt_pk_bf16(siluf_(cvv[0]), siluf_(cvv[1])); sg[m].y = cvt_pk_bf16(siluf_(cvv[2]), siluf_(cvv[3]));
;                         } else {
;                             f32x4 h;
;                             h[0] = __uint_as_float(sg[m].x << 16) * cvv[0]; h[1] = __uint_as_float(sg[m].x & 0xffff0000u) * cvv[1];
;                             h[2] = __uint_as_float(sg[m].y << 16) * cvv[2]; h[3] = __uint_as_float(sg[m].y & 0xffff0000u) * cvv[3];
;                             u32x2v w; w.x = cvt_pk_bf16(h[0], h[1]); w.y = cvt_pk_bf16(h[2], h[3]);
;                             *(u32x2v*)(H + (size_t)(rowb + m * 16 + fr) * dff + cg) = w;
	v_lshlrev_b32_e32 v110, 16, v224
	v_and_b32_e32 v111, 0xffff0000, v224
	v_pk_mul_f32 v[106:107], v[106:107], v[110:111]
	v_lshlrev_b32_e32 v110, 16, v202
	v_and_b32_e32 v111, 0xffff0000, v202
	v_or_b32_e32 v142, s39, v236
	v_pk_mul_f32 v[108:109], v[108:109], v[110:111]
	v_cvt_pk_bf16_f32 v106, v106, v107
	v_cvt_pk_bf16_f32 v107, v108, v109
	v_or_b32_e32 v110, 48, v142
	v_mov_b64_e32 v[108:109], s[18:19]
	v_mad_i64_i32 v[110:111], s[50:51], v110, s83, v[108:109]
	v_lshlrev_b64 v[130:131], 1, v[170:171]
	v_mov_b32_e32 v183, v182
	v_lshl_add_u64 v[134:135], v[110:111], 0, v[130:131]
	global_store_dwordx2 v[134:135], v[106:107], off
	v_mov_b32_e32 v106, v182
	v_mov_b32_e32 v107, v182
	v_pk_mul_f32 v[102:103], v[102:103], v[106:107]
	v_pk_mul_f32 v[100:101], v[100:101], v[182:183]
	s_nop 1
	v_mov_b32_dpp v106, v100 row_ror:1 row_mask:0xf bank_mask:0xf
	v_mov_b32_dpp v110, v100 row_ror:2 row_mask:0xf bank_mask:0xf
	v_mov_b32_dpp v107, v101 row_ror:1 row_mask:0xf bank_mask:0xf
	v_mov_b32_dpp v111, v101 row_ror:2 row_mask:0xf bank_mask:0xf
	v_mov_b32_dpp v106, v104 row_shr:1 row_mask:0xf bank_mask:0xf
	v_mov_b32_dpp v110, v104 row_shr:2 row_mask:0xf bank_mask:0xf
	v_mov_b32_dpp v107, v105 row_shr:1 row_mask:0xf bank_mask:0xf
	v_mov_b32_dpp v111, v105 row_shr:2 row_mask:0xf bank_mask:0xf
	v_mov_b32_dpp v132, v102 row_ror:1 row_mask:0xf bank_mask:0xf
	v_mov_b32_dpp v136, v102 row_ror:2 row_mask:0xf bank_mask:0xf
	v_mov_b32_dpp v133, v103 row_ror:1 row_mask:0xf bank_mask:0xf
	v_mov_b32_dpp v137, v103 row_ror:2 row_mask:0xf bank_mask:0xf
	v_pk_fma_f32 v[104:105], v[104:105], v[120:121], v[124:125]
	v_mov_b32_dpp v132, v96 row_shr:1 row_mask:0xf bank_mask:0xf
	v_mov_b32_dpp v136, v96 row_shr:2 row_mask:0xf bank_mask:0xf
	v_mov_b32_dpp v133, v97 row_shr:1 row_mask:0xf bank_mask:0xf
	v_mov_b32_dpp v137, v97 row_shr:2 row_mask:0xf bank_mask:0xf
	v_pk_fma_f32 v[96:97], v[96:97], v[122:123], v[126:127]
	v_pk_fma_f32 v[104:105], v[116:117], v[106:107], v[104:105]
	v_pk_fma_f32 v[96:97], v[118:119], v[132:133], v[96:97]
	v_pk_fma_f32 v[104:105], v[112:113], v[110:111], v[104:105]
	v_lshlrev_b32_e32 v106, 16, v203
	v_and_b32_e32 v107, 0xffff0000, v203
	v_pk_fma_f32 v[96:97], v[114:115], v[136:137], v[96:97]
	v_pk_mul_f32 v[104:105], v[104:105], v[106:107]
	v_lshlrev_b32_e32 v106, 16, v196
	v_and_b32_e32 v107, 0xffff0000, v196
	v_pk_mul_f32 v[96:97], v[96:97], v[106:107]
	v_cvt_pk_bf16_f32 v104, v104, v105
	v_cvt_pk_bf16_f32 v105, v96, v97
	v_or_b32_e32 v96, 32, v142
	v_mad_i64_i32 v[96:97], s[50:51], v96, s83, v[108:109]
	v_lshl_add_u64 v[136:137], v[96:97], 0, v[130:131]
	global_store_dwordx2 v[136:137], v[104:105], off
	v_mov_b32_e32 v96, v180
	v_mov_b32_e32 v97, v180
	v_pk_mul_f32 v[98:99], v[98:99], v[96:97]
	v_mov_b32_dpp v104, v128 row_ror:1 row_mask:0xf bank_mask:0xf
	v_mov_b32_dpp v106, v128 row_ror:2 row_mask:0xf bank_mask:0xf
	v_mov_b32_dpp v105, v129 row_ror:1 row_mask:0xf bank_mask:0xf
	v_mov_b32_dpp v107, v129 row_ror:2 row_mask:0xf bank_mask:0xf
	v_mov_b32_dpp v104, v100 row_shr:1 row_mask:0xf bank_mask:0xf
	v_mov_b32_dpp v106, v100 row_shr:2 row_mask:0xf bank_mask:0xf
	v_mov_b32_dpp v105, v101 row_shr:1 row_mask:0xf bank_mask:0xf
	v_mov_b32_dpp v107, v101 row_shr:2 row_mask:0xf bank_mask:0xf
	v_mov_b32_dpp v110, v98 row_ror:1 row_mask:0xf bank_mask:0xf
	v_mov_b32_dpp v132, v98 row_ror:2 row_mask:0xf bank_mask:0xf
	v_mov_b32_dpp v111, v99 row_ror:1 row_mask:0xf bank_mask:0xf
	v_mov_b32_dpp v133, v99 row_ror:2 row_mask:0xf bank_mask:0xf
	v_pk_fma_f32 v[100:101], v[100:101], v[120:121], v[124:125]
	v_mov_b32_dpp v110, v102 row_shr:1 row_mask:0xf bank_mask:0xf
	v_mov_b32_dpp v132, v102 row_shr:2 row_mask:0xf bank_mask:0xf
	v_mov_b32_dpp v111, v103 row_shr:1 row_mask:0xf bank_mask:0xf
	v_mov_b32_dpp v133, v103 row_shr:2 row_mask:0xf bank_mask:0xf
	v_pk_fma_f32 v[102:103], v[102:103], v[122:123], v[126:127]
	v_pk_fma_f32 v[100:101], v[116:117], v[104:105], v[100:101]
	v_pk_fma_f32 v[102:103], v[118:119], v[110:111], v[102:103]
	v_pk_fma_f32 v[100:101], v[112:113], v[106:107], v[100:101]
	v_lshlrev_b32_e32 v104, 16, v150
	v_and_b32_e32 v105, 0xffff0000, v150
	v_pk_fma_f32 v[102:103], v[114:115], v[132:133], v[102:103]
	v_pk_mul_f32 v[100:101], v[100:101], v[104:105]
	v_lshlrev_b32_e32 v104, 16, v138
	v_and_b32_e32 v105, 0xffff0000, v138
	v_pk_mul_f32 v[102:103], v[102:103], v[104:105]
	v_cvt_pk_bf16_f32 v100, v100, v101
	v_cvt_pk_bf16_f32 v101, v102, v103
	v_or_b32_e32 v102, 16, v142
	v_mad_i64_i32 v[102:103], s[50:51], v102, s83, v[108:109]
	v_lshl_add_u64 v[138:139], v[102:103], 0, v[130:131]
	global_store_dwordx2 v[138:139], v[100:101], off
	v_mov_b32_e32 v101, 0
	v_mov_b32_e32 v105, 0
	v_pk_fma_f32 v[110:111], v[128:129], v[120:121], v[124:125]
	v_mov_b32_dpp v101, v101 row_ror:1 row_mask:0xf bank_mask:0xf
	v_mov_b32_dpp v105, v105 row_ror:2 row_mask:0xf bank_mask:0xf
	v_mov_b32_e32 v102, v101
	v_mov_b32_e32 v103, v101
	v_mov_b32_e32 v100, v101
	v_mov_b32_e32 v104, v105
	v_mov_b32_dpp v102, v128 row_shr:1 row_mask:0xf bank_mask:0xf
	v_mov_b32_e32 v106, v105
	v_mov_b32_dpp v103, v129 row_shr:1 row_mask:0xf bank_mask:0xf
	v_mov_b32_e32 v107, v105
	v_mov_b32_dpp v100, v98 row_shr:1 row_mask:0xf bank_mask:0xf
	v_mov_b32_dpp v104, v98 row_shr:2 row_mask:0xf bank_mask:0xf
	v_mov_b32_dpp v101, v99 row_shr:1 row_mask:0xf bank_mask:0xf
	v_mov_b32_dpp v105, v99 row_shr:2 row_mask:0xf bank_mask:0xf
	v_pk_fma_f32 v[98:99], v[98:99], v[122:123], v[126:127]
	v_mov_b32_dpp v106, v128 row_shr:2 row_mask:0xf bank_mask:0xf
	v_mov_b32_dpp v107, v129 row_shr:2 row_mask:0xf bank_mask:0xf
	v_pk_fma_f32 v[98:99], v[118:119], v[100:101], v[98:99]
	v_pk_fma_f32 v[100:101], v[116:117], v[102:103], v[110:111]
	v_lshlrev_b32_e32 v102, 16, v140
	v_pk_fma_f32 v[100:101], v[112:113], v[106:107], v[100:101]
	v_and_b32_e32 v103, 0xffff0000, v140
	v_pk_fma_f32 v[98:99], v[114:115], v[104:105], v[98:99]
	v_pk_mul_f32 v[100:101], v[100:101], v[102:103]
	v_lshlrev_b32_e32 v102, 16, v141
	v_and_b32_e32 v103, 0xffff0000, v141
	v_pk_mul_f32 v[98:99], v[98:99], v[102:103]
	v_cvt_pk_bf16_f32 v100, v100, v101
	v_cvt_pk_bf16_f32 v101, v98, v99
	v_mad_i64_i32 v[98:99], s[50:51], v142, s83, v[108:109]
	v_lshl_add_u64 v[140:141], v[98:99], 0, v[130:131]
	global_store_dwordx2 v[140:141], v[100:101], off
	v_or_b32_e32 v122, 4, v170
	v_ashrrev_i32_e32 v123, 31, v122
	v_lshlrev_b64 v[98:99], 2, v[122:123]
	v_lshl_add_u64 v[124:125], s[22:23], 0, v[98:99]
	v_lshl_add_u64 v[128:129], s[30:31], 0, v[98:99]
	v_lshl_add_u64 v[132:133], s[14:15], 0, v[98:99]
	v_lshl_add_u64 v[126:127], s[28:29], 0, v[98:99]
	global_load_dwordx4 v[100:103], v[124:125], off
	global_load_dwordx4 v[104:107], v[126:127], off
	global_load_dwordx4 v[108:111], v[128:129], off
	global_load_dwordx4 v[112:115], v[132:133], off
	v_pk_mul_f32 v[116:117], v[80:81], v[180:181]
	s_and_saveexec_b64 s[50:51], s[8:9]
	s_cbranch_execz .LBB0_2090
;     __device__ __forceinline__ void operator()(const f32x4 (&acc)[2][2][4][2], const Unit& u, int wr, int wc, int fr, int fq) const {
;     ...
;                     if (fr < 2) *(f32x4*)(RB + ((size_t)(blk * 4 + fr) * 2 + bj) * dff + cg) = acc[ai][bj][0][n] * rs[0];
	v_mov_b64_e32 v[80:81], s[20:21]
	v_mad_i64_i32 v[80:81], s[54:55], v246, s81, v[80:81]
	v_pk_mul_f32 v[118:119], v[82:83], v[96:97]
	v_lshl_add_u64 v[80:81], v[170:171], 2, v[80:81]
	global_store_dwordx4 v[80:81], v[116:119], off offset:16

;     __device__ __forceinline__ void operator()(const f32x4 (&acc)[2][2][4][2], const Unit& u, int wr, int wc, int fr, int fq) const {
;     ...
;                     const f32x4 w0 = *(const f32x4*)(cw + col), w1 = *(const f32x4*)(cw + 2 * dff + col), w2 = *(const f32x4*)(cw + 4 * dff + col), wb = *(const f32x4*)(cb + col);
;                     if (fr < 2) *(f32x4*)(RB + ((size_t)(blk * 4 + fr) * 2 + bj) * dff + cg) = acc[ai][bj][0][n] * rs[0];
;                     if (fr >= 14) *(f32x4*)(RB + ((size_t)(blk * 4 + fr - 12) * 2 + bj) * dff + cg) = acc[ai][bj][3][n] * rs[3];
; #pragma unroll
;                     for (int m = 3; m >= 0; --m) {
;                         const f32x4 cur = acc[ai][bj][m][n] * rs[m];
;                         f32x4 prev = zero4;
;                         if (m > 0) prev = acc[ai][bj][m - 1][n] * rs[m - 1];
;                         f32x4 r1, r2;
; #pragma unroll
;                         for (int i = 0; i < 4; ++i) {
;                             r1[i] = dpp_mov<0x111>(dpp_mov<0x121>(0.f, prev[i]), cur[i]);
;                             r2[i] = dpp_mov<0x112>(dpp_mov<0x122>(0.f, prev[i]), cur[i]); }
.LBB0_2092:
	s_or_b64 exec, exec, s[50:51]
	v_mov_b32_e32 v80, v184
	v_mov_b32_e32 v81, v184
	v_pk_mul_f32 v[150:151], v[90:91], v[80:81]
	v_pk_mul_f32 v[152:153], v[88:89], v[184:185]
	s_nop 1
	v_mov_b32_dpp v214, v152 row_ror:1 row_mask:0xf bank_mask:0xf
	v_mov_b32_dpp v210, v152 row_ror:2 row_mask:0xf bank_mask:0xf
	v_mov_b32_dpp v215, v153 row_ror:1 row_mask:0xf bank_mask:0xf
	v_mov_b32_dpp v211, v153 row_ror:2 row_mask:0xf bank_mask:0xf
	v_mov_b32_dpp v220, v150 row_ror:1 row_mask:0xf bank_mask:0xf
	v_mov_b32_dpp v216, v150 row_ror:2 row_mask:0xf bank_mask:0xf
	v_mov_b32_dpp v221, v151 row_ror:1 row_mask:0xf bank_mask:0xf
	v_mov_b32_dpp v217, v151 row_ror:2 row_mask:0xf bank_mask:0xf
	v_mov_b32_dpp v214, v118 row_shr:1 row_mask:0xf bank_mask:0xf
	v_mov_b32_dpp v210, v118 row_shr:2 row_mask:0xf bank_mask:0xf
	v_mov_b32_dpp v215, v119 row_shr:1 row_mask:0xf bank_mask:0xf
	v_mov_b32_dpp v211, v119 row_shr:2 row_mask:0xf bank_mask:0xf
	v_mov_b32_dpp v220, v120 row_shr:1 row_mask:0xf bank_mask:0xf
	v_mov_b32_dpp v216, v120 row_shr:2 row_mask:0xf bank_mask:0xf
	v_mov_b32_dpp v221, v121 row_shr:1 row_mask:0xf bank_mask:0xf
	v_mov_b32_dpp v217, v121 row_shr:2 row_mask:0xf bank_mask:0xf
	v_mov_b32_e32 v80, v182
	v_mov_b32_e32 v81, v182
	v_pk_mul_f32 v[144:145], v[86:87], v[80:81]
	v_pk_mul_f32 v[146:147], v[84:85], v[182:183]
	s_nop 1
	v_mov_b32_dpp v206, v146 row_ror:1 row_mask:0xf bank_mask:0xf
	v_mov_b32_dpp v204, v146 row_ror:2 row_mask:0xf bank_mask:0xf
	v_mov_b32_dpp v207, v147 row_ror:1 row_mask:0xf bank_mask:0xf
	v_mov_b32_dpp v205, v147 row_ror:2 row_mask:0xf bank_mask:0xf
	v_mov_b32_dpp v218, v144 row_ror:1 row_mask:0xf bank_mask:0xf
	v_mov_b32_dpp v208, v144 row_ror:2 row_mask:0xf bank_mask:0xf
	v_mov_b32_dpp v219, v145 row_ror:1 row_mask:0xf bank_mask:0xf
	v_mov_b32_dpp v209, v145 row_ror:2 row_mask:0xf bank_mask:0xf
	v_mov_b32_dpp v206, v152 row_shr:1 row_mask:0xf bank_mask:0xf
	v_mov_b32_dpp v204, v152 row_shr:2 row_mask:0xf bank_mask:0xf
	v_mov_b32_dpp v207, v153 row_shr:1 row_mask:0xf bank_mask:0xf
	v_mov_b32_dpp v205, v153 row_shr:2 row_mask:0xf bank_mask:0xf
	v_mov_b32_dpp v218, v150 row_shr:1 row_mask:0xf bank_mask:0xf
	v_mov_b32_dpp v208, v150 row_shr:2 row_mask:0xf bank_mask:0xf
	v_mov_b32_dpp v219, v151 row_shr:1 row_mask:0xf bank_mask:0xf
	v_mov_b32_dpp v209, v151 row_shr:2 row_mask:0xf bank_mask:0xf
	v_mov_b32_e32 v98, v180
	v_mov_b32_e32 v99, v180
	v_pk_mul_f32 v[142:143], v[82:83], v[98:99]
	v_mov_b32_dpp v200, v116 row_ror:1 row_mask:0xf bank_mask:0xf
	v_mov_b32_dpp v198, v116 row_ror:2 row_mask:0xf bank_mask:0xf
	v_mov_b32_dpp v201, v117 row_ror:1 row_mask:0xf bank_mask:0xf
	v_mov_b32_dpp v199, v117 row_ror:2 row_mask:0xf bank_mask:0xf
	v_mov_b32_dpp v212, v142 row_ror:1 row_mask:0xf bank_mask:0xf
	v_mov_b32_dpp v202, v142 row_ror:2 row_mask:0xf bank_mask:0xf
	v_mov_b32_dpp v213, v143 row_ror:1 row_mask:0xf bank_mask:0xf
	v_mov_b32_dpp v203, v143 row_ror:2 row_mask:0xf bank_mask:0xf
	v_mov_b32_dpp v200, v146 row_shr:1 row_mask:0xf bank_mask:0xf
	v_mov_b32_dpp v198, v146 row_shr:2 row_mask:0xf bank_mask:0xf
	v_mov_b32_dpp v201, v147 row_shr:1 row_mask:0xf bank_mask:0xf
	v_mov_b32_dpp v199, v147 row_shr:2 row_mask:0xf bank_mask:0xf
	v_mov_b32_dpp v212, v144 row_shr:1 row_mask:0xf bank_mask:0xf
	v_mov_b32_dpp v202, v144 row_shr:2 row_mask:0xf bank_mask:0xf
	v_mov_b32_dpp v213, v145 row_shr:1 row_mask:0xf bank_mask:0xf
	v_mov_b32_dpp v203, v145 row_shr:2 row_mask:0xf bank_mask:0xf
	v_mov_b32_e32 v197, 0
	v_mov_b32_e32 v149, 0
	s_nop 0
	v_mov_b32_dpp v197, v197 row_ror:1 row_mask:0xf bank_mask:0xf
	v_mov_b32_dpp v149, v149 row_ror:2 row_mask:0xf bank_mask:0xf
	v_mov_b32_e32 v194, v197
	v_mov_b32_e32 v192, v149
	v_mov_b32_e32 v195, v197
	v_mov_b32_e32 v193, v149
	v_mov_b32_e32 v196, v197
	v_mov_b32_e32 v148, v149
	v_mov_b32_dpp v194, v116 row_shr:1 row_mask:0xf bank_mask:0xf
	v_mov_b32_dpp v192, v116 row_shr:2 row_mask:0xf bank_mask:0xf
	v_mov_b32_dpp v195, v117 row_shr:1 row_mask:0xf bank_mask:0xf
	v_mov_b32_dpp v193, v117 row_shr:2 row_mask:0xf bank_mask:0xf
	v_mov_b32_dpp v196, v142 row_shr:1 row_mask:0xf bank_mask:0xf
	v_mov_b32_dpp v148, v142 row_shr:2 row_mask:0xf bank_mask:0xf
	v_mov_b32_dpp v197, v143 row_shr:1 row_mask:0xf bank_mask:0xf
	v_mov_b32_dpp v149, v143 row_shr:2 row_mask:0xf bank_mask:0xf
	v_add_co_u32_e32 v88, vcc, 0x5000, v176
	global_load_dwordx4 v[80:83], v[188:189], off offset:2064
	global_load_dwordx4 v[84:87], v[190:191], off offset:2064
	v_addc_co_u32_e32 v89, vcc, 0, v177, vcc
	v_add_co_u32_e32 v92, vcc, 0x5000, v178
	global_load_dwordx4 v[88:91], v[88:89], off offset:2064
	s_nop 0
	v_addc_co_u32_e32 v93, vcc, 0, v179, vcc
	global_load_dwordx4 v[92:95], v[92:93], off offset:2064
	v_pk_mul_f32 v[96:97], v[64:65], v[180:181]
	s_and_saveexec_b64 s[50:51], s[8:9]
	s_cbranch_execz .LBB0_2094
	v_mov_b64_e32 v[64:65], s[20:21]
	v_mad_i64_i32 v[64:65], s[54:55], v246, s81, v[64:65]
	v_lshl_add_u64 v[64:65], v[122:123], 2, v[64:65]
	v_add_co_u32_e32 v64, vcc, 0x5000, v64
	v_pk_mul_f32 v[98:99], v[66:67], v[98:99]
	s_nop 0
	v_addc_co_u32_e32 v65, vcc, 0, v65, vcc
	global_store_dwordx4 v[64:65], v[96:99], off offset:2048

; __device__ __forceinline__ unsigned cvt_pk_bf16(float lo, float hi) { f32x2_cv v = {lo, hi}; bf16x2_cv b = __builtin_convertvector(v, bf16x2_cv); return __builtin_bit_cast(unsigned, b); }
; __device__ __forceinline__ float siluf_(float x) { return x * __builtin_amdgcn_rcpf(1.0f + __expf(-x)); }
;     __device__ __forceinline__ void operator()(const f32x4 (&acc)[2][2][4][2], const Unit& u, int wr, int wc, int fr, int fq) const {
;     ...
;                     for (int m = 3; m >= 0; --m) {
;                         const f32x4 cur = acc[ai][bj][m][n] * rs[m];
;                         f32x4 prev = zero4;
;                         if (m > 0) prev = acc[ai][bj][m - 1][n] * rs[m - 1];
;                         f32x4 r1, r2;
; #pragma unroll
;                         for (int i = 0; i < 4; ++i) {
;                             r1[i] = dpp_mov<0x111>(dpp_mov<0x121>(0.f, prev[i]), cur[i]);
;                             r2[i] = dpp_mov<0x112>(dpp_mov<0x122>(0.f, prev[i]), cur[i]); }
;                         const f32x4 cvv = wb + w2 * cur + w1 * r1 + w0 * r2;
;                         if (bj == 0) {
;                             sg[m].x = cvt_pk_bf16(siluf_(cvv[0]), siluf_(cvv[1])); sg[m].y = cvt_pk_bf16(siluf_(cvv[2]), siluf_(cvv[3]));
;                         } else {
;                             f32x4 h;
;                             h[0] = __uint_as_float(sg[m].x << 16) * cvv[0]; h[1] = __uint_as_float(sg[m].x & 0xffff0000u) * cvv[1];
;                             h[2] = __uint_as_float(sg[m].y << 16) * cvv[2]; h[3] = __uint_as_float(sg[m].y & 0xffff0000u) * cvv[3];
;                             u32x2v w; w.x = cvt_pk_bf16(h[0], h[1]); w.y = cvt_pk_bf16(h[2], h[3]);
.LBB0_2096:
	s_or_b64 exec, exec, s[50:51]
	s_waitcnt vmcnt(4)
	v_pk_fma_f32 v[98:99], v[118:119], v[108:109], v[112:113]
	v_pk_fma_f32 v[64:65], v[120:121], v[110:111], v[114:115]
	v_pk_fma_f32 v[98:99], v[104:105], v[214:215], v[98:99]
	v_pk_fma_f32 v[64:65], v[106:107], v[220:221], v[64:65]
	v_pk_fma_f32 v[98:99], v[100:101], v[210:211], v[98:99]
	v_pk_fma_f32 v[64:65], v[102:103], v[216:217], v[64:65]
	v_mul_f32_e32 v118, 0xbfb8aa3b, v98
	v_mul_f32_e32 v119, 0xbfb8aa3b, v99
	v_exp_f32_e32 v118, v118
	v_exp_f32_e32 v119, v119
	v_mul_f32_e32 v120, 0xbfb8aa3b, v64
	v_mul_f32_e32 v121, 0xbfb8aa3b, v65
	v_exp_f32_e32 v120, v120
	v_exp_f32_e32 v121, v121
	v_add_f32_e32 v118, 1.0, v118
	v_add_f32_e32 v119, 1.0, v119
	v_rcp_f32_e32 v118, v118
	v_rcp_f32_e32 v119, v119
	v_add_f32_e32 v120, 1.0, v120
	v_add_f32_e32 v121, 1.0, v121
	v_rcp_f32_e32 v120, v120
	v_rcp_f32_e32 v121, v121
	v_pk_mul_f32 v[98:99], v[98:99], v[118:119]
	v_pk_fma_f32 v[118:119], v[152:153], v[108:109], v[112:113]
	v_cvt_pk_bf16_f32 v181, v98, v99
	v_pk_fma_f32 v[98:99], v[150:151], v[110:111], v[114:115]
	v_pk_fma_f32 v[118:119], v[104:105], v[206:207], v[118:119]
	v_pk_fma_f32 v[98:99], v[106:107], v[218:219], v[98:99]
	v_pk_fma_f32 v[118:119], v[100:101], v[204:205], v[118:119]
	v_pk_mul_f32 v[64:65], v[64:65], v[120:121]
	v_mul_f32_e32 v120, 0xbfb8aa3b, v118
	v_mul_f32_e32 v121, 0xbfb8aa3b, v119
	v_pk_fma_f32 v[98:99], v[102:103], v[208:209], v[98:99]
	v_exp_f32_e32 v120, v120
	v_exp_f32_e32 v121, v121
	v_mul_f32_e32 v150, 0xbfb8aa3b, v98
	v_mul_f32_e32 v151, 0xbfb8aa3b, v99
	v_exp_f32_e32 v150, v150
	v_exp_f32_e32 v151, v151
	v_add_f32_e32 v120, 1.0, v120
	v_add_f32_e32 v121, 1.0, v121
	v_rcp_f32_e32 v120, v120
	v_rcp_f32_e32 v121, v121
	v_add_f32_e32 v150, 1.0, v150
	v_add_f32_e32 v151, 1.0, v151
	v_rcp_f32_e32 v150, v150
	v_rcp_f32_e32 v151, v151
	v_cvt_pk_bf16_f32 v152, v64, v65
	v_pk_mul_f32 v[64:65], v[118:119], v[120:121]
	v_pk_fma_f32 v[118:119], v[146:147], v[108:109], v[112:113]
	v_cvt_pk_bf16_f32 v153, v64, v65
	v_pk_mul_f32 v[64:65], v[98:99], v[150:151]
	v_pk_fma_f32 v[98:99], v[144:145], v[110:111], v[114:115]
	v_pk_fma_f32 v[118:119], v[104:105], v[200:201], v[118:119]
	v_pk_fma_f32 v[98:99], v[106:107], v[212:213], v[98:99]
	v_pk_fma_f32 v[118:119], v[100:101], v[198:199], v[118:119]
	v_pk_fma_f32 v[98:99], v[102:103], v[202:203], v[98:99]
	v_mul_f32_e32 v120, 0xbfb8aa3b, v118
	v_mul_f32_e32 v121, 0xbfb8aa3b, v119
	v_exp_f32_e32 v120, v120
	v_exp_f32_e32 v121, v121
	v_mul_f32_e32 v144, 0xbfb8aa3b, v98
	v_mul_f32_e32 v145, 0xbfb8aa3b, v99
	v_exp_f32_e32 v144, v144
	v_exp_f32_e32 v145, v145
	v_add_f32_e32 v120, 1.0, v120
	v_add_f32_e32 v121, 1.0, v121
	v_rcp_f32_e32 v120, v120
	v_rcp_f32_e32 v121, v121
	v_add_f32_e32 v144, 1.0, v144
	v_add_f32_e32 v145, 1.0, v145
	v_pk_fma_f32 v[108:109], v[116:117], v[108:109], v[112:113]
	v_rcp_f32_e32 v144, v144
	v_rcp_f32_e32 v145, v145
	v_pk_fma_f32 v[104:105], v[104:105], v[194:195], v[108:109]
	v_cvt_pk_bf16_f32 v146, v64, v65
	v_pk_fma_f32 v[100:101], v[100:101], v[192:193], v[104:105]
	v_pk_mul_f32 v[64:65], v[118:119], v[120:121]
	v_mul_f32_e32 v104, 0xbfb8aa3b, v100
	v_mul_f32_e32 v105, 0xbfb8aa3b, v101
	v_exp_f32_e32 v104, v104
	v_exp_f32_e32 v105, v105
	v_cvt_pk_bf16_f32 v118, v64, v65
	v_pk_mul_f32 v[64:65], v[98:99], v[144:145]
	v_pk_fma_f32 v[98:99], v[142:143], v[110:111], v[114:115]
	v_pk_mul_f32 v[72:73], v[72:73], v[184:185]
	v_pk_fma_f32 v[98:99], v[106:107], v[196:197], v[98:99]
	v_cvt_pk_bf16_f32 v106, v64, v65
	v_pk_fma_f32 v[98:99], v[102:103], v[148:149], v[98:99]
	v_add_f32_e32 v102, 1.0, v104
	v_add_f32_e32 v103, 1.0, v105
	v_mul_f32_e32 v104, 0xbfb8aa3b, v98
	v_mul_f32_e32 v105, 0xbfb8aa3b, v99
	v_exp_f32_e32 v104, v104
	v_exp_f32_e32 v105, v105
	v_rcp_f32_e32 v102, v102
	v_rcp_f32_e32 v103, v103
	v_add_f32_e32 v104, 1.0, v104
	v_add_f32_e32 v105, 1.0, v105
	v_rcp_f32_e32 v104, v104
	v_rcp_f32_e32 v105, v105
	v_pk_mul_f32 v[64:65], v[100:101], v[102:103]
	v_cvt_pk_bf16_f32 v107, v64, v65
	v_pk_mul_f32 v[64:65], v[98:99], v[104:105]
	v_cvt_pk_bf16_f32 v104, v64, v65
	v_mov_b32_e32 v64, v184
	v_mov_b32_e32 v65, v184
	v_pk_mul_f32 v[64:65], v[74:75], v[64:65]
	v_mov_b32_dpp v74, v72 row_ror:1 row_mask:0xf bank_mask:0xf
	v_mov_b32_dpp v98, v72 row_ror:2 row_mask:0xf bank_mask:0xf
	v_mov_b32_dpp v75, v73 row_ror:1 row_mask:0xf bank_mask:0xf
	v_mov_b32_dpp v99, v73 row_ror:2 row_mask:0xf bank_mask:0xf
	v_mov_b32_dpp v100, v64 row_ror:1 row_mask:0xf bank_mask:0xf
	v_mov_b32_dpp v102, v64 row_ror:2 row_mask:0xf bank_mask:0xf
	v_mov_b32_dpp v101, v65 row_ror:1 row_mask:0xf bank_mask:0xf
	v_mov_b32_dpp v103, v65 row_ror:2 row_mask:0xf bank_mask:0xf
	v_mov_b32_dpp v74, v76 row_shr:1 row_mask:0xf bank_mask:0xf
	v_mov_b32_dpp v98, v76 row_shr:2 row_mask:0xf bank_mask:0xf
	v_mov_b32_dpp v75, v77 row_shr:1 row_mask:0xf bank_mask:0xf
	v_mov_b32_dpp v99, v77 row_shr:2 row_mask:0xf bank_mask:0xf
	v_mov_b32_dpp v100, v78 row_shr:1 row_mask:0xf bank_mask:0xf
	v_mov_b32_dpp v102, v78 row_shr:2 row_mask:0xf bank_mask:0xf
	v_mov_b32_dpp v101, v79 row_shr:1 row_mask:0xf bank_mask:0xf
	v_mov_b32_dpp v103, v79 row_shr:2 row_mask:0xf bank_mask:0xf
	s_waitcnt vmcnt(0)
; __device__ __forceinline__ unsigned cvt_pk_bf16(float lo, float hi) { f32x2_cv v = {lo, hi}; bf16x2_cv b = __builtin_convertvector(v, bf16x2_cv); return __builtin_bit_cast(unsigned, b); }
; __device__ __forceinline__ float siluf_(float x) { return x * __builtin_amdgcn_rcpf(1.0f + __expf(-x)); }
;     __device__ __forceinline__ void operator()(const f32x4 (&acc)[2][2][4][2], const Unit& u, int wr, int wc, int fr, int fq) const {
;     ...
;             const int rowb = u.pm * BM + ai * HALF + wr * 64;
;             const int blk = rowb >> 6;
;             float rs[4];
; #pragma unroll
;             for (int m = 0; m < 4; ++m) rs[m] = rt[ai * HALF + m * 16];
; #pragma unroll
;             for (int n = 0; n < 2; ++n) {
;                 const int cg = jb + 4 * n;
;                 u32x2v sg[4];
; #pragma unroll
;                 for (int bj = 0; bj < 2; ++bj) {
;                     const int col = bj * dff + cg;
;                     const f32x4 w0 = *(const f32x4*)(cw + col), w1 = *(const f32x4*)(cw + 2 * dff + col), w2 = *(const f32x4*)(cw + 4 * dff + col), wb = *(const f32x4*)(cb + col);
;                     if (fr < 2) *(f32x4*)(RB + ((size_t)(blk * 4 + fr) * 2 + bj) * dff + cg) = acc[ai][bj][0][n] * rs[0];
;     ...
;                         for (int i = 0; i < 4; ++i) {
;                             r1[i] = dpp_mov<0x111>(dpp_mov<0x121>(0.f, prev[i]), cur[i]);
;                             r2[i] = dpp_mov<0x112>(dpp_mov<0x122>(0.f, prev[i]), cur[i]); }
;                         const f32x4 cvv = wb + w2 * cur + w1 * r1 + w0 * r2;
;                         if (bj == 0) {
;                             sg[m].x = cvt_pk_bf16(siluf_(cvv[0]), siluf_(cvv[1])); sg[m].y = cvt_pk_bf16(siluf_(cvv[2]), siluf_(cvv[3]));
;                         } else {
;                             f32x4 h;
;                             h[0] = __uint_as_float(sg[m].x << 16) * cvv[0]; h[1] = __uint_as_float(sg[m].x & 0xffff0000u) * cvv[1];
;                             h[2] = __uint_as_float(sg[m].y << 16) * cvv[2]; h[3] = __uint_as_float(sg[m].y & 0xffff0000u) * cvv[3];
;                             u32x2v w; w.x = cvt_pk_bf16(h[0], h[1]); w.y = cvt_pk_bf16(h[2], h[3]);
;                             *(u32x2v*)(H + (size_t)(rowb + m * 16 + fr) * dff + cg) = w;
	v_pk_fma_f32 v[78:79], v[78:79], v[90:91], v[94:95]
	v_pk_fma_f32 v[76:77], v[76:77], v[88:89], v[92:93]
	v_pk_fma_f32 v[78:79], v[86:87], v[100:101], v[78:79]
	v_pk_fma_f32 v[74:75], v[84:85], v[74:75], v[76:77]
	v_pk_fma_f32 v[76:77], v[82:83], v[102:103], v[78:79]
	v_pk_fma_f32 v[74:75], v[80:81], v[98:99], v[74:75]
	v_lshlrev_b32_e32 v78, 16, v181
	v_and_b32_e32 v79, 0xffff0000, v181
	v_pk_mul_f32 v[74:75], v[74:75], v[78:79]
	v_lshlrev_b32_e32 v78, 16, v152
	v_and_b32_e32 v79, 0xffff0000, v152
	v_pk_mul_f32 v[76:77], v[76:77], v[78:79]
	v_cvt_pk_bf16_f32 v74, v74, v75
	v_cvt_pk_bf16_f32 v75, v76, v77
	global_store_dwordx2 v[134:135], v[74:75], off offset:8
	v_mov_b32_e32 v74, v182
	v_mov_b32_e32 v75, v182
	v_pk_mul_f32 v[70:71], v[70:71], v[74:75]
	v_pk_mul_f32 v[68:69], v[68:69], v[182:183]
	s_nop 1
	v_mov_b32_dpp v74, v68 row_ror:1 row_mask:0xf bank_mask:0xf
	v_mov_b32_dpp v76, v68 row_ror:2 row_mask:0xf bank_mask:0xf
	v_mov_b32_dpp v75, v69 row_ror:1 row_mask:0xf bank_mask:0xf
	v_mov_b32_dpp v77, v69 row_ror:2 row_mask:0xf bank_mask:0xf
	v_mov_b32_dpp v74, v72 row_shr:1 row_mask:0xf bank_mask:0xf
	v_mov_b32_dpp v76, v72 row_shr:2 row_mask:0xf bank_mask:0xf
	v_mov_b32_dpp v75, v73 row_shr:1 row_mask:0xf bank_mask:0xf
	v_mov_b32_dpp v77, v73 row_shr:2 row_mask:0xf bank_mask:0xf
	v_mov_b32_dpp v78, v70 row_ror:1 row_mask:0xf bank_mask:0xf
	v_mov_b32_dpp v98, v70 row_ror:2 row_mask:0xf bank_mask:0xf
	v_mov_b32_dpp v79, v71 row_ror:1 row_mask:0xf bank_mask:0xf
	v_mov_b32_dpp v99, v71 row_ror:2 row_mask:0xf bank_mask:0xf
	v_pk_fma_f32 v[72:73], v[72:73], v[88:89], v[92:93]
	v_mov_b32_dpp v78, v64 row_shr:1 row_mask:0xf bank_mask:0xf
	v_mov_b32_dpp v98, v64 row_shr:2 row_mask:0xf bank_mask:0xf
	v_mov_b32_dpp v79, v65 row_shr:1 row_mask:0xf bank_mask:0xf
	v_mov_b32_dpp v99, v65 row_shr:2 row_mask:0xf bank_mask:0xf
	v_pk_fma_f32 v[64:65], v[64:65], v[90:91], v[94:95]
	v_pk_fma_f32 v[72:73], v[84:85], v[74:75], v[72:73]
	v_pk_fma_f32 v[64:65], v[86:87], v[78:79], v[64:65]
	v_pk_fma_f32 v[72:73], v[80:81], v[76:77], v[72:73]
	v_lshlrev_b32_e32 v74, 16, v153
	v_and_b32_e32 v75, 0xffff0000, v153
	v_pk_fma_f32 v[64:65], v[82:83], v[98:99], v[64:65]
	v_pk_mul_f32 v[72:73], v[72:73], v[74:75]
	v_lshlrev_b32_e32 v74, 16, v146
	v_and_b32_e32 v75, 0xffff0000, v146
	v_pk_mul_f32 v[64:65], v[64:65], v[74:75]
	v_cvt_pk_bf16_f32 v72, v72, v73
	v_cvt_pk_bf16_f32 v73, v64, v65
	global_store_dwordx2 v[136:137], v[72:73], off offset:8
	v_mov_b32_e32 v181, v180
	v_pk_mul_f32 v[64:65], v[66:67], v[180:181]
	v_mov_b32_dpp v66, v96 row_ror:1 row_mask:0xf bank_mask:0xf
	v_mov_b32_dpp v72, v96 row_ror:2 row_mask:0xf bank_mask:0xf
	v_mov_b32_dpp v67, v97 row_ror:1 row_mask:0xf bank_mask:0xf
	v_mov_b32_dpp v73, v97 row_ror:2 row_mask:0xf bank_mask:0xf
	v_mov_b32_dpp v74, v64 row_ror:1 row_mask:0xf bank_mask:0xf
	v_mov_b32_dpp v76, v64 row_ror:2 row_mask:0xf bank_mask:0xf
	v_mov_b32_dpp v75, v65 row_ror:1 row_mask:0xf bank_mask:0xf
	v_mov_b32_dpp v77, v65 row_ror:2 row_mask:0xf bank_mask:0xf
	v_mov_b32_dpp v66, v68 row_shr:1 row_mask:0xf bank_mask:0xf
	v_mov_b32_dpp v72, v68 row_shr:2 row_mask:0xf bank_mask:0xf
	v_mov_b32_dpp v67, v69 row_shr:1 row_mask:0xf bank_mask:0xf
	v_mov_b32_dpp v73, v69 row_shr:2 row_mask:0xf bank_mask:0xf
	v_mov_b32_dpp v74, v70 row_shr:1 row_mask:0xf bank_mask:0xf
	v_mov_b32_dpp v76, v70 row_shr:2 row_mask:0xf bank_mask:0xf
	v_mov_b32_dpp v75, v71 row_shr:1 row_mask:0xf bank_mask:0xf
	v_mov_b32_dpp v77, v71 row_shr:2 row_mask:0xf bank_mask:0xf
	v_pk_fma_f32 v[70:71], v[70:71], v[90:91], v[94:95]
	v_pk_fma_f32 v[68:69], v[68:69], v[88:89], v[92:93]
	v_pk_fma_f32 v[70:71], v[86:87], v[74:75], v[70:71]
	v_pk_fma_f32 v[66:67], v[84:85], v[66:67], v[68:69]
	v_pk_fma_f32 v[68:69], v[82:83], v[76:77], v[70:71]
	v_pk_fma_f32 v[66:67], v[80:81], v[72:73], v[66:67]
	v_lshlrev_b32_e32 v70, 16, v118
	v_and_b32_e32 v71, 0xffff0000, v118
	v_pk_mul_f32 v[66:67], v[66:67], v[70:71]
	v_lshlrev_b32_e32 v70, 16, v106
	v_and_b32_e32 v71, 0xffff0000, v106
	v_pk_mul_f32 v[68:69], v[68:69], v[70:71]
	v_cvt_pk_bf16_f32 v66, v66, v67
	v_cvt_pk_bf16_f32 v67, v68, v69
	global_store_dwordx2 v[138:139], v[66:67], off offset:8
	v_mov_b32_e32 v67, 0
	v_mov_b32_e32 v71, 0
	v_pk_fma_f32 v[74:75], v[96:97], v[88:89], v[92:93]
	v_mov_b32_dpp v67, v67 row_ror:1 row_mask:0xf bank_mask:0xf
	v_mov_b32_dpp v71, v71 row_ror:2 row_mask:0xf bank_mask:0xf
	v_mov_b32_e32 v68, v67
	v_mov_b32_e32 v69, v67
	v_mov_b32_e32 v66, v67
	v_mov_b32_e32 v70, v71
	v_mov_b32_dpp v68, v96 row_shr:1 row_mask:0xf bank_mask:0xf
	v_mov_b32_e32 v72, v71
	v_mov_b32_dpp v69, v97 row_shr:1 row_mask:0xf bank_mask:0xf
	v_mov_b32_e32 v73, v71
	v_mov_b32_dpp v66, v64 row_shr:1 row_mask:0xf bank_mask:0xf
	v_mov_b32_dpp v70, v64 row_shr:2 row_mask:0xf bank_mask:0xf
	v_mov_b32_dpp v67, v65 row_shr:1 row_mask:0xf bank_mask:0xf
	v_mov_b32_dpp v71, v65 row_shr:2 row_mask:0xf bank_mask:0xf
	v_pk_fma_f32 v[64:65], v[64:65], v[90:91], v[94:95]
	v_mov_b32_dpp v72, v96 row_shr:2 row_mask:0xf bank_mask:0xf
	v_mov_b32_dpp v73, v97 row_shr:2 row_mask:0xf bank_mask:0xf
	v_pk_fma_f32 v[64:65], v[86:87], v[66:67], v[64:65]
	v_pk_fma_f32 v[66:67], v[84:85], v[68:69], v[74:75]
	v_lshlrev_b32_e32 v68, 16, v107
	v_pk_fma_f32 v[66:67], v[80:81], v[72:73], v[66:67]
	v_and_b32_e32 v69, 0xffff0000, v107
	v_pk_fma_f32 v[64:65], v[82:83], v[70:71], v[64:65]
	v_pk_mul_f32 v[66:67], v[66:67], v[68:69]
	v_lshlrev_b32_e32 v68, 16, v104
	v_and_b32_e32 v69, 0xffff0000, v104
	v_pk_mul_f32 v[64:65], v[64:65], v[68:69]
	v_cvt_pk_bf16_f32 v66, v66, v67
	v_cvt_pk_bf16_f32 v67, v64, v65
	global_store_dwordx2 v[140:141], v[66:67], off offset:8
	global_load_dwordx4 v[68:71], v[172:173], off
	global_load_dwordx4 v[72:75], v[174:175], off
	global_load_dwordx4 v[76:79], v[176:177], off
	global_load_dwordx4 v[80:83], v[178:179], off
	ds_read2_b32 v[90:91], v244 offset0:128 offset1:144
	ds_read2_b32 v[94:95], v244 offset0:160 offset1:176
	s_addk_i32 s39, 0x80
	s_ashr_i32 s41, s39, 4
	v_or_b32_e32 v153, s41, v236
	s_waitcnt lgkmcnt(1)
	v_mov_b32_e32 v92, v91
	v_mov_b32_e32 v91, v90
	s_waitcnt lgkmcnt(0)
	v_mov_b32_e32 v96, v95
	v_pk_mul_f32 v[84:85], v[48:49], v[90:91]
	s_and_saveexec_b64 s[50:51], s[8:9]
	s_cbranch_execz .LBB0_2098
	v_mov_b32_e32 v48, v90
	v_mov_b32_e32 v49, v90
	v_pk_mul_f32 v[86:87], v[50:51], v[48:49]
	v_mov_b64_e32 v[48:49], s[20:21]
	v_mad_i64_i32 v[48:49], s[54:55], v153, s81, v[48:49]
	v_lshl_add_u64 v[48:49], v[170:171], 2, v[48:49]
	global_store_dwordx4 v[48:49], v[84:87], off

;     __device__ __forceinline__ void operator()(const f32x4 (&acc)[2][2][4][2], const Unit& u, int wr, int wc, int fr, int fq) const {
;     ...
;                     const f32x4 w0 = *(const f32x4*)(cw + col), w1 = *(const f32x4*)(cw + 2 * dff + col), w2 = *(const f32x4*)(cw + 4 * dff + col), wb = *(const f32x4*)(cb + col);
;                     if (fr < 2) *(f32x4*)(RB + ((size_t)(blk * 4 + fr) * 2 + bj) * dff + cg) = acc[ai][bj][0][n] * rs[0];
;                     if (fr >= 14) *(f32x4*)(RB + ((size_t)(blk * 4 + fr - 12) * 2 + bj) * dff + cg) = acc[ai][bj][3][n] * rs[3];
; #pragma unroll
;                     for (int m = 3; m >= 0; --m) {
;                         const f32x4 cur = acc[ai][bj][m][n] * rs[m];
;                         f32x4 prev = zero4;
;                         if (m > 0) prev = acc[ai][bj][m - 1][n] * rs[m - 1];
;                         f32x4 r1, r2;
; #pragma unroll
;                         for (int i = 0; i < 4; ++i) {
;                             r1[i] = dpp_mov<0x111>(dpp_mov<0x121>(0.f, prev[i]), cur[i]);
;                             r2[i] = dpp_mov<0x112>(dpp_mov<0x122>(0.f, prev[i]), cur[i]); }
.LBB0_2100:
	s_or_b64 exec, exec, s[50:51]
	v_pk_mul_f32 v[106:107], v[58:59], v[94:95] op_sel_hi:[1,0]
	v_pk_mul_f32 v[108:109], v[56:57], v[94:95] op_sel_hi:[1,0]
	s_nop 1
	v_mov_b32_dpp v144, v108 row_ror:1 row_mask:0xf bank_mask:0xf
	v_mov_b32_dpp v142, v108 row_ror:2 row_mask:0xf bank_mask:0xf
	v_mov_b32_dpp v145, v109 row_ror:1 row_mask:0xf bank_mask:0xf
	v_mov_b32_dpp v143, v109 row_ror:2 row_mask:0xf bank_mask:0xf
	v_mov_b32_dpp v150, v106 row_ror:1 row_mask:0xf bank_mask:0xf
	v_mov_b32_dpp v146, v106 row_ror:2 row_mask:0xf bank_mask:0xf
	v_mov_b32_dpp v151, v107 row_ror:1 row_mask:0xf bank_mask:0xf
	v_mov_b32_dpp v147, v107 row_ror:2 row_mask:0xf bank_mask:0xf
	v_lshl_add_u64 v[48:49], v[172:173], 0, s[34:35]
	v_lshl_add_u64 v[60:61], v[174:175], 0, s[34:35]
	v_lshl_add_u64 v[62:63], v[176:177], 0, s[34:35]
	v_lshl_add_u64 v[64:65], v[178:179], 0, s[34:35]
	v_mov_b32_dpp v144, v86 row_shr:1 row_mask:0xf bank_mask:0xf
	v_mov_b32_dpp v142, v86 row_shr:2 row_mask:0xf bank_mask:0xf
	v_mov_b32_dpp v145, v87 row_shr:1 row_mask:0xf bank_mask:0xf
	v_mov_b32_dpp v143, v87 row_shr:2 row_mask:0xf bank_mask:0xf
	v_mov_b32_dpp v150, v88 row_shr:1 row_mask:0xf bank_mask:0xf
	v_mov_b32_dpp v146, v88 row_shr:2 row_mask:0xf bank_mask:0xf
	v_mov_b32_dpp v151, v89 row_shr:1 row_mask:0xf bank_mask:0xf
	v_mov_b32_dpp v147, v89 row_shr:2 row_mask:0xf bank_mask:0xf
	v_pk_mul_f32 v[100:101], v[54:55], v[92:93] op_sel_hi:[1,0]
	v_pk_mul_f32 v[102:103], v[52:53], v[92:93] op_sel_hi:[1,0]
	s_nop 1
	v_mov_b32_dpp v136, v102 row_ror:1 row_mask:0xf bank_mask:0xf
	v_mov_b32_dpp v134, v102 row_ror:2 row_mask:0xf bank_mask:0xf
	v_mov_b32_dpp v137, v103 row_ror:1 row_mask:0xf bank_mask:0xf
	v_mov_b32_dpp v135, v103 row_ror:2 row_mask:0xf bank_mask:0xf
	v_mov_b32_dpp v148, v100 row_ror:1 row_mask:0xf bank_mask:0xf
	v_mov_b32_dpp v138, v100 row_ror:2 row_mask:0xf bank_mask:0xf
	v_mov_b32_dpp v149, v101 row_ror:1 row_mask:0xf bank_mask:0xf
	v_mov_b32_dpp v139, v101 row_ror:2 row_mask:0xf bank_mask:0xf
	v_mov_b32_dpp v136, v108 row_shr:1 row_mask:0xf bank_mask:0xf
	v_mov_b32_dpp v134, v108 row_shr:2 row_mask:0xf bank_mask:0xf
	v_mov_b32_dpp v137, v109 row_shr:1 row_mask:0xf bank_mask:0xf
	v_mov_b32_dpp v135, v109 row_shr:2 row_mask:0xf bank_mask:0xf
	v_mov_b32_dpp v148, v106 row_shr:1 row_mask:0xf bank_mask:0xf
	v_mov_b32_dpp v138, v106 row_shr:2 row_mask:0xf bank_mask:0xf
	v_mov_b32_dpp v149, v107 row_shr:1 row_mask:0xf bank_mask:0xf
	v_mov_b32_dpp v139, v107 row_shr:2 row_mask:0xf bank_mask:0xf
	v_mov_b32_e32 v66, v90
	v_mov_b32_e32 v67, v90
	v_pk_mul_f32 v[98:99], v[50:51], v[66:67]
	v_mov_b32_dpp v118, v84 row_ror:1 row_mask:0xf bank_mask:0xf
	v_mov_b32_dpp v116, v84 row_ror:2 row_mask:0xf bank_mask:0xf
	v_mov_b32_dpp v119, v85 row_ror:1 row_mask:0xf bank_mask:0xf
	v_mov_b32_dpp v117, v85 row_ror:2 row_mask:0xf bank_mask:0xf
	v_mov_b32_dpp v140, v98 row_ror:1 row_mask:0xf bank_mask:0xf
	v_mov_b32_dpp v120, v98 row_ror:2 row_mask:0xf bank_mask:0xf
	v_mov_b32_dpp v141, v99 row_ror:1 row_mask:0xf bank_mask:0xf
	v_mov_b32_dpp v121, v99 row_ror:2 row_mask:0xf bank_mask:0xf
	v_mov_b32_dpp v118, v102 row_shr:1 row_mask:0xf bank_mask:0xf
	v_mov_b32_dpp v116, v102 row_shr:2 row_mask:0xf bank_mask:0xf
	v_mov_b32_dpp v119, v103 row_shr:1 row_mask:0xf bank_mask:0xf
	v_mov_b32_dpp v117, v103 row_shr:2 row_mask:0xf bank_mask:0xf
	v_mov_b32_dpp v140, v100 row_shr:1 row_mask:0xf bank_mask:0xf
	v_mov_b32_dpp v120, v100 row_shr:2 row_mask:0xf bank_mask:0xf
	v_mov_b32_dpp v141, v101 row_shr:1 row_mask:0xf bank_mask:0xf
	v_mov_b32_dpp v121, v101 row_shr:2 row_mask:0xf bank_mask:0xf
	v_mov_b32_e32 v115, 0
	v_mov_b32_e32 v105, 0
	s_nop 0
	v_mov_b32_dpp v115, v115 row_ror:1 row_mask:0xf bank_mask:0xf
	v_mov_b32_dpp v105, v105 row_ror:2 row_mask:0xf bank_mask:0xf
	v_mov_b32_e32 v112, v115
	v_mov_b32_e32 v110, v105
	v_mov_b32_e32 v113, v115
	v_mov_b32_e32 v111, v105
	v_mov_b32_e32 v114, v115
	v_mov_b32_e32 v104, v105
	v_mov_b32_dpp v112, v84 row_shr:1 row_mask:0xf bank_mask:0xf
	v_mov_b32_dpp v110, v84 row_shr:2 row_mask:0xf bank_mask:0xf
	v_mov_b32_dpp v113, v85 row_shr:1 row_mask:0xf bank_mask:0xf
	v_mov_b32_dpp v111, v85 row_shr:2 row_mask:0xf bank_mask:0xf
	v_mov_b32_dpp v114, v98 row_shr:1 row_mask:0xf bank_mask:0xf
	v_mov_b32_dpp v104, v98 row_shr:2 row_mask:0xf bank_mask:0xf
	v_mov_b32_dpp v115, v99 row_shr:1 row_mask:0xf bank_mask:0xf
	v_mov_b32_dpp v105, v99 row_shr:2 row_mask:0xf bank_mask:0xf
	global_load_dwordx4 v[48:51], v[48:49], off
	s_nop 0
	global_load_dwordx4 v[52:55], v[60:61], off
	global_load_dwordx4 v[56:59], v[62:63], off
	s_nop 0
	global_load_dwordx4 v[60:63], v[64:65], off
	v_pk_mul_f32 v[64:65], v[32:33], v[90:91]
	s_and_saveexec_b64 s[50:51], s[8:9]
	s_cbranch_execz .LBB0_2102
	v_mov_b64_e32 v[32:33], s[20:21]
	v_mad_i64_i32 v[32:33], s[54:55], v153, s81, v[32:33]
	v_lshl_add_u64 v[32:33], v[170:171], 2, v[32:33]
	v_add_co_u32_e32 v32, vcc, 0x5000, v32
	v_pk_mul_f32 v[66:67], v[34:35], v[66:67]
	s_nop 0
	v_addc_co_u32_e32 v33, vcc, 0, v33, vcc
	global_store_dwordx4 v[32:33], v[64:67], off offset:2048

; __device__ __forceinline__ unsigned cvt_pk_bf16(float lo, float hi) { f32x2_cv v = {lo, hi}; bf16x2_cv b = __builtin_convertvector(v, bf16x2_cv); return __builtin_bit_cast(unsigned, b); }
; __device__ __forceinline__ float siluf_(float x) { return x * __builtin_amdgcn_rcpf(1.0f + __expf(-x)); }
;     __device__ __forceinline__ void operator()(const f32x4 (&acc)[2][2][4][2], const Unit& u, int wr, int wc, int fr, int fq) const {
;     ...
;                     for (int m = 3; m >= 0; --m) {
;                         const f32x4 cur = acc[ai][bj][m][n] * rs[m];
;                         f32x4 prev = zero4;
;                         if (m > 0) prev = acc[ai][bj][m - 1][n] * rs[m - 1];
;                         f32x4 r1, r2;
; #pragma unroll
;                         for (int i = 0; i < 4; ++i) {
;                             r1[i] = dpp_mov<0x111>(dpp_mov<0x121>(0.f, prev[i]), cur[i]);
;                             r2[i] = dpp_mov<0x112>(dpp_mov<0x122>(0.f, prev[i]), cur[i]); }
;                         const f32x4 cvv = wb + w2 * cur + w1 * r1 + w0 * r2;
;                         if (bj == 0) {
;                             sg[m].x = cvt_pk_bf16(siluf_(cvv[0]), siluf_(cvv[1])); sg[m].y = cvt_pk_bf16(siluf_(cvv[2]), siluf_(cvv[3]));
;                         } else {
;                             f32x4 h;
;                             h[0] = __uint_as_float(sg[m].x << 16) * cvv[0]; h[1] = __uint_as_float(sg[m].x & 0xffff0000u) * cvv[1];
;                             h[2] = __uint_as_float(sg[m].y << 16) * cvv[2]; h[3] = __uint_as_float(sg[m].y & 0xffff0000u) * cvv[3];
;                             u32x2v w; w.x = cvt_pk_bf16(h[0], h[1]); w.y = cvt_pk_bf16(h[2], h[3]);
.LBB0_2104:
	s_or_b64 exec, exec, s[50:51]
	s_waitcnt vmcnt(4)
	v_pk_fma_f32 v[66:67], v[76:77], v[86:87], v[80:81]
	v_pk_fma_f32 v[32:33], v[78:79], v[88:89], v[82:83]
	v_pk_fma_f32 v[66:67], v[72:73], v[144:145], v[66:67]
	v_pk_fma_f32 v[32:33], v[74:75], v[150:151], v[32:33]
	v_pk_fma_f32 v[66:67], v[68:69], v[142:143], v[66:67]
	v_pk_fma_f32 v[32:33], v[70:71], v[146:147], v[32:33]
	v_mul_f32_e32 v86, 0xbfb8aa3b, v66
	v_mul_f32_e32 v87, 0xbfb8aa3b, v67
	v_exp_f32_e32 v86, v86
	v_exp_f32_e32 v87, v87
	v_mul_f32_e32 v88, 0xbfb8aa3b, v32
	v_mul_f32_e32 v89, 0xbfb8aa3b, v33
	v_exp_f32_e32 v88, v88
	v_exp_f32_e32 v89, v89
	v_add_f32_e32 v86, 1.0, v86
	v_add_f32_e32 v87, 1.0, v87
	v_rcp_f32_e32 v86, v86
	v_rcp_f32_e32 v87, v87
	v_add_f32_e32 v88, 1.0, v88
	v_add_f32_e32 v89, 1.0, v89
	v_rcp_f32_e32 v88, v88
	v_rcp_f32_e32 v89, v89
	v_pk_mul_f32 v[66:67], v[66:67], v[86:87]
	v_pk_fma_f32 v[86:87], v[108:109], v[76:77], v[80:81]
	v_cvt_pk_bf16_f32 v142, v66, v67
	v_pk_fma_f32 v[66:67], v[106:107], v[78:79], v[82:83]
	v_pk_fma_f32 v[86:87], v[72:73], v[136:137], v[86:87]
	v_pk_fma_f32 v[66:67], v[74:75], v[148:149], v[66:67]
	v_pk_fma_f32 v[86:87], v[68:69], v[134:135], v[86:87]
	v_pk_mul_f32 v[32:33], v[32:33], v[88:89]
	v_mul_f32_e32 v88, 0xbfb8aa3b, v86
	v_mul_f32_e32 v89, 0xbfb8aa3b, v87
	v_pk_fma_f32 v[66:67], v[70:71], v[138:139], v[66:67]
	v_exp_f32_e32 v88, v88
	v_exp_f32_e32 v89, v89
	v_mul_f32_e32 v106, 0xbfb8aa3b, v66
	v_mul_f32_e32 v107, 0xbfb8aa3b, v67
	v_exp_f32_e32 v106, v106
	v_exp_f32_e32 v107, v107
	v_add_f32_e32 v88, 1.0, v88
	v_add_f32_e32 v89, 1.0, v89
	v_rcp_f32_e32 v88, v88
	v_rcp_f32_e32 v89, v89
	v_add_f32_e32 v106, 1.0, v106
	v_add_f32_e32 v107, 1.0, v107
	v_rcp_f32_e32 v106, v106
	v_rcp_f32_e32 v107, v107
	v_cvt_pk_bf16_f32 v108, v32, v33
	v_pk_mul_f32 v[32:33], v[86:87], v[88:89]
	v_pk_fma_f32 v[86:87], v[102:103], v[76:77], v[80:81]
	v_cvt_pk_bf16_f32 v109, v32, v33
	v_pk_mul_f32 v[32:33], v[66:67], v[106:107]
	v_pk_fma_f32 v[66:67], v[100:101], v[78:79], v[82:83]
	v_pk_fma_f32 v[86:87], v[72:73], v[118:119], v[86:87]
	v_pk_fma_f32 v[66:67], v[74:75], v[140:141], v[66:67]
	v_pk_fma_f32 v[86:87], v[68:69], v[116:117], v[86:87]
	v_pk_fma_f32 v[66:67], v[70:71], v[120:121], v[66:67]
	v_mul_f32_e32 v88, 0xbfb8aa3b, v86
	v_mul_f32_e32 v89, 0xbfb8aa3b, v87
	v_exp_f32_e32 v88, v88
	v_exp_f32_e32 v89, v89
	v_mul_f32_e32 v100, 0xbfb8aa3b, v66
	v_mul_f32_e32 v101, 0xbfb8aa3b, v67
	v_exp_f32_e32 v100, v100
	v_exp_f32_e32 v101, v101
	v_add_f32_e32 v88, 1.0, v88
	v_add_f32_e32 v89, 1.0, v89
	v_rcp_f32_e32 v88, v88
	v_rcp_f32_e32 v89, v89
	v_add_f32_e32 v100, 1.0, v100
	v_add_f32_e32 v101, 1.0, v101
	v_pk_fma_f32 v[76:77], v[84:85], v[76:77], v[80:81]
	v_rcp_f32_e32 v100, v100
	v_rcp_f32_e32 v101, v101
	v_pk_fma_f32 v[72:73], v[72:73], v[112:113], v[76:77]
	v_cvt_pk_bf16_f32 v102, v32, v33
	v_pk_fma_f32 v[68:69], v[68:69], v[110:111], v[72:73]
	v_pk_mul_f32 v[32:33], v[86:87], v[88:89]
	v_mul_f32_e32 v72, 0xbfb8aa3b, v68
	v_mul_f32_e32 v73, 0xbfb8aa3b, v69
	v_exp_f32_e32 v72, v72
	v_exp_f32_e32 v73, v73
	v_cvt_pk_bf16_f32 v86, v32, v33
	v_pk_mul_f32 v[32:33], v[66:67], v[100:101]
	v_pk_fma_f32 v[66:67], v[98:99], v[78:79], v[82:83]
	v_mov_b32_e32 v95, v94
	v_pk_fma_f32 v[66:67], v[74:75], v[114:115], v[66:67]
	v_cvt_pk_bf16_f32 v74, v32, v33
	v_pk_fma_f32 v[66:67], v[70:71], v[104:105], v[66:67]
	v_add_f32_e32 v70, 1.0, v72
	v_add_f32_e32 v71, 1.0, v73
	v_mul_f32_e32 v72, 0xbfb8aa3b, v66
	v_mul_f32_e32 v73, 0xbfb8aa3b, v67
	v_exp_f32_e32 v72, v72
	v_exp_f32_e32 v73, v73
	v_rcp_f32_e32 v70, v70
	v_rcp_f32_e32 v71, v71
	v_add_f32_e32 v72, 1.0, v72
	v_add_f32_e32 v73, 1.0, v73
	v_rcp_f32_e32 v72, v72
	v_rcp_f32_e32 v73, v73
	v_pk_mul_f32 v[32:33], v[68:69], v[70:71]
	v_pk_mul_f32 v[40:41], v[40:41], v[94:95]
	v_cvt_pk_bf16_f32 v75, v32, v33
	v_pk_mul_f32 v[32:33], v[66:67], v[72:73]
	v_cvt_pk_bf16_f32 v72, v32, v33
	v_mov_b32_e32 v32, v94
	v_mov_b32_e32 v33, v94
	v_pk_mul_f32 v[32:33], v[42:43], v[32:33]
	v_mov_b32_dpp v42, v40 row_ror:1 row_mask:0xf bank_mask:0xf
	v_mov_b32_dpp v66, v40 row_ror:2 row_mask:0xf bank_mask:0xf
	v_mov_b32_dpp v43, v41 row_ror:1 row_mask:0xf bank_mask:0xf
	v_mov_b32_dpp v67, v41 row_ror:2 row_mask:0xf bank_mask:0xf
	v_mov_b32_dpp v68, v32 row_ror:1 row_mask:0xf bank_mask:0xf
	v_mov_b32_dpp v70, v32 row_ror:2 row_mask:0xf bank_mask:0xf
	v_mov_b32_dpp v69, v33 row_ror:1 row_mask:0xf bank_mask:0xf
	v_mov_b32_dpp v71, v33 row_ror:2 row_mask:0xf bank_mask:0xf
	v_mov_b32_dpp v42, v44 row_shr:1 row_mask:0xf bank_mask:0xf
	v_mov_b32_dpp v66, v44 row_shr:2 row_mask:0xf bank_mask:0xf
	v_mov_b32_dpp v43, v45 row_shr:1 row_mask:0xf bank_mask:0xf
	v_mov_b32_dpp v67, v45 row_shr:2 row_mask:0xf bank_mask:0xf
	v_mov_b32_dpp v68, v46 row_shr:1 row_mask:0xf bank_mask:0xf
	v_mov_b32_dpp v70, v46 row_shr:2 row_mask:0xf bank_mask:0xf
	v_mov_b32_dpp v69, v47 row_shr:1 row_mask:0xf bank_mask:0xf
	v_mov_b32_dpp v71, v47 row_shr:2 row_mask:0xf bank_mask:0xf
	s_waitcnt vmcnt(0)
; __device__ __forceinline__ unsigned cvt_pk_bf16(float lo, float hi) { f32x2_cv v = {lo, hi}; bf16x2_cv b = __builtin_convertvector(v, bf16x2_cv); return __builtin_bit_cast(unsigned, b); }
; __device__ __forceinline__ float siluf_(float x) { return x * __builtin_amdgcn_rcpf(1.0f + __expf(-x)); }
;     __device__ __forceinline__ void operator()(const f32x4 (&acc)[2][2][4][2], const Unit& u, int wr, int wc, int fr, int fq) const {
;     ...
;                         for (int i = 0; i < 4; ++i) {
;                             r1[i] = dpp_mov<0x111>(dpp_mov<0x121>(0.f, prev[i]), cur[i]);
;                             r2[i] = dpp_mov<0x112>(dpp_mov<0x122>(0.f, prev[i]), cur[i]); }
;                         const f32x4 cvv = wb + w2 * cur + w1 * r1 + w0 * r2;
;                         if (bj == 0) {
;                             sg[m].x = cvt_pk_bf16(siluf_(cvv[0]), siluf_(cvv[1])); sg[m].y = cvt_pk_bf16(siluf_(cvv[2]), siluf_(cvv[3]));
;                         } else {
;                             f32x4 h;
;                             h[0] = __uint_as_float(sg[m].x << 16) * cvv[0]; h[1] = __uint_as_float(sg[m].x & 0xffff0000u) * cvv[1];
;                             h[2] = __uint_as_float(sg[m].y << 16) * cvv[2]; h[3] = __uint_as_float(sg[m].y & 0xffff0000u) * cvv[3];
;                             u32x2v w; w.x = cvt_pk_bf16(h[0], h[1]); w.y = cvt_pk_bf16(h[2], h[3]);
;                             *(u32x2v*)(H + (size_t)(rowb + m * 16 + fr) * dff + cg) = w;
	v_pk_fma_f32 v[46:47], v[46:47], v[58:59], v[62:63]
	v_pk_fma_f32 v[44:45], v[44:45], v[56:57], v[60:61]
	v_pk_fma_f32 v[46:47], v[54:55], v[68:69], v[46:47]
	v_pk_fma_f32 v[42:43], v[52:53], v[42:43], v[44:45]
	v_pk_fma_f32 v[44:45], v[50:51], v[70:71], v[46:47]
	v_pk_fma_f32 v[42:43], v[48:49], v[66:67], v[42:43]
	v_lshlrev_b32_e32 v46, 16, v142
	v_and_b32_e32 v47, 0xffff0000, v142
	v_pk_mul_f32 v[42:43], v[42:43], v[46:47]
	v_lshlrev_b32_e32 v46, 16, v108
	v_and_b32_e32 v47, 0xffff0000, v108
	v_or_b32_e32 v73, s39, v236
	v_pk_mul_f32 v[44:45], v[44:45], v[46:47]
	v_cvt_pk_bf16_f32 v42, v42, v43
	v_cvt_pk_bf16_f32 v43, v44, v45
	v_or_b32_e32 v46, 48, v73
	v_mov_b64_e32 v[44:45], s[18:19]
	v_mad_i64_i32 v[46:47], s[50:51], v46, s83, v[44:45]
	v_mov_b32_e32 v93, v92
	v_lshl_add_u64 v[66:67], v[46:47], 0, v[130:131]
	global_store_dwordx2 v[66:67], v[42:43], off
	v_mov_b32_e32 v42, v92
	v_mov_b32_e32 v43, v92
	v_pk_mul_f32 v[38:39], v[38:39], v[42:43]
	v_pk_mul_f32 v[36:37], v[36:37], v[92:93]
	s_nop 1
	v_mov_b32_dpp v42, v36 row_ror:1 row_mask:0xf bank_mask:0xf
	v_mov_b32_dpp v46, v36 row_ror:2 row_mask:0xf bank_mask:0xf
	v_mov_b32_dpp v43, v37 row_ror:1 row_mask:0xf bank_mask:0xf
	v_mov_b32_dpp v47, v37 row_ror:2 row_mask:0xf bank_mask:0xf
	v_mov_b32_dpp v42, v40 row_shr:1 row_mask:0xf bank_mask:0xf
	v_mov_b32_dpp v46, v40 row_shr:2 row_mask:0xf bank_mask:0xf
	v_mov_b32_dpp v43, v41 row_shr:1 row_mask:0xf bank_mask:0xf
	v_mov_b32_dpp v47, v41 row_shr:2 row_mask:0xf bank_mask:0xf
	v_mov_b32_dpp v68, v38 row_ror:1 row_mask:0xf bank_mask:0xf
	v_mov_b32_dpp v70, v38 row_ror:2 row_mask:0xf bank_mask:0xf
	v_mov_b32_dpp v69, v39 row_ror:1 row_mask:0xf bank_mask:0xf
	v_mov_b32_dpp v71, v39 row_ror:2 row_mask:0xf bank_mask:0xf
	v_pk_fma_f32 v[40:41], v[40:41], v[56:57], v[60:61]
	v_mov_b32_dpp v68, v32 row_shr:1 row_mask:0xf bank_mask:0xf
	v_mov_b32_dpp v70, v32 row_shr:2 row_mask:0xf bank_mask:0xf
	v_mov_b32_dpp v69, v33 row_shr:1 row_mask:0xf bank_mask:0xf
	v_mov_b32_dpp v71, v33 row_shr:2 row_mask:0xf bank_mask:0xf
	v_pk_fma_f32 v[32:33], v[32:33], v[58:59], v[62:63]
	v_pk_fma_f32 v[40:41], v[52:53], v[42:43], v[40:41]
	v_pk_fma_f32 v[32:33], v[54:55], v[68:69], v[32:33]
	v_pk_fma_f32 v[40:41], v[48:49], v[46:47], v[40:41]
	v_lshlrev_b32_e32 v42, 16, v109
	v_and_b32_e32 v43, 0xffff0000, v109
	v_pk_fma_f32 v[32:33], v[50:51], v[70:71], v[32:33]
	v_pk_mul_f32 v[40:41], v[40:41], v[42:43]
	v_lshlrev_b32_e32 v42, 16, v102
	v_and_b32_e32 v43, 0xffff0000, v102
	v_pk_mul_f32 v[32:33], v[32:33], v[42:43]
	v_cvt_pk_bf16_f32 v40, v40, v41
	v_cvt_pk_bf16_f32 v41, v32, v33
	v_or_b32_e32 v32, 32, v73
	v_mad_i64_i32 v[32:33], s[50:51], v32, s83, v[44:45]
	v_lshl_add_u64 v[68:69], v[32:33], 0, v[130:131]
	global_store_dwordx2 v[68:69], v[40:41], off
	v_mov_b32_e32 v32, v90
	v_mov_b32_e32 v33, v90
	v_pk_mul_f32 v[34:35], v[34:35], v[32:33]
	v_mov_b32_dpp v40, v64 row_ror:1 row_mask:0xf bank_mask:0xf
	v_mov_b32_dpp v42, v64 row_ror:2 row_mask:0xf bank_mask:0xf
	v_mov_b32_dpp v41, v65 row_ror:1 row_mask:0xf bank_mask:0xf
	v_mov_b32_dpp v43, v65 row_ror:2 row_mask:0xf bank_mask:0xf
	v_mov_b32_dpp v40, v36 row_shr:1 row_mask:0xf bank_mask:0xf
	v_mov_b32_dpp v42, v36 row_shr:2 row_mask:0xf bank_mask:0xf
	v_mov_b32_dpp v41, v37 row_shr:1 row_mask:0xf bank_mask:0xf
	v_mov_b32_dpp v43, v37 row_shr:2 row_mask:0xf bank_mask:0xf
	v_mov_b32_dpp v46, v34 row_ror:1 row_mask:0xf bank_mask:0xf
	v_mov_b32_dpp v70, v34 row_ror:2 row_mask:0xf bank_mask:0xf
	v_mov_b32_dpp v47, v35 row_ror:1 row_mask:0xf bank_mask:0xf
	v_mov_b32_dpp v71, v35 row_ror:2 row_mask:0xf bank_mask:0xf
	v_pk_fma_f32 v[36:37], v[36:37], v[56:57], v[60:61]
	v_mov_b32_dpp v46, v38 row_shr:1 row_mask:0xf bank_mask:0xf
	v_mov_b32_dpp v70, v38 row_shr:2 row_mask:0xf bank_mask:0xf
	v_mov_b32_dpp v47, v39 row_shr:1 row_mask:0xf bank_mask:0xf
	v_mov_b32_dpp v71, v39 row_shr:2 row_mask:0xf bank_mask:0xf
	v_pk_fma_f32 v[38:39], v[38:39], v[58:59], v[62:63]
	v_pk_fma_f32 v[36:37], v[52:53], v[40:41], v[36:37]
	v_pk_fma_f32 v[38:39], v[54:55], v[46:47], v[38:39]
	v_pk_fma_f32 v[36:37], v[48:49], v[42:43], v[36:37]
	v_lshlrev_b32_e32 v40, 16, v86
	v_and_b32_e32 v41, 0xffff0000, v86
	v_pk_fma_f32 v[38:39], v[50:51], v[70:71], v[38:39]
	v_pk_mul_f32 v[36:37], v[36:37], v[40:41]
	v_lshlrev_b32_e32 v40, 16, v74
	v_and_b32_e32 v41, 0xffff0000, v74
	v_pk_mul_f32 v[38:39], v[38:39], v[40:41]
	v_cvt_pk_bf16_f32 v36, v36, v37
	v_cvt_pk_bf16_f32 v37, v38, v39
	v_or_b32_e32 v38, 16, v73
	v_mad_i64_i32 v[38:39], s[50:51], v38, s83, v[44:45]
	v_lshl_add_u64 v[70:71], v[38:39], 0, v[130:131]
	global_store_dwordx2 v[70:71], v[36:37], off
	v_mov_b32_e32 v37, 0
	v_mov_b32_e32 v41, 0
	v_pk_fma_f32 v[46:47], v[64:65], v[56:57], v[60:61]
	v_mov_b32_dpp v37, v37 row_ror:1 row_mask:0xf bank_mask:0xf
	v_mov_b32_dpp v41, v41 row_ror:2 row_mask:0xf bank_mask:0xf
	v_mov_b32_e32 v38, v37
	v_mov_b32_e32 v39, v37
	v_mov_b32_e32 v36, v37
	v_mov_b32_e32 v40, v41
	v_mov_b32_dpp v38, v64 row_shr:1 row_mask:0xf bank_mask:0xf
	v_mov_b32_e32 v42, v41
	v_mov_b32_dpp v39, v65 row_shr:1 row_mask:0xf bank_mask:0xf
	v_mov_b32_e32 v43, v41
	v_mov_b32_dpp v36, v34 row_shr:1 row_mask:0xf bank_mask:0xf
	v_mov_b32_dpp v40, v34 row_shr:2 row_mask:0xf bank_mask:0xf
	v_mov_b32_dpp v37, v35 row_shr:1 row_mask:0xf bank_mask:0xf
	v_mov_b32_dpp v41, v35 row_shr:2 row_mask:0xf bank_mask:0xf
	v_pk_fma_f32 v[34:35], v[34:35], v[58:59], v[62:63]
	v_mov_b32_dpp v42, v64 row_shr:2 row_mask:0xf bank_mask:0xf
	v_mov_b32_dpp v43, v65 row_shr:2 row_mask:0xf bank_mask:0xf
	v_pk_fma_f32 v[34:35], v[54:55], v[36:37], v[34:35]
	v_pk_fma_f32 v[36:37], v[52:53], v[38:39], v[46:47]
	v_lshlrev_b32_e32 v38, 16, v75
	v_pk_fma_f32 v[36:37], v[48:49], v[42:43], v[36:37]
	v_and_b32_e32 v39, 0xffff0000, v75
	v_pk_fma_f32 v[34:35], v[50:51], v[40:41], v[34:35]
	v_pk_mul_f32 v[36:37], v[36:37], v[38:39]
	v_lshlrev_b32_e32 v38, 16, v72
	v_and_b32_e32 v39, 0xffff0000, v72
	v_pk_mul_f32 v[34:35], v[34:35], v[38:39]
	v_cvt_pk_bf16_f32 v36, v36, v37
	v_cvt_pk_bf16_f32 v37, v34, v35
	v_mad_i64_i32 v[34:35], s[50:51], v73, s83, v[44:45]
	v_lshl_add_u64 v[60:61], v[34:35], 0, v[130:131]
	global_store_dwordx2 v[60:61], v[36:37], off
	global_load_dwordx4 v[36:39], v[124:125], off
	global_load_dwordx4 v[40:43], v[126:127], off
	global_load_dwordx4 v[44:47], v[128:129], off
	global_load_dwordx4 v[48:51], v[132:133], off
	v_pk_mul_f32 v[56:57], v[16:17], v[90:91]
	s_and_saveexec_b64 s[50:51], s[8:9]
	s_cbranch_execz .LBB0_2106
	v_mov_b64_e32 v[16:17], s[20:21]
	v_mad_i64_i32 v[16:17], s[54:55], v153, s81, v[16:17]
	v_pk_mul_f32 v[58:59], v[18:19], v[32:33]
	v_lshl_add_u64 v[16:17], v[170:171], 2, v[16:17]
	global_store_dwordx4 v[16:17], v[56:59], off offset:16

;     __device__ __forceinline__ void operator()(const f32x4 (&acc)[2][2][4][2], const Unit& u, int wr, int wc, int fr, int fq) const {
;     ...
;                     const f32x4 w0 = *(const f32x4*)(cw + col), w1 = *(const f32x4*)(cw + 2 * dff + col), w2 = *(const f32x4*)(cw + 4 * dff + col), wb = *(const f32x4*)(cb + col);
;                     if (fr < 2) *(f32x4*)(RB + ((size_t)(blk * 4 + fr) * 2 + bj) * dff + cg) = acc[ai][bj][0][n] * rs[0];
;                     if (fr >= 14) *(f32x4*)(RB + ((size_t)(blk * 4 + fr - 12) * 2 + bj) * dff + cg) = acc[ai][bj][3][n] * rs[3];
; #pragma unroll
;                     for (int m = 3; m >= 0; --m) {
;                         const f32x4 cur = acc[ai][bj][m][n] * rs[m];
;                         f32x4 prev = zero4;
;                         if (m > 0) prev = acc[ai][bj][m - 1][n] * rs[m - 1];
;                         f32x4 r1, r2;
; #pragma unroll
;                         for (int i = 0; i < 4; ++i) {
;                             r1[i] = dpp_mov<0x111>(dpp_mov<0x121>(0.f, prev[i]), cur[i]);
;                             r2[i] = dpp_mov<0x112>(dpp_mov<0x122>(0.f, prev[i]), cur[i]); }
.LBB0_2108:
	s_or_b64 exec, exec, s[50:51]
	v_mov_b32_e32 v34, v94
	v_mov_b32_e32 v35, v94
	v_pk_mul_f32 v[74:75], v[26:27], v[34:35]
	v_pk_mul_f32 v[76:77], v[24:25], v[94:95]
	s_nop 1
	v_mov_b32_dpp v62, v76 row_ror:1 row_mask:0xf bank_mask:0xf
	v_mov_b32_dpp v58, v76 row_ror:2 row_mask:0xf bank_mask:0xf
	v_mov_b32_dpp v63, v77 row_ror:1 row_mask:0xf bank_mask:0xf
	v_mov_b32_dpp v59, v77 row_ror:2 row_mask:0xf bank_mask:0xf
	v_mov_b32_dpp v72, v74 row_ror:1 row_mask:0xf bank_mask:0xf
	v_mov_b32_dpp v64, v74 row_ror:2 row_mask:0xf bank_mask:0xf
	v_mov_b32_dpp v73, v75 row_ror:1 row_mask:0xf bank_mask:0xf
	v_mov_b32_dpp v65, v75 row_ror:2 row_mask:0xf bank_mask:0xf
	v_lshl_add_u64 v[16:17], v[172:173], 0, s[36:37]
	v_lshl_add_u64 v[28:29], v[174:175], 0, s[36:37]
	v_lshl_add_u64 v[30:31], v[176:177], 0, s[36:37]
	v_lshl_add_u64 v[32:33], v[178:179], 0, s[36:37]
	v_mov_b32_dpp v62, v52 row_shr:1 row_mask:0xf bank_mask:0xf
	v_mov_b32_dpp v58, v52 row_shr:2 row_mask:0xf bank_mask:0xf
	v_mov_b32_dpp v63, v53 row_shr:1 row_mask:0xf bank_mask:0xf
	v_mov_b32_dpp v59, v53 row_shr:2 row_mask:0xf bank_mask:0xf
	v_mov_b32_dpp v72, v54 row_shr:1 row_mask:0xf bank_mask:0xf
	v_mov_b32_dpp v64, v54 row_shr:2 row_mask:0xf bank_mask:0xf
	v_mov_b32_dpp v73, v55 row_shr:1 row_mask:0xf bank_mask:0xf
	v_mov_b32_dpp v65, v55 row_shr:2 row_mask:0xf bank_mask:0xf
	v_mov_b32_e32 v24, v92
	v_mov_b32_e32 v25, v92
	v_pk_mul_f32 v[86:87], v[22:23], v[24:25]
	v_pk_mul_f32 v[88:89], v[20:21], v[92:93]
	s_nop 1
	v_mov_b32_dpp v80, v88 row_ror:1 row_mask:0xf bank_mask:0xf
	v_mov_b32_dpp v78, v88 row_ror:2 row_mask:0xf bank_mask:0xf
	v_mov_b32_dpp v81, v89 row_ror:1 row_mask:0xf bank_mask:0xf
	v_mov_b32_dpp v79, v89 row_ror:2 row_mask:0xf bank_mask:0xf
	v_mov_b32_dpp v84, v86 row_ror:1 row_mask:0xf bank_mask:0xf
	v_mov_b32_dpp v82, v86 row_ror:2 row_mask:0xf bank_mask:0xf
	v_mov_b32_dpp v85, v87 row_ror:1 row_mask:0xf bank_mask:0xf
	v_mov_b32_dpp v83, v87 row_ror:2 row_mask:0xf bank_mask:0xf
	v_mov_b32_dpp v80, v76 row_shr:1 row_mask:0xf bank_mask:0xf
	v_mov_b32_dpp v78, v76 row_shr:2 row_mask:0xf bank_mask:0xf
	v_mov_b32_dpp v81, v77 row_shr:1 row_mask:0xf bank_mask:0xf
	v_mov_b32_dpp v79, v77 row_shr:2 row_mask:0xf bank_mask:0xf
	v_mov_b32_dpp v84, v74 row_shr:1 row_mask:0xf bank_mask:0xf
	v_mov_b32_dpp v82, v74 row_shr:2 row_mask:0xf bank_mask:0xf
	v_mov_b32_dpp v85, v75 row_shr:1 row_mask:0xf bank_mask:0xf
	v_mov_b32_dpp v83, v75 row_shr:2 row_mask:0xf bank_mask:0xf
	v_mov_b32_e32 v34, v90
	v_mov_b32_e32 v35, v90
	v_pk_mul_f32 v[106:107], v[18:19], v[34:35]
	v_mov_b32_dpp v100, v56 row_ror:1 row_mask:0xf bank_mask:0xf
	v_mov_b32_dpp v98, v56 row_ror:2 row_mask:0xf bank_mask:0xf
	v_mov_b32_dpp v101, v57 row_ror:1 row_mask:0xf bank_mask:0xf
	v_mov_b32_dpp v99, v57 row_ror:2 row_mask:0xf bank_mask:0xf
	v_mov_b32_dpp v104, v106 row_ror:1 row_mask:0xf bank_mask:0xf
	v_mov_b32_dpp v102, v106 row_ror:2 row_mask:0xf bank_mask:0xf
	v_mov_b32_dpp v105, v107 row_ror:1 row_mask:0xf bank_mask:0xf
	v_mov_b32_dpp v103, v107 row_ror:2 row_mask:0xf bank_mask:0xf
	v_mov_b32_dpp v100, v88 row_shr:1 row_mask:0xf bank_mask:0xf
	v_mov_b32_dpp v98, v88 row_shr:2 row_mask:0xf bank_mask:0xf
	v_mov_b32_dpp v101, v89 row_shr:1 row_mask:0xf bank_mask:0xf
	v_mov_b32_dpp v99, v89 row_shr:2 row_mask:0xf bank_mask:0xf
	v_mov_b32_dpp v104, v86 row_shr:1 row_mask:0xf bank_mask:0xf
	v_mov_b32_dpp v102, v86 row_shr:2 row_mask:0xf bank_mask:0xf
	v_mov_b32_dpp v105, v87 row_shr:1 row_mask:0xf bank_mask:0xf
	v_mov_b32_dpp v103, v87 row_shr:2 row_mask:0xf bank_mask:0xf
	v_mov_b32_e32 v115, 0
	v_mov_b32_e32 v111, 0
	s_nop 0
	v_mov_b32_dpp v115, v115 row_ror:1 row_mask:0xf bank_mask:0xf
	v_mov_b32_dpp v111, v111 row_ror:2 row_mask:0xf bank_mask:0xf
	v_mov_b32_e32 v112, v115
	v_mov_b32_e32 v108, v111
	v_mov_b32_e32 v113, v115
	v_mov_b32_e32 v109, v111
	v_mov_b32_e32 v114, v115
	v_mov_b32_e32 v110, v111
	v_mov_b32_dpp v112, v56 row_shr:1 row_mask:0xf bank_mask:0xf
	v_mov_b32_dpp v108, v56 row_shr:2 row_mask:0xf bank_mask:0xf
	v_mov_b32_dpp v113, v57 row_shr:1 row_mask:0xf bank_mask:0xf
	v_mov_b32_dpp v109, v57 row_shr:2 row_mask:0xf bank_mask:0xf
	v_mov_b32_dpp v114, v106 row_shr:1 row_mask:0xf bank_mask:0xf
	v_mov_b32_dpp v110, v106 row_shr:2 row_mask:0xf bank_mask:0xf
	v_mov_b32_dpp v115, v107 row_shr:1 row_mask:0xf bank_mask:0xf
	v_mov_b32_dpp v111, v107 row_shr:2 row_mask:0xf bank_mask:0xf
	global_load_dwordx4 v[16:19], v[16:17], off
	s_nop 0
	global_load_dwordx4 v[20:23], v[28:29], off
	global_load_dwordx4 v[24:27], v[30:31], off
	s_nop 0
	global_load_dwordx4 v[28:31], v[32:33], off
	v_pk_mul_f32 v[32:33], v[0:1], v[90:91]
	s_and_saveexec_b64 s[50:51], s[8:9]
	s_cbranch_execz .LBB0_2110
	v_mov_b64_e32 v[0:1], s[20:21]
	v_mad_i64_i32 v[0:1], s[54:55], v153, s81, v[0:1]
	v_lshl_add_u64 v[0:1], v[122:123], 2, v[0:1]
	v_add_co_u32_e32 v0, vcc, 0x5000, v0
	v_pk_mul_f32 v[34:35], v[2:3], v[34:35]
	s_nop 0
	v_addc_co_u32_e32 v1, vcc, 0, v1, vcc
	global_store_dwordx4 v[0:1], v[32:35], off offset:2048

; __device__ __forceinline__ unsigned cvt_pk_bf16(float lo, float hi) { f32x2_cv v = {lo, hi}; bf16x2_cv b = __builtin_convertvector(v, bf16x2_cv); return __builtin_bit_cast(unsigned, b); }
; __device__ __forceinline__ float siluf_(float x) { return x * __builtin_amdgcn_rcpf(1.0f + __expf(-x)); }
;     __device__ __forceinline__ void operator()(const f32x4 (&acc)[2][2][4][2], const Unit& u, int wr, int wc, int fr, int fq) const {
;     ...
;                     for (int m = 3; m >= 0; --m) {
;                         const f32x4 cur = acc[ai][bj][m][n] * rs[m];
;                         f32x4 prev = zero4;
;                         if (m > 0) prev = acc[ai][bj][m - 1][n] * rs[m - 1];
;                         f32x4 r1, r2;
; #pragma unroll
;                         for (int i = 0; i < 4; ++i) {
;                             r1[i] = dpp_mov<0x111>(dpp_mov<0x121>(0.f, prev[i]), cur[i]);
;                             r2[i] = dpp_mov<0x112>(dpp_mov<0x122>(0.f, prev[i]), cur[i]); }
;                         const f32x4 cvv = wb + w2 * cur + w1 * r1 + w0 * r2;
;                         if (bj == 0) {
;                             sg[m].x = cvt_pk_bf16(siluf_(cvv[0]), siluf_(cvv[1])); sg[m].y = cvt_pk_bf16(siluf_(cvv[2]), siluf_(cvv[3]));
;                         } else {
;                             f32x4 h;
;                             h[0] = __uint_as_float(sg[m].x << 16) * cvv[0]; h[1] = __uint_as_float(sg[m].x & 0xffff0000u) * cvv[1];
;                             h[2] = __uint_as_float(sg[m].y << 16) * cvv[2]; h[3] = __uint_as_float(sg[m].y & 0xffff0000u) * cvv[3];
;                             u32x2v w; w.x = cvt_pk_bf16(h[0], h[1]); w.y = cvt_pk_bf16(h[2], h[3]);
;                             *(u32x2v*)(H + (size_t)(rowb + m * 16 + fr) * dff + cg) = w;
.LBB0_2112:
	s_or_b64 exec, exec, s[50:51]
	s_waitcnt vmcnt(4)
	v_pk_fma_f32 v[0:1], v[106:107], v[46:47], v[50:51]
	v_pk_fma_f32 v[34:35], v[56:57], v[44:45], v[48:49]
	v_pk_fma_f32 v[0:1], v[42:43], v[114:115], v[0:1]
	v_pk_fma_f32 v[34:35], v[40:41], v[112:113], v[34:35]
	v_pk_fma_f32 v[0:1], v[38:39], v[110:111], v[0:1]
	v_pk_fma_f32 v[34:35], v[36:37], v[108:109], v[34:35]
	v_mul_f32_e32 v56, 0xbfb8aa3b, v0
	v_mul_f32_e32 v57, 0xbfb8aa3b, v1
	v_mul_f32_e32 v91, 0xbfb8aa3b, v34
	v_exp_f32_e32 v56, v56
	v_exp_f32_e32 v57, v57
	v_exp_f32_e32 v91, v91
	v_mul_f32_e32 v96, 0xbfb8aa3b, v35
	v_exp_f32_e32 v97, v96
	v_add_f32_e32 v56, 1.0, v56
	v_add_f32_e32 v57, 1.0, v57
	v_add_f32_e32 v91, 1.0, v91
	v_rcp_f32_e32 v56, v56
	v_rcp_f32_e32 v57, v57
	v_rcp_f32_e32 v96, v91
	v_add_f32_e32 v91, 1.0, v97
	v_rcp_f32_e32 v97, v91
	v_pk_mul_f32 v[0:1], v[0:1], v[56:57]
	v_pk_fma_f32 v[56:57], v[88:89], v[44:45], v[48:49]
	v_cvt_pk_bf16_f32 v106, v0, v1
	v_pk_mul_f32 v[0:1], v[34:35], v[96:97]
	v_pk_fma_f32 v[34:35], v[86:87], v[46:47], v[50:51]
	v_pk_fma_f32 v[56:57], v[40:41], v[100:101], v[56:57]
	v_pk_fma_f32 v[34:35], v[42:43], v[104:105], v[34:35]
	v_pk_fma_f32 v[56:57], v[36:37], v[98:99], v[56:57]
	v_pk_fma_f32 v[34:35], v[38:39], v[102:103], v[34:35]
	v_cvt_pk_bf16_f32 v96, v0, v1
	v_mul_f32_e32 v86, 0xbfb8aa3b, v34
	v_mul_f32_e32 v87, 0xbfb8aa3b, v35
	v_exp_f32_e32 v86, v86
	v_exp_f32_e32 v87, v87
	v_mul_f32_e32 v88, 0xbfb8aa3b, v56
	v_mul_f32_e32 v89, 0xbfb8aa3b, v57
	v_add_f32_e32 v86, 1.0, v86
	v_add_f32_e32 v87, 1.0, v87
	v_rcp_f32_e32 v86, v86
	v_rcp_f32_e32 v87, v87
	v_exp_f32_e32 v88, v88
	v_exp_f32_e32 v89, v89
	v_pk_mul_f32 v[8:9], v[8:9], v[94:95]
	v_pk_mul_f32 v[0:1], v[34:35], v[86:87]
	v_pk_fma_f32 v[34:35], v[74:75], v[46:47], v[50:51]
	v_add_f32_e32 v88, 1.0, v88
	v_pk_fma_f32 v[34:35], v[42:43], v[84:85], v[34:35]
	v_add_f32_e32 v89, 1.0, v89
	v_pk_fma_f32 v[34:35], v[38:39], v[82:83], v[34:35]
	v_rcp_f32_e32 v88, v88
	v_mul_f32_e32 v74, 0xbfb8aa3b, v34
	v_mul_f32_e32 v75, 0xbfb8aa3b, v35
	v_exp_f32_e32 v74, v74
	v_exp_f32_e32 v75, v75
	v_rcp_f32_e32 v89, v89
	v_cvt_pk_bf16_f32 v86, v0, v1
	v_add_f32_e32 v74, 1.0, v74
	v_add_f32_e32 v75, 1.0, v75
	v_rcp_f32_e32 v74, v74
	v_rcp_f32_e32 v75, v75
	v_pk_mul_f32 v[0:1], v[56:57], v[88:89]
	v_pk_fma_f32 v[56:57], v[76:77], v[44:45], v[48:49]
	v_pk_fma_f32 v[44:45], v[52:53], v[44:45], v[48:49]
	v_pk_fma_f32 v[56:57], v[40:41], v[80:81], v[56:57]
	v_pk_fma_f32 v[40:41], v[40:41], v[62:63], v[44:45]
	v_pk_fma_f32 v[56:57], v[36:37], v[78:79], v[56:57]
	v_cvt_pk_bf16_f32 v78, v0, v1
	v_pk_mul_f32 v[0:1], v[34:35], v[74:75]
	v_pk_fma_f32 v[34:35], v[54:55], v[46:47], v[50:51]
	v_mul_f32_e32 v76, 0xbfb8aa3b, v56
	v_pk_fma_f32 v[34:35], v[42:43], v[72:73], v[34:35]
	v_mul_f32_e32 v77, 0xbfb8aa3b, v57
	v_pk_fma_f32 v[34:35], v[38:39], v[64:65], v[34:35]
	v_exp_f32_e32 v76, v76
	v_exp_f32_e32 v77, v77
	v_mul_f32_e32 v38, 0xbfb8aa3b, v34
	v_mul_f32_e32 v39, 0xbfb8aa3b, v35
	v_pk_fma_f32 v[36:37], v[36:37], v[58:59], v[40:41]
	v_exp_f32_e32 v38, v38
	v_exp_f32_e32 v39, v39
	v_mul_f32_e32 v40, 0xbfb8aa3b, v36
	v_mul_f32_e32 v41, 0xbfb8aa3b, v37
	v_exp_f32_e32 v40, v40
	v_exp_f32_e32 v41, v41
	v_add_f32_e32 v76, 1.0, v76
	v_add_f32_e32 v77, 1.0, v77
	v_rcp_f32_e32 v76, v76
	v_rcp_f32_e32 v77, v77
	v_add_f32_e32 v38, 1.0, v38
	v_add_f32_e32 v39, 1.0, v39
	v_rcp_f32_e32 v38, v38
	v_rcp_f32_e32 v39, v39
	v_add_f32_e32 v40, 1.0, v40
	v_add_f32_e32 v41, 1.0, v41
	v_rcp_f32_e32 v40, v40
	v_rcp_f32_e32 v41, v41
	v_cvt_pk_bf16_f32 v74, v0, v1
	v_pk_mul_f32 v[0:1], v[56:57], v[76:77]
	s_nop 0
	v_cvt_pk_bf16_f32 v42, v0, v1
	v_pk_mul_f32 v[0:1], v[34:35], v[38:39]
	v_cvt_pk_bf16_f32 v43, v0, v1
	v_pk_mul_f32 v[0:1], v[36:37], v[40:41]
	v_cvt_pk_bf16_f32 v40, v0, v1
	v_mov_b32_e32 v0, v94
	v_mov_b32_e32 v1, v94
	v_pk_mul_f32 v[0:1], v[10:11], v[0:1]
	v_mov_b32_dpp v10, v8 row_ror:1 row_mask:0xf bank_mask:0xf
	v_mov_b32_dpp v34, v8 row_ror:2 row_mask:0xf bank_mask:0xf
	v_mov_b32_dpp v11, v9 row_ror:1 row_mask:0xf bank_mask:0xf
	v_mov_b32_dpp v35, v9 row_ror:2 row_mask:0xf bank_mask:0xf
	v_mov_b32_dpp v36, v0 row_ror:1 row_mask:0xf bank_mask:0xf
	v_mov_b32_dpp v38, v0 row_ror:2 row_mask:0xf bank_mask:0xf
	v_mov_b32_dpp v37, v1 row_ror:1 row_mask:0xf bank_mask:0xf
	v_mov_b32_dpp v39, v1 row_ror:2 row_mask:0xf bank_mask:0xf
	v_mov_b32_dpp v10, v12 row_shr:1 row_mask:0xf bank_mask:0xf
	v_mov_b32_dpp v34, v12 row_shr:2 row_mask:0xf bank_mask:0xf
	v_mov_b32_dpp v11, v13 row_shr:1 row_mask:0xf bank_mask:0xf
	v_mov_b32_dpp v35, v13 row_shr:2 row_mask:0xf bank_mask:0xf
	v_mov_b32_dpp v36, v14 row_shr:1 row_mask:0xf bank_mask:0xf
	v_mov_b32_dpp v38, v14 row_shr:2 row_mask:0xf bank_mask:0xf
	v_mov_b32_dpp v37, v15 row_shr:1 row_mask:0xf bank_mask:0xf
	v_mov_b32_dpp v39, v15 row_shr:2 row_mask:0xf bank_mask:0xf
	s_waitcnt vmcnt(0)
; __device__ __forceinline__ float siluf_(float x) { return x * __builtin_amdgcn_rcpf(1.0f + __expf(-x)); }
; #define PG8_BAR __builtin_amdgcn_s_barrier()
;     __device__ __forceinline__ void operator()(const f32x4 (&acc)[2][2][4][2], const Unit& u, int wr, int wc, int fr, int fq) const {
;     ...
;                         const f32x4 cur = acc[ai][bj][m][n] * rs[m];
;                         f32x4 prev = zero4;
;                         if (m > 0) prev = acc[ai][bj][m - 1][n] * rs[m - 1];
;                         f32x4 r1, r2;
; #pragma unroll
;                         for (int i = 0; i < 4; ++i) {
;                             r1[i] = dpp_mov<0x111>(dpp_mov<0x121>(0.f, prev[i]), cur[i]);
;                             r2[i] = dpp_mov<0x112>(dpp_mov<0x122>(0.f, prev[i]), cur[i]); }
;                         const f32x4 cvv = wb + w2 * cur + w1 * r1 + w0 * r2;
;                         if (bj == 0) {
;                             sg[m].x = cvt_pk_bf16(siluf_(cvv[0]), siluf_(cvv[1])); sg[m].y = cvt_pk_bf16(siluf_(cvv[2]), siluf_(cvv[3]));
;                         } else {
;                             f32x4 h;
;                             h[0] = __uint_as_float(sg[m].x << 16) * cvv[0]; h[1] = __uint_as_float(sg[m].x & 0xffff0000u) * cvv[1];
;                             h[2] = __uint_as_float(sg[m].y << 16) * cvv[2]; h[3] = __uint_as_float(sg[m].y & 0xffff0000u) * cvv[3];
;                             u32x2v w; w.x = cvt_pk_bf16(h[0], h[1]); w.y = cvt_pk_bf16(h[2], h[3]);
;                             *(u32x2v*)(H + (size_t)(rowb + m * 16 + fr) * dff + cg) = w;
;                         }
; template <class Epi, class Sched, bool ALIGN_EPI = false, bool SP2 = false>
; __device__ __forceinline__ void gemm_phase(PG8_LAS unsigned char* lds, const Gemm g, const Sched& S, const Epi& E) {
;     ...
;         if constexpr (ALIGN_EPI) { if (wr == 0) PG8_BAR; }
;         if constexpr (!Epi::AFTER_DRAIN) { E(acc, cur, wr, wc, fr, fq); S.done(cur); }
;         if (!has_next) break;
; #pragma unroll
;         for (int a = 0; a < 2; ++a)
; #pragma unroll
;             for (int b = 0; b < 2; ++b)
; #pragma unroll
;                 for (int m = 0; m < 4; ++m)
; #pragma unroll
;                     for (int n = 0; n < 2; ++n) acc[a][b][m][n] = (f32x4){0.f, 0.f, 0.f, 0.f};
;         cur = nxt; cA = nA; cB = nB; ++ui;
;         if constexpr (ALIGN_EPI) { if (wr == 1) PG8_BAR; }
	v_pk_fma_f32 v[14:15], v[14:15], v[26:27], v[30:31]
	v_pk_fma_f32 v[12:13], v[12:13], v[24:25], v[28:29]
	v_pk_fma_f32 v[14:15], v[22:23], v[36:37], v[14:15]
	v_pk_fma_f32 v[10:11], v[20:21], v[10:11], v[12:13]
	v_pk_fma_f32 v[12:13], v[18:19], v[38:39], v[14:15]
	v_pk_fma_f32 v[10:11], v[16:17], v[34:35], v[10:11]
	v_lshlrev_b32_e32 v14, 16, v40
	v_and_b32_e32 v15, 0xffff0000, v40
	v_pk_mul_f32 v[10:11], v[10:11], v[14:15]
	v_lshlrev_b32_e32 v14, 16, v43
	v_and_b32_e32 v15, 0xffff0000, v43
	v_pk_mul_f32 v[12:13], v[12:13], v[14:15]
	v_cvt_pk_bf16_f32 v10, v10, v11
	v_cvt_pk_bf16_f32 v11, v12, v13
	global_store_dwordx2 v[66:67], v[10:11], off offset:8
	v_mov_b32_e32 v10, v92
	v_mov_b32_e32 v11, v92
	v_pk_mul_f32 v[6:7], v[6:7], v[10:11]
	v_pk_mul_f32 v[4:5], v[4:5], v[92:93]
	s_nop 1
	v_mov_b32_dpp v10, v4 row_ror:1 row_mask:0xf bank_mask:0xf
	v_mov_b32_dpp v12, v4 row_ror:2 row_mask:0xf bank_mask:0xf
	v_mov_b32_dpp v11, v5 row_ror:1 row_mask:0xf bank_mask:0xf
	v_mov_b32_dpp v13, v5 row_ror:2 row_mask:0xf bank_mask:0xf
	v_mov_b32_dpp v10, v8 row_shr:1 row_mask:0xf bank_mask:0xf
	v_mov_b32_dpp v12, v8 row_shr:2 row_mask:0xf bank_mask:0xf
	v_mov_b32_dpp v11, v9 row_shr:1 row_mask:0xf bank_mask:0xf
	v_mov_b32_dpp v13, v9 row_shr:2 row_mask:0xf bank_mask:0xf
	v_mov_b32_dpp v14, v6 row_ror:1 row_mask:0xf bank_mask:0xf
	v_mov_b32_dpp v34, v6 row_ror:2 row_mask:0xf bank_mask:0xf
	v_mov_b32_dpp v15, v7 row_ror:1 row_mask:0xf bank_mask:0xf
	v_mov_b32_dpp v35, v7 row_ror:2 row_mask:0xf bank_mask:0xf
	v_pk_fma_f32 v[8:9], v[8:9], v[24:25], v[28:29]
	v_mov_b32_dpp v14, v0 row_shr:1 row_mask:0xf bank_mask:0xf
	v_mov_b32_dpp v34, v0 row_shr:2 row_mask:0xf bank_mask:0xf
	v_mov_b32_dpp v15, v1 row_shr:1 row_mask:0xf bank_mask:0xf
	v_mov_b32_dpp v35, v1 row_shr:2 row_mask:0xf bank_mask:0xf
	v_pk_fma_f32 v[0:1], v[0:1], v[26:27], v[30:31]
	v_pk_fma_f32 v[8:9], v[20:21], v[10:11], v[8:9]
	v_pk_fma_f32 v[0:1], v[22:23], v[14:15], v[0:1]
	v_pk_fma_f32 v[8:9], v[16:17], v[12:13], v[8:9]
	v_lshlrev_b32_e32 v10, 16, v42
	v_and_b32_e32 v11, 0xffff0000, v42
	v_pk_fma_f32 v[0:1], v[18:19], v[34:35], v[0:1]
	v_pk_mul_f32 v[8:9], v[8:9], v[10:11]
	v_lshlrev_b32_e32 v10, 16, v74
	v_and_b32_e32 v11, 0xffff0000, v74
	v_pk_mul_f32 v[0:1], v[0:1], v[10:11]
	v_cvt_pk_bf16_f32 v8, v8, v9
	v_cvt_pk_bf16_f32 v9, v0, v1
	global_store_dwordx2 v[68:69], v[8:9], off offset:8
	v_mov_b32_e32 v91, v90
	v_pk_mul_f32 v[0:1], v[2:3], v[90:91]
	v_mov_b32_dpp v2, v32 row_ror:1 row_mask:0xf bank_mask:0xf
	v_mov_b32_dpp v8, v32 row_ror:2 row_mask:0xf bank_mask:0xf
	v_mov_b32_dpp v3, v33 row_ror:1 row_mask:0xf bank_mask:0xf
	v_mov_b32_dpp v9, v33 row_ror:2 row_mask:0xf bank_mask:0xf
	v_mov_b32_dpp v10, v0 row_ror:1 row_mask:0xf bank_mask:0xf
	v_mov_b32_dpp v12, v0 row_ror:2 row_mask:0xf bank_mask:0xf
	v_mov_b32_dpp v11, v1 row_ror:1 row_mask:0xf bank_mask:0xf
	v_mov_b32_dpp v13, v1 row_ror:2 row_mask:0xf bank_mask:0xf
	v_mov_b32_dpp v2, v4 row_shr:1 row_mask:0xf bank_mask:0xf
	v_mov_b32_dpp v8, v4 row_shr:2 row_mask:0xf bank_mask:0xf
	v_mov_b32_dpp v3, v5 row_shr:1 row_mask:0xf bank_mask:0xf
	v_mov_b32_dpp v9, v5 row_shr:2 row_mask:0xf bank_mask:0xf
	v_mov_b32_dpp v10, v6 row_shr:1 row_mask:0xf bank_mask:0xf
	v_mov_b32_dpp v12, v6 row_shr:2 row_mask:0xf bank_mask:0xf
	v_mov_b32_dpp v11, v7 row_shr:1 row_mask:0xf bank_mask:0xf
	v_mov_b32_dpp v13, v7 row_shr:2 row_mask:0xf bank_mask:0xf
	v_pk_fma_f32 v[6:7], v[6:7], v[26:27], v[30:31]
	v_pk_fma_f32 v[4:5], v[4:5], v[24:25], v[28:29]
	v_pk_fma_f32 v[6:7], v[22:23], v[10:11], v[6:7]
	v_pk_fma_f32 v[2:3], v[20:21], v[2:3], v[4:5]
	v_pk_fma_f32 v[4:5], v[18:19], v[12:13], v[6:7]
	v_pk_fma_f32 v[2:3], v[16:17], v[8:9], v[2:3]
	v_lshlrev_b32_e32 v6, 16, v78
	v_and_b32_e32 v7, 0xffff0000, v78
	v_pk_mul_f32 v[2:3], v[2:3], v[6:7]
	v_lshlrev_b32_e32 v6, 16, v86
	v_and_b32_e32 v7, 0xffff0000, v86
	v_pk_mul_f32 v[4:5], v[4:5], v[6:7]
	v_cvt_pk_bf16_f32 v2, v2, v3
	v_cvt_pk_bf16_f32 v3, v4, v5
	global_store_dwordx2 v[70:71], v[2:3], off offset:8
	v_mov_b32_e32 v3, 0
	v_mov_b32_e32 v7, 0
	v_pk_fma_f32 v[10:11], v[32:33], v[24:25], v[28:29]
	v_mov_b32_dpp v3, v3 row_ror:1 row_mask:0xf bank_mask:0xf
	v_mov_b32_dpp v7, v7 row_ror:2 row_mask:0xf bank_mask:0xf
	v_mov_b32_e32 v4, v3
	v_mov_b32_e32 v5, v3
	v_mov_b32_e32 v2, v3
	v_mov_b32_e32 v6, v7
	v_mov_b32_dpp v4, v32 row_shr:1 row_mask:0xf bank_mask:0xf
	v_mov_b32_e32 v8, v7
	v_mov_b32_dpp v5, v33 row_shr:1 row_mask:0xf bank_mask:0xf
	v_mov_b32_e32 v9, v7
	v_mov_b32_dpp v2, v0 row_shr:1 row_mask:0xf bank_mask:0xf
	v_mov_b32_dpp v6, v0 row_shr:2 row_mask:0xf bank_mask:0xf
	v_mov_b32_dpp v3, v1 row_shr:1 row_mask:0xf bank_mask:0xf
	v_mov_b32_dpp v7, v1 row_shr:2 row_mask:0xf bank_mask:0xf
	v_pk_fma_f32 v[0:1], v[0:1], v[26:27], v[30:31]
	v_mov_b32_dpp v8, v32 row_shr:2 row_mask:0xf bank_mask:0xf
	v_mov_b32_dpp v9, v33 row_shr:2 row_mask:0xf bank_mask:0xf
	v_pk_fma_f32 v[0:1], v[22:23], v[2:3], v[0:1]
	v_pk_fma_f32 v[2:3], v[20:21], v[4:5], v[10:11]
	v_lshlrev_b32_e32 v4, 16, v96
	v_pk_fma_f32 v[2:3], v[16:17], v[8:9], v[2:3]
	v_and_b32_e32 v5, 0xffff0000, v96
	v_pk_fma_f32 v[0:1], v[18:19], v[6:7], v[0:1]
	v_pk_mul_f32 v[2:3], v[2:3], v[4:5]
	v_lshlrev_b32_e32 v4, 16, v106
	v_and_b32_e32 v5, 0xffff0000, v106
	v_pk_mul_f32 v[0:1], v[0:1], v[4:5]
	v_cvt_pk_bf16_f32 v2, v2, v3
	v_cvt_pk_bf16_f32 v3, v0, v1
	global_store_dwordx2 v[60:61], v[2:3], off offset:8
	s_andn2_b64 vcc, exec, s[12:13]
	s_mov_b64 s[12:13], -1
	s_cbranch_vccnz .LBB0_2073
	s_andn2_b64 vcc, exec, s[16:17]
	s_cbranch_vccnz .LBB0_2072
	s_barrier
	s_branch .LBB0_2072

; __device__ __forceinline__ float wave_sum(float v) {
; #pragma unroll
;     for (int o = 1; o < 64; o <<= 1) v += __shfl_xor(v, o);
;     return v;
; __device__ __forceinline__ void final_norm_pass(const Ctx& C, const bf16* XB, const float* g, float* out) {
;     const int gw = C.bid * 8 + C.wave, NGW = C.G * 8;
;     for (int m = gw; m < M; m += NGW) {
;         const v2u* xr = (const v2u*)(XB + (size_t)m * D) + C.lane; f32x4 v[8]; float s = 0.f;
; #pragma unroll
;         for (int j = 0; j < 8; ++j) { const v2u w = xr[64 * j]; v[j] = (f32x4){__uint_as_float(w.x << 16), __uint_as_float(w.x & 0xffff0000u), __uint_as_float(w.y << 16), __uint_as_float(w.y & 0xffff0000u)};
;             s += (v[j][0] * v[j][0] + v[j][1] * v[j][1]) + (v[j][2] * v[j][2] + v[j][3] * v[j][3]); }
;         const float rstd = rsqrtf(wave_sum(s) * (1.0f / D) + EPS);
;         const f32x4* gr = (const f32x4*)g + C.lane; f32x4* o = (f32x4*)(out + (size_t)m * D) + C.lane;
; #pragma unroll
;         for (int j = 0; j < 8; ++j) o[64 * j] = v[j] * rstd * gr[64 * j];
;     }
.LBB0_2444:
	s_or_b64 exec, exec, s[2:3]
	s_waitcnt lgkmcnt(0)
	s_barrier
	v_readlane_b32 s3, v254, 0
	v_readfirstlane_b32 s2, v234
	s_ashr_i32 s2, s2, 6
	s_add_i32 s2, s2, s3
	s_mov_b32 s8, 0
	s_cmpk_gt_i32 s2, 0x3fff
	s_cbranch_scc1 .LBB0_2447
	s_load_dwordx2 s[12:13], s[0:1], 0xb0
	s_load_dwordx4 s[4:7], s[0:1], 0xb8
	v_and_b32_e32 v1, 63, v234
	v_lshlrev_b32_e32 v2, 4, v1
	v_lshlrev_b32_e32 v3, 3, v1
	v_lshlrev_b32_e32 v4, 2, v1
	v_xor_b32_e32 v10, 4, v4
	v_xor_b32_e32 v11, 8, v4
	v_xor_b32_e32 v12, 16, v4
	v_xor_b32_e32 v13, 32, v4
	v_xor_b32_e32 v14, 64, v4
	v_xor_b32_e32 v15, 128, v4
	v_mov_b32_e32 v5, 0x358637bd
	s_waitcnt lgkmcnt(0)
	s_add_u32 s12, s12, 0x1000
	s_addc_u32 s13, s13, 0
	global_load_dwordx4 v[128:131], v2, s[12:13] offset:-4096
	global_load_dwordx4 v[132:135], v2, s[12:13] offset:-3072
	global_load_dwordx4 v[136:139], v2, s[12:13] offset:-2048
	global_load_dwordx4 v[140:143], v2, s[12:13] offset:-1024
	global_load_dwordx4 v[144:147], v2, s[12:13] offset:0
	global_load_dwordx4 v[148:151], v2, s[12:13] offset:1024
	global_load_dwordx4 v[152:155], v2, s[12:13] offset:2048
	global_load_dwordx4 v[156:159], v2, s[12:13] offset:3072
	s_add_u32 s6, s6, 0x26100800
	s_addc_u32 s7, s7, 0
	s_add_u32 s4, s4, 0x1000
	s_addc_u32 s5, s5, 0
	s_lshl_b32 s8, s2, 12
	s_add_u32 s10, s6, s8
	s_addc_u32 s11, s7, 0
	global_load_dwordx2 v[20:21], v3, s[10:11] offset:-2048
	global_load_dwordx2 v[22:23], v3, s[10:11] offset:-1536
	global_load_dwordx2 v[24:25], v3, s[10:11] offset:-1024
	global_load_dwordx2 v[26:27], v3, s[10:11] offset:-512
	global_load_dwordx2 v[28:29], v3, s[10:11] offset:0
	global_load_dwordx2 v[30:31], v3, s[10:11] offset:512
	global_load_dwordx2 v[32:33], v3, s[10:11] offset:1024
	global_load_dwordx2 v[34:35], v3, s[10:11] offset:1536
	s_lshl_b32 s8, s2, 13
	s_add_u32 s14, s4, s8
	s_addc_u32 s15, s5, 0
	s_add_u32 s2, s2, s44
	s_lshl_b32 s8, s2, 12
	s_add_u32 s10, s6, s8
	s_addc_u32 s11, s7, 0
	global_load_dwordx2 v[36:37], v3, s[10:11] offset:-2048
	global_load_dwordx2 v[38:39], v3, s[10:11] offset:-1536
	global_load_dwordx2 v[40:41], v3, s[10:11] offset:-1024
	global_load_dwordx2 v[42:43], v3, s[10:11] offset:-512
	global_load_dwordx2 v[44:45], v3, s[10:11] offset:0
	global_load_dwordx2 v[46:47], v3, s[10:11] offset:512
	global_load_dwordx2 v[48:49], v3, s[10:11] offset:1024
	global_load_dwordx2 v[50:51], v3, s[10:11] offset:1536
	s_waitcnt vmcnt(8)
	v_lshlrev_b32_e32 v64, 16, v20
	v_and_b32_e32 v65, 0xffff0000, v20
	v_lshlrev_b32_e32 v66, 16, v21
	v_and_b32_e32 v67, 0xffff0000, v21
	v_mul_f32_e32 v8, v65, v65
	v_mul_f32_e32 v9, v67, v67
	v_fmac_f32_e32 v8, v64, v64
	v_fmac_f32_e32 v9, v66, v66
	v_add_f32_e32 v17, v8, v9
	v_lshlrev_b32_e32 v68, 16, v22
	v_and_b32_e32 v69, 0xffff0000, v22
	v_lshlrev_b32_e32 v70, 16, v23
	v_and_b32_e32 v71, 0xffff0000, v23
	v_mul_f32_e32 v8, v69, v69
	v_mul_f32_e32 v9, v71, v71
	v_fmac_f32_e32 v8, v68, v68
	v_fmac_f32_e32 v9, v70, v70
	v_add_f32_e32 v8, v8, v9
	v_add_f32_e32 v17, v17, v8
	v_lshlrev_b32_e32 v72, 16, v24
	v_and_b32_e32 v73, 0xffff0000, v24
	v_lshlrev_b32_e32 v74, 16, v25
	v_and_b32_e32 v75, 0xffff0000, v25
	v_mul_f32_e32 v8, v73, v73
	v_mul_f32_e32 v9, v75, v75
	v_fmac_f32_e32 v8, v72, v72
	v_fmac_f32_e32 v9, v74, v74
	v_add_f32_e32 v8, v8, v9
	v_add_f32_e32 v17, v17, v8
	v_lshlrev_b32_e32 v76, 16, v26
	v_and_b32_e32 v77, 0xffff0000, v26
	v_lshlrev_b32_e32 v78, 16, v27
	v_and_b32_e32 v79, 0xffff0000, v27
	v_mul_f32_e32 v8, v77, v77
	v_mul_f32_e32 v9, v79, v79
	v_fmac_f32_e32 v8, v76, v76
	v_fmac_f32_e32 v9, v78, v78
	v_add_f32_e32 v8, v8, v9
	v_add_f32_e32 v17, v17, v8
	v_lshlrev_b32_e32 v80, 16, v28
	v_and_b32_e32 v81, 0xffff0000, v28
	v_lshlrev_b32_e32 v82, 16, v29
	v_and_b32_e32 v83, 0xffff0000, v29
	v_mul_f32_e32 v8, v81, v81
	v_mul_f32_e32 v9, v83, v83
	v_fmac_f32_e32 v8, v80, v80
	v_fmac_f32_e32 v9, v82, v82
	v_add_f32_e32 v8, v8, v9
	v_add_f32_e32 v17, v17, v8
	v_lshlrev_b32_e32 v84, 16, v30
	v_and_b32_e32 v85, 0xffff0000, v30
	v_lshlrev_b32_e32 v86, 16, v31
	v_and_b32_e32 v87, 0xffff0000, v31
	v_mul_f32_e32 v8, v85, v85
	v_mul_f32_e32 v9, v87, v87
	v_fmac_f32_e32 v8, v84, v84
	v_fmac_f32_e32 v9, v86, v86
	v_add_f32_e32 v8, v8, v9
	v_add_f32_e32 v17, v17, v8
	v_lshlrev_b32_e32 v88, 16, v32
	v_and_b32_e32 v89, 0xffff0000, v32
	v_lshlrev_b32_e32 v90, 16, v33
	v_and_b32_e32 v91, 0xffff0000, v33
	v_mul_f32_e32 v8, v89, v89
	v_mul_f32_e32 v9, v91, v91
	v_fmac_f32_e32 v8, v88, v88
	v_fmac_f32_e32 v9, v90, v90
	v_add_f32_e32 v8, v8, v9
	v_add_f32_e32 v17, v17, v8
	v_lshlrev_b32_e32 v92, 16, v34
	v_and_b32_e32 v93, 0xffff0000, v34
	v_lshlrev_b32_e32 v94, 16, v35
	v_and_b32_e32 v95, 0xffff0000, v35
	v_mul_f32_e32 v8, v93, v93
	v_mul_f32_e32 v9, v95, v95
	v_fmac_f32_e32 v8, v92, v92
	v_fmac_f32_e32 v9, v94, v94
	v_add_f32_e32 v8, v8, v9
	v_add_f32_e32 v17, v17, v8
	ds_bpermute_b32 v18, v10, v17
	s_waitcnt lgkmcnt(0)
	v_add_f32_e32 v17, v17, v18
	ds_bpermute_b32 v18, v11, v17
	s_waitcnt lgkmcnt(0)
	v_add_f32_e32 v17, v17, v18
	ds_bpermute_b32 v18, v12, v17
	s_waitcnt lgkmcnt(0)
	v_add_f32_e32 v17, v17, v18
	ds_bpermute_b32 v18, v13, v17
	s_waitcnt lgkmcnt(0)
	v_add_f32_e32 v17, v17, v18
	ds_bpermute_b32 v18, v14, v17
	s_waitcnt lgkmcnt(0)
	v_add_f32_e32 v17, v17, v18
	ds_bpermute_b32 v18, v15, v17
	s_waitcnt lgkmcnt(0)
; __device__ __forceinline__ void final_norm_pass(const Ctx& C, const bf16* XB, const float* g, float* out) {
;     ...
;     for (int m = gw; m < M; m += NGW) {
;         const v2u* xr = (const v2u*)(XB + (size_t)m * D) + C.lane; f32x4 v[8]; float s = 0.f;
; #pragma unroll
;         for (int j = 0; j < 8; ++j) { const v2u w = xr[64 * j]; v[j] = (f32x4){__uint_as_float(w.x << 16), __uint_as_float(w.x & 0xffff0000u), __uint_as_float(w.y << 16), __uint_as_float(w.y & 0xffff0000u)};
;             s += (v[j][0] * v[j][0] + v[j][1] * v[j][1]) + (v[j][2] * v[j][2] + v[j][3] * v[j][3]); }
;         const float rstd = rsqrtf(wave_sum(s) * (1.0f / D) + EPS);
;         const f32x4* gr = (const f32x4*)g + C.lane; f32x4* o = (f32x4*)(out + (size_t)m * D) + C.lane;
; #pragma unroll
;         for (int j = 0; j < 8; ++j) o[64 * j] = v[j] * rstd * gr[64 * j];
;     }
	v_add_f32_e32 v17, v17, v18
	v_fmamk_f32 v6, v17, 0x3a000000, v5
	v_rsq_f32_e32 v6, v6
	s_nop 0
	v_pk_mul_f32 v[64:65], v[6:7], v[64:65] op_sel_hi:[0,1]
	v_pk_mul_f32 v[66:67], v[6:7], v[66:67] op_sel_hi:[0,1]
	v_pk_mul_f32 v[96:97], v[128:129], v[64:65]
	v_pk_mul_f32 v[98:99], v[130:131], v[66:67]
	global_store_dwordx4 v2, v[96:99], s[14:15] offset:-4096
	v_pk_mul_f32 v[68:69], v[6:7], v[68:69] op_sel_hi:[0,1]
	v_pk_mul_f32 v[70:71], v[6:7], v[70:71] op_sel_hi:[0,1]
	v_pk_mul_f32 v[100:101], v[132:133], v[68:69]
	v_pk_mul_f32 v[102:103], v[134:135], v[70:71]
	global_store_dwordx4 v2, v[100:103], s[14:15] offset:-3072
	v_pk_mul_f32 v[72:73], v[6:7], v[72:73] op_sel_hi:[0,1]
	v_pk_mul_f32 v[74:75], v[6:7], v[74:75] op_sel_hi:[0,1]
	v_pk_mul_f32 v[104:105], v[136:137], v[72:73]
	v_pk_mul_f32 v[106:107], v[138:139], v[74:75]
	global_store_dwordx4 v2, v[104:107], s[14:15] offset:-2048
	v_pk_mul_f32 v[76:77], v[6:7], v[76:77] op_sel_hi:[0,1]
	v_pk_mul_f32 v[78:79], v[6:7], v[78:79] op_sel_hi:[0,1]
	v_pk_mul_f32 v[108:109], v[140:141], v[76:77]
	v_pk_mul_f32 v[110:111], v[142:143], v[78:79]
	global_store_dwordx4 v2, v[108:111], s[14:15] offset:-1024
	v_pk_mul_f32 v[80:81], v[6:7], v[80:81] op_sel_hi:[0,1]
	v_pk_mul_f32 v[82:83], v[6:7], v[82:83] op_sel_hi:[0,1]
	v_pk_mul_f32 v[112:113], v[144:145], v[80:81]
	v_pk_mul_f32 v[114:115], v[146:147], v[82:83]
	global_store_dwordx4 v2, v[112:115], s[14:15] offset:0
	v_pk_mul_f32 v[84:85], v[6:7], v[84:85] op_sel_hi:[0,1]
	v_pk_mul_f32 v[86:87], v[6:7], v[86:87] op_sel_hi:[0,1]
	v_pk_mul_f32 v[116:117], v[148:149], v[84:85]
	v_pk_mul_f32 v[118:119], v[150:151], v[86:87]
	global_store_dwordx4 v2, v[116:119], s[14:15] offset:1024
	v_pk_mul_f32 v[88:89], v[6:7], v[88:89] op_sel_hi:[0,1]
	v_pk_mul_f32 v[90:91], v[6:7], v[90:91] op_sel_hi:[0,1]
	v_pk_mul_f32 v[120:121], v[152:153], v[88:89]
	v_pk_mul_f32 v[122:123], v[154:155], v[90:91]
	global_store_dwordx4 v2, v[120:123], s[14:15] offset:2048
	v_pk_mul_f32 v[92:93], v[6:7], v[92:93] op_sel_hi:[0,1]
	v_pk_mul_f32 v[94:95], v[6:7], v[94:95] op_sel_hi:[0,1]
	v_pk_mul_f32 v[124:125], v[156:157], v[92:93]
	v_pk_mul_f32 v[126:127], v[158:159], v[94:95]
	global_store_dwordx4 v2, v[124:127], s[14:15] offset:3072
	s_lshl_b32 s8, s2, 13
	s_add_u32 s14, s4, s8
	s_addc_u32 s15, s5, 0
	s_add_u32 s2, s2, s44
	s_lshl_b32 s8, s2, 12
	s_add_u32 s10, s6, s8
	s_addc_u32 s11, s7, 0
	global_load_dwordx2 v[20:21], v3, s[10:11] offset:-2048
	global_load_dwordx2 v[22:23], v3, s[10:11] offset:-1536
	global_load_dwordx2 v[24:25], v3, s[10:11] offset:-1024
	global_load_dwordx2 v[26:27], v3, s[10:11] offset:-512
	global_load_dwordx2 v[28:29], v3, s[10:11] offset:0
	global_load_dwordx2 v[30:31], v3, s[10:11] offset:512
	global_load_dwordx2 v[32:33], v3, s[10:11] offset:1024
	global_load_dwordx2 v[34:35], v3, s[10:11] offset:1536
	s_waitcnt vmcnt(16)
	v_lshlrev_b32_e32 v64, 16, v36
	v_and_b32_e32 v65, 0xffff0000, v36
	v_lshlrev_b32_e32 v66, 16, v37
	v_and_b32_e32 v67, 0xffff0000, v37
	v_mul_f32_e32 v8, v65, v65
	v_mul_f32_e32 v9, v67, v67
	v_fmac_f32_e32 v8, v64, v64
	v_fmac_f32_e32 v9, v66, v66
	v_add_f32_e32 v17, v8, v9
	v_lshlrev_b32_e32 v68, 16, v38
	v_and_b32_e32 v69, 0xffff0000, v38
	v_lshlrev_b32_e32 v70, 16, v39
	v_and_b32_e32 v71, 0xffff0000, v39
	v_mul_f32_e32 v8, v69, v69
	v_mul_f32_e32 v9, v71, v71
	v_fmac_f32_e32 v8, v68, v68
	v_fmac_f32_e32 v9, v70, v70
	v_add_f32_e32 v8, v8, v9
	v_add_f32_e32 v17, v17, v8
	v_lshlrev_b32_e32 v72, 16, v40
	v_and_b32_e32 v73, 0xffff0000, v40
	v_lshlrev_b32_e32 v74, 16, v41
	v_and_b32_e32 v75, 0xffff0000, v41
	v_mul_f32_e32 v8, v73, v73
	v_mul_f32_e32 v9, v75, v75
	v_fmac_f32_e32 v8, v72, v72
	v_fmac_f32_e32 v9, v74, v74
	v_add_f32_e32 v8, v8, v9
	v_add_f32_e32 v17, v17, v8
	v_lshlrev_b32_e32 v76, 16, v42
	v_and_b32_e32 v77, 0xffff0000, v42
	v_lshlrev_b32_e32 v78, 16, v43
	v_and_b32_e32 v79, 0xffff0000, v43
	v_mul_f32_e32 v8, v77, v77
	v_mul_f32_e32 v9, v79, v79
	v_fmac_f32_e32 v8, v76, v76
	v_fmac_f32_e32 v9, v78, v78
	v_add_f32_e32 v8, v8, v9
	v_add_f32_e32 v17, v17, v8
	v_lshlrev_b32_e32 v80, 16, v44
	v_and_b32_e32 v81, 0xffff0000, v44
	v_lshlrev_b32_e32 v82, 16, v45
	v_and_b32_e32 v83, 0xffff0000, v45
	v_mul_f32_e32 v8, v81, v81
	v_mul_f32_e32 v9, v83, v83
	v_fmac_f32_e32 v8, v80, v80
	v_fmac_f32_e32 v9, v82, v82
	v_add_f32_e32 v8, v8, v9
	v_add_f32_e32 v17, v17, v8
	v_lshlrev_b32_e32 v84, 16, v46
	v_and_b32_e32 v85, 0xffff0000, v46
	v_lshlrev_b32_e32 v86, 16, v47
	v_and_b32_e32 v87, 0xffff0000, v47
	v_mul_f32_e32 v8, v85, v85
	v_mul_f32_e32 v9, v87, v87
	v_fmac_f32_e32 v8, v84, v84
	v_fmac_f32_e32 v9, v86, v86
	v_add_f32_e32 v8, v8, v9
	v_add_f32_e32 v17, v17, v8
	v_lshlrev_b32_e32 v88, 16, v48
	v_and_b32_e32 v89, 0xffff0000, v48
	v_lshlrev_b32_e32 v90, 16, v49
	v_and_b32_e32 v91, 0xffff0000, v49
	v_mul_f32_e32 v8, v89, v89
	v_mul_f32_e32 v9, v91, v91
	v_fmac_f32_e32 v8, v88, v88
	v_fmac_f32_e32 v9, v90, v90
	v_add_f32_e32 v8, v8, v9
	v_add_f32_e32 v17, v17, v8
	v_lshlrev_b32_e32 v92, 16, v50
	v_and_b32_e32 v93, 0xffff0000, v50
	v_lshlrev_b32_e32 v94, 16, v51
	v_and_b32_e32 v95, 0xffff0000, v51
	v_mul_f32_e32 v8, v93, v93
	v_mul_f32_e32 v9, v95, v95
	v_fmac_f32_e32 v8, v92, v92
	v_fmac_f32_e32 v9, v94, v94
	v_add_f32_e32 v8, v8, v9
	v_add_f32_e32 v17, v17, v8
	ds_bpermute_b32 v18, v10, v17
	s_waitcnt lgkmcnt(0)
	v_add_f32_e32 v17, v17, v18
	ds_bpermute_b32 v18, v11, v17
	s_waitcnt lgkmcnt(0)
	v_add_f32_e32 v17, v17, v18
	ds_bpermute_b32 v18, v12, v17
	s_waitcnt lgkmcnt(0)
	v_add_f32_e32 v17, v17, v18
	ds_bpermute_b32 v18, v13, v17
	s_waitcnt lgkmcnt(0)
	v_add_f32_e32 v17, v17, v18
	ds_bpermute_b32 v18, v14, v17
	s_waitcnt lgkmcnt(0)
; __device__ __forceinline__ void final_norm_pass(const Ctx& C, const bf16* XB, const float* g, float* out) {
;     ...
;     for (int m = gw; m < M; m += NGW) {
;         const v2u* xr = (const v2u*)(XB + (size_t)m * D) + C.lane; f32x4 v[8]; float s = 0.f;
; #pragma unroll
;         for (int j = 0; j < 8; ++j) { const v2u w = xr[64 * j]; v[j] = (f32x4){__uint_as_float(w.x << 16), __uint_as_float(w.x & 0xffff0000u), __uint_as_float(w.y << 16), __uint_as_float(w.y & 0xffff0000u)};
;             s += (v[j][0] * v[j][0] + v[j][1] * v[j][1]) + (v[j][2] * v[j][2] + v[j][3] * v[j][3]); }
;         const float rstd = rsqrtf(wave_sum(s) * (1.0f / D) + EPS);
;         const f32x4* gr = (const f32x4*)g + C.lane; f32x4* o = (f32x4*)(out + (size_t)m * D) + C.lane;
; #pragma unroll
;         for (int j = 0; j < 8; ++j) o[64 * j] = v[j] * rstd * gr[64 * j];
;     }
	v_add_f32_e32 v17, v17, v18
	ds_bpermute_b32 v18, v15, v17
	s_waitcnt lgkmcnt(0)
	v_add_f32_e32 v17, v17, v18
	v_fmamk_f32 v6, v17, 0x3a000000, v5
	v_rsq_f32_e32 v6, v6
	s_nop 0
	v_pk_mul_f32 v[64:65], v[6:7], v[64:65] op_sel_hi:[0,1]
	v_pk_mul_f32 v[66:67], v[6:7], v[66:67] op_sel_hi:[0,1]
	v_pk_mul_f32 v[96:97], v[128:129], v[64:65]
	v_pk_mul_f32 v[98:99], v[130:131], v[66:67]
	global_store_dwordx4 v2, v[96:99], s[14:15] offset:-4096
	v_pk_mul_f32 v[68:69], v[6:7], v[68:69] op_sel_hi:[0,1]
	v_pk_mul_f32 v[70:71], v[6:7], v[70:71] op_sel_hi:[0,1]
	v_pk_mul_f32 v[100:101], v[132:133], v[68:69]
	v_pk_mul_f32 v[102:103], v[134:135], v[70:71]
	global_store_dwordx4 v2, v[100:103], s[14:15] offset:-3072
	v_pk_mul_f32 v[72:73], v[6:7], v[72:73] op_sel_hi:[0,1]
	v_pk_mul_f32 v[74:75], v[6:7], v[74:75] op_sel_hi:[0,1]
	v_pk_mul_f32 v[104:105], v[136:137], v[72:73]
	v_pk_mul_f32 v[106:107], v[138:139], v[74:75]
	global_store_dwordx4 v2, v[104:107], s[14:15] offset:-2048
	v_pk_mul_f32 v[76:77], v[6:7], v[76:77] op_sel_hi:[0,1]
	v_pk_mul_f32 v[78:79], v[6:7], v[78:79] op_sel_hi:[0,1]
	v_pk_mul_f32 v[108:109], v[140:141], v[76:77]
	v_pk_mul_f32 v[110:111], v[142:143], v[78:79]
	global_store_dwordx4 v2, v[108:111], s[14:15] offset:-1024
	v_pk_mul_f32 v[80:81], v[6:7], v[80:81] op_sel_hi:[0,1]
	v_pk_mul_f32 v[82:83], v[6:7], v[82:83] op_sel_hi:[0,1]
	v_pk_mul_f32 v[112:113], v[144:145], v[80:81]
	v_pk_mul_f32 v[114:115], v[146:147], v[82:83]
	global_store_dwordx4 v2, v[112:115], s[14:15] offset:0
	v_pk_mul_f32 v[84:85], v[6:7], v[84:85] op_sel_hi:[0,1]
	v_pk_mul_f32 v[86:87], v[6:7], v[86:87] op_sel_hi:[0,1]
	v_pk_mul_f32 v[116:117], v[148:149], v[84:85]
	v_pk_mul_f32 v[118:119], v[150:151], v[86:87]
	global_store_dwordx4 v2, v[116:119], s[14:15] offset:1024
	v_pk_mul_f32 v[88:89], v[6:7], v[88:89] op_sel_hi:[0,1]
	v_pk_mul_f32 v[90:91], v[6:7], v[90:91] op_sel_hi:[0,1]
	v_pk_mul_f32 v[120:121], v[152:153], v[88:89]
	v_pk_mul_f32 v[122:123], v[154:155], v[90:91]
	global_store_dwordx4 v2, v[120:123], s[14:15] offset:2048
	v_pk_mul_f32 v[92:93], v[6:7], v[92:93] op_sel_hi:[0,1]
	v_pk_mul_f32 v[94:95], v[6:7], v[94:95] op_sel_hi:[0,1]
	v_pk_mul_f32 v[124:125], v[156:157], v[92:93]
	v_pk_mul_f32 v[126:127], v[158:159], v[94:95]
	global_store_dwordx4 v2, v[124:127], s[14:15] offset:3072
	s_lshl_b32 s8, s2, 13
	s_add_u32 s14, s4, s8
	s_addc_u32 s15, s5, 0
	s_add_u32 s2, s2, s44
	s_lshl_b32 s8, s2, 12
	s_add_u32 s10, s6, s8
	s_addc_u32 s11, s7, 0
	global_load_dwordx2 v[36:37], v3, s[10:11] offset:-2048
	global_load_dwordx2 v[38:39], v3, s[10:11] offset:-1536
	global_load_dwordx2 v[40:41], v3, s[10:11] offset:-1024
	global_load_dwordx2 v[42:43], v3, s[10:11] offset:-512
	global_load_dwordx2 v[44:45], v3, s[10:11] offset:0
	global_load_dwordx2 v[46:47], v3, s[10:11] offset:512
	global_load_dwordx2 v[48:49], v3, s[10:11] offset:1024
	global_load_dwordx2 v[50:51], v3, s[10:11] offset:1536
	s_waitcnt vmcnt(16)
	v_lshlrev_b32_e32 v64, 16, v20
	v_and_b32_e32 v65, 0xffff0000, v20
	v_lshlrev_b32_e32 v66, 16, v21
	v_and_b32_e32 v67, 0xffff0000, v21
	v_mul_f32_e32 v8, v65, v65
	v_mul_f32_e32 v9, v67, v67
	v_fmac_f32_e32 v8, v64, v64
	v_fmac_f32_e32 v9, v66, v66
	v_add_f32_e32 v17, v8, v9
	v_lshlrev_b32_e32 v68, 16, v22
	v_and_b32_e32 v69, 0xffff0000, v22
	v_lshlrev_b32_e32 v70, 16, v23
	v_and_b32_e32 v71, 0xffff0000, v23
	v_mul_f32_e32 v8, v69, v69
	v_mul_f32_e32 v9, v71, v71
	v_fmac_f32_e32 v8, v68, v68
	v_fmac_f32_e32 v9, v70, v70
	v_add_f32_e32 v8, v8, v9
	v_add_f32_e32 v17, v17, v8
	v_lshlrev_b32_e32 v72, 16, v24
	v_and_b32_e32 v73, 0xffff0000, v24
	v_lshlrev_b32_e32 v74, 16, v25
	v_and_b32_e32 v75, 0xffff0000, v25
	v_mul_f32_e32 v8, v73, v73
	v_mul_f32_e32 v9, v75, v75
	v_fmac_f32_e32 v8, v72, v72
	v_fmac_f32_e32 v9, v74, v74
	v_add_f32_e32 v8, v8, v9
	v_add_f32_e32 v17, v17, v8
	v_lshlrev_b32_e32 v76, 16, v26
	v_and_b32_e32 v77, 0xffff0000, v26
	v_lshlrev_b32_e32 v78, 16, v27
	v_and_b32_e32 v79, 0xffff0000, v27
	v_mul_f32_e32 v8, v77, v77
	v_mul_f32_e32 v9, v79, v79
	v_fmac_f32_e32 v8, v76, v76
	v_fmac_f32_e32 v9, v78, v78
	v_add_f32_e32 v8, v8, v9
	v_add_f32_e32 v17, v17, v8
	v_lshlrev_b32_e32 v80, 16, v28
	v_and_b32_e32 v81, 0xffff0000, v28
	v_lshlrev_b32_e32 v82, 16, v29
	v_and_b32_e32 v83, 0xffff0000, v29
	v_mul_f32_e32 v8, v81, v81
	v_mul_f32_e32 v9, v83, v83
	v_fmac_f32_e32 v8, v80, v80
	v_fmac_f32_e32 v9, v82, v82
	v_add_f32_e32 v8, v8, v9
	v_add_f32_e32 v17, v17, v8
	v_lshlrev_b32_e32 v84, 16, v30
	v_and_b32_e32 v85, 0xffff0000, v30
	v_lshlrev_b32_e32 v86, 16, v31
	v_and_b32_e32 v87, 0xffff0000, v31
	v_mul_f32_e32 v8, v85, v85
	v_mul_f32_e32 v9, v87, v87
	v_fmac_f32_e32 v8, v84, v84
	v_fmac_f32_e32 v9, v86, v86
	v_add_f32_e32 v8, v8, v9
	v_add_f32_e32 v17, v17, v8
	v_lshlrev_b32_e32 v88, 16, v32
	v_and_b32_e32 v89, 0xffff0000, v32
	v_lshlrev_b32_e32 v90, 16, v33
	v_and_b32_e32 v91, 0xffff0000, v33
	v_mul_f32_e32 v8, v89, v89
	v_mul_f32_e32 v9, v91, v91
	v_fmac_f32_e32 v8, v88, v88
	v_fmac_f32_e32 v9, v90, v90
	v_add_f32_e32 v8, v8, v9
	v_add_f32_e32 v17, v17, v8
	v_lshlrev_b32_e32 v92, 16, v34
	v_and_b32_e32 v93, 0xffff0000, v34
	v_lshlrev_b32_e32 v94, 16, v35
	v_and_b32_e32 v95, 0xffff0000, v35
	v_mul_f32_e32 v8, v93, v93
	v_mul_f32_e32 v9, v95, v95
	v_fmac_f32_e32 v8, v92, v92
	v_fmac_f32_e32 v9, v94, v94
	v_add_f32_e32 v8, v8, v9
	v_add_f32_e32 v17, v17, v8
	ds_bpermute_b32 v18, v10, v17
	s_waitcnt lgkmcnt(0)
	v_add_f32_e32 v17, v17, v18
	ds_bpermute_b32 v18, v11, v17
	s_waitcnt lgkmcnt(0)
	v_add_f32_e32 v17, v17, v18
	ds_bpermute_b32 v18, v12, v17
	s_waitcnt lgkmcnt(0)
	v_add_f32_e32 v17, v17, v18
	ds_bpermute_b32 v18, v13, v17
	s_waitcnt lgkmcnt(0)
; __device__ __forceinline__ void final_norm_pass(const Ctx& C, const bf16* XB, const float* g, float* out) {
;     ...
;     for (int m = gw; m < M; m += NGW) {
;         const v2u* xr = (const v2u*)(XB + (size_t)m * D) + C.lane; f32x4 v[8]; float s = 0.f;
; #pragma unroll
;         for (int j = 0; j < 8; ++j) { const v2u w = xr[64 * j]; v[j] = (f32x4){__uint_as_float(w.x << 16), __uint_as_float(w.x & 0xffff0000u), __uint_as_float(w.y << 16), __uint_as_float(w.y & 0xffff0000u)};
;             s += (v[j][0] * v[j][0] + v[j][1] * v[j][1]) + (v[j][2] * v[j][2] + v[j][3] * v[j][3]); }
;         const float rstd = rsqrtf(wave_sum(s) * (1.0f / D) + EPS);
;         const f32x4* gr = (const f32x4*)g + C.lane; f32x4* o = (f32x4*)(out + (size_t)m * D) + C.lane;
; #pragma unroll
;         for (int j = 0; j < 8; ++j) o[64 * j] = v[j] * rstd * gr[64 * j];
;     }
	v_add_f32_e32 v17, v17, v18
	ds_bpermute_b32 v18, v14, v17
	s_waitcnt lgkmcnt(0)
	v_add_f32_e32 v17, v17, v18
	ds_bpermute_b32 v18, v15, v17
	s_waitcnt lgkmcnt(0)
	v_add_f32_e32 v17, v17, v18
	v_fmamk_f32 v6, v17, 0x3a000000, v5
	v_rsq_f32_e32 v6, v6
	s_nop 0
	v_pk_mul_f32 v[64:65], v[6:7], v[64:65] op_sel_hi:[0,1]
	v_pk_mul_f32 v[66:67], v[6:7], v[66:67] op_sel_hi:[0,1]
	v_pk_mul_f32 v[96:97], v[128:129], v[64:65]
	v_pk_mul_f32 v[98:99], v[130:131], v[66:67]
	global_store_dwordx4 v2, v[96:99], s[14:15] offset:-4096
	v_pk_mul_f32 v[68:69], v[6:7], v[68:69] op_sel_hi:[0,1]
	v_pk_mul_f32 v[70:71], v[6:7], v[70:71] op_sel_hi:[0,1]
	v_pk_mul_f32 v[100:101], v[132:133], v[68:69]
	v_pk_mul_f32 v[102:103], v[134:135], v[70:71]
	global_store_dwordx4 v2, v[100:103], s[14:15] offset:-3072
	v_pk_mul_f32 v[72:73], v[6:7], v[72:73] op_sel_hi:[0,1]
	v_pk_mul_f32 v[74:75], v[6:7], v[74:75] op_sel_hi:[0,1]
	v_pk_mul_f32 v[104:105], v[136:137], v[72:73]
	v_pk_mul_f32 v[106:107], v[138:139], v[74:75]
	global_store_dwordx4 v2, v[104:107], s[14:15] offset:-2048
	v_pk_mul_f32 v[76:77], v[6:7], v[76:77] op_sel_hi:[0,1]
	v_pk_mul_f32 v[78:79], v[6:7], v[78:79] op_sel_hi:[0,1]
	v_pk_mul_f32 v[108:109], v[140:141], v[76:77]
	v_pk_mul_f32 v[110:111], v[142:143], v[78:79]
	global_store_dwordx4 v2, v[108:111], s[14:15] offset:-1024
	v_pk_mul_f32 v[80:81], v[6:7], v[80:81] op_sel_hi:[0,1]
	v_pk_mul_f32 v[82:83], v[6:7], v[82:83] op_sel_hi:[0,1]
	v_pk_mul_f32 v[112:113], v[144:145], v[80:81]
	v_pk_mul_f32 v[114:115], v[146:147], v[82:83]
	global_store_dwordx4 v2, v[112:115], s[14:15] offset:0
	v_pk_mul_f32 v[84:85], v[6:7], v[84:85] op_sel_hi:[0,1]
	v_pk_mul_f32 v[86:87], v[6:7], v[86:87] op_sel_hi:[0,1]
	v_pk_mul_f32 v[116:117], v[148:149], v[84:85]
	v_pk_mul_f32 v[118:119], v[150:151], v[86:87]
	global_store_dwordx4 v2, v[116:119], s[14:15] offset:1024
	v_pk_mul_f32 v[88:89], v[6:7], v[88:89] op_sel_hi:[0,1]
	v_pk_mul_f32 v[90:91], v[6:7], v[90:91] op_sel_hi:[0,1]
	v_pk_mul_f32 v[120:121], v[152:153], v[88:89]
	v_pk_mul_f32 v[122:123], v[154:155], v[90:91]
	global_store_dwordx4 v2, v[120:123], s[14:15] offset:2048
	v_pk_mul_f32 v[92:93], v[6:7], v[92:93] op_sel_hi:[0,1]
	v_pk_mul_f32 v[94:95], v[6:7], v[94:95] op_sel_hi:[0,1]
	v_pk_mul_f32 v[124:125], v[156:157], v[92:93]
	v_pk_mul_f32 v[126:127], v[158:159], v[94:95]
	global_store_dwordx4 v2, v[124:127], s[14:15] offset:3072
	s_lshl_b32 s8, s2, 13
	s_add_u32 s14, s4, s8
	s_addc_u32 s15, s5, 0
	s_add_u32 s2, s2, s44
	s_lshl_b32 s8, s2, 12
	s_add_u32 s10, s6, s8
	s_addc_u32 s11, s7, 0
	global_load_dwordx2 v[20:21], v3, s[10:11] offset:-2048
	global_load_dwordx2 v[22:23], v3, s[10:11] offset:-1536
	global_load_dwordx2 v[24:25], v3, s[10:11] offset:-1024
	global_load_dwordx2 v[26:27], v3, s[10:11] offset:-512
	global_load_dwordx2 v[28:29], v3, s[10:11] offset:0
	global_load_dwordx2 v[30:31], v3, s[10:11] offset:512
	global_load_dwordx2 v[32:33], v3, s[10:11] offset:1024
	global_load_dwordx2 v[34:35], v3, s[10:11] offset:1536
	s_waitcnt vmcnt(16)
	v_lshlrev_b32_e32 v64, 16, v36
	v_and_b32_e32 v65, 0xffff0000, v36
	v_lshlrev_b32_e32 v66, 16, v37
	v_and_b32_e32 v67, 0xffff0000, v37
	v_mul_f32_e32 v8, v65, v65
	v_mul_f32_e32 v9, v67, v67
	v_fmac_f32_e32 v8, v64, v64
	v_fmac_f32_e32 v9, v66, v66
	v_add_f32_e32 v17, v8, v9
	v_lshlrev_b32_e32 v68, 16, v38
	v_and_b32_e32 v69, 0xffff0000, v38
	v_lshlrev_b32_e32 v70, 16, v39
	v_and_b32_e32 v71, 0xffff0000, v39
	v_mul_f32_e32 v8, v69, v69
	v_mul_f32_e32 v9, v71, v71
	v_fmac_f32_e32 v8, v68, v68
	v_fmac_f32_e32 v9, v70, v70
	v_add_f32_e32 v8, v8, v9
	v_add_f32_e32 v17, v17, v8
	v_lshlrev_b32_e32 v72, 16, v40
	v_and_b32_e32 v73, 0xffff0000, v40
	v_lshlrev_b32_e32 v74, 16, v41
	v_and_b32_e32 v75, 0xffff0000, v41
	v_mul_f32_e32 v8, v73, v73
	v_mul_f32_e32 v9, v75, v75
	v_fmac_f32_e32 v8, v72, v72
	v_fmac_f32_e32 v9, v74, v74
	v_add_f32_e32 v8, v8, v9
	v_add_f32_e32 v17, v17, v8
	v_lshlrev_b32_e32 v76, 16, v42
	v_and_b32_e32 v77, 0xffff0000, v42
	v_lshlrev_b32_e32 v78, 16, v43
	v_and_b32_e32 v79, 0xffff0000, v43
	v_mul_f32_e32 v8, v77, v77
	v_mul_f32_e32 v9, v79, v79
	v_fmac_f32_e32 v8, v76, v76
	v_fmac_f32_e32 v9, v78, v78
	v_add_f32_e32 v8, v8, v9
	v_add_f32_e32 v17, v17, v8
	v_lshlrev_b32_e32 v80, 16, v44
	v_and_b32_e32 v81, 0xffff0000, v44
	v_lshlrev_b32_e32 v82, 16, v45
	v_and_b32_e32 v83, 0xffff0000, v45
	v_mul_f32_e32 v8, v81, v81
	v_mul_f32_e32 v9, v83, v83
	v_fmac_f32_e32 v8, v80, v80
	v_fmac_f32_e32 v9, v82, v82
	v_add_f32_e32 v8, v8, v9
	v_add_f32_e32 v17, v17, v8
	v_lshlrev_b32_e32 v84, 16, v46
	v_and_b32_e32 v85, 0xffff0000, v46
	v_lshlrev_b32_e32 v86, 16, v47
	v_and_b32_e32 v87, 0xffff0000, v47
	v_mul_f32_e32 v8, v85, v85
	v_mul_f32_e32 v9, v87, v87
	v_fmac_f32_e32 v8, v84, v84
	v_fmac_f32_e32 v9, v86, v86
	v_add_f32_e32 v8, v8, v9
	v_add_f32_e32 v17, v17, v8
	v_lshlrev_b32_e32 v88, 16, v48
	v_and_b32_e32 v89, 0xffff0000, v48
	v_lshlrev_b32_e32 v90, 16, v49
	v_and_b32_e32 v91, 0xffff0000, v49
	v_mul_f32_e32 v8, v89, v89
	v_mul_f32_e32 v9, v91, v91
	v_fmac_f32_e32 v8, v88, v88
	v_fmac_f32_e32 v9, v90, v90
	v_add_f32_e32 v8, v8, v9
	v_add_f32_e32 v17, v17, v8
	v_lshlrev_b32_e32 v92, 16, v50
	v_and_b32_e32 v93, 0xffff0000, v50
	v_lshlrev_b32_e32 v94, 16, v51
	v_and_b32_e32 v95, 0xffff0000, v51
	v_mul_f32_e32 v8, v93, v93
	v_mul_f32_e32 v9, v95, v95
	v_fmac_f32_e32 v8, v92, v92
	v_fmac_f32_e32 v9, v94, v94
	v_add_f32_e32 v8, v8, v9
	v_add_f32_e32 v17, v17, v8
	ds_bpermute_b32 v18, v10, v17
	s_waitcnt lgkmcnt(0)
	v_add_f32_e32 v17, v17, v18
	ds_bpermute_b32 v18, v11, v17
	s_waitcnt lgkmcnt(0)
	v_add_f32_e32 v17, v17, v18
	ds_bpermute_b32 v18, v12, v17
	s_waitcnt lgkmcnt(0)
; __device__ __forceinline__ void final_norm_pass(const Ctx& C, const bf16* XB, const float* g, float* out) {
;     ...
;     for (int m = gw; m < M; m += NGW) {
;         const v2u* xr = (const v2u*)(XB + (size_t)m * D) + C.lane; f32x4 v[8]; float s = 0.f;
; #pragma unroll
;         for (int j = 0; j < 8; ++j) { const v2u w = xr[64 * j]; v[j] = (f32x4){__uint_as_float(w.x << 16), __uint_as_float(w.x & 0xffff0000u), __uint_as_float(w.y << 16), __uint_as_float(w.y & 0xffff0000u)};
;             s += (v[j][0] * v[j][0] + v[j][1] * v[j][1]) + (v[j][2] * v[j][2] + v[j][3] * v[j][3]); }
;         const float rstd = rsqrtf(wave_sum(s) * (1.0f / D) + EPS);
;         const f32x4* gr = (const f32x4*)g + C.lane; f32x4* o = (f32x4*)(out + (size_t)m * D) + C.lane;
; #pragma unroll
;         for (int j = 0; j < 8; ++j) o[64 * j] = v[j] * rstd * gr[64 * j];
;     }
	v_add_f32_e32 v17, v17, v18
	ds_bpermute_b32 v18, v13, v17
	s_waitcnt lgkmcnt(0)
	v_add_f32_e32 v17, v17, v18
	ds_bpermute_b32 v18, v14, v17
	s_waitcnt lgkmcnt(0)
	v_add_f32_e32 v17, v17, v18
	ds_bpermute_b32 v18, v15, v17
	s_waitcnt lgkmcnt(0)
	v_add_f32_e32 v17, v17, v18
	v_fmamk_f32 v6, v17, 0x3a000000, v5
	v_rsq_f32_e32 v6, v6
	s_nop 0
	v_pk_mul_f32 v[64:65], v[6:7], v[64:65] op_sel_hi:[0,1]
	v_pk_mul_f32 v[66:67], v[6:7], v[66:67] op_sel_hi:[0,1]
	v_pk_mul_f32 v[96:97], v[128:129], v[64:65]
	v_pk_mul_f32 v[98:99], v[130:131], v[66:67]
	global_store_dwordx4 v2, v[96:99], s[14:15] offset:-4096
	v_pk_mul_f32 v[68:69], v[6:7], v[68:69] op_sel_hi:[0,1]
	v_pk_mul_f32 v[70:71], v[6:7], v[70:71] op_sel_hi:[0,1]
	v_pk_mul_f32 v[100:101], v[132:133], v[68:69]
	v_pk_mul_f32 v[102:103], v[134:135], v[70:71]
	global_store_dwordx4 v2, v[100:103], s[14:15] offset:-3072
	v_pk_mul_f32 v[72:73], v[6:7], v[72:73] op_sel_hi:[0,1]
	v_pk_mul_f32 v[74:75], v[6:7], v[74:75] op_sel_hi:[0,1]
	v_pk_mul_f32 v[104:105], v[136:137], v[72:73]
	v_pk_mul_f32 v[106:107], v[138:139], v[74:75]
	global_store_dwordx4 v2, v[104:107], s[14:15] offset:-2048
	v_pk_mul_f32 v[76:77], v[6:7], v[76:77] op_sel_hi:[0,1]
	v_pk_mul_f32 v[78:79], v[6:7], v[78:79] op_sel_hi:[0,1]
	v_pk_mul_f32 v[108:109], v[140:141], v[76:77]
	v_pk_mul_f32 v[110:111], v[142:143], v[78:79]
	global_store_dwordx4 v2, v[108:111], s[14:15] offset:-1024
	v_pk_mul_f32 v[80:81], v[6:7], v[80:81] op_sel_hi:[0,1]
	v_pk_mul_f32 v[82:83], v[6:7], v[82:83] op_sel_hi:[0,1]
	v_pk_mul_f32 v[112:113], v[144:145], v[80:81]
	v_pk_mul_f32 v[114:115], v[146:147], v[82:83]
	global_store_dwordx4 v2, v[112:115], s[14:15] offset:0
	v_pk_mul_f32 v[84:85], v[6:7], v[84:85] op_sel_hi:[0,1]
	v_pk_mul_f32 v[86:87], v[6:7], v[86:87] op_sel_hi:[0,1]
	v_pk_mul_f32 v[116:117], v[148:149], v[84:85]
	v_pk_mul_f32 v[118:119], v[150:151], v[86:87]
	global_store_dwordx4 v2, v[116:119], s[14:15] offset:1024
	v_pk_mul_f32 v[88:89], v[6:7], v[88:89] op_sel_hi:[0,1]
	v_pk_mul_f32 v[90:91], v[6:7], v[90:91] op_sel_hi:[0,1]
	v_pk_mul_f32 v[120:121], v[152:153], v[88:89]
	v_pk_mul_f32 v[122:123], v[154:155], v[90:91]
	global_store_dwordx4 v2, v[120:123], s[14:15] offset:2048
	v_pk_mul_f32 v[92:93], v[6:7], v[92:93] op_sel_hi:[0,1]
	v_pk_mul_f32 v[94:95], v[6:7], v[94:95] op_sel_hi:[0,1]
	v_pk_mul_f32 v[124:125], v[156:157], v[92:93]
	v_pk_mul_f32 v[126:127], v[158:159], v[94:95]
	global_store_dwordx4 v2, v[124:127], s[14:15] offset:3072
	s_lshl_b32 s8, s2, 13
	s_add_u32 s14, s4, s8
	s_addc_u32 s15, s5, 0
	s_add_u32 s2, s2, s44
	s_lshl_b32 s8, s2, 12
	s_add_u32 s10, s6, s8
	s_addc_u32 s11, s7, 0
	global_load_dwordx2 v[36:37], v3, s[10:11] offset:-2048
	global_load_dwordx2 v[38:39], v3, s[10:11] offset:-1536
	global_load_dwordx2 v[40:41], v3, s[10:11] offset:-1024
	global_load_dwordx2 v[42:43], v3, s[10:11] offset:-512
	global_load_dwordx2 v[44:45], v3, s[10:11] offset:0
	global_load_dwordx2 v[46:47], v3, s[10:11] offset:512
	global_load_dwordx2 v[48:49], v3, s[10:11] offset:1024
	global_load_dwordx2 v[50:51], v3, s[10:11] offset:1536
	s_waitcnt vmcnt(16)
	v_lshlrev_b32_e32 v64, 16, v20
	v_and_b32_e32 v65, 0xffff0000, v20
	v_lshlrev_b32_e32 v66, 16, v21
	v_and_b32_e32 v67, 0xffff0000, v21
	v_mul_f32_e32 v8, v65, v65
	v_mul_f32_e32 v9, v67, v67
	v_fmac_f32_e32 v8, v64, v64
	v_fmac_f32_e32 v9, v66, v66
	v_add_f32_e32 v17, v8, v9
	v_lshlrev_b32_e32 v68, 16, v22
	v_and_b32_e32 v69, 0xffff0000, v22
	v_lshlrev_b32_e32 v70, 16, v23
	v_and_b32_e32 v71, 0xffff0000, v23
	v_mul_f32_e32 v8, v69, v69
	v_mul_f32_e32 v9, v71, v71
	v_fmac_f32_e32 v8, v68, v68
	v_fmac_f32_e32 v9, v70, v70
	v_add_f32_e32 v8, v8, v9
	v_add_f32_e32 v17, v17, v8
	v_lshlrev_b32_e32 v72, 16, v24
	v_and_b32_e32 v73, 0xffff0000, v24
	v_lshlrev_b32_e32 v74, 16, v25
	v_and_b32_e32 v75, 0xffff0000, v25
	v_mul_f32_e32 v8, v73, v73
	v_mul_f32_e32 v9, v75, v75
	v_fmac_f32_e32 v8, v72, v72
	v_fmac_f32_e32 v9, v74, v74
	v_add_f32_e32 v8, v8, v9
	v_add_f32_e32 v17, v17, v8
	v_lshlrev_b32_e32 v76, 16, v26
	v_and_b32_e32 v77, 0xffff0000, v26
	v_lshlrev_b32_e32 v78, 16, v27
	v_and_b32_e32 v79, 0xffff0000, v27
	v_mul_f32_e32 v8, v77, v77
	v_mul_f32_e32 v9, v79, v79
	v_fmac_f32_e32 v8, v76, v76
	v_fmac_f32_e32 v9, v78, v78
	v_add_f32_e32 v8, v8, v9
	v_add_f32_e32 v17, v17, v8
	v_lshlrev_b32_e32 v80, 16, v28
	v_and_b32_e32 v81, 0xffff0000, v28
	v_lshlrev_b32_e32 v82, 16, v29
	v_and_b32_e32 v83, 0xffff0000, v29
	v_mul_f32_e32 v8, v81, v81
	v_mul_f32_e32 v9, v83, v83
	v_fmac_f32_e32 v8, v80, v80
	v_fmac_f32_e32 v9, v82, v82
	v_add_f32_e32 v8, v8, v9
	v_add_f32_e32 v17, v17, v8
	v_lshlrev_b32_e32 v84, 16, v30
	v_and_b32_e32 v85, 0xffff0000, v30
	v_lshlrev_b32_e32 v86, 16, v31
	v_and_b32_e32 v87, 0xffff0000, v31
	v_mul_f32_e32 v8, v85, v85
	v_mul_f32_e32 v9, v87, v87
	v_fmac_f32_e32 v8, v84, v84
	v_fmac_f32_e32 v9, v86, v86
	v_add_f32_e32 v8, v8, v9
	v_add_f32_e32 v17, v17, v8
	v_lshlrev_b32_e32 v88, 16, v32
	v_and_b32_e32 v89, 0xffff0000, v32
	v_lshlrev_b32_e32 v90, 16, v33
	v_and_b32_e32 v91, 0xffff0000, v33
	v_mul_f32_e32 v8, v89, v89
	v_mul_f32_e32 v9, v91, v91
	v_fmac_f32_e32 v8, v88, v88
	v_fmac_f32_e32 v9, v90, v90
	v_add_f32_e32 v8, v8, v9
	v_add_f32_e32 v17, v17, v8
	v_lshlrev_b32_e32 v92, 16, v34
	v_and_b32_e32 v93, 0xffff0000, v34
	v_lshlrev_b32_e32 v94, 16, v35
	v_and_b32_e32 v95, 0xffff0000, v35
	v_mul_f32_e32 v8, v93, v93
	v_mul_f32_e32 v9, v95, v95
	v_fmac_f32_e32 v8, v92, v92
	v_fmac_f32_e32 v9, v94, v94
	v_add_f32_e32 v8, v8, v9
	v_add_f32_e32 v17, v17, v8
	ds_bpermute_b32 v18, v10, v17
	s_waitcnt lgkmcnt(0)
	v_add_f32_e32 v17, v17, v18
	ds_bpermute_b32 v18, v11, v17
	s_waitcnt lgkmcnt(0)
; __device__ __forceinline__ void final_norm_pass(const Ctx& C, const bf16* XB, const float* g, float* out) {
;     ...
;     for (int m = gw; m < M; m += NGW) {
;         const v2u* xr = (const v2u*)(XB + (size_t)m * D) + C.lane; f32x4 v[8]; float s = 0.f;
; #pragma unroll
;         for (int j = 0; j < 8; ++j) { const v2u w = xr[64 * j]; v[j] = (f32x4){__uint_as_float(w.x << 16), __uint_as_float(w.x & 0xffff0000u), __uint_as_float(w.y << 16), __uint_as_float(w.y & 0xffff0000u)};
;             s += (v[j][0] * v[j][0] + v[j][1] * v[j][1]) + (v[j][2] * v[j][2] + v[j][3] * v[j][3]); }
;         const float rstd = rsqrtf(wave_sum(s) * (1.0f / D) + EPS);
;         const f32x4* gr = (const f32x4*)g + C.lane; f32x4* o = (f32x4*)(out + (size_t)m * D) + C.lane;
; #pragma unroll
;         for (int j = 0; j < 8; ++j) o[64 * j] = v[j] * rstd * gr[64 * j];
;     }
	v_add_f32_e32 v17, v17, v18
	ds_bpermute_b32 v18, v12, v17
	s_waitcnt lgkmcnt(0)
	v_add_f32_e32 v17, v17, v18
	ds_bpermute_b32 v18, v13, v17
	s_waitcnt lgkmcnt(0)
	v_add_f32_e32 v17, v17, v18
	ds_bpermute_b32 v18, v14, v17
	s_waitcnt lgkmcnt(0)
	v_add_f32_e32 v17, v17, v18
	ds_bpermute_b32 v18, v15, v17
	s_waitcnt lgkmcnt(0)
	v_add_f32_e32 v17, v17, v18
	v_fmamk_f32 v6, v17, 0x3a000000, v5
	v_rsq_f32_e32 v6, v6
	s_nop 0
	v_pk_mul_f32 v[64:65], v[6:7], v[64:65] op_sel_hi:[0,1]
	v_pk_mul_f32 v[66:67], v[6:7], v[66:67] op_sel_hi:[0,1]
	v_pk_mul_f32 v[96:97], v[128:129], v[64:65]
	v_pk_mul_f32 v[98:99], v[130:131], v[66:67]
	global_store_dwordx4 v2, v[96:99], s[14:15] offset:-4096
	v_pk_mul_f32 v[68:69], v[6:7], v[68:69] op_sel_hi:[0,1]
	v_pk_mul_f32 v[70:71], v[6:7], v[70:71] op_sel_hi:[0,1]
	v_pk_mul_f32 v[100:101], v[132:133], v[68:69]
	v_pk_mul_f32 v[102:103], v[134:135], v[70:71]
	global_store_dwordx4 v2, v[100:103], s[14:15] offset:-3072
	v_pk_mul_f32 v[72:73], v[6:7], v[72:73] op_sel_hi:[0,1]
	v_pk_mul_f32 v[74:75], v[6:7], v[74:75] op_sel_hi:[0,1]
	v_pk_mul_f32 v[104:105], v[136:137], v[72:73]
	v_pk_mul_f32 v[106:107], v[138:139], v[74:75]
	global_store_dwordx4 v2, v[104:107], s[14:15] offset:-2048
	v_pk_mul_f32 v[76:77], v[6:7], v[76:77] op_sel_hi:[0,1]
	v_pk_mul_f32 v[78:79], v[6:7], v[78:79] op_sel_hi:[0,1]
	v_pk_mul_f32 v[108:109], v[140:141], v[76:77]
	v_pk_mul_f32 v[110:111], v[142:143], v[78:79]
	global_store_dwordx4 v2, v[108:111], s[14:15] offset:-1024
	v_pk_mul_f32 v[80:81], v[6:7], v[80:81] op_sel_hi:[0,1]
	v_pk_mul_f32 v[82:83], v[6:7], v[82:83] op_sel_hi:[0,1]
	v_pk_mul_f32 v[112:113], v[144:145], v[80:81]
	v_pk_mul_f32 v[114:115], v[146:147], v[82:83]
	global_store_dwordx4 v2, v[112:115], s[14:15] offset:0
	v_pk_mul_f32 v[84:85], v[6:7], v[84:85] op_sel_hi:[0,1]
	v_pk_mul_f32 v[86:87], v[6:7], v[86:87] op_sel_hi:[0,1]
	v_pk_mul_f32 v[116:117], v[148:149], v[84:85]
	v_pk_mul_f32 v[118:119], v[150:151], v[86:87]
	global_store_dwordx4 v2, v[116:119], s[14:15] offset:1024
	v_pk_mul_f32 v[88:89], v[6:7], v[88:89] op_sel_hi:[0,1]
	v_pk_mul_f32 v[90:91], v[6:7], v[90:91] op_sel_hi:[0,1]
	v_pk_mul_f32 v[120:121], v[152:153], v[88:89]
	v_pk_mul_f32 v[122:123], v[154:155], v[90:91]
	global_store_dwordx4 v2, v[120:123], s[14:15] offset:2048
	v_pk_mul_f32 v[92:93], v[6:7], v[92:93] op_sel_hi:[0,1]
	v_pk_mul_f32 v[94:95], v[6:7], v[94:95] op_sel_hi:[0,1]
	v_pk_mul_f32 v[124:125], v[156:157], v[92:93]
	v_pk_mul_f32 v[126:127], v[158:159], v[94:95]
	global_store_dwordx4 v2, v[124:127], s[14:15] offset:3072
	s_lshl_b32 s8, s2, 13
	s_add_u32 s14, s4, s8
	s_addc_u32 s15, s5, 0
	s_add_u32 s2, s2, s44
	s_lshl_b32 s8, s2, 12
	s_add_u32 s10, s6, s8
	s_addc_u32 s11, s7, 0
	global_load_dwordx2 v[20:21], v3, s[10:11] offset:-2048
	global_load_dwordx2 v[22:23], v3, s[10:11] offset:-1536
	global_load_dwordx2 v[24:25], v3, s[10:11] offset:-1024
	global_load_dwordx2 v[26:27], v3, s[10:11] offset:-512
	global_load_dwordx2 v[28:29], v3, s[10:11] offset:0
	global_load_dwordx2 v[30:31], v3, s[10:11] offset:512
	global_load_dwordx2 v[32:33], v3, s[10:11] offset:1024
	global_load_dwordx2 v[34:35], v3, s[10:11] offset:1536
	s_waitcnt vmcnt(16)
	v_lshlrev_b32_e32 v64, 16, v36
	v_and_b32_e32 v65, 0xffff0000, v36
	v_lshlrev_b32_e32 v66, 16, v37
	v_and_b32_e32 v67, 0xffff0000, v37
	v_mul_f32_e32 v8, v65, v65
	v_mul_f32_e32 v9, v67, v67
	v_fmac_f32_e32 v8, v64, v64
	v_fmac_f32_e32 v9, v66, v66
	v_add_f32_e32 v17, v8, v9
	v_lshlrev_b32_e32 v68, 16, v38
	v_and_b32_e32 v69, 0xffff0000, v38
	v_lshlrev_b32_e32 v70, 16, v39
	v_and_b32_e32 v71, 0xffff0000, v39
	v_mul_f32_e32 v8, v69, v69
	v_mul_f32_e32 v9, v71, v71
	v_fmac_f32_e32 v8, v68, v68
	v_fmac_f32_e32 v9, v70, v70
	v_add_f32_e32 v8, v8, v9
	v_add_f32_e32 v17, v17, v8
	v_lshlrev_b32_e32 v72, 16, v40
	v_and_b32_e32 v73, 0xffff0000, v40
	v_lshlrev_b32_e32 v74, 16, v41
	v_and_b32_e32 v75, 0xffff0000, v41
	v_mul_f32_e32 v8, v73, v73
	v_mul_f32_e32 v9, v75, v75
	v_fmac_f32_e32 v8, v72, v72
	v_fmac_f32_e32 v9, v74, v74
	v_add_f32_e32 v8, v8, v9
	v_add_f32_e32 v17, v17, v8
	v_lshlrev_b32_e32 v76, 16, v42
	v_and_b32_e32 v77, 0xffff0000, v42
	v_lshlrev_b32_e32 v78, 16, v43
	v_and_b32_e32 v79, 0xffff0000, v43
	v_mul_f32_e32 v8, v77, v77
	v_mul_f32_e32 v9, v79, v79
	v_fmac_f32_e32 v8, v76, v76
	v_fmac_f32_e32 v9, v78, v78
	v_add_f32_e32 v8, v8, v9
	v_add_f32_e32 v17, v17, v8
	v_lshlrev_b32_e32 v80, 16, v44
	v_and_b32_e32 v81, 0xffff0000, v44
	v_lshlrev_b32_e32 v82, 16, v45
	v_and_b32_e32 v83, 0xffff0000, v45
	v_mul_f32_e32 v8, v81, v81
	v_mul_f32_e32 v9, v83, v83
	v_fmac_f32_e32 v8, v80, v80
	v_fmac_f32_e32 v9, v82, v82
	v_add_f32_e32 v8, v8, v9
	v_add_f32_e32 v17, v17, v8
	v_lshlrev_b32_e32 v84, 16, v46
	v_and_b32_e32 v85, 0xffff0000, v46
	v_lshlrev_b32_e32 v86, 16, v47
	v_and_b32_e32 v87, 0xffff0000, v47
	v_mul_f32_e32 v8, v85, v85
	v_mul_f32_e32 v9, v87, v87
	v_fmac_f32_e32 v8, v84, v84
	v_fmac_f32_e32 v9, v86, v86
	v_add_f32_e32 v8, v8, v9
	v_add_f32_e32 v17, v17, v8
	v_lshlrev_b32_e32 v88, 16, v48
	v_and_b32_e32 v89, 0xffff0000, v48
	v_lshlrev_b32_e32 v90, 16, v49
	v_and_b32_e32 v91, 0xffff0000, v49
	v_mul_f32_e32 v8, v89, v89
	v_mul_f32_e32 v9, v91, v91
	v_fmac_f32_e32 v8, v88, v88
	v_fmac_f32_e32 v9, v90, v90
	v_add_f32_e32 v8, v8, v9
	v_add_f32_e32 v17, v17, v8
	v_lshlrev_b32_e32 v92, 16, v50
	v_and_b32_e32 v93, 0xffff0000, v50
	v_lshlrev_b32_e32 v94, 16, v51
	v_and_b32_e32 v95, 0xffff0000, v51
	v_mul_f32_e32 v8, v93, v93
	v_mul_f32_e32 v9, v95, v95
	v_fmac_f32_e32 v8, v92, v92
	v_fmac_f32_e32 v9, v94, v94
	v_add_f32_e32 v8, v8, v9
	v_add_f32_e32 v17, v17, v8
	ds_bpermute_b32 v18, v10, v17
	s_waitcnt lgkmcnt(0)
; __device__ __forceinline__ void final_norm_pass(const Ctx& C, const bf16* XB, const float* g, float* out) {
;     ...
;     for (int m = gw; m < M; m += NGW) {
;         const v2u* xr = (const v2u*)(XB + (size_t)m * D) + C.lane; f32x4 v[8]; float s = 0.f;
; #pragma unroll
;         for (int j = 0; j < 8; ++j) { const v2u w = xr[64 * j]; v[j] = (f32x4){__uint_as_float(w.x << 16), __uint_as_float(w.x & 0xffff0000u), __uint_as_float(w.y << 16), __uint_as_float(w.y & 0xffff0000u)};
;             s += (v[j][0] * v[j][0] + v[j][1] * v[j][1]) + (v[j][2] * v[j][2] + v[j][3] * v[j][3]); }
;         const float rstd = rsqrtf(wave_sum(s) * (1.0f / D) + EPS);
;         const f32x4* gr = (const f32x4*)g + C.lane; f32x4* o = (f32x4*)(out + (size_t)m * D) + C.lane;
; #pragma unroll
;         for (int j = 0; j < 8; ++j) o[64 * j] = v[j] * rstd * gr[64 * j];
;     }
	v_add_f32_e32 v17, v17, v18
	ds_bpermute_b32 v18, v11, v17
	s_waitcnt lgkmcnt(0)
	v_add_f32_e32 v17, v17, v18
	ds_bpermute_b32 v18, v12, v17
	s_waitcnt lgkmcnt(0)
	v_add_f32_e32 v17, v17, v18
	ds_bpermute_b32 v18, v13, v17
	s_waitcnt lgkmcnt(0)
	v_add_f32_e32 v17, v17, v18
	ds_bpermute_b32 v18, v14, v17
	s_waitcnt lgkmcnt(0)
	v_add_f32_e32 v17, v17, v18
	ds_bpermute_b32 v18, v15, v17
	s_waitcnt lgkmcnt(0)
	v_add_f32_e32 v17, v17, v18
	v_fmamk_f32 v6, v17, 0x3a000000, v5
	v_rsq_f32_e32 v6, v6
	s_nop 0
	v_pk_mul_f32 v[64:65], v[6:7], v[64:65] op_sel_hi:[0,1]
	v_pk_mul_f32 v[66:67], v[6:7], v[66:67] op_sel_hi:[0,1]
	v_pk_mul_f32 v[96:97], v[128:129], v[64:65]
	v_pk_mul_f32 v[98:99], v[130:131], v[66:67]
	global_store_dwordx4 v2, v[96:99], s[14:15] offset:-4096
	v_pk_mul_f32 v[68:69], v[6:7], v[68:69] op_sel_hi:[0,1]
	v_pk_mul_f32 v[70:71], v[6:7], v[70:71] op_sel_hi:[0,1]
	v_pk_mul_f32 v[100:101], v[132:133], v[68:69]
	v_pk_mul_f32 v[102:103], v[134:135], v[70:71]
	global_store_dwordx4 v2, v[100:103], s[14:15] offset:-3072
	v_pk_mul_f32 v[72:73], v[6:7], v[72:73] op_sel_hi:[0,1]
	v_pk_mul_f32 v[74:75], v[6:7], v[74:75] op_sel_hi:[0,1]
	v_pk_mul_f32 v[104:105], v[136:137], v[72:73]
	v_pk_mul_f32 v[106:107], v[138:139], v[74:75]
	global_store_dwordx4 v2, v[104:107], s[14:15] offset:-2048
	v_pk_mul_f32 v[76:77], v[6:7], v[76:77] op_sel_hi:[0,1]
	v_pk_mul_f32 v[78:79], v[6:7], v[78:79] op_sel_hi:[0,1]
	v_pk_mul_f32 v[108:109], v[140:141], v[76:77]
	v_pk_mul_f32 v[110:111], v[142:143], v[78:79]
	global_store_dwordx4 v2, v[108:111], s[14:15] offset:-1024
	v_pk_mul_f32 v[80:81], v[6:7], v[80:81] op_sel_hi:[0,1]
	v_pk_mul_f32 v[82:83], v[6:7], v[82:83] op_sel_hi:[0,1]
	v_pk_mul_f32 v[112:113], v[144:145], v[80:81]
	v_pk_mul_f32 v[114:115], v[146:147], v[82:83]
	global_store_dwordx4 v2, v[112:115], s[14:15] offset:0
	v_pk_mul_f32 v[84:85], v[6:7], v[84:85] op_sel_hi:[0,1]
	v_pk_mul_f32 v[86:87], v[6:7], v[86:87] op_sel_hi:[0,1]
	v_pk_mul_f32 v[116:117], v[148:149], v[84:85]
	v_pk_mul_f32 v[118:119], v[150:151], v[86:87]
	global_store_dwordx4 v2, v[116:119], s[14:15] offset:1024
	v_pk_mul_f32 v[88:89], v[6:7], v[88:89] op_sel_hi:[0,1]
	v_pk_mul_f32 v[90:91], v[6:7], v[90:91] op_sel_hi:[0,1]
	v_pk_mul_f32 v[120:121], v[152:153], v[88:89]
	v_pk_mul_f32 v[122:123], v[154:155], v[90:91]
	global_store_dwordx4 v2, v[120:123], s[14:15] offset:2048
	v_pk_mul_f32 v[92:93], v[6:7], v[92:93] op_sel_hi:[0,1]
	v_pk_mul_f32 v[94:95], v[6:7], v[94:95] op_sel_hi:[0,1]
	v_pk_mul_f32 v[124:125], v[156:157], v[92:93]
	v_pk_mul_f32 v[126:127], v[158:159], v[94:95]
	global_store_dwordx4 v2, v[124:127], s[14:15] offset:3072
	s_lshl_b32 s8, s2, 13
	s_add_u32 s14, s4, s8
	s_addc_u32 s15, s5, 0
	s_add_u32 s2, s2, s44
	s_lshl_b32 s8, s2, 12
	s_add_u32 s10, s6, s8
	s_addc_u32 s11, s7, 0
	global_load_dwordx2 v[36:37], v3, s[10:11] offset:-2048
	global_load_dwordx2 v[38:39], v3, s[10:11] offset:-1536
	global_load_dwordx2 v[40:41], v3, s[10:11] offset:-1024
	global_load_dwordx2 v[42:43], v3, s[10:11] offset:-512
	global_load_dwordx2 v[44:45], v3, s[10:11] offset:0
	global_load_dwordx2 v[46:47], v3, s[10:11] offset:512
	global_load_dwordx2 v[48:49], v3, s[10:11] offset:1024
	global_load_dwordx2 v[50:51], v3, s[10:11] offset:1536
	s_waitcnt vmcnt(16)
	v_lshlrev_b32_e32 v64, 16, v20
	v_and_b32_e32 v65, 0xffff0000, v20
	v_lshlrev_b32_e32 v66, 16, v21
	v_and_b32_e32 v67, 0xffff0000, v21
	v_mul_f32_e32 v8, v65, v65
	v_mul_f32_e32 v9, v67, v67
	v_fmac_f32_e32 v8, v64, v64
	v_fmac_f32_e32 v9, v66, v66
	v_add_f32_e32 v17, v8, v9
	v_lshlrev_b32_e32 v68, 16, v22
	v_and_b32_e32 v69, 0xffff0000, v22
	v_lshlrev_b32_e32 v70, 16, v23
	v_and_b32_e32 v71, 0xffff0000, v23
	v_mul_f32_e32 v8, v69, v69
	v_mul_f32_e32 v9, v71, v71
	v_fmac_f32_e32 v8, v68, v68
	v_fmac_f32_e32 v9, v70, v70
	v_add_f32_e32 v8, v8, v9
	v_add_f32_e32 v17, v17, v8
	v_lshlrev_b32_e32 v72, 16, v24
	v_and_b32_e32 v73, 0xffff0000, v24
	v_lshlrev_b32_e32 v74, 16, v25
	v_and_b32_e32 v75, 0xffff0000, v25
	v_mul_f32_e32 v8, v73, v73
	v_mul_f32_e32 v9, v75, v75
	v_fmac_f32_e32 v8, v72, v72
	v_fmac_f32_e32 v9, v74, v74
	v_add_f32_e32 v8, v8, v9
	v_add_f32_e32 v17, v17, v8
	v_lshlrev_b32_e32 v76, 16, v26
	v_and_b32_e32 v77, 0xffff0000, v26
	v_lshlrev_b32_e32 v78, 16, v27
	v_and_b32_e32 v79, 0xffff0000, v27
	v_mul_f32_e32 v8, v77, v77
	v_mul_f32_e32 v9, v79, v79
	v_fmac_f32_e32 v8, v76, v76
	v_fmac_f32_e32 v9, v78, v78
	v_add_f32_e32 v8, v8, v9
	v_add_f32_e32 v17, v17, v8
	v_lshlrev_b32_e32 v80, 16, v28
	v_and_b32_e32 v81, 0xffff0000, v28
	v_lshlrev_b32_e32 v82, 16, v29
	v_and_b32_e32 v83, 0xffff0000, v29
	v_mul_f32_e32 v8, v81, v81
	v_mul_f32_e32 v9, v83, v83
	v_fmac_f32_e32 v8, v80, v80
	v_fmac_f32_e32 v9, v82, v82
	v_add_f32_e32 v8, v8, v9
	v_add_f32_e32 v17, v17, v8
	v_lshlrev_b32_e32 v84, 16, v30
	v_and_b32_e32 v85, 0xffff0000, v30
	v_lshlrev_b32_e32 v86, 16, v31
	v_and_b32_e32 v87, 0xffff0000, v31
	v_mul_f32_e32 v8, v85, v85
	v_mul_f32_e32 v9, v87, v87
	v_fmac_f32_e32 v8, v84, v84
	v_fmac_f32_e32 v9, v86, v86
	v_add_f32_e32 v8, v8, v9
	v_add_f32_e32 v17, v17, v8
	v_lshlrev_b32_e32 v88, 16, v32
	v_and_b32_e32 v89, 0xffff0000, v32
	v_lshlrev_b32_e32 v90, 16, v33
	v_and_b32_e32 v91, 0xffff0000, v33
	v_mul_f32_e32 v8, v89, v89
	v_mul_f32_e32 v9, v91, v91
	v_fmac_f32_e32 v8, v88, v88
	v_fmac_f32_e32 v9, v90, v90
	v_add_f32_e32 v8, v8, v9
	v_add_f32_e32 v17, v17, v8
	v_lshlrev_b32_e32 v92, 16, v34
	v_and_b32_e32 v93, 0xffff0000, v34
	v_lshlrev_b32_e32 v94, 16, v35
	v_and_b32_e32 v95, 0xffff0000, v35
	v_mul_f32_e32 v8, v93, v93
	v_mul_f32_e32 v9, v95, v95
	v_fmac_f32_e32 v8, v92, v92
	v_fmac_f32_e32 v9, v94, v94
	v_add_f32_e32 v8, v8, v9
	v_add_f32_e32 v17, v17, v8
	ds_bpermute_b32 v18, v10, v17
	s_waitcnt lgkmcnt(0)
; __device__ __forceinline__ void final_norm_pass(const Ctx& C, const bf16* XB, const float* g, float* out) {
;     ...
;     for (int m = gw; m < M; m += NGW) {
;         const v2u* xr = (const v2u*)(XB + (size_t)m * D) + C.lane; f32x4 v[8]; float s = 0.f;
; #pragma unroll
;         for (int j = 0; j < 8; ++j) { const v2u w = xr[64 * j]; v[j] = (f32x4){__uint_as_float(w.x << 16), __uint_as_float(w.x & 0xffff0000u), __uint_as_float(w.y << 16), __uint_as_float(w.y & 0xffff0000u)};
;             s += (v[j][0] * v[j][0] + v[j][1] * v[j][1]) + (v[j][2] * v[j][2] + v[j][3] * v[j][3]); }
;         const float rstd = rsqrtf(wave_sum(s) * (1.0f / D) + EPS);
;         const f32x4* gr = (const f32x4*)g + C.lane; f32x4* o = (f32x4*)(out + (size_t)m * D) + C.lane;
; #pragma unroll
;         for (int j = 0; j < 8; ++j) o[64 * j] = v[j] * rstd * gr[64 * j];
;     }
	v_add_f32_e32 v17, v17, v18
	ds_bpermute_b32 v18, v11, v17
	s_waitcnt lgkmcnt(0)
	v_add_f32_e32 v17, v17, v18
	ds_bpermute_b32 v18, v12, v17
	s_waitcnt lgkmcnt(0)
	v_add_f32_e32 v17, v17, v18
	ds_bpermute_b32 v18, v13, v17
	s_waitcnt lgkmcnt(0)
	v_add_f32_e32 v17, v17, v18
	ds_bpermute_b32 v18, v14, v17
	s_waitcnt lgkmcnt(0)
	v_add_f32_e32 v17, v17, v18
	ds_bpermute_b32 v18, v15, v17
	s_waitcnt lgkmcnt(0)
	v_add_f32_e32 v17, v17, v18
	v_fmamk_f32 v6, v17, 0x3a000000, v5
	v_rsq_f32_e32 v6, v6
	s_nop 0
	v_pk_mul_f32 v[64:65], v[6:7], v[64:65] op_sel_hi:[0,1]
	v_pk_mul_f32 v[66:67], v[6:7], v[66:67] op_sel_hi:[0,1]
	v_pk_mul_f32 v[96:97], v[128:129], v[64:65]
	v_pk_mul_f32 v[98:99], v[130:131], v[66:67]
	global_store_dwordx4 v2, v[96:99], s[14:15] offset:-4096
	v_pk_mul_f32 v[68:69], v[6:7], v[68:69] op_sel_hi:[0,1]
	v_pk_mul_f32 v[70:71], v[6:7], v[70:71] op_sel_hi:[0,1]
	v_pk_mul_f32 v[100:101], v[132:133], v[68:69]
	v_pk_mul_f32 v[102:103], v[134:135], v[70:71]
	global_store_dwordx4 v2, v[100:103], s[14:15] offset:-3072
	v_pk_mul_f32 v[72:73], v[6:7], v[72:73] op_sel_hi:[0,1]
	v_pk_mul_f32 v[74:75], v[6:7], v[74:75] op_sel_hi:[0,1]
	v_pk_mul_f32 v[104:105], v[136:137], v[72:73]
	v_pk_mul_f32 v[106:107], v[138:139], v[74:75]
	global_store_dwordx4 v2, v[104:107], s[14:15] offset:-2048
	v_pk_mul_f32 v[76:77], v[6:7], v[76:77] op_sel_hi:[0,1]
	v_pk_mul_f32 v[78:79], v[6:7], v[78:79] op_sel_hi:[0,1]
	v_pk_mul_f32 v[108:109], v[140:141], v[76:77]
	v_pk_mul_f32 v[110:111], v[142:143], v[78:79]
	global_store_dwordx4 v2, v[108:111], s[14:15] offset:-1024
	v_pk_mul_f32 v[80:81], v[6:7], v[80:81] op_sel_hi:[0,1]
	v_pk_mul_f32 v[82:83], v[6:7], v[82:83] op_sel_hi:[0,1]
	v_pk_mul_f32 v[112:113], v[144:145], v[80:81]
	v_pk_mul_f32 v[114:115], v[146:147], v[82:83]
	global_store_dwordx4 v2, v[112:115], s[14:15] offset:0
	v_pk_mul_f32 v[84:85], v[6:7], v[84:85] op_sel_hi:[0,1]
	v_pk_mul_f32 v[86:87], v[6:7], v[86:87] op_sel_hi:[0,1]
	v_pk_mul_f32 v[116:117], v[148:149], v[84:85]
	v_pk_mul_f32 v[118:119], v[150:151], v[86:87]
	global_store_dwordx4 v2, v[116:119], s[14:15] offset:1024
	v_pk_mul_f32 v[88:89], v[6:7], v[88:89] op_sel_hi:[0,1]
	v_pk_mul_f32 v[90:91], v[6:7], v[90:91] op_sel_hi:[0,1]
	v_pk_mul_f32 v[120:121], v[152:153], v[88:89]
	v_pk_mul_f32 v[122:123], v[154:155], v[90:91]
	global_store_dwordx4 v2, v[120:123], s[14:15] offset:2048
	v_pk_mul_f32 v[92:93], v[6:7], v[92:93] op_sel_hi:[0,1]
	v_pk_mul_f32 v[94:95], v[6:7], v[94:95] op_sel_hi:[0,1]
	v_pk_mul_f32 v[124:125], v[156:157], v[92:93]
	v_pk_mul_f32 v[126:127], v[158:159], v[94:95]
	global_store_dwordx4 v2, v[124:127], s[14:15] offset:3072
	s_lshl_b32 s8, s2, 13
	s_add_u32 s14, s4, s8
	s_addc_u32 s15, s5, 0
	s_waitcnt vmcnt(8)
; __device__ __forceinline__ void final_norm_pass(const Ctx& C, const bf16* XB, const float* g, float* out) {
;     ...
;     for (int m = gw; m < M; m += NGW) {
;         const v2u* xr = (const v2u*)(XB + (size_t)m * D) + C.lane; f32x4 v[8]; float s = 0.f;
; #pragma unroll
;         for (int j = 0; j < 8; ++j) { const v2u w = xr[64 * j]; v[j] = (f32x4){__uint_as_float(w.x << 16), __uint_as_float(w.x & 0xffff0000u), __uint_as_float(w.y << 16), __uint_as_float(w.y & 0xffff0000u)};
;             s += (v[j][0] * v[j][0] + v[j][1] * v[j][1]) + (v[j][2] * v[j][2] + v[j][3] * v[j][3]); }
;         const float rstd = rsqrtf(wave_sum(s) * (1.0f / D) + EPS);
;         const f32x4* gr = (const f32x4*)g + C.lane; f32x4* o = (f32x4*)(out + (size_t)m * D) + C.lane;
; #pragma unroll
;         for (int j = 0; j < 8; ++j) o[64 * j] = v[j] * rstd * gr[64 * j];
;     }
	v_lshlrev_b32_e32 v64, 16, v36
	v_and_b32_e32 v65, 0xffff0000, v36
	v_lshlrev_b32_e32 v66, 16, v37
	v_and_b32_e32 v67, 0xffff0000, v37
	v_mul_f32_e32 v8, v65, v65
	v_mul_f32_e32 v9, v67, v67
	v_fmac_f32_e32 v8, v64, v64
	v_fmac_f32_e32 v9, v66, v66
	v_add_f32_e32 v17, v8, v9
	v_lshlrev_b32_e32 v68, 16, v38
	v_and_b32_e32 v69, 0xffff0000, v38
	v_lshlrev_b32_e32 v70, 16, v39
	v_and_b32_e32 v71, 0xffff0000, v39
	v_mul_f32_e32 v8, v69, v69
	v_mul_f32_e32 v9, v71, v71
	v_fmac_f32_e32 v8, v68, v68
	v_fmac_f32_e32 v9, v70, v70
	v_add_f32_e32 v8, v8, v9
	v_add_f32_e32 v17, v17, v8
	v_lshlrev_b32_e32 v72, 16, v40
	v_and_b32_e32 v73, 0xffff0000, v40
	v_lshlrev_b32_e32 v74, 16, v41
	v_and_b32_e32 v75, 0xffff0000, v41
	v_mul_f32_e32 v8, v73, v73
	v_mul_f32_e32 v9, v75, v75
	v_fmac_f32_e32 v8, v72, v72
	v_fmac_f32_e32 v9, v74, v74
	v_add_f32_e32 v8, v8, v9
	v_add_f32_e32 v17, v17, v8
	v_lshlrev_b32_e32 v76, 16, v42
	v_and_b32_e32 v77, 0xffff0000, v42
	v_lshlrev_b32_e32 v78, 16, v43
	v_and_b32_e32 v79, 0xffff0000, v43
	v_mul_f32_e32 v8, v77, v77
	v_mul_f32_e32 v9, v79, v79
	v_fmac_f32_e32 v8, v76, v76
	v_fmac_f32_e32 v9, v78, v78
	v_add_f32_e32 v8, v8, v9
	v_add_f32_e32 v17, v17, v8
	v_lshlrev_b32_e32 v80, 16, v44
	v_and_b32_e32 v81, 0xffff0000, v44
	v_lshlrev_b32_e32 v82, 16, v45
	v_and_b32_e32 v83, 0xffff0000, v45
	v_mul_f32_e32 v8, v81, v81
	v_mul_f32_e32 v9, v83, v83
	v_fmac_f32_e32 v8, v80, v80
	v_fmac_f32_e32 v9, v82, v82
	v_add_f32_e32 v8, v8, v9
	v_add_f32_e32 v17, v17, v8
	v_lshlrev_b32_e32 v84, 16, v46
	v_and_b32_e32 v85, 0xffff0000, v46
	v_lshlrev_b32_e32 v86, 16, v47
	v_and_b32_e32 v87, 0xffff0000, v47
	v_mul_f32_e32 v8, v85, v85
	v_mul_f32_e32 v9, v87, v87
	v_fmac_f32_e32 v8, v84, v84
	v_fmac_f32_e32 v9, v86, v86
	v_add_f32_e32 v8, v8, v9
	v_add_f32_e32 v17, v17, v8
	v_lshlrev_b32_e32 v88, 16, v48
	v_and_b32_e32 v89, 0xffff0000, v48
	v_lshlrev_b32_e32 v90, 16, v49
	v_and_b32_e32 v91, 0xffff0000, v49
	v_mul_f32_e32 v8, v89, v89
	v_mul_f32_e32 v9, v91, v91
	v_fmac_f32_e32 v8, v88, v88
	v_fmac_f32_e32 v9, v90, v90
	v_add_f32_e32 v8, v8, v9
	v_add_f32_e32 v17, v17, v8
	v_lshlrev_b32_e32 v92, 16, v50
	v_and_b32_e32 v93, 0xffff0000, v50
	v_lshlrev_b32_e32 v94, 16, v51
	v_and_b32_e32 v95, 0xffff0000, v51
	v_mul_f32_e32 v8, v93, v93
	v_mul_f32_e32 v9, v95, v95
	v_fmac_f32_e32 v8, v92, v92
	v_fmac_f32_e32 v9, v94, v94
	v_add_f32_e32 v8, v8, v9
	v_add_f32_e32 v17, v17, v8
	ds_bpermute_b32 v18, v10, v17
	s_waitcnt lgkmcnt(0)
	v_add_f32_e32 v17, v17, v18
	ds_bpermute_b32 v18, v11, v17
	s_waitcnt lgkmcnt(0)
	v_add_f32_e32 v17, v17, v18
	ds_bpermute_b32 v18, v12, v17
	s_waitcnt lgkmcnt(0)
	v_add_f32_e32 v17, v17, v18
	ds_bpermute_b32 v18, v13, v17
	s_waitcnt lgkmcnt(0)
	v_add_f32_e32 v17, v17, v18
	ds_bpermute_b32 v18, v14, v17
	s_waitcnt lgkmcnt(0)
	v_add_f32_e32 v17, v17, v18
	ds_bpermute_b32 v18, v15, v17
	s_waitcnt lgkmcnt(0)
	v_add_f32_e32 v17, v17, v18
	v_fmamk_f32 v6, v17, 0x3a000000, v5
	v_rsq_f32_e32 v6, v6
	s_nop 0
	v_pk_mul_f32 v[64:65], v[6:7], v[64:65] op_sel_hi:[0,1]
	v_pk_mul_f32 v[66:67], v[6:7], v[66:67] op_sel_hi:[0,1]
	v_pk_mul_f32 v[96:97], v[128:129], v[64:65]
	v_pk_mul_f32 v[98:99], v[130:131], v[66:67]
	global_store_dwordx4 v2, v[96:99], s[14:15] offset:-4096
	v_pk_mul_f32 v[68:69], v[6:7], v[68:69] op_sel_hi:[0,1]
	v_pk_mul_f32 v[70:71], v[6:7], v[70:71] op_sel_hi:[0,1]
	v_pk_mul_f32 v[100:101], v[132:133], v[68:69]
	v_pk_mul_f32 v[102:103], v[134:135], v[70:71]
	global_store_dwordx4 v2, v[100:103], s[14:15] offset:-3072
	v_pk_mul_f32 v[72:73], v[6:7], v[72:73] op_sel_hi:[0,1]
	v_pk_mul_f32 v[74:75], v[6:7], v[74:75] op_sel_hi:[0,1]
	v_pk_mul_f32 v[104:105], v[136:137], v[72:73]
	v_pk_mul_f32 v[106:107], v[138:139], v[74:75]
	global_store_dwordx4 v2, v[104:107], s[14:15] offset:-2048
	v_pk_mul_f32 v[76:77], v[6:7], v[76:77] op_sel_hi:[0,1]
	v_pk_mul_f32 v[78:79], v[6:7], v[78:79] op_sel_hi:[0,1]
	v_pk_mul_f32 v[108:109], v[140:141], v[76:77]
	v_pk_mul_f32 v[110:111], v[142:143], v[78:79]
	global_store_dwordx4 v2, v[108:111], s[14:15] offset:-1024
	v_pk_mul_f32 v[80:81], v[6:7], v[80:81] op_sel_hi:[0,1]
	v_pk_mul_f32 v[82:83], v[6:7], v[82:83] op_sel_hi:[0,1]
	v_pk_mul_f32 v[112:113], v[144:145], v[80:81]
	v_pk_mul_f32 v[114:115], v[146:147], v[82:83]
	global_store_dwordx4 v2, v[112:115], s[14:15] offset:0
	v_pk_mul_f32 v[84:85], v[6:7], v[84:85] op_sel_hi:[0,1]
	v_pk_mul_f32 v[86:87], v[6:7], v[86:87] op_sel_hi:[0,1]
	v_pk_mul_f32 v[116:117], v[148:149], v[84:85]
	v_pk_mul_f32 v[118:119], v[150:151], v[86:87]
	global_store_dwordx4 v2, v[116:119], s[14:15] offset:1024
	v_pk_mul_f32 v[88:89], v[6:7], v[88:89] op_sel_hi:[0,1]
	v_pk_mul_f32 v[90:91], v[6:7], v[90:91] op_sel_hi:[0,1]
	v_pk_mul_f32 v[120:121], v[152:153], v[88:89]
	v_pk_mul_f32 v[122:123], v[154:155], v[90:91]
	global_store_dwordx4 v2, v[120:123], s[14:15] offset:2048
	v_pk_mul_f32 v[92:93], v[6:7], v[92:93] op_sel_hi:[0,1]
	v_pk_mul_f32 v[94:95], v[6:7], v[94:95] op_sel_hi:[0,1]
	v_pk_mul_f32 v[124:125], v[156:157], v[92:93]
	v_pk_mul_f32 v[126:127], v[158:159], v[94:95]
	global_store_dwordx4 v2, v[124:127], s[14:15] offset:3072
